# GEMM K-loops duplicated: workgroup with LDS base 0 runs s_setprio 3/2, its CU partner 1/0, so co-resident workgroups fall into anti-phase (DMA vs MFMA)
# baseline (speedup 1.0000x reference)
_Z11mega_kernel6Params:
	s_load_dwordx2 s[56:57], s[0:1], 0x200
	s_add_u32 s4, s0, 0x200
	v_and_b32_e32 v180, 0x3ff, v0
	s_addc_u32 s5, s1, 0
	v_cmp_eq_u32_e64 s[46:47], 0, v180
	s_and_saveexec_b64 s[6:7], s[46:47]
	v_mov_b32_e32 v2, 0
	v_mov_b32_e32 v3, v2
	v_mov_b32_e32 v4, v2
	v_mov_b32_e32 v5, v2
	ds_write_b128 v2, v[2:5]
	s_or_b64 exec, exec, s[6:7]
	s_load_dwordx2 s[52:53], s[0:1], 0x1f0
	s_load_dword s3, s[0:1], 0x208
	s_waitcnt lgkmcnt(0)
	s_barrier
	s_add_u32 s54, s52, 0x14e28000
	s_getreg_b32 s6, hwreg(HW_REG_XCC_ID, 0, 4)
	s_addc_u32 s55, s53, 0
	s_and_b32 s33, s6, 15
	s_getreg_b32 s32, hwreg(HW_REG_LDS_ALLOC, 0, 12)
	s_cmp_eq_u32 s32, 0
	s_cselect_b32 s32, 1, 0
	v_mov_b32_e32 v1, 0
	s_and_saveexec_b64 s[6:7], s[46:47]
	s_cbranch_execz .LBB0_6
	s_mov_b64 s[10:11], exec
	v_mbcnt_lo_u32_b32 v1, s10, 0
	v_mbcnt_hi_u32_b32 v1, s11, v1
	v_cmp_eq_u32_e32 vcc, 0, v1
	s_and_saveexec_b64 s[8:9], vcc
	s_cbranch_execz .LBB0_5
	s_lshl_b32 s12, s33, 8
	s_bcnt1_i32_b64 s10, s[10:11]
	v_mov_b32_e32 v2, s12
	v_mov_b32_e32 v3, s10
	global_atomic_add v2, v2, v3, s[54:55] offset:1024 sc0

.LBB0_258:
	s_mul_hi_i32 s4, s44, 0x2aaaaaab
	s_lshr_b32 s5, s4, 31
	s_ashr_i32 s4, s4, 1
	s_add_i32 s4, s4, s5
	s_mul_i32 s5, s4, -12
	s_add_i32 s5, s5, s44
	s_lshl_b32 s6, s5, 7
	v_add_u32_e32 v0, s6, v112
	v_ashrrev_i32_e32 v1, 31, v0
	v_add_u32_e32 v2, 0x4000, v113
	v_lshlrev_b64 v[0:1], 11, v[0:1]
	v_readfirstlane_b32 s5, v2
	s_lshl_b32 s30, s4, 7
	v_lshl_add_u64 v[0:1], v[66:67], 0, v[0:1]
	s_mov_b32 m0, s5
	v_readfirstlane_b32 s5, v113
	global_load_lds_dwordx4 v[0:1], off
	v_add_u32_e32 v0, s30, v112
	v_ashrrev_i32_e32 v1, 31, v0
	v_lshlrev_b64 v[0:1], 11, v[0:1]
	v_lshl_add_u64 v[2:3], v[72:73], 0, v[0:1]
	s_mov_b32 m0, s5
	v_readfirstlane_b32 s5, v137
	global_load_lds_dwordx4 v[2:3], off
	v_add_u32_e32 v2, s6, v114
	v_ashrrev_i32_e32 v3, 31, v2
	v_lshlrev_b64 v[2:3], 11, v[2:3]
	v_lshl_add_u64 v[2:3], v[68:69], 0, v[2:3]
	s_mov_b32 m0, s5
	v_add_u32_e32 v4, 0x400, v113
	global_load_lds_dwordx4 v[2:3], off
	v_add_u32_e32 v2, s30, v114
	v_ashrrev_i32_e32 v3, 31, v2
	v_lshlrev_b64 v[2:3], 11, v[2:3]
	v_readfirstlane_b32 s5, v4
	v_lshl_add_u64 v[2:3], v[74:75], 0, v[2:3]
	s_mov_b32 m0, s5
	v_readfirstlane_b32 s5, v138
	global_load_lds_dwordx4 v[2:3], off
	v_add_u32_e32 v2, s6, v116
	v_ashrrev_i32_e32 v3, 31, v2
	v_lshlrev_b64 v[2:3], 11, v[2:3]
	v_lshl_add_u64 v[2:3], v[66:67], 0, v[2:3]
	s_mov_b32 m0, s5
	v_add_u32_e32 v4, 0x800, v113
	global_load_lds_dwordx4 v[2:3], off
	v_add_u32_e32 v2, s30, v116
	v_ashrrev_i32_e32 v3, 31, v2
	v_lshlrev_b64 v[2:3], 11, v[2:3]
	v_readfirstlane_b32 s5, v4
	v_lshl_add_u64 v[2:3], v[72:73], 0, v[2:3]
	s_mov_b32 m0, s5
	v_readfirstlane_b32 s5, v139
	global_load_lds_dwordx4 v[2:3], off
	v_add_u32_e32 v2, s6, v118
	v_ashrrev_i32_e32 v3, 31, v2
	v_lshlrev_b64 v[2:3], 11, v[2:3]
	v_lshl_add_u64 v[2:3], v[70:71], 0, v[2:3]
	s_mov_b32 m0, s5
	v_add_u32_e32 v4, 0xc00, v113
	global_load_lds_dwordx4 v[2:3], off
	v_add_u32_e32 v2, s30, v118
	v_ashrrev_i32_e32 v3, 31, v2
	v_lshlrev_b64 v[2:3], 11, v[2:3]
	v_readfirstlane_b32 s5, v4
	v_lshl_add_u64 v[2:3], v[76:77], 0, v[2:3]
	s_mov_b32 m0, s5
	s_mulk_i32 s4, 0x600
	global_load_lds_dwordx4 v[2:3], off
	v_lshl_add_u64 v[98:99], v[84:85], 0, v[0:1]
	v_subrev_u32_e32 v0, s4, v129
	v_ashrrev_i32_e32 v1, 31, v0
	v_lshlrev_b64 v[0:1], 11, v[0:1]
	v_lshl_add_u64 v[100:101], v[86:87], 0, v[0:1]
	v_add_u32_e32 v0, s30, v130
	v_ashrrev_i32_e32 v1, 31, v0
	v_lshlrev_b64 v[0:1], 11, v[0:1]
	v_lshl_add_u64 v[102:103], v[88:89], 0, v[0:1]
	v_subrev_u32_e32 v0, s4, v131
	v_ashrrev_i32_e32 v1, 31, v0
	v_lshlrev_b64 v[0:1], 11, v[0:1]
	v_lshl_add_u64 v[104:105], v[82:83], 0, v[0:1]
	v_add_u32_e32 v0, s30, v132
	v_ashrrev_i32_e32 v1, 31, v0
	v_lshlrev_b64 v[0:1], 11, v[0:1]
	v_lshl_add_u64 v[106:107], v[84:85], 0, v[0:1]
	v_subrev_u32_e32 v0, s4, v133
	v_ashrrev_i32_e32 v1, 31, v0
	v_lshlrev_b64 v[0:1], 11, v[0:1]
	v_subrev_u32_e32 v2, s4, v128
	v_lshl_add_u64 v[108:109], v[90:91], 0, v[0:1]
	v_add_u32_e32 v0, s30, v134
	v_ashrrev_i32_e32 v3, 31, v2
	v_ashrrev_i32_e32 v1, 31, v0
	v_lshlrev_b64 v[2:3], 11, v[2:3]
	v_lshlrev_b64 v[0:1], 11, v[0:1]
	v_lshl_add_u64 v[96:97], v[82:83], 0, v[2:3]
	v_lshl_add_u64 v[110:111], v[92:93], 0, v[0:1]
	s_mov_b64 s[4:5], 0
	s_mov_b32 s7, 0
	v_mov_b32_e32 v0, v65
	v_mov_b32_e32 v1, v65
	v_mov_b32_e32 v2, v65
	v_mov_b32_e32 v3, v65
	v_mov_b32_e32 v4, v65
	v_mov_b32_e32 v5, v65
	v_mov_b32_e32 v6, v65
	v_mov_b32_e32 v7, v65
	v_mov_b32_e32 v8, v65
	v_mov_b32_e32 v9, v65
	v_mov_b32_e32 v10, v65
	v_mov_b32_e32 v11, v65
	v_mov_b32_e32 v12, v65
	v_mov_b32_e32 v13, v65
	v_mov_b32_e32 v14, v65
	v_mov_b32_e32 v15, v65
	v_mov_b32_e32 v16, v65
	v_mov_b32_e32 v17, v65
	v_mov_b32_e32 v18, v65
	v_mov_b32_e32 v19, v65
	v_mov_b32_e32 v20, v65
	v_mov_b32_e32 v21, v65
	v_mov_b32_e32 v22, v65
	v_mov_b32_e32 v23, v65
	v_mov_b32_e32 v24, v65
	v_mov_b32_e32 v25, v65
	v_mov_b32_e32 v26, v65
	v_mov_b32_e32 v27, v65
	v_mov_b32_e32 v28, v65
	v_mov_b32_e32 v29, v65
	v_mov_b32_e32 v30, v65
	v_mov_b32_e32 v31, v65
	v_mov_b32_e32 v32, v65
	v_mov_b32_e32 v33, v65
	v_mov_b32_e32 v34, v65
	v_mov_b32_e32 v35, v65
	v_mov_b32_e32 v36, v65
	v_mov_b32_e32 v37, v65
	v_mov_b32_e32 v38, v65
	v_mov_b32_e32 v39, v65
	v_mov_b32_e32 v40, v65
	v_mov_b32_e32 v41, v65
	v_mov_b32_e32 v42, v65
	v_mov_b32_e32 v43, v65
	v_mov_b32_e32 v44, v65
	v_mov_b32_e32 v45, v65
	v_mov_b32_e32 v46, v65
	v_mov_b32_e32 v47, v65
	v_mov_b32_e32 v48, v65
	v_mov_b32_e32 v49, v65
	v_mov_b32_e32 v50, v65
	v_mov_b32_e32 v51, v65
	v_mov_b32_e32 v52, v65
	v_mov_b32_e32 v53, v65
	v_mov_b32_e32 v54, v65
	v_mov_b32_e32 v55, v65
	v_mov_b32_e32 v56, v65
	v_mov_b32_e32 v57, v65
	v_mov_b32_e32 v58, v65
	v_mov_b32_e32 v59, v65
	v_mov_b32_e32 v60, v65
	v_mov_b32_e32 v61, v65
	v_mov_b32_e32 v62, v65
	v_mov_b32_e32 v63, v65
	s_waitcnt vmcnt(0) lgkmcnt(0)
	s_barrier
	v_add3_u32 v182, 0, v140, v141
	v_add_u32_e32 v183, 0x4000, v182
	s_nop 0
	v_readfirstlane_b32 s82, v183
	v_lshl_add_u32 v183, v115, 1, 0
	s_nop 0
	v_readfirstlane_b32 s83, v182
	v_add3_u32 v183, v183, v141, s37
	s_nop 0
	v_readfirstlane_b32 s84, v183
	v_add_u32_e32 v183, 0x400, v182
	s_nop 0
	v_readfirstlane_b32 s85, v183
	v_lshl_add_u32 v183, v117, 1, 0
	v_add3_u32 v183, v183, v141, s37
	s_nop 0
	v_readfirstlane_b32 s86, v183
	v_add_u32_e32 v183, 0x800, v182
	s_nop 0
	v_readfirstlane_b32 s87, v183
	v_lshl_add_u32 v183, v119, 1, 0
	v_add3_u32 v183, v183, v141, s37
	s_nop 0
	v_readfirstlane_b32 s88, v183
	v_add_u32_e32 v182, 0xc00, v182
	s_nop 0
	v_readfirstlane_b32 s89, v182
	v_subrev_u32_e32 v184, s52, v96
	v_subrev_u32_e32 v185, s52, v98
	v_subrev_u32_e32 v186, s52, v100
	v_subrev_u32_e32 v187, s52, v102
	v_subrev_u32_e32 v188, s52, v104
	v_subrev_u32_e32 v189, s52, v106
	v_subrev_u32_e32 v190, s52, v108
	v_subrev_u32_e32 v191, s52, v110
	s_bitcmp1_b32 s32, 0
	s_cbranch_scc1 .Lxk_259
.LBB0_259:
	s_and_b32 s8, s7, 0x4000
	s_xor_b32 s9, s8, 0x4000
	s_lshl_b32 s9, s9, 1
	s_add_i32 s9, s9, 32
	s_add_u32 s90, s52, s4
	s_addc_u32 s91, s53, s5
	s_add_i32 m0, s9, s82
	s_lshl_b32 s8, s8, 1
	global_load_lds_dwordx4 v184, s[90:91]
	s_add_i32 m0, s9, s83
	s_add_i32 s8, s8, 32
	global_load_lds_dwordx4 v185, s[90:91]
	s_add_i32 m0, s9, s84
	v_lshl_add_u32 v64, v120, 1, s8
	global_load_lds_dwordx4 v186, s[90:91]
	s_add_i32 m0, s9, s85
	v_lshl_add_u32 v95, v121, 1, s8
	global_load_lds_dwordx4 v187, s[90:91]
	s_add_i32 m0, s9, s86
	v_add_u32_e32 v166, v64, v142
	global_load_lds_dwordx4 v188, s[90:91]
	s_add_i32 m0, s9, s87
	v_add_u32_e32 v174, v95, v142
	global_load_lds_dwordx4 v189, s[90:91]
	s_add_i32 m0, s9, s88
	s_addk_i32 s7, 0x4000
	global_load_lds_dwordx4 v190, s[90:91]
	s_add_i32 m0, s9, s89
	s_add_u32 s4, s4, 0x80
	s_addc_u32 s5, s5, 0
	global_load_lds_dwordx4 v191, s[90:91]
	ds_read_b128 v[146:149], v166
	ds_read_b128 v[154:157], v174 offset:16384
	ds_read_b128 v[158:161], v174 offset:18432
	ds_read_b128 v[170:173], v174 offset:20480
	ds_read_b128 v[174:177], v174 offset:22528
	ds_read_b128 v[150:153], v166 offset:2048
	ds_read_b128 v[162:165], v166 offset:4096
	ds_read_b128 v[166:169], v166 offset:6144
	v_add_u32_e32 v64, v64, v143
	v_add_u32_e32 v95, v95, v143
	ds_read_b128 v[204:207], v64
	ds_read_b128 v[208:211], v95 offset:16384
	ds_read_b128 v[212:215], v95 offset:18432
	ds_read_b128 v[216:219], v95 offset:20480
	ds_read_b128 v[220:223], v95 offset:22528
	ds_read_b128 v[224:227], v64 offset:2048
	ds_read_b128 v[228:231], v64 offset:4096
	ds_read_b128 v[232:235], v64 offset:6144
	s_setprio 1
	s_waitcnt lgkmcnt(11)
	v_mfma_f32_16x16x32_bf16 v[60:63], v[146:149], v[154:157], v[60:63]
	v_mfma_f32_16x16x32_bf16 v[56:59], v[146:149], v[158:161], v[56:59]
	v_mfma_f32_16x16x32_bf16 v[52:55], v[146:149], v[170:173], v[52:55]
	v_mfma_f32_16x16x32_bf16 v[48:51], v[146:149], v[174:177], v[48:51]
	s_waitcnt lgkmcnt(10)
	v_mfma_f32_16x16x32_bf16 v[44:47], v[150:153], v[154:157], v[44:47]
	v_mfma_f32_16x16x32_bf16 v[40:43], v[150:153], v[158:161], v[40:43]
	v_mfma_f32_16x16x32_bf16 v[36:39], v[150:153], v[170:173], v[36:39]
	v_mfma_f32_16x16x32_bf16 v[32:35], v[150:153], v[174:177], v[32:35]
	s_waitcnt lgkmcnt(9)
	v_mfma_f32_16x16x32_bf16 v[28:31], v[162:165], v[154:157], v[28:31]
	v_mfma_f32_16x16x32_bf16 v[24:27], v[162:165], v[158:161], v[24:27]
	v_mfma_f32_16x16x32_bf16 v[20:23], v[162:165], v[170:173], v[20:23]
	v_mfma_f32_16x16x32_bf16 v[16:19], v[162:165], v[174:177], v[16:19]
	s_waitcnt lgkmcnt(8)
	v_mfma_f32_16x16x32_bf16 v[12:15], v[166:169], v[154:157], v[12:15]
	v_mfma_f32_16x16x32_bf16 v[8:11], v[166:169], v[158:161], v[8:11]
	v_mfma_f32_16x16x32_bf16 v[4:7], v[166:169], v[170:173], v[4:7]
	v_mfma_f32_16x16x32_bf16 v[0:3], v[166:169], v[174:177], v[0:3]
	s_waitcnt lgkmcnt(3)
	v_mfma_f32_16x16x32_bf16 v[60:63], v[204:207], v[208:211], v[60:63]
	v_mfma_f32_16x16x32_bf16 v[56:59], v[204:207], v[212:215], v[56:59]
	v_mfma_f32_16x16x32_bf16 v[52:55], v[204:207], v[216:219], v[52:55]
	v_mfma_f32_16x16x32_bf16 v[48:51], v[204:207], v[220:223], v[48:51]
	s_waitcnt lgkmcnt(2)
	v_mfma_f32_16x16x32_bf16 v[44:47], v[224:227], v[208:211], v[44:47]
	v_mfma_f32_16x16x32_bf16 v[40:43], v[224:227], v[212:215], v[40:43]
	v_mfma_f32_16x16x32_bf16 v[36:39], v[224:227], v[216:219], v[36:39]
	v_mfma_f32_16x16x32_bf16 v[32:35], v[224:227], v[220:223], v[32:35]
	s_waitcnt lgkmcnt(1)
	v_mfma_f32_16x16x32_bf16 v[28:31], v[228:231], v[208:211], v[28:31]
	v_mfma_f32_16x16x32_bf16 v[24:27], v[228:231], v[212:215], v[24:27]
	v_mfma_f32_16x16x32_bf16 v[20:23], v[228:231], v[216:219], v[20:23]
	v_mfma_f32_16x16x32_bf16 v[16:19], v[228:231], v[220:223], v[16:19]
	s_waitcnt lgkmcnt(0)
	v_mfma_f32_16x16x32_bf16 v[12:15], v[232:235], v[208:211], v[12:15]
	v_mfma_f32_16x16x32_bf16 v[8:11], v[232:235], v[212:215], v[8:11]
	v_mfma_f32_16x16x32_bf16 v[4:7], v[232:235], v[216:219], v[4:7]
	v_mfma_f32_16x16x32_bf16 v[0:3], v[232:235], v[220:223], v[0:3]
	s_setprio 0
	s_cmpk_eq_i32 s4, 0x780
	s_waitcnt vmcnt(0)
	s_barrier
	s_cbranch_scc0 .LBB0_259
	s_branch .Lxk_exit_259
.Lxk_259:
	s_and_b32 s8, s7, 0x4000
	s_xor_b32 s9, s8, 0x4000
	s_lshl_b32 s9, s9, 1
	s_add_i32 s9, s9, 32
	s_add_u32 s90, s52, s4
	s_addc_u32 s91, s53, s5
	s_add_i32 m0, s9, s82
	s_lshl_b32 s8, s8, 1
	global_load_lds_dwordx4 v184, s[90:91]
	s_add_i32 m0, s9, s83
	s_add_i32 s8, s8, 32
	global_load_lds_dwordx4 v185, s[90:91]
	s_add_i32 m0, s9, s84
	v_lshl_add_u32 v64, v120, 1, s8
	global_load_lds_dwordx4 v186, s[90:91]
	s_add_i32 m0, s9, s85
	v_lshl_add_u32 v95, v121, 1, s8
	global_load_lds_dwordx4 v187, s[90:91]
	s_add_i32 m0, s9, s86
	v_add_u32_e32 v166, v64, v142
	global_load_lds_dwordx4 v188, s[90:91]
	s_add_i32 m0, s9, s87
	v_add_u32_e32 v174, v95, v142
	global_load_lds_dwordx4 v189, s[90:91]
	s_add_i32 m0, s9, s88
	s_addk_i32 s7, 0x4000
	global_load_lds_dwordx4 v190, s[90:91]
	s_add_i32 m0, s9, s89
	s_add_u32 s4, s4, 0x80
	s_addc_u32 s5, s5, 0
	global_load_lds_dwordx4 v191, s[90:91]
	ds_read_b128 v[146:149], v166
	ds_read_b128 v[154:157], v174 offset:16384
	ds_read_b128 v[158:161], v174 offset:18432
	ds_read_b128 v[170:173], v174 offset:20480
	ds_read_b128 v[174:177], v174 offset:22528
	ds_read_b128 v[150:153], v166 offset:2048
	ds_read_b128 v[162:165], v166 offset:4096
	ds_read_b128 v[166:169], v166 offset:6144
	v_add_u32_e32 v64, v64, v143
	v_add_u32_e32 v95, v95, v143
	ds_read_b128 v[204:207], v64
	ds_read_b128 v[208:211], v95 offset:16384
	ds_read_b128 v[212:215], v95 offset:18432
	ds_read_b128 v[216:219], v95 offset:20480
	ds_read_b128 v[220:223], v95 offset:22528
	ds_read_b128 v[224:227], v64 offset:2048
	ds_read_b128 v[228:231], v64 offset:4096
	ds_read_b128 v[232:235], v64 offset:6144
	s_setprio 3
	s_waitcnt lgkmcnt(11)
	v_mfma_f32_16x16x32_bf16 v[60:63], v[146:149], v[154:157], v[60:63]
	v_mfma_f32_16x16x32_bf16 v[56:59], v[146:149], v[158:161], v[56:59]
	v_mfma_f32_16x16x32_bf16 v[52:55], v[146:149], v[170:173], v[52:55]
	v_mfma_f32_16x16x32_bf16 v[48:51], v[146:149], v[174:177], v[48:51]
	s_waitcnt lgkmcnt(10)
	v_mfma_f32_16x16x32_bf16 v[44:47], v[150:153], v[154:157], v[44:47]
	v_mfma_f32_16x16x32_bf16 v[40:43], v[150:153], v[158:161], v[40:43]
	v_mfma_f32_16x16x32_bf16 v[36:39], v[150:153], v[170:173], v[36:39]
	v_mfma_f32_16x16x32_bf16 v[32:35], v[150:153], v[174:177], v[32:35]
	s_waitcnt lgkmcnt(9)
	v_mfma_f32_16x16x32_bf16 v[28:31], v[162:165], v[154:157], v[28:31]
	v_mfma_f32_16x16x32_bf16 v[24:27], v[162:165], v[158:161], v[24:27]
	v_mfma_f32_16x16x32_bf16 v[20:23], v[162:165], v[170:173], v[20:23]
	v_mfma_f32_16x16x32_bf16 v[16:19], v[162:165], v[174:177], v[16:19]
	s_waitcnt lgkmcnt(8)
	v_mfma_f32_16x16x32_bf16 v[12:15], v[166:169], v[154:157], v[12:15]
	v_mfma_f32_16x16x32_bf16 v[8:11], v[166:169], v[158:161], v[8:11]
	v_mfma_f32_16x16x32_bf16 v[4:7], v[166:169], v[170:173], v[4:7]
	v_mfma_f32_16x16x32_bf16 v[0:3], v[166:169], v[174:177], v[0:3]
	s_waitcnt lgkmcnt(3)
	v_mfma_f32_16x16x32_bf16 v[60:63], v[204:207], v[208:211], v[60:63]
	v_mfma_f32_16x16x32_bf16 v[56:59], v[204:207], v[212:215], v[56:59]
	v_mfma_f32_16x16x32_bf16 v[52:55], v[204:207], v[216:219], v[52:55]
	v_mfma_f32_16x16x32_bf16 v[48:51], v[204:207], v[220:223], v[48:51]
	s_waitcnt lgkmcnt(2)
	v_mfma_f32_16x16x32_bf16 v[44:47], v[224:227], v[208:211], v[44:47]
	v_mfma_f32_16x16x32_bf16 v[40:43], v[224:227], v[212:215], v[40:43]
	v_mfma_f32_16x16x32_bf16 v[36:39], v[224:227], v[216:219], v[36:39]
	v_mfma_f32_16x16x32_bf16 v[32:35], v[224:227], v[220:223], v[32:35]
	s_waitcnt lgkmcnt(1)
	v_mfma_f32_16x16x32_bf16 v[28:31], v[228:231], v[208:211], v[28:31]
	v_mfma_f32_16x16x32_bf16 v[24:27], v[228:231], v[212:215], v[24:27]
	v_mfma_f32_16x16x32_bf16 v[20:23], v[228:231], v[216:219], v[20:23]
	v_mfma_f32_16x16x32_bf16 v[16:19], v[228:231], v[220:223], v[16:19]
	s_waitcnt lgkmcnt(0)
	v_mfma_f32_16x16x32_bf16 v[12:15], v[232:235], v[208:211], v[12:15]
	v_mfma_f32_16x16x32_bf16 v[8:11], v[232:235], v[212:215], v[8:11]
	v_mfma_f32_16x16x32_bf16 v[4:7], v[232:235], v[216:219], v[4:7]
	v_mfma_f32_16x16x32_bf16 v[0:3], v[232:235], v[220:223], v[0:3]
	s_setprio 2
	s_cmpk_eq_i32 s4, 0x780
	s_waitcnt vmcnt(0)
	s_barrier
	s_cbranch_scc0 .Lxk_259
.Lxk_exit_259:
	ds_read_b128 v[96:99], v122 offset:55296
	ds_read_b128 v[100:103], v122 offset:53248
	ds_read_b128 v[104:107], v123 offset:38912
	ds_read_b128 v[108:111], v123 offset:36864
	ds_read_b128 v[146:149], v122 offset:51200
	ds_read_b128 v[150:153], v122 offset:49152
	ds_read_b128 v[154:157], v123 offset:34816
	ds_read_b128 v[158:161], v123 offset:32768
	s_setprio 1
	s_waitcnt lgkmcnt(3)
	v_mfma_f32_16x16x32_bf16 v[24:27], v[108:111], v[146:149], v[24:27]
	v_mfma_f32_16x16x32_bf16 v[20:23], v[108:111], v[100:103], v[20:23]
	v_mfma_f32_16x16x32_bf16 v[16:19], v[108:111], v[96:99], v[16:19]
	s_waitcnt lgkmcnt(0)
	v_mfma_f32_16x16x32_bf16 v[60:63], v[158:161], v[150:153], v[60:63]
	v_mfma_f32_16x16x32_bf16 v[56:59], v[158:161], v[146:149], v[56:59]
	v_mfma_f32_16x16x32_bf16 v[52:55], v[158:161], v[100:103], v[52:55]
	v_mfma_f32_16x16x32_bf16 v[48:51], v[158:161], v[96:99], v[48:51]
	v_mfma_f32_16x16x32_bf16 v[44:47], v[154:157], v[150:153], v[44:47]
	v_mfma_f32_16x16x32_bf16 v[40:43], v[154:157], v[146:149], v[40:43]
	v_mfma_f32_16x16x32_bf16 v[36:39], v[154:157], v[100:103], v[36:39]
	v_mfma_f32_16x16x32_bf16 v[32:35], v[154:157], v[96:99], v[32:35]
	v_mfma_f32_16x16x32_bf16 v[28:31], v[108:111], v[150:153], v[28:31]
	v_mfma_f32_16x16x32_bf16 v[12:15], v[104:107], v[150:153], v[12:15]
	v_mfma_f32_16x16x32_bf16 v[8:11], v[104:107], v[146:149], v[8:11]
	v_mfma_f32_16x16x32_bf16 v[4:7], v[104:107], v[100:103], v[4:7]
	v_mfma_f32_16x16x32_bf16 v[0:3], v[104:107], v[96:99], v[0:3]
	s_setprio 0
	ds_read_b128 v[96:99], v124 offset:32768
	ds_read_b128 v[100:103], v124 offset:34816
	ds_read_b128 v[104:107], v125 offset:49152
	ds_read_b128 v[108:111], v125 offset:51200
	ds_read_b128 v[146:149], v124 offset:36864
	ds_read_b128 v[150:153], v124 offset:38912
	ds_read_b128 v[154:157], v125 offset:53248
	ds_read_b128 v[158:161], v125 offset:55296
	s_setprio 1
	s_waitcnt lgkmcnt(3)
	v_mfma_f32_16x16x32_bf16 v[24:27], v[146:149], v[108:111], v[24:27]
	s_waitcnt lgkmcnt(1)
	v_mfma_f32_16x16x32_bf16 v[20:23], v[146:149], v[154:157], v[20:23]
	s_waitcnt lgkmcnt(0)
	v_mfma_f32_16x16x32_bf16 v[16:19], v[146:149], v[158:161], v[16:19]
	v_mfma_f32_16x16x32_bf16 v[60:63], v[96:99], v[104:107], v[60:63]
	v_mfma_f32_16x16x32_bf16 v[56:59], v[96:99], v[108:111], v[56:59]
	v_mfma_f32_16x16x32_bf16 v[52:55], v[96:99], v[154:157], v[52:55]
	v_mfma_f32_16x16x32_bf16 v[48:51], v[96:99], v[158:161], v[48:51]
	v_mfma_f32_16x16x32_bf16 v[44:47], v[100:103], v[104:107], v[44:47]
	v_mfma_f32_16x16x32_bf16 v[40:43], v[100:103], v[108:111], v[40:43]
	v_mfma_f32_16x16x32_bf16 v[36:39], v[100:103], v[154:157], v[36:39]
	v_mfma_f32_16x16x32_bf16 v[32:35], v[100:103], v[158:161], v[32:35]
	v_mfma_f32_16x16x32_bf16 v[28:31], v[146:149], v[104:107], v[28:31]
	v_mfma_f32_16x16x32_bf16 v[12:15], v[150:153], v[104:107], v[12:15]
	v_mfma_f32_16x16x32_bf16 v[8:11], v[150:153], v[108:111], v[8:11]
	v_mfma_f32_16x16x32_bf16 v[4:7], v[150:153], v[154:157], v[4:7]
	v_mfma_f32_16x16x32_bf16 v[0:3], v[150:153], v[158:161], v[0:3]
	s_setprio 0
	s_barrier
	ds_write2_b32 v126, v60, v56 offset1:16
	ds_write2_b32 v126, v61, v57 offset0:132 offset1:148
	v_add_u32_e32 v56, 0x400, v126
	ds_write2_b32 v56, v62, v58 offset0:8 offset1:24
	ds_write2_b32 v56, v63, v59 offset0:140 offset1:156
	ds_write2_b32 v126, v52, v48 offset0:32 offset1:48
	ds_write2_b32 v126, v53, v49 offset0:164 offset1:180
	ds_write2_b32 v56, v54, v50 offset0:40 offset1:56
	ds_write2_b32 v56, v55, v51 offset0:172 offset1:188
	v_add_u32_e32 v48, 0x2000, v126
	ds_write2_b32 v48, v44, v40 offset0:64 offset1:80
	ds_write2_b32 v48, v45, v41 offset0:196 offset1:212
	v_add_u32_e32 v40, 0x2400, v126
	ds_write2_b32 v40, v46, v42 offset0:72 offset1:88
	ds_write2_b32 v40, v47, v43 offset0:204 offset1:220
	ds_write2_b32 v48, v36, v32 offset0:96 offset1:112
	ds_write2_b32 v48, v37, v33 offset0:228 offset1:244
	ds_write2_b32 v40, v38, v34 offset0:104 offset1:120
	ds_write2_b32 v40, v39, v35 offset0:236 offset1:252
	v_add_u32_e32 v32, 0x4000, v126
	ds_write2_b32 v32, v28, v24 offset0:128 offset1:144
	v_add_u32_e32 v24, 0x4400, v126
	ds_write2_b32 v24, v29, v25 offset0:4 offset1:20
	ds_write2_b32 v24, v30, v26 offset0:136 offset1:152
	v_add_u32_e32 v25, 0x4800, v126
	ds_write2_b32 v25, v31, v27 offset0:12 offset1:28
	ds_write2_b32 v32, v20, v16 offset0:160 offset1:176
	ds_write2_b32 v24, v21, v17 offset0:36 offset1:52
	ds_write2_b32 v24, v22, v18 offset0:168 offset1:184
	ds_write2_b32 v25, v23, v19 offset0:44 offset1:60
	v_add_u32_e32 v16, 0x6000, v126
	ds_write2_b32 v16, v12, v8 offset0:192 offset1:208
	v_add_u32_e32 v8, 0x6400, v126
	ds_write2_b32 v8, v13, v9 offset0:68 offset1:84
	ds_write2_b32 v8, v14, v10 offset0:200 offset1:216
	v_add_u32_e32 v9, 0x6800, v126
	v_or_b32_e32 v64, s6, v127
	ds_write2_b32 v9, v15, v11 offset0:76 offset1:92
	ds_write2_b32 v16, v4, v0 offset0:224 offset1:240
	ds_write2_b32 v8, v5, v1 offset0:100 offset1:116
	ds_write2_b32 v8, v6, v2 offset0:232 offset1:248
	ds_write2_b32 v9, v7, v3 offset0:108 offset1:124
	v_ashrrev_i32_e32 v1, 31, v64
	v_mov_b32_e32 v0, v64
	v_lshlrev_b64 v[2:3], 1, v[64:65]
	v_lshl_add_u64 v[20:21], v[0:1], 1, s[10:11]
	v_mov_b32_e32 v0, s15
	v_mov_b32_e32 v1, s13
	v_cmp_gt_i32_e64 s[8:9], s38, v64
	v_lshl_add_u64 v[16:17], s[18:19], 0, v[2:3]
	v_lshl_add_u64 v[18:19], s[16:17], 0, v[2:3]
	v_cndmask_b32_e64 v1, v0, v1, s[8:9]
	v_mov_b32_e32 v0, s14
	v_mov_b32_e32 v2, s12
	v_cndmask_b32_e64 v0, v0, v2, s[8:9]
	v_mov_b32_e32 v95, v65
	v_cmp_lt_i32_e64 s[4:5], s39, v64
	v_cmp_lt_i32_e64 s[6:7], s40, v64
	v_lshl_add_u64 v[22:23], v[0:1], 0, v[94:95]
	v_add_u32_e32 v24, s30, v135
	s_mov_b32 s45, 0
	s_waitcnt lgkmcnt(0)
	s_barrier
	s_branch .LBB0_263

.LBB0_277:
	s_add_i32 s4, s30, 0xffffff70
	s_cmpk_lt_i32 s30, 0x90
	s_cselect_b32 s5, 8, 4
	v_cvt_f32_ubyte0_e32 v0, s5
	v_rcp_iflag_f32_e32 v0, v0
	s_cselect_b32 s7, 0, 0x400
	s_cselect_b32 s4, s30, s4
	s_cselect_b32 s6, 3, 2
	v_mul_f32_e32 v0, 0x4f7ffffe, v0
	v_cvt_u32_f32_e32 v0, v0
	s_sub_i32 s20, 0, s5
	s_abs_i32 s9, s4
	s_ashr_i32 s8, s4, 31
	v_readfirstlane_b32 s21, v0
	s_mul_i32 s20, s20, s21
	s_mul_hi_u32 s20, s21, s20
	s_add_i32 s21, s21, s20
	s_mul_hi_u32 s20, s9, s21
	s_mul_i32 s21, s20, s5
	s_sub_i32 s9, s9, s21
	s_add_i32 s21, s20, 1
	s_sub_i32 s22, s9, s5
	s_cmp_ge_u32 s9, s5
	s_cselect_b32 s20, s21, s20
	s_cselect_b32 s9, s22, s9
	s_add_i32 s21, s20, 1
	s_cmp_ge_u32 s9, s5
	s_cselect_b32 s5, s21, s20
	s_xor_b32 s5, s5, s8
	s_sub_i32 s5, s5, s8
	s_lshl_b32 s8, s5, s6
	s_sub_i32 s6, s4, s8
	s_lshl_b32 s6, s6, 7
	v_add_u32_e32 v0, s5, v112
	s_add_i32 s6, s6, s7
	v_lshlrev_b32_e32 v143, 7, v0
	v_add_u32_e32 v0, s6, v113
	v_ashrrev_i32_e32 v1, 31, v0
	v_add_u32_e32 v2, 0x4000, v114
	v_lshlrev_b64 v[0:1], 11, v[0:1]
	v_readfirstlane_b32 s5, v2
	v_lshl_add_u64 v[0:1], v[66:67], 0, v[0:1]
	s_mov_b32 m0, s5
	v_readfirstlane_b32 s5, v114
	global_load_lds_dwordx4 v[0:1], off
	v_add_u32_e32 v0, v143, v113
	v_ashrrev_i32_e32 v1, 31, v0
	v_lshlrev_b64 v[0:1], 11, v[0:1]
	v_lshl_add_u64 v[2:3], v[72:73], 0, v[0:1]
	s_mov_b32 m0, s5
	v_readfirstlane_b32 s5, v134
	global_load_lds_dwordx4 v[2:3], off
	v_add_u32_e32 v2, s6, v115
	v_ashrrev_i32_e32 v3, 31, v2
	v_lshlrev_b64 v[2:3], 11, v[2:3]
	v_lshl_add_u64 v[2:3], v[68:69], 0, v[2:3]
	s_mov_b32 m0, s5
	v_add_u32_e32 v4, 0x400, v114
	global_load_lds_dwordx4 v[2:3], off
	v_add_u32_e32 v2, v143, v115
	v_ashrrev_i32_e32 v3, 31, v2
	v_lshlrev_b64 v[2:3], 11, v[2:3]
	v_readfirstlane_b32 s5, v4
	v_lshl_add_u64 v[2:3], v[74:75], 0, v[2:3]
	s_mov_b32 m0, s5
	v_readfirstlane_b32 s5, v135
	global_load_lds_dwordx4 v[2:3], off
	v_add_u32_e32 v2, s6, v117
	v_ashrrev_i32_e32 v3, 31, v2
	v_lshlrev_b64 v[2:3], 11, v[2:3]
	v_lshl_add_u64 v[2:3], v[66:67], 0, v[2:3]
	s_mov_b32 m0, s5
	v_add_u32_e32 v4, 0x800, v114
	global_load_lds_dwordx4 v[2:3], off
	v_add_u32_e32 v2, v143, v117
	v_ashrrev_i32_e32 v3, 31, v2
	v_lshlrev_b64 v[2:3], 11, v[2:3]
	v_readfirstlane_b32 s5, v4
	v_lshl_add_u64 v[2:3], v[72:73], 0, v[2:3]
	s_mov_b32 m0, s5
	v_readfirstlane_b32 s5, v136
	global_load_lds_dwordx4 v[2:3], off
	v_add_u32_e32 v2, s6, v119
	v_ashrrev_i32_e32 v3, 31, v2
	v_lshlrev_b64 v[2:3], 11, v[2:3]
	v_lshl_add_u64 v[2:3], v[70:71], 0, v[2:3]
	s_mov_b32 m0, s5
	v_add_u32_e32 v4, 0xc00, v114
	global_load_lds_dwordx4 v[2:3], off
	v_add_u32_e32 v2, v143, v119
	v_ashrrev_i32_e32 v3, 31, v2
	v_lshlrev_b64 v[2:3], 11, v[2:3]
	v_readfirstlane_b32 s5, v4
	v_lshl_add_u64 v[2:3], v[76:77], 0, v[2:3]
	s_mov_b32 m0, s5
	s_lshl_b32 s4, s4, 7
	global_load_lds_dwordx4 v[2:3], off
	s_add_i32 s4, s4, s7
	s_lshl_b32 s5, s8, 7
	v_lshl_add_u64 v[98:99], v[84:85], 0, v[0:1]
	v_add_u32_e32 v0, s4, v129
	v_subrev_u32_e32 v0, s5, v0
	v_ashrrev_i32_e32 v1, 31, v0
	v_lshlrev_b64 v[0:1], 11, v[0:1]
	v_lshl_add_u64 v[100:101], v[86:87], 0, v[0:1]
	v_add_u32_e32 v0, v129, v143
	v_ashrrev_i32_e32 v1, 31, v0
	v_lshlrev_b64 v[0:1], 11, v[0:1]
	v_lshl_add_u64 v[102:103], v[88:89], 0, v[0:1]
	v_add_u32_e32 v0, s4, v130
	v_subrev_u32_e32 v0, s5, v0
	v_ashrrev_i32_e32 v1, 31, v0
	v_lshlrev_b64 v[0:1], 11, v[0:1]
	v_lshl_add_u64 v[104:105], v[82:83], 0, v[0:1]
	v_add_u32_e32 v0, v130, v143
	v_ashrrev_i32_e32 v1, 31, v0
	v_lshlrev_b64 v[0:1], 11, v[0:1]
	v_lshl_add_u64 v[106:107], v[84:85], 0, v[0:1]
	v_add_u32_e32 v0, s4, v131
	v_subrev_u32_e32 v0, s5, v0
	v_ashrrev_i32_e32 v1, 31, v0
	v_lshlrev_b64 v[0:1], 11, v[0:1]
	v_add_u32_e32 v2, s4, v113
	v_lshl_add_u64 v[108:109], v[90:91], 0, v[0:1]
	v_add_u32_e32 v0, v131, v143
	v_subrev_u32_e32 v2, s5, v2
	v_ashrrev_i32_e32 v1, 31, v0
	v_ashrrev_i32_e32 v3, 31, v2
	v_lshlrev_b64 v[0:1], 11, v[0:1]
	v_lshlrev_b64 v[2:3], 11, v[2:3]
	v_lshl_add_u64 v[110:111], v[92:93], 0, v[0:1]
	v_mov_b32_e32 v0, 0
	v_lshl_add_u64 v[96:97], v[82:83], 0, v[2:3]
	s_mov_b64 s[4:5], 0
	s_mov_b32 s7, 0
	v_mov_b32_e32 v1, v0
	v_mov_b32_e32 v2, v0
	v_mov_b32_e32 v3, v0
	v_mov_b32_e32 v4, v0
	v_mov_b32_e32 v5, v0
	v_mov_b32_e32 v6, v0
	v_mov_b32_e32 v7, v0
	v_mov_b32_e32 v8, v0
	v_mov_b32_e32 v9, v0
	v_mov_b32_e32 v10, v0
	v_mov_b32_e32 v11, v0
	v_mov_b32_e32 v12, v0
	v_mov_b32_e32 v13, v0
	v_mov_b32_e32 v14, v0
	v_mov_b32_e32 v15, v0
	v_mov_b32_e32 v16, v0
	v_mov_b32_e32 v17, v0
	v_mov_b32_e32 v18, v0
	v_mov_b32_e32 v19, v0
	v_mov_b32_e32 v20, v0
	v_mov_b32_e32 v21, v0
	v_mov_b32_e32 v22, v0
	v_mov_b32_e32 v23, v0
	v_mov_b32_e32 v24, v0
	v_mov_b32_e32 v25, v0
	v_mov_b32_e32 v26, v0
	v_mov_b32_e32 v27, v0
	v_mov_b32_e32 v28, v0
	v_mov_b32_e32 v29, v0
	v_mov_b32_e32 v30, v0
	v_mov_b32_e32 v31, v0
	v_mov_b32_e32 v32, v0
	v_mov_b32_e32 v33, v0
	v_mov_b32_e32 v34, v0
	v_mov_b32_e32 v35, v0
	v_mov_b32_e32 v36, v0
	v_mov_b32_e32 v37, v0
	v_mov_b32_e32 v38, v0
	v_mov_b32_e32 v39, v0
	v_mov_b32_e32 v40, v0
	v_mov_b32_e32 v41, v0
	v_mov_b32_e32 v42, v0
	v_mov_b32_e32 v43, v0
	v_mov_b32_e32 v44, v0
	v_mov_b32_e32 v45, v0
	v_mov_b32_e32 v46, v0
	v_mov_b32_e32 v47, v0
	v_mov_b32_e32 v48, v0
	v_mov_b32_e32 v49, v0
	v_mov_b32_e32 v50, v0
	v_mov_b32_e32 v51, v0
	v_mov_b32_e32 v52, v0
	v_mov_b32_e32 v53, v0
	v_mov_b32_e32 v54, v0
	v_mov_b32_e32 v55, v0
	v_mov_b32_e32 v56, v0
	v_mov_b32_e32 v57, v0
	v_mov_b32_e32 v58, v0
	v_mov_b32_e32 v59, v0
	v_mov_b32_e32 v60, v0
	v_mov_b32_e32 v61, v0
	v_mov_b32_e32 v62, v0
	v_mov_b32_e32 v63, v0
	s_waitcnt vmcnt(0) lgkmcnt(0)
	s_barrier
	v_add3_u32 v182, 0, v137, v138
	v_add_u32_e32 v183, 0x4000, v182
	s_nop 0
	v_readfirstlane_b32 s82, v183
	v_lshl_add_u32 v183, v116, 1, 0
	s_nop 0
	v_readfirstlane_b32 s83, v182
	v_add3_u32 v183, v183, v138, s25
	s_nop 0
	v_readfirstlane_b32 s84, v183
	v_add_u32_e32 v183, 0x400, v182
	s_nop 0
	v_readfirstlane_b32 s85, v183
	v_lshl_add_u32 v183, v118, 1, 0
	v_add3_u32 v183, v183, v138, s25
	s_nop 0
	v_readfirstlane_b32 s86, v183
	v_add_u32_e32 v183, 0x800, v182
	s_nop 0
	v_readfirstlane_b32 s87, v183
	v_lshl_add_u32 v183, v120, 1, 0
	v_add3_u32 v183, v183, v138, s25
	s_nop 0
	v_readfirstlane_b32 s88, v183
	v_add_u32_e32 v182, 0xc00, v182
	s_nop 0
	v_readfirstlane_b32 s89, v182
	v_subrev_u32_e32 v184, s52, v96
	v_subrev_u32_e32 v185, s52, v98
	v_subrev_u32_e32 v186, s52, v100
	v_subrev_u32_e32 v187, s52, v102
	v_subrev_u32_e32 v188, s52, v104
	v_subrev_u32_e32 v189, s52, v106
	v_subrev_u32_e32 v190, s52, v108
	v_subrev_u32_e32 v191, s52, v110
	s_bitcmp1_b32 s32, 0
	s_cbranch_scc1 .Lxk_278
.LBB0_278:
	s_and_b32 s8, s7, 0x4000
	s_xor_b32 s9, s8, 0x4000
	s_lshl_b32 s9, s9, 1
	s_add_i32 s9, s9, 32
	s_add_u32 s90, s52, s4
	s_addc_u32 s91, s53, s5
	s_add_i32 m0, s9, s82
	s_lshl_b32 s8, s8, 1
	global_load_lds_dwordx4 v184, s[90:91]
	s_add_i32 m0, s9, s83
	s_add_i32 s8, s8, 32
	global_load_lds_dwordx4 v185, s[90:91]
	s_add_i32 m0, s9, s84
	v_lshl_add_u32 v64, v121, 1, s8
	global_load_lds_dwordx4 v186, s[90:91]
	s_add_i32 m0, s9, s85
	v_lshl_add_u32 v95, v122, 1, s8
	global_load_lds_dwordx4 v187, s[90:91]
	s_add_i32 m0, s9, s86
	v_add_u32_e32 v164, v64, v139
	global_load_lds_dwordx4 v188, s[90:91]
	s_add_i32 m0, s9, s87
	v_add_u32_e32 v172, v95, v139
	global_load_lds_dwordx4 v189, s[90:91]
	s_add_i32 m0, s9, s88
	s_addk_i32 s7, 0x4000
	global_load_lds_dwordx4 v190, s[90:91]
	s_add_i32 m0, s9, s89
	s_add_u32 s4, s4, 0x80
	s_addc_u32 s5, s5, 0
	global_load_lds_dwordx4 v191, s[90:91]
	ds_read_b128 v[144:147], v164
	ds_read_b128 v[152:155], v172 offset:16384
	ds_read_b128 v[156:159], v172 offset:18432
	ds_read_b128 v[168:171], v172 offset:20480
	ds_read_b128 v[172:175], v172 offset:22528
	ds_read_b128 v[148:151], v164 offset:2048
	ds_read_b128 v[160:163], v164 offset:4096
	ds_read_b128 v[164:167], v164 offset:6144
	v_add_u32_e32 v64, v64, v140
	v_add_u32_e32 v95, v95, v140
	ds_read_b128 v[204:207], v64
	ds_read_b128 v[208:211], v95 offset:16384
	ds_read_b128 v[212:215], v95 offset:18432
	ds_read_b128 v[216:219], v95 offset:20480
	ds_read_b128 v[220:223], v95 offset:22528
	ds_read_b128 v[224:227], v64 offset:2048
	ds_read_b128 v[228:231], v64 offset:4096
	ds_read_b128 v[232:235], v64 offset:6144
	s_setprio 1
	s_waitcnt lgkmcnt(11)
	v_mfma_f32_16x16x32_bf16 v[60:63], v[144:147], v[152:155], v[60:63]
	v_mfma_f32_16x16x32_bf16 v[56:59], v[144:147], v[156:159], v[56:59]
	v_mfma_f32_16x16x32_bf16 v[52:55], v[144:147], v[168:171], v[52:55]
	v_mfma_f32_16x16x32_bf16 v[48:51], v[144:147], v[172:175], v[48:51]
	s_waitcnt lgkmcnt(10)
	v_mfma_f32_16x16x32_bf16 v[44:47], v[148:151], v[152:155], v[44:47]
	v_mfma_f32_16x16x32_bf16 v[40:43], v[148:151], v[156:159], v[40:43]
	v_mfma_f32_16x16x32_bf16 v[36:39], v[148:151], v[168:171], v[36:39]
	v_mfma_f32_16x16x32_bf16 v[32:35], v[148:151], v[172:175], v[32:35]
	s_waitcnt lgkmcnt(9)
	v_mfma_f32_16x16x32_bf16 v[28:31], v[160:163], v[152:155], v[28:31]
	v_mfma_f32_16x16x32_bf16 v[24:27], v[160:163], v[156:159], v[24:27]
	v_mfma_f32_16x16x32_bf16 v[20:23], v[160:163], v[168:171], v[20:23]
	v_mfma_f32_16x16x32_bf16 v[16:19], v[160:163], v[172:175], v[16:19]
	s_waitcnt lgkmcnt(8)
	v_mfma_f32_16x16x32_bf16 v[12:15], v[164:167], v[152:155], v[12:15]
	v_mfma_f32_16x16x32_bf16 v[8:11], v[164:167], v[156:159], v[8:11]
	v_mfma_f32_16x16x32_bf16 v[4:7], v[164:167], v[168:171], v[4:7]
	v_mfma_f32_16x16x32_bf16 v[0:3], v[164:167], v[172:175], v[0:3]
	s_waitcnt lgkmcnt(3)
	v_mfma_f32_16x16x32_bf16 v[60:63], v[204:207], v[208:211], v[60:63]
	v_mfma_f32_16x16x32_bf16 v[56:59], v[204:207], v[212:215], v[56:59]
	v_mfma_f32_16x16x32_bf16 v[52:55], v[204:207], v[216:219], v[52:55]
	v_mfma_f32_16x16x32_bf16 v[48:51], v[204:207], v[220:223], v[48:51]
	s_waitcnt lgkmcnt(2)
	v_mfma_f32_16x16x32_bf16 v[44:47], v[224:227], v[208:211], v[44:47]
	v_mfma_f32_16x16x32_bf16 v[40:43], v[224:227], v[212:215], v[40:43]
	v_mfma_f32_16x16x32_bf16 v[36:39], v[224:227], v[216:219], v[36:39]
	v_mfma_f32_16x16x32_bf16 v[32:35], v[224:227], v[220:223], v[32:35]
	s_waitcnt lgkmcnt(1)
	v_mfma_f32_16x16x32_bf16 v[28:31], v[228:231], v[208:211], v[28:31]
	v_mfma_f32_16x16x32_bf16 v[24:27], v[228:231], v[212:215], v[24:27]
	v_mfma_f32_16x16x32_bf16 v[20:23], v[228:231], v[216:219], v[20:23]
	v_mfma_f32_16x16x32_bf16 v[16:19], v[228:231], v[220:223], v[16:19]
	s_waitcnt lgkmcnt(0)
	v_mfma_f32_16x16x32_bf16 v[12:15], v[232:235], v[208:211], v[12:15]
	v_mfma_f32_16x16x32_bf16 v[8:11], v[232:235], v[212:215], v[8:11]
	v_mfma_f32_16x16x32_bf16 v[4:7], v[232:235], v[216:219], v[4:7]
	v_mfma_f32_16x16x32_bf16 v[0:3], v[232:235], v[220:223], v[0:3]
	s_setprio 0
	s_cmpk_eq_i32 s4, 0x780
	s_waitcnt vmcnt(0)
	s_barrier
	s_cbranch_scc0 .LBB0_278
	s_branch .Lxk_exit_278
.Lxk_278:
	s_and_b32 s8, s7, 0x4000
	s_xor_b32 s9, s8, 0x4000
	s_lshl_b32 s9, s9, 1
	s_add_i32 s9, s9, 32
	s_add_u32 s90, s52, s4
	s_addc_u32 s91, s53, s5
	s_add_i32 m0, s9, s82
	s_lshl_b32 s8, s8, 1
	global_load_lds_dwordx4 v184, s[90:91]
	s_add_i32 m0, s9, s83
	s_add_i32 s8, s8, 32
	global_load_lds_dwordx4 v185, s[90:91]
	s_add_i32 m0, s9, s84
	v_lshl_add_u32 v64, v121, 1, s8
	global_load_lds_dwordx4 v186, s[90:91]
	s_add_i32 m0, s9, s85
	v_lshl_add_u32 v95, v122, 1, s8
	global_load_lds_dwordx4 v187, s[90:91]
	s_add_i32 m0, s9, s86
	v_add_u32_e32 v164, v64, v139
	global_load_lds_dwordx4 v188, s[90:91]
	s_add_i32 m0, s9, s87
	v_add_u32_e32 v172, v95, v139
	global_load_lds_dwordx4 v189, s[90:91]
	s_add_i32 m0, s9, s88
	s_addk_i32 s7, 0x4000
	global_load_lds_dwordx4 v190, s[90:91]
	s_add_i32 m0, s9, s89
	s_add_u32 s4, s4, 0x80
	s_addc_u32 s5, s5, 0
	global_load_lds_dwordx4 v191, s[90:91]
	ds_read_b128 v[144:147], v164
	ds_read_b128 v[152:155], v172 offset:16384
	ds_read_b128 v[156:159], v172 offset:18432
	ds_read_b128 v[168:171], v172 offset:20480
	ds_read_b128 v[172:175], v172 offset:22528
	ds_read_b128 v[148:151], v164 offset:2048
	ds_read_b128 v[160:163], v164 offset:4096
	ds_read_b128 v[164:167], v164 offset:6144
	v_add_u32_e32 v64, v64, v140
	v_add_u32_e32 v95, v95, v140
	ds_read_b128 v[204:207], v64
	ds_read_b128 v[208:211], v95 offset:16384
	ds_read_b128 v[212:215], v95 offset:18432
	ds_read_b128 v[216:219], v95 offset:20480
	ds_read_b128 v[220:223], v95 offset:22528
	ds_read_b128 v[224:227], v64 offset:2048
	ds_read_b128 v[228:231], v64 offset:4096
	ds_read_b128 v[232:235], v64 offset:6144
	s_setprio 3
	s_waitcnt lgkmcnt(11)
	v_mfma_f32_16x16x32_bf16 v[60:63], v[144:147], v[152:155], v[60:63]
	v_mfma_f32_16x16x32_bf16 v[56:59], v[144:147], v[156:159], v[56:59]
	v_mfma_f32_16x16x32_bf16 v[52:55], v[144:147], v[168:171], v[52:55]
	v_mfma_f32_16x16x32_bf16 v[48:51], v[144:147], v[172:175], v[48:51]
	s_waitcnt lgkmcnt(10)
	v_mfma_f32_16x16x32_bf16 v[44:47], v[148:151], v[152:155], v[44:47]
	v_mfma_f32_16x16x32_bf16 v[40:43], v[148:151], v[156:159], v[40:43]
	v_mfma_f32_16x16x32_bf16 v[36:39], v[148:151], v[168:171], v[36:39]
	v_mfma_f32_16x16x32_bf16 v[32:35], v[148:151], v[172:175], v[32:35]
	s_waitcnt lgkmcnt(9)
	v_mfma_f32_16x16x32_bf16 v[28:31], v[160:163], v[152:155], v[28:31]
	v_mfma_f32_16x16x32_bf16 v[24:27], v[160:163], v[156:159], v[24:27]
	v_mfma_f32_16x16x32_bf16 v[20:23], v[160:163], v[168:171], v[20:23]
	v_mfma_f32_16x16x32_bf16 v[16:19], v[160:163], v[172:175], v[16:19]
	s_waitcnt lgkmcnt(8)
	v_mfma_f32_16x16x32_bf16 v[12:15], v[164:167], v[152:155], v[12:15]
	v_mfma_f32_16x16x32_bf16 v[8:11], v[164:167], v[156:159], v[8:11]
	v_mfma_f32_16x16x32_bf16 v[4:7], v[164:167], v[168:171], v[4:7]
	v_mfma_f32_16x16x32_bf16 v[0:3], v[164:167], v[172:175], v[0:3]
	s_waitcnt lgkmcnt(3)
	v_mfma_f32_16x16x32_bf16 v[60:63], v[204:207], v[208:211], v[60:63]
	v_mfma_f32_16x16x32_bf16 v[56:59], v[204:207], v[212:215], v[56:59]
	v_mfma_f32_16x16x32_bf16 v[52:55], v[204:207], v[216:219], v[52:55]
	v_mfma_f32_16x16x32_bf16 v[48:51], v[204:207], v[220:223], v[48:51]
	s_waitcnt lgkmcnt(2)
	v_mfma_f32_16x16x32_bf16 v[44:47], v[224:227], v[208:211], v[44:47]
	v_mfma_f32_16x16x32_bf16 v[40:43], v[224:227], v[212:215], v[40:43]
	v_mfma_f32_16x16x32_bf16 v[36:39], v[224:227], v[216:219], v[36:39]
	v_mfma_f32_16x16x32_bf16 v[32:35], v[224:227], v[220:223], v[32:35]
	s_waitcnt lgkmcnt(1)
	v_mfma_f32_16x16x32_bf16 v[28:31], v[228:231], v[208:211], v[28:31]
	v_mfma_f32_16x16x32_bf16 v[24:27], v[228:231], v[212:215], v[24:27]
	v_mfma_f32_16x16x32_bf16 v[20:23], v[228:231], v[216:219], v[20:23]
	v_mfma_f32_16x16x32_bf16 v[16:19], v[228:231], v[220:223], v[16:19]
	s_waitcnt lgkmcnt(0)
	v_mfma_f32_16x16x32_bf16 v[12:15], v[232:235], v[208:211], v[12:15]
	v_mfma_f32_16x16x32_bf16 v[8:11], v[232:235], v[212:215], v[8:11]
	v_mfma_f32_16x16x32_bf16 v[4:7], v[232:235], v[216:219], v[4:7]
	v_mfma_f32_16x16x32_bf16 v[0:3], v[232:235], v[220:223], v[0:3]
	s_setprio 2
	s_cmpk_eq_i32 s4, 0x780
	s_waitcnt vmcnt(0)
	s_barrier
	s_cbranch_scc0 .Lxk_278
.Lxk_exit_278:
	ds_read_b128 v[96:99], v123 offset:55296
	ds_read_b128 v[100:103], v123 offset:53248
	ds_read_b128 v[104:107], v124 offset:38912
	ds_read_b128 v[108:111], v124 offset:36864
	ds_read_b128 v[144:147], v123 offset:51200
	ds_read_b128 v[148:151], v123 offset:49152
	ds_read_b128 v[152:155], v124 offset:34816
	ds_read_b128 v[156:159], v124 offset:32768
	s_setprio 1
	s_waitcnt lgkmcnt(3)
	v_mfma_f32_16x16x32_bf16 v[24:27], v[108:111], v[144:147], v[24:27]
	v_mfma_f32_16x16x32_bf16 v[20:23], v[108:111], v[100:103], v[20:23]
	v_mfma_f32_16x16x32_bf16 v[16:19], v[108:111], v[96:99], v[16:19]
	s_waitcnt lgkmcnt(0)
	v_mfma_f32_16x16x32_bf16 v[60:63], v[156:159], v[148:151], v[60:63]
	v_mfma_f32_16x16x32_bf16 v[56:59], v[156:159], v[144:147], v[56:59]
	v_mfma_f32_16x16x32_bf16 v[52:55], v[156:159], v[100:103], v[52:55]
	v_mfma_f32_16x16x32_bf16 v[48:51], v[156:159], v[96:99], v[48:51]
	v_mfma_f32_16x16x32_bf16 v[44:47], v[152:155], v[148:151], v[44:47]
	v_mfma_f32_16x16x32_bf16 v[40:43], v[152:155], v[144:147], v[40:43]
	v_mfma_f32_16x16x32_bf16 v[36:39], v[152:155], v[100:103], v[36:39]
	v_mfma_f32_16x16x32_bf16 v[32:35], v[152:155], v[96:99], v[32:35]
	v_mfma_f32_16x16x32_bf16 v[28:31], v[108:111], v[148:151], v[28:31]
	v_mfma_f32_16x16x32_bf16 v[12:15], v[104:107], v[148:151], v[12:15]
	v_mfma_f32_16x16x32_bf16 v[8:11], v[104:107], v[144:147], v[8:11]
	v_mfma_f32_16x16x32_bf16 v[4:7], v[104:107], v[100:103], v[4:7]
	v_mfma_f32_16x16x32_bf16 v[0:3], v[104:107], v[96:99], v[0:3]
	s_setprio 0
	ds_read_b128 v[96:99], v125 offset:32768
	ds_read_b128 v[100:103], v125 offset:34816
	ds_read_b128 v[104:107], v126 offset:49152
	ds_read_b128 v[108:111], v126 offset:51200
	ds_read_b128 v[144:147], v125 offset:36864
	ds_read_b128 v[148:151], v125 offset:38912
	ds_read_b128 v[152:155], v126 offset:53248
	ds_read_b128 v[156:159], v126 offset:55296
	s_setprio 1
	s_waitcnt lgkmcnt(3)
	v_mfma_f32_16x16x32_bf16 v[24:27], v[144:147], v[108:111], v[24:27]
	s_waitcnt lgkmcnt(1)
	v_mfma_f32_16x16x32_bf16 v[20:23], v[144:147], v[152:155], v[20:23]
	s_waitcnt lgkmcnt(0)
	v_mfma_f32_16x16x32_bf16 v[16:19], v[144:147], v[156:159], v[16:19]
	v_mfma_f32_16x16x32_bf16 v[60:63], v[96:99], v[104:107], v[60:63]
	v_mfma_f32_16x16x32_bf16 v[56:59], v[96:99], v[108:111], v[56:59]
	v_mfma_f32_16x16x32_bf16 v[52:55], v[96:99], v[152:155], v[52:55]
	v_mfma_f32_16x16x32_bf16 v[48:51], v[96:99], v[156:159], v[48:51]
	v_mfma_f32_16x16x32_bf16 v[44:47], v[100:103], v[104:107], v[44:47]
	v_mfma_f32_16x16x32_bf16 v[40:43], v[100:103], v[108:111], v[40:43]
	v_mfma_f32_16x16x32_bf16 v[36:39], v[100:103], v[152:155], v[36:39]
	v_mfma_f32_16x16x32_bf16 v[32:35], v[100:103], v[156:159], v[32:35]
	v_mfma_f32_16x16x32_bf16 v[28:31], v[144:147], v[104:107], v[28:31]
	v_mfma_f32_16x16x32_bf16 v[12:15], v[148:151], v[104:107], v[12:15]
	v_mfma_f32_16x16x32_bf16 v[8:11], v[148:151], v[108:111], v[8:11]
	v_mfma_f32_16x16x32_bf16 v[4:7], v[148:151], v[152:155], v[4:7]
	v_mfma_f32_16x16x32_bf16 v[0:3], v[148:151], v[156:159], v[0:3]
	s_setprio 0
	s_barrier
	ds_write2_b32 v127, v60, v56 offset1:16
	ds_write2_b32 v127, v61, v57 offset0:132 offset1:148
	v_add_u32_e32 v56, 0x400, v127
	ds_write2_b32 v56, v62, v58 offset0:8 offset1:24
	ds_write2_b32 v56, v63, v59 offset0:140 offset1:156
	ds_write2_b32 v127, v52, v48 offset0:32 offset1:48
	ds_write2_b32 v127, v53, v49 offset0:164 offset1:180
	ds_write2_b32 v56, v54, v50 offset0:40 offset1:56
	ds_write2_b32 v56, v55, v51 offset0:172 offset1:188
	v_add_u32_e32 v48, 0x2000, v127
	ds_write2_b32 v48, v44, v40 offset0:64 offset1:80
	ds_write2_b32 v48, v45, v41 offset0:196 offset1:212
	v_add_u32_e32 v40, 0x2400, v127
	ds_write2_b32 v40, v46, v42 offset0:72 offset1:88
	ds_write2_b32 v40, v47, v43 offset0:204 offset1:220
	ds_write2_b32 v48, v36, v32 offset0:96 offset1:112
	ds_write2_b32 v48, v37, v33 offset0:228 offset1:244
	ds_write2_b32 v40, v38, v34 offset0:104 offset1:120
	ds_write2_b32 v40, v39, v35 offset0:236 offset1:252
	v_add_u32_e32 v32, 0x4000, v127
	ds_write2_b32 v32, v28, v24 offset0:128 offset1:144
	v_add_u32_e32 v24, 0x4400, v127
	ds_write2_b32 v24, v29, v25 offset0:4 offset1:20
	ds_write2_b32 v24, v30, v26 offset0:136 offset1:152
	v_add_u32_e32 v25, 0x4800, v127
	ds_write2_b32 v25, v31, v27 offset0:12 offset1:28
	ds_write2_b32 v32, v20, v16 offset0:160 offset1:176
	ds_write2_b32 v24, v21, v17 offset0:36 offset1:52
	ds_write2_b32 v24, v22, v18 offset0:168 offset1:184
	ds_write2_b32 v25, v23, v19 offset0:44 offset1:60
	v_add_u32_e32 v16, 0x6000, v127
	ds_write2_b32 v16, v12, v8 offset0:192 offset1:208
	v_add_u32_e32 v8, 0x6400, v127
	ds_write2_b32 v8, v13, v9 offset0:68 offset1:84
	ds_write2_b32 v8, v14, v10 offset0:200 offset1:216
	v_add_u32_e32 v9, 0x6800, v127
	v_or_b32_e32 v64, s6, v128
	ds_write2_b32 v9, v15, v11 offset0:76 offset1:92
	ds_write2_b32 v16, v4, v0 offset0:224 offset1:240
	ds_write2_b32 v8, v5, v1 offset0:100 offset1:116
	ds_write2_b32 v8, v6, v2 offset0:232 offset1:248
	ds_write2_b32 v9, v7, v3 offset0:108 offset1:124
	v_ashrrev_i32_e32 v1, 31, v64
	v_mov_b32_e32 v0, v64
	v_lshlrev_b64 v[2:3], 1, v[64:65]
	v_lshl_add_u64 v[20:21], v[0:1], 1, s[10:11]
	v_mov_b32_e32 v0, s15
	v_mov_b32_e32 v1, s13
	v_cmp_gt_i32_e64 s[8:9], s24, v64
	v_lshl_add_u64 v[16:17], s[18:19], 0, v[2:3]
	v_lshl_add_u64 v[18:19], s[16:17], 0, v[2:3]
	v_cndmask_b32_e64 v1, v0, v1, s[8:9]
	v_mov_b32_e32 v0, s14
	v_mov_b32_e32 v2, s12
	v_cndmask_b32_e64 v0, v0, v2, s[8:9]
	v_mov_b32_e32 v95, v65
	v_cmp_lt_i32_e64 s[4:5], s26, v64
	v_cmp_lt_i32_e64 s[6:7], s27, v64
	v_lshl_add_u64 v[22:23], v[0:1], 0, v[94:95]
	v_add_u32_e32 v24, v132, v143
	s_mov_b32 s35, 0
	s_waitcnt lgkmcnt(0)
	s_barrier
	s_branch .LBB0_282

.LBB0_422:
	s_ashr_i32 s14, s21, 31
	s_lshr_b32 s14, s14, 29
	s_add_i32 s14, s21, s14
	s_ashr_i32 s14, s14, 3
	s_lshl_b32 s22, s14, 7
	s_lshl_b32 s14, s14, 10
	s_lshl_b32 s15, s21, 7
	s_sub_i32 s23, s15, s14
	v_add_u32_e32 v0, s23, v106
	v_ashrrev_i32_e32 v1, 31, v0
	v_add_u32_e32 v2, 0x4000, v107
	v_lshlrev_b64 v[0:1], 11, v[0:1]
	v_readfirstlane_b32 s15, v2
	v_lshl_add_u64 v[0:1], v[66:67], 0, v[0:1]
	s_mov_b32 m0, s15
	v_readfirstlane_b32 s15, v107
	global_load_lds_dwordx4 v[0:1], off
	v_add_u32_e32 v0, s22, v106
	v_ashrrev_i32_e32 v1, 31, v0
	v_lshlrev_b64 v[0:1], 11, v[0:1]
	v_lshl_add_u64 v[2:3], v[72:73], 0, v[0:1]
	s_mov_b32 m0, s15
	v_readfirstlane_b32 s15, v130
	global_load_lds_dwordx4 v[2:3], off
	v_add_u32_e32 v2, s23, v108
	v_ashrrev_i32_e32 v3, 31, v2
	v_lshlrev_b64 v[2:3], 11, v[2:3]
	v_lshl_add_u64 v[2:3], v[68:69], 0, v[2:3]
	s_mov_b32 m0, s15
	v_add_u32_e32 v4, 0x400, v107
	global_load_lds_dwordx4 v[2:3], off
	v_add_u32_e32 v2, s22, v108
	v_ashrrev_i32_e32 v3, 31, v2
	v_lshlrev_b64 v[2:3], 11, v[2:3]
	v_readfirstlane_b32 s15, v4
	v_lshl_add_u64 v[2:3], v[74:75], 0, v[2:3]
	s_mov_b32 m0, s15
	v_readfirstlane_b32 s15, v131
	global_load_lds_dwordx4 v[2:3], off
	v_add_u32_e32 v2, s23, v110
	v_ashrrev_i32_e32 v3, 31, v2
	v_lshlrev_b64 v[2:3], 11, v[2:3]
	v_lshl_add_u64 v[2:3], v[66:67], 0, v[2:3]
	s_mov_b32 m0, s15
	v_add_u32_e32 v4, 0x800, v107
	global_load_lds_dwordx4 v[2:3], off
	v_add_u32_e32 v2, s22, v110
	v_ashrrev_i32_e32 v3, 31, v2
	v_lshlrev_b64 v[2:3], 11, v[2:3]
	v_readfirstlane_b32 s15, v4
	v_lshl_add_u64 v[2:3], v[72:73], 0, v[2:3]
	s_mov_b32 m0, s15
	v_readfirstlane_b32 s15, v132
	global_load_lds_dwordx4 v[2:3], off
	v_add_u32_e32 v2, s23, v112
	v_ashrrev_i32_e32 v3, 31, v2
	v_lshlrev_b64 v[2:3], 11, v[2:3]
	v_lshl_add_u64 v[2:3], v[70:71], 0, v[2:3]
	s_mov_b32 m0, s15
	v_add_u32_e32 v4, 0xc00, v107
	global_load_lds_dwordx4 v[2:3], off
	v_add_u32_e32 v2, s22, v112
	v_ashrrev_i32_e32 v3, 31, v2
	v_lshlrev_b64 v[2:3], 11, v[2:3]
	v_readfirstlane_b32 s15, v4
	v_lshl_add_u64 v[2:3], v[76:77], 0, v[2:3]
	s_mov_b32 m0, s15
	v_lshl_add_u64 v[92:93], v[80:81], 0, v[0:1]
	global_load_lds_dwordx4 v[2:3], off
	v_subrev_u32_e32 v0, s14, v123
	v_ashrrev_i32_e32 v1, 31, v0
	v_lshlrev_b64 v[0:1], 11, v[0:1]
	v_lshl_add_u64 v[94:95], v[82:83], 0, v[0:1]
	v_add_u32_e32 v0, s22, v124
	v_ashrrev_i32_e32 v1, 31, v0
	v_lshlrev_b64 v[0:1], 11, v[0:1]
	v_lshl_add_u64 v[96:97], v[84:85], 0, v[0:1]
	v_subrev_u32_e32 v0, s14, v125
	v_ashrrev_i32_e32 v1, 31, v0
	v_lshlrev_b64 v[0:1], 11, v[0:1]
	v_lshl_add_u64 v[98:99], v[78:79], 0, v[0:1]
	v_add_u32_e32 v0, s22, v126
	v_ashrrev_i32_e32 v1, 31, v0
	v_lshlrev_b64 v[0:1], 11, v[0:1]
	v_lshl_add_u64 v[100:101], v[80:81], 0, v[0:1]
	v_subrev_u32_e32 v0, s14, v64
	v_ashrrev_i32_e32 v1, 31, v0
	v_lshlrev_b64 v[0:1], 11, v[0:1]
	v_subrev_u32_e32 v2, s14, v122
	v_lshl_add_u64 v[102:103], v[86:87], 0, v[0:1]
	v_add_u32_e32 v0, s22, v127
	v_ashrrev_i32_e32 v3, 31, v2
	v_ashrrev_i32_e32 v1, 31, v0
	v_lshlrev_b64 v[2:3], 11, v[2:3]
	v_lshlrev_b64 v[0:1], 11, v[0:1]
	v_lshl_add_u64 v[90:91], v[78:79], 0, v[2:3]
	v_lshl_add_u64 v[104:105], v[88:89], 0, v[0:1]
	s_mov_b32 s24, 0
	s_mov_b64 s[14:15], 0
	v_mov_b32_e32 v0, 0
	v_mov_b32_e32 v1, v65
	v_mov_b32_e32 v2, v65
	v_mov_b32_e32 v3, v65
	v_mov_b32_e32 v4, 0
	v_mov_b32_e32 v5, v65
	v_mov_b32_e32 v6, v65
	v_mov_b32_e32 v7, v65
	v_mov_b32_e32 v8, 0
	v_mov_b32_e32 v9, v65
	v_mov_b32_e32 v10, v65
	v_mov_b32_e32 v11, v65
	v_mov_b32_e32 v12, 0
	v_mov_b32_e32 v13, v65
	v_mov_b32_e32 v14, v65
	v_mov_b32_e32 v15, v65
	v_mov_b32_e32 v16, 0
	v_mov_b32_e32 v17, v65
	v_mov_b32_e32 v18, v65
	v_mov_b32_e32 v19, v65
	v_mov_b32_e32 v20, 0
	v_mov_b32_e32 v21, v65
	v_mov_b32_e32 v22, v65
	v_mov_b32_e32 v23, v65
	v_mov_b32_e32 v24, 0
	v_mov_b32_e32 v25, v65
	v_mov_b32_e32 v26, v65
	v_mov_b32_e32 v27, v65
	v_mov_b32_e32 v28, 0
	v_mov_b32_e32 v29, v65
	v_mov_b32_e32 v30, v65
	v_mov_b32_e32 v31, v65
	v_mov_b32_e32 v32, 0
	v_mov_b32_e32 v33, v65
	v_mov_b32_e32 v34, v65
	v_mov_b32_e32 v35, v65
	v_mov_b32_e32 v36, 0
	v_mov_b32_e32 v37, v65
	v_mov_b32_e32 v38, v65
	v_mov_b32_e32 v39, v65
	v_mov_b32_e32 v40, 0
	v_mov_b32_e32 v41, v65
	v_mov_b32_e32 v42, v65
	v_mov_b32_e32 v43, v65
	v_mov_b32_e32 v44, 0
	v_mov_b32_e32 v45, v65
	v_mov_b32_e32 v46, v65
	v_mov_b32_e32 v47, v65
	v_mov_b32_e32 v48, 0
	v_mov_b32_e32 v49, v65
	v_mov_b32_e32 v50, v65
	v_mov_b32_e32 v51, v65
	v_mov_b32_e32 v52, 0
	v_mov_b32_e32 v53, v65
	v_mov_b32_e32 v54, v65
	v_mov_b32_e32 v55, v65
	v_mov_b32_e32 v56, 0
	v_mov_b32_e32 v57, v65
	v_mov_b32_e32 v58, v65
	v_mov_b32_e32 v59, v65
	v_mov_b32_e32 v60, 0
	v_mov_b32_e32 v61, v65
	v_mov_b32_e32 v62, v65
	v_mov_b32_e32 v63, v65
	s_waitcnt vmcnt(0) lgkmcnt(0)
	s_barrier
	v_add3_u32 v186, 0, v133, v134
	v_add_u32_e32 v187, 0x4000, v186
	s_nop 0
	v_readfirstlane_b32 s82, v187
	v_lshl_add_u32 v187, v109, 1, 0
	s_nop 0
	v_readfirstlane_b32 s83, v186
	v_add3_u32 v187, v187, v134, s17
	s_nop 0
	v_readfirstlane_b32 s84, v187
	v_add_u32_e32 v187, 0x400, v186
	s_nop 0
	v_readfirstlane_b32 s85, v187
	v_lshl_add_u32 v187, v111, 1, 0
	v_add3_u32 v187, v187, v134, s17
	s_nop 0
	v_readfirstlane_b32 s86, v187
	v_add_u32_e32 v187, 0x800, v186
	s_nop 0
	v_readfirstlane_b32 s87, v187
	v_lshl_add_u32 v187, v113, 1, 0
	v_add3_u32 v187, v187, v134, s17
	s_nop 0
	v_readfirstlane_b32 s88, v187
	v_add_u32_e32 v186, 0xc00, v186
	s_nop 0
	v_readfirstlane_b32 s89, v186
	v_subrev_u32_e32 v188, s52, v90
	v_subrev_u32_e32 v189, s52, v92
	v_subrev_u32_e32 v190, s52, v94
	v_subrev_u32_e32 v191, s52, v96
	v_subrev_u32_e32 v192, s52, v98
	v_subrev_u32_e32 v193, s52, v100
	v_subrev_u32_e32 v194, s52, v102
	v_subrev_u32_e32 v195, s52, v104
	s_bitcmp1_b32 s32, 0
	s_cbranch_scc1 .Lxk_423
.LBB0_423:
	s_and_b32 s25, s24, 0x4000
	s_xor_b32 s26, s25, 0x4000
	s_lshl_b32 s26, s26, 1
	s_add_i32 s26, s26, 32
	s_add_u32 s90, s52, s14
	s_addc_u32 s91, s53, s15
	s_add_i32 m0, s26, s82
	s_lshl_b32 s25, s25, 1
	global_load_lds_dwordx4 v188, s[90:91]
	s_add_i32 m0, s26, s83
	s_add_i32 s25, s25, 32
	global_load_lds_dwordx4 v189, s[90:91]
	s_add_i32 m0, s26, s84
	v_add3_u32 v170, s25, v114, v135
	global_load_lds_dwordx4 v190, s[90:91]
	s_add_i32 m0, s26, s85
	v_add3_u32 v171, s25, v115, v135
	global_load_lds_dwordx4 v191, s[90:91]
	s_add_i32 m0, s26, s86
	v_add_u32_e32 v158, v170, v136
	global_load_lds_dwordx4 v192, s[90:91]
	s_add_i32 m0, s26, s87
	v_add_u32_e32 v166, v171, v136
	global_load_lds_dwordx4 v193, s[90:91]
	s_add_i32 m0, s26, s88
	s_addk_i32 s24, 0x4000
	global_load_lds_dwordx4 v194, s[90:91]
	s_add_i32 m0, s26, s89
	s_add_u32 s14, s14, 0x80
	s_addc_u32 s15, s15, 0
	global_load_lds_dwordx4 v195, s[90:91]
	ds_read_b128 v[138:141], v158
	ds_read_b128 v[146:149], v166 offset:16384
	ds_read_b128 v[150:153], v166 offset:18432
	ds_read_b128 v[162:165], v166 offset:20480
	ds_read_b128 v[166:169], v166 offset:22528
	ds_read_b128 v[142:145], v158 offset:2048
	ds_read_b128 v[154:157], v158 offset:4096
	ds_read_b128 v[158:161], v158 offset:6144
	v_add_u32_e32 v236, v170, v137
	v_add_u32_e32 v237, v171, v137
	ds_read_b128 v[204:207], v236
	ds_read_b128 v[208:211], v237 offset:16384
	ds_read_b128 v[212:215], v237 offset:18432
	ds_read_b128 v[216:219], v237 offset:20480
	ds_read_b128 v[220:223], v237 offset:22528
	ds_read_b128 v[224:227], v236 offset:2048
	ds_read_b128 v[228:231], v236 offset:4096
	ds_read_b128 v[232:235], v236 offset:6144
	s_setprio 1
	s_waitcnt lgkmcnt(11)
	v_mfma_f32_16x16x32_bf16 v[60:63], v[138:141], v[146:149], v[60:63]
	v_mfma_f32_16x16x32_bf16 v[56:59], v[138:141], v[150:153], v[56:59]
	v_mfma_f32_16x16x32_bf16 v[52:55], v[138:141], v[162:165], v[52:55]
	v_mfma_f32_16x16x32_bf16 v[48:51], v[138:141], v[166:169], v[48:51]
	s_waitcnt lgkmcnt(10)
	v_mfma_f32_16x16x32_bf16 v[44:47], v[142:145], v[146:149], v[44:47]
	v_mfma_f32_16x16x32_bf16 v[40:43], v[142:145], v[150:153], v[40:43]
	v_mfma_f32_16x16x32_bf16 v[36:39], v[142:145], v[162:165], v[36:39]
	v_mfma_f32_16x16x32_bf16 v[32:35], v[142:145], v[166:169], v[32:35]
	s_waitcnt lgkmcnt(9)
	v_mfma_f32_16x16x32_bf16 v[28:31], v[154:157], v[146:149], v[28:31]
	v_mfma_f32_16x16x32_bf16 v[24:27], v[154:157], v[150:153], v[24:27]
	v_mfma_f32_16x16x32_bf16 v[20:23], v[154:157], v[162:165], v[20:23]
	v_mfma_f32_16x16x32_bf16 v[16:19], v[154:157], v[166:169], v[16:19]
	s_waitcnt lgkmcnt(8)
	v_mfma_f32_16x16x32_bf16 v[12:15], v[158:161], v[146:149], v[12:15]
	v_mfma_f32_16x16x32_bf16 v[8:11], v[158:161], v[150:153], v[8:11]
	v_mfma_f32_16x16x32_bf16 v[4:7], v[158:161], v[162:165], v[4:7]
	v_mfma_f32_16x16x32_bf16 v[0:3], v[158:161], v[166:169], v[0:3]
	s_waitcnt lgkmcnt(3)
	v_mfma_f32_16x16x32_bf16 v[60:63], v[204:207], v[208:211], v[60:63]
	v_mfma_f32_16x16x32_bf16 v[56:59], v[204:207], v[212:215], v[56:59]
	v_mfma_f32_16x16x32_bf16 v[52:55], v[204:207], v[216:219], v[52:55]
	v_mfma_f32_16x16x32_bf16 v[48:51], v[204:207], v[220:223], v[48:51]
	s_waitcnt lgkmcnt(2)
	v_mfma_f32_16x16x32_bf16 v[44:47], v[224:227], v[208:211], v[44:47]
	v_mfma_f32_16x16x32_bf16 v[40:43], v[224:227], v[212:215], v[40:43]
	v_mfma_f32_16x16x32_bf16 v[36:39], v[224:227], v[216:219], v[36:39]
	v_mfma_f32_16x16x32_bf16 v[32:35], v[224:227], v[220:223], v[32:35]
	s_waitcnt lgkmcnt(1)
	v_mfma_f32_16x16x32_bf16 v[28:31], v[228:231], v[208:211], v[28:31]
	v_mfma_f32_16x16x32_bf16 v[24:27], v[228:231], v[212:215], v[24:27]
	v_mfma_f32_16x16x32_bf16 v[20:23], v[228:231], v[216:219], v[20:23]
	v_mfma_f32_16x16x32_bf16 v[16:19], v[228:231], v[220:223], v[16:19]
	s_waitcnt lgkmcnt(0)
	v_mfma_f32_16x16x32_bf16 v[12:15], v[232:235], v[208:211], v[12:15]
	v_mfma_f32_16x16x32_bf16 v[8:11], v[232:235], v[212:215], v[8:11]
	v_mfma_f32_16x16x32_bf16 v[4:7], v[232:235], v[216:219], v[4:7]
	v_mfma_f32_16x16x32_bf16 v[0:3], v[232:235], v[220:223], v[0:3]
	s_setprio 0
	s_cmpk_eq_i32 s14, 0x780
	s_waitcnt vmcnt(0)
	s_barrier
	s_cbranch_scc0 .LBB0_423
	s_branch .Lxk_exit_423
.Lxk_423:
	s_and_b32 s25, s24, 0x4000
	s_xor_b32 s26, s25, 0x4000
	s_lshl_b32 s26, s26, 1
	s_add_i32 s26, s26, 32
	s_add_u32 s90, s52, s14
	s_addc_u32 s91, s53, s15
	s_add_i32 m0, s26, s82
	s_lshl_b32 s25, s25, 1
	global_load_lds_dwordx4 v188, s[90:91]
	s_add_i32 m0, s26, s83
	s_add_i32 s25, s25, 32
	global_load_lds_dwordx4 v189, s[90:91]
	s_add_i32 m0, s26, s84
	v_add3_u32 v170, s25, v114, v135
	global_load_lds_dwordx4 v190, s[90:91]
	s_add_i32 m0, s26, s85
	v_add3_u32 v171, s25, v115, v135
	global_load_lds_dwordx4 v191, s[90:91]
	s_add_i32 m0, s26, s86
	v_add_u32_e32 v158, v170, v136
	global_load_lds_dwordx4 v192, s[90:91]
	s_add_i32 m0, s26, s87
	v_add_u32_e32 v166, v171, v136
	global_load_lds_dwordx4 v193, s[90:91]
	s_add_i32 m0, s26, s88
	s_addk_i32 s24, 0x4000
	global_load_lds_dwordx4 v194, s[90:91]
	s_add_i32 m0, s26, s89
	s_add_u32 s14, s14, 0x80
	s_addc_u32 s15, s15, 0
	global_load_lds_dwordx4 v195, s[90:91]
	ds_read_b128 v[138:141], v158
	ds_read_b128 v[146:149], v166 offset:16384
	ds_read_b128 v[150:153], v166 offset:18432
	ds_read_b128 v[162:165], v166 offset:20480
	ds_read_b128 v[166:169], v166 offset:22528
	ds_read_b128 v[142:145], v158 offset:2048
	ds_read_b128 v[154:157], v158 offset:4096
	ds_read_b128 v[158:161], v158 offset:6144
	v_add_u32_e32 v236, v170, v137
	v_add_u32_e32 v237, v171, v137
	ds_read_b128 v[204:207], v236
	ds_read_b128 v[208:211], v237 offset:16384
	ds_read_b128 v[212:215], v237 offset:18432
	ds_read_b128 v[216:219], v237 offset:20480
	ds_read_b128 v[220:223], v237 offset:22528
	ds_read_b128 v[224:227], v236 offset:2048
	ds_read_b128 v[228:231], v236 offset:4096
	ds_read_b128 v[232:235], v236 offset:6144
	s_setprio 3
	s_waitcnt lgkmcnt(11)
	v_mfma_f32_16x16x32_bf16 v[60:63], v[138:141], v[146:149], v[60:63]
	v_mfma_f32_16x16x32_bf16 v[56:59], v[138:141], v[150:153], v[56:59]
	v_mfma_f32_16x16x32_bf16 v[52:55], v[138:141], v[162:165], v[52:55]
	v_mfma_f32_16x16x32_bf16 v[48:51], v[138:141], v[166:169], v[48:51]
	s_waitcnt lgkmcnt(10)
	v_mfma_f32_16x16x32_bf16 v[44:47], v[142:145], v[146:149], v[44:47]
	v_mfma_f32_16x16x32_bf16 v[40:43], v[142:145], v[150:153], v[40:43]
	v_mfma_f32_16x16x32_bf16 v[36:39], v[142:145], v[162:165], v[36:39]
	v_mfma_f32_16x16x32_bf16 v[32:35], v[142:145], v[166:169], v[32:35]
	s_waitcnt lgkmcnt(9)
	v_mfma_f32_16x16x32_bf16 v[28:31], v[154:157], v[146:149], v[28:31]
	v_mfma_f32_16x16x32_bf16 v[24:27], v[154:157], v[150:153], v[24:27]
	v_mfma_f32_16x16x32_bf16 v[20:23], v[154:157], v[162:165], v[20:23]
	v_mfma_f32_16x16x32_bf16 v[16:19], v[154:157], v[166:169], v[16:19]
	s_waitcnt lgkmcnt(8)
	v_mfma_f32_16x16x32_bf16 v[12:15], v[158:161], v[146:149], v[12:15]
	v_mfma_f32_16x16x32_bf16 v[8:11], v[158:161], v[150:153], v[8:11]
	v_mfma_f32_16x16x32_bf16 v[4:7], v[158:161], v[162:165], v[4:7]
	v_mfma_f32_16x16x32_bf16 v[0:3], v[158:161], v[166:169], v[0:3]
	s_waitcnt lgkmcnt(3)
	v_mfma_f32_16x16x32_bf16 v[60:63], v[204:207], v[208:211], v[60:63]
	v_mfma_f32_16x16x32_bf16 v[56:59], v[204:207], v[212:215], v[56:59]
	v_mfma_f32_16x16x32_bf16 v[52:55], v[204:207], v[216:219], v[52:55]
	v_mfma_f32_16x16x32_bf16 v[48:51], v[204:207], v[220:223], v[48:51]
	s_waitcnt lgkmcnt(2)
	v_mfma_f32_16x16x32_bf16 v[44:47], v[224:227], v[208:211], v[44:47]
	v_mfma_f32_16x16x32_bf16 v[40:43], v[224:227], v[212:215], v[40:43]
	v_mfma_f32_16x16x32_bf16 v[36:39], v[224:227], v[216:219], v[36:39]
	v_mfma_f32_16x16x32_bf16 v[32:35], v[224:227], v[220:223], v[32:35]
	s_waitcnt lgkmcnt(1)
	v_mfma_f32_16x16x32_bf16 v[28:31], v[228:231], v[208:211], v[28:31]
	v_mfma_f32_16x16x32_bf16 v[24:27], v[228:231], v[212:215], v[24:27]
	v_mfma_f32_16x16x32_bf16 v[20:23], v[228:231], v[216:219], v[20:23]
	v_mfma_f32_16x16x32_bf16 v[16:19], v[228:231], v[220:223], v[16:19]
	s_waitcnt lgkmcnt(0)
	v_mfma_f32_16x16x32_bf16 v[12:15], v[232:235], v[208:211], v[12:15]
	v_mfma_f32_16x16x32_bf16 v[8:11], v[232:235], v[212:215], v[8:11]
	v_mfma_f32_16x16x32_bf16 v[4:7], v[232:235], v[216:219], v[4:7]
	v_mfma_f32_16x16x32_bf16 v[0:3], v[232:235], v[220:223], v[0:3]
	s_setprio 2
	s_cmpk_eq_i32 s14, 0x780
	s_waitcnt vmcnt(0)
	s_barrier
	s_cbranch_scc0 .Lxk_423
.Lxk_exit_423:
	ds_read_b128 v[90:93], v118 offset:55296
	ds_read_b128 v[94:97], v118 offset:53248
	ds_read_b128 v[98:101], v119 offset:38912
	ds_read_b128 v[102:105], v119 offset:36864
	ds_read_b128 v[138:141], v118 offset:51200
	ds_read_b128 v[142:145], v118 offset:49152
	ds_read_b128 v[146:149], v119 offset:34816
	ds_read_b128 v[150:153], v119 offset:32768
	s_setprio 1
	s_waitcnt lgkmcnt(5)
	v_mfma_f32_16x16x32_bf16 v[4:7], v[98:101], v[94:97], v[4:7]
	v_mfma_f32_16x16x32_bf16 v[0:3], v[98:101], v[90:93], v[0:3]
	s_waitcnt lgkmcnt(0)
	v_mfma_f32_16x16x32_bf16 v[60:63], v[150:153], v[142:145], v[60:63]
	v_mfma_f32_16x16x32_bf16 v[56:59], v[150:153], v[138:141], v[56:59]
	v_mfma_f32_16x16x32_bf16 v[52:55], v[150:153], v[94:97], v[52:55]
	v_mfma_f32_16x16x32_bf16 v[48:51], v[150:153], v[90:93], v[48:51]
	v_mfma_f32_16x16x32_bf16 v[44:47], v[146:149], v[142:145], v[44:47]
	v_mfma_f32_16x16x32_bf16 v[40:43], v[146:149], v[138:141], v[40:43]
	v_mfma_f32_16x16x32_bf16 v[36:39], v[146:149], v[94:97], v[36:39]
	v_mfma_f32_16x16x32_bf16 v[32:35], v[146:149], v[90:93], v[32:35]
	v_mfma_f32_16x16x32_bf16 v[28:31], v[102:105], v[142:145], v[28:31]
	v_mfma_f32_16x16x32_bf16 v[24:27], v[102:105], v[138:141], v[24:27]
	v_mfma_f32_16x16x32_bf16 v[20:23], v[102:105], v[94:97], v[20:23]
	v_mfma_f32_16x16x32_bf16 v[16:19], v[102:105], v[90:93], v[16:19]
	v_mfma_f32_16x16x32_bf16 v[12:15], v[98:101], v[142:145], v[12:15]
	v_mfma_f32_16x16x32_bf16 v[8:11], v[98:101], v[138:141], v[8:11]
	s_setprio 0
	ds_read_b128 v[90:93], v120 offset:32768
	ds_read_b128 v[94:97], v120 offset:34816
	ds_read_b128 v[98:101], v121 offset:49152
	ds_read_b128 v[102:105], v121 offset:51200
	ds_read_b128 v[138:141], v120 offset:36864
	ds_read_b128 v[142:145], v120 offset:38912
	ds_read_b128 v[146:149], v121 offset:53248
	ds_read_b128 v[150:153], v121 offset:55296
	s_setprio 1
	s_waitcnt lgkmcnt(1)
	v_mfma_f32_16x16x32_bf16 v[4:7], v[142:145], v[146:149], v[4:7]
	s_waitcnt lgkmcnt(0)
	v_mfma_f32_16x16x32_bf16 v[0:3], v[142:145], v[150:153], v[0:3]
	v_mfma_f32_16x16x32_bf16 v[60:63], v[90:93], v[98:101], v[60:63]
	v_mfma_f32_16x16x32_bf16 v[56:59], v[90:93], v[102:105], v[56:59]
	v_mfma_f32_16x16x32_bf16 v[52:55], v[90:93], v[146:149], v[52:55]
	v_mfma_f32_16x16x32_bf16 v[48:51], v[90:93], v[150:153], v[48:51]
	v_mfma_f32_16x16x32_bf16 v[44:47], v[94:97], v[98:101], v[44:47]
	v_mfma_f32_16x16x32_bf16 v[40:43], v[94:97], v[102:105], v[40:43]
	v_mfma_f32_16x16x32_bf16 v[36:39], v[94:97], v[146:149], v[36:39]
	v_mfma_f32_16x16x32_bf16 v[32:35], v[94:97], v[150:153], v[32:35]
	v_mfma_f32_16x16x32_bf16 v[28:31], v[138:141], v[98:101], v[28:31]
	v_mfma_f32_16x16x32_bf16 v[24:27], v[138:141], v[102:105], v[24:27]
	v_mfma_f32_16x16x32_bf16 v[20:23], v[138:141], v[146:149], v[20:23]
	v_mfma_f32_16x16x32_bf16 v[16:19], v[138:141], v[150:153], v[16:19]
	v_mfma_f32_16x16x32_bf16 v[12:15], v[142:145], v[98:101], v[12:15]
	v_mfma_f32_16x16x32_bf16 v[8:11], v[142:145], v[102:105], v[8:11]
	s_setprio 0
	s_barrier
	ds_write2_b32 v116, v60, v56 offset1:16
	ds_write2_b32 v116, v61, v57 offset0:132 offset1:148
	v_add_u32_e32 v56, 0x400, v116
	ds_write2_b32 v56, v62, v58 offset0:8 offset1:24
	ds_write2_b32 v56, v63, v59 offset0:140 offset1:156
	ds_write2_b32 v116, v52, v48 offset0:32 offset1:48
	ds_write2_b32 v116, v53, v49 offset0:164 offset1:180
	ds_write2_b32 v56, v54, v50 offset0:40 offset1:56
	ds_write2_b32 v56, v55, v51 offset0:172 offset1:188
	v_add_u32_e32 v48, 0x2000, v116
	ds_write2_b32 v48, v44, v40 offset0:64 offset1:80
	ds_write2_b32 v48, v45, v41 offset0:196 offset1:212
	v_add_u32_e32 v40, 0x2400, v116
	ds_write2_b32 v40, v46, v42 offset0:72 offset1:88
	ds_write2_b32 v40, v47, v43 offset0:204 offset1:220
	ds_write2_b32 v48, v36, v32 offset0:96 offset1:112
	ds_write2_b32 v48, v37, v33 offset0:228 offset1:244
	ds_write2_b32 v40, v38, v34 offset0:104 offset1:120
	ds_write2_b32 v40, v39, v35 offset0:236 offset1:252
	v_add_u32_e32 v32, 0x4000, v116
	ds_write2_b32 v32, v28, v24 offset0:128 offset1:144
	v_add_u32_e32 v24, 0x4400, v116
	ds_write2_b32 v24, v29, v25 offset0:4 offset1:20
	ds_write2_b32 v24, v30, v26 offset0:136 offset1:152
	v_add_u32_e32 v25, 0x4800, v116
	ds_write2_b32 v25, v31, v27 offset0:12 offset1:28
	ds_write2_b32 v32, v20, v16 offset0:160 offset1:176
	ds_write2_b32 v24, v21, v17 offset0:36 offset1:52
	ds_write2_b32 v24, v22, v18 offset0:168 offset1:184
	ds_write2_b32 v25, v23, v19 offset0:44 offset1:60
	v_add_u32_e32 v16, 0x6000, v116
	ds_write2_b32 v16, v12, v8 offset0:192 offset1:208
	v_add_u32_e32 v8, 0x6400, v116
	ds_write2_b32 v8, v13, v9 offset0:68 offset1:84
	ds_write2_b32 v8, v14, v10 offset0:200 offset1:216
	v_add_u32_e32 v9, 0x6800, v116
	ds_write2_b32 v9, v15, v11 offset0:76 offset1:92
	ds_write2_b32 v16, v4, v0 offset0:224 offset1:240
	ds_write2_b32 v8, v5, v1 offset0:100 offset1:116
	ds_write2_b32 v8, v6, v2 offset0:232 offset1:248
	ds_write2_b32 v9, v7, v3 offset0:108 offset1:124
	v_or_b32_e32 v0, s23, v117
	v_ashrrev_i32_e32 v1, 31, v0
	v_lshlrev_b64 v[2:3], 2, v[0:1]
	v_lshl_add_u64 v[0:1], s[12:13], 0, v[2:3]
	v_lshl_add_u64 v[2:3], s[8:9], 0, v[2:3]
	v_add_u32_e32 v4, s22, v128
	s_mov_b32 s14, 0
	s_waitcnt lgkmcnt(0)
	s_barrier

.LBB0_431:
	s_ashr_i32 s14, s16, 31
	s_lshr_b32 s14, s14, 29
	s_add_i32 s14, s16, s14
	s_ashr_i32 s14, s14, 3
	s_lshl_b32 s15, s14, 10
	s_lshl_b32 s23, s16, 7
	v_add_u32_e32 v0, s14, v104
	s_sub_i32 s23, s23, s15
	v_lshlrev_b32_e32 v2, 7, v0
	v_add_u32_e32 v0, s23, v105
	v_ashrrev_i32_e32 v1, 31, v0
	v_add_u32_e32 v3, 0x4000, v106
	v_lshlrev_b64 v[0:1], 11, v[0:1]
	v_readfirstlane_b32 s24, v3
	v_lshl_add_u64 v[0:1], v[64:65], 0, v[0:1]
	s_mov_b32 m0, s24
	v_readfirstlane_b32 s24, v106
	global_load_lds_dwordx4 v[0:1], off
	v_add_u32_e32 v0, v2, v105
	v_ashrrev_i32_e32 v1, 31, v0
	v_lshlrev_b64 v[0:1], 11, v[0:1]
	v_lshl_add_u64 v[0:1], v[70:71], 0, v[0:1]
	s_mov_b32 m0, s24
	v_readfirstlane_b32 s24, v131
	global_load_lds_dwordx4 v[0:1], off
	v_add_u32_e32 v0, s23, v107
	v_ashrrev_i32_e32 v1, 31, v0
	v_lshlrev_b64 v[0:1], 11, v[0:1]
	v_lshl_add_u64 v[0:1], v[66:67], 0, v[0:1]
	s_mov_b32 m0, s24
	v_add_u32_e32 v3, 0x400, v106
	global_load_lds_dwordx4 v[0:1], off
	v_add_u32_e32 v0, v2, v107
	v_ashrrev_i32_e32 v1, 31, v0
	v_lshlrev_b64 v[0:1], 11, v[0:1]
	v_readfirstlane_b32 s24, v3
	v_lshl_add_u64 v[0:1], v[72:73], 0, v[0:1]
	s_mov_b32 m0, s24
	v_readfirstlane_b32 s24, v132
	global_load_lds_dwordx4 v[0:1], off
	v_add_u32_e32 v0, s23, v109
	v_ashrrev_i32_e32 v1, 31, v0
	v_lshlrev_b64 v[0:1], 11, v[0:1]
	v_lshl_add_u64 v[0:1], v[64:65], 0, v[0:1]
	s_mov_b32 m0, s24
	v_add_u32_e32 v3, 0x800, v106
	global_load_lds_dwordx4 v[0:1], off
	v_add_u32_e32 v0, v2, v109
	v_ashrrev_i32_e32 v1, 31, v0
	v_lshlrev_b64 v[0:1], 11, v[0:1]
	v_readfirstlane_b32 s24, v3
	v_lshl_add_u64 v[0:1], v[70:71], 0, v[0:1]
	s_mov_b32 m0, s24
	v_readfirstlane_b32 s24, v133
	global_load_lds_dwordx4 v[0:1], off
	v_add_u32_e32 v0, s23, v111
	v_ashrrev_i32_e32 v1, 31, v0
	v_lshlrev_b64 v[0:1], 11, v[0:1]
	v_lshl_add_u64 v[0:1], v[68:69], 0, v[0:1]
	s_mov_b32 m0, s24
	s_mov_b32 s25, 0
	global_load_lds_dwordx4 v[0:1], off
	v_add_u32_e32 v0, v2, v111
	v_ashrrev_i32_e32 v1, 31, v0
	v_add_u32_e32 v2, 0xc00, v106
	v_lshlrev_b64 v[0:1], 11, v[0:1]
	v_readfirstlane_b32 s24, v2
	v_lshl_add_u64 v[0:1], v[74:75], 0, v[0:1]
	s_mov_b32 m0, s24
	s_lshl_b32 s24, s14, 7
	global_load_lds_dwordx4 v[0:1], off
	v_subrev_u32_e32 v0, s15, v121
	v_ashrrev_i32_e32 v1, 31, v0
	v_lshlrev_b64 v[0:1], 11, v[0:1]
	v_lshl_add_u64 v[88:89], v[76:77], 0, v[0:1]
	v_add_u32_e32 v0, s24, v122
	v_ashrrev_i32_e32 v1, 31, v0
	v_lshlrev_b64 v[0:1], 11, v[0:1]
	v_lshl_add_u64 v[90:91], v[78:79], 0, v[0:1]
	v_subrev_u32_e32 v0, s15, v123
	v_ashrrev_i32_e32 v1, 31, v0
	v_lshlrev_b64 v[0:1], 11, v[0:1]
	v_lshl_add_u64 v[92:93], v[80:81], 0, v[0:1]
	v_add_u32_e32 v0, s24, v124
	v_ashrrev_i32_e32 v1, 31, v0
	v_lshlrev_b64 v[0:1], 11, v[0:1]
	v_lshl_add_u64 v[94:95], v[82:83], 0, v[0:1]
	v_subrev_u32_e32 v0, s15, v125
	v_ashrrev_i32_e32 v1, 31, v0
	v_lshlrev_b64 v[0:1], 11, v[0:1]
	v_lshl_add_u64 v[96:97], v[76:77], 0, v[0:1]
	v_add_u32_e32 v0, s24, v126
	v_ashrrev_i32_e32 v1, 31, v0
	v_lshlrev_b64 v[0:1], 11, v[0:1]
	v_lshl_add_u64 v[98:99], v[78:79], 0, v[0:1]
	v_subrev_u32_e32 v0, s15, v127
	v_ashrrev_i32_e32 v1, 31, v0
	v_lshlrev_b64 v[0:1], 11, v[0:1]
	v_lshl_add_u64 v[100:101], v[84:85], 0, v[0:1]
	v_add_u32_e32 v0, s24, v128
	v_ashrrev_i32_e32 v1, 31, v0
	v_lshlrev_b64 v[0:1], 11, v[0:1]
	v_lshl_add_u64 v[102:103], v[86:87], 0, v[0:1]
	v_mov_b32_e32 v0, 0
	s_mov_b64 s[14:15], 0
	v_mov_b32_e32 v1, v0
	v_mov_b32_e32 v2, v0
	v_mov_b32_e32 v3, v0
	v_mov_b32_e32 v4, v0
	v_mov_b32_e32 v5, v0
	v_mov_b32_e32 v6, v0
	v_mov_b32_e32 v7, v0
	v_mov_b32_e32 v8, v0
	v_mov_b32_e32 v9, v0
	v_mov_b32_e32 v10, v0
	v_mov_b32_e32 v11, v0
	v_mov_b32_e32 v12, v0
	v_mov_b32_e32 v13, v0
	v_mov_b32_e32 v14, v0
	v_mov_b32_e32 v15, v0
	v_mov_b32_e32 v16, v0
	v_mov_b32_e32 v17, v0
	v_mov_b32_e32 v18, v0
	v_mov_b32_e32 v19, v0
	v_mov_b32_e32 v20, v0
	v_mov_b32_e32 v21, v0
	v_mov_b32_e32 v22, v0
	v_mov_b32_e32 v23, v0
	v_mov_b32_e32 v24, v0
	v_mov_b32_e32 v25, v0
	v_mov_b32_e32 v26, v0
	v_mov_b32_e32 v27, v0
	v_mov_b32_e32 v28, v0
	v_mov_b32_e32 v29, v0
	v_mov_b32_e32 v30, v0
	v_mov_b32_e32 v31, v0
	v_mov_b32_e32 v32, v0
	v_mov_b32_e32 v33, v0
	v_mov_b32_e32 v34, v0
	v_mov_b32_e32 v35, v0
	v_mov_b32_e32 v36, v0
	v_mov_b32_e32 v37, v0
	v_mov_b32_e32 v38, v0
	v_mov_b32_e32 v39, v0
	v_mov_b32_e32 v40, v0
	v_mov_b32_e32 v41, v0
	v_mov_b32_e32 v42, v0
	v_mov_b32_e32 v43, v0
	v_mov_b32_e32 v44, v0
	v_mov_b32_e32 v45, v0
	v_mov_b32_e32 v46, v0
	v_mov_b32_e32 v47, v0
	v_mov_b32_e32 v48, v0
	v_mov_b32_e32 v49, v0
	v_mov_b32_e32 v50, v0
	v_mov_b32_e32 v51, v0
	v_mov_b32_e32 v52, v0
	v_mov_b32_e32 v53, v0
	v_mov_b32_e32 v54, v0
	v_mov_b32_e32 v55, v0
	v_mov_b32_e32 v56, v0
	v_mov_b32_e32 v57, v0
	v_mov_b32_e32 v58, v0
	v_mov_b32_e32 v59, v0
	v_mov_b32_e32 v60, v0
	v_mov_b32_e32 v61, v0
	v_mov_b32_e32 v62, v0
	v_mov_b32_e32 v63, v0
	s_waitcnt vmcnt(0) lgkmcnt(0)
	s_barrier
	v_add3_u32 v186, 0, v134, v135
	v_add_u32_e32 v187, 0x4000, v186
	s_nop 0
	v_readfirstlane_b32 s82, v187
	v_lshl_add_u32 v187, v108, 1, 0
	s_nop 0
	v_readfirstlane_b32 s83, v186
	v_add3_u32 v187, v187, v135, s19
	s_nop 0
	v_readfirstlane_b32 s84, v187
	v_add_u32_e32 v187, 0x400, v186
	s_nop 0
	v_readfirstlane_b32 s85, v187
	v_lshl_add_u32 v187, v110, 1, 0
	v_add3_u32 v187, v187, v135, s19
	s_nop 0
	v_readfirstlane_b32 s86, v187
	v_add_u32_e32 v187, 0x800, v186
	s_nop 0
	v_readfirstlane_b32 s87, v187
	v_lshl_add_u32 v187, v112, 1, 0
	v_add3_u32 v187, v187, v135, s19
	s_nop 0
	v_readfirstlane_b32 s88, v187
	v_add_u32_e32 v186, 0xc00, v186
	s_nop 0
	v_readfirstlane_b32 s89, v186
	v_subrev_u32_e32 v188, s52, v88
	v_subrev_u32_e32 v189, s52, v90
	v_subrev_u32_e32 v190, s52, v92
	v_subrev_u32_e32 v191, s52, v94
	v_subrev_u32_e32 v192, s52, v96
	v_subrev_u32_e32 v193, s52, v98
	v_subrev_u32_e32 v194, s52, v100
	v_subrev_u32_e32 v195, s52, v102
	s_bitcmp1_b32 s32, 0
	s_cbranch_scc1 .Lxk_432
.LBB0_432:
	s_and_b32 s26, s25, 0x4000
	s_xor_b32 s27, s26, 0x4000
	s_lshl_b32 s27, s27, 1
	s_add_i32 s27, s27, 32
	s_add_u32 s90, s52, s14
	s_addc_u32 s91, s53, s15
	s_add_i32 m0, s27, s82
	s_lshl_b32 s26, s26, 1
	global_load_lds_dwordx4 v188, s[90:91]
	s_add_i32 m0, s27, s83
	s_add_i32 s26, s26, 32
	global_load_lds_dwordx4 v189, s[90:91]
	s_add_i32 m0, s27, s84
	v_add3_u32 v139, s26, v113, v136
	global_load_lds_dwordx4 v190, s[90:91]
	s_add_i32 m0, s27, s85
	v_add3_u32 v172, s26, v114, v136
	global_load_lds_dwordx4 v191, s[90:91]
	s_add_i32 m0, s27, s86
	v_add_u32_e32 v160, v139, v137
	global_load_lds_dwordx4 v192, s[90:91]
	s_add_i32 m0, s27, s87
	v_add_u32_e32 v168, v172, v137
	global_load_lds_dwordx4 v193, s[90:91]
	s_add_i32 m0, s27, s88
	s_addk_i32 s25, 0x4000
	global_load_lds_dwordx4 v194, s[90:91]
	s_add_i32 m0, s27, s89
	s_add_u32 s14, s14, 0x80
	s_addc_u32 s15, s15, 0
	global_load_lds_dwordx4 v195, s[90:91]
	ds_read_b128 v[140:143], v160
	ds_read_b128 v[148:151], v168 offset:16384
	ds_read_b128 v[152:155], v168 offset:18432
	ds_read_b128 v[164:167], v168 offset:20480
	ds_read_b128 v[168:171], v168 offset:22528
	ds_read_b128 v[144:147], v160 offset:2048
	ds_read_b128 v[156:159], v160 offset:4096
	ds_read_b128 v[160:163], v160 offset:6144
	v_add_u32_e32 v139, v139, v138
	v_add_u32_e32 v236, v172, v138
	ds_read_b128 v[204:207], v139
	ds_read_b128 v[208:211], v236 offset:16384
	ds_read_b128 v[212:215], v236 offset:18432
	ds_read_b128 v[216:219], v236 offset:20480
	ds_read_b128 v[220:223], v236 offset:22528
	ds_read_b128 v[224:227], v139 offset:2048
	ds_read_b128 v[228:231], v139 offset:4096
	ds_read_b128 v[232:235], v139 offset:6144
	s_setprio 1
	s_waitcnt lgkmcnt(11)
	v_mfma_f32_16x16x32_bf16 v[60:63], v[140:143], v[148:151], v[60:63]
	v_mfma_f32_16x16x32_bf16 v[56:59], v[140:143], v[152:155], v[56:59]
	v_mfma_f32_16x16x32_bf16 v[52:55], v[140:143], v[164:167], v[52:55]
	v_mfma_f32_16x16x32_bf16 v[48:51], v[140:143], v[168:171], v[48:51]
	s_waitcnt lgkmcnt(10)
	v_mfma_f32_16x16x32_bf16 v[44:47], v[144:147], v[148:151], v[44:47]
	v_mfma_f32_16x16x32_bf16 v[40:43], v[144:147], v[152:155], v[40:43]
	v_mfma_f32_16x16x32_bf16 v[36:39], v[144:147], v[164:167], v[36:39]
	v_mfma_f32_16x16x32_bf16 v[32:35], v[144:147], v[168:171], v[32:35]
	s_waitcnt lgkmcnt(9)
	v_mfma_f32_16x16x32_bf16 v[28:31], v[156:159], v[148:151], v[28:31]
	v_mfma_f32_16x16x32_bf16 v[24:27], v[156:159], v[152:155], v[24:27]
	v_mfma_f32_16x16x32_bf16 v[20:23], v[156:159], v[164:167], v[20:23]
	v_mfma_f32_16x16x32_bf16 v[16:19], v[156:159], v[168:171], v[16:19]
	s_waitcnt lgkmcnt(8)
	v_mfma_f32_16x16x32_bf16 v[12:15], v[160:163], v[148:151], v[12:15]
	v_mfma_f32_16x16x32_bf16 v[8:11], v[160:163], v[152:155], v[8:11]
	v_mfma_f32_16x16x32_bf16 v[4:7], v[160:163], v[164:167], v[4:7]
	v_mfma_f32_16x16x32_bf16 v[0:3], v[160:163], v[168:171], v[0:3]
	s_waitcnt lgkmcnt(3)
	v_mfma_f32_16x16x32_bf16 v[60:63], v[204:207], v[208:211], v[60:63]
	v_mfma_f32_16x16x32_bf16 v[56:59], v[204:207], v[212:215], v[56:59]
	v_mfma_f32_16x16x32_bf16 v[52:55], v[204:207], v[216:219], v[52:55]
	v_mfma_f32_16x16x32_bf16 v[48:51], v[204:207], v[220:223], v[48:51]
	s_waitcnt lgkmcnt(2)
	v_mfma_f32_16x16x32_bf16 v[44:47], v[224:227], v[208:211], v[44:47]
	v_mfma_f32_16x16x32_bf16 v[40:43], v[224:227], v[212:215], v[40:43]
	v_mfma_f32_16x16x32_bf16 v[36:39], v[224:227], v[216:219], v[36:39]
	v_mfma_f32_16x16x32_bf16 v[32:35], v[224:227], v[220:223], v[32:35]
	s_waitcnt lgkmcnt(1)
	v_mfma_f32_16x16x32_bf16 v[28:31], v[228:231], v[208:211], v[28:31]
	v_mfma_f32_16x16x32_bf16 v[24:27], v[228:231], v[212:215], v[24:27]
	v_mfma_f32_16x16x32_bf16 v[20:23], v[228:231], v[216:219], v[20:23]
	v_mfma_f32_16x16x32_bf16 v[16:19], v[228:231], v[220:223], v[16:19]
	s_waitcnt lgkmcnt(0)
	v_mfma_f32_16x16x32_bf16 v[12:15], v[232:235], v[208:211], v[12:15]
	v_mfma_f32_16x16x32_bf16 v[8:11], v[232:235], v[212:215], v[8:11]
	v_mfma_f32_16x16x32_bf16 v[4:7], v[232:235], v[216:219], v[4:7]
	v_mfma_f32_16x16x32_bf16 v[0:3], v[232:235], v[220:223], v[0:3]
	s_setprio 0
	s_cmpk_eq_i32 s14, 0x780
	s_waitcnt vmcnt(0)
	s_barrier
	s_cbranch_scc0 .LBB0_432
	s_branch .Lxk_exit_432
.Lxk_432:
	s_and_b32 s26, s25, 0x4000
	s_xor_b32 s27, s26, 0x4000
	s_lshl_b32 s27, s27, 1
	s_add_i32 s27, s27, 32
	s_add_u32 s90, s52, s14
	s_addc_u32 s91, s53, s15
	s_add_i32 m0, s27, s82
	s_lshl_b32 s26, s26, 1
	global_load_lds_dwordx4 v188, s[90:91]
	s_add_i32 m0, s27, s83
	s_add_i32 s26, s26, 32
	global_load_lds_dwordx4 v189, s[90:91]
	s_add_i32 m0, s27, s84
	v_add3_u32 v139, s26, v113, v136
	global_load_lds_dwordx4 v190, s[90:91]
	s_add_i32 m0, s27, s85
	v_add3_u32 v172, s26, v114, v136
	global_load_lds_dwordx4 v191, s[90:91]
	s_add_i32 m0, s27, s86
	v_add_u32_e32 v160, v139, v137
	global_load_lds_dwordx4 v192, s[90:91]
	s_add_i32 m0, s27, s87
	v_add_u32_e32 v168, v172, v137
	global_load_lds_dwordx4 v193, s[90:91]
	s_add_i32 m0, s27, s88
	s_addk_i32 s25, 0x4000
	global_load_lds_dwordx4 v194, s[90:91]
	s_add_i32 m0, s27, s89
	s_add_u32 s14, s14, 0x80
	s_addc_u32 s15, s15, 0
	global_load_lds_dwordx4 v195, s[90:91]
	ds_read_b128 v[140:143], v160
	ds_read_b128 v[148:151], v168 offset:16384
	ds_read_b128 v[152:155], v168 offset:18432
	ds_read_b128 v[164:167], v168 offset:20480
	ds_read_b128 v[168:171], v168 offset:22528
	ds_read_b128 v[144:147], v160 offset:2048
	ds_read_b128 v[156:159], v160 offset:4096
	ds_read_b128 v[160:163], v160 offset:6144
	v_add_u32_e32 v139, v139, v138
	v_add_u32_e32 v236, v172, v138
	ds_read_b128 v[204:207], v139
	ds_read_b128 v[208:211], v236 offset:16384
	ds_read_b128 v[212:215], v236 offset:18432
	ds_read_b128 v[216:219], v236 offset:20480
	ds_read_b128 v[220:223], v236 offset:22528
	ds_read_b128 v[224:227], v139 offset:2048
	ds_read_b128 v[228:231], v139 offset:4096
	ds_read_b128 v[232:235], v139 offset:6144
	s_setprio 3
	s_waitcnt lgkmcnt(11)
	v_mfma_f32_16x16x32_bf16 v[60:63], v[140:143], v[148:151], v[60:63]
	v_mfma_f32_16x16x32_bf16 v[56:59], v[140:143], v[152:155], v[56:59]
	v_mfma_f32_16x16x32_bf16 v[52:55], v[140:143], v[164:167], v[52:55]
	v_mfma_f32_16x16x32_bf16 v[48:51], v[140:143], v[168:171], v[48:51]
	s_waitcnt lgkmcnt(10)
	v_mfma_f32_16x16x32_bf16 v[44:47], v[144:147], v[148:151], v[44:47]
	v_mfma_f32_16x16x32_bf16 v[40:43], v[144:147], v[152:155], v[40:43]
	v_mfma_f32_16x16x32_bf16 v[36:39], v[144:147], v[164:167], v[36:39]
	v_mfma_f32_16x16x32_bf16 v[32:35], v[144:147], v[168:171], v[32:35]
	s_waitcnt lgkmcnt(9)
	v_mfma_f32_16x16x32_bf16 v[28:31], v[156:159], v[148:151], v[28:31]
	v_mfma_f32_16x16x32_bf16 v[24:27], v[156:159], v[152:155], v[24:27]
	v_mfma_f32_16x16x32_bf16 v[20:23], v[156:159], v[164:167], v[20:23]
	v_mfma_f32_16x16x32_bf16 v[16:19], v[156:159], v[168:171], v[16:19]
	s_waitcnt lgkmcnt(8)
	v_mfma_f32_16x16x32_bf16 v[12:15], v[160:163], v[148:151], v[12:15]
	v_mfma_f32_16x16x32_bf16 v[8:11], v[160:163], v[152:155], v[8:11]
	v_mfma_f32_16x16x32_bf16 v[4:7], v[160:163], v[164:167], v[4:7]
	v_mfma_f32_16x16x32_bf16 v[0:3], v[160:163], v[168:171], v[0:3]
	s_waitcnt lgkmcnt(3)
	v_mfma_f32_16x16x32_bf16 v[60:63], v[204:207], v[208:211], v[60:63]
	v_mfma_f32_16x16x32_bf16 v[56:59], v[204:207], v[212:215], v[56:59]
	v_mfma_f32_16x16x32_bf16 v[52:55], v[204:207], v[216:219], v[52:55]
	v_mfma_f32_16x16x32_bf16 v[48:51], v[204:207], v[220:223], v[48:51]
	s_waitcnt lgkmcnt(2)
	v_mfma_f32_16x16x32_bf16 v[44:47], v[224:227], v[208:211], v[44:47]
	v_mfma_f32_16x16x32_bf16 v[40:43], v[224:227], v[212:215], v[40:43]
	v_mfma_f32_16x16x32_bf16 v[36:39], v[224:227], v[216:219], v[36:39]
	v_mfma_f32_16x16x32_bf16 v[32:35], v[224:227], v[220:223], v[32:35]
	s_waitcnt lgkmcnt(1)
	v_mfma_f32_16x16x32_bf16 v[28:31], v[228:231], v[208:211], v[28:31]
	v_mfma_f32_16x16x32_bf16 v[24:27], v[228:231], v[212:215], v[24:27]
	v_mfma_f32_16x16x32_bf16 v[20:23], v[228:231], v[216:219], v[20:23]
	v_mfma_f32_16x16x32_bf16 v[16:19], v[228:231], v[220:223], v[16:19]
	s_waitcnt lgkmcnt(0)
	v_mfma_f32_16x16x32_bf16 v[12:15], v[232:235], v[208:211], v[12:15]
	v_mfma_f32_16x16x32_bf16 v[8:11], v[232:235], v[212:215], v[8:11]
	v_mfma_f32_16x16x32_bf16 v[4:7], v[232:235], v[216:219], v[4:7]
	v_mfma_f32_16x16x32_bf16 v[0:3], v[232:235], v[220:223], v[0:3]
	s_setprio 2
	s_cmpk_eq_i32 s14, 0x780
	s_waitcnt vmcnt(0)
	s_barrier
	s_cbranch_scc0 .Lxk_432
.Lxk_exit_432:
	ds_read_b128 v[88:91], v117 offset:55296
	ds_read_b128 v[92:95], v117 offset:53248
	ds_read_b128 v[96:99], v118 offset:38912
	ds_read_b128 v[100:103], v118 offset:36864
	ds_read_b128 v[140:143], v117 offset:51200
	ds_read_b128 v[144:147], v117 offset:49152
	ds_read_b128 v[148:151], v118 offset:34816
	ds_read_b128 v[152:155], v118 offset:32768
	s_setprio 1
	s_waitcnt lgkmcnt(5)
	v_mfma_f32_16x16x32_bf16 v[4:7], v[96:99], v[92:95], v[4:7]
	v_mfma_f32_16x16x32_bf16 v[0:3], v[96:99], v[88:91], v[0:3]
	s_waitcnt lgkmcnt(0)
	v_mfma_f32_16x16x32_bf16 v[60:63], v[152:155], v[144:147], v[60:63]
	v_mfma_f32_16x16x32_bf16 v[56:59], v[152:155], v[140:143], v[56:59]
	v_mfma_f32_16x16x32_bf16 v[52:55], v[152:155], v[92:95], v[52:55]
	v_mfma_f32_16x16x32_bf16 v[48:51], v[152:155], v[88:91], v[48:51]
	v_mfma_f32_16x16x32_bf16 v[44:47], v[148:151], v[144:147], v[44:47]
	v_mfma_f32_16x16x32_bf16 v[40:43], v[148:151], v[140:143], v[40:43]
	v_mfma_f32_16x16x32_bf16 v[36:39], v[148:151], v[92:95], v[36:39]
	v_mfma_f32_16x16x32_bf16 v[32:35], v[148:151], v[88:91], v[32:35]
	v_mfma_f32_16x16x32_bf16 v[28:31], v[100:103], v[144:147], v[28:31]
	v_mfma_f32_16x16x32_bf16 v[24:27], v[100:103], v[140:143], v[24:27]
	v_mfma_f32_16x16x32_bf16 v[20:23], v[100:103], v[92:95], v[20:23]
	v_mfma_f32_16x16x32_bf16 v[16:19], v[100:103], v[88:91], v[16:19]
	v_mfma_f32_16x16x32_bf16 v[12:15], v[96:99], v[144:147], v[12:15]
	v_mfma_f32_16x16x32_bf16 v[8:11], v[96:99], v[140:143], v[8:11]
	s_setprio 0
	ds_read_b128 v[88:91], v119 offset:32768
	ds_read_b128 v[92:95], v119 offset:34816
	ds_read_b128 v[96:99], v120 offset:49152
	ds_read_b128 v[100:103], v120 offset:51200
	ds_read_b128 v[140:143], v119 offset:36864
	ds_read_b128 v[144:147], v119 offset:38912
	ds_read_b128 v[148:151], v120 offset:53248
	ds_read_b128 v[152:155], v120 offset:55296
	s_setprio 1
	s_waitcnt lgkmcnt(1)
	v_mfma_f32_16x16x32_bf16 v[4:7], v[144:147], v[148:151], v[4:7]
	s_waitcnt lgkmcnt(0)
	v_mfma_f32_16x16x32_bf16 v[0:3], v[144:147], v[152:155], v[0:3]
	v_mfma_f32_16x16x32_bf16 v[60:63], v[88:91], v[96:99], v[60:63]
	v_mfma_f32_16x16x32_bf16 v[56:59], v[88:91], v[100:103], v[56:59]
	v_mfma_f32_16x16x32_bf16 v[52:55], v[88:91], v[148:151], v[52:55]
	v_mfma_f32_16x16x32_bf16 v[48:51], v[88:91], v[152:155], v[48:51]
	v_mfma_f32_16x16x32_bf16 v[44:47], v[92:95], v[96:99], v[44:47]
	v_mfma_f32_16x16x32_bf16 v[40:43], v[92:95], v[100:103], v[40:43]
	v_mfma_f32_16x16x32_bf16 v[36:39], v[92:95], v[148:151], v[36:39]
	v_mfma_f32_16x16x32_bf16 v[32:35], v[92:95], v[152:155], v[32:35]
	v_mfma_f32_16x16x32_bf16 v[28:31], v[140:143], v[96:99], v[28:31]
	v_mfma_f32_16x16x32_bf16 v[24:27], v[140:143], v[100:103], v[24:27]
	v_mfma_f32_16x16x32_bf16 v[20:23], v[140:143], v[148:151], v[20:23]
	v_mfma_f32_16x16x32_bf16 v[16:19], v[140:143], v[152:155], v[16:19]
	v_mfma_f32_16x16x32_bf16 v[12:15], v[144:147], v[96:99], v[12:15]
	v_mfma_f32_16x16x32_bf16 v[8:11], v[144:147], v[100:103], v[8:11]
	s_setprio 0
	s_barrier
	ds_write2_b32 v115, v60, v56 offset1:16
	ds_write2_b32 v115, v61, v57 offset0:132 offset1:148
	v_add_u32_e32 v56, 0x400, v115
	ds_write2_b32 v56, v62, v58 offset0:8 offset1:24
	ds_write2_b32 v56, v63, v59 offset0:140 offset1:156
	ds_write2_b32 v115, v52, v48 offset0:32 offset1:48
	ds_write2_b32 v115, v53, v49 offset0:164 offset1:180
	ds_write2_b32 v56, v54, v50 offset0:40 offset1:56
	ds_write2_b32 v56, v55, v51 offset0:172 offset1:188
	v_add_u32_e32 v48, 0x2000, v115
	ds_write2_b32 v48, v44, v40 offset0:64 offset1:80
	ds_write2_b32 v48, v45, v41 offset0:196 offset1:212
	v_add_u32_e32 v40, 0x2400, v115
	ds_write2_b32 v40, v46, v42 offset0:72 offset1:88
	ds_write2_b32 v40, v47, v43 offset0:204 offset1:220
	ds_write2_b32 v48, v36, v32 offset0:96 offset1:112
	ds_write2_b32 v48, v37, v33 offset0:228 offset1:244
	ds_write2_b32 v40, v38, v34 offset0:104 offset1:120
	ds_write2_b32 v40, v39, v35 offset0:236 offset1:252
	v_add_u32_e32 v32, 0x4000, v115
	ds_write2_b32 v32, v28, v24 offset0:128 offset1:144
	v_add_u32_e32 v24, 0x4400, v115
	ds_write2_b32 v24, v29, v25 offset0:4 offset1:20
	ds_write2_b32 v24, v30, v26 offset0:136 offset1:152
	v_add_u32_e32 v25, 0x4800, v115
	ds_write2_b32 v25, v31, v27 offset0:12 offset1:28
	ds_write2_b32 v32, v20, v16 offset0:160 offset1:176
	ds_write2_b32 v24, v21, v17 offset0:36 offset1:52
	ds_write2_b32 v24, v22, v18 offset0:168 offset1:184
	ds_write2_b32 v25, v23, v19 offset0:44 offset1:60
	v_add_u32_e32 v16, 0x6000, v115
	ds_write2_b32 v16, v12, v8 offset0:192 offset1:208
	v_add_u32_e32 v8, 0x6400, v115
	ds_write2_b32 v8, v13, v9 offset0:68 offset1:84
	ds_write2_b32 v8, v14, v10 offset0:200 offset1:216
	v_add_u32_e32 v9, 0x6800, v115
	ds_write2_b32 v9, v15, v11 offset0:76 offset1:92
	ds_write2_b32 v16, v4, v0 offset0:224 offset1:240
	ds_write2_b32 v8, v5, v1 offset0:100 offset1:116
	ds_write2_b32 v8, v6, v2 offset0:232 offset1:248
	ds_write2_b32 v9, v7, v3 offset0:108 offset1:124
	v_or_b32_e32 v0, s23, v116
	v_ashrrev_i32_e32 v1, 31, v0
	v_lshlrev_b64 v[2:3], 2, v[0:1]
	v_lshl_add_u64 v[0:1], s[12:13], 0, v[2:3]
	v_lshl_add_u64 v[2:3], s[8:9], 0, v[2:3]
	v_add_u32_e32 v4, s24, v129
	s_mov_b32 s14, 0
	s_waitcnt lgkmcnt(0)
	s_barrier

.LBB0_442:
	s_and_b32 s10, s16, 0x380
	v_add_lshl_u32 v70, v138, s10, 11
	v_lshl_add_u64 v[96:97], v[84:85], 0, v[70:71]
	v_add_lshl_u32 v70, v140, s10, 11
	v_lshl_add_u64 v[98:99], v[88:89], 0, v[70:71]
	v_add_lshl_u32 v70, v142, s10, 11
	s_lshl_b32 s22, s21, 7
	v_lshl_add_u64 v[100:101], v[84:85], 0, v[70:71]
	v_add_lshl_u32 v70, v144, s10, 11
	s_ashr_i32 s10, s21, 3
	s_and_b32 s22, s22, 0x380
	v_add_u32_e32 v2, 0x4000, v133
	v_lshl_add_u64 v[102:103], v[92:93], 0, v[70:71]
	s_add_i32 s11, s10, s15
	v_add_lshl_u32 v70, s22, v132, 11
	v_readfirstlane_b32 s23, v2
	s_lshl_b32 s11, s11, 7
	v_lshl_add_u64 v[0:1], v[72:73], 0, v[70:71]
	s_mov_b32 m0, s23
	v_readfirstlane_b32 s23, v133
	global_load_lds_dwordx4 v[0:1], off
	v_add_u32_e32 v0, s11, v132
	v_ashrrev_i32_e32 v1, 31, v0
	v_lshlrev_b64 v[0:1], 11, v[0:1]
	v_lshl_add_u64 v[0:1], v[78:79], 0, v[0:1]
	s_mov_b32 m0, s23
	v_add_lshl_u32 v70, s22, v119, 11
	v_readfirstlane_b32 s23, v148
	global_load_lds_dwordx4 v[0:1], off
	v_lshl_add_u64 v[0:1], v[74:75], 0, v[70:71]
	s_mov_b32 m0, s23
	v_add_u32_e32 v2, 0x400, v133
	global_load_lds_dwordx4 v[0:1], off
	v_add_u32_e32 v0, s11, v119
	v_ashrrev_i32_e32 v1, 31, v0
	v_lshlrev_b64 v[0:1], 11, v[0:1]
	v_readfirstlane_b32 s23, v2
	v_lshl_add_u64 v[0:1], v[80:81], 0, v[0:1]
	s_mov_b32 m0, s23
	v_add_lshl_u32 v70, s22, v120, 11
	v_readfirstlane_b32 s23, v149
	global_load_lds_dwordx4 v[0:1], off
	v_lshl_add_u64 v[0:1], v[72:73], 0, v[70:71]
	s_mov_b32 m0, s23
	v_add_u32_e32 v2, 0x800, v133
	global_load_lds_dwordx4 v[0:1], off
	v_add_u32_e32 v0, s11, v120
	v_ashrrev_i32_e32 v1, 31, v0
	v_lshlrev_b64 v[0:1], 11, v[0:1]
	v_readfirstlane_b32 s23, v2
	v_lshl_add_u64 v[0:1], v[78:79], 0, v[0:1]
	s_mov_b32 m0, s23
	v_add_lshl_u32 v70, s22, v118, 11
	v_readfirstlane_b32 s23, v150
	global_load_lds_dwordx4 v[0:1], off
	v_lshl_add_u64 v[0:1], v[76:77], 0, v[70:71]
	s_mov_b32 m0, s23
	v_add_u32_e32 v2, 0xc00, v133
	global_load_lds_dwordx4 v[0:1], off
	v_add_u32_e32 v0, s11, v118
	v_ashrrev_i32_e32 v1, 31, v0
	v_lshlrev_b64 v[0:1], 11, v[0:1]
	v_readfirstlane_b32 s11, v2
	v_lshl_add_u64 v[0:1], v[82:83], 0, v[0:1]
	s_mov_b32 m0, s11
	s_lshl_b32 s23, s10, 7
	global_load_lds_dwordx4 v[0:1], off
	v_add_u32_e32 v0, s23, v139
	v_ashrrev_i32_e32 v1, 31, v0
	v_lshlrev_b64 v[0:1], 11, v[0:1]
	v_lshl_add_u64 v[104:105], v[86:87], 0, v[0:1]
	v_add_u32_e32 v0, s23, v141
	v_ashrrev_i32_e32 v1, 31, v0
	v_lshlrev_b64 v[0:1], 11, v[0:1]
	v_lshl_add_u64 v[106:107], v[90:91], 0, v[0:1]
	v_add_u32_e32 v0, s23, v143
	v_ashrrev_i32_e32 v1, 31, v0
	v_lshlrev_b64 v[0:1], 11, v[0:1]
	v_lshl_add_u64 v[108:109], v[86:87], 0, v[0:1]
	v_add_u32_e32 v0, s23, v145
	v_ashrrev_i32_e32 v1, 31, v0
	v_lshlrev_b64 v[0:1], 11, v[0:1]
	v_lshl_add_u64 v[110:111], v[94:95], 0, v[0:1]
	s_mov_b64 s[10:11], 0
	s_mov_b32 s24, 0
	v_mov_b32_e32 v0, 0
	v_mov_b32_e32 v1, v71
	v_mov_b32_e32 v2, v71
	v_mov_b32_e32 v3, v71
	v_mov_b32_e32 v4, 0
	v_mov_b32_e32 v5, v71
	v_mov_b32_e32 v6, v71
	v_mov_b32_e32 v7, v71
	v_mov_b32_e32 v8, 0
	v_mov_b32_e32 v9, v71
	v_mov_b32_e32 v10, v71
	v_mov_b32_e32 v11, v71
	v_mov_b32_e32 v12, 0
	v_mov_b32_e32 v13, v71
	v_mov_b32_e32 v14, v71
	v_mov_b32_e32 v15, v71
	v_mov_b32_e32 v16, 0
	v_mov_b32_e32 v17, v71
	v_mov_b32_e32 v18, v71
	v_mov_b32_e32 v19, v71
	v_mov_b32_e32 v20, 0
	v_mov_b32_e32 v21, v71
	v_mov_b32_e32 v22, v71
	v_mov_b32_e32 v23, v71
	v_mov_b32_e32 v24, 0
	v_mov_b32_e32 v25, v71
	v_mov_b32_e32 v26, v71
	v_mov_b32_e32 v27, v71
	v_mov_b32_e32 v28, 0
	v_mov_b32_e32 v29, v71
	v_mov_b32_e32 v30, v71
	v_mov_b32_e32 v31, v71
	v_mov_b32_e32 v32, 0
	v_mov_b32_e32 v33, v71
	v_mov_b32_e32 v34, v71
	v_mov_b32_e32 v35, v71
	v_mov_b32_e32 v36, 0
	v_mov_b32_e32 v37, v71
	v_mov_b32_e32 v38, v71
	v_mov_b32_e32 v39, v71
	v_mov_b32_e32 v40, 0
	v_mov_b32_e32 v41, v71
	v_mov_b32_e32 v42, v71
	v_mov_b32_e32 v43, v71
	v_mov_b32_e32 v44, 0
	v_mov_b32_e32 v45, v71
	v_mov_b32_e32 v46, v71
	v_mov_b32_e32 v47, v71
	v_mov_b32_e32 v48, 0
	v_mov_b32_e32 v49, v71
	v_mov_b32_e32 v50, v71
	v_mov_b32_e32 v51, v71
	v_mov_b32_e32 v52, 0
	v_mov_b32_e32 v53, v71
	v_mov_b32_e32 v54, v71
	v_mov_b32_e32 v55, v71
	v_mov_b32_e32 v56, 0
	v_mov_b32_e32 v57, v71
	v_mov_b32_e32 v58, v71
	v_mov_b32_e32 v59, v71
	v_mov_b32_e32 v60, 0
	v_mov_b32_e32 v61, v71
	v_mov_b32_e32 v62, v71
	v_mov_b32_e32 v63, v71
	s_waitcnt vmcnt(0) lgkmcnt(0)
	s_barrier
	v_lshlrev_b32_e32 v186, 1, v130
	v_lshlrev_b32_e32 v187, 1, v131
	v_add3_u32 v186, 0, v186, v187
	v_add_u32_e32 v188, 0x4000, v186
	s_nop 0
	v_readfirstlane_b32 s82, v188
	v_lshl_add_u32 v188, v123, 1, 0
	s_nop 0
	v_readfirstlane_b32 s83, v186
	v_add3_u32 v188, v188, v187, s17
	s_nop 0
	v_readfirstlane_b32 s84, v188
	v_add_u32_e32 v188, 0x400, v186
	s_nop 0
	v_readfirstlane_b32 s85, v188
	v_lshl_add_u32 v188, v121, 1, 0
	v_add3_u32 v188, v188, v187, s17
	s_nop 0
	v_readfirstlane_b32 s86, v188
	v_add_u32_e32 v188, 0x800, v186
	s_nop 0
	v_readfirstlane_b32 s87, v188
	v_lshl_add_u32 v188, v122, 1, 0
	v_add3_u32 v187, v188, v187, s17
	s_nop 0
	v_readfirstlane_b32 s88, v187
	v_add_u32_e32 v186, 0xc00, v186
	s_nop 0
	v_readfirstlane_b32 s89, v186
	v_subrev_u32_e32 v189, s52, v96
	v_subrev_u32_e32 v190, s52, v104
	v_subrev_u32_e32 v191, s52, v98
	v_subrev_u32_e32 v192, s52, v106
	v_subrev_u32_e32 v193, s52, v100
	v_subrev_u32_e32 v194, s52, v108
	v_subrev_u32_e32 v195, s52, v102
	v_subrev_u32_e32 v196, s52, v110
	s_bitcmp1_b32 s32, 0
	s_cbranch_scc1 .Lxk_443
.LBB0_443:
	s_and_b32 s25, s24, 0x4000
	s_xor_b32 s26, s25, 0x4000
	s_lshl_b32 s26, s26, 1
	s_add_i32 s26, s26, 32
	s_add_u32 s90, s52, s10
	s_addc_u32 s91, s53, s11
	s_add_i32 m0, s26, s82
	s_lshl_b32 s25, s25, 1
	global_load_lds_dwordx4 v189, s[90:91]
	s_add_i32 m0, s26, s83
	s_add_i32 s25, s25, 32
	global_load_lds_dwordx4 v190, s[90:91]
	s_add_i32 m0, s26, s84
	v_lshlrev_b32_e32 v70, 1, v129
	global_load_lds_dwordx4 v191, s[90:91]
	s_add_i32 m0, s26, s85
	v_add3_u32 v151, s25, v124, v70
	global_load_lds_dwordx4 v192, s[90:91]
	s_add_i32 m0, s26, s86
	v_lshlrev_b32_e32 v152, 1, v117
	global_load_lds_dwordx4 v193, s[90:91]
	s_add_i32 m0, s26, s87
	v_add3_u32 v70, s25, v125, v70
	global_load_lds_dwordx4 v194, s[90:91]
	s_add_i32 m0, s26, s88
	v_add_u32_e32 v172, v151, v152
	global_load_lds_dwordx4 v195, s[90:91]
	s_add_i32 m0, s26, s89
	v_add_u32_e32 v181, v70, v152
	global_load_lds_dwordx4 v196, s[90:91]
	ds_read_b128 v[152:155], v172
	ds_read_b128 v[160:163], v181 offset:16384
	ds_read_b128 v[164:167], v181 offset:18432
	ds_read_b128 v[176:179], v181 offset:20480
	ds_read_b128 v[182:185], v181 offset:22528
	ds_read_b128 v[156:159], v172 offset:2048
	ds_read_b128 v[168:171], v172 offset:4096
	ds_read_b128 v[172:175], v172 offset:6144
	v_lshlrev_b32_e32 v236, 1, v116
	v_add_u32_e32 v151, v151, v236
	v_add_u32_e32 v70, v70, v236
	ds_read_b128 v[204:207], v151
	ds_read_b128 v[208:211], v70 offset:16384
	ds_read_b128 v[212:215], v70 offset:18432
	ds_read_b128 v[216:219], v70 offset:20480
	ds_read_b128 v[220:223], v70 offset:22528
	ds_read_b128 v[224:227], v151 offset:2048
	ds_read_b128 v[228:231], v151 offset:4096
	ds_read_b128 v[232:235], v151 offset:6144
	s_setprio 1
	s_waitcnt lgkmcnt(11)
	v_mfma_f32_16x16x32_bf16 v[60:63], v[152:155], v[160:163], v[60:63]
	v_mfma_f32_16x16x32_bf16 v[56:59], v[152:155], v[164:167], v[56:59]
	v_mfma_f32_16x16x32_bf16 v[52:55], v[152:155], v[176:179], v[52:55]
	v_mfma_f32_16x16x32_bf16 v[48:51], v[152:155], v[182:185], v[48:51]
	s_waitcnt lgkmcnt(10)
	v_mfma_f32_16x16x32_bf16 v[44:47], v[156:159], v[160:163], v[44:47]
	v_mfma_f32_16x16x32_bf16 v[40:43], v[156:159], v[164:167], v[40:43]
	v_mfma_f32_16x16x32_bf16 v[36:39], v[156:159], v[176:179], v[36:39]
	v_mfma_f32_16x16x32_bf16 v[32:35], v[156:159], v[182:185], v[32:35]
	s_waitcnt lgkmcnt(9)
	v_mfma_f32_16x16x32_bf16 v[28:31], v[168:171], v[160:163], v[28:31]
	v_mfma_f32_16x16x32_bf16 v[24:27], v[168:171], v[164:167], v[24:27]
	v_mfma_f32_16x16x32_bf16 v[20:23], v[168:171], v[176:179], v[20:23]
	v_mfma_f32_16x16x32_bf16 v[16:19], v[168:171], v[182:185], v[16:19]
	s_waitcnt lgkmcnt(8)
	v_mfma_f32_16x16x32_bf16 v[12:15], v[172:175], v[160:163], v[12:15]
	v_mfma_f32_16x16x32_bf16 v[8:11], v[172:175], v[164:167], v[8:11]
	v_mfma_f32_16x16x32_bf16 v[4:7], v[172:175], v[176:179], v[4:7]
	v_mfma_f32_16x16x32_bf16 v[0:3], v[172:175], v[182:185], v[0:3]
	s_waitcnt lgkmcnt(3)
	v_mfma_f32_16x16x32_bf16 v[60:63], v[204:207], v[208:211], v[60:63]
	v_mfma_f32_16x16x32_bf16 v[56:59], v[204:207], v[212:215], v[56:59]
	v_mfma_f32_16x16x32_bf16 v[52:55], v[204:207], v[216:219], v[52:55]
	v_mfma_f32_16x16x32_bf16 v[48:51], v[204:207], v[220:223], v[48:51]
	s_waitcnt lgkmcnt(2)
	v_mfma_f32_16x16x32_bf16 v[44:47], v[224:227], v[208:211], v[44:47]
	v_mfma_f32_16x16x32_bf16 v[40:43], v[224:227], v[212:215], v[40:43]
	v_mfma_f32_16x16x32_bf16 v[36:39], v[224:227], v[216:219], v[36:39]
	v_mfma_f32_16x16x32_bf16 v[32:35], v[224:227], v[220:223], v[32:35]
	s_waitcnt lgkmcnt(1)
	v_mfma_f32_16x16x32_bf16 v[28:31], v[228:231], v[208:211], v[28:31]
	v_mfma_f32_16x16x32_bf16 v[24:27], v[228:231], v[212:215], v[24:27]
	v_mfma_f32_16x16x32_bf16 v[20:23], v[228:231], v[216:219], v[20:23]
	v_mfma_f32_16x16x32_bf16 v[16:19], v[228:231], v[220:223], v[16:19]
	s_waitcnt lgkmcnt(0)
	v_mfma_f32_16x16x32_bf16 v[12:15], v[232:235], v[208:211], v[12:15]
	v_mfma_f32_16x16x32_bf16 v[8:11], v[232:235], v[212:215], v[8:11]
	v_mfma_f32_16x16x32_bf16 v[4:7], v[232:235], v[216:219], v[4:7]
	v_mfma_f32_16x16x32_bf16 v[0:3], v[232:235], v[220:223], v[0:3]
	s_setprio 0
	s_add_u32 s10, s10, 0x80
	s_addc_u32 s11, s11, 0
	s_addk_i32 s24, 0x4000
	s_cmpk_eq_i32 s10, 0x780
	s_waitcnt vmcnt(0)
	s_barrier
	s_cbranch_scc0 .LBB0_443
	s_branch .Lxk_exit_443
.Lxk_443:
	s_and_b32 s25, s24, 0x4000
	s_xor_b32 s26, s25, 0x4000
	s_lshl_b32 s26, s26, 1
	s_add_i32 s26, s26, 32
	s_add_u32 s90, s52, s10
	s_addc_u32 s91, s53, s11
	s_add_i32 m0, s26, s82
	s_lshl_b32 s25, s25, 1
	global_load_lds_dwordx4 v189, s[90:91]
	s_add_i32 m0, s26, s83
	s_add_i32 s25, s25, 32
	global_load_lds_dwordx4 v190, s[90:91]
	s_add_i32 m0, s26, s84
	v_lshlrev_b32_e32 v70, 1, v129
	global_load_lds_dwordx4 v191, s[90:91]
	s_add_i32 m0, s26, s85
	v_add3_u32 v151, s25, v124, v70
	global_load_lds_dwordx4 v192, s[90:91]
	s_add_i32 m0, s26, s86
	v_lshlrev_b32_e32 v152, 1, v117
	global_load_lds_dwordx4 v193, s[90:91]
	s_add_i32 m0, s26, s87
	v_add3_u32 v70, s25, v125, v70
	global_load_lds_dwordx4 v194, s[90:91]
	s_add_i32 m0, s26, s88
	v_add_u32_e32 v172, v151, v152
	global_load_lds_dwordx4 v195, s[90:91]
	s_add_i32 m0, s26, s89
	v_add_u32_e32 v181, v70, v152
	global_load_lds_dwordx4 v196, s[90:91]
	ds_read_b128 v[152:155], v172
	ds_read_b128 v[160:163], v181 offset:16384
	ds_read_b128 v[164:167], v181 offset:18432
	ds_read_b128 v[176:179], v181 offset:20480
	ds_read_b128 v[182:185], v181 offset:22528
	ds_read_b128 v[156:159], v172 offset:2048
	ds_read_b128 v[168:171], v172 offset:4096
	ds_read_b128 v[172:175], v172 offset:6144
	v_lshlrev_b32_e32 v236, 1, v116
	v_add_u32_e32 v151, v151, v236
	v_add_u32_e32 v70, v70, v236
	ds_read_b128 v[204:207], v151
	ds_read_b128 v[208:211], v70 offset:16384
	ds_read_b128 v[212:215], v70 offset:18432
	ds_read_b128 v[216:219], v70 offset:20480
	ds_read_b128 v[220:223], v70 offset:22528
	ds_read_b128 v[224:227], v151 offset:2048
	ds_read_b128 v[228:231], v151 offset:4096
	ds_read_b128 v[232:235], v151 offset:6144
	s_setprio 3
	s_waitcnt lgkmcnt(11)
	v_mfma_f32_16x16x32_bf16 v[60:63], v[152:155], v[160:163], v[60:63]
	v_mfma_f32_16x16x32_bf16 v[56:59], v[152:155], v[164:167], v[56:59]
	v_mfma_f32_16x16x32_bf16 v[52:55], v[152:155], v[176:179], v[52:55]
	v_mfma_f32_16x16x32_bf16 v[48:51], v[152:155], v[182:185], v[48:51]
	s_waitcnt lgkmcnt(10)
	v_mfma_f32_16x16x32_bf16 v[44:47], v[156:159], v[160:163], v[44:47]
	v_mfma_f32_16x16x32_bf16 v[40:43], v[156:159], v[164:167], v[40:43]
	v_mfma_f32_16x16x32_bf16 v[36:39], v[156:159], v[176:179], v[36:39]
	v_mfma_f32_16x16x32_bf16 v[32:35], v[156:159], v[182:185], v[32:35]
	s_waitcnt lgkmcnt(9)
	v_mfma_f32_16x16x32_bf16 v[28:31], v[168:171], v[160:163], v[28:31]
	v_mfma_f32_16x16x32_bf16 v[24:27], v[168:171], v[164:167], v[24:27]
	v_mfma_f32_16x16x32_bf16 v[20:23], v[168:171], v[176:179], v[20:23]
	v_mfma_f32_16x16x32_bf16 v[16:19], v[168:171], v[182:185], v[16:19]
	s_waitcnt lgkmcnt(8)
	v_mfma_f32_16x16x32_bf16 v[12:15], v[172:175], v[160:163], v[12:15]
	v_mfma_f32_16x16x32_bf16 v[8:11], v[172:175], v[164:167], v[8:11]
	v_mfma_f32_16x16x32_bf16 v[4:7], v[172:175], v[176:179], v[4:7]
	v_mfma_f32_16x16x32_bf16 v[0:3], v[172:175], v[182:185], v[0:3]
	s_waitcnt lgkmcnt(3)
	v_mfma_f32_16x16x32_bf16 v[60:63], v[204:207], v[208:211], v[60:63]
	v_mfma_f32_16x16x32_bf16 v[56:59], v[204:207], v[212:215], v[56:59]
	v_mfma_f32_16x16x32_bf16 v[52:55], v[204:207], v[216:219], v[52:55]
	v_mfma_f32_16x16x32_bf16 v[48:51], v[204:207], v[220:223], v[48:51]
	s_waitcnt lgkmcnt(2)
	v_mfma_f32_16x16x32_bf16 v[44:47], v[224:227], v[208:211], v[44:47]
	v_mfma_f32_16x16x32_bf16 v[40:43], v[224:227], v[212:215], v[40:43]
	v_mfma_f32_16x16x32_bf16 v[36:39], v[224:227], v[216:219], v[36:39]
	v_mfma_f32_16x16x32_bf16 v[32:35], v[224:227], v[220:223], v[32:35]
	s_waitcnt lgkmcnt(1)
	v_mfma_f32_16x16x32_bf16 v[28:31], v[228:231], v[208:211], v[28:31]
	v_mfma_f32_16x16x32_bf16 v[24:27], v[228:231], v[212:215], v[24:27]
	v_mfma_f32_16x16x32_bf16 v[20:23], v[228:231], v[216:219], v[20:23]
	v_mfma_f32_16x16x32_bf16 v[16:19], v[228:231], v[220:223], v[16:19]
	s_waitcnt lgkmcnt(0)
	v_mfma_f32_16x16x32_bf16 v[12:15], v[232:235], v[208:211], v[12:15]
	v_mfma_f32_16x16x32_bf16 v[8:11], v[232:235], v[212:215], v[8:11]
	v_mfma_f32_16x16x32_bf16 v[4:7], v[232:235], v[216:219], v[4:7]
	v_mfma_f32_16x16x32_bf16 v[0:3], v[232:235], v[220:223], v[0:3]
	s_setprio 2
	s_add_u32 s10, s10, 0x80
	s_addc_u32 s11, s11, 0
	s_addk_i32 s24, 0x4000
	s_cmpk_eq_i32 s10, 0x780
	s_waitcnt vmcnt(0)
	s_barrier
	s_cbranch_scc0 .Lxk_443
.Lxk_exit_443:
	ds_read_b128 v[96:99], v69 offset:32768
	ds_read_b128 v[100:103], v69 offset:34816
	ds_read_b128 v[104:107], v135 offset:49152
	ds_read_b128 v[108:111], v135 offset:51200
	ds_read_b128 v[152:155], v69 offset:36864
	ds_read_b128 v[156:159], v69 offset:38912
	ds_read_b128 v[160:163], v135 offset:53248
	ds_read_b128 v[164:167], v135 offset:55296
	s_setprio 1
	s_waitcnt lgkmcnt(1)
	v_mfma_f32_16x16x32_bf16 v[4:7], v[156:159], v[160:163], v[4:7]
	s_waitcnt lgkmcnt(0)
	v_mfma_f32_16x16x32_bf16 v[0:3], v[156:159], v[164:167], v[0:3]
	v_mfma_f32_16x16x32_bf16 v[60:63], v[96:99], v[104:107], v[60:63]
	v_mfma_f32_16x16x32_bf16 v[56:59], v[96:99], v[108:111], v[56:59]
	v_mfma_f32_16x16x32_bf16 v[52:55], v[96:99], v[160:163], v[52:55]
	v_mfma_f32_16x16x32_bf16 v[48:51], v[96:99], v[164:167], v[48:51]
	v_mfma_f32_16x16x32_bf16 v[44:47], v[100:103], v[104:107], v[44:47]
	v_mfma_f32_16x16x32_bf16 v[40:43], v[100:103], v[108:111], v[40:43]
	v_mfma_f32_16x16x32_bf16 v[36:39], v[100:103], v[160:163], v[36:39]
	v_mfma_f32_16x16x32_bf16 v[32:35], v[100:103], v[164:167], v[32:35]
	v_mfma_f32_16x16x32_bf16 v[28:31], v[152:155], v[104:107], v[28:31]
	v_mfma_f32_16x16x32_bf16 v[24:27], v[152:155], v[108:111], v[24:27]
	v_mfma_f32_16x16x32_bf16 v[20:23], v[152:155], v[160:163], v[20:23]
	v_mfma_f32_16x16x32_bf16 v[16:19], v[152:155], v[164:167], v[16:19]
	v_mfma_f32_16x16x32_bf16 v[12:15], v[156:159], v[104:107], v[12:15]
	v_mfma_f32_16x16x32_bf16 v[8:11], v[156:159], v[108:111], v[8:11]
	s_setprio 0
	ds_read_b128 v[96:99], v136 offset:32768
	ds_read_b128 v[100:103], v136 offset:34816
	ds_read_b128 v[104:107], v137 offset:49152
	ds_read_b128 v[108:111], v137 offset:51200
	ds_read_b128 v[152:155], v136 offset:36864
	ds_read_b128 v[156:159], v136 offset:38912
	ds_read_b128 v[160:163], v137 offset:53248
	ds_read_b128 v[164:167], v137 offset:55296
	s_setprio 1
	s_waitcnt lgkmcnt(1)
	v_mfma_f32_16x16x32_bf16 v[4:7], v[156:159], v[160:163], v[4:7]
	s_waitcnt lgkmcnt(0)
	v_mfma_f32_16x16x32_bf16 v[0:3], v[156:159], v[164:167], v[0:3]
	v_mfma_f32_16x16x32_bf16 v[60:63], v[96:99], v[104:107], v[60:63]
	v_mfma_f32_16x16x32_bf16 v[56:59], v[96:99], v[108:111], v[56:59]
	v_mfma_f32_16x16x32_bf16 v[52:55], v[96:99], v[160:163], v[52:55]
	v_mfma_f32_16x16x32_bf16 v[48:51], v[96:99], v[164:167], v[48:51]
	v_mfma_f32_16x16x32_bf16 v[44:47], v[100:103], v[104:107], v[44:47]
	v_mfma_f32_16x16x32_bf16 v[40:43], v[100:103], v[108:111], v[40:43]
	v_mfma_f32_16x16x32_bf16 v[36:39], v[100:103], v[160:163], v[36:39]
	v_mfma_f32_16x16x32_bf16 v[32:35], v[100:103], v[164:167], v[32:35]
	v_mfma_f32_16x16x32_bf16 v[28:31], v[152:155], v[104:107], v[28:31]
	v_mfma_f32_16x16x32_bf16 v[24:27], v[152:155], v[108:111], v[24:27]
	v_mfma_f32_16x16x32_bf16 v[20:23], v[152:155], v[160:163], v[20:23]
	v_mfma_f32_16x16x32_bf16 v[16:19], v[152:155], v[164:167], v[16:19]
	v_mfma_f32_16x16x32_bf16 v[12:15], v[156:159], v[104:107], v[12:15]
	v_mfma_f32_16x16x32_bf16 v[8:11], v[156:159], v[108:111], v[8:11]
	s_setprio 0
	s_barrier
	ds_write2_b32 v134, v60, v56 offset1:16
	ds_write2_b32 v134, v61, v57 offset0:132 offset1:148
	v_add_u32_e32 v56, 0x400, v134
	ds_write2_b32 v56, v62, v58 offset0:8 offset1:24
	ds_write2_b32 v56, v63, v59 offset0:140 offset1:156
	ds_write2_b32 v134, v52, v48 offset0:32 offset1:48
	ds_write2_b32 v134, v53, v49 offset0:164 offset1:180
	ds_write2_b32 v56, v54, v50 offset0:40 offset1:56
	ds_write2_b32 v56, v55, v51 offset0:172 offset1:188
	v_add_u32_e32 v48, 0x2000, v134
	ds_write2_b32 v48, v44, v40 offset0:64 offset1:80
	ds_write2_b32 v48, v45, v41 offset0:196 offset1:212
	v_add_u32_e32 v40, 0x2400, v134
	ds_write2_b32 v40, v46, v42 offset0:72 offset1:88
	ds_write2_b32 v40, v47, v43 offset0:204 offset1:220
	ds_write2_b32 v48, v36, v32 offset0:96 offset1:112
	ds_write2_b32 v48, v37, v33 offset0:228 offset1:244
	ds_write2_b32 v40, v38, v34 offset0:104 offset1:120
	ds_write2_b32 v40, v39, v35 offset0:236 offset1:252
	v_add_u32_e32 v32, 0x4000, v134
	ds_write2_b32 v32, v28, v24 offset0:128 offset1:144
	v_add_u32_e32 v24, 0x4400, v134
	ds_write2_b32 v24, v29, v25 offset0:4 offset1:20
	ds_write2_b32 v24, v30, v26 offset0:136 offset1:152
	v_add_u32_e32 v25, 0x4800, v134
	ds_write2_b32 v25, v31, v27 offset0:12 offset1:28
	ds_write2_b32 v32, v20, v16 offset0:160 offset1:176
	ds_write2_b32 v24, v21, v17 offset0:36 offset1:52
	ds_write2_b32 v24, v22, v18 offset0:168 offset1:184
	ds_write2_b32 v25, v23, v19 offset0:44 offset1:60
	v_add_u32_e32 v16, 0x6000, v134
	ds_write2_b32 v16, v12, v8 offset0:192 offset1:208
	v_add_u32_e32 v8, 0x6400, v134
	ds_write2_b32 v8, v13, v9 offset0:68 offset1:84
	ds_write2_b32 v8, v14, v10 offset0:200 offset1:216
	v_add_u32_e32 v9, 0x6800, v134
	ds_write2_b32 v9, v15, v11 offset0:76 offset1:92
	ds_write2_b32 v16, v4, v0 offset0:224 offset1:240
	ds_write2_b32 v8, v5, v1 offset0:100 offset1:116
	ds_write2_b32 v8, v6, v2 offset0:232 offset1:248
	ds_write2_b32 v9, v7, v3 offset0:108 offset1:124
	v_or_b32_e32 v0, s22, v113
	v_lshlrev_b32_e32 v70, 2, v0
	v_lshl_add_u64 v[0:1], s[12:13], 0, v[70:71]
	v_lshl_add_u64 v[2:3], s[8:9], 0, v[70:71]
	v_add_u32_e32 v4, s23, v146
	s_mov_b32 s10, 0
	s_waitcnt lgkmcnt(0)
	s_barrier

.LBB0_604:
	s_ashr_i32 s10, s14, 31
	s_lshr_b32 s10, s10, 27
	s_add_i32 s10, s14, s10
	s_ashr_i32 s10, s10, 5
	s_lshl_b32 s15, s10, 7
	s_lshl_b32 s10, s10, 12
	s_lshl_b32 s11, s14, 7
	s_sub_i32 s16, s11, s10
	v_add_u32_e32 v0, s16, v106
	v_ashrrev_i32_e32 v1, 31, v0
	v_add_u32_e32 v2, 0x4000, v107
	v_lshlrev_b64 v[0:1], 11, v[0:1]
	v_readfirstlane_b32 s11, v2
	v_lshl_add_u64 v[0:1], v[66:67], 0, v[0:1]
	s_mov_b32 m0, s11
	v_readfirstlane_b32 s11, v107
	global_load_lds_dwordx4 v[0:1], off
	v_add_u32_e32 v0, s15, v106
	v_ashrrev_i32_e32 v1, 31, v0
	v_lshlrev_b64 v[0:1], 11, v[0:1]
	v_lshl_add_u64 v[2:3], v[72:73], 0, v[0:1]
	s_mov_b32 m0, s11
	v_readfirstlane_b32 s11, v130
	global_load_lds_dwordx4 v[2:3], off
	v_add_u32_e32 v2, s16, v108
	v_ashrrev_i32_e32 v3, 31, v2
	v_lshlrev_b64 v[2:3], 11, v[2:3]
	v_lshl_add_u64 v[2:3], v[68:69], 0, v[2:3]
	s_mov_b32 m0, s11
	v_add_u32_e32 v4, 0x400, v107
	global_load_lds_dwordx4 v[2:3], off
	v_add_u32_e32 v2, s15, v108
	v_ashrrev_i32_e32 v3, 31, v2
	v_lshlrev_b64 v[2:3], 11, v[2:3]
	v_readfirstlane_b32 s11, v4
	v_lshl_add_u64 v[2:3], v[74:75], 0, v[2:3]
	s_mov_b32 m0, s11
	v_readfirstlane_b32 s11, v131
	global_load_lds_dwordx4 v[2:3], off
	v_add_u32_e32 v2, s16, v110
	v_ashrrev_i32_e32 v3, 31, v2
	v_lshlrev_b64 v[2:3], 11, v[2:3]
	v_lshl_add_u64 v[2:3], v[66:67], 0, v[2:3]
	s_mov_b32 m0, s11
	v_add_u32_e32 v4, 0x800, v107
	global_load_lds_dwordx4 v[2:3], off
	v_add_u32_e32 v2, s15, v110
	v_ashrrev_i32_e32 v3, 31, v2
	v_lshlrev_b64 v[2:3], 11, v[2:3]
	v_readfirstlane_b32 s11, v4
	v_lshl_add_u64 v[2:3], v[72:73], 0, v[2:3]
	s_mov_b32 m0, s11
	v_readfirstlane_b32 s11, v132
	global_load_lds_dwordx4 v[2:3], off
	v_add_u32_e32 v2, s16, v112
	v_ashrrev_i32_e32 v3, 31, v2
	v_lshlrev_b64 v[2:3], 11, v[2:3]
	v_lshl_add_u64 v[2:3], v[70:71], 0, v[2:3]
	s_mov_b32 m0, s11
	v_add_u32_e32 v4, 0xc00, v107
	global_load_lds_dwordx4 v[2:3], off
	v_add_u32_e32 v2, s15, v112
	v_ashrrev_i32_e32 v3, 31, v2
	v_lshlrev_b64 v[2:3], 11, v[2:3]
	v_readfirstlane_b32 s11, v4
	v_lshl_add_u64 v[2:3], v[76:77], 0, v[2:3]
	s_mov_b32 m0, s11
	v_lshl_add_u64 v[92:93], v[80:81], 0, v[0:1]
	global_load_lds_dwordx4 v[2:3], off
	v_subrev_u32_e32 v0, s10, v123
	v_ashrrev_i32_e32 v1, 31, v0
	v_lshlrev_b64 v[0:1], 11, v[0:1]
	v_lshl_add_u64 v[94:95], v[82:83], 0, v[0:1]
	v_add_u32_e32 v0, s15, v124
	v_ashrrev_i32_e32 v1, 31, v0
	v_lshlrev_b64 v[0:1], 11, v[0:1]
	v_lshl_add_u64 v[96:97], v[84:85], 0, v[0:1]
	v_subrev_u32_e32 v0, s10, v125
	v_ashrrev_i32_e32 v1, 31, v0
	v_lshlrev_b64 v[0:1], 11, v[0:1]
	v_lshl_add_u64 v[98:99], v[78:79], 0, v[0:1]
	v_add_u32_e32 v0, s15, v126
	v_ashrrev_i32_e32 v1, 31, v0
	v_lshlrev_b64 v[0:1], 11, v[0:1]
	v_lshl_add_u64 v[100:101], v[80:81], 0, v[0:1]
	v_subrev_u32_e32 v0, s10, v64
	v_ashrrev_i32_e32 v1, 31, v0
	v_lshlrev_b64 v[0:1], 11, v[0:1]
	v_subrev_u32_e32 v2, s10, v122
	v_lshl_add_u64 v[102:103], v[86:87], 0, v[0:1]
	v_add_u32_e32 v0, s15, v127
	v_ashrrev_i32_e32 v3, 31, v2
	v_ashrrev_i32_e32 v1, 31, v0
	v_lshlrev_b64 v[2:3], 11, v[2:3]
	v_lshlrev_b64 v[0:1], 11, v[0:1]
	v_lshl_add_u64 v[90:91], v[78:79], 0, v[2:3]
	v_lshl_add_u64 v[104:105], v[88:89], 0, v[0:1]
	s_mov_b64 s[10:11], 0
	s_mov_b32 s17, 0
	v_mov_b32_e32 v0, 0
	v_mov_b32_e32 v1, v65
	v_mov_b32_e32 v2, v65
	v_mov_b32_e32 v3, v65
	v_mov_b32_e32 v4, 0
	v_mov_b32_e32 v5, v65
	v_mov_b32_e32 v6, v65
	v_mov_b32_e32 v7, v65
	v_mov_b32_e32 v8, 0
	v_mov_b32_e32 v9, v65
	v_mov_b32_e32 v10, v65
	v_mov_b32_e32 v11, v65
	v_mov_b32_e32 v12, 0
	v_mov_b32_e32 v13, v65
	v_mov_b32_e32 v14, v65
	v_mov_b32_e32 v15, v65
	v_mov_b32_e32 v16, 0
	v_mov_b32_e32 v17, v65
	v_mov_b32_e32 v18, v65
	v_mov_b32_e32 v19, v65
	v_mov_b32_e32 v20, 0
	v_mov_b32_e32 v21, v65
	v_mov_b32_e32 v22, v65
	v_mov_b32_e32 v23, v65
	v_mov_b32_e32 v24, 0
	v_mov_b32_e32 v25, v65
	v_mov_b32_e32 v26, v65
	v_mov_b32_e32 v27, v65
	v_mov_b32_e32 v28, 0
	v_mov_b32_e32 v29, v65
	v_mov_b32_e32 v30, v65
	v_mov_b32_e32 v31, v65
	v_mov_b32_e32 v32, 0
	v_mov_b32_e32 v33, v65
	v_mov_b32_e32 v34, v65
	v_mov_b32_e32 v35, v65
	v_mov_b32_e32 v36, 0
	v_mov_b32_e32 v37, v65
	v_mov_b32_e32 v38, v65
	v_mov_b32_e32 v39, v65
	v_mov_b32_e32 v40, 0
	v_mov_b32_e32 v41, v65
	v_mov_b32_e32 v42, v65
	v_mov_b32_e32 v43, v65
	v_mov_b32_e32 v44, 0
	v_mov_b32_e32 v45, v65
	v_mov_b32_e32 v46, v65
	v_mov_b32_e32 v47, v65
	v_mov_b32_e32 v48, 0
	v_mov_b32_e32 v49, v65
	v_mov_b32_e32 v50, v65
	v_mov_b32_e32 v51, v65
	v_mov_b32_e32 v52, 0
	v_mov_b32_e32 v53, v65
	v_mov_b32_e32 v54, v65
	v_mov_b32_e32 v55, v65
	v_mov_b32_e32 v56, 0
	v_mov_b32_e32 v57, v65
	v_mov_b32_e32 v58, v65
	v_mov_b32_e32 v59, v65
	v_mov_b32_e32 v60, 0
	v_mov_b32_e32 v61, v65
	v_mov_b32_e32 v62, v65
	v_mov_b32_e32 v63, v65
	s_waitcnt vmcnt(0) lgkmcnt(0)
	s_barrier
	v_add3_u32 v182, 0, v133, v134
	v_add_u32_e32 v183, 0x4000, v182
	s_nop 0
	v_readfirstlane_b32 s82, v183
	v_lshl_add_u32 v183, v109, 1, 0
	s_nop 0
	v_readfirstlane_b32 s83, v182
	v_add3_u32 v183, v183, v134, s13
	s_nop 0
	v_readfirstlane_b32 s84, v183
	v_add_u32_e32 v183, 0x400, v182
	s_nop 0
	v_readfirstlane_b32 s85, v183
	v_lshl_add_u32 v183, v111, 1, 0
	v_add3_u32 v183, v183, v134, s13
	s_nop 0
	v_readfirstlane_b32 s86, v183
	v_add_u32_e32 v183, 0x800, v182
	s_nop 0
	v_readfirstlane_b32 s87, v183
	v_lshl_add_u32 v183, v113, 1, 0
	v_add3_u32 v183, v183, v134, s13
	s_nop 0
	v_readfirstlane_b32 s88, v183
	v_add_u32_e32 v182, 0xc00, v182
	s_nop 0
	v_readfirstlane_b32 s89, v182
	v_subrev_u32_e32 v184, s52, v90
	v_subrev_u32_e32 v185, s52, v92
	v_subrev_u32_e32 v186, s52, v94
	v_subrev_u32_e32 v187, s52, v96
	v_subrev_u32_e32 v188, s52, v98
	v_subrev_u32_e32 v189, s52, v100
	v_subrev_u32_e32 v190, s52, v102
	v_subrev_u32_e32 v191, s52, v104
	s_bitcmp1_b32 s32, 0
	s_cbranch_scc1 .Lxk_605
.LBB0_605:
	s_and_b32 s18, s17, 0x4000
	s_xor_b32 s19, s18, 0x4000
	s_lshl_b32 s19, s19, 1
	s_add_i32 s19, s19, 32
	s_add_u32 s90, s52, s10
	s_addc_u32 s91, s53, s11
	s_add_i32 m0, s19, s82
	s_lshl_b32 s18, s18, 1
	global_load_lds_dwordx4 v184, s[90:91]
	s_add_i32 m0, s19, s83
	s_add_i32 s18, s18, 32
	global_load_lds_dwordx4 v185, s[90:91]
	s_add_i32 m0, s19, s84
	v_lshl_add_u32 v137, v114, 1, s18
	global_load_lds_dwordx4 v186, s[90:91]
	s_add_i32 m0, s19, s85
	v_lshl_add_u32 v170, v115, 1, s18
	global_load_lds_dwordx4 v187, s[90:91]
	s_add_i32 m0, s19, s86
	v_add_u32_e32 v158, v137, v135
	global_load_lds_dwordx4 v188, s[90:91]
	s_add_i32 m0, s19, s87
	v_add_u32_e32 v166, v170, v135
	global_load_lds_dwordx4 v189, s[90:91]
	s_add_i32 m0, s19, s88
	s_addk_i32 s17, 0x4000
	global_load_lds_dwordx4 v190, s[90:91]
	s_add_i32 m0, s19, s89
	s_add_u32 s10, s10, 0x80
	s_addc_u32 s11, s11, 0
	global_load_lds_dwordx4 v191, s[90:91]
	ds_read_b128 v[138:141], v158
	ds_read_b128 v[146:149], v166 offset:16384
	ds_read_b128 v[150:153], v166 offset:18432
	ds_read_b128 v[162:165], v166 offset:20480
	ds_read_b128 v[166:169], v166 offset:22528
	ds_read_b128 v[142:145], v158 offset:2048
	ds_read_b128 v[154:157], v158 offset:4096
	ds_read_b128 v[158:161], v158 offset:6144
	v_add_u32_e32 v137, v137, v136
	v_add_u32_e32 v236, v170, v136
	ds_read_b128 v[204:207], v137
	ds_read_b128 v[208:211], v236 offset:16384
	ds_read_b128 v[212:215], v236 offset:18432
	ds_read_b128 v[216:219], v236 offset:20480
	ds_read_b128 v[220:223], v236 offset:22528
	ds_read_b128 v[224:227], v137 offset:2048
	ds_read_b128 v[228:231], v137 offset:4096
	ds_read_b128 v[232:235], v137 offset:6144
	s_setprio 1
	s_waitcnt lgkmcnt(11)
	v_mfma_f32_16x16x32_bf16 v[60:63], v[138:141], v[146:149], v[60:63]
	v_mfma_f32_16x16x32_bf16 v[56:59], v[138:141], v[150:153], v[56:59]
	v_mfma_f32_16x16x32_bf16 v[52:55], v[138:141], v[162:165], v[52:55]
	v_mfma_f32_16x16x32_bf16 v[48:51], v[138:141], v[166:169], v[48:51]
	s_waitcnt lgkmcnt(10)
	v_mfma_f32_16x16x32_bf16 v[44:47], v[142:145], v[146:149], v[44:47]
	v_mfma_f32_16x16x32_bf16 v[40:43], v[142:145], v[150:153], v[40:43]
	v_mfma_f32_16x16x32_bf16 v[36:39], v[142:145], v[162:165], v[36:39]
	v_mfma_f32_16x16x32_bf16 v[32:35], v[142:145], v[166:169], v[32:35]
	s_waitcnt lgkmcnt(9)
	v_mfma_f32_16x16x32_bf16 v[28:31], v[154:157], v[146:149], v[28:31]
	v_mfma_f32_16x16x32_bf16 v[24:27], v[154:157], v[150:153], v[24:27]
	v_mfma_f32_16x16x32_bf16 v[20:23], v[154:157], v[162:165], v[20:23]
	v_mfma_f32_16x16x32_bf16 v[16:19], v[154:157], v[166:169], v[16:19]
	s_waitcnt lgkmcnt(8)
	v_mfma_f32_16x16x32_bf16 v[12:15], v[158:161], v[146:149], v[12:15]
	v_mfma_f32_16x16x32_bf16 v[8:11], v[158:161], v[150:153], v[8:11]
	v_mfma_f32_16x16x32_bf16 v[4:7], v[158:161], v[162:165], v[4:7]
	v_mfma_f32_16x16x32_bf16 v[0:3], v[158:161], v[166:169], v[0:3]
	s_waitcnt lgkmcnt(3)
	v_mfma_f32_16x16x32_bf16 v[60:63], v[204:207], v[208:211], v[60:63]
	v_mfma_f32_16x16x32_bf16 v[56:59], v[204:207], v[212:215], v[56:59]
	v_mfma_f32_16x16x32_bf16 v[52:55], v[204:207], v[216:219], v[52:55]
	v_mfma_f32_16x16x32_bf16 v[48:51], v[204:207], v[220:223], v[48:51]
	s_waitcnt lgkmcnt(2)
	v_mfma_f32_16x16x32_bf16 v[44:47], v[224:227], v[208:211], v[44:47]
	v_mfma_f32_16x16x32_bf16 v[40:43], v[224:227], v[212:215], v[40:43]
	v_mfma_f32_16x16x32_bf16 v[36:39], v[224:227], v[216:219], v[36:39]
	v_mfma_f32_16x16x32_bf16 v[32:35], v[224:227], v[220:223], v[32:35]
	s_waitcnt lgkmcnt(1)
	v_mfma_f32_16x16x32_bf16 v[28:31], v[228:231], v[208:211], v[28:31]
	v_mfma_f32_16x16x32_bf16 v[24:27], v[228:231], v[212:215], v[24:27]
	v_mfma_f32_16x16x32_bf16 v[20:23], v[228:231], v[216:219], v[20:23]
	v_mfma_f32_16x16x32_bf16 v[16:19], v[228:231], v[220:223], v[16:19]
	s_waitcnt lgkmcnt(0)
	v_mfma_f32_16x16x32_bf16 v[12:15], v[232:235], v[208:211], v[12:15]
	v_mfma_f32_16x16x32_bf16 v[8:11], v[232:235], v[212:215], v[8:11]
	v_mfma_f32_16x16x32_bf16 v[4:7], v[232:235], v[216:219], v[4:7]
	v_mfma_f32_16x16x32_bf16 v[0:3], v[232:235], v[220:223], v[0:3]
	s_setprio 0
	s_cmpk_eq_i32 s10, 0x780
	s_waitcnt vmcnt(0)
	s_barrier
	s_cbranch_scc0 .LBB0_605
	s_branch .Lxk_exit_605
.Lxk_605:
	s_and_b32 s18, s17, 0x4000
	s_xor_b32 s19, s18, 0x4000
	s_lshl_b32 s19, s19, 1
	s_add_i32 s19, s19, 32
	s_add_u32 s90, s52, s10
	s_addc_u32 s91, s53, s11
	s_add_i32 m0, s19, s82
	s_lshl_b32 s18, s18, 1
	global_load_lds_dwordx4 v184, s[90:91]
	s_add_i32 m0, s19, s83
	s_add_i32 s18, s18, 32
	global_load_lds_dwordx4 v185, s[90:91]
	s_add_i32 m0, s19, s84
	v_lshl_add_u32 v137, v114, 1, s18
	global_load_lds_dwordx4 v186, s[90:91]
	s_add_i32 m0, s19, s85
	v_lshl_add_u32 v170, v115, 1, s18
	global_load_lds_dwordx4 v187, s[90:91]
	s_add_i32 m0, s19, s86
	v_add_u32_e32 v158, v137, v135
	global_load_lds_dwordx4 v188, s[90:91]
	s_add_i32 m0, s19, s87
	v_add_u32_e32 v166, v170, v135
	global_load_lds_dwordx4 v189, s[90:91]
	s_add_i32 m0, s19, s88
	s_addk_i32 s17, 0x4000
	global_load_lds_dwordx4 v190, s[90:91]
	s_add_i32 m0, s19, s89
	s_add_u32 s10, s10, 0x80
	s_addc_u32 s11, s11, 0
	global_load_lds_dwordx4 v191, s[90:91]
	ds_read_b128 v[138:141], v158
	ds_read_b128 v[146:149], v166 offset:16384
	ds_read_b128 v[150:153], v166 offset:18432
	ds_read_b128 v[162:165], v166 offset:20480
	ds_read_b128 v[166:169], v166 offset:22528
	ds_read_b128 v[142:145], v158 offset:2048
	ds_read_b128 v[154:157], v158 offset:4096
	ds_read_b128 v[158:161], v158 offset:6144
	v_add_u32_e32 v137, v137, v136
	v_add_u32_e32 v236, v170, v136
	ds_read_b128 v[204:207], v137
	ds_read_b128 v[208:211], v236 offset:16384
	ds_read_b128 v[212:215], v236 offset:18432
	ds_read_b128 v[216:219], v236 offset:20480
	ds_read_b128 v[220:223], v236 offset:22528
	ds_read_b128 v[224:227], v137 offset:2048
	ds_read_b128 v[228:231], v137 offset:4096
	ds_read_b128 v[232:235], v137 offset:6144
	s_setprio 3
	s_waitcnt lgkmcnt(11)
	v_mfma_f32_16x16x32_bf16 v[60:63], v[138:141], v[146:149], v[60:63]
	v_mfma_f32_16x16x32_bf16 v[56:59], v[138:141], v[150:153], v[56:59]
	v_mfma_f32_16x16x32_bf16 v[52:55], v[138:141], v[162:165], v[52:55]
	v_mfma_f32_16x16x32_bf16 v[48:51], v[138:141], v[166:169], v[48:51]
	s_waitcnt lgkmcnt(10)
	v_mfma_f32_16x16x32_bf16 v[44:47], v[142:145], v[146:149], v[44:47]
	v_mfma_f32_16x16x32_bf16 v[40:43], v[142:145], v[150:153], v[40:43]
	v_mfma_f32_16x16x32_bf16 v[36:39], v[142:145], v[162:165], v[36:39]
	v_mfma_f32_16x16x32_bf16 v[32:35], v[142:145], v[166:169], v[32:35]
	s_waitcnt lgkmcnt(9)
	v_mfma_f32_16x16x32_bf16 v[28:31], v[154:157], v[146:149], v[28:31]
	v_mfma_f32_16x16x32_bf16 v[24:27], v[154:157], v[150:153], v[24:27]
	v_mfma_f32_16x16x32_bf16 v[20:23], v[154:157], v[162:165], v[20:23]
	v_mfma_f32_16x16x32_bf16 v[16:19], v[154:157], v[166:169], v[16:19]
	s_waitcnt lgkmcnt(8)
	v_mfma_f32_16x16x32_bf16 v[12:15], v[158:161], v[146:149], v[12:15]
	v_mfma_f32_16x16x32_bf16 v[8:11], v[158:161], v[150:153], v[8:11]
	v_mfma_f32_16x16x32_bf16 v[4:7], v[158:161], v[162:165], v[4:7]
	v_mfma_f32_16x16x32_bf16 v[0:3], v[158:161], v[166:169], v[0:3]
	s_waitcnt lgkmcnt(3)
	v_mfma_f32_16x16x32_bf16 v[60:63], v[204:207], v[208:211], v[60:63]
	v_mfma_f32_16x16x32_bf16 v[56:59], v[204:207], v[212:215], v[56:59]
	v_mfma_f32_16x16x32_bf16 v[52:55], v[204:207], v[216:219], v[52:55]
	v_mfma_f32_16x16x32_bf16 v[48:51], v[204:207], v[220:223], v[48:51]
	s_waitcnt lgkmcnt(2)
	v_mfma_f32_16x16x32_bf16 v[44:47], v[224:227], v[208:211], v[44:47]
	v_mfma_f32_16x16x32_bf16 v[40:43], v[224:227], v[212:215], v[40:43]
	v_mfma_f32_16x16x32_bf16 v[36:39], v[224:227], v[216:219], v[36:39]
	v_mfma_f32_16x16x32_bf16 v[32:35], v[224:227], v[220:223], v[32:35]
	s_waitcnt lgkmcnt(1)
	v_mfma_f32_16x16x32_bf16 v[28:31], v[228:231], v[208:211], v[28:31]
	v_mfma_f32_16x16x32_bf16 v[24:27], v[228:231], v[212:215], v[24:27]
	v_mfma_f32_16x16x32_bf16 v[20:23], v[228:231], v[216:219], v[20:23]
	v_mfma_f32_16x16x32_bf16 v[16:19], v[228:231], v[220:223], v[16:19]
	s_waitcnt lgkmcnt(0)
	v_mfma_f32_16x16x32_bf16 v[12:15], v[232:235], v[208:211], v[12:15]
	v_mfma_f32_16x16x32_bf16 v[8:11], v[232:235], v[212:215], v[8:11]
	v_mfma_f32_16x16x32_bf16 v[4:7], v[232:235], v[216:219], v[4:7]
	v_mfma_f32_16x16x32_bf16 v[0:3], v[232:235], v[220:223], v[0:3]
	s_setprio 2
	s_cmpk_eq_i32 s10, 0x780
	s_waitcnt vmcnt(0)
	s_barrier
	s_cbranch_scc0 .Lxk_605
.Lxk_exit_605:
	ds_read_b128 v[90:93], v116 offset:55296
	ds_read_b128 v[94:97], v116 offset:53248
	ds_read_b128 v[98:101], v117 offset:38912
	ds_read_b128 v[102:105], v117 offset:36864
	ds_read_b128 v[138:141], v116 offset:51200
	ds_read_b128 v[142:145], v116 offset:49152
	ds_read_b128 v[146:149], v117 offset:34816
	ds_read_b128 v[150:153], v117 offset:32768
	s_setprio 1
	s_waitcnt lgkmcnt(5)
	v_mfma_f32_16x16x32_bf16 v[0:3], v[98:101], v[90:93], v[0:3]
	s_waitcnt lgkmcnt(0)
	v_mfma_f32_16x16x32_bf16 v[60:63], v[150:153], v[142:145], v[60:63]
	v_mfma_f32_16x16x32_bf16 v[56:59], v[150:153], v[138:141], v[56:59]
	v_mfma_f32_16x16x32_bf16 v[52:55], v[150:153], v[94:97], v[52:55]
	v_mfma_f32_16x16x32_bf16 v[48:51], v[150:153], v[90:93], v[48:51]
	v_mfma_f32_16x16x32_bf16 v[44:47], v[146:149], v[142:145], v[44:47]
	v_mfma_f32_16x16x32_bf16 v[40:43], v[146:149], v[138:141], v[40:43]
	v_mfma_f32_16x16x32_bf16 v[36:39], v[146:149], v[94:97], v[36:39]
	v_mfma_f32_16x16x32_bf16 v[32:35], v[146:149], v[90:93], v[32:35]
	v_mfma_f32_16x16x32_bf16 v[28:31], v[102:105], v[142:145], v[28:31]
	v_mfma_f32_16x16x32_bf16 v[24:27], v[102:105], v[138:141], v[24:27]
	v_mfma_f32_16x16x32_bf16 v[20:23], v[102:105], v[94:97], v[20:23]
	v_mfma_f32_16x16x32_bf16 v[16:19], v[102:105], v[90:93], v[16:19]
	v_mfma_f32_16x16x32_bf16 v[12:15], v[98:101], v[142:145], v[12:15]
	v_mfma_f32_16x16x32_bf16 v[8:11], v[98:101], v[138:141], v[8:11]
	v_mfma_f32_16x16x32_bf16 v[4:7], v[98:101], v[94:97], v[4:7]
	s_setprio 0
	ds_read_b128 v[90:93], v118 offset:32768
	ds_read_b128 v[94:97], v118 offset:34816
	ds_read_b128 v[98:101], v119 offset:49152
	ds_read_b128 v[102:105], v119 offset:51200
	ds_read_b128 v[138:141], v118 offset:36864
	ds_read_b128 v[142:145], v118 offset:38912
	ds_read_b128 v[146:149], v119 offset:53248
	ds_read_b128 v[150:153], v119 offset:55296
	s_setprio 1
	s_waitcnt lgkmcnt(0)
	v_mfma_f32_16x16x32_bf16 v[0:3], v[142:145], v[150:153], v[0:3]
	v_mfma_f32_16x16x32_bf16 v[60:63], v[90:93], v[98:101], v[60:63]
	v_mfma_f32_16x16x32_bf16 v[56:59], v[90:93], v[102:105], v[56:59]
	v_mfma_f32_16x16x32_bf16 v[52:55], v[90:93], v[146:149], v[52:55]
	v_mfma_f32_16x16x32_bf16 v[48:51], v[90:93], v[150:153], v[48:51]
	v_mfma_f32_16x16x32_bf16 v[44:47], v[94:97], v[98:101], v[44:47]
	v_mfma_f32_16x16x32_bf16 v[40:43], v[94:97], v[102:105], v[40:43]
	v_mfma_f32_16x16x32_bf16 v[36:39], v[94:97], v[146:149], v[36:39]
	v_mfma_f32_16x16x32_bf16 v[32:35], v[94:97], v[150:153], v[32:35]
	v_mfma_f32_16x16x32_bf16 v[28:31], v[138:141], v[98:101], v[28:31]
	v_mfma_f32_16x16x32_bf16 v[24:27], v[138:141], v[102:105], v[24:27]
	v_mfma_f32_16x16x32_bf16 v[20:23], v[138:141], v[146:149], v[20:23]
	v_mfma_f32_16x16x32_bf16 v[16:19], v[138:141], v[150:153], v[16:19]
	v_mfma_f32_16x16x32_bf16 v[12:15], v[142:145], v[98:101], v[12:15]
	v_mfma_f32_16x16x32_bf16 v[8:11], v[142:145], v[102:105], v[8:11]
	v_mfma_f32_16x16x32_bf16 v[4:7], v[142:145], v[146:149], v[4:7]
	s_setprio 0
	s_barrier
	ds_write2_b32 v120, v60, v56 offset1:16
	ds_write2_b32 v120, v61, v57 offset0:132 offset1:148
	v_add_u32_e32 v56, 0x400, v120
	ds_write2_b32 v56, v62, v58 offset0:8 offset1:24
	ds_write2_b32 v56, v63, v59 offset0:140 offset1:156
	ds_write2_b32 v120, v52, v48 offset0:32 offset1:48
	ds_write2_b32 v120, v53, v49 offset0:164 offset1:180
	ds_write2_b32 v56, v54, v50 offset0:40 offset1:56
	ds_write2_b32 v56, v55, v51 offset0:172 offset1:188
	v_add_u32_e32 v48, 0x2000, v120
	ds_write2_b32 v48, v44, v40 offset0:64 offset1:80
	ds_write2_b32 v48, v45, v41 offset0:196 offset1:212
	v_add_u32_e32 v40, 0x2400, v120
	ds_write2_b32 v40, v46, v42 offset0:72 offset1:88
	ds_write2_b32 v40, v47, v43 offset0:204 offset1:220
	ds_write2_b32 v48, v36, v32 offset0:96 offset1:112
	ds_write2_b32 v48, v37, v33 offset0:228 offset1:244
	ds_write2_b32 v40, v38, v34 offset0:104 offset1:120
	ds_write2_b32 v40, v39, v35 offset0:236 offset1:252
	v_add_u32_e32 v32, 0x4000, v120
	ds_write2_b32 v32, v28, v24 offset0:128 offset1:144
	v_add_u32_e32 v24, 0x4400, v120
	ds_write2_b32 v24, v29, v25 offset0:4 offset1:20
	ds_write2_b32 v24, v30, v26 offset0:136 offset1:152
	v_add_u32_e32 v25, 0x4800, v120
	ds_write2_b32 v25, v31, v27 offset0:12 offset1:28
	ds_write2_b32 v32, v20, v16 offset0:160 offset1:176
	ds_write2_b32 v24, v21, v17 offset0:36 offset1:52
	ds_write2_b32 v24, v22, v18 offset0:168 offset1:184
	ds_write2_b32 v25, v23, v19 offset0:44 offset1:60
	v_add_u32_e32 v16, 0x6000, v120
	ds_write2_b32 v16, v12, v8 offset0:192 offset1:208
	v_add_u32_e32 v8, 0x6400, v120
	ds_write2_b32 v8, v13, v9 offset0:68 offset1:84
	ds_write2_b32 v8, v14, v10 offset0:200 offset1:216
	v_add_u32_e32 v9, 0x6800, v120
	ds_write2_b32 v9, v15, v11 offset0:76 offset1:92
	ds_write2_b32 v16, v4, v0 offset0:224 offset1:240
	ds_write2_b32 v8, v5, v1 offset0:100 offset1:116
	ds_write2_b32 v8, v6, v2 offset0:232 offset1:248
	ds_write2_b32 v9, v7, v3 offset0:108 offset1:124
	v_or_b32_e32 v0, s16, v121
	v_ashrrev_i32_e32 v1, 31, v0
	v_lshl_add_u64 v[0:1], v[0:1], 1, s[4:5]
	v_add_u32_e32 v2, s15, v128
	s_mov_b32 s10, 0
	s_waitcnt lgkmcnt(0)
	s_barrier

.LBB0_615:
	s_ashr_i32 s12, s7, 31
	s_lshr_b32 s12, s12, 29
	s_add_i32 s12, s7, s12
	s_ashr_i32 s13, s12, 3
	s_lshl_b32 s14, s13, 10
	s_lshl_b32 s7, s7, 7
	s_sub_i32 s12, s7, s14
	v_add_u32_e32 v0, s13, v104
	s_add_i32 s12, s12, s6
	v_lshlrev_b32_e32 v2, 7, v0
	v_add_u32_e32 v0, s12, v105
	v_ashrrev_i32_e32 v1, 31, v0
	v_add_u32_e32 v3, 0x4000, v106
	v_lshlrev_b64 v[0:1], 11, v[0:1]
	v_readfirstlane_b32 s15, v3
	v_lshl_add_u64 v[0:1], v[64:65], 0, v[0:1]
	s_mov_b32 m0, s15
	v_readfirstlane_b32 s15, v106
	global_load_lds_dwordx4 v[0:1], off
	v_add_u32_e32 v0, v2, v105
	v_ashrrev_i32_e32 v1, 31, v0
	v_lshlrev_b64 v[0:1], 11, v[0:1]
	v_lshl_add_u64 v[0:1], v[70:71], 0, v[0:1]
	s_mov_b32 m0, s15
	v_readfirstlane_b32 s15, v130
	global_load_lds_dwordx4 v[0:1], off
	v_add_u32_e32 v0, s12, v107
	v_ashrrev_i32_e32 v1, 31, v0
	v_lshlrev_b64 v[0:1], 11, v[0:1]
	v_lshl_add_u64 v[0:1], v[66:67], 0, v[0:1]
	s_mov_b32 m0, s15
	v_add_u32_e32 v3, 0x400, v106
	global_load_lds_dwordx4 v[0:1], off
	v_add_u32_e32 v0, v2, v107
	v_ashrrev_i32_e32 v1, 31, v0
	v_lshlrev_b64 v[0:1], 11, v[0:1]
	v_readfirstlane_b32 s15, v3
	v_lshl_add_u64 v[0:1], v[72:73], 0, v[0:1]
	s_mov_b32 m0, s15
	v_readfirstlane_b32 s15, v131
	global_load_lds_dwordx4 v[0:1], off
	v_add_u32_e32 v0, s12, v109
	v_ashrrev_i32_e32 v1, 31, v0
	v_lshlrev_b64 v[0:1], 11, v[0:1]
	v_lshl_add_u64 v[0:1], v[64:65], 0, v[0:1]
	s_mov_b32 m0, s15
	v_add_u32_e32 v3, 0x800, v106
	global_load_lds_dwordx4 v[0:1], off
	v_add_u32_e32 v0, v2, v109
	v_ashrrev_i32_e32 v1, 31, v0
	v_lshlrev_b64 v[0:1], 11, v[0:1]
	v_readfirstlane_b32 s15, v3
	v_lshl_add_u64 v[0:1], v[70:71], 0, v[0:1]
	s_mov_b32 m0, s15
	v_readfirstlane_b32 s15, v132
	global_load_lds_dwordx4 v[0:1], off
	v_add_u32_e32 v0, s12, v111
	v_ashrrev_i32_e32 v1, 31, v0
	v_lshlrev_b64 v[0:1], 11, v[0:1]
	v_lshl_add_u64 v[0:1], v[68:69], 0, v[0:1]
	s_mov_b32 m0, s15
	s_add_i32 s7, s7, s6
	global_load_lds_dwordx4 v[0:1], off
	v_add_u32_e32 v0, v2, v111
	v_ashrrev_i32_e32 v1, 31, v0
	v_add_u32_e32 v2, 0xc00, v106
	v_lshlrev_b64 v[0:1], 11, v[0:1]
	v_readfirstlane_b32 s15, v2
	v_lshl_add_u64 v[0:1], v[74:75], 0, v[0:1]
	s_mov_b32 m0, s15
	s_lshl_b32 s13, s13, 7
	global_load_lds_dwordx4 v[0:1], off
	v_add_u32_e32 v0, s7, v105
	v_subrev_u32_e32 v0, s14, v0
	v_ashrrev_i32_e32 v1, 31, v0
	v_lshlrev_b64 v[0:1], 11, v[0:1]
	v_lshl_add_u64 v[88:89], v[76:77], 0, v[0:1]
	v_add_u32_e32 v0, s13, v121
	v_ashrrev_i32_e32 v1, 31, v0
	v_lshlrev_b64 v[0:1], 11, v[0:1]
	v_lshl_add_u64 v[90:91], v[78:79], 0, v[0:1]
	v_add_u32_e32 v0, s7, v122
	v_subrev_u32_e32 v0, s14, v0
	v_ashrrev_i32_e32 v1, 31, v0
	v_lshlrev_b64 v[0:1], 11, v[0:1]
	v_lshl_add_u64 v[92:93], v[80:81], 0, v[0:1]
	v_add_u32_e32 v0, s13, v123
	v_ashrrev_i32_e32 v1, 31, v0
	v_lshlrev_b64 v[0:1], 11, v[0:1]
	v_lshl_add_u64 v[94:95], v[82:83], 0, v[0:1]
	v_add_u32_e32 v0, s7, v124
	v_subrev_u32_e32 v0, s14, v0
	v_ashrrev_i32_e32 v1, 31, v0
	v_lshlrev_b64 v[0:1], 11, v[0:1]
	v_lshl_add_u64 v[96:97], v[76:77], 0, v[0:1]
	v_add_u32_e32 v0, s13, v125
	v_ashrrev_i32_e32 v1, 31, v0
	v_lshlrev_b64 v[0:1], 11, v[0:1]
	v_lshl_add_u64 v[98:99], v[78:79], 0, v[0:1]
	v_add_u32_e32 v0, s7, v126
	v_subrev_u32_e32 v0, s14, v0
	v_ashrrev_i32_e32 v1, 31, v0
	v_lshlrev_b64 v[0:1], 11, v[0:1]
	v_lshl_add_u64 v[100:101], v[84:85], 0, v[0:1]
	v_add_u32_e32 v0, s13, v127
	v_ashrrev_i32_e32 v1, 31, v0
	v_lshlrev_b64 v[0:1], 11, v[0:1]
	v_lshl_add_u64 v[102:103], v[86:87], 0, v[0:1]
	v_mov_b32_e32 v0, 0
	s_mov_b32 s14, 0
	s_mov_b64 s[6:7], 0
	v_mov_b32_e32 v1, v0
	v_mov_b32_e32 v2, v0
	v_mov_b32_e32 v3, v0
	v_mov_b32_e32 v4, v0
	v_mov_b32_e32 v5, v0
	v_mov_b32_e32 v6, v0
	v_mov_b32_e32 v7, v0
	v_mov_b32_e32 v8, v0
	v_mov_b32_e32 v9, v0
	v_mov_b32_e32 v10, v0
	v_mov_b32_e32 v11, v0
	v_mov_b32_e32 v12, v0
	v_mov_b32_e32 v13, v0
	v_mov_b32_e32 v14, v0
	v_mov_b32_e32 v15, v0
	v_mov_b32_e32 v16, v0
	v_mov_b32_e32 v17, v0
	v_mov_b32_e32 v18, v0
	v_mov_b32_e32 v19, v0
	v_mov_b32_e32 v20, v0
	v_mov_b32_e32 v21, v0
	v_mov_b32_e32 v22, v0
	v_mov_b32_e32 v23, v0
	v_mov_b32_e32 v24, v0
	v_mov_b32_e32 v25, v0
	v_mov_b32_e32 v26, v0
	v_mov_b32_e32 v27, v0
	v_mov_b32_e32 v28, v0
	v_mov_b32_e32 v29, v0
	v_mov_b32_e32 v30, v0
	v_mov_b32_e32 v31, v0
	v_mov_b32_e32 v32, v0
	v_mov_b32_e32 v33, v0
	v_mov_b32_e32 v34, v0
	v_mov_b32_e32 v35, v0
	v_mov_b32_e32 v36, v0
	v_mov_b32_e32 v37, v0
	v_mov_b32_e32 v38, v0
	v_mov_b32_e32 v39, v0
	v_mov_b32_e32 v40, v0
	v_mov_b32_e32 v41, v0
	v_mov_b32_e32 v42, v0
	v_mov_b32_e32 v43, v0
	v_mov_b32_e32 v44, v0
	v_mov_b32_e32 v45, v0
	v_mov_b32_e32 v46, v0
	v_mov_b32_e32 v47, v0
	v_mov_b32_e32 v48, v0
	v_mov_b32_e32 v49, v0
	v_mov_b32_e32 v50, v0
	v_mov_b32_e32 v51, v0
	v_mov_b32_e32 v52, v0
	v_mov_b32_e32 v53, v0
	v_mov_b32_e32 v54, v0
	v_mov_b32_e32 v55, v0
	v_mov_b32_e32 v56, v0
	v_mov_b32_e32 v57, v0
	v_mov_b32_e32 v58, v0
	v_mov_b32_e32 v59, v0
	v_mov_b32_e32 v60, v0
	v_mov_b32_e32 v61, v0
	v_mov_b32_e32 v62, v0
	v_mov_b32_e32 v63, v0
	s_waitcnt vmcnt(0) lgkmcnt(0)
	s_barrier
	v_add3_u32 v182, 0, v133, v134
	v_add_u32_e32 v183, 0x4000, v182
	s_nop 0
	v_readfirstlane_b32 s82, v183
	v_lshl_add_u32 v183, v108, 1, 0
	s_nop 0
	v_readfirstlane_b32 s83, v182
	v_add3_u32 v183, v183, v134, s9
	s_nop 0
	v_readfirstlane_b32 s84, v183
	v_add_u32_e32 v183, 0x400, v182
	s_nop 0
	v_readfirstlane_b32 s85, v183
	v_lshl_add_u32 v183, v110, 1, 0
	v_add3_u32 v183, v183, v134, s9
	s_nop 0
	v_readfirstlane_b32 s86, v183
	v_add_u32_e32 v183, 0x800, v182
	s_nop 0
	v_readfirstlane_b32 s87, v183
	v_lshl_add_u32 v183, v112, 1, 0
	v_add3_u32 v183, v183, v134, s9
	s_nop 0
	v_readfirstlane_b32 s88, v183
	v_add_u32_e32 v182, 0xc00, v182
	s_nop 0
	v_readfirstlane_b32 s89, v182
	v_subrev_u32_e32 v184, s52, v88
	v_subrev_u32_e32 v185, s52, v90
	v_subrev_u32_e32 v186, s52, v92
	v_subrev_u32_e32 v187, s52, v94
	v_subrev_u32_e32 v188, s52, v96
	v_subrev_u32_e32 v189, s52, v98
	v_subrev_u32_e32 v190, s52, v100
	v_subrev_u32_e32 v191, s52, v102
	s_bitcmp1_b32 s32, 0
	s_cbranch_scc1 .Lxk_616
.LBB0_616:
	s_and_b32 s15, s14, 0x4000
	s_xor_b32 s16, s15, 0x4000
	s_lshl_b32 s16, s16, 1
	s_add_i32 s16, s16, 32
	s_add_u32 s90, s52, s6
	s_addc_u32 s91, s53, s7
	s_add_i32 m0, s16, s82
	s_lshl_b32 s15, s15, 1
	global_load_lds_dwordx4 v184, s[90:91]
	s_add_i32 m0, s16, s83
	s_add_i32 s15, s15, 32
	global_load_lds_dwordx4 v185, s[90:91]
	s_add_i32 m0, s16, s84
	v_lshl_add_u32 v137, v113, 1, s15
	global_load_lds_dwordx4 v186, s[90:91]
	s_add_i32 m0, s16, s85
	v_lshl_add_u32 v170, v114, 1, s15
	global_load_lds_dwordx4 v187, s[90:91]
	s_add_i32 m0, s16, s86
	v_add_u32_e32 v158, v137, v135
	global_load_lds_dwordx4 v188, s[90:91]
	s_add_i32 m0, s16, s87
	v_add_u32_e32 v166, v170, v135
	global_load_lds_dwordx4 v189, s[90:91]
	s_add_i32 m0, s16, s88
	s_addk_i32 s14, 0x4000
	global_load_lds_dwordx4 v190, s[90:91]
	s_add_i32 m0, s16, s89
	s_add_u32 s6, s6, 0x80
	s_addc_u32 s7, s7, 0
	global_load_lds_dwordx4 v191, s[90:91]
	ds_read_b128 v[138:141], v158
	ds_read_b128 v[146:149], v166 offset:16384
	ds_read_b128 v[150:153], v166 offset:18432
	ds_read_b128 v[162:165], v166 offset:20480
	ds_read_b128 v[166:169], v166 offset:22528
	ds_read_b128 v[142:145], v158 offset:2048
	ds_read_b128 v[154:157], v158 offset:4096
	ds_read_b128 v[158:161], v158 offset:6144
	v_add_u32_e32 v137, v137, v136
	v_add_u32_e32 v236, v170, v136
	ds_read_b128 v[204:207], v137
	ds_read_b128 v[208:211], v236 offset:16384
	ds_read_b128 v[212:215], v236 offset:18432
	ds_read_b128 v[216:219], v236 offset:20480
	ds_read_b128 v[220:223], v236 offset:22528
	ds_read_b128 v[224:227], v137 offset:2048
	ds_read_b128 v[228:231], v137 offset:4096
	ds_read_b128 v[232:235], v137 offset:6144
	s_setprio 1
	s_waitcnt lgkmcnt(11)
	v_mfma_f32_16x16x32_bf16 v[60:63], v[138:141], v[146:149], v[60:63]
	v_mfma_f32_16x16x32_bf16 v[56:59], v[138:141], v[150:153], v[56:59]
	v_mfma_f32_16x16x32_bf16 v[52:55], v[138:141], v[162:165], v[52:55]
	v_mfma_f32_16x16x32_bf16 v[48:51], v[138:141], v[166:169], v[48:51]
	s_waitcnt lgkmcnt(10)
	v_mfma_f32_16x16x32_bf16 v[44:47], v[142:145], v[146:149], v[44:47]
	v_mfma_f32_16x16x32_bf16 v[40:43], v[142:145], v[150:153], v[40:43]
	v_mfma_f32_16x16x32_bf16 v[36:39], v[142:145], v[162:165], v[36:39]
	v_mfma_f32_16x16x32_bf16 v[32:35], v[142:145], v[166:169], v[32:35]
	s_waitcnt lgkmcnt(9)
	v_mfma_f32_16x16x32_bf16 v[28:31], v[154:157], v[146:149], v[28:31]
	v_mfma_f32_16x16x32_bf16 v[24:27], v[154:157], v[150:153], v[24:27]
	v_mfma_f32_16x16x32_bf16 v[20:23], v[154:157], v[162:165], v[20:23]
	v_mfma_f32_16x16x32_bf16 v[16:19], v[154:157], v[166:169], v[16:19]
	s_waitcnt lgkmcnt(8)
	v_mfma_f32_16x16x32_bf16 v[12:15], v[158:161], v[146:149], v[12:15]
	v_mfma_f32_16x16x32_bf16 v[8:11], v[158:161], v[150:153], v[8:11]
	v_mfma_f32_16x16x32_bf16 v[4:7], v[158:161], v[162:165], v[4:7]
	v_mfma_f32_16x16x32_bf16 v[0:3], v[158:161], v[166:169], v[0:3]
	s_waitcnt lgkmcnt(3)
	v_mfma_f32_16x16x32_bf16 v[60:63], v[204:207], v[208:211], v[60:63]
	v_mfma_f32_16x16x32_bf16 v[56:59], v[204:207], v[212:215], v[56:59]
	v_mfma_f32_16x16x32_bf16 v[52:55], v[204:207], v[216:219], v[52:55]
	v_mfma_f32_16x16x32_bf16 v[48:51], v[204:207], v[220:223], v[48:51]
	s_waitcnt lgkmcnt(2)
	v_mfma_f32_16x16x32_bf16 v[44:47], v[224:227], v[208:211], v[44:47]
	v_mfma_f32_16x16x32_bf16 v[40:43], v[224:227], v[212:215], v[40:43]
	v_mfma_f32_16x16x32_bf16 v[36:39], v[224:227], v[216:219], v[36:39]
	v_mfma_f32_16x16x32_bf16 v[32:35], v[224:227], v[220:223], v[32:35]
	s_waitcnt lgkmcnt(1)
	v_mfma_f32_16x16x32_bf16 v[28:31], v[228:231], v[208:211], v[28:31]
	v_mfma_f32_16x16x32_bf16 v[24:27], v[228:231], v[212:215], v[24:27]
	v_mfma_f32_16x16x32_bf16 v[20:23], v[228:231], v[216:219], v[20:23]
	v_mfma_f32_16x16x32_bf16 v[16:19], v[228:231], v[220:223], v[16:19]
	s_waitcnt lgkmcnt(0)
	v_mfma_f32_16x16x32_bf16 v[12:15], v[232:235], v[208:211], v[12:15]
	v_mfma_f32_16x16x32_bf16 v[8:11], v[232:235], v[212:215], v[8:11]
	v_mfma_f32_16x16x32_bf16 v[4:7], v[232:235], v[216:219], v[4:7]
	v_mfma_f32_16x16x32_bf16 v[0:3], v[232:235], v[220:223], v[0:3]
	s_setprio 0
	s_cmpk_eq_i32 s6, 0x780
	s_waitcnt vmcnt(0)
	s_barrier
	s_cbranch_scc0 .LBB0_616
	s_branch .Lxk_exit_616
.Lxk_616:
	s_and_b32 s15, s14, 0x4000
	s_xor_b32 s16, s15, 0x4000
	s_lshl_b32 s16, s16, 1
	s_add_i32 s16, s16, 32
	s_add_u32 s90, s52, s6
	s_addc_u32 s91, s53, s7
	s_add_i32 m0, s16, s82
	s_lshl_b32 s15, s15, 1
	global_load_lds_dwordx4 v184, s[90:91]
	s_add_i32 m0, s16, s83
	s_add_i32 s15, s15, 32
	global_load_lds_dwordx4 v185, s[90:91]
	s_add_i32 m0, s16, s84
	v_lshl_add_u32 v137, v113, 1, s15
	global_load_lds_dwordx4 v186, s[90:91]
	s_add_i32 m0, s16, s85
	v_lshl_add_u32 v170, v114, 1, s15
	global_load_lds_dwordx4 v187, s[90:91]
	s_add_i32 m0, s16, s86
	v_add_u32_e32 v158, v137, v135
	global_load_lds_dwordx4 v188, s[90:91]
	s_add_i32 m0, s16, s87
	v_add_u32_e32 v166, v170, v135
	global_load_lds_dwordx4 v189, s[90:91]
	s_add_i32 m0, s16, s88
	s_addk_i32 s14, 0x4000
	global_load_lds_dwordx4 v190, s[90:91]
	s_add_i32 m0, s16, s89
	s_add_u32 s6, s6, 0x80
	s_addc_u32 s7, s7, 0
	global_load_lds_dwordx4 v191, s[90:91]
	ds_read_b128 v[138:141], v158
	ds_read_b128 v[146:149], v166 offset:16384
	ds_read_b128 v[150:153], v166 offset:18432
	ds_read_b128 v[162:165], v166 offset:20480
	ds_read_b128 v[166:169], v166 offset:22528
	ds_read_b128 v[142:145], v158 offset:2048
	ds_read_b128 v[154:157], v158 offset:4096
	ds_read_b128 v[158:161], v158 offset:6144
	v_add_u32_e32 v137, v137, v136
	v_add_u32_e32 v236, v170, v136
	ds_read_b128 v[204:207], v137
	ds_read_b128 v[208:211], v236 offset:16384
	ds_read_b128 v[212:215], v236 offset:18432
	ds_read_b128 v[216:219], v236 offset:20480
	ds_read_b128 v[220:223], v236 offset:22528
	ds_read_b128 v[224:227], v137 offset:2048
	ds_read_b128 v[228:231], v137 offset:4096
	ds_read_b128 v[232:235], v137 offset:6144
	s_setprio 3
	s_waitcnt lgkmcnt(11)
	v_mfma_f32_16x16x32_bf16 v[60:63], v[138:141], v[146:149], v[60:63]
	v_mfma_f32_16x16x32_bf16 v[56:59], v[138:141], v[150:153], v[56:59]
	v_mfma_f32_16x16x32_bf16 v[52:55], v[138:141], v[162:165], v[52:55]
	v_mfma_f32_16x16x32_bf16 v[48:51], v[138:141], v[166:169], v[48:51]
	s_waitcnt lgkmcnt(10)
	v_mfma_f32_16x16x32_bf16 v[44:47], v[142:145], v[146:149], v[44:47]
	v_mfma_f32_16x16x32_bf16 v[40:43], v[142:145], v[150:153], v[40:43]
	v_mfma_f32_16x16x32_bf16 v[36:39], v[142:145], v[162:165], v[36:39]
	v_mfma_f32_16x16x32_bf16 v[32:35], v[142:145], v[166:169], v[32:35]
	s_waitcnt lgkmcnt(9)
	v_mfma_f32_16x16x32_bf16 v[28:31], v[154:157], v[146:149], v[28:31]
	v_mfma_f32_16x16x32_bf16 v[24:27], v[154:157], v[150:153], v[24:27]
	v_mfma_f32_16x16x32_bf16 v[20:23], v[154:157], v[162:165], v[20:23]
	v_mfma_f32_16x16x32_bf16 v[16:19], v[154:157], v[166:169], v[16:19]
	s_waitcnt lgkmcnt(8)
	v_mfma_f32_16x16x32_bf16 v[12:15], v[158:161], v[146:149], v[12:15]
	v_mfma_f32_16x16x32_bf16 v[8:11], v[158:161], v[150:153], v[8:11]
	v_mfma_f32_16x16x32_bf16 v[4:7], v[158:161], v[162:165], v[4:7]
	v_mfma_f32_16x16x32_bf16 v[0:3], v[158:161], v[166:169], v[0:3]
	s_waitcnt lgkmcnt(3)
	v_mfma_f32_16x16x32_bf16 v[60:63], v[204:207], v[208:211], v[60:63]
	v_mfma_f32_16x16x32_bf16 v[56:59], v[204:207], v[212:215], v[56:59]
	v_mfma_f32_16x16x32_bf16 v[52:55], v[204:207], v[216:219], v[52:55]
	v_mfma_f32_16x16x32_bf16 v[48:51], v[204:207], v[220:223], v[48:51]
	s_waitcnt lgkmcnt(2)
	v_mfma_f32_16x16x32_bf16 v[44:47], v[224:227], v[208:211], v[44:47]
	v_mfma_f32_16x16x32_bf16 v[40:43], v[224:227], v[212:215], v[40:43]
	v_mfma_f32_16x16x32_bf16 v[36:39], v[224:227], v[216:219], v[36:39]
	v_mfma_f32_16x16x32_bf16 v[32:35], v[224:227], v[220:223], v[32:35]
	s_waitcnt lgkmcnt(1)
	v_mfma_f32_16x16x32_bf16 v[28:31], v[228:231], v[208:211], v[28:31]
	v_mfma_f32_16x16x32_bf16 v[24:27], v[228:231], v[212:215], v[24:27]
	v_mfma_f32_16x16x32_bf16 v[20:23], v[228:231], v[216:219], v[20:23]
	v_mfma_f32_16x16x32_bf16 v[16:19], v[228:231], v[220:223], v[16:19]
	s_waitcnt lgkmcnt(0)
	v_mfma_f32_16x16x32_bf16 v[12:15], v[232:235], v[208:211], v[12:15]
	v_mfma_f32_16x16x32_bf16 v[8:11], v[232:235], v[212:215], v[8:11]
	v_mfma_f32_16x16x32_bf16 v[4:7], v[232:235], v[216:219], v[4:7]
	v_mfma_f32_16x16x32_bf16 v[0:3], v[232:235], v[220:223], v[0:3]
	s_setprio 2
	s_cmpk_eq_i32 s6, 0x780
	s_waitcnt vmcnt(0)
	s_barrier
	s_cbranch_scc0 .Lxk_616
.Lxk_exit_616:
	ds_read_b128 v[88:91], v115 offset:55296
	ds_read_b128 v[92:95], v115 offset:53248
	ds_read_b128 v[96:99], v116 offset:38912
	ds_read_b128 v[100:103], v116 offset:36864
	ds_read_b128 v[138:141], v115 offset:51200
	ds_read_b128 v[142:145], v115 offset:49152
	ds_read_b128 v[146:149], v116 offset:34816
	ds_read_b128 v[150:153], v116 offset:32768
	s_setprio 1
	s_waitcnt lgkmcnt(5)
	v_mfma_f32_16x16x32_bf16 v[0:3], v[96:99], v[88:91], v[0:3]
	s_waitcnt lgkmcnt(0)
	v_mfma_f32_16x16x32_bf16 v[60:63], v[150:153], v[142:145], v[60:63]
	v_mfma_f32_16x16x32_bf16 v[56:59], v[150:153], v[138:141], v[56:59]
	v_mfma_f32_16x16x32_bf16 v[52:55], v[150:153], v[92:95], v[52:55]
	v_mfma_f32_16x16x32_bf16 v[48:51], v[150:153], v[88:91], v[48:51]
	v_mfma_f32_16x16x32_bf16 v[44:47], v[146:149], v[142:145], v[44:47]
	v_mfma_f32_16x16x32_bf16 v[40:43], v[146:149], v[138:141], v[40:43]
	v_mfma_f32_16x16x32_bf16 v[36:39], v[146:149], v[92:95], v[36:39]
	v_mfma_f32_16x16x32_bf16 v[32:35], v[146:149], v[88:91], v[32:35]
	v_mfma_f32_16x16x32_bf16 v[28:31], v[100:103], v[142:145], v[28:31]
	v_mfma_f32_16x16x32_bf16 v[24:27], v[100:103], v[138:141], v[24:27]
	v_mfma_f32_16x16x32_bf16 v[20:23], v[100:103], v[92:95], v[20:23]
	v_mfma_f32_16x16x32_bf16 v[16:19], v[100:103], v[88:91], v[16:19]
	v_mfma_f32_16x16x32_bf16 v[12:15], v[96:99], v[142:145], v[12:15]
	v_mfma_f32_16x16x32_bf16 v[8:11], v[96:99], v[138:141], v[8:11]
	v_mfma_f32_16x16x32_bf16 v[4:7], v[96:99], v[92:95], v[4:7]
	s_setprio 0
	ds_read_b128 v[88:91], v117 offset:32768
	ds_read_b128 v[92:95], v117 offset:34816
	ds_read_b128 v[96:99], v118 offset:49152
	ds_read_b128 v[100:103], v118 offset:51200
	ds_read_b128 v[138:141], v117 offset:36864
	ds_read_b128 v[142:145], v117 offset:38912
	ds_read_b128 v[146:149], v118 offset:53248
	ds_read_b128 v[150:153], v118 offset:55296
	s_setprio 1
	s_waitcnt lgkmcnt(0)
	v_mfma_f32_16x16x32_bf16 v[0:3], v[142:145], v[150:153], v[0:3]
	v_mfma_f32_16x16x32_bf16 v[60:63], v[88:91], v[96:99], v[60:63]
	v_mfma_f32_16x16x32_bf16 v[56:59], v[88:91], v[100:103], v[56:59]
	v_mfma_f32_16x16x32_bf16 v[52:55], v[88:91], v[146:149], v[52:55]
	v_mfma_f32_16x16x32_bf16 v[48:51], v[88:91], v[150:153], v[48:51]
	v_mfma_f32_16x16x32_bf16 v[44:47], v[92:95], v[96:99], v[44:47]
	v_mfma_f32_16x16x32_bf16 v[40:43], v[92:95], v[100:103], v[40:43]
	v_mfma_f32_16x16x32_bf16 v[36:39], v[92:95], v[146:149], v[36:39]
	v_mfma_f32_16x16x32_bf16 v[32:35], v[92:95], v[150:153], v[32:35]
	v_mfma_f32_16x16x32_bf16 v[28:31], v[138:141], v[96:99], v[28:31]
	v_mfma_f32_16x16x32_bf16 v[24:27], v[138:141], v[100:103], v[24:27]
	v_mfma_f32_16x16x32_bf16 v[20:23], v[138:141], v[146:149], v[20:23]
	v_mfma_f32_16x16x32_bf16 v[16:19], v[138:141], v[150:153], v[16:19]
	v_mfma_f32_16x16x32_bf16 v[12:15], v[142:145], v[96:99], v[12:15]
	v_mfma_f32_16x16x32_bf16 v[8:11], v[142:145], v[100:103], v[8:11]
	v_mfma_f32_16x16x32_bf16 v[4:7], v[142:145], v[146:149], v[4:7]
	s_setprio 0
	s_barrier
	ds_write2_b32 v119, v60, v56 offset1:16
	ds_write2_b32 v119, v61, v57 offset0:132 offset1:148
	v_add_u32_e32 v56, 0x400, v119
	ds_write2_b32 v56, v62, v58 offset0:8 offset1:24
	ds_write2_b32 v56, v63, v59 offset0:140 offset1:156
	ds_write2_b32 v119, v52, v48 offset0:32 offset1:48
	ds_write2_b32 v119, v53, v49 offset0:164 offset1:180
	ds_write2_b32 v56, v54, v50 offset0:40 offset1:56
	ds_write2_b32 v56, v55, v51 offset0:172 offset1:188
	v_add_u32_e32 v48, 0x2000, v119
	ds_write2_b32 v48, v44, v40 offset0:64 offset1:80
	ds_write2_b32 v48, v45, v41 offset0:196 offset1:212
	v_add_u32_e32 v40, 0x2400, v119
	ds_write2_b32 v40, v46, v42 offset0:72 offset1:88
	ds_write2_b32 v40, v47, v43 offset0:204 offset1:220
	ds_write2_b32 v48, v36, v32 offset0:96 offset1:112
	ds_write2_b32 v48, v37, v33 offset0:228 offset1:244
	ds_write2_b32 v40, v38, v34 offset0:104 offset1:120
	ds_write2_b32 v40, v39, v35 offset0:236 offset1:252
	v_add_u32_e32 v32, 0x4000, v119
	ds_write2_b32 v32, v28, v24 offset0:128 offset1:144
	v_add_u32_e32 v24, 0x4400, v119
	ds_write2_b32 v24, v29, v25 offset0:4 offset1:20
	ds_write2_b32 v24, v30, v26 offset0:136 offset1:152
	v_add_u32_e32 v25, 0x4800, v119
	ds_write2_b32 v25, v31, v27 offset0:12 offset1:28
	ds_write2_b32 v32, v20, v16 offset0:160 offset1:176
	ds_write2_b32 v24, v21, v17 offset0:36 offset1:52
	ds_write2_b32 v24, v22, v18 offset0:168 offset1:184
	ds_write2_b32 v25, v23, v19 offset0:44 offset1:60
	v_add_u32_e32 v16, 0x6000, v119
	ds_write2_b32 v16, v12, v8 offset0:192 offset1:208
	v_add_u32_e32 v8, 0x6400, v119
	ds_write2_b32 v8, v13, v9 offset0:68 offset1:84
	ds_write2_b32 v8, v14, v10 offset0:200 offset1:216
	v_add_u32_e32 v9, 0x6800, v119
	ds_write2_b32 v9, v15, v11 offset0:76 offset1:92
	ds_write2_b32 v16, v4, v0 offset0:224 offset1:240
	ds_write2_b32 v8, v5, v1 offset0:100 offset1:116
	ds_write2_b32 v8, v6, v2 offset0:232 offset1:248
	ds_write2_b32 v9, v7, v3 offset0:108 offset1:124
	v_or_b32_e32 v0, s12, v120
	v_ashrrev_i32_e32 v1, 31, v0
	v_lshl_add_u64 v[0:1], v[0:1], 1, s[4:5]
	v_add_u32_e32 v2, s13, v128
	s_mov_b32 s6, 0
	s_waitcnt lgkmcnt(0)
	s_barrier

.LBB0_681:
	s_ashr_i32 s14, s21, 31
	s_lshr_b32 s14, s14, 29
	s_add_i32 s14, s21, s14
	s_ashr_i32 s14, s14, 3
	s_lshl_b32 s22, s14, 7
	s_lshl_b32 s14, s14, 10
	s_lshl_b32 s15, s21, 7
	s_sub_i32 s23, s15, s14
	v_add_u32_e32 v0, s23, v106
	v_ashrrev_i32_e32 v1, 31, v0
	v_add_u32_e32 v2, 0x4000, v107
	v_lshlrev_b64 v[0:1], 13, v[0:1]
	v_readfirstlane_b32 s15, v2
	v_lshl_add_u64 v[0:1], v[66:67], 0, v[0:1]
	s_mov_b32 m0, s15
	v_readfirstlane_b32 s15, v107
	global_load_lds_dwordx4 v[0:1], off
	v_add_u32_e32 v0, s22, v106
	v_ashrrev_i32_e32 v1, 31, v0
	v_lshlrev_b64 v[0:1], 13, v[0:1]
	v_lshl_add_u64 v[2:3], v[72:73], 0, v[0:1]
	s_mov_b32 m0, s15
	v_readfirstlane_b32 s15, v130
	global_load_lds_dwordx4 v[2:3], off
	v_add_u32_e32 v2, s23, v108
	v_ashrrev_i32_e32 v3, 31, v2
	v_lshlrev_b64 v[2:3], 13, v[2:3]
	v_lshl_add_u64 v[2:3], v[68:69], 0, v[2:3]
	s_mov_b32 m0, s15
	v_add_u32_e32 v4, 0x400, v107
	global_load_lds_dwordx4 v[2:3], off
	v_add_u32_e32 v2, s22, v108
	v_ashrrev_i32_e32 v3, 31, v2
	v_lshlrev_b64 v[2:3], 13, v[2:3]
	v_readfirstlane_b32 s15, v4
	v_lshl_add_u64 v[2:3], v[74:75], 0, v[2:3]
	s_mov_b32 m0, s15
	v_readfirstlane_b32 s15, v131
	global_load_lds_dwordx4 v[2:3], off
	v_add_u32_e32 v2, s23, v110
	v_ashrrev_i32_e32 v3, 31, v2
	v_lshlrev_b64 v[2:3], 13, v[2:3]
	v_lshl_add_u64 v[2:3], v[66:67], 0, v[2:3]
	s_mov_b32 m0, s15
	v_add_u32_e32 v4, 0x800, v107
	global_load_lds_dwordx4 v[2:3], off
	v_add_u32_e32 v2, s22, v110
	v_ashrrev_i32_e32 v3, 31, v2
	v_lshlrev_b64 v[2:3], 13, v[2:3]
	v_readfirstlane_b32 s15, v4
	v_lshl_add_u64 v[2:3], v[72:73], 0, v[2:3]
	s_mov_b32 m0, s15
	v_readfirstlane_b32 s15, v132
	global_load_lds_dwordx4 v[2:3], off
	v_add_u32_e32 v2, s23, v112
	v_ashrrev_i32_e32 v3, 31, v2
	v_lshlrev_b64 v[2:3], 13, v[2:3]
	v_lshl_add_u64 v[2:3], v[70:71], 0, v[2:3]
	s_mov_b32 m0, s15
	v_add_u32_e32 v4, 0xc00, v107
	global_load_lds_dwordx4 v[2:3], off
	v_add_u32_e32 v2, s22, v112
	v_ashrrev_i32_e32 v3, 31, v2
	v_lshlrev_b64 v[2:3], 13, v[2:3]
	v_readfirstlane_b32 s15, v4
	v_lshl_add_u64 v[2:3], v[76:77], 0, v[2:3]
	s_mov_b32 m0, s15
	v_lshl_add_u64 v[92:93], v[80:81], 0, v[0:1]
	global_load_lds_dwordx4 v[2:3], off
	v_subrev_u32_e32 v0, s14, v123
	v_ashrrev_i32_e32 v1, 31, v0
	v_lshlrev_b64 v[0:1], 13, v[0:1]
	v_lshl_add_u64 v[94:95], v[82:83], 0, v[0:1]
	v_add_u32_e32 v0, s22, v124
	v_ashrrev_i32_e32 v1, 31, v0
	v_lshlrev_b64 v[0:1], 13, v[0:1]
	v_lshl_add_u64 v[96:97], v[84:85], 0, v[0:1]
	v_subrev_u32_e32 v0, s14, v125
	v_ashrrev_i32_e32 v1, 31, v0
	v_lshlrev_b64 v[0:1], 13, v[0:1]
	v_lshl_add_u64 v[98:99], v[78:79], 0, v[0:1]
	v_add_u32_e32 v0, s22, v126
	v_ashrrev_i32_e32 v1, 31, v0
	v_lshlrev_b64 v[0:1], 13, v[0:1]
	v_lshl_add_u64 v[100:101], v[80:81], 0, v[0:1]
	v_subrev_u32_e32 v0, s14, v64
	v_ashrrev_i32_e32 v1, 31, v0
	v_lshlrev_b64 v[0:1], 13, v[0:1]
	v_subrev_u32_e32 v2, s14, v122
	v_lshl_add_u64 v[102:103], v[86:87], 0, v[0:1]
	v_add_u32_e32 v0, s22, v127
	v_ashrrev_i32_e32 v3, 31, v2
	v_ashrrev_i32_e32 v1, 31, v0
	v_lshlrev_b64 v[2:3], 13, v[2:3]
	v_lshlrev_b64 v[0:1], 13, v[0:1]
	v_lshl_add_u64 v[90:91], v[78:79], 0, v[2:3]
	v_lshl_add_u64 v[104:105], v[88:89], 0, v[0:1]
	s_mov_b32 s24, 0
	s_mov_b64 s[14:15], 0
	v_mov_b32_e32 v0, 0
	v_mov_b32_e32 v1, v65
	v_mov_b32_e32 v2, v65
	v_mov_b32_e32 v3, v65
	v_mov_b32_e32 v4, 0
	v_mov_b32_e32 v5, v65
	v_mov_b32_e32 v6, v65
	v_mov_b32_e32 v7, v65
	v_mov_b32_e32 v8, 0
	v_mov_b32_e32 v9, v65
	v_mov_b32_e32 v10, v65
	v_mov_b32_e32 v11, v65
	v_mov_b32_e32 v12, 0
	v_mov_b32_e32 v13, v65
	v_mov_b32_e32 v14, v65
	v_mov_b32_e32 v15, v65
	v_mov_b32_e32 v16, 0
	v_mov_b32_e32 v17, v65
	v_mov_b32_e32 v18, v65
	v_mov_b32_e32 v19, v65
	v_mov_b32_e32 v20, 0
	v_mov_b32_e32 v21, v65
	v_mov_b32_e32 v22, v65
	v_mov_b32_e32 v23, v65
	v_mov_b32_e32 v24, 0
	v_mov_b32_e32 v25, v65
	v_mov_b32_e32 v26, v65
	v_mov_b32_e32 v27, v65
	v_mov_b32_e32 v28, 0
	v_mov_b32_e32 v29, v65
	v_mov_b32_e32 v30, v65
	v_mov_b32_e32 v31, v65
	v_mov_b32_e32 v32, 0
	v_mov_b32_e32 v33, v65
	v_mov_b32_e32 v34, v65
	v_mov_b32_e32 v35, v65
	v_mov_b32_e32 v36, 0
	v_mov_b32_e32 v37, v65
	v_mov_b32_e32 v38, v65
	v_mov_b32_e32 v39, v65
	v_mov_b32_e32 v40, 0
	v_mov_b32_e32 v41, v65
	v_mov_b32_e32 v42, v65
	v_mov_b32_e32 v43, v65
	v_mov_b32_e32 v44, 0
	v_mov_b32_e32 v45, v65
	v_mov_b32_e32 v46, v65
	v_mov_b32_e32 v47, v65
	v_mov_b32_e32 v48, 0
	v_mov_b32_e32 v49, v65
	v_mov_b32_e32 v50, v65
	v_mov_b32_e32 v51, v65
	v_mov_b32_e32 v52, 0
	v_mov_b32_e32 v53, v65
	v_mov_b32_e32 v54, v65
	v_mov_b32_e32 v55, v65
	v_mov_b32_e32 v56, 0
	v_mov_b32_e32 v57, v65
	v_mov_b32_e32 v58, v65
	v_mov_b32_e32 v59, v65
	v_mov_b32_e32 v60, 0
	v_mov_b32_e32 v61, v65
	v_mov_b32_e32 v62, v65
	v_mov_b32_e32 v63, v65
	s_waitcnt vmcnt(0) lgkmcnt(0)
	s_barrier
	v_add3_u32 v190, 0, v133, v134
	v_add_u32_e32 v191, 0x4000, v190
	s_nop 0
	v_readfirstlane_b32 s82, v191
	v_lshl_add_u32 v191, v109, 1, 0
	s_nop 0
	v_readfirstlane_b32 s83, v190
	v_add3_u32 v191, v191, v134, s17
	s_nop 0
	v_readfirstlane_b32 s84, v191
	v_add_u32_e32 v191, 0x400, v190
	s_nop 0
	v_readfirstlane_b32 s85, v191
	v_lshl_add_u32 v191, v111, 1, 0
	v_add3_u32 v191, v191, v134, s17
	s_nop 0
	v_readfirstlane_b32 s86, v191
	v_add_u32_e32 v191, 0x800, v190
	s_nop 0
	v_readfirstlane_b32 s87, v191
	v_lshl_add_u32 v191, v113, 1, 0
	v_add3_u32 v191, v191, v134, s17
	s_nop 0
	v_readfirstlane_b32 s88, v191
	v_add_u32_e32 v190, 0xc00, v190
	s_nop 0
	v_readfirstlane_b32 s89, v190
	v_subrev_u32_e32 v192, s52, v90
	v_subrev_u32_e32 v193, s52, v92
	v_subrev_u32_e32 v194, s52, v94
	v_subrev_u32_e32 v195, s52, v96
	v_subrev_u32_e32 v196, s52, v98
	v_subrev_u32_e32 v197, s52, v100
	v_subrev_u32_e32 v198, s52, v102
	v_subrev_u32_e32 v199, s52, v104
	s_bitcmp1_b32 s32, 0
	s_cbranch_scc1 .Lxk_682
.LBB0_682:
	s_and_b32 s25, s24, 0x4000
	s_xor_b32 s26, s25, 0x4000
	s_lshl_b32 s26, s26, 1
	s_add_i32 s26, s26, 32
	s_add_u32 s90, s52, s14
	s_addc_u32 s91, s53, s15
	s_add_i32 m0, s26, s82
	s_lshl_b32 s25, s25, 1
	global_load_lds_dwordx4 v192, s[90:91]
	s_add_i32 m0, s26, s83
	s_add_i32 s25, s25, 32
	global_load_lds_dwordx4 v193, s[90:91]
	s_add_i32 m0, s26, s84
	v_add3_u32 v170, s25, v114, v135
	global_load_lds_dwordx4 v194, s[90:91]
	s_add_i32 m0, s26, s85
	v_add3_u32 v171, s25, v115, v135
	global_load_lds_dwordx4 v195, s[90:91]
	s_add_i32 m0, s26, s86
	v_add_u32_e32 v158, v170, v136
	global_load_lds_dwordx4 v196, s[90:91]
	s_add_i32 m0, s26, s87
	v_add_u32_e32 v166, v171, v136
	global_load_lds_dwordx4 v197, s[90:91]
	s_add_i32 m0, s26, s88
	s_addk_i32 s24, 0x4000
	global_load_lds_dwordx4 v198, s[90:91]
	s_add_i32 m0, s26, s89
	s_add_u32 s14, s14, 0x80
	s_addc_u32 s15, s15, 0
	global_load_lds_dwordx4 v199, s[90:91]
	ds_read_b128 v[138:141], v158
	ds_read_b128 v[146:149], v166 offset:16384
	ds_read_b128 v[150:153], v166 offset:18432
	ds_read_b128 v[162:165], v166 offset:20480
	ds_read_b128 v[166:169], v166 offset:22528
	ds_read_b128 v[142:145], v158 offset:2048
	ds_read_b128 v[154:157], v158 offset:4096
	ds_read_b128 v[158:161], v158 offset:6144
	v_add_u32_e32 v236, v170, v137
	v_add_u32_e32 v237, v171, v137
	ds_read_b128 v[204:207], v236
	ds_read_b128 v[208:211], v237 offset:16384
	ds_read_b128 v[212:215], v237 offset:18432
	ds_read_b128 v[216:219], v237 offset:20480
	ds_read_b128 v[220:223], v237 offset:22528
	ds_read_b128 v[224:227], v236 offset:2048
	ds_read_b128 v[228:231], v236 offset:4096
	ds_read_b128 v[232:235], v236 offset:6144
	s_setprio 1
	s_waitcnt lgkmcnt(11)
	v_mfma_f32_16x16x32_bf16 v[60:63], v[138:141], v[146:149], v[60:63]
	v_mfma_f32_16x16x32_bf16 v[56:59], v[138:141], v[150:153], v[56:59]
	v_mfma_f32_16x16x32_bf16 v[52:55], v[138:141], v[162:165], v[52:55]
	v_mfma_f32_16x16x32_bf16 v[48:51], v[138:141], v[166:169], v[48:51]
	s_waitcnt lgkmcnt(10)
	v_mfma_f32_16x16x32_bf16 v[44:47], v[142:145], v[146:149], v[44:47]
	v_mfma_f32_16x16x32_bf16 v[40:43], v[142:145], v[150:153], v[40:43]
	v_mfma_f32_16x16x32_bf16 v[36:39], v[142:145], v[162:165], v[36:39]
	v_mfma_f32_16x16x32_bf16 v[32:35], v[142:145], v[166:169], v[32:35]
	s_waitcnt lgkmcnt(9)
	v_mfma_f32_16x16x32_bf16 v[28:31], v[154:157], v[146:149], v[28:31]
	v_mfma_f32_16x16x32_bf16 v[24:27], v[154:157], v[150:153], v[24:27]
	v_mfma_f32_16x16x32_bf16 v[20:23], v[154:157], v[162:165], v[20:23]
	v_mfma_f32_16x16x32_bf16 v[16:19], v[154:157], v[166:169], v[16:19]
	s_waitcnt lgkmcnt(8)
	v_mfma_f32_16x16x32_bf16 v[12:15], v[158:161], v[146:149], v[12:15]
	v_mfma_f32_16x16x32_bf16 v[8:11], v[158:161], v[150:153], v[8:11]
	v_mfma_f32_16x16x32_bf16 v[4:7], v[158:161], v[162:165], v[4:7]
	v_mfma_f32_16x16x32_bf16 v[0:3], v[158:161], v[166:169], v[0:3]
	s_waitcnt lgkmcnt(3)
	v_mfma_f32_16x16x32_bf16 v[60:63], v[204:207], v[208:211], v[60:63]
	v_mfma_f32_16x16x32_bf16 v[56:59], v[204:207], v[212:215], v[56:59]
	v_mfma_f32_16x16x32_bf16 v[52:55], v[204:207], v[216:219], v[52:55]
	v_mfma_f32_16x16x32_bf16 v[48:51], v[204:207], v[220:223], v[48:51]
	s_waitcnt lgkmcnt(2)
	v_mfma_f32_16x16x32_bf16 v[44:47], v[224:227], v[208:211], v[44:47]
	v_mfma_f32_16x16x32_bf16 v[40:43], v[224:227], v[212:215], v[40:43]
	v_mfma_f32_16x16x32_bf16 v[36:39], v[224:227], v[216:219], v[36:39]
	v_mfma_f32_16x16x32_bf16 v[32:35], v[224:227], v[220:223], v[32:35]
	s_waitcnt lgkmcnt(1)
	v_mfma_f32_16x16x32_bf16 v[28:31], v[228:231], v[208:211], v[28:31]
	v_mfma_f32_16x16x32_bf16 v[24:27], v[228:231], v[212:215], v[24:27]
	v_mfma_f32_16x16x32_bf16 v[20:23], v[228:231], v[216:219], v[20:23]
	v_mfma_f32_16x16x32_bf16 v[16:19], v[228:231], v[220:223], v[16:19]
	s_waitcnt lgkmcnt(0)
	v_mfma_f32_16x16x32_bf16 v[12:15], v[232:235], v[208:211], v[12:15]
	v_mfma_f32_16x16x32_bf16 v[8:11], v[232:235], v[212:215], v[8:11]
	v_mfma_f32_16x16x32_bf16 v[4:7], v[232:235], v[216:219], v[4:7]
	v_mfma_f32_16x16x32_bf16 v[0:3], v[232:235], v[220:223], v[0:3]
	s_setprio 0
	s_cmpk_eq_i32 s14, 0x1f80
	s_waitcnt vmcnt(0)
	s_barrier
	s_cbranch_scc0 .LBB0_682
	s_branch .Lxk_exit_682
.Lxk_682:
	s_and_b32 s25, s24, 0x4000
	s_xor_b32 s26, s25, 0x4000
	s_lshl_b32 s26, s26, 1
	s_add_i32 s26, s26, 32
	s_add_u32 s90, s52, s14
	s_addc_u32 s91, s53, s15
	s_add_i32 m0, s26, s82
	s_lshl_b32 s25, s25, 1
	global_load_lds_dwordx4 v192, s[90:91]
	s_add_i32 m0, s26, s83
	s_add_i32 s25, s25, 32
	global_load_lds_dwordx4 v193, s[90:91]
	s_add_i32 m0, s26, s84
	v_add3_u32 v170, s25, v114, v135
	global_load_lds_dwordx4 v194, s[90:91]
	s_add_i32 m0, s26, s85
	v_add3_u32 v171, s25, v115, v135
	global_load_lds_dwordx4 v195, s[90:91]
	s_add_i32 m0, s26, s86
	v_add_u32_e32 v158, v170, v136
	global_load_lds_dwordx4 v196, s[90:91]
	s_add_i32 m0, s26, s87
	v_add_u32_e32 v166, v171, v136
	global_load_lds_dwordx4 v197, s[90:91]
	s_add_i32 m0, s26, s88
	s_addk_i32 s24, 0x4000
	global_load_lds_dwordx4 v198, s[90:91]
	s_add_i32 m0, s26, s89
	s_add_u32 s14, s14, 0x80
	s_addc_u32 s15, s15, 0
	global_load_lds_dwordx4 v199, s[90:91]
	ds_read_b128 v[138:141], v158
	ds_read_b128 v[146:149], v166 offset:16384
	ds_read_b128 v[150:153], v166 offset:18432
	ds_read_b128 v[162:165], v166 offset:20480
	ds_read_b128 v[166:169], v166 offset:22528
	ds_read_b128 v[142:145], v158 offset:2048
	ds_read_b128 v[154:157], v158 offset:4096
	ds_read_b128 v[158:161], v158 offset:6144
	v_add_u32_e32 v236, v170, v137
	v_add_u32_e32 v237, v171, v137
	ds_read_b128 v[204:207], v236
	ds_read_b128 v[208:211], v237 offset:16384
	ds_read_b128 v[212:215], v237 offset:18432
	ds_read_b128 v[216:219], v237 offset:20480
	ds_read_b128 v[220:223], v237 offset:22528
	ds_read_b128 v[224:227], v236 offset:2048
	ds_read_b128 v[228:231], v236 offset:4096
	ds_read_b128 v[232:235], v236 offset:6144
	s_setprio 3
	s_waitcnt lgkmcnt(11)
	v_mfma_f32_16x16x32_bf16 v[60:63], v[138:141], v[146:149], v[60:63]
	v_mfma_f32_16x16x32_bf16 v[56:59], v[138:141], v[150:153], v[56:59]
	v_mfma_f32_16x16x32_bf16 v[52:55], v[138:141], v[162:165], v[52:55]
	v_mfma_f32_16x16x32_bf16 v[48:51], v[138:141], v[166:169], v[48:51]
	s_waitcnt lgkmcnt(10)
	v_mfma_f32_16x16x32_bf16 v[44:47], v[142:145], v[146:149], v[44:47]
	v_mfma_f32_16x16x32_bf16 v[40:43], v[142:145], v[150:153], v[40:43]
	v_mfma_f32_16x16x32_bf16 v[36:39], v[142:145], v[162:165], v[36:39]
	v_mfma_f32_16x16x32_bf16 v[32:35], v[142:145], v[166:169], v[32:35]
	s_waitcnt lgkmcnt(9)
	v_mfma_f32_16x16x32_bf16 v[28:31], v[154:157], v[146:149], v[28:31]
	v_mfma_f32_16x16x32_bf16 v[24:27], v[154:157], v[150:153], v[24:27]
	v_mfma_f32_16x16x32_bf16 v[20:23], v[154:157], v[162:165], v[20:23]
	v_mfma_f32_16x16x32_bf16 v[16:19], v[154:157], v[166:169], v[16:19]
	s_waitcnt lgkmcnt(8)
	v_mfma_f32_16x16x32_bf16 v[12:15], v[158:161], v[146:149], v[12:15]
	v_mfma_f32_16x16x32_bf16 v[8:11], v[158:161], v[150:153], v[8:11]
	v_mfma_f32_16x16x32_bf16 v[4:7], v[158:161], v[162:165], v[4:7]
	v_mfma_f32_16x16x32_bf16 v[0:3], v[158:161], v[166:169], v[0:3]
	s_waitcnt lgkmcnt(3)
	v_mfma_f32_16x16x32_bf16 v[60:63], v[204:207], v[208:211], v[60:63]
	v_mfma_f32_16x16x32_bf16 v[56:59], v[204:207], v[212:215], v[56:59]
	v_mfma_f32_16x16x32_bf16 v[52:55], v[204:207], v[216:219], v[52:55]
	v_mfma_f32_16x16x32_bf16 v[48:51], v[204:207], v[220:223], v[48:51]
	s_waitcnt lgkmcnt(2)
	v_mfma_f32_16x16x32_bf16 v[44:47], v[224:227], v[208:211], v[44:47]
	v_mfma_f32_16x16x32_bf16 v[40:43], v[224:227], v[212:215], v[40:43]
	v_mfma_f32_16x16x32_bf16 v[36:39], v[224:227], v[216:219], v[36:39]
	v_mfma_f32_16x16x32_bf16 v[32:35], v[224:227], v[220:223], v[32:35]
	s_waitcnt lgkmcnt(1)
	v_mfma_f32_16x16x32_bf16 v[28:31], v[228:231], v[208:211], v[28:31]
	v_mfma_f32_16x16x32_bf16 v[24:27], v[228:231], v[212:215], v[24:27]
	v_mfma_f32_16x16x32_bf16 v[20:23], v[228:231], v[216:219], v[20:23]
	v_mfma_f32_16x16x32_bf16 v[16:19], v[228:231], v[220:223], v[16:19]
	s_waitcnt lgkmcnt(0)
	v_mfma_f32_16x16x32_bf16 v[12:15], v[232:235], v[208:211], v[12:15]
	v_mfma_f32_16x16x32_bf16 v[8:11], v[232:235], v[212:215], v[8:11]
	v_mfma_f32_16x16x32_bf16 v[4:7], v[232:235], v[216:219], v[4:7]
	v_mfma_f32_16x16x32_bf16 v[0:3], v[232:235], v[220:223], v[0:3]
	s_setprio 2
	s_cmpk_eq_i32 s14, 0x1f80
	s_waitcnt vmcnt(0)
	s_barrier
	s_cbranch_scc0 .Lxk_682
.Lxk_exit_682:
	ds_read_b128 v[90:93], v118 offset:55296
	ds_read_b128 v[94:97], v118 offset:53248
	ds_read_b128 v[98:101], v119 offset:38912
	ds_read_b128 v[102:105], v119 offset:36864
	ds_read_b128 v[138:141], v118 offset:51200
	ds_read_b128 v[142:145], v118 offset:49152
	ds_read_b128 v[146:149], v119 offset:34816
	ds_read_b128 v[150:153], v119 offset:32768
	s_setprio 1
	s_waitcnt lgkmcnt(5)
	v_mfma_f32_16x16x32_bf16 v[4:7], v[98:101], v[94:97], v[4:7]
	v_mfma_f32_16x16x32_bf16 v[0:3], v[98:101], v[90:93], v[0:3]
	s_waitcnt lgkmcnt(0)
	v_mfma_f32_16x16x32_bf16 v[60:63], v[150:153], v[142:145], v[60:63]
	v_mfma_f32_16x16x32_bf16 v[56:59], v[150:153], v[138:141], v[56:59]
	v_mfma_f32_16x16x32_bf16 v[52:55], v[150:153], v[94:97], v[52:55]
	v_mfma_f32_16x16x32_bf16 v[48:51], v[150:153], v[90:93], v[48:51]
	v_mfma_f32_16x16x32_bf16 v[44:47], v[146:149], v[142:145], v[44:47]
	v_mfma_f32_16x16x32_bf16 v[40:43], v[146:149], v[138:141], v[40:43]
	v_mfma_f32_16x16x32_bf16 v[36:39], v[146:149], v[94:97], v[36:39]
	v_mfma_f32_16x16x32_bf16 v[32:35], v[146:149], v[90:93], v[32:35]
	v_mfma_f32_16x16x32_bf16 v[28:31], v[102:105], v[142:145], v[28:31]
	v_mfma_f32_16x16x32_bf16 v[24:27], v[102:105], v[138:141], v[24:27]
	v_mfma_f32_16x16x32_bf16 v[20:23], v[102:105], v[94:97], v[20:23]
	v_mfma_f32_16x16x32_bf16 v[16:19], v[102:105], v[90:93], v[16:19]
	v_mfma_f32_16x16x32_bf16 v[12:15], v[98:101], v[142:145], v[12:15]
	v_mfma_f32_16x16x32_bf16 v[8:11], v[98:101], v[138:141], v[8:11]
	s_setprio 0
	ds_read_b128 v[90:93], v120 offset:32768
	ds_read_b128 v[94:97], v120 offset:34816
	ds_read_b128 v[98:101], v121 offset:49152
	ds_read_b128 v[102:105], v121 offset:51200
	ds_read_b128 v[138:141], v120 offset:36864
	ds_read_b128 v[142:145], v120 offset:38912
	ds_read_b128 v[146:149], v121 offset:53248
	ds_read_b128 v[150:153], v121 offset:55296
	s_setprio 1
	s_waitcnt lgkmcnt(1)
	v_mfma_f32_16x16x32_bf16 v[4:7], v[142:145], v[146:149], v[4:7]
	s_waitcnt lgkmcnt(0)
	v_mfma_f32_16x16x32_bf16 v[0:3], v[142:145], v[150:153], v[0:3]
	v_mfma_f32_16x16x32_bf16 v[60:63], v[90:93], v[98:101], v[60:63]
	v_mfma_f32_16x16x32_bf16 v[56:59], v[90:93], v[102:105], v[56:59]
	v_mfma_f32_16x16x32_bf16 v[52:55], v[90:93], v[146:149], v[52:55]
	v_mfma_f32_16x16x32_bf16 v[48:51], v[90:93], v[150:153], v[48:51]
	v_mfma_f32_16x16x32_bf16 v[44:47], v[94:97], v[98:101], v[44:47]
	v_mfma_f32_16x16x32_bf16 v[40:43], v[94:97], v[102:105], v[40:43]
	v_mfma_f32_16x16x32_bf16 v[36:39], v[94:97], v[146:149], v[36:39]
	v_mfma_f32_16x16x32_bf16 v[32:35], v[94:97], v[150:153], v[32:35]
	v_mfma_f32_16x16x32_bf16 v[28:31], v[138:141], v[98:101], v[28:31]
	v_mfma_f32_16x16x32_bf16 v[24:27], v[138:141], v[102:105], v[24:27]
	v_mfma_f32_16x16x32_bf16 v[20:23], v[138:141], v[146:149], v[20:23]
	v_mfma_f32_16x16x32_bf16 v[16:19], v[138:141], v[150:153], v[16:19]
	v_mfma_f32_16x16x32_bf16 v[12:15], v[142:145], v[98:101], v[12:15]
	v_mfma_f32_16x16x32_bf16 v[8:11], v[142:145], v[102:105], v[8:11]
	s_setprio 0
	s_barrier
	ds_write2_b32 v116, v60, v56 offset1:16
	ds_write2_b32 v116, v61, v57 offset0:132 offset1:148
	v_add_u32_e32 v56, 0x400, v116
	ds_write2_b32 v56, v62, v58 offset0:8 offset1:24
	ds_write2_b32 v56, v63, v59 offset0:140 offset1:156
	ds_write2_b32 v116, v52, v48 offset0:32 offset1:48
	ds_write2_b32 v116, v53, v49 offset0:164 offset1:180
	ds_write2_b32 v56, v54, v50 offset0:40 offset1:56
	ds_write2_b32 v56, v55, v51 offset0:172 offset1:188
	v_add_u32_e32 v48, 0x2000, v116
	ds_write2_b32 v48, v44, v40 offset0:64 offset1:80
	ds_write2_b32 v48, v45, v41 offset0:196 offset1:212
	v_add_u32_e32 v40, 0x2400, v116
	ds_write2_b32 v40, v46, v42 offset0:72 offset1:88
	ds_write2_b32 v40, v47, v43 offset0:204 offset1:220
	ds_write2_b32 v48, v36, v32 offset0:96 offset1:112
	ds_write2_b32 v48, v37, v33 offset0:228 offset1:244
	ds_write2_b32 v40, v38, v34 offset0:104 offset1:120
	ds_write2_b32 v40, v39, v35 offset0:236 offset1:252
	v_add_u32_e32 v32, 0x4000, v116
	ds_write2_b32 v32, v28, v24 offset0:128 offset1:144
	v_add_u32_e32 v24, 0x4400, v116
	ds_write2_b32 v24, v29, v25 offset0:4 offset1:20
	ds_write2_b32 v24, v30, v26 offset0:136 offset1:152
	v_add_u32_e32 v25, 0x4800, v116
	ds_write2_b32 v25, v31, v27 offset0:12 offset1:28
	ds_write2_b32 v32, v20, v16 offset0:160 offset1:176
	ds_write2_b32 v24, v21, v17 offset0:36 offset1:52
	ds_write2_b32 v24, v22, v18 offset0:168 offset1:184
	ds_write2_b32 v25, v23, v19 offset0:44 offset1:60
	v_add_u32_e32 v16, 0x6000, v116
	ds_write2_b32 v16, v12, v8 offset0:192 offset1:208
	v_add_u32_e32 v8, 0x6400, v116
	ds_write2_b32 v8, v13, v9 offset0:68 offset1:84
	ds_write2_b32 v8, v14, v10 offset0:200 offset1:216
	v_add_u32_e32 v9, 0x6800, v116
	ds_write2_b32 v9, v15, v11 offset0:76 offset1:92
	ds_write2_b32 v16, v4, v0 offset0:224 offset1:240
	ds_write2_b32 v8, v5, v1 offset0:100 offset1:116
	ds_write2_b32 v8, v6, v2 offset0:232 offset1:248
	ds_write2_b32 v9, v7, v3 offset0:108 offset1:124
	v_or_b32_e32 v0, s23, v117
	v_ashrrev_i32_e32 v1, 31, v0
	v_lshlrev_b64 v[2:3], 2, v[0:1]
	v_lshl_add_u64 v[0:1], s[12:13], 0, v[2:3]
	v_lshl_add_u64 v[2:3], s[10:11], 0, v[2:3]
	v_add_u32_e32 v4, s22, v128
	s_mov_b32 s14, 0
	s_waitcnt lgkmcnt(0)
	s_barrier

.LBB0_690:
	s_ashr_i32 s14, s16, 31
	s_lshr_b32 s14, s14, 29
	s_add_i32 s14, s16, s14
	s_ashr_i32 s14, s14, 3
	s_lshl_b32 s15, s14, 10
	s_lshl_b32 s23, s16, 7
	v_add_u32_e32 v0, s14, v104
	s_sub_i32 s23, s23, s15
	v_lshlrev_b32_e32 v2, 7, v0
	v_add_u32_e32 v0, s23, v105
	v_ashrrev_i32_e32 v1, 31, v0
	v_add_u32_e32 v3, 0x4000, v106
	v_lshlrev_b64 v[0:1], 13, v[0:1]
	v_readfirstlane_b32 s24, v3
	v_lshl_add_u64 v[0:1], v[64:65], 0, v[0:1]
	s_mov_b32 m0, s24
	v_readfirstlane_b32 s24, v106
	global_load_lds_dwordx4 v[0:1], off
	v_add_u32_e32 v0, v2, v105
	v_ashrrev_i32_e32 v1, 31, v0
	v_lshlrev_b64 v[0:1], 13, v[0:1]
	v_lshl_add_u64 v[0:1], v[70:71], 0, v[0:1]
	s_mov_b32 m0, s24
	v_readfirstlane_b32 s24, v131
	global_load_lds_dwordx4 v[0:1], off
	v_add_u32_e32 v0, s23, v107
	v_ashrrev_i32_e32 v1, 31, v0
	v_lshlrev_b64 v[0:1], 13, v[0:1]
	v_lshl_add_u64 v[0:1], v[66:67], 0, v[0:1]
	s_mov_b32 m0, s24
	v_add_u32_e32 v3, 0x400, v106
	global_load_lds_dwordx4 v[0:1], off
	v_add_u32_e32 v0, v2, v107
	v_ashrrev_i32_e32 v1, 31, v0
	v_lshlrev_b64 v[0:1], 13, v[0:1]
	v_readfirstlane_b32 s24, v3
	v_lshl_add_u64 v[0:1], v[72:73], 0, v[0:1]
	s_mov_b32 m0, s24
	v_readfirstlane_b32 s24, v132
	global_load_lds_dwordx4 v[0:1], off
	v_add_u32_e32 v0, s23, v109
	v_ashrrev_i32_e32 v1, 31, v0
	v_lshlrev_b64 v[0:1], 13, v[0:1]
	v_lshl_add_u64 v[0:1], v[64:65], 0, v[0:1]
	s_mov_b32 m0, s24
	v_add_u32_e32 v3, 0x800, v106
	global_load_lds_dwordx4 v[0:1], off
	v_add_u32_e32 v0, v2, v109
	v_ashrrev_i32_e32 v1, 31, v0
	v_lshlrev_b64 v[0:1], 13, v[0:1]
	v_readfirstlane_b32 s24, v3
	v_lshl_add_u64 v[0:1], v[70:71], 0, v[0:1]
	s_mov_b32 m0, s24
	v_readfirstlane_b32 s24, v133
	global_load_lds_dwordx4 v[0:1], off
	v_add_u32_e32 v0, s23, v111
	v_ashrrev_i32_e32 v1, 31, v0
	v_lshlrev_b64 v[0:1], 13, v[0:1]
	v_lshl_add_u64 v[0:1], v[68:69], 0, v[0:1]
	s_mov_b32 m0, s24
	s_mov_b32 s25, 0
	global_load_lds_dwordx4 v[0:1], off
	v_add_u32_e32 v0, v2, v111
	v_ashrrev_i32_e32 v1, 31, v0
	v_add_u32_e32 v2, 0xc00, v106
	v_lshlrev_b64 v[0:1], 13, v[0:1]
	v_readfirstlane_b32 s24, v2
	v_lshl_add_u64 v[0:1], v[74:75], 0, v[0:1]
	s_mov_b32 m0, s24
	s_lshl_b32 s24, s14, 7
	global_load_lds_dwordx4 v[0:1], off
	v_subrev_u32_e32 v0, s15, v121
	v_ashrrev_i32_e32 v1, 31, v0
	v_lshlrev_b64 v[0:1], 13, v[0:1]
	v_lshl_add_u64 v[88:89], v[76:77], 0, v[0:1]
	v_add_u32_e32 v0, s24, v122
	v_ashrrev_i32_e32 v1, 31, v0
	v_lshlrev_b64 v[0:1], 13, v[0:1]
	v_lshl_add_u64 v[90:91], v[78:79], 0, v[0:1]
	v_subrev_u32_e32 v0, s15, v123
	v_ashrrev_i32_e32 v1, 31, v0
	v_lshlrev_b64 v[0:1], 13, v[0:1]
	v_lshl_add_u64 v[92:93], v[80:81], 0, v[0:1]
	v_add_u32_e32 v0, s24, v124
	v_ashrrev_i32_e32 v1, 31, v0
	v_lshlrev_b64 v[0:1], 13, v[0:1]
	v_lshl_add_u64 v[94:95], v[82:83], 0, v[0:1]
	v_subrev_u32_e32 v0, s15, v125
	v_ashrrev_i32_e32 v1, 31, v0
	v_lshlrev_b64 v[0:1], 13, v[0:1]
	v_lshl_add_u64 v[96:97], v[76:77], 0, v[0:1]
	v_add_u32_e32 v0, s24, v126
	v_ashrrev_i32_e32 v1, 31, v0
	v_lshlrev_b64 v[0:1], 13, v[0:1]
	v_lshl_add_u64 v[98:99], v[78:79], 0, v[0:1]
	v_subrev_u32_e32 v0, s15, v127
	v_ashrrev_i32_e32 v1, 31, v0
	v_lshlrev_b64 v[0:1], 13, v[0:1]
	v_lshl_add_u64 v[100:101], v[84:85], 0, v[0:1]
	v_add_u32_e32 v0, s24, v128
	v_ashrrev_i32_e32 v1, 31, v0
	v_lshlrev_b64 v[0:1], 13, v[0:1]
	v_lshl_add_u64 v[102:103], v[86:87], 0, v[0:1]
	v_mov_b32_e32 v0, 0
	s_mov_b64 s[14:15], 0
	v_mov_b32_e32 v1, v0
	v_mov_b32_e32 v2, v0
	v_mov_b32_e32 v3, v0
	v_mov_b32_e32 v4, v0
	v_mov_b32_e32 v5, v0
	v_mov_b32_e32 v6, v0
	v_mov_b32_e32 v7, v0
	v_mov_b32_e32 v8, v0
	v_mov_b32_e32 v9, v0
	v_mov_b32_e32 v10, v0
	v_mov_b32_e32 v11, v0
	v_mov_b32_e32 v12, v0
	v_mov_b32_e32 v13, v0
	v_mov_b32_e32 v14, v0
	v_mov_b32_e32 v15, v0
	v_mov_b32_e32 v16, v0
	v_mov_b32_e32 v17, v0
	v_mov_b32_e32 v18, v0
	v_mov_b32_e32 v19, v0
	v_mov_b32_e32 v20, v0
	v_mov_b32_e32 v21, v0
	v_mov_b32_e32 v22, v0
	v_mov_b32_e32 v23, v0
	v_mov_b32_e32 v24, v0
	v_mov_b32_e32 v25, v0
	v_mov_b32_e32 v26, v0
	v_mov_b32_e32 v27, v0
	v_mov_b32_e32 v28, v0
	v_mov_b32_e32 v29, v0
	v_mov_b32_e32 v30, v0
	v_mov_b32_e32 v31, v0
	v_mov_b32_e32 v32, v0
	v_mov_b32_e32 v33, v0
	v_mov_b32_e32 v34, v0
	v_mov_b32_e32 v35, v0
	v_mov_b32_e32 v36, v0
	v_mov_b32_e32 v37, v0
	v_mov_b32_e32 v38, v0
	v_mov_b32_e32 v39, v0
	v_mov_b32_e32 v40, v0
	v_mov_b32_e32 v41, v0
	v_mov_b32_e32 v42, v0
	v_mov_b32_e32 v43, v0
	v_mov_b32_e32 v44, v0
	v_mov_b32_e32 v45, v0
	v_mov_b32_e32 v46, v0
	v_mov_b32_e32 v47, v0
	v_mov_b32_e32 v48, v0
	v_mov_b32_e32 v49, v0
	v_mov_b32_e32 v50, v0
	v_mov_b32_e32 v51, v0
	v_mov_b32_e32 v52, v0
	v_mov_b32_e32 v53, v0
	v_mov_b32_e32 v54, v0
	v_mov_b32_e32 v55, v0
	v_mov_b32_e32 v56, v0
	v_mov_b32_e32 v57, v0
	v_mov_b32_e32 v58, v0
	v_mov_b32_e32 v59, v0
	v_mov_b32_e32 v60, v0
	v_mov_b32_e32 v61, v0
	v_mov_b32_e32 v62, v0
	v_mov_b32_e32 v63, v0
	s_waitcnt vmcnt(0) lgkmcnt(0)
	s_barrier
	v_add3_u32 v190, 0, v134, v135
	v_add_u32_e32 v191, 0x4000, v190
	s_nop 0
	v_readfirstlane_b32 s82, v191
	v_lshl_add_u32 v191, v108, 1, 0
	s_nop 0
	v_readfirstlane_b32 s83, v190
	v_add3_u32 v191, v191, v135, s19
	s_nop 0
	v_readfirstlane_b32 s84, v191
	v_add_u32_e32 v191, 0x400, v190
	s_nop 0
	v_readfirstlane_b32 s85, v191
	v_lshl_add_u32 v191, v110, 1, 0
	v_add3_u32 v191, v191, v135, s19
	s_nop 0
	v_readfirstlane_b32 s86, v191
	v_add_u32_e32 v191, 0x800, v190
	s_nop 0
	v_readfirstlane_b32 s87, v191
	v_lshl_add_u32 v191, v112, 1, 0
	v_add3_u32 v191, v191, v135, s19
	s_nop 0
	v_readfirstlane_b32 s88, v191
	v_add_u32_e32 v190, 0xc00, v190
	s_nop 0
	v_readfirstlane_b32 s89, v190
	v_subrev_u32_e32 v192, s52, v88
	v_subrev_u32_e32 v193, s52, v90
	v_subrev_u32_e32 v194, s52, v92
	v_subrev_u32_e32 v195, s52, v94
	v_subrev_u32_e32 v196, s52, v96
	v_subrev_u32_e32 v197, s52, v98
	v_subrev_u32_e32 v198, s52, v100
	v_subrev_u32_e32 v199, s52, v102
	s_bitcmp1_b32 s32, 0
	s_cbranch_scc1 .Lxk_691
.LBB0_691:
	s_and_b32 s26, s25, 0x4000
	s_xor_b32 s27, s26, 0x4000
	s_lshl_b32 s27, s27, 1
	s_add_i32 s27, s27, 32
	s_add_u32 s90, s52, s14
	s_addc_u32 s91, s53, s15
	s_add_i32 m0, s27, s82
	s_lshl_b32 s26, s26, 1
	global_load_lds_dwordx4 v192, s[90:91]
	s_add_i32 m0, s27, s83
	s_add_i32 s26, s26, 32
	global_load_lds_dwordx4 v193, s[90:91]
	s_add_i32 m0, s27, s84
	v_add3_u32 v139, s26, v113, v136
	global_load_lds_dwordx4 v194, s[90:91]
	s_add_i32 m0, s27, s85
	v_add3_u32 v172, s26, v114, v136
	global_load_lds_dwordx4 v195, s[90:91]
	s_add_i32 m0, s27, s86
	v_add_u32_e32 v160, v139, v137
	global_load_lds_dwordx4 v196, s[90:91]
	s_add_i32 m0, s27, s87
	v_add_u32_e32 v168, v172, v137
	global_load_lds_dwordx4 v197, s[90:91]
	s_add_i32 m0, s27, s88
	s_addk_i32 s25, 0x4000
	global_load_lds_dwordx4 v198, s[90:91]
	s_add_i32 m0, s27, s89
	s_add_u32 s14, s14, 0x80
	s_addc_u32 s15, s15, 0
	global_load_lds_dwordx4 v199, s[90:91]
	ds_read_b128 v[140:143], v160
	ds_read_b128 v[148:151], v168 offset:16384
	ds_read_b128 v[152:155], v168 offset:18432
	ds_read_b128 v[164:167], v168 offset:20480
	ds_read_b128 v[168:171], v168 offset:22528
	ds_read_b128 v[144:147], v160 offset:2048
	ds_read_b128 v[156:159], v160 offset:4096
	ds_read_b128 v[160:163], v160 offset:6144
	v_add_u32_e32 v139, v139, v138
	v_add_u32_e32 v236, v172, v138
	ds_read_b128 v[204:207], v139
	ds_read_b128 v[208:211], v236 offset:16384
	ds_read_b128 v[212:215], v236 offset:18432
	ds_read_b128 v[216:219], v236 offset:20480
	ds_read_b128 v[220:223], v236 offset:22528
	ds_read_b128 v[224:227], v139 offset:2048
	ds_read_b128 v[228:231], v139 offset:4096
	ds_read_b128 v[232:235], v139 offset:6144
	s_setprio 1
	s_waitcnt lgkmcnt(11)
	v_mfma_f32_16x16x32_bf16 v[60:63], v[140:143], v[148:151], v[60:63]
	v_mfma_f32_16x16x32_bf16 v[56:59], v[140:143], v[152:155], v[56:59]
	v_mfma_f32_16x16x32_bf16 v[52:55], v[140:143], v[164:167], v[52:55]
	v_mfma_f32_16x16x32_bf16 v[48:51], v[140:143], v[168:171], v[48:51]
	s_waitcnt lgkmcnt(10)
	v_mfma_f32_16x16x32_bf16 v[44:47], v[144:147], v[148:151], v[44:47]
	v_mfma_f32_16x16x32_bf16 v[40:43], v[144:147], v[152:155], v[40:43]
	v_mfma_f32_16x16x32_bf16 v[36:39], v[144:147], v[164:167], v[36:39]
	v_mfma_f32_16x16x32_bf16 v[32:35], v[144:147], v[168:171], v[32:35]
	s_waitcnt lgkmcnt(9)
	v_mfma_f32_16x16x32_bf16 v[28:31], v[156:159], v[148:151], v[28:31]
	v_mfma_f32_16x16x32_bf16 v[24:27], v[156:159], v[152:155], v[24:27]
	v_mfma_f32_16x16x32_bf16 v[20:23], v[156:159], v[164:167], v[20:23]
	v_mfma_f32_16x16x32_bf16 v[16:19], v[156:159], v[168:171], v[16:19]
	s_waitcnt lgkmcnt(8)
	v_mfma_f32_16x16x32_bf16 v[12:15], v[160:163], v[148:151], v[12:15]
	v_mfma_f32_16x16x32_bf16 v[8:11], v[160:163], v[152:155], v[8:11]
	v_mfma_f32_16x16x32_bf16 v[4:7], v[160:163], v[164:167], v[4:7]
	v_mfma_f32_16x16x32_bf16 v[0:3], v[160:163], v[168:171], v[0:3]
	s_waitcnt lgkmcnt(3)
	v_mfma_f32_16x16x32_bf16 v[60:63], v[204:207], v[208:211], v[60:63]
	v_mfma_f32_16x16x32_bf16 v[56:59], v[204:207], v[212:215], v[56:59]
	v_mfma_f32_16x16x32_bf16 v[52:55], v[204:207], v[216:219], v[52:55]
	v_mfma_f32_16x16x32_bf16 v[48:51], v[204:207], v[220:223], v[48:51]
	s_waitcnt lgkmcnt(2)
	v_mfma_f32_16x16x32_bf16 v[44:47], v[224:227], v[208:211], v[44:47]
	v_mfma_f32_16x16x32_bf16 v[40:43], v[224:227], v[212:215], v[40:43]
	v_mfma_f32_16x16x32_bf16 v[36:39], v[224:227], v[216:219], v[36:39]
	v_mfma_f32_16x16x32_bf16 v[32:35], v[224:227], v[220:223], v[32:35]
	s_waitcnt lgkmcnt(1)
	v_mfma_f32_16x16x32_bf16 v[28:31], v[228:231], v[208:211], v[28:31]
	v_mfma_f32_16x16x32_bf16 v[24:27], v[228:231], v[212:215], v[24:27]
	v_mfma_f32_16x16x32_bf16 v[20:23], v[228:231], v[216:219], v[20:23]
	v_mfma_f32_16x16x32_bf16 v[16:19], v[228:231], v[220:223], v[16:19]
	s_waitcnt lgkmcnt(0)
	v_mfma_f32_16x16x32_bf16 v[12:15], v[232:235], v[208:211], v[12:15]
	v_mfma_f32_16x16x32_bf16 v[8:11], v[232:235], v[212:215], v[8:11]
	v_mfma_f32_16x16x32_bf16 v[4:7], v[232:235], v[216:219], v[4:7]
	v_mfma_f32_16x16x32_bf16 v[0:3], v[232:235], v[220:223], v[0:3]
	s_setprio 0
	s_cmpk_eq_i32 s14, 0x1f80
	s_waitcnt vmcnt(0)
	s_barrier
	s_cbranch_scc0 .LBB0_691
	s_branch .Lxk_exit_691
.Lxk_691:
	s_and_b32 s26, s25, 0x4000
	s_xor_b32 s27, s26, 0x4000
	s_lshl_b32 s27, s27, 1
	s_add_i32 s27, s27, 32
	s_add_u32 s90, s52, s14
	s_addc_u32 s91, s53, s15
	s_add_i32 m0, s27, s82
	s_lshl_b32 s26, s26, 1
	global_load_lds_dwordx4 v192, s[90:91]
	s_add_i32 m0, s27, s83
	s_add_i32 s26, s26, 32
	global_load_lds_dwordx4 v193, s[90:91]
	s_add_i32 m0, s27, s84
	v_add3_u32 v139, s26, v113, v136
	global_load_lds_dwordx4 v194, s[90:91]
	s_add_i32 m0, s27, s85
	v_add3_u32 v172, s26, v114, v136
	global_load_lds_dwordx4 v195, s[90:91]
	s_add_i32 m0, s27, s86
	v_add_u32_e32 v160, v139, v137
	global_load_lds_dwordx4 v196, s[90:91]
	s_add_i32 m0, s27, s87
	v_add_u32_e32 v168, v172, v137
	global_load_lds_dwordx4 v197, s[90:91]
	s_add_i32 m0, s27, s88
	s_addk_i32 s25, 0x4000
	global_load_lds_dwordx4 v198, s[90:91]
	s_add_i32 m0, s27, s89
	s_add_u32 s14, s14, 0x80
	s_addc_u32 s15, s15, 0
	global_load_lds_dwordx4 v199, s[90:91]
	ds_read_b128 v[140:143], v160
	ds_read_b128 v[148:151], v168 offset:16384
	ds_read_b128 v[152:155], v168 offset:18432
	ds_read_b128 v[164:167], v168 offset:20480
	ds_read_b128 v[168:171], v168 offset:22528
	ds_read_b128 v[144:147], v160 offset:2048
	ds_read_b128 v[156:159], v160 offset:4096
	ds_read_b128 v[160:163], v160 offset:6144
	v_add_u32_e32 v139, v139, v138
	v_add_u32_e32 v236, v172, v138
	ds_read_b128 v[204:207], v139
	ds_read_b128 v[208:211], v236 offset:16384
	ds_read_b128 v[212:215], v236 offset:18432
	ds_read_b128 v[216:219], v236 offset:20480
	ds_read_b128 v[220:223], v236 offset:22528
	ds_read_b128 v[224:227], v139 offset:2048
	ds_read_b128 v[228:231], v139 offset:4096
	ds_read_b128 v[232:235], v139 offset:6144
	s_setprio 3
	s_waitcnt lgkmcnt(11)
	v_mfma_f32_16x16x32_bf16 v[60:63], v[140:143], v[148:151], v[60:63]
	v_mfma_f32_16x16x32_bf16 v[56:59], v[140:143], v[152:155], v[56:59]
	v_mfma_f32_16x16x32_bf16 v[52:55], v[140:143], v[164:167], v[52:55]
	v_mfma_f32_16x16x32_bf16 v[48:51], v[140:143], v[168:171], v[48:51]
	s_waitcnt lgkmcnt(10)
	v_mfma_f32_16x16x32_bf16 v[44:47], v[144:147], v[148:151], v[44:47]
	v_mfma_f32_16x16x32_bf16 v[40:43], v[144:147], v[152:155], v[40:43]
	v_mfma_f32_16x16x32_bf16 v[36:39], v[144:147], v[164:167], v[36:39]
	v_mfma_f32_16x16x32_bf16 v[32:35], v[144:147], v[168:171], v[32:35]
	s_waitcnt lgkmcnt(9)
	v_mfma_f32_16x16x32_bf16 v[28:31], v[156:159], v[148:151], v[28:31]
	v_mfma_f32_16x16x32_bf16 v[24:27], v[156:159], v[152:155], v[24:27]
	v_mfma_f32_16x16x32_bf16 v[20:23], v[156:159], v[164:167], v[20:23]
	v_mfma_f32_16x16x32_bf16 v[16:19], v[156:159], v[168:171], v[16:19]
	s_waitcnt lgkmcnt(8)
	v_mfma_f32_16x16x32_bf16 v[12:15], v[160:163], v[148:151], v[12:15]
	v_mfma_f32_16x16x32_bf16 v[8:11], v[160:163], v[152:155], v[8:11]
	v_mfma_f32_16x16x32_bf16 v[4:7], v[160:163], v[164:167], v[4:7]
	v_mfma_f32_16x16x32_bf16 v[0:3], v[160:163], v[168:171], v[0:3]
	s_waitcnt lgkmcnt(3)
	v_mfma_f32_16x16x32_bf16 v[60:63], v[204:207], v[208:211], v[60:63]
	v_mfma_f32_16x16x32_bf16 v[56:59], v[204:207], v[212:215], v[56:59]
	v_mfma_f32_16x16x32_bf16 v[52:55], v[204:207], v[216:219], v[52:55]
	v_mfma_f32_16x16x32_bf16 v[48:51], v[204:207], v[220:223], v[48:51]
	s_waitcnt lgkmcnt(2)
	v_mfma_f32_16x16x32_bf16 v[44:47], v[224:227], v[208:211], v[44:47]
	v_mfma_f32_16x16x32_bf16 v[40:43], v[224:227], v[212:215], v[40:43]
	v_mfma_f32_16x16x32_bf16 v[36:39], v[224:227], v[216:219], v[36:39]
	v_mfma_f32_16x16x32_bf16 v[32:35], v[224:227], v[220:223], v[32:35]
	s_waitcnt lgkmcnt(1)
	v_mfma_f32_16x16x32_bf16 v[28:31], v[228:231], v[208:211], v[28:31]
	v_mfma_f32_16x16x32_bf16 v[24:27], v[228:231], v[212:215], v[24:27]
	v_mfma_f32_16x16x32_bf16 v[20:23], v[228:231], v[216:219], v[20:23]
	v_mfma_f32_16x16x32_bf16 v[16:19], v[228:231], v[220:223], v[16:19]
	s_waitcnt lgkmcnt(0)
	v_mfma_f32_16x16x32_bf16 v[12:15], v[232:235], v[208:211], v[12:15]
	v_mfma_f32_16x16x32_bf16 v[8:11], v[232:235], v[212:215], v[8:11]
	v_mfma_f32_16x16x32_bf16 v[4:7], v[232:235], v[216:219], v[4:7]
	v_mfma_f32_16x16x32_bf16 v[0:3], v[232:235], v[220:223], v[0:3]
	s_setprio 2
	s_cmpk_eq_i32 s14, 0x1f80
	s_waitcnt vmcnt(0)
	s_barrier
	s_cbranch_scc0 .Lxk_691
.Lxk_exit_691:
	ds_read_b128 v[88:91], v117 offset:55296
	ds_read_b128 v[92:95], v117 offset:53248
	ds_read_b128 v[96:99], v118 offset:38912
	ds_read_b128 v[100:103], v118 offset:36864
	ds_read_b128 v[140:143], v117 offset:51200
	ds_read_b128 v[144:147], v117 offset:49152
	ds_read_b128 v[148:151], v118 offset:34816
	ds_read_b128 v[152:155], v118 offset:32768
	s_setprio 1
	s_waitcnt lgkmcnt(5)
	v_mfma_f32_16x16x32_bf16 v[4:7], v[96:99], v[92:95], v[4:7]
	v_mfma_f32_16x16x32_bf16 v[0:3], v[96:99], v[88:91], v[0:3]
	s_waitcnt lgkmcnt(0)
	v_mfma_f32_16x16x32_bf16 v[60:63], v[152:155], v[144:147], v[60:63]
	v_mfma_f32_16x16x32_bf16 v[56:59], v[152:155], v[140:143], v[56:59]
	v_mfma_f32_16x16x32_bf16 v[52:55], v[152:155], v[92:95], v[52:55]
	v_mfma_f32_16x16x32_bf16 v[48:51], v[152:155], v[88:91], v[48:51]
	v_mfma_f32_16x16x32_bf16 v[44:47], v[148:151], v[144:147], v[44:47]
	v_mfma_f32_16x16x32_bf16 v[40:43], v[148:151], v[140:143], v[40:43]
	v_mfma_f32_16x16x32_bf16 v[36:39], v[148:151], v[92:95], v[36:39]
	v_mfma_f32_16x16x32_bf16 v[32:35], v[148:151], v[88:91], v[32:35]
	v_mfma_f32_16x16x32_bf16 v[28:31], v[100:103], v[144:147], v[28:31]
	v_mfma_f32_16x16x32_bf16 v[24:27], v[100:103], v[140:143], v[24:27]
	v_mfma_f32_16x16x32_bf16 v[20:23], v[100:103], v[92:95], v[20:23]
	v_mfma_f32_16x16x32_bf16 v[16:19], v[100:103], v[88:91], v[16:19]
	v_mfma_f32_16x16x32_bf16 v[12:15], v[96:99], v[144:147], v[12:15]
	v_mfma_f32_16x16x32_bf16 v[8:11], v[96:99], v[140:143], v[8:11]
	s_setprio 0
	ds_read_b128 v[88:91], v119 offset:32768
	ds_read_b128 v[92:95], v119 offset:34816
	ds_read_b128 v[96:99], v120 offset:49152
	ds_read_b128 v[100:103], v120 offset:51200
	ds_read_b128 v[140:143], v119 offset:36864
	ds_read_b128 v[144:147], v119 offset:38912
	ds_read_b128 v[148:151], v120 offset:53248
	ds_read_b128 v[152:155], v120 offset:55296
	s_setprio 1
	s_waitcnt lgkmcnt(1)
	v_mfma_f32_16x16x32_bf16 v[4:7], v[144:147], v[148:151], v[4:7]
	s_waitcnt lgkmcnt(0)
	v_mfma_f32_16x16x32_bf16 v[0:3], v[144:147], v[152:155], v[0:3]
	v_mfma_f32_16x16x32_bf16 v[60:63], v[88:91], v[96:99], v[60:63]
	v_mfma_f32_16x16x32_bf16 v[56:59], v[88:91], v[100:103], v[56:59]
	v_mfma_f32_16x16x32_bf16 v[52:55], v[88:91], v[148:151], v[52:55]
	v_mfma_f32_16x16x32_bf16 v[48:51], v[88:91], v[152:155], v[48:51]
	v_mfma_f32_16x16x32_bf16 v[44:47], v[92:95], v[96:99], v[44:47]
	v_mfma_f32_16x16x32_bf16 v[40:43], v[92:95], v[100:103], v[40:43]
	v_mfma_f32_16x16x32_bf16 v[36:39], v[92:95], v[148:151], v[36:39]
	v_mfma_f32_16x16x32_bf16 v[32:35], v[92:95], v[152:155], v[32:35]
	v_mfma_f32_16x16x32_bf16 v[28:31], v[140:143], v[96:99], v[28:31]
	v_mfma_f32_16x16x32_bf16 v[24:27], v[140:143], v[100:103], v[24:27]
	v_mfma_f32_16x16x32_bf16 v[20:23], v[140:143], v[148:151], v[20:23]
	v_mfma_f32_16x16x32_bf16 v[16:19], v[140:143], v[152:155], v[16:19]
	v_mfma_f32_16x16x32_bf16 v[12:15], v[144:147], v[96:99], v[12:15]
	v_mfma_f32_16x16x32_bf16 v[8:11], v[144:147], v[100:103], v[8:11]
	s_setprio 0
	s_barrier
	ds_write2_b32 v115, v60, v56 offset1:16
	ds_write2_b32 v115, v61, v57 offset0:132 offset1:148
	v_add_u32_e32 v56, 0x400, v115
	ds_write2_b32 v56, v62, v58 offset0:8 offset1:24
	ds_write2_b32 v56, v63, v59 offset0:140 offset1:156
	ds_write2_b32 v115, v52, v48 offset0:32 offset1:48
	ds_write2_b32 v115, v53, v49 offset0:164 offset1:180
	ds_write2_b32 v56, v54, v50 offset0:40 offset1:56
	ds_write2_b32 v56, v55, v51 offset0:172 offset1:188
	v_add_u32_e32 v48, 0x2000, v115
	ds_write2_b32 v48, v44, v40 offset0:64 offset1:80
	ds_write2_b32 v48, v45, v41 offset0:196 offset1:212
	v_add_u32_e32 v40, 0x2400, v115
	ds_write2_b32 v40, v46, v42 offset0:72 offset1:88
	ds_write2_b32 v40, v47, v43 offset0:204 offset1:220
	ds_write2_b32 v48, v36, v32 offset0:96 offset1:112
	ds_write2_b32 v48, v37, v33 offset0:228 offset1:244
	ds_write2_b32 v40, v38, v34 offset0:104 offset1:120
	ds_write2_b32 v40, v39, v35 offset0:236 offset1:252
	v_add_u32_e32 v32, 0x4000, v115
	ds_write2_b32 v32, v28, v24 offset0:128 offset1:144
	v_add_u32_e32 v24, 0x4400, v115
	ds_write2_b32 v24, v29, v25 offset0:4 offset1:20
	ds_write2_b32 v24, v30, v26 offset0:136 offset1:152
	v_add_u32_e32 v25, 0x4800, v115
	ds_write2_b32 v25, v31, v27 offset0:12 offset1:28
	ds_write2_b32 v32, v20, v16 offset0:160 offset1:176
	ds_write2_b32 v24, v21, v17 offset0:36 offset1:52
	ds_write2_b32 v24, v22, v18 offset0:168 offset1:184
	ds_write2_b32 v25, v23, v19 offset0:44 offset1:60
	v_add_u32_e32 v16, 0x6000, v115
	ds_write2_b32 v16, v12, v8 offset0:192 offset1:208
	v_add_u32_e32 v8, 0x6400, v115
	ds_write2_b32 v8, v13, v9 offset0:68 offset1:84
	ds_write2_b32 v8, v14, v10 offset0:200 offset1:216
	v_add_u32_e32 v9, 0x6800, v115
	ds_write2_b32 v9, v15, v11 offset0:76 offset1:92
	ds_write2_b32 v16, v4, v0 offset0:224 offset1:240
	ds_write2_b32 v8, v5, v1 offset0:100 offset1:116
	ds_write2_b32 v8, v6, v2 offset0:232 offset1:248
	ds_write2_b32 v9, v7, v3 offset0:108 offset1:124
	v_or_b32_e32 v0, s23, v116
	v_ashrrev_i32_e32 v1, 31, v0
	v_lshlrev_b64 v[2:3], 2, v[0:1]
	v_lshl_add_u64 v[0:1], s[12:13], 0, v[2:3]
	v_lshl_add_u64 v[2:3], s[10:11], 0, v[2:3]
	v_add_u32_e32 v4, s24, v129
	s_mov_b32 s14, 0
	s_waitcnt lgkmcnt(0)
	s_barrier

.LBB0_701:
	s_and_b32 s14, s18, 0x380
	v_add_lshl_u32 v72, v141, s14, 13
	v_lshl_add_u64 v[98:99], v[86:87], 0, v[72:73]
	v_add_lshl_u32 v72, v143, s14, 13
	v_lshl_add_u64 v[100:101], v[90:91], 0, v[72:73]
	v_add_lshl_u32 v72, v145, s14, 13
	s_lshl_b32 s24, s23, 7
	v_lshl_add_u64 v[102:103], v[86:87], 0, v[72:73]
	v_add_lshl_u32 v72, v147, s14, 13
	s_ashr_i32 s14, s23, 3
	s_and_b32 s24, s24, 0x380
	v_add_u32_e32 v2, 0x4000, v135
	v_lshl_add_u64 v[104:105], v[94:95], 0, v[72:73]
	s_add_i32 s15, s14, s17
	v_add_lshl_u32 v72, s24, v134, 13
	v_readfirstlane_b32 s25, v2
	s_lshl_b32 s15, s15, 7
	v_lshl_add_u64 v[0:1], v[74:75], 0, v[72:73]
	s_mov_b32 m0, s25
	v_readfirstlane_b32 s25, v135
	global_load_lds_dwordx4 v[0:1], off
	v_add_u32_e32 v0, s15, v134
	v_ashrrev_i32_e32 v1, 31, v0
	v_lshlrev_b64 v[0:1], 13, v[0:1]
	v_lshl_add_u64 v[0:1], v[80:81], 0, v[0:1]
	s_mov_b32 m0, s25
	v_add_lshl_u32 v72, s24, v126, 13
	v_readfirstlane_b32 s25, v151
	global_load_lds_dwordx4 v[0:1], off
	v_lshl_add_u64 v[0:1], v[76:77], 0, v[72:73]
	s_mov_b32 m0, s25
	v_add_u32_e32 v2, 0x400, v135
	global_load_lds_dwordx4 v[0:1], off
	v_add_u32_e32 v0, s15, v126
	v_ashrrev_i32_e32 v1, 31, v0
	v_lshlrev_b64 v[0:1], 13, v[0:1]
	v_readfirstlane_b32 s25, v2
	v_lshl_add_u64 v[0:1], v[82:83], 0, v[0:1]
	s_mov_b32 m0, s25
	v_add_lshl_u32 v72, s24, v127, 13
	v_readfirstlane_b32 s25, v152
	global_load_lds_dwordx4 v[0:1], off
	v_lshl_add_u64 v[0:1], v[74:75], 0, v[72:73]
	s_mov_b32 m0, s25
	v_add_u32_e32 v2, 0x800, v135
	global_load_lds_dwordx4 v[0:1], off
	v_add_u32_e32 v0, s15, v127
	v_ashrrev_i32_e32 v1, 31, v0
	v_lshlrev_b64 v[0:1], 13, v[0:1]
	v_readfirstlane_b32 s25, v2
	v_lshl_add_u64 v[0:1], v[80:81], 0, v[0:1]
	s_mov_b32 m0, s25
	v_add_lshl_u32 v72, s24, v125, 13
	v_readfirstlane_b32 s25, v153
	global_load_lds_dwordx4 v[0:1], off
	v_lshl_add_u64 v[0:1], v[78:79], 0, v[72:73]
	s_mov_b32 m0, s25
	v_add_u32_e32 v2, 0xc00, v135
	global_load_lds_dwordx4 v[0:1], off
	v_add_u32_e32 v0, s15, v125
	v_ashrrev_i32_e32 v1, 31, v0
	v_lshlrev_b64 v[0:1], 13, v[0:1]
	v_readfirstlane_b32 s15, v2
	v_lshl_add_u64 v[0:1], v[84:85], 0, v[0:1]
	s_mov_b32 m0, s15
	s_lshl_b32 s25, s14, 7
	global_load_lds_dwordx4 v[0:1], off
	v_add_u32_e32 v0, s25, v142
	v_ashrrev_i32_e32 v1, 31, v0
	v_lshlrev_b64 v[0:1], 13, v[0:1]
	v_lshl_add_u64 v[106:107], v[88:89], 0, v[0:1]
	v_add_u32_e32 v0, s25, v144
	v_ashrrev_i32_e32 v1, 31, v0
	v_lshlrev_b64 v[0:1], 13, v[0:1]
	v_lshl_add_u64 v[108:109], v[92:93], 0, v[0:1]
	v_add_u32_e32 v0, s25, v146
	v_ashrrev_i32_e32 v1, 31, v0
	v_lshlrev_b64 v[0:1], 13, v[0:1]
	v_lshl_add_u64 v[110:111], v[88:89], 0, v[0:1]
	v_add_u32_e32 v0, s25, v148
	v_ashrrev_i32_e32 v1, 31, v0
	v_lshlrev_b64 v[0:1], 13, v[0:1]
	v_lshl_add_u64 v[112:113], v[96:97], 0, v[0:1]
	s_mov_b64 s[14:15], 0
	s_mov_b32 s26, 0
	v_mov_b32_e32 v0, 0
	v_mov_b32_e32 v1, v73
	v_mov_b32_e32 v2, v73
	v_mov_b32_e32 v3, v73
	v_mov_b32_e32 v4, 0
	v_mov_b32_e32 v5, v73
	v_mov_b32_e32 v6, v73
	v_mov_b32_e32 v7, v73
	v_mov_b32_e32 v8, 0
	v_mov_b32_e32 v9, v73
	v_mov_b32_e32 v10, v73
	v_mov_b32_e32 v11, v73
	v_mov_b32_e32 v12, 0
	v_mov_b32_e32 v13, v73
	v_mov_b32_e32 v14, v73
	v_mov_b32_e32 v15, v73
	v_mov_b32_e32 v16, 0
	v_mov_b32_e32 v17, v73
	v_mov_b32_e32 v18, v73
	v_mov_b32_e32 v19, v73
	v_mov_b32_e32 v20, 0
	v_mov_b32_e32 v21, v73
	v_mov_b32_e32 v22, v73
	v_mov_b32_e32 v23, v73
	v_mov_b32_e32 v24, 0
	v_mov_b32_e32 v25, v73
	v_mov_b32_e32 v26, v73
	v_mov_b32_e32 v27, v73
	v_mov_b32_e32 v28, 0
	v_mov_b32_e32 v29, v73
	v_mov_b32_e32 v30, v73
	v_mov_b32_e32 v31, v73
	v_mov_b32_e32 v32, 0
	v_mov_b32_e32 v33, v73
	v_mov_b32_e32 v34, v73
	v_mov_b32_e32 v35, v73
	v_mov_b32_e32 v36, 0
	v_mov_b32_e32 v37, v73
	v_mov_b32_e32 v38, v73
	v_mov_b32_e32 v39, v73
	v_mov_b32_e32 v40, 0
	v_mov_b32_e32 v41, v73
	v_mov_b32_e32 v42, v73
	v_mov_b32_e32 v43, v73
	v_mov_b32_e32 v44, 0
	v_mov_b32_e32 v45, v73
	v_mov_b32_e32 v46, v73
	v_mov_b32_e32 v47, v73
	v_mov_b32_e32 v48, 0
	v_mov_b32_e32 v49, v73
	v_mov_b32_e32 v50, v73
	v_mov_b32_e32 v51, v73
	v_mov_b32_e32 v52, 0
	v_mov_b32_e32 v53, v73
	v_mov_b32_e32 v54, v73
	v_mov_b32_e32 v55, v73
	v_mov_b32_e32 v56, 0
	v_mov_b32_e32 v57, v73
	v_mov_b32_e32 v58, v73
	v_mov_b32_e32 v59, v73
	v_mov_b32_e32 v60, 0
	v_mov_b32_e32 v61, v73
	v_mov_b32_e32 v62, v73
	v_mov_b32_e32 v63, v73
	s_waitcnt vmcnt(0) lgkmcnt(0)
	s_barrier
	v_lshlrev_b32_e32 v190, 1, v132
	v_lshlrev_b32_e32 v191, 1, v133
	v_add3_u32 v190, 0, v190, v191
	v_add_u32_e32 v192, 0x4000, v190
	s_nop 0
	v_readfirstlane_b32 s82, v192
	v_lshl_add_u32 v192, v118, 1, 0
	s_nop 0
	v_readfirstlane_b32 s83, v190
	v_add3_u32 v192, v192, v191, s19
	s_nop 0
	v_readfirstlane_b32 s84, v192
	v_add_u32_e32 v192, 0x400, v190
	s_nop 0
	v_readfirstlane_b32 s85, v192
	v_lshl_add_u32 v192, v119, 1, 0
	v_add3_u32 v192, v192, v191, s19
	s_nop 0
	v_readfirstlane_b32 s86, v192
	v_add_u32_e32 v192, 0x800, v190
	s_nop 0
	v_readfirstlane_b32 s87, v192
	v_lshl_add_u32 v192, v120, 1, 0
	v_add3_u32 v191, v192, v191, s19
	s_nop 0
	v_readfirstlane_b32 s88, v191
	v_add_u32_e32 v190, 0xc00, v190
	s_nop 0
	v_readfirstlane_b32 s89, v190
	v_subrev_u32_e32 v193, s52, v98
	v_subrev_u32_e32 v194, s52, v106
	v_subrev_u32_e32 v195, s52, v100
	v_subrev_u32_e32 v196, s52, v108
	v_subrev_u32_e32 v197, s52, v102
	v_subrev_u32_e32 v198, s52, v110
	v_subrev_u32_e32 v199, s52, v104
	v_subrev_u32_e32 v200, s52, v112
	s_bitcmp1_b32 s32, 0
	s_cbranch_scc1 .Lxk_702
.LBB0_702:
	s_and_b32 s27, s26, 0x4000
	s_xor_b32 s28, s27, 0x4000
	s_lshl_b32 s28, s28, 1
	s_add_i32 s28, s28, 32
	s_add_u32 s90, s52, s14
	s_addc_u32 s91, s53, s15
	s_add_i32 m0, s28, s82
	s_lshl_b32 s27, s27, 1
	global_load_lds_dwordx4 v193, s[90:91]
	s_add_i32 m0, s28, s83
	s_add_i32 s27, s27, 32
	global_load_lds_dwordx4 v194, s[90:91]
	s_add_i32 m0, s28, s84
	v_lshlrev_b32_e32 v72, 1, v131
	global_load_lds_dwordx4 v195, s[90:91]
	s_add_i32 m0, s28, s85
	v_add3_u32 v178, s27, v129, v72
	global_load_lds_dwordx4 v196, s[90:91]
	s_add_i32 m0, s28, s86
	v_lshlrev_b32_e32 v154, 1, v121
	global_load_lds_dwordx4 v197, s[90:91]
	s_add_i32 m0, s28, s87
	v_add3_u32 v72, s27, v130, v72
	global_load_lds_dwordx4 v198, s[90:91]
	s_add_i32 m0, s28, s88
	v_add_u32_e32 v174, v178, v154
	global_load_lds_dwordx4 v199, s[90:91]
	s_add_i32 m0, s28, s89
	v_add_u32_e32 v179, v72, v154
	global_load_lds_dwordx4 v200, s[90:91]
	ds_read_b128 v[154:157], v174
	ds_read_b128 v[162:165], v179 offset:16384
	ds_read_b128 v[166:169], v179 offset:18432
	ds_read_b128 v[182:185], v179 offset:20480
	ds_read_b128 v[186:189], v179 offset:22528
	ds_read_b128 v[158:161], v174 offset:2048
	ds_read_b128 v[170:173], v174 offset:4096
	ds_read_b128 v[174:177], v174 offset:6144
	v_lshlrev_b32_e32 v236, 1, v122
	v_add_u32_e32 v237, v178, v236
	v_add_u32_e32 v72, v72, v236
	ds_read_b128 v[204:207], v237
	ds_read_b128 v[208:211], v72 offset:16384
	ds_read_b128 v[212:215], v72 offset:18432
	ds_read_b128 v[216:219], v72 offset:20480
	ds_read_b128 v[220:223], v72 offset:22528
	ds_read_b128 v[224:227], v237 offset:2048
	ds_read_b128 v[228:231], v237 offset:4096
	ds_read_b128 v[232:235], v237 offset:6144
	s_setprio 1
	s_waitcnt lgkmcnt(11)
	v_mfma_f32_16x16x32_bf16 v[60:63], v[154:157], v[162:165], v[60:63]
	v_mfma_f32_16x16x32_bf16 v[56:59], v[154:157], v[166:169], v[56:59]
	v_mfma_f32_16x16x32_bf16 v[52:55], v[154:157], v[182:185], v[52:55]
	v_mfma_f32_16x16x32_bf16 v[48:51], v[154:157], v[186:189], v[48:51]
	s_waitcnt lgkmcnt(10)
	v_mfma_f32_16x16x32_bf16 v[44:47], v[158:161], v[162:165], v[44:47]
	v_mfma_f32_16x16x32_bf16 v[40:43], v[158:161], v[166:169], v[40:43]
	v_mfma_f32_16x16x32_bf16 v[36:39], v[158:161], v[182:185], v[36:39]
	v_mfma_f32_16x16x32_bf16 v[32:35], v[158:161], v[186:189], v[32:35]
	s_waitcnt lgkmcnt(9)
	v_mfma_f32_16x16x32_bf16 v[28:31], v[170:173], v[162:165], v[28:31]
	v_mfma_f32_16x16x32_bf16 v[24:27], v[170:173], v[166:169], v[24:27]
	v_mfma_f32_16x16x32_bf16 v[20:23], v[170:173], v[182:185], v[20:23]
	v_mfma_f32_16x16x32_bf16 v[16:19], v[170:173], v[186:189], v[16:19]
	s_waitcnt lgkmcnt(8)
	v_mfma_f32_16x16x32_bf16 v[12:15], v[174:177], v[162:165], v[12:15]
	v_mfma_f32_16x16x32_bf16 v[8:11], v[174:177], v[166:169], v[8:11]
	v_mfma_f32_16x16x32_bf16 v[4:7], v[174:177], v[182:185], v[4:7]
	v_mfma_f32_16x16x32_bf16 v[0:3], v[174:177], v[186:189], v[0:3]
	s_waitcnt lgkmcnt(3)
	v_mfma_f32_16x16x32_bf16 v[60:63], v[204:207], v[208:211], v[60:63]
	v_mfma_f32_16x16x32_bf16 v[56:59], v[204:207], v[212:215], v[56:59]
	v_mfma_f32_16x16x32_bf16 v[52:55], v[204:207], v[216:219], v[52:55]
	v_mfma_f32_16x16x32_bf16 v[48:51], v[204:207], v[220:223], v[48:51]
	s_waitcnt lgkmcnt(2)
	v_mfma_f32_16x16x32_bf16 v[44:47], v[224:227], v[208:211], v[44:47]
	v_mfma_f32_16x16x32_bf16 v[40:43], v[224:227], v[212:215], v[40:43]
	v_mfma_f32_16x16x32_bf16 v[36:39], v[224:227], v[216:219], v[36:39]
	v_mfma_f32_16x16x32_bf16 v[32:35], v[224:227], v[220:223], v[32:35]
	s_waitcnt lgkmcnt(1)
	v_mfma_f32_16x16x32_bf16 v[28:31], v[228:231], v[208:211], v[28:31]
	v_mfma_f32_16x16x32_bf16 v[24:27], v[228:231], v[212:215], v[24:27]
	v_mfma_f32_16x16x32_bf16 v[20:23], v[228:231], v[216:219], v[20:23]
	v_mfma_f32_16x16x32_bf16 v[16:19], v[228:231], v[220:223], v[16:19]
	s_waitcnt lgkmcnt(0)
	v_mfma_f32_16x16x32_bf16 v[12:15], v[232:235], v[208:211], v[12:15]
	v_mfma_f32_16x16x32_bf16 v[8:11], v[232:235], v[212:215], v[8:11]
	v_mfma_f32_16x16x32_bf16 v[4:7], v[232:235], v[216:219], v[4:7]
	v_mfma_f32_16x16x32_bf16 v[0:3], v[232:235], v[220:223], v[0:3]
	s_setprio 0
	s_add_u32 s14, s14, 0x80
	s_addc_u32 s15, s15, 0
	s_addk_i32 s26, 0x4000
	s_cmpk_eq_i32 s14, 0x1f80
	s_waitcnt vmcnt(0)
	s_barrier
	s_cbranch_scc0 .LBB0_702
	s_branch .Lxk_exit_702
.Lxk_702:
	s_and_b32 s27, s26, 0x4000
	s_xor_b32 s28, s27, 0x4000
	s_lshl_b32 s28, s28, 1
	s_add_i32 s28, s28, 32
	s_add_u32 s90, s52, s14
	s_addc_u32 s91, s53, s15
	s_add_i32 m0, s28, s82
	s_lshl_b32 s27, s27, 1
	global_load_lds_dwordx4 v193, s[90:91]
	s_add_i32 m0, s28, s83
	s_add_i32 s27, s27, 32
	global_load_lds_dwordx4 v194, s[90:91]
	s_add_i32 m0, s28, s84
	v_lshlrev_b32_e32 v72, 1, v131
	global_load_lds_dwordx4 v195, s[90:91]
	s_add_i32 m0, s28, s85
	v_add3_u32 v178, s27, v129, v72
	global_load_lds_dwordx4 v196, s[90:91]
	s_add_i32 m0, s28, s86
	v_lshlrev_b32_e32 v154, 1, v121
	global_load_lds_dwordx4 v197, s[90:91]
	s_add_i32 m0, s28, s87
	v_add3_u32 v72, s27, v130, v72
	global_load_lds_dwordx4 v198, s[90:91]
	s_add_i32 m0, s28, s88
	v_add_u32_e32 v174, v178, v154
	global_load_lds_dwordx4 v199, s[90:91]
	s_add_i32 m0, s28, s89
	v_add_u32_e32 v179, v72, v154
	global_load_lds_dwordx4 v200, s[90:91]
	ds_read_b128 v[154:157], v174
	ds_read_b128 v[162:165], v179 offset:16384
	ds_read_b128 v[166:169], v179 offset:18432
	ds_read_b128 v[182:185], v179 offset:20480
	ds_read_b128 v[186:189], v179 offset:22528
	ds_read_b128 v[158:161], v174 offset:2048
	ds_read_b128 v[170:173], v174 offset:4096
	ds_read_b128 v[174:177], v174 offset:6144
	v_lshlrev_b32_e32 v236, 1, v122
	v_add_u32_e32 v237, v178, v236
	v_add_u32_e32 v72, v72, v236
	ds_read_b128 v[204:207], v237
	ds_read_b128 v[208:211], v72 offset:16384
	ds_read_b128 v[212:215], v72 offset:18432
	ds_read_b128 v[216:219], v72 offset:20480
	ds_read_b128 v[220:223], v72 offset:22528
	ds_read_b128 v[224:227], v237 offset:2048
	ds_read_b128 v[228:231], v237 offset:4096
	ds_read_b128 v[232:235], v237 offset:6144
	s_setprio 3
	s_waitcnt lgkmcnt(11)
	v_mfma_f32_16x16x32_bf16 v[60:63], v[154:157], v[162:165], v[60:63]
	v_mfma_f32_16x16x32_bf16 v[56:59], v[154:157], v[166:169], v[56:59]
	v_mfma_f32_16x16x32_bf16 v[52:55], v[154:157], v[182:185], v[52:55]
	v_mfma_f32_16x16x32_bf16 v[48:51], v[154:157], v[186:189], v[48:51]
	s_waitcnt lgkmcnt(10)
	v_mfma_f32_16x16x32_bf16 v[44:47], v[158:161], v[162:165], v[44:47]
	v_mfma_f32_16x16x32_bf16 v[40:43], v[158:161], v[166:169], v[40:43]
	v_mfma_f32_16x16x32_bf16 v[36:39], v[158:161], v[182:185], v[36:39]
	v_mfma_f32_16x16x32_bf16 v[32:35], v[158:161], v[186:189], v[32:35]
	s_waitcnt lgkmcnt(9)
	v_mfma_f32_16x16x32_bf16 v[28:31], v[170:173], v[162:165], v[28:31]
	v_mfma_f32_16x16x32_bf16 v[24:27], v[170:173], v[166:169], v[24:27]
	v_mfma_f32_16x16x32_bf16 v[20:23], v[170:173], v[182:185], v[20:23]
	v_mfma_f32_16x16x32_bf16 v[16:19], v[170:173], v[186:189], v[16:19]
	s_waitcnt lgkmcnt(8)
	v_mfma_f32_16x16x32_bf16 v[12:15], v[174:177], v[162:165], v[12:15]
	v_mfma_f32_16x16x32_bf16 v[8:11], v[174:177], v[166:169], v[8:11]
	v_mfma_f32_16x16x32_bf16 v[4:7], v[174:177], v[182:185], v[4:7]
	v_mfma_f32_16x16x32_bf16 v[0:3], v[174:177], v[186:189], v[0:3]
	s_waitcnt lgkmcnt(3)
	v_mfma_f32_16x16x32_bf16 v[60:63], v[204:207], v[208:211], v[60:63]
	v_mfma_f32_16x16x32_bf16 v[56:59], v[204:207], v[212:215], v[56:59]
	v_mfma_f32_16x16x32_bf16 v[52:55], v[204:207], v[216:219], v[52:55]
	v_mfma_f32_16x16x32_bf16 v[48:51], v[204:207], v[220:223], v[48:51]
	s_waitcnt lgkmcnt(2)
	v_mfma_f32_16x16x32_bf16 v[44:47], v[224:227], v[208:211], v[44:47]
	v_mfma_f32_16x16x32_bf16 v[40:43], v[224:227], v[212:215], v[40:43]
	v_mfma_f32_16x16x32_bf16 v[36:39], v[224:227], v[216:219], v[36:39]
	v_mfma_f32_16x16x32_bf16 v[32:35], v[224:227], v[220:223], v[32:35]
	s_waitcnt lgkmcnt(1)
	v_mfma_f32_16x16x32_bf16 v[28:31], v[228:231], v[208:211], v[28:31]
	v_mfma_f32_16x16x32_bf16 v[24:27], v[228:231], v[212:215], v[24:27]
	v_mfma_f32_16x16x32_bf16 v[20:23], v[228:231], v[216:219], v[20:23]
	v_mfma_f32_16x16x32_bf16 v[16:19], v[228:231], v[220:223], v[16:19]
	s_waitcnt lgkmcnt(0)
	v_mfma_f32_16x16x32_bf16 v[12:15], v[232:235], v[208:211], v[12:15]
	v_mfma_f32_16x16x32_bf16 v[8:11], v[232:235], v[212:215], v[8:11]
	v_mfma_f32_16x16x32_bf16 v[4:7], v[232:235], v[216:219], v[4:7]
	v_mfma_f32_16x16x32_bf16 v[0:3], v[232:235], v[220:223], v[0:3]
	s_setprio 2
	s_add_u32 s14, s14, 0x80
	s_addc_u32 s15, s15, 0
	s_addk_i32 s26, 0x4000
	s_cmpk_eq_i32 s14, 0x1f80
	s_waitcnt vmcnt(0)
	s_barrier
	s_cbranch_scc0 .Lxk_702
.Lxk_exit_702:
	ds_read_b128 v[98:101], v71 offset:32768
	ds_read_b128 v[102:105], v71 offset:34816
	ds_read_b128 v[106:109], v138 offset:49152
	ds_read_b128 v[110:113], v138 offset:51200
	ds_read_b128 v[154:157], v71 offset:36864
	ds_read_b128 v[158:161], v71 offset:38912
	ds_read_b128 v[162:165], v138 offset:53248
	ds_read_b128 v[166:169], v138 offset:55296
	s_setprio 1
	s_waitcnt lgkmcnt(1)
	v_mfma_f32_16x16x32_bf16 v[4:7], v[158:161], v[162:165], v[4:7]
	s_waitcnt lgkmcnt(0)
	v_mfma_f32_16x16x32_bf16 v[0:3], v[158:161], v[166:169], v[0:3]
	v_mfma_f32_16x16x32_bf16 v[60:63], v[98:101], v[106:109], v[60:63]
	v_mfma_f32_16x16x32_bf16 v[56:59], v[98:101], v[110:113], v[56:59]
	v_mfma_f32_16x16x32_bf16 v[52:55], v[98:101], v[162:165], v[52:55]
	v_mfma_f32_16x16x32_bf16 v[48:51], v[98:101], v[166:169], v[48:51]
	v_mfma_f32_16x16x32_bf16 v[44:47], v[102:105], v[106:109], v[44:47]
	v_mfma_f32_16x16x32_bf16 v[40:43], v[102:105], v[110:113], v[40:43]
	v_mfma_f32_16x16x32_bf16 v[36:39], v[102:105], v[162:165], v[36:39]
	v_mfma_f32_16x16x32_bf16 v[32:35], v[102:105], v[166:169], v[32:35]
	v_mfma_f32_16x16x32_bf16 v[28:31], v[154:157], v[106:109], v[28:31]
	v_mfma_f32_16x16x32_bf16 v[24:27], v[154:157], v[110:113], v[24:27]
	v_mfma_f32_16x16x32_bf16 v[20:23], v[154:157], v[162:165], v[20:23]
	v_mfma_f32_16x16x32_bf16 v[16:19], v[154:157], v[166:169], v[16:19]
	v_mfma_f32_16x16x32_bf16 v[12:15], v[158:161], v[106:109], v[12:15]
	v_mfma_f32_16x16x32_bf16 v[8:11], v[158:161], v[110:113], v[8:11]
	s_setprio 0
	ds_read_b128 v[98:101], v139 offset:32768
	ds_read_b128 v[102:105], v139 offset:34816
	ds_read_b128 v[106:109], v140 offset:49152
	ds_read_b128 v[110:113], v140 offset:51200
	ds_read_b128 v[154:157], v139 offset:36864
	ds_read_b128 v[158:161], v139 offset:38912
	ds_read_b128 v[162:165], v140 offset:53248
	ds_read_b128 v[166:169], v140 offset:55296
	s_setprio 1
	s_waitcnt lgkmcnt(1)
	v_mfma_f32_16x16x32_bf16 v[4:7], v[158:161], v[162:165], v[4:7]
	s_waitcnt lgkmcnt(0)
	v_mfma_f32_16x16x32_bf16 v[0:3], v[158:161], v[166:169], v[0:3]
	v_mfma_f32_16x16x32_bf16 v[60:63], v[98:101], v[106:109], v[60:63]
	v_mfma_f32_16x16x32_bf16 v[56:59], v[98:101], v[110:113], v[56:59]
	v_mfma_f32_16x16x32_bf16 v[52:55], v[98:101], v[162:165], v[52:55]
	v_mfma_f32_16x16x32_bf16 v[48:51], v[98:101], v[166:169], v[48:51]
	v_mfma_f32_16x16x32_bf16 v[44:47], v[102:105], v[106:109], v[44:47]
	v_mfma_f32_16x16x32_bf16 v[40:43], v[102:105], v[110:113], v[40:43]
	v_mfma_f32_16x16x32_bf16 v[36:39], v[102:105], v[162:165], v[36:39]
	v_mfma_f32_16x16x32_bf16 v[32:35], v[102:105], v[166:169], v[32:35]
	v_mfma_f32_16x16x32_bf16 v[28:31], v[154:157], v[106:109], v[28:31]
	v_mfma_f32_16x16x32_bf16 v[24:27], v[154:157], v[110:113], v[24:27]
	v_mfma_f32_16x16x32_bf16 v[20:23], v[154:157], v[162:165], v[20:23]
	v_mfma_f32_16x16x32_bf16 v[16:19], v[154:157], v[166:169], v[16:19]
	v_mfma_f32_16x16x32_bf16 v[12:15], v[158:161], v[106:109], v[12:15]
	v_mfma_f32_16x16x32_bf16 v[8:11], v[158:161], v[110:113], v[8:11]
	s_setprio 0
	s_barrier
	ds_write2_b32 v136, v60, v56 offset1:16
	ds_write2_b32 v136, v61, v57 offset0:132 offset1:148
	v_add_u32_e32 v56, 0x400, v136
	ds_write2_b32 v56, v62, v58 offset0:8 offset1:24
	ds_write2_b32 v56, v63, v59 offset0:140 offset1:156
	ds_write2_b32 v136, v52, v48 offset0:32 offset1:48
	ds_write2_b32 v136, v53, v49 offset0:164 offset1:180
	ds_write2_b32 v56, v54, v50 offset0:40 offset1:56
	ds_write2_b32 v56, v55, v51 offset0:172 offset1:188
	v_add_u32_e32 v48, 0x2000, v136
	ds_write2_b32 v48, v44, v40 offset0:64 offset1:80
	ds_write2_b32 v48, v45, v41 offset0:196 offset1:212
	v_add_u32_e32 v40, 0x2400, v136
	ds_write2_b32 v40, v46, v42 offset0:72 offset1:88
	ds_write2_b32 v40, v47, v43 offset0:204 offset1:220
	ds_write2_b32 v48, v36, v32 offset0:96 offset1:112
	ds_write2_b32 v48, v37, v33 offset0:228 offset1:244
	ds_write2_b32 v40, v38, v34 offset0:104 offset1:120
	ds_write2_b32 v40, v39, v35 offset0:236 offset1:252
	v_add_u32_e32 v32, 0x4000, v136
	ds_write2_b32 v32, v28, v24 offset0:128 offset1:144
	v_add_u32_e32 v24, 0x4400, v136
	ds_write2_b32 v24, v29, v25 offset0:4 offset1:20
	ds_write2_b32 v24, v30, v26 offset0:136 offset1:152
	v_add_u32_e32 v25, 0x4800, v136
	ds_write2_b32 v25, v31, v27 offset0:12 offset1:28
	ds_write2_b32 v32, v20, v16 offset0:160 offset1:176
	ds_write2_b32 v24, v21, v17 offset0:36 offset1:52
	ds_write2_b32 v24, v22, v18 offset0:168 offset1:184
	ds_write2_b32 v25, v23, v19 offset0:44 offset1:60
	v_add_u32_e32 v16, 0x6000, v136
	ds_write2_b32 v16, v12, v8 offset0:192 offset1:208
	v_add_u32_e32 v8, 0x6400, v136
	ds_write2_b32 v8, v13, v9 offset0:68 offset1:84
	ds_write2_b32 v8, v14, v10 offset0:200 offset1:216
	v_add_u32_e32 v9, 0x6800, v136
	ds_write2_b32 v9, v15, v11 offset0:76 offset1:92
	ds_write2_b32 v16, v4, v0 offset0:224 offset1:240
	ds_write2_b32 v8, v5, v1 offset0:100 offset1:116
	ds_write2_b32 v8, v6, v2 offset0:232 offset1:248
	ds_write2_b32 v9, v7, v3 offset0:108 offset1:124
	v_or_b32_e32 v0, s24, v137
	v_lshlrev_b32_e32 v72, 2, v0
	v_lshl_add_u64 v[0:1], s[12:13], 0, v[72:73]
	v_lshl_add_u64 v[2:3], s[10:11], 0, v[72:73]
	v_add_u32_e32 v4, s25, v149
	s_mov_b32 s14, 0
	s_waitcnt lgkmcnt(0)
	s_barrier

.LBB0_707:
	s_ashr_i32 s15, s16, 2
	s_add_i32 s10, s15, 0x80
	s_and_b32 s14, s16, 3
	s_ashr_i32 s18, s10, 3
	s_add_i32 s19, s18, s17
	s_lshl_b32 s10, s14, 11
	s_add_u32 s6, s6, s10
	s_addc_u32 s7, s7, 0
	s_add_u32 s16, s8, s10
	s_addc_u32 s17, s9, 0
	s_lshl_b32 s9, s15, 7
	s_lshl_b32 s8, s19, 7
	s_and_b32 s9, s9, 0x380
	v_lshlrev_b32_e32 v83, 1, v2
	v_lshlrev_b32_e32 v84, 1, v3
	v_add_lshl_u32 v0, s9, v134, 13
	v_mov_b32_e32 v1, 0
	v_add3_u32 v20, 32, v83, v84
	v_add_u32_e32 v2, s8, v134
	v_lshl_add_u64 v[4:5], s[16:17], 0, v[0:1]
	v_add_u32_e32 v0, 0x4000, v20
	v_ashrrev_i32_e32 v3, 31, v2
	v_mov_b32_e32 v71, v1
	v_readfirstlane_b32 s19, v0
	v_lshlrev_b64 v[2:3], 13, v[2:3]
	v_lshl_add_u64 v[4:5], v[4:5], 0, v[70:71]
	s_mov_b32 m0, s19
	v_lshl_add_u64 v[2:3], s[6:7], 0, v[2:3]
	v_readfirstlane_b32 s19, v20
	global_load_lds_dwordx4 v[4:5], off
	v_lshl_add_u64 v[2:3], v[2:3], 0, v[70:71]
	s_mov_b32 m0, s19
	v_add_lshl_u32 v0, v126, s9, 12
	s_movk_i32 s15, 0x4000
	global_load_lds_dwordx4 v[2:3], off
	v_lshlrev_b64 v[2:3], 1, v[0:1]
	v_lshl_add_u32 v0, v118, 1, 32
	v_add3_u32 v0, v0, v84, s15
	v_lshl_add_u64 v[4:5], s[16:17], 0, v[2:3]
	v_lshlrev_b64 v[6:7], 1, v[66:67]
	v_readfirstlane_b32 s19, v0
	v_lshl_add_u64 v[4:5], v[4:5], 0, v[6:7]
	s_mov_b32 m0, s19
	v_add_u32_e32 v0, 0x400, v20
	global_load_lds_dwordx4 v[4:5], off
	v_add_u32_e32 v4, s8, v126
	v_ashrrev_i32_e32 v5, 31, v4
	v_lshlrev_b64 v[4:5], 13, v[4:5]
	v_lshl_add_u64 v[8:9], s[6:7], 0, v[4:5]
	v_readfirstlane_b32 s19, v0
	v_lshl_add_u64 v[8:9], v[8:9], 0, v[6:7]
	s_mov_b32 m0, s19
	v_add_lshl_u32 v0, v127, s9, 12
	global_load_lds_dwordx4 v[8:9], off
	v_lshlrev_b64 v[8:9], 1, v[0:1]
	v_lshl_add_u32 v0, v119, 1, 32
	v_add3_u32 v0, v0, v84, s15
	v_lshl_add_u64 v[10:11], s[16:17], 0, v[8:9]
	v_readfirstlane_b32 s19, v0
	v_lshl_add_u64 v[10:11], v[10:11], 0, v[70:71]
	s_mov_b32 m0, s19
	v_add_u32_e32 v0, 0x800, v20
	global_load_lds_dwordx4 v[10:11], off
	v_add_u32_e32 v10, s8, v127
	v_ashrrev_i32_e32 v11, 31, v10
	v_lshlrev_b64 v[10:11], 13, v[10:11]
	v_lshl_add_u64 v[12:13], s[6:7], 0, v[10:11]
	v_readfirstlane_b32 s19, v0
	v_lshl_add_u64 v[12:13], v[12:13], 0, v[70:71]
	s_mov_b32 m0, s19
	v_add_lshl_u32 v0, v125, s9, 12
	global_load_lds_dwordx4 v[12:13], off
	v_lshlrev_b64 v[12:13], 1, v[0:1]
	v_lshl_add_u32 v0, v120, 1, 32
	v_add3_u32 v0, v0, v84, s15
	v_lshl_add_u64 v[14:15], s[16:17], 0, v[12:13]
	v_lshlrev_b64 v[16:17], 1, v[68:69]
	v_readfirstlane_b32 s16, v0
	v_lshl_add_u64 v[14:15], v[14:15], 0, v[16:17]
	s_mov_b32 m0, s16
	v_add_u32_e32 v0, 0xc00, v20
	global_load_lds_dwordx4 v[14:15], off
	v_add_u32_e32 v14, s8, v125
	v_ashrrev_i32_e32 v15, 31, v14
	v_lshlrev_b64 v[14:15], 13, v[14:15]
	v_lshl_add_u64 v[18:19], s[6:7], 0, v[14:15]
	v_readfirstlane_b32 s6, v0
	v_lshl_add_u64 v[18:19], v[18:19], 0, v[16:17]
	s_mov_b32 m0, s6
	s_mov_b32 s11, 0
	global_load_lds_dwordx4 v[18:19], off
	v_or_b32_e32 v0, s9, v124
	v_lshl_add_u64 v[6:7], s[10:11], 0, v[6:7]
	v_add_lshl_u32 v0, v0, v123, 13
	v_lshl_add_u64 v[18:19], s[10:11], 0, v[64:65]
	v_lshl_add_u64 v[2:3], v[6:7], 0, v[2:3]
	v_lshl_add_u64 v[20:21], v[18:19], 0, v[0:1]
	s_mov_b64 s[6:7], 0x800080
	v_lshl_add_u64 v[2:3], s[4:5], 0, v[2:3]
	v_lshl_add_u64 v[20:21], s[4:5], 0, v[20:21]
	s_lshl_b32 s16, s18, 7
	v_lshl_add_u64 v[68:69], v[2:3], 0, s[6:7]
	v_lshl_add_u64 v[2:3], v[6:7], 0, v[4:5]
	v_lshl_add_u64 v[64:65], v[20:21], 0, s[6:7]
	v_add3_u32 v20, v128, s16, v123
	s_mov_b64 s[16:17], 0x8600080
	v_lshl_add_u64 v[2:3], s[4:5], 0, v[2:3]
	v_lshl_add_u64 v[70:71], v[2:3], 0, s[16:17]
	v_lshl_add_u64 v[2:3], v[18:19], 0, v[8:9]
	v_lshl_add_u64 v[2:3], s[4:5], 0, v[2:3]
	v_lshl_add_u64 v[72:73], v[2:3], 0, s[6:7]
	v_lshl_add_u64 v[2:3], v[18:19], 0, v[10:11]
	v_ashrrev_i32_e32 v21, 31, v20
	v_lshl_add_u64 v[2:3], s[4:5], 0, v[2:3]
	v_lshlrev_b64 v[20:21], 13, v[20:21]
	v_lshl_add_u64 v[74:75], v[2:3], 0, s[16:17]
	v_lshl_add_u64 v[2:3], s[10:11], 0, v[16:17]
	v_lshl_add_u64 v[20:21], v[18:19], 0, v[20:21]
	v_lshl_add_u64 v[4:5], v[2:3], 0, v[12:13]
	v_lshl_add_u64 v[2:3], v[2:3], 0, v[14:15]
	v_lshl_add_u64 v[20:21], s[4:5], 0, v[20:21]
	v_lshl_add_u64 v[4:5], s[4:5], 0, v[4:5]
	v_lshl_add_u64 v[2:3], s[4:5], 0, v[2:3]
	v_lshl_add_u64 v[66:67], v[20:21], 0, s[16:17]
	v_lshl_add_u64 v[76:77], v[4:5], 0, s[6:7]
	v_lshl_add_u64 v[78:79], v[2:3], 0, s[16:17]
	s_mov_b64 s[4:5], 0
	v_mov_b32_e32 v0, v1
	v_mov_b32_e32 v2, v1
	v_mov_b32_e32 v3, v1
	v_mov_b32_e32 v4, v1
	v_mov_b32_e32 v5, v1
	v_mov_b32_e32 v6, v1
	v_mov_b32_e32 v7, v1
	v_mov_b32_e32 v8, v1
	v_mov_b32_e32 v9, v1
	v_mov_b32_e32 v10, v1
	v_mov_b32_e32 v11, v1
	v_mov_b32_e32 v12, v1
	v_mov_b32_e32 v13, v1
	v_mov_b32_e32 v14, v1
	v_mov_b32_e32 v15, v1
	v_mov_b32_e32 v16, v1
	v_mov_b32_e32 v17, v1
	v_mov_b32_e32 v18, v1
	v_mov_b32_e32 v19, v1
	v_mov_b32_e32 v20, v1
	v_mov_b32_e32 v21, v1
	v_mov_b32_e32 v22, v1
	v_mov_b32_e32 v23, v1
	v_mov_b32_e32 v24, v1
	v_mov_b32_e32 v25, v1
	v_mov_b32_e32 v26, v1
	v_mov_b32_e32 v27, v1
	v_mov_b32_e32 v28, v1
	v_mov_b32_e32 v29, v1
	v_mov_b32_e32 v30, v1
	v_mov_b32_e32 v31, v1
	v_mov_b32_e32 v32, v1
	v_mov_b32_e32 v33, v1
	v_mov_b32_e32 v34, v1
	v_mov_b32_e32 v35, v1
	v_mov_b32_e32 v36, v1
	v_mov_b32_e32 v37, v1
	v_mov_b32_e32 v38, v1
	v_mov_b32_e32 v39, v1
	v_mov_b32_e32 v40, v1
	v_mov_b32_e32 v41, v1
	v_mov_b32_e32 v42, v1
	v_mov_b32_e32 v43, v1
	v_mov_b32_e32 v44, v1
	v_mov_b32_e32 v45, v1
	v_mov_b32_e32 v46, v1
	v_mov_b32_e32 v47, v1
	v_mov_b32_e32 v48, v1
	v_mov_b32_e32 v49, v1
	v_mov_b32_e32 v50, v1
	v_mov_b32_e32 v51, v1
	v_mov_b32_e32 v52, v1
	v_mov_b32_e32 v53, v1
	v_mov_b32_e32 v54, v1
	v_mov_b32_e32 v55, v1
	v_mov_b32_e32 v56, v1
	v_mov_b32_e32 v57, v1
	v_mov_b32_e32 v58, v1
	v_mov_b32_e32 v59, v1
	v_mov_b32_e32 v60, v1
	v_mov_b32_e32 v61, v1
	v_mov_b32_e32 v62, v1
	v_mov_b32_e32 v63, v1
	s_waitcnt vmcnt(0) lgkmcnt(0)
	s_barrier
	v_add3_u32 v190, 0, v83, v84
	v_add_u32_e32 v191, 0x4000, v190
	s_nop 0
	v_readfirstlane_b32 s82, v191
	v_lshl_add_u32 v191, v118, 1, 0
	s_nop 0
	v_readfirstlane_b32 s83, v190
	v_add3_u32 v191, v191, v84, s15
	s_nop 0
	v_readfirstlane_b32 s84, v191
	v_add_u32_e32 v191, 0x400, v190
	s_nop 0
	v_readfirstlane_b32 s85, v191
	v_lshl_add_u32 v191, v119, 1, 0
	v_add3_u32 v191, v191, v84, s15
	s_nop 0
	v_readfirstlane_b32 s86, v191
	v_add_u32_e32 v191, 0x800, v190
	s_nop 0
	v_readfirstlane_b32 s87, v191
	v_lshl_add_u32 v191, v120, 1, 0
	v_add3_u32 v191, v191, v84, s15
	s_nop 0
	v_readfirstlane_b32 s88, v191
	v_add_u32_e32 v190, 0xc00, v190
	s_nop 0
	v_readfirstlane_b32 s89, v190
	v_subrev_u32_e32 v192, s52, v64
	v_subrev_u32_e32 v193, s52, v66
	v_subrev_u32_e32 v194, s52, v68
	v_subrev_u32_e32 v195, s52, v70
	v_subrev_u32_e32 v196, s52, v72
	v_subrev_u32_e32 v197, s52, v74
	v_subrev_u32_e32 v198, s52, v76
	v_subrev_u32_e32 v199, s52, v78
	s_bitcmp1_b32 s32, 0
	s_cbranch_scc1 .Lxk_708
.LBB0_708:
	s_and_b32 s6, s11, 0x4000
	s_xor_b32 s7, s6, 0x4000
	s_lshl_b32 s7, s7, 1
	s_add_i32 s7, s7, 32
	s_add_u32 s90, s52, s4
	s_addc_u32 s91, s53, s5
	s_add_i32 m0, s7, s82
	s_lshl_b32 s6, s6, 1
	global_load_lds_dwordx4 v192, s[90:91]
	s_add_i32 m0, s7, s83
	s_add_i32 s6, s6, 32
	global_load_lds_dwordx4 v193, s[90:91]
	s_add_i32 m0, s7, s84
	v_lshlrev_b32_e32 v85, 1, v80
	global_load_lds_dwordx4 v194, s[90:91]
	s_add_i32 m0, s7, s85
	v_add3_u32 v112, s6, v81, v85
	global_load_lds_dwordx4 v195, s[90:91]
	s_add_i32 m0, s7, s86
	v_lshlrev_b32_e32 v86, 1, v121
	global_load_lds_dwordx4 v196, s[90:91]
	s_add_i32 m0, s7, s87
	v_add3_u32 v113, s6, v82, v85
	global_load_lds_dwordx4 v197, s[90:91]
	s_add_i32 m0, s7, s88
	v_add_u32_e32 v87, v112, v86
	global_load_lds_dwordx4 v198, s[90:91]
	s_add_i32 m0, s7, s89
	v_add_u32_e32 v123, v113, v86
	global_load_lds_dwordx4 v199, s[90:91]
	ds_read_b128 v[88:91], v87
	ds_read_b128 v[96:99], v123 offset:16384
	ds_read_b128 v[100:103], v123 offset:18432
	ds_read_b128 v[124:127], v123 offset:20480
	ds_read_b128 v[128:131], v123 offset:22528
	ds_read_b128 v[92:95], v87 offset:2048
	ds_read_b128 v[104:107], v87 offset:4096
	ds_read_b128 v[108:111], v87 offset:6144
	v_lshlrev_b32_e32 v87, 1, v122
	v_add_u32_e32 v236, v112, v87
	v_add_u32_e32 v112, v113, v87
	ds_read_b128 v[204:207], v236
	ds_read_b128 v[208:211], v112 offset:16384
	ds_read_b128 v[212:215], v112 offset:18432
	ds_read_b128 v[216:219], v112 offset:20480
	ds_read_b128 v[220:223], v112 offset:22528
	ds_read_b128 v[224:227], v236 offset:2048
	ds_read_b128 v[228:231], v236 offset:4096
	ds_read_b128 v[232:235], v236 offset:6144
	s_setprio 1
	s_waitcnt lgkmcnt(11)
	v_mfma_f32_16x16x32_bf16 v[60:63], v[88:91], v[96:99], v[60:63]
	v_mfma_f32_16x16x32_bf16 v[56:59], v[88:91], v[100:103], v[56:59]
	v_mfma_f32_16x16x32_bf16 v[52:55], v[88:91], v[124:127], v[52:55]
	v_mfma_f32_16x16x32_bf16 v[48:51], v[88:91], v[128:131], v[48:51]
	s_waitcnt lgkmcnt(10)
	v_mfma_f32_16x16x32_bf16 v[44:47], v[92:95], v[96:99], v[44:47]
	v_mfma_f32_16x16x32_bf16 v[40:43], v[92:95], v[100:103], v[40:43]
	v_mfma_f32_16x16x32_bf16 v[36:39], v[92:95], v[124:127], v[36:39]
	v_mfma_f32_16x16x32_bf16 v[32:35], v[92:95], v[128:131], v[32:35]
	s_waitcnt lgkmcnt(9)
	v_mfma_f32_16x16x32_bf16 v[28:31], v[104:107], v[96:99], v[28:31]
	v_mfma_f32_16x16x32_bf16 v[24:27], v[104:107], v[100:103], v[24:27]
	v_mfma_f32_16x16x32_bf16 v[20:23], v[104:107], v[124:127], v[20:23]
	v_mfma_f32_16x16x32_bf16 v[16:19], v[104:107], v[128:131], v[16:19]
	s_waitcnt lgkmcnt(8)
	v_mfma_f32_16x16x32_bf16 v[12:15], v[108:111], v[96:99], v[12:15]
	v_mfma_f32_16x16x32_bf16 v[8:11], v[108:111], v[100:103], v[8:11]
	v_mfma_f32_16x16x32_bf16 v[4:7], v[108:111], v[124:127], v[4:7]
	v_mfma_f32_16x16x32_bf16 v[0:3], v[108:111], v[128:131], v[0:3]
	s_waitcnt lgkmcnt(3)
	v_mfma_f32_16x16x32_bf16 v[60:63], v[204:207], v[208:211], v[60:63]
	v_mfma_f32_16x16x32_bf16 v[56:59], v[204:207], v[212:215], v[56:59]
	v_mfma_f32_16x16x32_bf16 v[52:55], v[204:207], v[216:219], v[52:55]
	v_mfma_f32_16x16x32_bf16 v[48:51], v[204:207], v[220:223], v[48:51]
	s_waitcnt lgkmcnt(2)
	v_mfma_f32_16x16x32_bf16 v[44:47], v[224:227], v[208:211], v[44:47]
	v_mfma_f32_16x16x32_bf16 v[40:43], v[224:227], v[212:215], v[40:43]
	v_mfma_f32_16x16x32_bf16 v[36:39], v[224:227], v[216:219], v[36:39]
	v_mfma_f32_16x16x32_bf16 v[32:35], v[224:227], v[220:223], v[32:35]
	s_waitcnt lgkmcnt(1)
	v_mfma_f32_16x16x32_bf16 v[28:31], v[228:231], v[208:211], v[28:31]
	v_mfma_f32_16x16x32_bf16 v[24:27], v[228:231], v[212:215], v[24:27]
	v_mfma_f32_16x16x32_bf16 v[20:23], v[228:231], v[216:219], v[20:23]
	v_mfma_f32_16x16x32_bf16 v[16:19], v[228:231], v[220:223], v[16:19]
	s_waitcnt lgkmcnt(0)
	v_mfma_f32_16x16x32_bf16 v[12:15], v[232:235], v[208:211], v[12:15]
	v_mfma_f32_16x16x32_bf16 v[8:11], v[232:235], v[212:215], v[8:11]
	v_mfma_f32_16x16x32_bf16 v[4:7], v[232:235], v[216:219], v[4:7]
	v_mfma_f32_16x16x32_bf16 v[0:3], v[232:235], v[220:223], v[0:3]
	s_setprio 0
	s_add_u32 s4, s4, 0x80
	s_addc_u32 s5, s5, 0
	s_addk_i32 s11, 0x4000
	s_cmpk_eq_i32 s4, 0x780
	s_waitcnt vmcnt(0)
	s_barrier
	s_cbranch_scc0 .LBB0_708
	s_branch .Lxk_exit_708
.Lxk_708:
	s_and_b32 s6, s11, 0x4000
	s_xor_b32 s7, s6, 0x4000
	s_lshl_b32 s7, s7, 1
	s_add_i32 s7, s7, 32
	s_add_u32 s90, s52, s4
	s_addc_u32 s91, s53, s5
	s_add_i32 m0, s7, s82
	s_lshl_b32 s6, s6, 1
	global_load_lds_dwordx4 v192, s[90:91]
	s_add_i32 m0, s7, s83
	s_add_i32 s6, s6, 32
	global_load_lds_dwordx4 v193, s[90:91]
	s_add_i32 m0, s7, s84
	v_lshlrev_b32_e32 v85, 1, v80
	global_load_lds_dwordx4 v194, s[90:91]
	s_add_i32 m0, s7, s85
	v_add3_u32 v112, s6, v81, v85
	global_load_lds_dwordx4 v195, s[90:91]
	s_add_i32 m0, s7, s86
	v_lshlrev_b32_e32 v86, 1, v121
	global_load_lds_dwordx4 v196, s[90:91]
	s_add_i32 m0, s7, s87
	v_add3_u32 v113, s6, v82, v85
	global_load_lds_dwordx4 v197, s[90:91]
	s_add_i32 m0, s7, s88
	v_add_u32_e32 v87, v112, v86
	global_load_lds_dwordx4 v198, s[90:91]
	s_add_i32 m0, s7, s89
	v_add_u32_e32 v123, v113, v86
	global_load_lds_dwordx4 v199, s[90:91]
	ds_read_b128 v[88:91], v87
	ds_read_b128 v[96:99], v123 offset:16384
	ds_read_b128 v[100:103], v123 offset:18432
	ds_read_b128 v[124:127], v123 offset:20480
	ds_read_b128 v[128:131], v123 offset:22528
	ds_read_b128 v[92:95], v87 offset:2048
	ds_read_b128 v[104:107], v87 offset:4096
	ds_read_b128 v[108:111], v87 offset:6144
	v_lshlrev_b32_e32 v87, 1, v122
	v_add_u32_e32 v236, v112, v87
	v_add_u32_e32 v112, v113, v87
	ds_read_b128 v[204:207], v236
	ds_read_b128 v[208:211], v112 offset:16384
	ds_read_b128 v[212:215], v112 offset:18432
	ds_read_b128 v[216:219], v112 offset:20480
	ds_read_b128 v[220:223], v112 offset:22528
	ds_read_b128 v[224:227], v236 offset:2048
	ds_read_b128 v[228:231], v236 offset:4096
	ds_read_b128 v[232:235], v236 offset:6144
	s_setprio 3
	s_waitcnt lgkmcnt(11)
	v_mfma_f32_16x16x32_bf16 v[60:63], v[88:91], v[96:99], v[60:63]
	v_mfma_f32_16x16x32_bf16 v[56:59], v[88:91], v[100:103], v[56:59]
	v_mfma_f32_16x16x32_bf16 v[52:55], v[88:91], v[124:127], v[52:55]
	v_mfma_f32_16x16x32_bf16 v[48:51], v[88:91], v[128:131], v[48:51]
	s_waitcnt lgkmcnt(10)
	v_mfma_f32_16x16x32_bf16 v[44:47], v[92:95], v[96:99], v[44:47]
	v_mfma_f32_16x16x32_bf16 v[40:43], v[92:95], v[100:103], v[40:43]
	v_mfma_f32_16x16x32_bf16 v[36:39], v[92:95], v[124:127], v[36:39]
	v_mfma_f32_16x16x32_bf16 v[32:35], v[92:95], v[128:131], v[32:35]
	s_waitcnt lgkmcnt(9)
	v_mfma_f32_16x16x32_bf16 v[28:31], v[104:107], v[96:99], v[28:31]
	v_mfma_f32_16x16x32_bf16 v[24:27], v[104:107], v[100:103], v[24:27]
	v_mfma_f32_16x16x32_bf16 v[20:23], v[104:107], v[124:127], v[20:23]
	v_mfma_f32_16x16x32_bf16 v[16:19], v[104:107], v[128:131], v[16:19]
	s_waitcnt lgkmcnt(8)
	v_mfma_f32_16x16x32_bf16 v[12:15], v[108:111], v[96:99], v[12:15]
	v_mfma_f32_16x16x32_bf16 v[8:11], v[108:111], v[100:103], v[8:11]
	v_mfma_f32_16x16x32_bf16 v[4:7], v[108:111], v[124:127], v[4:7]
	v_mfma_f32_16x16x32_bf16 v[0:3], v[108:111], v[128:131], v[0:3]
	s_waitcnt lgkmcnt(3)
	v_mfma_f32_16x16x32_bf16 v[60:63], v[204:207], v[208:211], v[60:63]
	v_mfma_f32_16x16x32_bf16 v[56:59], v[204:207], v[212:215], v[56:59]
	v_mfma_f32_16x16x32_bf16 v[52:55], v[204:207], v[216:219], v[52:55]
	v_mfma_f32_16x16x32_bf16 v[48:51], v[204:207], v[220:223], v[48:51]
	s_waitcnt lgkmcnt(2)
	v_mfma_f32_16x16x32_bf16 v[44:47], v[224:227], v[208:211], v[44:47]
	v_mfma_f32_16x16x32_bf16 v[40:43], v[224:227], v[212:215], v[40:43]
	v_mfma_f32_16x16x32_bf16 v[36:39], v[224:227], v[216:219], v[36:39]
	v_mfma_f32_16x16x32_bf16 v[32:35], v[224:227], v[220:223], v[32:35]
	s_waitcnt lgkmcnt(1)
	v_mfma_f32_16x16x32_bf16 v[28:31], v[228:231], v[208:211], v[28:31]
	v_mfma_f32_16x16x32_bf16 v[24:27], v[228:231], v[212:215], v[24:27]
	v_mfma_f32_16x16x32_bf16 v[20:23], v[228:231], v[216:219], v[20:23]
	v_mfma_f32_16x16x32_bf16 v[16:19], v[228:231], v[220:223], v[16:19]
	s_waitcnt lgkmcnt(0)
	v_mfma_f32_16x16x32_bf16 v[12:15], v[232:235], v[208:211], v[12:15]
	v_mfma_f32_16x16x32_bf16 v[8:11], v[232:235], v[212:215], v[8:11]
	v_mfma_f32_16x16x32_bf16 v[4:7], v[232:235], v[216:219], v[4:7]
	v_mfma_f32_16x16x32_bf16 v[0:3], v[232:235], v[220:223], v[0:3]
	s_setprio 2
	s_add_u32 s4, s4, 0x80
	s_addc_u32 s5, s5, 0
	s_addk_i32 s11, 0x4000
	s_cmpk_eq_i32 s4, 0x780
	s_waitcnt vmcnt(0)
	s_barrier
	s_cbranch_scc0 .Lxk_708
.Lxk_exit_708:
	v_add3_u32 v84, 32, v81, v85
	v_add3_u32 v85, 32, v82, v85
	v_add_u32_e32 v88, v84, v86
	v_add_u32_e32 v86, v85, v86
	ds_read_b128 v[64:67], v88 offset:32768
	ds_read_b128 v[68:71], v88 offset:34816
	ds_read_b128 v[72:75], v86 offset:49152
	ds_read_b128 v[76:79], v86 offset:51200
	ds_read_b128 v[80:83], v88 offset:36864
	ds_read_b128 v[88:91], v88 offset:38912
	ds_read_b128 v[92:95], v86 offset:53248
	ds_read_b128 v[96:99], v86 offset:55296
	s_setprio 1
	s_waitcnt lgkmcnt(0)
	v_mfma_f32_16x16x32_bf16 v[0:3], v[88:91], v[96:99], v[0:3]
	v_mfma_f32_16x16x32_bf16 v[60:63], v[64:67], v[72:75], v[60:63]
	v_mfma_f32_16x16x32_bf16 v[56:59], v[64:67], v[76:79], v[56:59]
	v_mfma_f32_16x16x32_bf16 v[52:55], v[64:67], v[92:95], v[52:55]
	v_mfma_f32_16x16x32_bf16 v[48:51], v[64:67], v[96:99], v[48:51]
	v_mfma_f32_16x16x32_bf16 v[44:47], v[68:71], v[72:75], v[44:47]
	v_mfma_f32_16x16x32_bf16 v[40:43], v[68:71], v[76:79], v[40:43]
	v_mfma_f32_16x16x32_bf16 v[36:39], v[68:71], v[92:95], v[36:39]
	v_mfma_f32_16x16x32_bf16 v[32:35], v[68:71], v[96:99], v[32:35]
	v_mfma_f32_16x16x32_bf16 v[28:31], v[80:83], v[72:75], v[28:31]
	v_mfma_f32_16x16x32_bf16 v[24:27], v[80:83], v[76:79], v[24:27]
	v_mfma_f32_16x16x32_bf16 v[20:23], v[80:83], v[92:95], v[20:23]
	v_mfma_f32_16x16x32_bf16 v[16:19], v[80:83], v[96:99], v[16:19]
	v_mfma_f32_16x16x32_bf16 v[12:15], v[88:91], v[72:75], v[12:15]
	v_mfma_f32_16x16x32_bf16 v[8:11], v[88:91], v[76:79], v[8:11]
	v_mfma_f32_16x16x32_bf16 v[4:7], v[88:91], v[92:95], v[4:7]
	s_setprio 0
	v_add_u32_e32 v84, v84, v87
	v_add_u32_e32 v92, v85, v87
	ds_read_b128 v[64:67], v84 offset:32768
	ds_read_b128 v[68:71], v84 offset:34816
	ds_read_b128 v[72:75], v92 offset:49152
	ds_read_b128 v[76:79], v92 offset:51200
	ds_read_b128 v[80:83], v84 offset:36864
	ds_read_b128 v[84:87], v84 offset:38912
	ds_read_b128 v[88:91], v92 offset:53248
	ds_read_b128 v[92:95], v92 offset:55296
	s_setprio 1
	s_waitcnt lgkmcnt(0)
	v_mfma_f32_16x16x32_bf16 v[0:3], v[84:87], v[92:95], v[0:3]
	v_mfma_f32_16x16x32_bf16 v[60:63], v[64:67], v[72:75], v[60:63]
	v_mfma_f32_16x16x32_bf16 v[56:59], v[64:67], v[76:79], v[56:59]
	v_mfma_f32_16x16x32_bf16 v[52:55], v[64:67], v[88:91], v[52:55]
	v_mfma_f32_16x16x32_bf16 v[48:51], v[64:67], v[92:95], v[48:51]
	v_mfma_f32_16x16x32_bf16 v[44:47], v[68:71], v[72:75], v[44:47]
	v_mfma_f32_16x16x32_bf16 v[40:43], v[68:71], v[76:79], v[40:43]
	v_mfma_f32_16x16x32_bf16 v[36:39], v[68:71], v[88:91], v[36:39]
	v_mfma_f32_16x16x32_bf16 v[32:35], v[68:71], v[92:95], v[32:35]
	v_mfma_f32_16x16x32_bf16 v[28:31], v[80:83], v[72:75], v[28:31]
	v_mfma_f32_16x16x32_bf16 v[24:27], v[80:83], v[76:79], v[24:27]
	v_mfma_f32_16x16x32_bf16 v[20:23], v[80:83], v[88:91], v[20:23]
	v_mfma_f32_16x16x32_bf16 v[16:19], v[80:83], v[92:95], v[16:19]
	v_mfma_f32_16x16x32_bf16 v[12:15], v[84:87], v[72:75], v[12:15]
	v_mfma_f32_16x16x32_bf16 v[8:11], v[84:87], v[76:79], v[8:11]
	v_mfma_f32_16x16x32_bf16 v[4:7], v[84:87], v[88:91], v[4:7]
	s_setprio 0
	v_lshl_or_b32 v64, v114, 2, v116
	v_mul_u32_u24_e32 v64, 0x210, v64
	v_add3_u32 v64, v115, v117, v64
	s_barrier
	ds_write2_b32 v64, v60, v56 offset1:16
	ds_write2_b32 v64, v61, v57 offset0:132 offset1:148
	v_add_u32_e32 v56, 0x400, v64
	ds_write2_b32 v56, v62, v58 offset0:8 offset1:24
	ds_write2_b32 v56, v63, v59 offset0:140 offset1:156
	ds_write2_b32 v64, v52, v48 offset0:32 offset1:48
	ds_write2_b32 v64, v53, v49 offset0:164 offset1:180
	ds_write2_b32 v56, v54, v50 offset0:40 offset1:56
	ds_write2_b32 v56, v55, v51 offset0:172 offset1:188
	v_add_u32_e32 v48, 0x2000, v64
	ds_write2_b32 v48, v44, v40 offset0:64 offset1:80
	ds_write2_b32 v48, v45, v41 offset0:196 offset1:212
	v_add_u32_e32 v40, 0x2400, v64
	ds_write2_b32 v40, v46, v42 offset0:72 offset1:88
	ds_write2_b32 v40, v47, v43 offset0:204 offset1:220
	ds_write2_b32 v48, v36, v32 offset0:96 offset1:112
	ds_write2_b32 v48, v37, v33 offset0:228 offset1:244
	ds_write2_b32 v40, v38, v34 offset0:104 offset1:120
	ds_write2_b32 v40, v39, v35 offset0:236 offset1:252
	v_add_u32_e32 v32, 0x4000, v64
	ds_write2_b32 v32, v28, v24 offset0:128 offset1:144
	v_add_u32_e32 v24, 0x4400, v64
	ds_write2_b32 v24, v29, v25 offset0:4 offset1:20
	ds_write2_b32 v24, v30, v26 offset0:136 offset1:152
	v_add_u32_e32 v25, 0x4800, v64
	ds_write2_b32 v25, v31, v27 offset0:12 offset1:28
	ds_write2_b32 v32, v20, v16 offset0:160 offset1:176
	ds_write2_b32 v24, v21, v17 offset0:36 offset1:52
	ds_write2_b32 v24, v22, v18 offset0:168 offset1:184
	ds_write2_b32 v25, v23, v19 offset0:44 offset1:60
	v_add_u32_e32 v16, 0x6000, v64
	ds_write2_b32 v16, v12, v8 offset0:192 offset1:208
	v_add_u32_e32 v8, 0x6400, v64
	ds_write2_b32 v8, v13, v9 offset0:68 offset1:84
	ds_write2_b32 v8, v14, v10 offset0:200 offset1:216
	v_add_u32_e32 v9, 0x6800, v64
	ds_write2_b32 v9, v15, v11 offset0:76 offset1:92
	ds_write2_b32 v16, v4, v0 offset0:224 offset1:240
	ds_write2_b32 v8, v5, v1 offset0:100 offset1:116
	ds_write2_b32 v8, v6, v2 offset0:232 offset1:248
	ds_write2_b32 v9, v7, v3 offset0:108 offset1:124
	v_lshlrev_b32_e32 v0, 4, v180
	v_and_b32_e32 v0, 0x70, v0
	s_lshl_b32 s5, s14, 23
	v_or_b32_e32 v0, s9, v0
	s_add_u32 s6, s12, s5
	s_addc_u32 s7, s13, 0
	v_lshlrev_b32_e32 v0, 2, v0
	v_mov_b32_e32 v1, 0
	v_lshrrev_b32_e32 v2, 3, v180
	v_and_b32_e32 v4, 7, v180
	v_lshl_add_u64 v[0:1], s[6:7], 0, v[0:1]
	s_mov_b64 s[6:7], 0x11600000
	v_mul_u32_u24_e32 v3, 0x210, v2
	v_lshlrev_b32_e32 v4, 6, v4
	s_mov_b32 s4, 0
	v_lshl_add_u64 v[0:1], v[0:1], 0, s[6:7]
	v_add3_u32 v3, v3, v4, 32
	s_mov_b32 s5, 0x38e38e39
	s_mov_b32 s6, 0x1ffffee
	s_movk_i32 s7, 0xf800
	s_waitcnt lgkmcnt(0)
	s_barrier

.LBB0_1813:
	s_ashr_i32 s16, s23, 31
	s_lshr_b32 s16, s16, 29
	s_add_i32 s16, s23, s16
	s_ashr_i32 s16, s16, 3
	s_lshl_b32 s24, s16, 7
	s_lshl_b32 s16, s16, 10
	s_lshl_b32 s17, s23, 7
	s_sub_i32 s25, s17, s16
	v_add_u32_e32 v0, s25, v106
	v_ashrrev_i32_e32 v1, 31, v0
	v_add_u32_e32 v2, 0x4000, v107
	v_lshlrev_b64 v[0:1], 11, v[0:1]
	v_readfirstlane_b32 s17, v2
	v_lshl_add_u64 v[0:1], v[66:67], 0, v[0:1]
	s_mov_b32 m0, s17
	v_readfirstlane_b32 s17, v107
	global_load_lds_dwordx4 v[0:1], off
	v_add_u32_e32 v0, s24, v106
	v_ashrrev_i32_e32 v1, 31, v0
	v_lshlrev_b64 v[0:1], 11, v[0:1]
	v_lshl_add_u64 v[2:3], v[72:73], 0, v[0:1]
	s_mov_b32 m0, s17
	v_readfirstlane_b32 s17, v130
	global_load_lds_dwordx4 v[2:3], off
	v_add_u32_e32 v2, s25, v108
	v_ashrrev_i32_e32 v3, 31, v2
	v_lshlrev_b64 v[2:3], 11, v[2:3]
	v_lshl_add_u64 v[2:3], v[68:69], 0, v[2:3]
	s_mov_b32 m0, s17
	v_add_u32_e32 v4, 0x400, v107
	global_load_lds_dwordx4 v[2:3], off
	v_add_u32_e32 v2, s24, v108
	v_ashrrev_i32_e32 v3, 31, v2
	v_lshlrev_b64 v[2:3], 11, v[2:3]
	v_readfirstlane_b32 s17, v4
	v_lshl_add_u64 v[2:3], v[74:75], 0, v[2:3]
	s_mov_b32 m0, s17
	v_readfirstlane_b32 s17, v131
	global_load_lds_dwordx4 v[2:3], off
	v_add_u32_e32 v2, s25, v110
	v_ashrrev_i32_e32 v3, 31, v2
	v_lshlrev_b64 v[2:3], 11, v[2:3]
	v_lshl_add_u64 v[2:3], v[66:67], 0, v[2:3]
	s_mov_b32 m0, s17
	v_add_u32_e32 v4, 0x800, v107
	global_load_lds_dwordx4 v[2:3], off
	v_add_u32_e32 v2, s24, v110
	v_ashrrev_i32_e32 v3, 31, v2
	v_lshlrev_b64 v[2:3], 11, v[2:3]
	v_readfirstlane_b32 s17, v4
	v_lshl_add_u64 v[2:3], v[72:73], 0, v[2:3]
	s_mov_b32 m0, s17
	v_readfirstlane_b32 s17, v132
	global_load_lds_dwordx4 v[2:3], off
	v_add_u32_e32 v2, s25, v112
	v_ashrrev_i32_e32 v3, 31, v2
	v_lshlrev_b64 v[2:3], 11, v[2:3]
	v_lshl_add_u64 v[2:3], v[70:71], 0, v[2:3]
	s_mov_b32 m0, s17
	v_add_u32_e32 v4, 0xc00, v107
	global_load_lds_dwordx4 v[2:3], off
	v_add_u32_e32 v2, s24, v112
	v_ashrrev_i32_e32 v3, 31, v2
	v_lshlrev_b64 v[2:3], 11, v[2:3]
	v_readfirstlane_b32 s17, v4
	v_lshl_add_u64 v[2:3], v[76:77], 0, v[2:3]
	s_mov_b32 m0, s17
	v_lshl_add_u64 v[92:93], v[80:81], 0, v[0:1]
	global_load_lds_dwordx4 v[2:3], off
	v_subrev_u32_e32 v0, s16, v123
	v_ashrrev_i32_e32 v1, 31, v0
	v_lshlrev_b64 v[0:1], 11, v[0:1]
	v_lshl_add_u64 v[94:95], v[82:83], 0, v[0:1]
	v_add_u32_e32 v0, s24, v124
	v_ashrrev_i32_e32 v1, 31, v0
	v_lshlrev_b64 v[0:1], 11, v[0:1]
	v_lshl_add_u64 v[96:97], v[84:85], 0, v[0:1]
	v_subrev_u32_e32 v0, s16, v125
	v_ashrrev_i32_e32 v1, 31, v0
	v_lshlrev_b64 v[0:1], 11, v[0:1]
	v_lshl_add_u64 v[98:99], v[78:79], 0, v[0:1]
	v_add_u32_e32 v0, s24, v126
	v_ashrrev_i32_e32 v1, 31, v0
	v_lshlrev_b64 v[0:1], 11, v[0:1]
	v_lshl_add_u64 v[100:101], v[80:81], 0, v[0:1]
	v_subrev_u32_e32 v0, s16, v64
	v_ashrrev_i32_e32 v1, 31, v0
	v_lshlrev_b64 v[0:1], 11, v[0:1]
	v_subrev_u32_e32 v2, s16, v122
	v_lshl_add_u64 v[102:103], v[86:87], 0, v[0:1]
	v_add_u32_e32 v0, s24, v127
	v_ashrrev_i32_e32 v3, 31, v2
	v_ashrrev_i32_e32 v1, 31, v0
	v_lshlrev_b64 v[2:3], 11, v[2:3]
	v_lshlrev_b64 v[0:1], 11, v[0:1]
	v_lshl_add_u64 v[90:91], v[78:79], 0, v[2:3]
	v_lshl_add_u64 v[104:105], v[88:89], 0, v[0:1]
	s_mov_b32 s26, 0
	s_mov_b64 s[16:17], 0
	v_mov_b32_e32 v0, 0
	v_mov_b32_e32 v1, v65
	v_mov_b32_e32 v2, v65
	v_mov_b32_e32 v3, v65
	v_mov_b32_e32 v4, 0
	v_mov_b32_e32 v5, v65
	v_mov_b32_e32 v6, v65
	v_mov_b32_e32 v7, v65
	v_mov_b32_e32 v8, 0
	v_mov_b32_e32 v9, v65
	v_mov_b32_e32 v10, v65
	v_mov_b32_e32 v11, v65
	v_mov_b32_e32 v12, 0
	v_mov_b32_e32 v13, v65
	v_mov_b32_e32 v14, v65
	v_mov_b32_e32 v15, v65
	v_mov_b32_e32 v16, 0
	v_mov_b32_e32 v17, v65
	v_mov_b32_e32 v18, v65
	v_mov_b32_e32 v19, v65
	v_mov_b32_e32 v20, 0
	v_mov_b32_e32 v21, v65
	v_mov_b32_e32 v22, v65
	v_mov_b32_e32 v23, v65
	v_mov_b32_e32 v24, 0
	v_mov_b32_e32 v25, v65
	v_mov_b32_e32 v26, v65
	v_mov_b32_e32 v27, v65
	v_mov_b32_e32 v28, 0
	v_mov_b32_e32 v29, v65
	v_mov_b32_e32 v30, v65
	v_mov_b32_e32 v31, v65
	s_waitcnt vmcnt(0)
	v_mov_b32_e32 v32, 0
	v_mov_b32_e32 v33, v65
	v_mov_b32_e32 v34, v65
	v_mov_b32_e32 v35, v65
	v_mov_b32_e32 v36, 0
	v_mov_b32_e32 v37, v65
	v_mov_b32_e32 v38, v65
	v_mov_b32_e32 v39, v65
	v_mov_b32_e32 v40, 0
	v_mov_b32_e32 v41, v65
	v_mov_b32_e32 v42, v65
	v_mov_b32_e32 v43, v65
	v_mov_b32_e32 v44, 0
	v_mov_b32_e32 v45, v65
	v_mov_b32_e32 v46, v65
	v_mov_b32_e32 v47, v65
	v_mov_b32_e32 v48, 0
	v_mov_b32_e32 v49, v65
	v_mov_b32_e32 v50, v65
	v_mov_b32_e32 v51, v65
	v_mov_b32_e32 v52, 0
	v_mov_b32_e32 v53, v65
	v_mov_b32_e32 v54, v65
	v_mov_b32_e32 v55, v65
	v_mov_b32_e32 v56, 0
	v_mov_b32_e32 v57, v65
	v_mov_b32_e32 v58, v65
	v_mov_b32_e32 v59, v65
	v_mov_b32_e32 v60, 0
	v_mov_b32_e32 v61, v65
	v_mov_b32_e32 v62, v65
	v_mov_b32_e32 v63, v65
	s_waitcnt lgkmcnt(0)
	s_barrier
	v_add3_u32 v186, 0, v133, v134
	v_add_u32_e32 v187, 0x4000, v186
	s_nop 0
	v_readfirstlane_b32 s82, v187
	v_lshl_add_u32 v187, v109, 1, 0
	s_nop 0
	v_readfirstlane_b32 s83, v186
	v_add3_u32 v187, v187, v134, s19
	s_nop 0
	v_readfirstlane_b32 s84, v187
	v_add_u32_e32 v187, 0x400, v186
	s_nop 0
	v_readfirstlane_b32 s85, v187
	v_lshl_add_u32 v187, v111, 1, 0
	v_add3_u32 v187, v187, v134, s19
	s_nop 0
	v_readfirstlane_b32 s86, v187
	v_add_u32_e32 v187, 0x800, v186
	s_nop 0
	v_readfirstlane_b32 s87, v187
	v_lshl_add_u32 v187, v113, 1, 0
	v_add3_u32 v187, v187, v134, s19
	s_nop 0
	v_readfirstlane_b32 s88, v187
	v_add_u32_e32 v186, 0xc00, v186
	s_nop 0
	v_readfirstlane_b32 s89, v186
	v_subrev_u32_e32 v188, s52, v90
	v_subrev_u32_e32 v189, s52, v92
	v_subrev_u32_e32 v190, s52, v94
	v_subrev_u32_e32 v191, s52, v96
	v_subrev_u32_e32 v192, s52, v98
	v_subrev_u32_e32 v193, s52, v100
	v_subrev_u32_e32 v194, s52, v102
	v_subrev_u32_e32 v195, s52, v104
	s_bitcmp1_b32 s32, 0
	s_cbranch_scc1 .Lxk_1814
.LBB0_1814:
	s_and_b32 s27, s26, 0x4000
	s_xor_b32 s28, s27, 0x4000
	s_lshl_b32 s28, s28, 1
	s_add_i32 s28, s28, 32
	s_add_u32 s90, s52, s16
	s_addc_u32 s91, s53, s17
	s_add_i32 m0, s28, s82
	s_lshl_b32 s27, s27, 1
	global_load_lds_dwordx4 v188, s[90:91]
	s_add_i32 m0, s28, s83
	s_add_i32 s27, s27, 32
	global_load_lds_dwordx4 v189, s[90:91]
	s_add_i32 m0, s28, s84
	v_add3_u32 v170, s27, v114, v135
	global_load_lds_dwordx4 v190, s[90:91]
	s_add_i32 m0, s28, s85
	v_add3_u32 v171, s27, v115, v135
	global_load_lds_dwordx4 v191, s[90:91]
	s_add_i32 m0, s28, s86
	v_add_u32_e32 v158, v170, v136
	global_load_lds_dwordx4 v192, s[90:91]
	s_add_i32 m0, s28, s87
	v_add_u32_e32 v166, v171, v136
	global_load_lds_dwordx4 v193, s[90:91]
	s_add_i32 m0, s28, s88
	s_addk_i32 s26, 0x4000
	global_load_lds_dwordx4 v194, s[90:91]
	s_add_i32 m0, s28, s89
	s_add_u32 s16, s16, 0x80
	s_addc_u32 s17, s17, 0
	global_load_lds_dwordx4 v195, s[90:91]
	ds_read_b128 v[138:141], v158
	ds_read_b128 v[146:149], v166 offset:16384
	ds_read_b128 v[150:153], v166 offset:18432
	ds_read_b128 v[162:165], v166 offset:20480
	ds_read_b128 v[166:169], v166 offset:22528
	ds_read_b128 v[142:145], v158 offset:2048
	ds_read_b128 v[154:157], v158 offset:4096
	ds_read_b128 v[158:161], v158 offset:6144
	v_add_u32_e32 v236, v170, v137
	v_add_u32_e32 v237, v171, v137
	ds_read_b128 v[204:207], v236
	ds_read_b128 v[208:211], v237 offset:16384
	ds_read_b128 v[212:215], v237 offset:18432
	ds_read_b128 v[216:219], v237 offset:20480
	ds_read_b128 v[220:223], v237 offset:22528
	ds_read_b128 v[224:227], v236 offset:2048
	ds_read_b128 v[228:231], v236 offset:4096
	ds_read_b128 v[232:235], v236 offset:6144
	s_setprio 1
	s_waitcnt lgkmcnt(11)
	v_mfma_f32_16x16x32_bf16 v[60:63], v[138:141], v[146:149], v[60:63]
	v_mfma_f32_16x16x32_bf16 v[56:59], v[138:141], v[150:153], v[56:59]
	v_mfma_f32_16x16x32_bf16 v[52:55], v[138:141], v[162:165], v[52:55]
	v_mfma_f32_16x16x32_bf16 v[48:51], v[138:141], v[166:169], v[48:51]
	s_waitcnt lgkmcnt(10)
	v_mfma_f32_16x16x32_bf16 v[44:47], v[142:145], v[146:149], v[44:47]
	v_mfma_f32_16x16x32_bf16 v[40:43], v[142:145], v[150:153], v[40:43]
	v_mfma_f32_16x16x32_bf16 v[36:39], v[142:145], v[162:165], v[36:39]
	v_mfma_f32_16x16x32_bf16 v[32:35], v[142:145], v[166:169], v[32:35]
	s_waitcnt lgkmcnt(9)
	v_mfma_f32_16x16x32_bf16 v[28:31], v[154:157], v[146:149], v[28:31]
	v_mfma_f32_16x16x32_bf16 v[24:27], v[154:157], v[150:153], v[24:27]
	v_mfma_f32_16x16x32_bf16 v[20:23], v[154:157], v[162:165], v[20:23]
	v_mfma_f32_16x16x32_bf16 v[16:19], v[154:157], v[166:169], v[16:19]
	s_waitcnt lgkmcnt(8)
	v_mfma_f32_16x16x32_bf16 v[12:15], v[158:161], v[146:149], v[12:15]
	v_mfma_f32_16x16x32_bf16 v[8:11], v[158:161], v[150:153], v[8:11]
	v_mfma_f32_16x16x32_bf16 v[4:7], v[158:161], v[162:165], v[4:7]
	v_mfma_f32_16x16x32_bf16 v[0:3], v[158:161], v[166:169], v[0:3]
	s_waitcnt lgkmcnt(3)
	v_mfma_f32_16x16x32_bf16 v[60:63], v[204:207], v[208:211], v[60:63]
	v_mfma_f32_16x16x32_bf16 v[56:59], v[204:207], v[212:215], v[56:59]
	v_mfma_f32_16x16x32_bf16 v[52:55], v[204:207], v[216:219], v[52:55]
	v_mfma_f32_16x16x32_bf16 v[48:51], v[204:207], v[220:223], v[48:51]
	s_waitcnt lgkmcnt(2)
	v_mfma_f32_16x16x32_bf16 v[44:47], v[224:227], v[208:211], v[44:47]
	v_mfma_f32_16x16x32_bf16 v[40:43], v[224:227], v[212:215], v[40:43]
	v_mfma_f32_16x16x32_bf16 v[36:39], v[224:227], v[216:219], v[36:39]
	v_mfma_f32_16x16x32_bf16 v[32:35], v[224:227], v[220:223], v[32:35]
	s_waitcnt lgkmcnt(1)
	v_mfma_f32_16x16x32_bf16 v[28:31], v[228:231], v[208:211], v[28:31]
	v_mfma_f32_16x16x32_bf16 v[24:27], v[228:231], v[212:215], v[24:27]
	v_mfma_f32_16x16x32_bf16 v[20:23], v[228:231], v[216:219], v[20:23]
	v_mfma_f32_16x16x32_bf16 v[16:19], v[228:231], v[220:223], v[16:19]
	s_waitcnt lgkmcnt(0)
	v_mfma_f32_16x16x32_bf16 v[12:15], v[232:235], v[208:211], v[12:15]
	v_mfma_f32_16x16x32_bf16 v[8:11], v[232:235], v[212:215], v[8:11]
	v_mfma_f32_16x16x32_bf16 v[4:7], v[232:235], v[216:219], v[4:7]
	v_mfma_f32_16x16x32_bf16 v[0:3], v[232:235], v[220:223], v[0:3]
	s_setprio 0
	s_cmpk_eq_i32 s16, 0x780
	s_waitcnt vmcnt(0)
	s_barrier
	s_cbranch_scc0 .LBB0_1814
	s_branch .Lxk_exit_1814
.Lxk_1814:
	s_and_b32 s27, s26, 0x4000
	s_xor_b32 s28, s27, 0x4000
	s_lshl_b32 s28, s28, 1
	s_add_i32 s28, s28, 32
	s_add_u32 s90, s52, s16
	s_addc_u32 s91, s53, s17
	s_add_i32 m0, s28, s82
	s_lshl_b32 s27, s27, 1
	global_load_lds_dwordx4 v188, s[90:91]
	s_add_i32 m0, s28, s83
	s_add_i32 s27, s27, 32
	global_load_lds_dwordx4 v189, s[90:91]
	s_add_i32 m0, s28, s84
	v_add3_u32 v170, s27, v114, v135
	global_load_lds_dwordx4 v190, s[90:91]
	s_add_i32 m0, s28, s85
	v_add3_u32 v171, s27, v115, v135
	global_load_lds_dwordx4 v191, s[90:91]
	s_add_i32 m0, s28, s86
	v_add_u32_e32 v158, v170, v136
	global_load_lds_dwordx4 v192, s[90:91]
	s_add_i32 m0, s28, s87
	v_add_u32_e32 v166, v171, v136
	global_load_lds_dwordx4 v193, s[90:91]
	s_add_i32 m0, s28, s88
	s_addk_i32 s26, 0x4000
	global_load_lds_dwordx4 v194, s[90:91]
	s_add_i32 m0, s28, s89
	s_add_u32 s16, s16, 0x80
	s_addc_u32 s17, s17, 0
	global_load_lds_dwordx4 v195, s[90:91]
	ds_read_b128 v[138:141], v158
	ds_read_b128 v[146:149], v166 offset:16384
	ds_read_b128 v[150:153], v166 offset:18432
	ds_read_b128 v[162:165], v166 offset:20480
	ds_read_b128 v[166:169], v166 offset:22528
	ds_read_b128 v[142:145], v158 offset:2048
	ds_read_b128 v[154:157], v158 offset:4096
	ds_read_b128 v[158:161], v158 offset:6144
	v_add_u32_e32 v236, v170, v137
	v_add_u32_e32 v237, v171, v137
	ds_read_b128 v[204:207], v236
	ds_read_b128 v[208:211], v237 offset:16384
	ds_read_b128 v[212:215], v237 offset:18432
	ds_read_b128 v[216:219], v237 offset:20480
	ds_read_b128 v[220:223], v237 offset:22528
	ds_read_b128 v[224:227], v236 offset:2048
	ds_read_b128 v[228:231], v236 offset:4096
	ds_read_b128 v[232:235], v236 offset:6144
	s_setprio 3
	s_waitcnt lgkmcnt(11)
	v_mfma_f32_16x16x32_bf16 v[60:63], v[138:141], v[146:149], v[60:63]
	v_mfma_f32_16x16x32_bf16 v[56:59], v[138:141], v[150:153], v[56:59]
	v_mfma_f32_16x16x32_bf16 v[52:55], v[138:141], v[162:165], v[52:55]
	v_mfma_f32_16x16x32_bf16 v[48:51], v[138:141], v[166:169], v[48:51]
	s_waitcnt lgkmcnt(10)
	v_mfma_f32_16x16x32_bf16 v[44:47], v[142:145], v[146:149], v[44:47]
	v_mfma_f32_16x16x32_bf16 v[40:43], v[142:145], v[150:153], v[40:43]
	v_mfma_f32_16x16x32_bf16 v[36:39], v[142:145], v[162:165], v[36:39]
	v_mfma_f32_16x16x32_bf16 v[32:35], v[142:145], v[166:169], v[32:35]
	s_waitcnt lgkmcnt(9)
	v_mfma_f32_16x16x32_bf16 v[28:31], v[154:157], v[146:149], v[28:31]
	v_mfma_f32_16x16x32_bf16 v[24:27], v[154:157], v[150:153], v[24:27]
	v_mfma_f32_16x16x32_bf16 v[20:23], v[154:157], v[162:165], v[20:23]
	v_mfma_f32_16x16x32_bf16 v[16:19], v[154:157], v[166:169], v[16:19]
	s_waitcnt lgkmcnt(8)
	v_mfma_f32_16x16x32_bf16 v[12:15], v[158:161], v[146:149], v[12:15]
	v_mfma_f32_16x16x32_bf16 v[8:11], v[158:161], v[150:153], v[8:11]
	v_mfma_f32_16x16x32_bf16 v[4:7], v[158:161], v[162:165], v[4:7]
	v_mfma_f32_16x16x32_bf16 v[0:3], v[158:161], v[166:169], v[0:3]
	s_waitcnt lgkmcnt(3)
	v_mfma_f32_16x16x32_bf16 v[60:63], v[204:207], v[208:211], v[60:63]
	v_mfma_f32_16x16x32_bf16 v[56:59], v[204:207], v[212:215], v[56:59]
	v_mfma_f32_16x16x32_bf16 v[52:55], v[204:207], v[216:219], v[52:55]
	v_mfma_f32_16x16x32_bf16 v[48:51], v[204:207], v[220:223], v[48:51]
	s_waitcnt lgkmcnt(2)
	v_mfma_f32_16x16x32_bf16 v[44:47], v[224:227], v[208:211], v[44:47]
	v_mfma_f32_16x16x32_bf16 v[40:43], v[224:227], v[212:215], v[40:43]
	v_mfma_f32_16x16x32_bf16 v[36:39], v[224:227], v[216:219], v[36:39]
	v_mfma_f32_16x16x32_bf16 v[32:35], v[224:227], v[220:223], v[32:35]
	s_waitcnt lgkmcnt(1)
	v_mfma_f32_16x16x32_bf16 v[28:31], v[228:231], v[208:211], v[28:31]
	v_mfma_f32_16x16x32_bf16 v[24:27], v[228:231], v[212:215], v[24:27]
	v_mfma_f32_16x16x32_bf16 v[20:23], v[228:231], v[216:219], v[20:23]
	v_mfma_f32_16x16x32_bf16 v[16:19], v[228:231], v[220:223], v[16:19]
	s_waitcnt lgkmcnt(0)
	v_mfma_f32_16x16x32_bf16 v[12:15], v[232:235], v[208:211], v[12:15]
	v_mfma_f32_16x16x32_bf16 v[8:11], v[232:235], v[212:215], v[8:11]
	v_mfma_f32_16x16x32_bf16 v[4:7], v[232:235], v[216:219], v[4:7]
	v_mfma_f32_16x16x32_bf16 v[0:3], v[232:235], v[220:223], v[0:3]
	s_setprio 2
	s_cmpk_eq_i32 s16, 0x780
	s_waitcnt vmcnt(0)
	s_barrier
	s_cbranch_scc0 .Lxk_1814
.Lxk_exit_1814:
	ds_read_b128 v[90:93], v118 offset:55296
	ds_read_b128 v[94:97], v118 offset:53248
	ds_read_b128 v[98:101], v119 offset:38912
	ds_read_b128 v[102:105], v119 offset:36864
	ds_read_b128 v[138:141], v118 offset:51200
	ds_read_b128 v[142:145], v118 offset:49152
	ds_read_b128 v[146:149], v119 offset:34816
	ds_read_b128 v[150:153], v119 offset:32768
	s_setprio 1
	s_waitcnt lgkmcnt(5)
	v_mfma_f32_16x16x32_bf16 v[4:7], v[98:101], v[94:97], v[4:7]
	v_mfma_f32_16x16x32_bf16 v[0:3], v[98:101], v[90:93], v[0:3]
	s_waitcnt lgkmcnt(0)
	v_mfma_f32_16x16x32_bf16 v[60:63], v[150:153], v[142:145], v[60:63]
	v_mfma_f32_16x16x32_bf16 v[56:59], v[150:153], v[138:141], v[56:59]
	v_mfma_f32_16x16x32_bf16 v[52:55], v[150:153], v[94:97], v[52:55]
	v_mfma_f32_16x16x32_bf16 v[48:51], v[150:153], v[90:93], v[48:51]
	v_mfma_f32_16x16x32_bf16 v[44:47], v[146:149], v[142:145], v[44:47]
	v_mfma_f32_16x16x32_bf16 v[40:43], v[146:149], v[138:141], v[40:43]
	v_mfma_f32_16x16x32_bf16 v[36:39], v[146:149], v[94:97], v[36:39]
	v_mfma_f32_16x16x32_bf16 v[32:35], v[146:149], v[90:93], v[32:35]
	v_mfma_f32_16x16x32_bf16 v[28:31], v[102:105], v[142:145], v[28:31]
	v_mfma_f32_16x16x32_bf16 v[24:27], v[102:105], v[138:141], v[24:27]
	v_mfma_f32_16x16x32_bf16 v[20:23], v[102:105], v[94:97], v[20:23]
	v_mfma_f32_16x16x32_bf16 v[16:19], v[102:105], v[90:93], v[16:19]
	v_mfma_f32_16x16x32_bf16 v[12:15], v[98:101], v[142:145], v[12:15]
	v_mfma_f32_16x16x32_bf16 v[8:11], v[98:101], v[138:141], v[8:11]
	s_setprio 0
	ds_read_b128 v[90:93], v120 offset:32768
	ds_read_b128 v[94:97], v120 offset:34816
	ds_read_b128 v[98:101], v121 offset:49152
	ds_read_b128 v[102:105], v121 offset:51200
	ds_read_b128 v[138:141], v120 offset:36864
	ds_read_b128 v[142:145], v120 offset:38912
	ds_read_b128 v[146:149], v121 offset:53248
	ds_read_b128 v[150:153], v121 offset:55296
	s_setprio 1
	s_waitcnt lgkmcnt(1)
	v_mfma_f32_16x16x32_bf16 v[4:7], v[142:145], v[146:149], v[4:7]
	s_waitcnt lgkmcnt(0)
	v_mfma_f32_16x16x32_bf16 v[0:3], v[142:145], v[150:153], v[0:3]
	v_mfma_f32_16x16x32_bf16 v[60:63], v[90:93], v[98:101], v[60:63]
	v_mfma_f32_16x16x32_bf16 v[56:59], v[90:93], v[102:105], v[56:59]
	v_mfma_f32_16x16x32_bf16 v[52:55], v[90:93], v[146:149], v[52:55]
	v_mfma_f32_16x16x32_bf16 v[48:51], v[90:93], v[150:153], v[48:51]
	v_mfma_f32_16x16x32_bf16 v[44:47], v[94:97], v[98:101], v[44:47]
	v_mfma_f32_16x16x32_bf16 v[40:43], v[94:97], v[102:105], v[40:43]
	v_mfma_f32_16x16x32_bf16 v[36:39], v[94:97], v[146:149], v[36:39]
	v_mfma_f32_16x16x32_bf16 v[32:35], v[94:97], v[150:153], v[32:35]
	v_mfma_f32_16x16x32_bf16 v[28:31], v[138:141], v[98:101], v[28:31]
	v_mfma_f32_16x16x32_bf16 v[24:27], v[138:141], v[102:105], v[24:27]
	v_mfma_f32_16x16x32_bf16 v[20:23], v[138:141], v[146:149], v[20:23]
	v_mfma_f32_16x16x32_bf16 v[16:19], v[138:141], v[150:153], v[16:19]
	v_mfma_f32_16x16x32_bf16 v[12:15], v[142:145], v[98:101], v[12:15]
	v_mfma_f32_16x16x32_bf16 v[8:11], v[142:145], v[102:105], v[8:11]
	s_setprio 0
	s_barrier
	ds_write2_b32 v116, v60, v56 offset1:16
	ds_write2_b32 v116, v61, v57 offset0:132 offset1:148
	v_add_u32_e32 v56, 0x400, v116
	ds_write2_b32 v56, v62, v58 offset0:8 offset1:24
	ds_write2_b32 v56, v63, v59 offset0:140 offset1:156
	ds_write2_b32 v116, v52, v48 offset0:32 offset1:48
	ds_write2_b32 v116, v53, v49 offset0:164 offset1:180
	ds_write2_b32 v56, v54, v50 offset0:40 offset1:56
	ds_write2_b32 v56, v55, v51 offset0:172 offset1:188
	v_add_u32_e32 v48, 0x2000, v116
	ds_write2_b32 v48, v44, v40 offset0:64 offset1:80
	ds_write2_b32 v48, v45, v41 offset0:196 offset1:212
	v_add_u32_e32 v40, 0x2400, v116
	ds_write2_b32 v40, v46, v42 offset0:72 offset1:88
	ds_write2_b32 v40, v47, v43 offset0:204 offset1:220
	ds_write2_b32 v48, v36, v32 offset0:96 offset1:112
	ds_write2_b32 v48, v37, v33 offset0:228 offset1:244
	ds_write2_b32 v40, v38, v34 offset0:104 offset1:120
	ds_write2_b32 v40, v39, v35 offset0:236 offset1:252
	v_add_u32_e32 v32, 0x4000, v116
	ds_write2_b32 v32, v28, v24 offset0:128 offset1:144
	v_add_u32_e32 v24, 0x4400, v116
	ds_write2_b32 v24, v29, v25 offset0:4 offset1:20
	ds_write2_b32 v24, v30, v26 offset0:136 offset1:152
	v_add_u32_e32 v25, 0x4800, v116
	ds_write2_b32 v25, v31, v27 offset0:12 offset1:28
	ds_write2_b32 v32, v20, v16 offset0:160 offset1:176
	ds_write2_b32 v24, v21, v17 offset0:36 offset1:52
	ds_write2_b32 v24, v22, v18 offset0:168 offset1:184
	ds_write2_b32 v25, v23, v19 offset0:44 offset1:60
	v_add_u32_e32 v16, 0x6000, v116
	ds_write2_b32 v16, v12, v8 offset0:192 offset1:208
	v_add_u32_e32 v8, 0x6400, v116
	ds_write2_b32 v8, v13, v9 offset0:68 offset1:84
	ds_write2_b32 v8, v14, v10 offset0:200 offset1:216
	v_add_u32_e32 v9, 0x6800, v116
	ds_write2_b32 v9, v15, v11 offset0:76 offset1:92
	ds_write2_b32 v16, v4, v0 offset0:224 offset1:240
	ds_write2_b32 v8, v5, v1 offset0:100 offset1:116
	ds_write2_b32 v8, v6, v2 offset0:232 offset1:248
	ds_write2_b32 v9, v7, v3 offset0:108 offset1:124
	v_or_b32_e32 v0, s25, v117
	v_ashrrev_i32_e32 v1, 31, v0
	v_lshlrev_b64 v[2:3], 2, v[0:1]
	v_lshl_add_u64 v[0:1], s[14:15], 0, v[2:3]
	v_lshl_add_u64 v[2:3], s[10:11], 0, v[2:3]
	v_add_u32_e32 v4, s24, v128
	s_mov_b32 s16, 0
	s_waitcnt lgkmcnt(0)
	s_barrier

.LBB0_1822:
	s_ashr_i32 s16, s18, 31
	s_lshr_b32 s16, s16, 29
	s_add_i32 s16, s18, s16
	s_ashr_i32 s16, s16, 3
	s_lshl_b32 s17, s16, 10
	s_lshl_b32 s25, s18, 7
	v_add_u32_e32 v0, s16, v104
	s_sub_i32 s25, s25, s17
	v_lshlrev_b32_e32 v2, 7, v0
	v_add_u32_e32 v0, s25, v105
	v_ashrrev_i32_e32 v1, 31, v0
	v_add_u32_e32 v3, 0x4000, v106
	v_lshlrev_b64 v[0:1], 11, v[0:1]
	v_readfirstlane_b32 s26, v3
	v_lshl_add_u64 v[0:1], v[64:65], 0, v[0:1]
	s_mov_b32 m0, s26
	v_readfirstlane_b32 s26, v106
	global_load_lds_dwordx4 v[0:1], off
	v_add_u32_e32 v0, v2, v105
	v_ashrrev_i32_e32 v1, 31, v0
	v_lshlrev_b64 v[0:1], 11, v[0:1]
	v_lshl_add_u64 v[0:1], v[70:71], 0, v[0:1]
	s_mov_b32 m0, s26
	v_readfirstlane_b32 s26, v131
	global_load_lds_dwordx4 v[0:1], off
	v_add_u32_e32 v0, s25, v107
	v_ashrrev_i32_e32 v1, 31, v0
	v_lshlrev_b64 v[0:1], 11, v[0:1]
	v_lshl_add_u64 v[0:1], v[66:67], 0, v[0:1]
	s_mov_b32 m0, s26
	v_add_u32_e32 v3, 0x400, v106
	global_load_lds_dwordx4 v[0:1], off
	v_add_u32_e32 v0, v2, v107
	v_ashrrev_i32_e32 v1, 31, v0
	v_lshlrev_b64 v[0:1], 11, v[0:1]
	v_readfirstlane_b32 s26, v3
	v_lshl_add_u64 v[0:1], v[72:73], 0, v[0:1]
	s_mov_b32 m0, s26
	v_readfirstlane_b32 s26, v132
	global_load_lds_dwordx4 v[0:1], off
	v_add_u32_e32 v0, s25, v109
	v_ashrrev_i32_e32 v1, 31, v0
	v_lshlrev_b64 v[0:1], 11, v[0:1]
	v_lshl_add_u64 v[0:1], v[64:65], 0, v[0:1]
	s_mov_b32 m0, s26
	v_add_u32_e32 v3, 0x800, v106
	global_load_lds_dwordx4 v[0:1], off
	v_add_u32_e32 v0, v2, v109
	v_ashrrev_i32_e32 v1, 31, v0
	v_lshlrev_b64 v[0:1], 11, v[0:1]
	v_readfirstlane_b32 s26, v3
	v_lshl_add_u64 v[0:1], v[70:71], 0, v[0:1]
	s_mov_b32 m0, s26
	v_readfirstlane_b32 s26, v133
	global_load_lds_dwordx4 v[0:1], off
	v_add_u32_e32 v0, s25, v111
	v_ashrrev_i32_e32 v1, 31, v0
	v_lshlrev_b64 v[0:1], 11, v[0:1]
	v_lshl_add_u64 v[0:1], v[68:69], 0, v[0:1]
	s_mov_b32 m0, s26
	s_mov_b32 s27, 0
	global_load_lds_dwordx4 v[0:1], off
	v_add_u32_e32 v0, v2, v111
	v_ashrrev_i32_e32 v1, 31, v0
	v_add_u32_e32 v2, 0xc00, v106
	v_lshlrev_b64 v[0:1], 11, v[0:1]
	v_readfirstlane_b32 s26, v2
	v_lshl_add_u64 v[0:1], v[74:75], 0, v[0:1]
	s_mov_b32 m0, s26
	s_lshl_b32 s26, s16, 7
	global_load_lds_dwordx4 v[0:1], off
	v_subrev_u32_e32 v0, s17, v121
	v_ashrrev_i32_e32 v1, 31, v0
	v_lshlrev_b64 v[0:1], 11, v[0:1]
	v_lshl_add_u64 v[88:89], v[76:77], 0, v[0:1]
	v_add_u32_e32 v0, s26, v122
	v_ashrrev_i32_e32 v1, 31, v0
	v_lshlrev_b64 v[0:1], 11, v[0:1]
	v_lshl_add_u64 v[90:91], v[78:79], 0, v[0:1]
	v_subrev_u32_e32 v0, s17, v123
	v_ashrrev_i32_e32 v1, 31, v0
	v_lshlrev_b64 v[0:1], 11, v[0:1]
	v_lshl_add_u64 v[92:93], v[80:81], 0, v[0:1]
	v_add_u32_e32 v0, s26, v124
	v_ashrrev_i32_e32 v1, 31, v0
	v_lshlrev_b64 v[0:1], 11, v[0:1]
	v_lshl_add_u64 v[94:95], v[82:83], 0, v[0:1]
	v_subrev_u32_e32 v0, s17, v125
	v_ashrrev_i32_e32 v1, 31, v0
	v_lshlrev_b64 v[0:1], 11, v[0:1]
	v_lshl_add_u64 v[96:97], v[76:77], 0, v[0:1]
	v_add_u32_e32 v0, s26, v126
	v_ashrrev_i32_e32 v1, 31, v0
	v_lshlrev_b64 v[0:1], 11, v[0:1]
	v_lshl_add_u64 v[98:99], v[78:79], 0, v[0:1]
	v_subrev_u32_e32 v0, s17, v127
	v_ashrrev_i32_e32 v1, 31, v0
	v_lshlrev_b64 v[0:1], 11, v[0:1]
	v_lshl_add_u64 v[100:101], v[84:85], 0, v[0:1]
	v_add_u32_e32 v0, s26, v128
	v_ashrrev_i32_e32 v1, 31, v0
	v_lshlrev_b64 v[0:1], 11, v[0:1]
	v_lshl_add_u64 v[102:103], v[86:87], 0, v[0:1]
	v_mov_b32_e32 v0, 0
	s_mov_b64 s[16:17], 0
	v_mov_b32_e32 v1, v0
	v_mov_b32_e32 v2, v0
	v_mov_b32_e32 v3, v0
	v_mov_b32_e32 v4, v0
	v_mov_b32_e32 v5, v0
	v_mov_b32_e32 v6, v0
	v_mov_b32_e32 v7, v0
	v_mov_b32_e32 v8, v0
	v_mov_b32_e32 v9, v0
	v_mov_b32_e32 v10, v0
	v_mov_b32_e32 v11, v0
	v_mov_b32_e32 v12, v0
	v_mov_b32_e32 v13, v0
	v_mov_b32_e32 v14, v0
	v_mov_b32_e32 v15, v0
	v_mov_b32_e32 v16, v0
	v_mov_b32_e32 v17, v0
	v_mov_b32_e32 v18, v0
	v_mov_b32_e32 v19, v0
	v_mov_b32_e32 v20, v0
	v_mov_b32_e32 v21, v0
	v_mov_b32_e32 v22, v0
	v_mov_b32_e32 v23, v0
	v_mov_b32_e32 v24, v0
	v_mov_b32_e32 v25, v0
	v_mov_b32_e32 v26, v0
	v_mov_b32_e32 v27, v0
	v_mov_b32_e32 v28, v0
	v_mov_b32_e32 v29, v0
	v_mov_b32_e32 v30, v0
	v_mov_b32_e32 v31, v0
	s_waitcnt vmcnt(0)
	v_mov_b32_e32 v32, v0
	v_mov_b32_e32 v33, v0
	v_mov_b32_e32 v34, v0
	v_mov_b32_e32 v35, v0
	v_mov_b32_e32 v36, v0
	v_mov_b32_e32 v37, v0
	v_mov_b32_e32 v38, v0
	v_mov_b32_e32 v39, v0
	v_mov_b32_e32 v40, v0
	v_mov_b32_e32 v41, v0
	v_mov_b32_e32 v42, v0
	v_mov_b32_e32 v43, v0
	v_mov_b32_e32 v44, v0
	v_mov_b32_e32 v45, v0
	v_mov_b32_e32 v46, v0
	v_mov_b32_e32 v47, v0
	v_mov_b32_e32 v48, v0
	v_mov_b32_e32 v49, v0
	v_mov_b32_e32 v50, v0
	v_mov_b32_e32 v51, v0
	v_mov_b32_e32 v52, v0
	v_mov_b32_e32 v53, v0
	v_mov_b32_e32 v54, v0
	v_mov_b32_e32 v55, v0
	v_mov_b32_e32 v56, v0
	v_mov_b32_e32 v57, v0
	v_mov_b32_e32 v58, v0
	v_mov_b32_e32 v59, v0
	v_mov_b32_e32 v60, v0
	v_mov_b32_e32 v61, v0
	v_mov_b32_e32 v62, v0
	v_mov_b32_e32 v63, v0
	s_waitcnt lgkmcnt(0)
	s_barrier
	v_add3_u32 v186, 0, v134, v135
	v_add_u32_e32 v187, 0x4000, v186
	s_nop 0
	v_readfirstlane_b32 s82, v187
	v_lshl_add_u32 v187, v108, 1, 0
	s_nop 0
	v_readfirstlane_b32 s83, v186
	v_add3_u32 v187, v187, v135, s21
	s_nop 0
	v_readfirstlane_b32 s84, v187
	v_add_u32_e32 v187, 0x400, v186
	s_nop 0
	v_readfirstlane_b32 s85, v187
	v_lshl_add_u32 v187, v110, 1, 0
	v_add3_u32 v187, v187, v135, s21
	s_nop 0
	v_readfirstlane_b32 s86, v187
	v_add_u32_e32 v187, 0x800, v186
	s_nop 0
	v_readfirstlane_b32 s87, v187
	v_lshl_add_u32 v187, v112, 1, 0
	v_add3_u32 v187, v187, v135, s21
	s_nop 0
	v_readfirstlane_b32 s88, v187
	v_add_u32_e32 v186, 0xc00, v186
	s_nop 0
	v_readfirstlane_b32 s89, v186
	v_subrev_u32_e32 v188, s52, v88
	v_subrev_u32_e32 v189, s52, v90
	v_subrev_u32_e32 v190, s52, v92
	v_subrev_u32_e32 v191, s52, v94
	v_subrev_u32_e32 v192, s52, v96
	v_subrev_u32_e32 v193, s52, v98
	v_subrev_u32_e32 v194, s52, v100
	v_subrev_u32_e32 v195, s52, v102
	s_bitcmp1_b32 s32, 0
	s_cbranch_scc1 .Lxk_1823
.LBB0_1823:
	s_and_b32 s28, s27, 0x4000
	s_xor_b32 s29, s28, 0x4000
	s_lshl_b32 s29, s29, 1
	s_add_i32 s29, s29, 32
	s_add_u32 s90, s52, s16
	s_addc_u32 s91, s53, s17
	s_add_i32 m0, s29, s82
	s_lshl_b32 s28, s28, 1
	global_load_lds_dwordx4 v188, s[90:91]
	s_add_i32 m0, s29, s83
	s_add_i32 s28, s28, 32
	global_load_lds_dwordx4 v189, s[90:91]
	s_add_i32 m0, s29, s84
	v_add3_u32 v139, s28, v113, v136
	global_load_lds_dwordx4 v190, s[90:91]
	s_add_i32 m0, s29, s85
	v_add3_u32 v172, s28, v114, v136
	global_load_lds_dwordx4 v191, s[90:91]
	s_add_i32 m0, s29, s86
	v_add_u32_e32 v160, v139, v137
	global_load_lds_dwordx4 v192, s[90:91]
	s_add_i32 m0, s29, s87
	v_add_u32_e32 v168, v172, v137
	global_load_lds_dwordx4 v193, s[90:91]
	s_add_i32 m0, s29, s88
	s_addk_i32 s27, 0x4000
	global_load_lds_dwordx4 v194, s[90:91]
	s_add_i32 m0, s29, s89
	s_add_u32 s16, s16, 0x80
	s_addc_u32 s17, s17, 0
	global_load_lds_dwordx4 v195, s[90:91]
	ds_read_b128 v[140:143], v160
	ds_read_b128 v[148:151], v168 offset:16384
	ds_read_b128 v[152:155], v168 offset:18432
	ds_read_b128 v[164:167], v168 offset:20480
	ds_read_b128 v[168:171], v168 offset:22528
	ds_read_b128 v[144:147], v160 offset:2048
	ds_read_b128 v[156:159], v160 offset:4096
	ds_read_b128 v[160:163], v160 offset:6144
	v_add_u32_e32 v139, v139, v138
	v_add_u32_e32 v236, v172, v138
	ds_read_b128 v[204:207], v139
	ds_read_b128 v[208:211], v236 offset:16384
	ds_read_b128 v[212:215], v236 offset:18432
	ds_read_b128 v[216:219], v236 offset:20480
	ds_read_b128 v[220:223], v236 offset:22528
	ds_read_b128 v[224:227], v139 offset:2048
	ds_read_b128 v[228:231], v139 offset:4096
	ds_read_b128 v[232:235], v139 offset:6144
	s_setprio 1
	s_waitcnt lgkmcnt(11)
	v_mfma_f32_16x16x32_bf16 v[60:63], v[140:143], v[148:151], v[60:63]
	v_mfma_f32_16x16x32_bf16 v[56:59], v[140:143], v[152:155], v[56:59]
	v_mfma_f32_16x16x32_bf16 v[52:55], v[140:143], v[164:167], v[52:55]
	v_mfma_f32_16x16x32_bf16 v[48:51], v[140:143], v[168:171], v[48:51]
	s_waitcnt lgkmcnt(10)
	v_mfma_f32_16x16x32_bf16 v[44:47], v[144:147], v[148:151], v[44:47]
	v_mfma_f32_16x16x32_bf16 v[40:43], v[144:147], v[152:155], v[40:43]
	v_mfma_f32_16x16x32_bf16 v[36:39], v[144:147], v[164:167], v[36:39]
	v_mfma_f32_16x16x32_bf16 v[32:35], v[144:147], v[168:171], v[32:35]
	s_waitcnt lgkmcnt(9)
	v_mfma_f32_16x16x32_bf16 v[28:31], v[156:159], v[148:151], v[28:31]
	v_mfma_f32_16x16x32_bf16 v[24:27], v[156:159], v[152:155], v[24:27]
	v_mfma_f32_16x16x32_bf16 v[20:23], v[156:159], v[164:167], v[20:23]
	v_mfma_f32_16x16x32_bf16 v[16:19], v[156:159], v[168:171], v[16:19]
	s_waitcnt lgkmcnt(8)
	v_mfma_f32_16x16x32_bf16 v[12:15], v[160:163], v[148:151], v[12:15]
	v_mfma_f32_16x16x32_bf16 v[8:11], v[160:163], v[152:155], v[8:11]
	v_mfma_f32_16x16x32_bf16 v[4:7], v[160:163], v[164:167], v[4:7]
	v_mfma_f32_16x16x32_bf16 v[0:3], v[160:163], v[168:171], v[0:3]
	s_waitcnt lgkmcnt(3)
	v_mfma_f32_16x16x32_bf16 v[60:63], v[204:207], v[208:211], v[60:63]
	v_mfma_f32_16x16x32_bf16 v[56:59], v[204:207], v[212:215], v[56:59]
	v_mfma_f32_16x16x32_bf16 v[52:55], v[204:207], v[216:219], v[52:55]
	v_mfma_f32_16x16x32_bf16 v[48:51], v[204:207], v[220:223], v[48:51]
	s_waitcnt lgkmcnt(2)
	v_mfma_f32_16x16x32_bf16 v[44:47], v[224:227], v[208:211], v[44:47]
	v_mfma_f32_16x16x32_bf16 v[40:43], v[224:227], v[212:215], v[40:43]
	v_mfma_f32_16x16x32_bf16 v[36:39], v[224:227], v[216:219], v[36:39]
	v_mfma_f32_16x16x32_bf16 v[32:35], v[224:227], v[220:223], v[32:35]
	s_waitcnt lgkmcnt(1)
	v_mfma_f32_16x16x32_bf16 v[28:31], v[228:231], v[208:211], v[28:31]
	v_mfma_f32_16x16x32_bf16 v[24:27], v[228:231], v[212:215], v[24:27]
	v_mfma_f32_16x16x32_bf16 v[20:23], v[228:231], v[216:219], v[20:23]
	v_mfma_f32_16x16x32_bf16 v[16:19], v[228:231], v[220:223], v[16:19]
	s_waitcnt lgkmcnt(0)
	v_mfma_f32_16x16x32_bf16 v[12:15], v[232:235], v[208:211], v[12:15]
	v_mfma_f32_16x16x32_bf16 v[8:11], v[232:235], v[212:215], v[8:11]
	v_mfma_f32_16x16x32_bf16 v[4:7], v[232:235], v[216:219], v[4:7]
	v_mfma_f32_16x16x32_bf16 v[0:3], v[232:235], v[220:223], v[0:3]
	s_setprio 0
	s_cmpk_eq_i32 s16, 0x780
	s_waitcnt vmcnt(0)
	s_barrier
	s_cbranch_scc0 .LBB0_1823
	s_branch .Lxk_exit_1823
.Lxk_1823:
	s_and_b32 s28, s27, 0x4000
	s_xor_b32 s29, s28, 0x4000
	s_lshl_b32 s29, s29, 1
	s_add_i32 s29, s29, 32
	s_add_u32 s90, s52, s16
	s_addc_u32 s91, s53, s17
	s_add_i32 m0, s29, s82
	s_lshl_b32 s28, s28, 1
	global_load_lds_dwordx4 v188, s[90:91]
	s_add_i32 m0, s29, s83
	s_add_i32 s28, s28, 32
	global_load_lds_dwordx4 v189, s[90:91]
	s_add_i32 m0, s29, s84
	v_add3_u32 v139, s28, v113, v136
	global_load_lds_dwordx4 v190, s[90:91]
	s_add_i32 m0, s29, s85
	v_add3_u32 v172, s28, v114, v136
	global_load_lds_dwordx4 v191, s[90:91]
	s_add_i32 m0, s29, s86
	v_add_u32_e32 v160, v139, v137
	global_load_lds_dwordx4 v192, s[90:91]
	s_add_i32 m0, s29, s87
	v_add_u32_e32 v168, v172, v137
	global_load_lds_dwordx4 v193, s[90:91]
	s_add_i32 m0, s29, s88
	s_addk_i32 s27, 0x4000
	global_load_lds_dwordx4 v194, s[90:91]
	s_add_i32 m0, s29, s89
	s_add_u32 s16, s16, 0x80
	s_addc_u32 s17, s17, 0
	global_load_lds_dwordx4 v195, s[90:91]
	ds_read_b128 v[140:143], v160
	ds_read_b128 v[148:151], v168 offset:16384
	ds_read_b128 v[152:155], v168 offset:18432
	ds_read_b128 v[164:167], v168 offset:20480
	ds_read_b128 v[168:171], v168 offset:22528
	ds_read_b128 v[144:147], v160 offset:2048
	ds_read_b128 v[156:159], v160 offset:4096
	ds_read_b128 v[160:163], v160 offset:6144
	v_add_u32_e32 v139, v139, v138
	v_add_u32_e32 v236, v172, v138
	ds_read_b128 v[204:207], v139
	ds_read_b128 v[208:211], v236 offset:16384
	ds_read_b128 v[212:215], v236 offset:18432
	ds_read_b128 v[216:219], v236 offset:20480
	ds_read_b128 v[220:223], v236 offset:22528
	ds_read_b128 v[224:227], v139 offset:2048
	ds_read_b128 v[228:231], v139 offset:4096
	ds_read_b128 v[232:235], v139 offset:6144
	s_setprio 3
	s_waitcnt lgkmcnt(11)
	v_mfma_f32_16x16x32_bf16 v[60:63], v[140:143], v[148:151], v[60:63]
	v_mfma_f32_16x16x32_bf16 v[56:59], v[140:143], v[152:155], v[56:59]
	v_mfma_f32_16x16x32_bf16 v[52:55], v[140:143], v[164:167], v[52:55]
	v_mfma_f32_16x16x32_bf16 v[48:51], v[140:143], v[168:171], v[48:51]
	s_waitcnt lgkmcnt(10)
	v_mfma_f32_16x16x32_bf16 v[44:47], v[144:147], v[148:151], v[44:47]
	v_mfma_f32_16x16x32_bf16 v[40:43], v[144:147], v[152:155], v[40:43]
	v_mfma_f32_16x16x32_bf16 v[36:39], v[144:147], v[164:167], v[36:39]
	v_mfma_f32_16x16x32_bf16 v[32:35], v[144:147], v[168:171], v[32:35]
	s_waitcnt lgkmcnt(9)
	v_mfma_f32_16x16x32_bf16 v[28:31], v[156:159], v[148:151], v[28:31]
	v_mfma_f32_16x16x32_bf16 v[24:27], v[156:159], v[152:155], v[24:27]
	v_mfma_f32_16x16x32_bf16 v[20:23], v[156:159], v[164:167], v[20:23]
	v_mfma_f32_16x16x32_bf16 v[16:19], v[156:159], v[168:171], v[16:19]
	s_waitcnt lgkmcnt(8)
	v_mfma_f32_16x16x32_bf16 v[12:15], v[160:163], v[148:151], v[12:15]
	v_mfma_f32_16x16x32_bf16 v[8:11], v[160:163], v[152:155], v[8:11]
	v_mfma_f32_16x16x32_bf16 v[4:7], v[160:163], v[164:167], v[4:7]
	v_mfma_f32_16x16x32_bf16 v[0:3], v[160:163], v[168:171], v[0:3]
	s_waitcnt lgkmcnt(3)
	v_mfma_f32_16x16x32_bf16 v[60:63], v[204:207], v[208:211], v[60:63]
	v_mfma_f32_16x16x32_bf16 v[56:59], v[204:207], v[212:215], v[56:59]
	v_mfma_f32_16x16x32_bf16 v[52:55], v[204:207], v[216:219], v[52:55]
	v_mfma_f32_16x16x32_bf16 v[48:51], v[204:207], v[220:223], v[48:51]
	s_waitcnt lgkmcnt(2)
	v_mfma_f32_16x16x32_bf16 v[44:47], v[224:227], v[208:211], v[44:47]
	v_mfma_f32_16x16x32_bf16 v[40:43], v[224:227], v[212:215], v[40:43]
	v_mfma_f32_16x16x32_bf16 v[36:39], v[224:227], v[216:219], v[36:39]
	v_mfma_f32_16x16x32_bf16 v[32:35], v[224:227], v[220:223], v[32:35]
	s_waitcnt lgkmcnt(1)
	v_mfma_f32_16x16x32_bf16 v[28:31], v[228:231], v[208:211], v[28:31]
	v_mfma_f32_16x16x32_bf16 v[24:27], v[228:231], v[212:215], v[24:27]
	v_mfma_f32_16x16x32_bf16 v[20:23], v[228:231], v[216:219], v[20:23]
	v_mfma_f32_16x16x32_bf16 v[16:19], v[228:231], v[220:223], v[16:19]
	s_waitcnt lgkmcnt(0)
	v_mfma_f32_16x16x32_bf16 v[12:15], v[232:235], v[208:211], v[12:15]
	v_mfma_f32_16x16x32_bf16 v[8:11], v[232:235], v[212:215], v[8:11]
	v_mfma_f32_16x16x32_bf16 v[4:7], v[232:235], v[216:219], v[4:7]
	v_mfma_f32_16x16x32_bf16 v[0:3], v[232:235], v[220:223], v[0:3]
	s_setprio 2
	s_cmpk_eq_i32 s16, 0x780
	s_waitcnt vmcnt(0)
	s_barrier
	s_cbranch_scc0 .Lxk_1823
.Lxk_exit_1823:
	ds_read_b128 v[88:91], v117 offset:55296
	ds_read_b128 v[92:95], v117 offset:53248
	ds_read_b128 v[96:99], v118 offset:38912
	ds_read_b128 v[100:103], v118 offset:36864
	ds_read_b128 v[140:143], v117 offset:51200
	ds_read_b128 v[144:147], v117 offset:49152
	ds_read_b128 v[148:151], v118 offset:34816
	ds_read_b128 v[152:155], v118 offset:32768
	s_setprio 1
	s_waitcnt lgkmcnt(5)
	v_mfma_f32_16x16x32_bf16 v[4:7], v[96:99], v[92:95], v[4:7]
	v_mfma_f32_16x16x32_bf16 v[0:3], v[96:99], v[88:91], v[0:3]
	s_waitcnt lgkmcnt(0)
	v_mfma_f32_16x16x32_bf16 v[60:63], v[152:155], v[144:147], v[60:63]
	v_mfma_f32_16x16x32_bf16 v[56:59], v[152:155], v[140:143], v[56:59]
	v_mfma_f32_16x16x32_bf16 v[52:55], v[152:155], v[92:95], v[52:55]
	v_mfma_f32_16x16x32_bf16 v[48:51], v[152:155], v[88:91], v[48:51]
	v_mfma_f32_16x16x32_bf16 v[44:47], v[148:151], v[144:147], v[44:47]
	v_mfma_f32_16x16x32_bf16 v[40:43], v[148:151], v[140:143], v[40:43]
	v_mfma_f32_16x16x32_bf16 v[36:39], v[148:151], v[92:95], v[36:39]
	v_mfma_f32_16x16x32_bf16 v[32:35], v[148:151], v[88:91], v[32:35]
	v_mfma_f32_16x16x32_bf16 v[28:31], v[100:103], v[144:147], v[28:31]
	v_mfma_f32_16x16x32_bf16 v[24:27], v[100:103], v[140:143], v[24:27]
	v_mfma_f32_16x16x32_bf16 v[20:23], v[100:103], v[92:95], v[20:23]
	v_mfma_f32_16x16x32_bf16 v[16:19], v[100:103], v[88:91], v[16:19]
	v_mfma_f32_16x16x32_bf16 v[12:15], v[96:99], v[144:147], v[12:15]
	v_mfma_f32_16x16x32_bf16 v[8:11], v[96:99], v[140:143], v[8:11]
	s_setprio 0
	ds_read_b128 v[88:91], v119 offset:32768
	ds_read_b128 v[92:95], v119 offset:34816
	ds_read_b128 v[96:99], v120 offset:49152
	ds_read_b128 v[100:103], v120 offset:51200
	ds_read_b128 v[140:143], v119 offset:36864
	ds_read_b128 v[144:147], v119 offset:38912
	ds_read_b128 v[148:151], v120 offset:53248
	ds_read_b128 v[152:155], v120 offset:55296
	s_setprio 1
	s_waitcnt lgkmcnt(1)
	v_mfma_f32_16x16x32_bf16 v[4:7], v[144:147], v[148:151], v[4:7]
	s_waitcnt lgkmcnt(0)
	v_mfma_f32_16x16x32_bf16 v[0:3], v[144:147], v[152:155], v[0:3]
	v_mfma_f32_16x16x32_bf16 v[60:63], v[88:91], v[96:99], v[60:63]
	v_mfma_f32_16x16x32_bf16 v[56:59], v[88:91], v[100:103], v[56:59]
	v_mfma_f32_16x16x32_bf16 v[52:55], v[88:91], v[148:151], v[52:55]
	v_mfma_f32_16x16x32_bf16 v[48:51], v[88:91], v[152:155], v[48:51]
	v_mfma_f32_16x16x32_bf16 v[44:47], v[92:95], v[96:99], v[44:47]
	v_mfma_f32_16x16x32_bf16 v[40:43], v[92:95], v[100:103], v[40:43]
	v_mfma_f32_16x16x32_bf16 v[36:39], v[92:95], v[148:151], v[36:39]
	v_mfma_f32_16x16x32_bf16 v[32:35], v[92:95], v[152:155], v[32:35]
	v_mfma_f32_16x16x32_bf16 v[28:31], v[140:143], v[96:99], v[28:31]
	v_mfma_f32_16x16x32_bf16 v[24:27], v[140:143], v[100:103], v[24:27]
	v_mfma_f32_16x16x32_bf16 v[20:23], v[140:143], v[148:151], v[20:23]
	v_mfma_f32_16x16x32_bf16 v[16:19], v[140:143], v[152:155], v[16:19]
	v_mfma_f32_16x16x32_bf16 v[12:15], v[144:147], v[96:99], v[12:15]
	v_mfma_f32_16x16x32_bf16 v[8:11], v[144:147], v[100:103], v[8:11]
	s_setprio 0
	s_barrier
	ds_write2_b32 v115, v60, v56 offset1:16
	ds_write2_b32 v115, v61, v57 offset0:132 offset1:148
	v_add_u32_e32 v56, 0x400, v115
	ds_write2_b32 v56, v62, v58 offset0:8 offset1:24
	ds_write2_b32 v56, v63, v59 offset0:140 offset1:156
	ds_write2_b32 v115, v52, v48 offset0:32 offset1:48
	ds_write2_b32 v115, v53, v49 offset0:164 offset1:180
	ds_write2_b32 v56, v54, v50 offset0:40 offset1:56
	ds_write2_b32 v56, v55, v51 offset0:172 offset1:188
	v_add_u32_e32 v48, 0x2000, v115
	ds_write2_b32 v48, v44, v40 offset0:64 offset1:80
	ds_write2_b32 v48, v45, v41 offset0:196 offset1:212
	v_add_u32_e32 v40, 0x2400, v115
	ds_write2_b32 v40, v46, v42 offset0:72 offset1:88
	ds_write2_b32 v40, v47, v43 offset0:204 offset1:220
	ds_write2_b32 v48, v36, v32 offset0:96 offset1:112
	ds_write2_b32 v48, v37, v33 offset0:228 offset1:244
	ds_write2_b32 v40, v38, v34 offset0:104 offset1:120
	ds_write2_b32 v40, v39, v35 offset0:236 offset1:252
	v_add_u32_e32 v32, 0x4000, v115
	ds_write2_b32 v32, v28, v24 offset0:128 offset1:144
	v_add_u32_e32 v24, 0x4400, v115
	ds_write2_b32 v24, v29, v25 offset0:4 offset1:20
	ds_write2_b32 v24, v30, v26 offset0:136 offset1:152
	v_add_u32_e32 v25, 0x4800, v115
	ds_write2_b32 v25, v31, v27 offset0:12 offset1:28
	ds_write2_b32 v32, v20, v16 offset0:160 offset1:176
	ds_write2_b32 v24, v21, v17 offset0:36 offset1:52
	ds_write2_b32 v24, v22, v18 offset0:168 offset1:184
	ds_write2_b32 v25, v23, v19 offset0:44 offset1:60
	v_add_u32_e32 v16, 0x6000, v115
	ds_write2_b32 v16, v12, v8 offset0:192 offset1:208
	v_add_u32_e32 v8, 0x6400, v115
	ds_write2_b32 v8, v13, v9 offset0:68 offset1:84
	ds_write2_b32 v8, v14, v10 offset0:200 offset1:216
	v_add_u32_e32 v9, 0x6800, v115
	ds_write2_b32 v9, v15, v11 offset0:76 offset1:92
	ds_write2_b32 v16, v4, v0 offset0:224 offset1:240
	ds_write2_b32 v8, v5, v1 offset0:100 offset1:116
	ds_write2_b32 v8, v6, v2 offset0:232 offset1:248
	ds_write2_b32 v9, v7, v3 offset0:108 offset1:124
	v_or_b32_e32 v0, s25, v116
	v_ashrrev_i32_e32 v1, 31, v0
	v_lshlrev_b64 v[2:3], 2, v[0:1]
	v_lshl_add_u64 v[0:1], s[14:15], 0, v[2:3]
	v_lshl_add_u64 v[2:3], s[10:11], 0, v[2:3]
	v_add_u32_e32 v4, s26, v129
	s_mov_b32 s16, 0
	s_waitcnt lgkmcnt(0)
	s_barrier

.LBB0_1833:
	s_and_b32 s12, s18, 0x380
	v_add_lshl_u32 v70, v138, s12, 11
	v_lshl_add_u64 v[96:97], v[84:85], 0, v[70:71]
	v_add_lshl_u32 v70, v140, s12, 11
	v_lshl_add_u64 v[98:99], v[88:89], 0, v[70:71]
	v_add_lshl_u32 v70, v142, s12, 11
	s_lshl_b32 s24, s23, 7
	v_lshl_add_u64 v[100:101], v[84:85], 0, v[70:71]
	v_add_lshl_u32 v70, v144, s12, 11
	s_ashr_i32 s12, s23, 3
	s_and_b32 s24, s24, 0x380
	v_add_u32_e32 v2, 0x4000, v133
	v_lshl_add_u64 v[102:103], v[92:93], 0, v[70:71]
	s_add_i32 s13, s12, s17
	v_add_lshl_u32 v70, s24, v132, 11
	v_readfirstlane_b32 s25, v2
	s_lshl_b32 s13, s13, 7
	v_lshl_add_u64 v[0:1], v[72:73], 0, v[70:71]
	s_mov_b32 m0, s25
	v_readfirstlane_b32 s25, v133
	global_load_lds_dwordx4 v[0:1], off
	v_add_u32_e32 v0, s13, v132
	v_ashrrev_i32_e32 v1, 31, v0
	v_lshlrev_b64 v[0:1], 11, v[0:1]
	v_lshl_add_u64 v[0:1], v[78:79], 0, v[0:1]
	s_mov_b32 m0, s25
	v_add_lshl_u32 v70, s24, v119, 11
	v_readfirstlane_b32 s25, v148
	global_load_lds_dwordx4 v[0:1], off
	v_lshl_add_u64 v[0:1], v[74:75], 0, v[70:71]
	s_mov_b32 m0, s25
	v_add_u32_e32 v2, 0x400, v133
	global_load_lds_dwordx4 v[0:1], off
	v_add_u32_e32 v0, s13, v119
	v_ashrrev_i32_e32 v1, 31, v0
	v_lshlrev_b64 v[0:1], 11, v[0:1]
	v_readfirstlane_b32 s25, v2
	v_lshl_add_u64 v[0:1], v[80:81], 0, v[0:1]
	s_mov_b32 m0, s25
	v_add_lshl_u32 v70, s24, v120, 11
	v_readfirstlane_b32 s25, v149
	global_load_lds_dwordx4 v[0:1], off
	v_lshl_add_u64 v[0:1], v[72:73], 0, v[70:71]
	s_mov_b32 m0, s25
	v_add_u32_e32 v2, 0x800, v133
	global_load_lds_dwordx4 v[0:1], off
	v_add_u32_e32 v0, s13, v120
	v_ashrrev_i32_e32 v1, 31, v0
	v_lshlrev_b64 v[0:1], 11, v[0:1]
	v_readfirstlane_b32 s25, v2
	v_lshl_add_u64 v[0:1], v[78:79], 0, v[0:1]
	s_mov_b32 m0, s25
	v_add_lshl_u32 v70, s24, v118, 11
	v_readfirstlane_b32 s25, v150
	global_load_lds_dwordx4 v[0:1], off
	v_lshl_add_u64 v[0:1], v[76:77], 0, v[70:71]
	s_mov_b32 m0, s25
	v_add_u32_e32 v2, 0xc00, v133
	global_load_lds_dwordx4 v[0:1], off
	v_add_u32_e32 v0, s13, v118
	v_ashrrev_i32_e32 v1, 31, v0
	v_lshlrev_b64 v[0:1], 11, v[0:1]
	v_readfirstlane_b32 s13, v2
	v_lshl_add_u64 v[0:1], v[82:83], 0, v[0:1]
	s_mov_b32 m0, s13
	s_lshl_b32 s25, s12, 7
	global_load_lds_dwordx4 v[0:1], off
	v_add_u32_e32 v0, s25, v139
	v_ashrrev_i32_e32 v1, 31, v0
	v_lshlrev_b64 v[0:1], 11, v[0:1]
	v_lshl_add_u64 v[104:105], v[86:87], 0, v[0:1]
	v_add_u32_e32 v0, s25, v141
	v_ashrrev_i32_e32 v1, 31, v0
	v_lshlrev_b64 v[0:1], 11, v[0:1]
	v_lshl_add_u64 v[106:107], v[90:91], 0, v[0:1]
	v_add_u32_e32 v0, s25, v143
	v_ashrrev_i32_e32 v1, 31, v0
	v_lshlrev_b64 v[0:1], 11, v[0:1]
	v_lshl_add_u64 v[108:109], v[86:87], 0, v[0:1]
	v_add_u32_e32 v0, s25, v145
	v_ashrrev_i32_e32 v1, 31, v0
	v_lshlrev_b64 v[0:1], 11, v[0:1]
	v_lshl_add_u64 v[110:111], v[94:95], 0, v[0:1]
	s_mov_b64 s[12:13], 0
	s_mov_b32 s26, 0
	v_mov_b32_e32 v0, 0
	v_mov_b32_e32 v1, v71
	v_mov_b32_e32 v2, v71
	v_mov_b32_e32 v3, v71
	v_mov_b32_e32 v4, 0
	v_mov_b32_e32 v5, v71
	v_mov_b32_e32 v6, v71
	v_mov_b32_e32 v7, v71
	v_mov_b32_e32 v8, 0
	v_mov_b32_e32 v9, v71
	v_mov_b32_e32 v10, v71
	v_mov_b32_e32 v11, v71
	v_mov_b32_e32 v12, 0
	v_mov_b32_e32 v13, v71
	v_mov_b32_e32 v14, v71
	v_mov_b32_e32 v15, v71
	v_mov_b32_e32 v16, 0
	v_mov_b32_e32 v17, v71
	v_mov_b32_e32 v18, v71
	v_mov_b32_e32 v19, v71
	v_mov_b32_e32 v20, 0
	v_mov_b32_e32 v21, v71
	v_mov_b32_e32 v22, v71
	v_mov_b32_e32 v23, v71
	v_mov_b32_e32 v24, 0
	v_mov_b32_e32 v25, v71
	v_mov_b32_e32 v26, v71
	v_mov_b32_e32 v27, v71
	v_mov_b32_e32 v28, 0
	v_mov_b32_e32 v29, v71
	v_mov_b32_e32 v30, v71
	v_mov_b32_e32 v31, v71
	s_waitcnt vmcnt(0)
	v_mov_b32_e32 v32, 0
	v_mov_b32_e32 v33, v71
	v_mov_b32_e32 v34, v71
	v_mov_b32_e32 v35, v71
	v_mov_b32_e32 v36, 0
	v_mov_b32_e32 v37, v71
	v_mov_b32_e32 v38, v71
	v_mov_b32_e32 v39, v71
	v_mov_b32_e32 v40, 0
	v_mov_b32_e32 v41, v71
	v_mov_b32_e32 v42, v71
	v_mov_b32_e32 v43, v71
	v_mov_b32_e32 v44, 0
	v_mov_b32_e32 v45, v71
	v_mov_b32_e32 v46, v71
	v_mov_b32_e32 v47, v71
	v_mov_b32_e32 v48, 0
	v_mov_b32_e32 v49, v71
	v_mov_b32_e32 v50, v71
	v_mov_b32_e32 v51, v71
	v_mov_b32_e32 v52, 0
	v_mov_b32_e32 v53, v71
	v_mov_b32_e32 v54, v71
	v_mov_b32_e32 v55, v71
	v_mov_b32_e32 v56, 0
	v_mov_b32_e32 v57, v71
	v_mov_b32_e32 v58, v71
	v_mov_b32_e32 v59, v71
	v_mov_b32_e32 v60, 0
	v_mov_b32_e32 v61, v71
	v_mov_b32_e32 v62, v71
	v_mov_b32_e32 v63, v71
	s_waitcnt lgkmcnt(0)
	s_barrier
	v_lshlrev_b32_e32 v186, 1, v130
	v_lshlrev_b32_e32 v187, 1, v131
	v_add3_u32 v186, 0, v186, v187
	v_add_u32_e32 v188, 0x4000, v186
	s_nop 0
	v_readfirstlane_b32 s82, v188
	v_lshl_add_u32 v188, v123, 1, 0
	s_nop 0
	v_readfirstlane_b32 s83, v186
	v_add3_u32 v188, v188, v187, s19
	s_nop 0
	v_readfirstlane_b32 s84, v188
	v_add_u32_e32 v188, 0x400, v186
	s_nop 0
	v_readfirstlane_b32 s85, v188
	v_lshl_add_u32 v188, v121, 1, 0
	v_add3_u32 v188, v188, v187, s19
	s_nop 0
	v_readfirstlane_b32 s86, v188
	v_add_u32_e32 v188, 0x800, v186
	s_nop 0
	v_readfirstlane_b32 s87, v188
	v_lshl_add_u32 v188, v122, 1, 0
	v_add3_u32 v187, v188, v187, s19
	s_nop 0
	v_readfirstlane_b32 s88, v187
	v_add_u32_e32 v186, 0xc00, v186
	s_nop 0
	v_readfirstlane_b32 s89, v186
	v_subrev_u32_e32 v189, s52, v96
	v_subrev_u32_e32 v190, s52, v104
	v_subrev_u32_e32 v191, s52, v98
	v_subrev_u32_e32 v192, s52, v106
	v_subrev_u32_e32 v193, s52, v100
	v_subrev_u32_e32 v194, s52, v108
	v_subrev_u32_e32 v195, s52, v102
	v_subrev_u32_e32 v196, s52, v110
	s_bitcmp1_b32 s32, 0
	s_cbranch_scc1 .Lxk_1834
.LBB0_1834:
	s_and_b32 s27, s26, 0x4000
	s_xor_b32 s28, s27, 0x4000
	s_lshl_b32 s28, s28, 1
	s_add_i32 s28, s28, 32
	s_add_u32 s90, s52, s12
	s_addc_u32 s91, s53, s13
	s_add_i32 m0, s28, s82
	s_lshl_b32 s27, s27, 1
	global_load_lds_dwordx4 v189, s[90:91]
	s_add_i32 m0, s28, s83
	s_add_i32 s27, s27, 32
	global_load_lds_dwordx4 v190, s[90:91]
	s_add_i32 m0, s28, s84
	v_lshlrev_b32_e32 v70, 1, v129
	global_load_lds_dwordx4 v191, s[90:91]
	s_add_i32 m0, s28, s85
	v_add3_u32 v151, s27, v124, v70
	global_load_lds_dwordx4 v192, s[90:91]
	s_add_i32 m0, s28, s86
	v_add3_u32 v70, s27, v125, v70
	global_load_lds_dwordx4 v193, s[90:91]
	s_add_i32 m0, s28, s87
	v_lshlrev_b32_e32 v152, 1, v117
	global_load_lds_dwordx4 v194, s[90:91]
	s_add_i32 m0, s28, s88
	v_add_u32_e32 v172, v151, v152
	global_load_lds_dwordx4 v195, s[90:91]
	s_add_i32 m0, s28, s89
	v_add_u32_e32 v182, v70, v152
	global_load_lds_dwordx4 v196, s[90:91]
	ds_read_b128 v[152:155], v172
	ds_read_b128 v[160:163], v182 offset:16384
	ds_read_b128 v[164:167], v182 offset:18432
	ds_read_b128 v[176:179], v182 offset:20480
	ds_read_b128 v[182:185], v182 offset:22528
	ds_read_b128 v[156:159], v172 offset:2048
	ds_read_b128 v[168:171], v172 offset:4096
	ds_read_b128 v[172:175], v172 offset:6144
	v_lshlrev_b32_e32 v236, 1, v116
	v_add_u32_e32 v151, v151, v236
	v_add_u32_e32 v70, v70, v236
	ds_read_b128 v[204:207], v151
	ds_read_b128 v[208:211], v70 offset:16384
	ds_read_b128 v[212:215], v70 offset:18432
	ds_read_b128 v[216:219], v70 offset:20480
	ds_read_b128 v[220:223], v70 offset:22528
	ds_read_b128 v[224:227], v151 offset:2048
	ds_read_b128 v[228:231], v151 offset:4096
	ds_read_b128 v[232:235], v151 offset:6144
	s_setprio 1
	s_waitcnt lgkmcnt(11)
	v_mfma_f32_16x16x32_bf16 v[60:63], v[152:155], v[160:163], v[60:63]
	v_mfma_f32_16x16x32_bf16 v[56:59], v[152:155], v[164:167], v[56:59]
	v_mfma_f32_16x16x32_bf16 v[52:55], v[152:155], v[176:179], v[52:55]
	v_mfma_f32_16x16x32_bf16 v[48:51], v[152:155], v[182:185], v[48:51]
	s_waitcnt lgkmcnt(10)
	v_mfma_f32_16x16x32_bf16 v[44:47], v[156:159], v[160:163], v[44:47]
	v_mfma_f32_16x16x32_bf16 v[40:43], v[156:159], v[164:167], v[40:43]
	v_mfma_f32_16x16x32_bf16 v[36:39], v[156:159], v[176:179], v[36:39]
	v_mfma_f32_16x16x32_bf16 v[32:35], v[156:159], v[182:185], v[32:35]
	s_waitcnt lgkmcnt(9)
	v_mfma_f32_16x16x32_bf16 v[28:31], v[168:171], v[160:163], v[28:31]
	v_mfma_f32_16x16x32_bf16 v[24:27], v[168:171], v[164:167], v[24:27]
	v_mfma_f32_16x16x32_bf16 v[20:23], v[168:171], v[176:179], v[20:23]
	v_mfma_f32_16x16x32_bf16 v[16:19], v[168:171], v[182:185], v[16:19]
	s_waitcnt lgkmcnt(8)
	v_mfma_f32_16x16x32_bf16 v[12:15], v[172:175], v[160:163], v[12:15]
	v_mfma_f32_16x16x32_bf16 v[8:11], v[172:175], v[164:167], v[8:11]
	v_mfma_f32_16x16x32_bf16 v[4:7], v[172:175], v[176:179], v[4:7]
	v_mfma_f32_16x16x32_bf16 v[0:3], v[172:175], v[182:185], v[0:3]
	s_waitcnt lgkmcnt(3)
	v_mfma_f32_16x16x32_bf16 v[60:63], v[204:207], v[208:211], v[60:63]
	v_mfma_f32_16x16x32_bf16 v[56:59], v[204:207], v[212:215], v[56:59]
	v_mfma_f32_16x16x32_bf16 v[52:55], v[204:207], v[216:219], v[52:55]
	v_mfma_f32_16x16x32_bf16 v[48:51], v[204:207], v[220:223], v[48:51]
	s_waitcnt lgkmcnt(2)
	v_mfma_f32_16x16x32_bf16 v[44:47], v[224:227], v[208:211], v[44:47]
	v_mfma_f32_16x16x32_bf16 v[40:43], v[224:227], v[212:215], v[40:43]
	v_mfma_f32_16x16x32_bf16 v[36:39], v[224:227], v[216:219], v[36:39]
	v_mfma_f32_16x16x32_bf16 v[32:35], v[224:227], v[220:223], v[32:35]
	s_waitcnt lgkmcnt(1)
	v_mfma_f32_16x16x32_bf16 v[28:31], v[228:231], v[208:211], v[28:31]
	v_mfma_f32_16x16x32_bf16 v[24:27], v[228:231], v[212:215], v[24:27]
	v_mfma_f32_16x16x32_bf16 v[20:23], v[228:231], v[216:219], v[20:23]
	v_mfma_f32_16x16x32_bf16 v[16:19], v[228:231], v[220:223], v[16:19]
	s_waitcnt lgkmcnt(0)
	v_mfma_f32_16x16x32_bf16 v[12:15], v[232:235], v[208:211], v[12:15]
	v_mfma_f32_16x16x32_bf16 v[8:11], v[232:235], v[212:215], v[8:11]
	v_mfma_f32_16x16x32_bf16 v[4:7], v[232:235], v[216:219], v[4:7]
	v_mfma_f32_16x16x32_bf16 v[0:3], v[232:235], v[220:223], v[0:3]
	s_setprio 0
	s_add_u32 s12, s12, 0x80
	s_addc_u32 s13, s13, 0
	s_addk_i32 s26, 0x4000
	s_cmpk_eq_i32 s12, 0x780
	s_waitcnt vmcnt(0)
	s_barrier
	s_cbranch_scc0 .LBB0_1834
	s_branch .Lxk_exit_1834
.Lxk_1834:
	s_and_b32 s27, s26, 0x4000
	s_xor_b32 s28, s27, 0x4000
	s_lshl_b32 s28, s28, 1
	s_add_i32 s28, s28, 32
	s_add_u32 s90, s52, s12
	s_addc_u32 s91, s53, s13
	s_add_i32 m0, s28, s82
	s_lshl_b32 s27, s27, 1
	global_load_lds_dwordx4 v189, s[90:91]
	s_add_i32 m0, s28, s83
	s_add_i32 s27, s27, 32
	global_load_lds_dwordx4 v190, s[90:91]
	s_add_i32 m0, s28, s84
	v_lshlrev_b32_e32 v70, 1, v129
	global_load_lds_dwordx4 v191, s[90:91]
	s_add_i32 m0, s28, s85
	v_add3_u32 v151, s27, v124, v70
	global_load_lds_dwordx4 v192, s[90:91]
	s_add_i32 m0, s28, s86
	v_add3_u32 v70, s27, v125, v70
	global_load_lds_dwordx4 v193, s[90:91]
	s_add_i32 m0, s28, s87
	v_lshlrev_b32_e32 v152, 1, v117
	global_load_lds_dwordx4 v194, s[90:91]
	s_add_i32 m0, s28, s88
	v_add_u32_e32 v172, v151, v152
	global_load_lds_dwordx4 v195, s[90:91]
	s_add_i32 m0, s28, s89
	v_add_u32_e32 v182, v70, v152
	global_load_lds_dwordx4 v196, s[90:91]
	ds_read_b128 v[152:155], v172
	ds_read_b128 v[160:163], v182 offset:16384
	ds_read_b128 v[164:167], v182 offset:18432
	ds_read_b128 v[176:179], v182 offset:20480
	ds_read_b128 v[182:185], v182 offset:22528
	ds_read_b128 v[156:159], v172 offset:2048
	ds_read_b128 v[168:171], v172 offset:4096
	ds_read_b128 v[172:175], v172 offset:6144
	v_lshlrev_b32_e32 v236, 1, v116
	v_add_u32_e32 v151, v151, v236
	v_add_u32_e32 v70, v70, v236
	ds_read_b128 v[204:207], v151
	ds_read_b128 v[208:211], v70 offset:16384
	ds_read_b128 v[212:215], v70 offset:18432
	ds_read_b128 v[216:219], v70 offset:20480
	ds_read_b128 v[220:223], v70 offset:22528
	ds_read_b128 v[224:227], v151 offset:2048
	ds_read_b128 v[228:231], v151 offset:4096
	ds_read_b128 v[232:235], v151 offset:6144
	s_setprio 3
	s_waitcnt lgkmcnt(11)
	v_mfma_f32_16x16x32_bf16 v[60:63], v[152:155], v[160:163], v[60:63]
	v_mfma_f32_16x16x32_bf16 v[56:59], v[152:155], v[164:167], v[56:59]
	v_mfma_f32_16x16x32_bf16 v[52:55], v[152:155], v[176:179], v[52:55]
	v_mfma_f32_16x16x32_bf16 v[48:51], v[152:155], v[182:185], v[48:51]
	s_waitcnt lgkmcnt(10)
	v_mfma_f32_16x16x32_bf16 v[44:47], v[156:159], v[160:163], v[44:47]
	v_mfma_f32_16x16x32_bf16 v[40:43], v[156:159], v[164:167], v[40:43]
	v_mfma_f32_16x16x32_bf16 v[36:39], v[156:159], v[176:179], v[36:39]
	v_mfma_f32_16x16x32_bf16 v[32:35], v[156:159], v[182:185], v[32:35]
	s_waitcnt lgkmcnt(9)
	v_mfma_f32_16x16x32_bf16 v[28:31], v[168:171], v[160:163], v[28:31]
	v_mfma_f32_16x16x32_bf16 v[24:27], v[168:171], v[164:167], v[24:27]
	v_mfma_f32_16x16x32_bf16 v[20:23], v[168:171], v[176:179], v[20:23]
	v_mfma_f32_16x16x32_bf16 v[16:19], v[168:171], v[182:185], v[16:19]
	s_waitcnt lgkmcnt(8)
	v_mfma_f32_16x16x32_bf16 v[12:15], v[172:175], v[160:163], v[12:15]
	v_mfma_f32_16x16x32_bf16 v[8:11], v[172:175], v[164:167], v[8:11]
	v_mfma_f32_16x16x32_bf16 v[4:7], v[172:175], v[176:179], v[4:7]
	v_mfma_f32_16x16x32_bf16 v[0:3], v[172:175], v[182:185], v[0:3]
	s_waitcnt lgkmcnt(3)
	v_mfma_f32_16x16x32_bf16 v[60:63], v[204:207], v[208:211], v[60:63]
	v_mfma_f32_16x16x32_bf16 v[56:59], v[204:207], v[212:215], v[56:59]
	v_mfma_f32_16x16x32_bf16 v[52:55], v[204:207], v[216:219], v[52:55]
	v_mfma_f32_16x16x32_bf16 v[48:51], v[204:207], v[220:223], v[48:51]
	s_waitcnt lgkmcnt(2)
	v_mfma_f32_16x16x32_bf16 v[44:47], v[224:227], v[208:211], v[44:47]
	v_mfma_f32_16x16x32_bf16 v[40:43], v[224:227], v[212:215], v[40:43]
	v_mfma_f32_16x16x32_bf16 v[36:39], v[224:227], v[216:219], v[36:39]
	v_mfma_f32_16x16x32_bf16 v[32:35], v[224:227], v[220:223], v[32:35]
	s_waitcnt lgkmcnt(1)
	v_mfma_f32_16x16x32_bf16 v[28:31], v[228:231], v[208:211], v[28:31]
	v_mfma_f32_16x16x32_bf16 v[24:27], v[228:231], v[212:215], v[24:27]
	v_mfma_f32_16x16x32_bf16 v[20:23], v[228:231], v[216:219], v[20:23]
	v_mfma_f32_16x16x32_bf16 v[16:19], v[228:231], v[220:223], v[16:19]
	s_waitcnt lgkmcnt(0)
	v_mfma_f32_16x16x32_bf16 v[12:15], v[232:235], v[208:211], v[12:15]
	v_mfma_f32_16x16x32_bf16 v[8:11], v[232:235], v[212:215], v[8:11]
	v_mfma_f32_16x16x32_bf16 v[4:7], v[232:235], v[216:219], v[4:7]
	v_mfma_f32_16x16x32_bf16 v[0:3], v[232:235], v[220:223], v[0:3]
	s_setprio 2
	s_add_u32 s12, s12, 0x80
	s_addc_u32 s13, s13, 0
	s_addk_i32 s26, 0x4000
	s_cmpk_eq_i32 s12, 0x780
	s_waitcnt vmcnt(0)
	s_barrier
	s_cbranch_scc0 .Lxk_1834
.Lxk_exit_1834:
	ds_read_b128 v[96:99], v69 offset:32768
	ds_read_b128 v[100:103], v69 offset:34816
	ds_read_b128 v[104:107], v135 offset:49152
	ds_read_b128 v[108:111], v135 offset:51200
	ds_read_b128 v[152:155], v69 offset:36864
	ds_read_b128 v[156:159], v69 offset:38912
	ds_read_b128 v[160:163], v135 offset:53248
	ds_read_b128 v[164:167], v135 offset:55296
	s_setprio 1
	s_waitcnt lgkmcnt(1)
	v_mfma_f32_16x16x32_bf16 v[4:7], v[156:159], v[160:163], v[4:7]
	s_waitcnt lgkmcnt(0)
	v_mfma_f32_16x16x32_bf16 v[0:3], v[156:159], v[164:167], v[0:3]
	v_mfma_f32_16x16x32_bf16 v[60:63], v[96:99], v[104:107], v[60:63]
	v_mfma_f32_16x16x32_bf16 v[56:59], v[96:99], v[108:111], v[56:59]
	v_mfma_f32_16x16x32_bf16 v[52:55], v[96:99], v[160:163], v[52:55]
	v_mfma_f32_16x16x32_bf16 v[48:51], v[96:99], v[164:167], v[48:51]
	v_mfma_f32_16x16x32_bf16 v[44:47], v[100:103], v[104:107], v[44:47]
	v_mfma_f32_16x16x32_bf16 v[40:43], v[100:103], v[108:111], v[40:43]
	v_mfma_f32_16x16x32_bf16 v[36:39], v[100:103], v[160:163], v[36:39]
	v_mfma_f32_16x16x32_bf16 v[32:35], v[100:103], v[164:167], v[32:35]
	v_mfma_f32_16x16x32_bf16 v[28:31], v[152:155], v[104:107], v[28:31]
	v_mfma_f32_16x16x32_bf16 v[24:27], v[152:155], v[108:111], v[24:27]
	v_mfma_f32_16x16x32_bf16 v[20:23], v[152:155], v[160:163], v[20:23]
	v_mfma_f32_16x16x32_bf16 v[16:19], v[152:155], v[164:167], v[16:19]
	v_mfma_f32_16x16x32_bf16 v[12:15], v[156:159], v[104:107], v[12:15]
	v_mfma_f32_16x16x32_bf16 v[8:11], v[156:159], v[108:111], v[8:11]
	s_setprio 0
	ds_read_b128 v[96:99], v136 offset:32768
	ds_read_b128 v[100:103], v136 offset:34816
	ds_read_b128 v[104:107], v137 offset:49152
	ds_read_b128 v[108:111], v137 offset:51200
	ds_read_b128 v[152:155], v136 offset:36864
	ds_read_b128 v[156:159], v136 offset:38912
	ds_read_b128 v[160:163], v137 offset:53248
	ds_read_b128 v[164:167], v137 offset:55296
	s_setprio 1
	s_waitcnt lgkmcnt(1)
	v_mfma_f32_16x16x32_bf16 v[4:7], v[156:159], v[160:163], v[4:7]
	s_waitcnt lgkmcnt(0)
	v_mfma_f32_16x16x32_bf16 v[0:3], v[156:159], v[164:167], v[0:3]
	v_mfma_f32_16x16x32_bf16 v[60:63], v[96:99], v[104:107], v[60:63]
	v_mfma_f32_16x16x32_bf16 v[56:59], v[96:99], v[108:111], v[56:59]
	v_mfma_f32_16x16x32_bf16 v[52:55], v[96:99], v[160:163], v[52:55]
	v_mfma_f32_16x16x32_bf16 v[48:51], v[96:99], v[164:167], v[48:51]
	v_mfma_f32_16x16x32_bf16 v[44:47], v[100:103], v[104:107], v[44:47]
	v_mfma_f32_16x16x32_bf16 v[40:43], v[100:103], v[108:111], v[40:43]
	v_mfma_f32_16x16x32_bf16 v[36:39], v[100:103], v[160:163], v[36:39]
	v_mfma_f32_16x16x32_bf16 v[32:35], v[100:103], v[164:167], v[32:35]
	v_mfma_f32_16x16x32_bf16 v[28:31], v[152:155], v[104:107], v[28:31]
	v_mfma_f32_16x16x32_bf16 v[24:27], v[152:155], v[108:111], v[24:27]
	v_mfma_f32_16x16x32_bf16 v[20:23], v[152:155], v[160:163], v[20:23]
	v_mfma_f32_16x16x32_bf16 v[16:19], v[152:155], v[164:167], v[16:19]
	v_mfma_f32_16x16x32_bf16 v[12:15], v[156:159], v[104:107], v[12:15]
	v_mfma_f32_16x16x32_bf16 v[8:11], v[156:159], v[108:111], v[8:11]
	s_setprio 0
	s_barrier
	ds_write2_b32 v134, v60, v56 offset1:16
	ds_write2_b32 v134, v61, v57 offset0:132 offset1:148
	v_add_u32_e32 v56, 0x400, v134
	ds_write2_b32 v56, v62, v58 offset0:8 offset1:24
	ds_write2_b32 v56, v63, v59 offset0:140 offset1:156
	ds_write2_b32 v134, v52, v48 offset0:32 offset1:48
	ds_write2_b32 v134, v53, v49 offset0:164 offset1:180
	ds_write2_b32 v56, v54, v50 offset0:40 offset1:56
	ds_write2_b32 v56, v55, v51 offset0:172 offset1:188
	v_add_u32_e32 v48, 0x2000, v134
	ds_write2_b32 v48, v44, v40 offset0:64 offset1:80
	ds_write2_b32 v48, v45, v41 offset0:196 offset1:212
	v_add_u32_e32 v40, 0x2400, v134
	ds_write2_b32 v40, v46, v42 offset0:72 offset1:88
	ds_write2_b32 v40, v47, v43 offset0:204 offset1:220
	ds_write2_b32 v48, v36, v32 offset0:96 offset1:112
	ds_write2_b32 v48, v37, v33 offset0:228 offset1:244
	ds_write2_b32 v40, v38, v34 offset0:104 offset1:120
	ds_write2_b32 v40, v39, v35 offset0:236 offset1:252
	v_add_u32_e32 v32, 0x4000, v134
	ds_write2_b32 v32, v28, v24 offset0:128 offset1:144
	v_add_u32_e32 v24, 0x4400, v134
	ds_write2_b32 v24, v29, v25 offset0:4 offset1:20
	ds_write2_b32 v24, v30, v26 offset0:136 offset1:152
	v_add_u32_e32 v25, 0x4800, v134
	ds_write2_b32 v25, v31, v27 offset0:12 offset1:28
	ds_write2_b32 v32, v20, v16 offset0:160 offset1:176
	ds_write2_b32 v24, v21, v17 offset0:36 offset1:52
	ds_write2_b32 v24, v22, v18 offset0:168 offset1:184
	ds_write2_b32 v25, v23, v19 offset0:44 offset1:60
	v_add_u32_e32 v16, 0x6000, v134
	ds_write2_b32 v16, v12, v8 offset0:192 offset1:208
	v_add_u32_e32 v8, 0x6400, v134
	ds_write2_b32 v8, v13, v9 offset0:68 offset1:84
	ds_write2_b32 v8, v14, v10 offset0:200 offset1:216
	v_add_u32_e32 v9, 0x6800, v134
	ds_write2_b32 v9, v15, v11 offset0:76 offset1:92
	ds_write2_b32 v16, v4, v0 offset0:224 offset1:240
	ds_write2_b32 v8, v5, v1 offset0:100 offset1:116
	ds_write2_b32 v8, v6, v2 offset0:232 offset1:248
	ds_write2_b32 v9, v7, v3 offset0:108 offset1:124
	v_or_b32_e32 v0, s24, v113
	v_lshlrev_b32_e32 v70, 2, v0
	v_lshl_add_u64 v[0:1], s[14:15], 0, v[70:71]
	v_lshl_add_u64 v[2:3], s[10:11], 0, v[70:71]
	v_add_u32_e32 v4, s25, v146
	s_mov_b32 s12, 0
	s_waitcnt lgkmcnt(0)
	s_barrier

.LBB0_1997:
	s_ashr_i32 s12, s16, 31
	s_lshr_b32 s12, s12, 27
	s_add_i32 s12, s16, s12
	s_ashr_i32 s12, s12, 5
	s_lshl_b32 s17, s12, 7
	s_lshl_b32 s12, s12, 12
	s_lshl_b32 s13, s16, 7
	s_sub_i32 s18, s13, s12
	v_add_u32_e32 v0, s18, v106
	v_ashrrev_i32_e32 v1, 31, v0
	v_add_u32_e32 v2, 0x4000, v107
	v_lshlrev_b64 v[0:1], 11, v[0:1]
	v_readfirstlane_b32 s13, v2
	v_lshl_add_u64 v[0:1], v[66:67], 0, v[0:1]
	s_mov_b32 m0, s13
	v_readfirstlane_b32 s13, v107
	global_load_lds_dwordx4 v[0:1], off
	v_add_u32_e32 v0, s17, v106
	v_ashrrev_i32_e32 v1, 31, v0
	v_lshlrev_b64 v[0:1], 11, v[0:1]
	v_lshl_add_u64 v[2:3], v[72:73], 0, v[0:1]
	s_mov_b32 m0, s13
	v_readfirstlane_b32 s13, v130
	global_load_lds_dwordx4 v[2:3], off
	v_add_u32_e32 v2, s18, v108
	v_ashrrev_i32_e32 v3, 31, v2
	v_lshlrev_b64 v[2:3], 11, v[2:3]
	v_lshl_add_u64 v[2:3], v[68:69], 0, v[2:3]
	s_mov_b32 m0, s13
	v_add_u32_e32 v4, 0x400, v107
	global_load_lds_dwordx4 v[2:3], off
	v_add_u32_e32 v2, s17, v108
	v_ashrrev_i32_e32 v3, 31, v2
	v_lshlrev_b64 v[2:3], 11, v[2:3]
	v_readfirstlane_b32 s13, v4
	v_lshl_add_u64 v[2:3], v[74:75], 0, v[2:3]
	s_mov_b32 m0, s13
	v_readfirstlane_b32 s13, v131
	global_load_lds_dwordx4 v[2:3], off
	v_add_u32_e32 v2, s18, v110
	v_ashrrev_i32_e32 v3, 31, v2
	v_lshlrev_b64 v[2:3], 11, v[2:3]
	v_lshl_add_u64 v[2:3], v[66:67], 0, v[2:3]
	s_mov_b32 m0, s13
	v_add_u32_e32 v4, 0x800, v107
	global_load_lds_dwordx4 v[2:3], off
	v_add_u32_e32 v2, s17, v110
	v_ashrrev_i32_e32 v3, 31, v2
	v_lshlrev_b64 v[2:3], 11, v[2:3]
	v_readfirstlane_b32 s13, v4
	v_lshl_add_u64 v[2:3], v[72:73], 0, v[2:3]
	s_mov_b32 m0, s13
	v_readfirstlane_b32 s13, v132
	global_load_lds_dwordx4 v[2:3], off
	v_add_u32_e32 v2, s18, v112
	v_ashrrev_i32_e32 v3, 31, v2
	v_lshlrev_b64 v[2:3], 11, v[2:3]
	v_lshl_add_u64 v[2:3], v[70:71], 0, v[2:3]
	s_mov_b32 m0, s13
	v_add_u32_e32 v4, 0xc00, v107
	global_load_lds_dwordx4 v[2:3], off
	v_add_u32_e32 v2, s17, v112
	v_ashrrev_i32_e32 v3, 31, v2
	v_lshlrev_b64 v[2:3], 11, v[2:3]
	v_readfirstlane_b32 s13, v4
	v_lshl_add_u64 v[2:3], v[76:77], 0, v[2:3]
	s_mov_b32 m0, s13
	v_lshl_add_u64 v[92:93], v[80:81], 0, v[0:1]
	global_load_lds_dwordx4 v[2:3], off
	v_subrev_u32_e32 v0, s12, v123
	v_ashrrev_i32_e32 v1, 31, v0
	v_lshlrev_b64 v[0:1], 11, v[0:1]
	v_lshl_add_u64 v[94:95], v[82:83], 0, v[0:1]
	v_add_u32_e32 v0, s17, v124
	v_ashrrev_i32_e32 v1, 31, v0
	v_lshlrev_b64 v[0:1], 11, v[0:1]
	v_lshl_add_u64 v[96:97], v[84:85], 0, v[0:1]
	v_subrev_u32_e32 v0, s12, v125
	v_ashrrev_i32_e32 v1, 31, v0
	v_lshlrev_b64 v[0:1], 11, v[0:1]
	v_lshl_add_u64 v[98:99], v[78:79], 0, v[0:1]
	v_add_u32_e32 v0, s17, v126
	v_ashrrev_i32_e32 v1, 31, v0
	v_lshlrev_b64 v[0:1], 11, v[0:1]
	v_lshl_add_u64 v[100:101], v[80:81], 0, v[0:1]
	v_subrev_u32_e32 v0, s12, v64
	v_ashrrev_i32_e32 v1, 31, v0
	v_lshlrev_b64 v[0:1], 11, v[0:1]
	v_subrev_u32_e32 v2, s12, v122
	v_lshl_add_u64 v[102:103], v[86:87], 0, v[0:1]
	v_add_u32_e32 v0, s17, v127
	v_ashrrev_i32_e32 v3, 31, v2
	v_ashrrev_i32_e32 v1, 31, v0
	v_lshlrev_b64 v[2:3], 11, v[2:3]
	v_lshlrev_b64 v[0:1], 11, v[0:1]
	v_lshl_add_u64 v[90:91], v[78:79], 0, v[2:3]
	v_lshl_add_u64 v[104:105], v[88:89], 0, v[0:1]
	s_mov_b64 s[12:13], 0
	s_mov_b32 s19, 0
	v_mov_b32_e32 v0, 0
	v_mov_b32_e32 v1, v65
	v_mov_b32_e32 v2, v65
	v_mov_b32_e32 v3, v65
	v_mov_b32_e32 v4, 0
	v_mov_b32_e32 v5, v65
	v_mov_b32_e32 v6, v65
	v_mov_b32_e32 v7, v65
	v_mov_b32_e32 v8, 0
	v_mov_b32_e32 v9, v65
	v_mov_b32_e32 v10, v65
	v_mov_b32_e32 v11, v65
	v_mov_b32_e32 v12, 0
	v_mov_b32_e32 v13, v65
	v_mov_b32_e32 v14, v65
	v_mov_b32_e32 v15, v65
	v_mov_b32_e32 v16, 0
	v_mov_b32_e32 v17, v65
	v_mov_b32_e32 v18, v65
	v_mov_b32_e32 v19, v65
	v_mov_b32_e32 v20, 0
	v_mov_b32_e32 v21, v65
	v_mov_b32_e32 v22, v65
	v_mov_b32_e32 v23, v65
	v_mov_b32_e32 v24, 0
	v_mov_b32_e32 v25, v65
	v_mov_b32_e32 v26, v65
	v_mov_b32_e32 v27, v65
	v_mov_b32_e32 v28, 0
	v_mov_b32_e32 v29, v65
	v_mov_b32_e32 v30, v65
	v_mov_b32_e32 v31, v65
	v_mov_b32_e32 v32, 0
	v_mov_b32_e32 v33, v65
	v_mov_b32_e32 v34, v65
	v_mov_b32_e32 v35, v65
	v_mov_b32_e32 v36, 0
	v_mov_b32_e32 v37, v65
	v_mov_b32_e32 v38, v65
	v_mov_b32_e32 v39, v65
	v_mov_b32_e32 v40, 0
	v_mov_b32_e32 v41, v65
	v_mov_b32_e32 v42, v65
	v_mov_b32_e32 v43, v65
	v_mov_b32_e32 v44, 0
	v_mov_b32_e32 v45, v65
	v_mov_b32_e32 v46, v65
	v_mov_b32_e32 v47, v65
	v_mov_b32_e32 v48, 0
	v_mov_b32_e32 v49, v65
	v_mov_b32_e32 v50, v65
	v_mov_b32_e32 v51, v65
	v_mov_b32_e32 v52, 0
	v_mov_b32_e32 v53, v65
	v_mov_b32_e32 v54, v65
	v_mov_b32_e32 v55, v65
	v_mov_b32_e32 v56, 0
	v_mov_b32_e32 v57, v65
	v_mov_b32_e32 v58, v65
	v_mov_b32_e32 v59, v65
	v_mov_b32_e32 v60, 0
	v_mov_b32_e32 v61, v65
	v_mov_b32_e32 v62, v65
	v_mov_b32_e32 v63, v65
	s_waitcnt vmcnt(0) lgkmcnt(0)
	s_barrier
	v_add3_u32 v182, 0, v133, v134
	v_add_u32_e32 v183, 0x4000, v182
	s_nop 0
	v_readfirstlane_b32 s82, v183
	v_lshl_add_u32 v183, v109, 1, 0
	s_nop 0
	v_readfirstlane_b32 s83, v182
	v_add3_u32 v183, v183, v134, s15
	s_nop 0
	v_readfirstlane_b32 s84, v183
	v_add_u32_e32 v183, 0x400, v182
	s_nop 0
	v_readfirstlane_b32 s85, v183
	v_lshl_add_u32 v183, v111, 1, 0
	v_add3_u32 v183, v183, v134, s15
	s_nop 0
	v_readfirstlane_b32 s86, v183
	v_add_u32_e32 v183, 0x800, v182
	s_nop 0
	v_readfirstlane_b32 s87, v183
	v_lshl_add_u32 v183, v113, 1, 0
	v_add3_u32 v183, v183, v134, s15
	s_nop 0
	v_readfirstlane_b32 s88, v183
	v_add_u32_e32 v182, 0xc00, v182
	s_nop 0
	v_readfirstlane_b32 s89, v182
	v_subrev_u32_e32 v184, s52, v90
	v_subrev_u32_e32 v185, s52, v92
	v_subrev_u32_e32 v186, s52, v94
	v_subrev_u32_e32 v187, s52, v96
	v_subrev_u32_e32 v188, s52, v98
	v_subrev_u32_e32 v189, s52, v100
	v_subrev_u32_e32 v190, s52, v102
	v_subrev_u32_e32 v191, s52, v104
	s_bitcmp1_b32 s32, 0
	s_cbranch_scc1 .Lxk_1998
.LBB0_1998:
	s_and_b32 s20, s19, 0x4000
	s_xor_b32 s21, s20, 0x4000
	s_lshl_b32 s21, s21, 1
	s_add_i32 s21, s21, 32
	s_add_u32 s90, s52, s12
	s_addc_u32 s91, s53, s13
	s_add_i32 m0, s21, s82
	s_lshl_b32 s20, s20, 1
	global_load_lds_dwordx4 v184, s[90:91]
	s_add_i32 m0, s21, s83
	s_add_i32 s20, s20, 32
	global_load_lds_dwordx4 v185, s[90:91]
	s_add_i32 m0, s21, s84
	v_lshl_add_u32 v137, v114, 1, s20
	global_load_lds_dwordx4 v186, s[90:91]
	s_add_i32 m0, s21, s85
	v_lshl_add_u32 v170, v115, 1, s20
	global_load_lds_dwordx4 v187, s[90:91]
	s_add_i32 m0, s21, s86
	v_add_u32_e32 v158, v137, v135
	global_load_lds_dwordx4 v188, s[90:91]
	s_add_i32 m0, s21, s87
	v_add_u32_e32 v166, v170, v135
	global_load_lds_dwordx4 v189, s[90:91]
	s_add_i32 m0, s21, s88
	s_addk_i32 s19, 0x4000
	global_load_lds_dwordx4 v190, s[90:91]
	s_add_i32 m0, s21, s89
	s_add_u32 s12, s12, 0x80
	s_addc_u32 s13, s13, 0
	global_load_lds_dwordx4 v191, s[90:91]
	ds_read_b128 v[138:141], v158
	ds_read_b128 v[146:149], v166 offset:16384
	ds_read_b128 v[150:153], v166 offset:18432
	ds_read_b128 v[162:165], v166 offset:20480
	ds_read_b128 v[166:169], v166 offset:22528
	ds_read_b128 v[142:145], v158 offset:2048
	ds_read_b128 v[154:157], v158 offset:4096
	ds_read_b128 v[158:161], v158 offset:6144
	v_add_u32_e32 v137, v137, v136
	v_add_u32_e32 v236, v170, v136
	ds_read_b128 v[204:207], v137
	ds_read_b128 v[208:211], v236 offset:16384
	ds_read_b128 v[212:215], v236 offset:18432
	ds_read_b128 v[216:219], v236 offset:20480
	ds_read_b128 v[220:223], v236 offset:22528
	ds_read_b128 v[224:227], v137 offset:2048
	ds_read_b128 v[228:231], v137 offset:4096
	ds_read_b128 v[232:235], v137 offset:6144
	s_setprio 1
	s_waitcnt lgkmcnt(11)
	v_mfma_f32_16x16x32_bf16 v[60:63], v[138:141], v[146:149], v[60:63]
	v_mfma_f32_16x16x32_bf16 v[56:59], v[138:141], v[150:153], v[56:59]
	v_mfma_f32_16x16x32_bf16 v[52:55], v[138:141], v[162:165], v[52:55]
	v_mfma_f32_16x16x32_bf16 v[48:51], v[138:141], v[166:169], v[48:51]
	s_waitcnt lgkmcnt(10)
	v_mfma_f32_16x16x32_bf16 v[44:47], v[142:145], v[146:149], v[44:47]
	v_mfma_f32_16x16x32_bf16 v[40:43], v[142:145], v[150:153], v[40:43]
	v_mfma_f32_16x16x32_bf16 v[36:39], v[142:145], v[162:165], v[36:39]
	v_mfma_f32_16x16x32_bf16 v[32:35], v[142:145], v[166:169], v[32:35]
	s_waitcnt lgkmcnt(9)
	v_mfma_f32_16x16x32_bf16 v[28:31], v[154:157], v[146:149], v[28:31]
	v_mfma_f32_16x16x32_bf16 v[24:27], v[154:157], v[150:153], v[24:27]
	v_mfma_f32_16x16x32_bf16 v[20:23], v[154:157], v[162:165], v[20:23]
	v_mfma_f32_16x16x32_bf16 v[16:19], v[154:157], v[166:169], v[16:19]
	s_waitcnt lgkmcnt(8)
	v_mfma_f32_16x16x32_bf16 v[12:15], v[158:161], v[146:149], v[12:15]
	v_mfma_f32_16x16x32_bf16 v[8:11], v[158:161], v[150:153], v[8:11]
	v_mfma_f32_16x16x32_bf16 v[4:7], v[158:161], v[162:165], v[4:7]
	v_mfma_f32_16x16x32_bf16 v[0:3], v[158:161], v[166:169], v[0:3]
	s_waitcnt lgkmcnt(3)
	v_mfma_f32_16x16x32_bf16 v[60:63], v[204:207], v[208:211], v[60:63]
	v_mfma_f32_16x16x32_bf16 v[56:59], v[204:207], v[212:215], v[56:59]
	v_mfma_f32_16x16x32_bf16 v[52:55], v[204:207], v[216:219], v[52:55]
	v_mfma_f32_16x16x32_bf16 v[48:51], v[204:207], v[220:223], v[48:51]
	s_waitcnt lgkmcnt(2)
	v_mfma_f32_16x16x32_bf16 v[44:47], v[224:227], v[208:211], v[44:47]
	v_mfma_f32_16x16x32_bf16 v[40:43], v[224:227], v[212:215], v[40:43]
	v_mfma_f32_16x16x32_bf16 v[36:39], v[224:227], v[216:219], v[36:39]
	v_mfma_f32_16x16x32_bf16 v[32:35], v[224:227], v[220:223], v[32:35]
	s_waitcnt lgkmcnt(1)
	v_mfma_f32_16x16x32_bf16 v[28:31], v[228:231], v[208:211], v[28:31]
	v_mfma_f32_16x16x32_bf16 v[24:27], v[228:231], v[212:215], v[24:27]
	v_mfma_f32_16x16x32_bf16 v[20:23], v[228:231], v[216:219], v[20:23]
	v_mfma_f32_16x16x32_bf16 v[16:19], v[228:231], v[220:223], v[16:19]
	s_waitcnt lgkmcnt(0)
	v_mfma_f32_16x16x32_bf16 v[12:15], v[232:235], v[208:211], v[12:15]
	v_mfma_f32_16x16x32_bf16 v[8:11], v[232:235], v[212:215], v[8:11]
	v_mfma_f32_16x16x32_bf16 v[4:7], v[232:235], v[216:219], v[4:7]
	v_mfma_f32_16x16x32_bf16 v[0:3], v[232:235], v[220:223], v[0:3]
	s_setprio 0
	s_cmpk_eq_i32 s12, 0x780
	s_waitcnt vmcnt(0)
	s_barrier
	s_cbranch_scc0 .LBB0_1998
	s_branch .Lxk_exit_1998
.Lxk_1998:
	s_and_b32 s20, s19, 0x4000
	s_xor_b32 s21, s20, 0x4000
	s_lshl_b32 s21, s21, 1
	s_add_i32 s21, s21, 32
	s_add_u32 s90, s52, s12
	s_addc_u32 s91, s53, s13
	s_add_i32 m0, s21, s82
	s_lshl_b32 s20, s20, 1
	global_load_lds_dwordx4 v184, s[90:91]
	s_add_i32 m0, s21, s83
	s_add_i32 s20, s20, 32
	global_load_lds_dwordx4 v185, s[90:91]
	s_add_i32 m0, s21, s84
	v_lshl_add_u32 v137, v114, 1, s20
	global_load_lds_dwordx4 v186, s[90:91]
	s_add_i32 m0, s21, s85
	v_lshl_add_u32 v170, v115, 1, s20
	global_load_lds_dwordx4 v187, s[90:91]
	s_add_i32 m0, s21, s86
	v_add_u32_e32 v158, v137, v135
	global_load_lds_dwordx4 v188, s[90:91]
	s_add_i32 m0, s21, s87
	v_add_u32_e32 v166, v170, v135
	global_load_lds_dwordx4 v189, s[90:91]
	s_add_i32 m0, s21, s88
	s_addk_i32 s19, 0x4000
	global_load_lds_dwordx4 v190, s[90:91]
	s_add_i32 m0, s21, s89
	s_add_u32 s12, s12, 0x80
	s_addc_u32 s13, s13, 0
	global_load_lds_dwordx4 v191, s[90:91]
	ds_read_b128 v[138:141], v158
	ds_read_b128 v[146:149], v166 offset:16384
	ds_read_b128 v[150:153], v166 offset:18432
	ds_read_b128 v[162:165], v166 offset:20480
	ds_read_b128 v[166:169], v166 offset:22528
	ds_read_b128 v[142:145], v158 offset:2048
	ds_read_b128 v[154:157], v158 offset:4096
	ds_read_b128 v[158:161], v158 offset:6144
	v_add_u32_e32 v137, v137, v136
	v_add_u32_e32 v236, v170, v136
	ds_read_b128 v[204:207], v137
	ds_read_b128 v[208:211], v236 offset:16384
	ds_read_b128 v[212:215], v236 offset:18432
	ds_read_b128 v[216:219], v236 offset:20480
	ds_read_b128 v[220:223], v236 offset:22528
	ds_read_b128 v[224:227], v137 offset:2048
	ds_read_b128 v[228:231], v137 offset:4096
	ds_read_b128 v[232:235], v137 offset:6144
	s_setprio 3
	s_waitcnt lgkmcnt(11)
	v_mfma_f32_16x16x32_bf16 v[60:63], v[138:141], v[146:149], v[60:63]
	v_mfma_f32_16x16x32_bf16 v[56:59], v[138:141], v[150:153], v[56:59]
	v_mfma_f32_16x16x32_bf16 v[52:55], v[138:141], v[162:165], v[52:55]
	v_mfma_f32_16x16x32_bf16 v[48:51], v[138:141], v[166:169], v[48:51]
	s_waitcnt lgkmcnt(10)
	v_mfma_f32_16x16x32_bf16 v[44:47], v[142:145], v[146:149], v[44:47]
	v_mfma_f32_16x16x32_bf16 v[40:43], v[142:145], v[150:153], v[40:43]
	v_mfma_f32_16x16x32_bf16 v[36:39], v[142:145], v[162:165], v[36:39]
	v_mfma_f32_16x16x32_bf16 v[32:35], v[142:145], v[166:169], v[32:35]
	s_waitcnt lgkmcnt(9)
	v_mfma_f32_16x16x32_bf16 v[28:31], v[154:157], v[146:149], v[28:31]
	v_mfma_f32_16x16x32_bf16 v[24:27], v[154:157], v[150:153], v[24:27]
	v_mfma_f32_16x16x32_bf16 v[20:23], v[154:157], v[162:165], v[20:23]
	v_mfma_f32_16x16x32_bf16 v[16:19], v[154:157], v[166:169], v[16:19]
	s_waitcnt lgkmcnt(8)
	v_mfma_f32_16x16x32_bf16 v[12:15], v[158:161], v[146:149], v[12:15]
	v_mfma_f32_16x16x32_bf16 v[8:11], v[158:161], v[150:153], v[8:11]
	v_mfma_f32_16x16x32_bf16 v[4:7], v[158:161], v[162:165], v[4:7]
	v_mfma_f32_16x16x32_bf16 v[0:3], v[158:161], v[166:169], v[0:3]
	s_waitcnt lgkmcnt(3)
	v_mfma_f32_16x16x32_bf16 v[60:63], v[204:207], v[208:211], v[60:63]
	v_mfma_f32_16x16x32_bf16 v[56:59], v[204:207], v[212:215], v[56:59]
	v_mfma_f32_16x16x32_bf16 v[52:55], v[204:207], v[216:219], v[52:55]
	v_mfma_f32_16x16x32_bf16 v[48:51], v[204:207], v[220:223], v[48:51]
	s_waitcnt lgkmcnt(2)
	v_mfma_f32_16x16x32_bf16 v[44:47], v[224:227], v[208:211], v[44:47]
	v_mfma_f32_16x16x32_bf16 v[40:43], v[224:227], v[212:215], v[40:43]
	v_mfma_f32_16x16x32_bf16 v[36:39], v[224:227], v[216:219], v[36:39]
	v_mfma_f32_16x16x32_bf16 v[32:35], v[224:227], v[220:223], v[32:35]
	s_waitcnt lgkmcnt(1)
	v_mfma_f32_16x16x32_bf16 v[28:31], v[228:231], v[208:211], v[28:31]
	v_mfma_f32_16x16x32_bf16 v[24:27], v[228:231], v[212:215], v[24:27]
	v_mfma_f32_16x16x32_bf16 v[20:23], v[228:231], v[216:219], v[20:23]
	v_mfma_f32_16x16x32_bf16 v[16:19], v[228:231], v[220:223], v[16:19]
	s_waitcnt lgkmcnt(0)
	v_mfma_f32_16x16x32_bf16 v[12:15], v[232:235], v[208:211], v[12:15]
	v_mfma_f32_16x16x32_bf16 v[8:11], v[232:235], v[212:215], v[8:11]
	v_mfma_f32_16x16x32_bf16 v[4:7], v[232:235], v[216:219], v[4:7]
	v_mfma_f32_16x16x32_bf16 v[0:3], v[232:235], v[220:223], v[0:3]
	s_setprio 2
	s_cmpk_eq_i32 s12, 0x780
	s_waitcnt vmcnt(0)
	s_barrier
	s_cbranch_scc0 .Lxk_1998
.Lxk_exit_1998:
	ds_read_b128 v[90:93], v116 offset:55296
	ds_read_b128 v[94:97], v116 offset:53248
	ds_read_b128 v[98:101], v117 offset:38912
	ds_read_b128 v[102:105], v117 offset:36864
	ds_read_b128 v[138:141], v116 offset:51200
	ds_read_b128 v[142:145], v116 offset:49152
	ds_read_b128 v[146:149], v117 offset:34816
	ds_read_b128 v[150:153], v117 offset:32768
	s_setprio 1
	s_waitcnt lgkmcnt(5)
	v_mfma_f32_16x16x32_bf16 v[0:3], v[98:101], v[90:93], v[0:3]
	s_waitcnt lgkmcnt(0)
	v_mfma_f32_16x16x32_bf16 v[60:63], v[150:153], v[142:145], v[60:63]
	v_mfma_f32_16x16x32_bf16 v[56:59], v[150:153], v[138:141], v[56:59]
	v_mfma_f32_16x16x32_bf16 v[52:55], v[150:153], v[94:97], v[52:55]
	v_mfma_f32_16x16x32_bf16 v[48:51], v[150:153], v[90:93], v[48:51]
	v_mfma_f32_16x16x32_bf16 v[44:47], v[146:149], v[142:145], v[44:47]
	v_mfma_f32_16x16x32_bf16 v[40:43], v[146:149], v[138:141], v[40:43]
	v_mfma_f32_16x16x32_bf16 v[36:39], v[146:149], v[94:97], v[36:39]
	v_mfma_f32_16x16x32_bf16 v[32:35], v[146:149], v[90:93], v[32:35]
	v_mfma_f32_16x16x32_bf16 v[28:31], v[102:105], v[142:145], v[28:31]
	v_mfma_f32_16x16x32_bf16 v[24:27], v[102:105], v[138:141], v[24:27]
	v_mfma_f32_16x16x32_bf16 v[20:23], v[102:105], v[94:97], v[20:23]
	v_mfma_f32_16x16x32_bf16 v[16:19], v[102:105], v[90:93], v[16:19]
	v_mfma_f32_16x16x32_bf16 v[12:15], v[98:101], v[142:145], v[12:15]
	v_mfma_f32_16x16x32_bf16 v[8:11], v[98:101], v[138:141], v[8:11]
	v_mfma_f32_16x16x32_bf16 v[4:7], v[98:101], v[94:97], v[4:7]
	s_setprio 0
	ds_read_b128 v[90:93], v118 offset:32768
	ds_read_b128 v[94:97], v118 offset:34816
	ds_read_b128 v[98:101], v119 offset:49152
	ds_read_b128 v[102:105], v119 offset:51200
	ds_read_b128 v[138:141], v118 offset:36864
	ds_read_b128 v[142:145], v118 offset:38912
	ds_read_b128 v[146:149], v119 offset:53248
	ds_read_b128 v[150:153], v119 offset:55296
	s_setprio 1
	s_waitcnt lgkmcnt(0)
	v_mfma_f32_16x16x32_bf16 v[0:3], v[142:145], v[150:153], v[0:3]
	v_mfma_f32_16x16x32_bf16 v[60:63], v[90:93], v[98:101], v[60:63]
	v_mfma_f32_16x16x32_bf16 v[56:59], v[90:93], v[102:105], v[56:59]
	v_mfma_f32_16x16x32_bf16 v[52:55], v[90:93], v[146:149], v[52:55]
	v_mfma_f32_16x16x32_bf16 v[48:51], v[90:93], v[150:153], v[48:51]
	v_mfma_f32_16x16x32_bf16 v[44:47], v[94:97], v[98:101], v[44:47]
	v_mfma_f32_16x16x32_bf16 v[40:43], v[94:97], v[102:105], v[40:43]
	v_mfma_f32_16x16x32_bf16 v[36:39], v[94:97], v[146:149], v[36:39]
	v_mfma_f32_16x16x32_bf16 v[32:35], v[94:97], v[150:153], v[32:35]
	v_mfma_f32_16x16x32_bf16 v[28:31], v[138:141], v[98:101], v[28:31]
	v_mfma_f32_16x16x32_bf16 v[24:27], v[138:141], v[102:105], v[24:27]
	v_mfma_f32_16x16x32_bf16 v[20:23], v[138:141], v[146:149], v[20:23]
	v_mfma_f32_16x16x32_bf16 v[16:19], v[138:141], v[150:153], v[16:19]
	v_mfma_f32_16x16x32_bf16 v[12:15], v[142:145], v[98:101], v[12:15]
	v_mfma_f32_16x16x32_bf16 v[8:11], v[142:145], v[102:105], v[8:11]
	v_mfma_f32_16x16x32_bf16 v[4:7], v[142:145], v[146:149], v[4:7]
	s_setprio 0
	s_barrier
	ds_write2_b32 v120, v60, v56 offset1:16
	ds_write2_b32 v120, v61, v57 offset0:132 offset1:148
	v_add_u32_e32 v56, 0x400, v120
	ds_write2_b32 v56, v62, v58 offset0:8 offset1:24
	ds_write2_b32 v56, v63, v59 offset0:140 offset1:156
	ds_write2_b32 v120, v52, v48 offset0:32 offset1:48
	ds_write2_b32 v120, v53, v49 offset0:164 offset1:180
	ds_write2_b32 v56, v54, v50 offset0:40 offset1:56
	ds_write2_b32 v56, v55, v51 offset0:172 offset1:188
	v_add_u32_e32 v48, 0x2000, v120
	ds_write2_b32 v48, v44, v40 offset0:64 offset1:80
	ds_write2_b32 v48, v45, v41 offset0:196 offset1:212
	v_add_u32_e32 v40, 0x2400, v120
	ds_write2_b32 v40, v46, v42 offset0:72 offset1:88
	ds_write2_b32 v40, v47, v43 offset0:204 offset1:220
	ds_write2_b32 v48, v36, v32 offset0:96 offset1:112
	ds_write2_b32 v48, v37, v33 offset0:228 offset1:244
	ds_write2_b32 v40, v38, v34 offset0:104 offset1:120
	ds_write2_b32 v40, v39, v35 offset0:236 offset1:252
	v_add_u32_e32 v32, 0x4000, v120
	ds_write2_b32 v32, v28, v24 offset0:128 offset1:144
	v_add_u32_e32 v24, 0x4400, v120
	ds_write2_b32 v24, v29, v25 offset0:4 offset1:20
	ds_write2_b32 v24, v30, v26 offset0:136 offset1:152
	v_add_u32_e32 v25, 0x4800, v120
	ds_write2_b32 v25, v31, v27 offset0:12 offset1:28
	ds_write2_b32 v32, v20, v16 offset0:160 offset1:176
	ds_write2_b32 v24, v21, v17 offset0:36 offset1:52
	ds_write2_b32 v24, v22, v18 offset0:168 offset1:184
	ds_write2_b32 v25, v23, v19 offset0:44 offset1:60
	v_add_u32_e32 v16, 0x6000, v120
	ds_write2_b32 v16, v12, v8 offset0:192 offset1:208
	v_add_u32_e32 v8, 0x6400, v120
	ds_write2_b32 v8, v13, v9 offset0:68 offset1:84
	ds_write2_b32 v8, v14, v10 offset0:200 offset1:216
	v_add_u32_e32 v9, 0x6800, v120
	ds_write2_b32 v9, v15, v11 offset0:76 offset1:92
	ds_write2_b32 v16, v4, v0 offset0:224 offset1:240
	ds_write2_b32 v8, v5, v1 offset0:100 offset1:116
	ds_write2_b32 v8, v6, v2 offset0:232 offset1:248
	ds_write2_b32 v9, v7, v3 offset0:108 offset1:124
	v_or_b32_e32 v0, s18, v121
	v_ashrrev_i32_e32 v1, 31, v0
	v_lshl_add_u64 v[0:1], v[0:1], 1, s[6:7]
	v_add_u32_e32 v2, s17, v128
	s_mov_b32 s12, 0
	s_waitcnt lgkmcnt(0)
	s_barrier

.LBB0_2008:
	s_ashr_i32 s14, s9, 31
	s_lshr_b32 s14, s14, 29
	s_add_i32 s14, s9, s14
	s_ashr_i32 s15, s14, 3
	s_lshl_b32 s16, s15, 10
	s_lshl_b32 s9, s9, 7
	s_sub_i32 s14, s9, s16
	v_add_u32_e32 v0, s15, v104
	s_add_i32 s14, s14, s8
	v_lshlrev_b32_e32 v2, 7, v0
	v_add_u32_e32 v0, s14, v105
	v_ashrrev_i32_e32 v1, 31, v0
	v_add_u32_e32 v3, 0x4000, v106
	v_lshlrev_b64 v[0:1], 11, v[0:1]
	v_readfirstlane_b32 s17, v3
	v_lshl_add_u64 v[0:1], v[64:65], 0, v[0:1]
	s_mov_b32 m0, s17
	v_readfirstlane_b32 s17, v106
	global_load_lds_dwordx4 v[0:1], off
	v_add_u32_e32 v0, v2, v105
	v_ashrrev_i32_e32 v1, 31, v0
	v_lshlrev_b64 v[0:1], 11, v[0:1]
	v_lshl_add_u64 v[0:1], v[70:71], 0, v[0:1]
	s_mov_b32 m0, s17
	v_readfirstlane_b32 s17, v130
	global_load_lds_dwordx4 v[0:1], off
	v_add_u32_e32 v0, s14, v107
	v_ashrrev_i32_e32 v1, 31, v0
	v_lshlrev_b64 v[0:1], 11, v[0:1]
	v_lshl_add_u64 v[0:1], v[66:67], 0, v[0:1]
	s_mov_b32 m0, s17
	v_add_u32_e32 v3, 0x400, v106
	global_load_lds_dwordx4 v[0:1], off
	v_add_u32_e32 v0, v2, v107
	v_ashrrev_i32_e32 v1, 31, v0
	v_lshlrev_b64 v[0:1], 11, v[0:1]
	v_readfirstlane_b32 s17, v3
	v_lshl_add_u64 v[0:1], v[72:73], 0, v[0:1]
	s_mov_b32 m0, s17
	v_readfirstlane_b32 s17, v131
	global_load_lds_dwordx4 v[0:1], off
	v_add_u32_e32 v0, s14, v109
	v_ashrrev_i32_e32 v1, 31, v0
	v_lshlrev_b64 v[0:1], 11, v[0:1]
	v_lshl_add_u64 v[0:1], v[64:65], 0, v[0:1]
	s_mov_b32 m0, s17
	v_add_u32_e32 v3, 0x800, v106
	global_load_lds_dwordx4 v[0:1], off
	v_add_u32_e32 v0, v2, v109
	v_ashrrev_i32_e32 v1, 31, v0
	v_lshlrev_b64 v[0:1], 11, v[0:1]
	v_readfirstlane_b32 s17, v3
	v_lshl_add_u64 v[0:1], v[70:71], 0, v[0:1]
	s_mov_b32 m0, s17
	v_readfirstlane_b32 s17, v132
	global_load_lds_dwordx4 v[0:1], off
	v_add_u32_e32 v0, s14, v111
	v_ashrrev_i32_e32 v1, 31, v0
	v_lshlrev_b64 v[0:1], 11, v[0:1]
	v_lshl_add_u64 v[0:1], v[68:69], 0, v[0:1]
	s_mov_b32 m0, s17
	s_add_i32 s9, s9, s8
	global_load_lds_dwordx4 v[0:1], off
	v_add_u32_e32 v0, v2, v111
	v_ashrrev_i32_e32 v1, 31, v0
	v_add_u32_e32 v2, 0xc00, v106
	v_lshlrev_b64 v[0:1], 11, v[0:1]
	v_readfirstlane_b32 s17, v2
	v_lshl_add_u64 v[0:1], v[74:75], 0, v[0:1]
	s_mov_b32 m0, s17
	s_lshl_b32 s15, s15, 7
	global_load_lds_dwordx4 v[0:1], off
	v_add_u32_e32 v0, s9, v105
	v_subrev_u32_e32 v0, s16, v0
	v_ashrrev_i32_e32 v1, 31, v0
	v_lshlrev_b64 v[0:1], 11, v[0:1]
	v_lshl_add_u64 v[88:89], v[76:77], 0, v[0:1]
	v_add_u32_e32 v0, s15, v121
	v_ashrrev_i32_e32 v1, 31, v0
	v_lshlrev_b64 v[0:1], 11, v[0:1]
	v_lshl_add_u64 v[90:91], v[78:79], 0, v[0:1]
	v_add_u32_e32 v0, s9, v122
	v_subrev_u32_e32 v0, s16, v0
	v_ashrrev_i32_e32 v1, 31, v0
	v_lshlrev_b64 v[0:1], 11, v[0:1]
	v_lshl_add_u64 v[92:93], v[80:81], 0, v[0:1]
	v_add_u32_e32 v0, s15, v123
	v_ashrrev_i32_e32 v1, 31, v0
	v_lshlrev_b64 v[0:1], 11, v[0:1]
	v_lshl_add_u64 v[94:95], v[82:83], 0, v[0:1]
	v_add_u32_e32 v0, s9, v124
	v_subrev_u32_e32 v0, s16, v0
	v_ashrrev_i32_e32 v1, 31, v0
	v_lshlrev_b64 v[0:1], 11, v[0:1]
	v_lshl_add_u64 v[96:97], v[76:77], 0, v[0:1]
	v_add_u32_e32 v0, s15, v125
	v_ashrrev_i32_e32 v1, 31, v0
	v_lshlrev_b64 v[0:1], 11, v[0:1]
	v_lshl_add_u64 v[98:99], v[78:79], 0, v[0:1]
	v_add_u32_e32 v0, s9, v126
	v_subrev_u32_e32 v0, s16, v0
	v_ashrrev_i32_e32 v1, 31, v0
	v_lshlrev_b64 v[0:1], 11, v[0:1]
	v_lshl_add_u64 v[100:101], v[84:85], 0, v[0:1]
	v_add_u32_e32 v0, s15, v127
	v_ashrrev_i32_e32 v1, 31, v0
	v_lshlrev_b64 v[0:1], 11, v[0:1]
	v_lshl_add_u64 v[102:103], v[86:87], 0, v[0:1]
	v_mov_b32_e32 v0, 0
	s_mov_b32 s16, 0
	s_mov_b64 s[8:9], 0
	v_mov_b32_e32 v1, v0
	v_mov_b32_e32 v2, v0
	v_mov_b32_e32 v3, v0
	v_mov_b32_e32 v4, v0
	v_mov_b32_e32 v5, v0
	v_mov_b32_e32 v6, v0
	v_mov_b32_e32 v7, v0
	v_mov_b32_e32 v8, v0
	v_mov_b32_e32 v9, v0
	v_mov_b32_e32 v10, v0
	v_mov_b32_e32 v11, v0
	v_mov_b32_e32 v12, v0
	v_mov_b32_e32 v13, v0
	v_mov_b32_e32 v14, v0
	v_mov_b32_e32 v15, v0
	v_mov_b32_e32 v16, v0
	v_mov_b32_e32 v17, v0
	v_mov_b32_e32 v18, v0
	v_mov_b32_e32 v19, v0
	v_mov_b32_e32 v20, v0
	v_mov_b32_e32 v21, v0
	v_mov_b32_e32 v22, v0
	v_mov_b32_e32 v23, v0
	v_mov_b32_e32 v24, v0
	v_mov_b32_e32 v25, v0
	v_mov_b32_e32 v26, v0
	v_mov_b32_e32 v27, v0
	v_mov_b32_e32 v28, v0
	v_mov_b32_e32 v29, v0
	v_mov_b32_e32 v30, v0
	v_mov_b32_e32 v31, v0
	v_mov_b32_e32 v32, v0
	v_mov_b32_e32 v33, v0
	v_mov_b32_e32 v34, v0
	v_mov_b32_e32 v35, v0
	v_mov_b32_e32 v36, v0
	v_mov_b32_e32 v37, v0
	v_mov_b32_e32 v38, v0
	v_mov_b32_e32 v39, v0
	v_mov_b32_e32 v40, v0
	v_mov_b32_e32 v41, v0
	v_mov_b32_e32 v42, v0
	v_mov_b32_e32 v43, v0
	v_mov_b32_e32 v44, v0
	v_mov_b32_e32 v45, v0
	v_mov_b32_e32 v46, v0
	v_mov_b32_e32 v47, v0
	v_mov_b32_e32 v48, v0
	v_mov_b32_e32 v49, v0
	v_mov_b32_e32 v50, v0
	v_mov_b32_e32 v51, v0
	v_mov_b32_e32 v52, v0
	v_mov_b32_e32 v53, v0
	v_mov_b32_e32 v54, v0
	v_mov_b32_e32 v55, v0
	v_mov_b32_e32 v56, v0
	v_mov_b32_e32 v57, v0
	v_mov_b32_e32 v58, v0
	v_mov_b32_e32 v59, v0
	v_mov_b32_e32 v60, v0
	v_mov_b32_e32 v61, v0
	v_mov_b32_e32 v62, v0
	v_mov_b32_e32 v63, v0
	s_waitcnt vmcnt(0) lgkmcnt(0)
	s_barrier
	v_add3_u32 v182, 0, v133, v134
	v_add_u32_e32 v183, 0x4000, v182
	s_nop 0
	v_readfirstlane_b32 s82, v183
	v_lshl_add_u32 v183, v108, 1, 0
	s_nop 0
	v_readfirstlane_b32 s83, v182
	v_add3_u32 v183, v183, v134, s11
	s_nop 0
	v_readfirstlane_b32 s84, v183
	v_add_u32_e32 v183, 0x400, v182
	s_nop 0
	v_readfirstlane_b32 s85, v183
	v_lshl_add_u32 v183, v110, 1, 0
	v_add3_u32 v183, v183, v134, s11
	s_nop 0
	v_readfirstlane_b32 s86, v183
	v_add_u32_e32 v183, 0x800, v182
	s_nop 0
	v_readfirstlane_b32 s87, v183
	v_lshl_add_u32 v183, v112, 1, 0
	v_add3_u32 v183, v183, v134, s11
	s_nop 0
	v_readfirstlane_b32 s88, v183
	v_add_u32_e32 v182, 0xc00, v182
	s_nop 0
	v_readfirstlane_b32 s89, v182
	v_subrev_u32_e32 v184, s52, v88
	v_subrev_u32_e32 v185, s52, v90
	v_subrev_u32_e32 v186, s52, v92
	v_subrev_u32_e32 v187, s52, v94
	v_subrev_u32_e32 v188, s52, v96
	v_subrev_u32_e32 v189, s52, v98
	v_subrev_u32_e32 v190, s52, v100
	v_subrev_u32_e32 v191, s52, v102
	s_bitcmp1_b32 s32, 0
	s_cbranch_scc1 .Lxk_2009
.LBB0_2009:
	s_and_b32 s17, s16, 0x4000
	s_xor_b32 s18, s17, 0x4000
	s_lshl_b32 s18, s18, 1
	s_add_i32 s18, s18, 32
	s_add_u32 s90, s52, s8
	s_addc_u32 s91, s53, s9
	s_add_i32 m0, s18, s82
	s_lshl_b32 s17, s17, 1
	global_load_lds_dwordx4 v184, s[90:91]
	s_add_i32 m0, s18, s83
	s_add_i32 s17, s17, 32
	global_load_lds_dwordx4 v185, s[90:91]
	s_add_i32 m0, s18, s84
	v_lshl_add_u32 v137, v113, 1, s17
	global_load_lds_dwordx4 v186, s[90:91]
	s_add_i32 m0, s18, s85
	v_lshl_add_u32 v170, v114, 1, s17
	global_load_lds_dwordx4 v187, s[90:91]
	s_add_i32 m0, s18, s86
	v_add_u32_e32 v158, v137, v135
	global_load_lds_dwordx4 v188, s[90:91]
	s_add_i32 m0, s18, s87
	v_add_u32_e32 v166, v170, v135
	global_load_lds_dwordx4 v189, s[90:91]
	s_add_i32 m0, s18, s88
	s_addk_i32 s16, 0x4000
	global_load_lds_dwordx4 v190, s[90:91]
	s_add_i32 m0, s18, s89
	s_add_u32 s8, s8, 0x80
	s_addc_u32 s9, s9, 0
	global_load_lds_dwordx4 v191, s[90:91]
	ds_read_b128 v[138:141], v158
	ds_read_b128 v[146:149], v166 offset:16384
	ds_read_b128 v[150:153], v166 offset:18432
	ds_read_b128 v[162:165], v166 offset:20480
	ds_read_b128 v[166:169], v166 offset:22528
	ds_read_b128 v[142:145], v158 offset:2048
	ds_read_b128 v[154:157], v158 offset:4096
	ds_read_b128 v[158:161], v158 offset:6144
	v_add_u32_e32 v137, v137, v136
	v_add_u32_e32 v236, v170, v136
	ds_read_b128 v[204:207], v137
	ds_read_b128 v[208:211], v236 offset:16384
	ds_read_b128 v[212:215], v236 offset:18432
	ds_read_b128 v[216:219], v236 offset:20480
	ds_read_b128 v[220:223], v236 offset:22528
	ds_read_b128 v[224:227], v137 offset:2048
	ds_read_b128 v[228:231], v137 offset:4096
	ds_read_b128 v[232:235], v137 offset:6144
	s_setprio 1
	s_waitcnt lgkmcnt(11)
	v_mfma_f32_16x16x32_bf16 v[60:63], v[138:141], v[146:149], v[60:63]
	v_mfma_f32_16x16x32_bf16 v[56:59], v[138:141], v[150:153], v[56:59]
	v_mfma_f32_16x16x32_bf16 v[52:55], v[138:141], v[162:165], v[52:55]
	v_mfma_f32_16x16x32_bf16 v[48:51], v[138:141], v[166:169], v[48:51]
	s_waitcnt lgkmcnt(10)
	v_mfma_f32_16x16x32_bf16 v[44:47], v[142:145], v[146:149], v[44:47]
	v_mfma_f32_16x16x32_bf16 v[40:43], v[142:145], v[150:153], v[40:43]
	v_mfma_f32_16x16x32_bf16 v[36:39], v[142:145], v[162:165], v[36:39]
	v_mfma_f32_16x16x32_bf16 v[32:35], v[142:145], v[166:169], v[32:35]
	s_waitcnt lgkmcnt(9)
	v_mfma_f32_16x16x32_bf16 v[28:31], v[154:157], v[146:149], v[28:31]
	v_mfma_f32_16x16x32_bf16 v[24:27], v[154:157], v[150:153], v[24:27]
	v_mfma_f32_16x16x32_bf16 v[20:23], v[154:157], v[162:165], v[20:23]
	v_mfma_f32_16x16x32_bf16 v[16:19], v[154:157], v[166:169], v[16:19]
	s_waitcnt lgkmcnt(8)
	v_mfma_f32_16x16x32_bf16 v[12:15], v[158:161], v[146:149], v[12:15]
	v_mfma_f32_16x16x32_bf16 v[8:11], v[158:161], v[150:153], v[8:11]
	v_mfma_f32_16x16x32_bf16 v[4:7], v[158:161], v[162:165], v[4:7]
	v_mfma_f32_16x16x32_bf16 v[0:3], v[158:161], v[166:169], v[0:3]
	s_waitcnt lgkmcnt(3)
	v_mfma_f32_16x16x32_bf16 v[60:63], v[204:207], v[208:211], v[60:63]
	v_mfma_f32_16x16x32_bf16 v[56:59], v[204:207], v[212:215], v[56:59]
	v_mfma_f32_16x16x32_bf16 v[52:55], v[204:207], v[216:219], v[52:55]
	v_mfma_f32_16x16x32_bf16 v[48:51], v[204:207], v[220:223], v[48:51]
	s_waitcnt lgkmcnt(2)
	v_mfma_f32_16x16x32_bf16 v[44:47], v[224:227], v[208:211], v[44:47]
	v_mfma_f32_16x16x32_bf16 v[40:43], v[224:227], v[212:215], v[40:43]
	v_mfma_f32_16x16x32_bf16 v[36:39], v[224:227], v[216:219], v[36:39]
	v_mfma_f32_16x16x32_bf16 v[32:35], v[224:227], v[220:223], v[32:35]
	s_waitcnt lgkmcnt(1)
	v_mfma_f32_16x16x32_bf16 v[28:31], v[228:231], v[208:211], v[28:31]
	v_mfma_f32_16x16x32_bf16 v[24:27], v[228:231], v[212:215], v[24:27]
	v_mfma_f32_16x16x32_bf16 v[20:23], v[228:231], v[216:219], v[20:23]
	v_mfma_f32_16x16x32_bf16 v[16:19], v[228:231], v[220:223], v[16:19]
	s_waitcnt lgkmcnt(0)
	v_mfma_f32_16x16x32_bf16 v[12:15], v[232:235], v[208:211], v[12:15]
	v_mfma_f32_16x16x32_bf16 v[8:11], v[232:235], v[212:215], v[8:11]
	v_mfma_f32_16x16x32_bf16 v[4:7], v[232:235], v[216:219], v[4:7]
	v_mfma_f32_16x16x32_bf16 v[0:3], v[232:235], v[220:223], v[0:3]
	s_setprio 0
	s_cmpk_eq_i32 s8, 0x780
	s_waitcnt vmcnt(0)
	s_barrier
	s_cbranch_scc0 .LBB0_2009
	s_branch .Lxk_exit_2009
.Lxk_2009:
	s_and_b32 s17, s16, 0x4000
	s_xor_b32 s18, s17, 0x4000
	s_lshl_b32 s18, s18, 1
	s_add_i32 s18, s18, 32
	s_add_u32 s90, s52, s8
	s_addc_u32 s91, s53, s9
	s_add_i32 m0, s18, s82
	s_lshl_b32 s17, s17, 1
	global_load_lds_dwordx4 v184, s[90:91]
	s_add_i32 m0, s18, s83
	s_add_i32 s17, s17, 32
	global_load_lds_dwordx4 v185, s[90:91]
	s_add_i32 m0, s18, s84
	v_lshl_add_u32 v137, v113, 1, s17
	global_load_lds_dwordx4 v186, s[90:91]
	s_add_i32 m0, s18, s85
	v_lshl_add_u32 v170, v114, 1, s17
	global_load_lds_dwordx4 v187, s[90:91]
	s_add_i32 m0, s18, s86
	v_add_u32_e32 v158, v137, v135
	global_load_lds_dwordx4 v188, s[90:91]
	s_add_i32 m0, s18, s87
	v_add_u32_e32 v166, v170, v135
	global_load_lds_dwordx4 v189, s[90:91]
	s_add_i32 m0, s18, s88
	s_addk_i32 s16, 0x4000
	global_load_lds_dwordx4 v190, s[90:91]
	s_add_i32 m0, s18, s89
	s_add_u32 s8, s8, 0x80
	s_addc_u32 s9, s9, 0
	global_load_lds_dwordx4 v191, s[90:91]
	ds_read_b128 v[138:141], v158
	ds_read_b128 v[146:149], v166 offset:16384
	ds_read_b128 v[150:153], v166 offset:18432
	ds_read_b128 v[162:165], v166 offset:20480
	ds_read_b128 v[166:169], v166 offset:22528
	ds_read_b128 v[142:145], v158 offset:2048
	ds_read_b128 v[154:157], v158 offset:4096
	ds_read_b128 v[158:161], v158 offset:6144
	v_add_u32_e32 v137, v137, v136
	v_add_u32_e32 v236, v170, v136
	ds_read_b128 v[204:207], v137
	ds_read_b128 v[208:211], v236 offset:16384
	ds_read_b128 v[212:215], v236 offset:18432
	ds_read_b128 v[216:219], v236 offset:20480
	ds_read_b128 v[220:223], v236 offset:22528
	ds_read_b128 v[224:227], v137 offset:2048
	ds_read_b128 v[228:231], v137 offset:4096
	ds_read_b128 v[232:235], v137 offset:6144
	s_setprio 3
	s_waitcnt lgkmcnt(11)
	v_mfma_f32_16x16x32_bf16 v[60:63], v[138:141], v[146:149], v[60:63]
	v_mfma_f32_16x16x32_bf16 v[56:59], v[138:141], v[150:153], v[56:59]
	v_mfma_f32_16x16x32_bf16 v[52:55], v[138:141], v[162:165], v[52:55]
	v_mfma_f32_16x16x32_bf16 v[48:51], v[138:141], v[166:169], v[48:51]
	s_waitcnt lgkmcnt(10)
	v_mfma_f32_16x16x32_bf16 v[44:47], v[142:145], v[146:149], v[44:47]
	v_mfma_f32_16x16x32_bf16 v[40:43], v[142:145], v[150:153], v[40:43]
	v_mfma_f32_16x16x32_bf16 v[36:39], v[142:145], v[162:165], v[36:39]
	v_mfma_f32_16x16x32_bf16 v[32:35], v[142:145], v[166:169], v[32:35]
	s_waitcnt lgkmcnt(9)
	v_mfma_f32_16x16x32_bf16 v[28:31], v[154:157], v[146:149], v[28:31]
	v_mfma_f32_16x16x32_bf16 v[24:27], v[154:157], v[150:153], v[24:27]
	v_mfma_f32_16x16x32_bf16 v[20:23], v[154:157], v[162:165], v[20:23]
	v_mfma_f32_16x16x32_bf16 v[16:19], v[154:157], v[166:169], v[16:19]
	s_waitcnt lgkmcnt(8)
	v_mfma_f32_16x16x32_bf16 v[12:15], v[158:161], v[146:149], v[12:15]
	v_mfma_f32_16x16x32_bf16 v[8:11], v[158:161], v[150:153], v[8:11]
	v_mfma_f32_16x16x32_bf16 v[4:7], v[158:161], v[162:165], v[4:7]
	v_mfma_f32_16x16x32_bf16 v[0:3], v[158:161], v[166:169], v[0:3]
	s_waitcnt lgkmcnt(3)
	v_mfma_f32_16x16x32_bf16 v[60:63], v[204:207], v[208:211], v[60:63]
	v_mfma_f32_16x16x32_bf16 v[56:59], v[204:207], v[212:215], v[56:59]
	v_mfma_f32_16x16x32_bf16 v[52:55], v[204:207], v[216:219], v[52:55]
	v_mfma_f32_16x16x32_bf16 v[48:51], v[204:207], v[220:223], v[48:51]
	s_waitcnt lgkmcnt(2)
	v_mfma_f32_16x16x32_bf16 v[44:47], v[224:227], v[208:211], v[44:47]
	v_mfma_f32_16x16x32_bf16 v[40:43], v[224:227], v[212:215], v[40:43]
	v_mfma_f32_16x16x32_bf16 v[36:39], v[224:227], v[216:219], v[36:39]
	v_mfma_f32_16x16x32_bf16 v[32:35], v[224:227], v[220:223], v[32:35]
	s_waitcnt lgkmcnt(1)
	v_mfma_f32_16x16x32_bf16 v[28:31], v[228:231], v[208:211], v[28:31]
	v_mfma_f32_16x16x32_bf16 v[24:27], v[228:231], v[212:215], v[24:27]
	v_mfma_f32_16x16x32_bf16 v[20:23], v[228:231], v[216:219], v[20:23]
	v_mfma_f32_16x16x32_bf16 v[16:19], v[228:231], v[220:223], v[16:19]
	s_waitcnt lgkmcnt(0)
	v_mfma_f32_16x16x32_bf16 v[12:15], v[232:235], v[208:211], v[12:15]
	v_mfma_f32_16x16x32_bf16 v[8:11], v[232:235], v[212:215], v[8:11]
	v_mfma_f32_16x16x32_bf16 v[4:7], v[232:235], v[216:219], v[4:7]
	v_mfma_f32_16x16x32_bf16 v[0:3], v[232:235], v[220:223], v[0:3]
	s_setprio 2
	s_cmpk_eq_i32 s8, 0x780
	s_waitcnt vmcnt(0)
	s_barrier
	s_cbranch_scc0 .Lxk_2009
.Lxk_exit_2009:
	ds_read_b128 v[88:91], v115 offset:55296
	ds_read_b128 v[92:95], v115 offset:53248
	ds_read_b128 v[96:99], v116 offset:38912
	ds_read_b128 v[100:103], v116 offset:36864
	ds_read_b128 v[138:141], v115 offset:51200
	ds_read_b128 v[142:145], v115 offset:49152
	ds_read_b128 v[146:149], v116 offset:34816
	ds_read_b128 v[150:153], v116 offset:32768
	s_setprio 1
	s_waitcnt lgkmcnt(5)
	v_mfma_f32_16x16x32_bf16 v[0:3], v[96:99], v[88:91], v[0:3]
	s_waitcnt lgkmcnt(0)
	v_mfma_f32_16x16x32_bf16 v[60:63], v[150:153], v[142:145], v[60:63]
	v_mfma_f32_16x16x32_bf16 v[56:59], v[150:153], v[138:141], v[56:59]
	v_mfma_f32_16x16x32_bf16 v[52:55], v[150:153], v[92:95], v[52:55]
	v_mfma_f32_16x16x32_bf16 v[48:51], v[150:153], v[88:91], v[48:51]
	v_mfma_f32_16x16x32_bf16 v[44:47], v[146:149], v[142:145], v[44:47]
	v_mfma_f32_16x16x32_bf16 v[40:43], v[146:149], v[138:141], v[40:43]
	v_mfma_f32_16x16x32_bf16 v[36:39], v[146:149], v[92:95], v[36:39]
	v_mfma_f32_16x16x32_bf16 v[32:35], v[146:149], v[88:91], v[32:35]
	v_mfma_f32_16x16x32_bf16 v[28:31], v[100:103], v[142:145], v[28:31]
	v_mfma_f32_16x16x32_bf16 v[24:27], v[100:103], v[138:141], v[24:27]
	v_mfma_f32_16x16x32_bf16 v[20:23], v[100:103], v[92:95], v[20:23]
	v_mfma_f32_16x16x32_bf16 v[16:19], v[100:103], v[88:91], v[16:19]
	v_mfma_f32_16x16x32_bf16 v[12:15], v[96:99], v[142:145], v[12:15]
	v_mfma_f32_16x16x32_bf16 v[8:11], v[96:99], v[138:141], v[8:11]
	v_mfma_f32_16x16x32_bf16 v[4:7], v[96:99], v[92:95], v[4:7]
	s_setprio 0
	ds_read_b128 v[88:91], v117 offset:32768
	ds_read_b128 v[92:95], v117 offset:34816
	ds_read_b128 v[96:99], v118 offset:49152
	ds_read_b128 v[100:103], v118 offset:51200
	ds_read_b128 v[138:141], v117 offset:36864
	ds_read_b128 v[142:145], v117 offset:38912
	ds_read_b128 v[146:149], v118 offset:53248
	ds_read_b128 v[150:153], v118 offset:55296
	s_setprio 1
	s_waitcnt lgkmcnt(0)
	v_mfma_f32_16x16x32_bf16 v[0:3], v[142:145], v[150:153], v[0:3]
	v_mfma_f32_16x16x32_bf16 v[60:63], v[88:91], v[96:99], v[60:63]
	v_mfma_f32_16x16x32_bf16 v[56:59], v[88:91], v[100:103], v[56:59]
	v_mfma_f32_16x16x32_bf16 v[52:55], v[88:91], v[146:149], v[52:55]
	v_mfma_f32_16x16x32_bf16 v[48:51], v[88:91], v[150:153], v[48:51]
	v_mfma_f32_16x16x32_bf16 v[44:47], v[92:95], v[96:99], v[44:47]
	v_mfma_f32_16x16x32_bf16 v[40:43], v[92:95], v[100:103], v[40:43]
	v_mfma_f32_16x16x32_bf16 v[36:39], v[92:95], v[146:149], v[36:39]
	v_mfma_f32_16x16x32_bf16 v[32:35], v[92:95], v[150:153], v[32:35]
	v_mfma_f32_16x16x32_bf16 v[28:31], v[138:141], v[96:99], v[28:31]
	v_mfma_f32_16x16x32_bf16 v[24:27], v[138:141], v[100:103], v[24:27]
	v_mfma_f32_16x16x32_bf16 v[20:23], v[138:141], v[146:149], v[20:23]
	v_mfma_f32_16x16x32_bf16 v[16:19], v[138:141], v[150:153], v[16:19]
	v_mfma_f32_16x16x32_bf16 v[12:15], v[142:145], v[96:99], v[12:15]
	v_mfma_f32_16x16x32_bf16 v[8:11], v[142:145], v[100:103], v[8:11]
	v_mfma_f32_16x16x32_bf16 v[4:7], v[142:145], v[146:149], v[4:7]
	s_setprio 0
	s_barrier
	ds_write2_b32 v119, v60, v56 offset1:16
	ds_write2_b32 v119, v61, v57 offset0:132 offset1:148
	v_add_u32_e32 v56, 0x400, v119
	ds_write2_b32 v56, v62, v58 offset0:8 offset1:24
	ds_write2_b32 v56, v63, v59 offset0:140 offset1:156
	ds_write2_b32 v119, v52, v48 offset0:32 offset1:48
	ds_write2_b32 v119, v53, v49 offset0:164 offset1:180
	ds_write2_b32 v56, v54, v50 offset0:40 offset1:56
	ds_write2_b32 v56, v55, v51 offset0:172 offset1:188
	v_add_u32_e32 v48, 0x2000, v119
	ds_write2_b32 v48, v44, v40 offset0:64 offset1:80
	ds_write2_b32 v48, v45, v41 offset0:196 offset1:212
	v_add_u32_e32 v40, 0x2400, v119
	ds_write2_b32 v40, v46, v42 offset0:72 offset1:88
	ds_write2_b32 v40, v47, v43 offset0:204 offset1:220
	ds_write2_b32 v48, v36, v32 offset0:96 offset1:112
	ds_write2_b32 v48, v37, v33 offset0:228 offset1:244
	ds_write2_b32 v40, v38, v34 offset0:104 offset1:120
	ds_write2_b32 v40, v39, v35 offset0:236 offset1:252
	v_add_u32_e32 v32, 0x4000, v119
	ds_write2_b32 v32, v28, v24 offset0:128 offset1:144
	v_add_u32_e32 v24, 0x4400, v119
	ds_write2_b32 v24, v29, v25 offset0:4 offset1:20
	ds_write2_b32 v24, v30, v26 offset0:136 offset1:152
	v_add_u32_e32 v25, 0x4800, v119
	ds_write2_b32 v25, v31, v27 offset0:12 offset1:28
	ds_write2_b32 v32, v20, v16 offset0:160 offset1:176
	ds_write2_b32 v24, v21, v17 offset0:36 offset1:52
	ds_write2_b32 v24, v22, v18 offset0:168 offset1:184
	ds_write2_b32 v25, v23, v19 offset0:44 offset1:60
	v_add_u32_e32 v16, 0x6000, v119
	ds_write2_b32 v16, v12, v8 offset0:192 offset1:208
	v_add_u32_e32 v8, 0x6400, v119
	ds_write2_b32 v8, v13, v9 offset0:68 offset1:84
	ds_write2_b32 v8, v14, v10 offset0:200 offset1:216
	v_add_u32_e32 v9, 0x6800, v119
	ds_write2_b32 v9, v15, v11 offset0:76 offset1:92
	ds_write2_b32 v16, v4, v0 offset0:224 offset1:240
	ds_write2_b32 v8, v5, v1 offset0:100 offset1:116
	ds_write2_b32 v8, v6, v2 offset0:232 offset1:248
	ds_write2_b32 v9, v7, v3 offset0:108 offset1:124
	v_or_b32_e32 v0, s14, v120
	v_ashrrev_i32_e32 v1, 31, v0
	v_lshl_add_u64 v[0:1], v[0:1], 1, s[6:7]
	v_add_u32_e32 v2, s15, v128
	s_mov_b32 s8, 0
	s_waitcnt lgkmcnt(0)
	s_barrier

.LBB0_2075:
	s_ashr_i32 s16, s23, 31
	s_lshr_b32 s16, s16, 29
	s_add_i32 s16, s23, s16
	s_ashr_i32 s16, s16, 3
	s_lshl_b32 s24, s16, 7
	s_lshl_b32 s16, s16, 10
	s_lshl_b32 s17, s23, 7
	s_sub_i32 s25, s17, s16
	v_add_u32_e32 v0, s25, v106
	v_ashrrev_i32_e32 v1, 31, v0
	v_add_u32_e32 v2, 0x4000, v107
	v_lshlrev_b64 v[0:1], 13, v[0:1]
	v_readfirstlane_b32 s17, v2
	v_lshl_add_u64 v[0:1], v[66:67], 0, v[0:1]
	s_mov_b32 m0, s17
	v_readfirstlane_b32 s17, v107
	global_load_lds_dwordx4 v[0:1], off
	v_add_u32_e32 v0, s24, v106
	v_ashrrev_i32_e32 v1, 31, v0
	v_lshlrev_b64 v[0:1], 13, v[0:1]
	v_lshl_add_u64 v[2:3], v[72:73], 0, v[0:1]
	s_mov_b32 m0, s17
	v_readfirstlane_b32 s17, v130
	global_load_lds_dwordx4 v[2:3], off
	v_add_u32_e32 v2, s25, v108
	v_ashrrev_i32_e32 v3, 31, v2
	v_lshlrev_b64 v[2:3], 13, v[2:3]
	v_lshl_add_u64 v[2:3], v[68:69], 0, v[2:3]
	s_mov_b32 m0, s17
	v_add_u32_e32 v4, 0x400, v107
	global_load_lds_dwordx4 v[2:3], off
	v_add_u32_e32 v2, s24, v108
	v_ashrrev_i32_e32 v3, 31, v2
	v_lshlrev_b64 v[2:3], 13, v[2:3]
	v_readfirstlane_b32 s17, v4
	v_lshl_add_u64 v[2:3], v[74:75], 0, v[2:3]
	s_mov_b32 m0, s17
	v_readfirstlane_b32 s17, v131
	global_load_lds_dwordx4 v[2:3], off
	v_add_u32_e32 v2, s25, v110
	v_ashrrev_i32_e32 v3, 31, v2
	v_lshlrev_b64 v[2:3], 13, v[2:3]
	v_lshl_add_u64 v[2:3], v[66:67], 0, v[2:3]
	s_mov_b32 m0, s17
	v_add_u32_e32 v4, 0x800, v107
	global_load_lds_dwordx4 v[2:3], off
	v_add_u32_e32 v2, s24, v110
	v_ashrrev_i32_e32 v3, 31, v2
	v_lshlrev_b64 v[2:3], 13, v[2:3]
	v_readfirstlane_b32 s17, v4
	v_lshl_add_u64 v[2:3], v[72:73], 0, v[2:3]
	s_mov_b32 m0, s17
	v_readfirstlane_b32 s17, v132
	global_load_lds_dwordx4 v[2:3], off
	v_add_u32_e32 v2, s25, v112
	v_ashrrev_i32_e32 v3, 31, v2
	v_lshlrev_b64 v[2:3], 13, v[2:3]
	v_lshl_add_u64 v[2:3], v[70:71], 0, v[2:3]
	s_mov_b32 m0, s17
	v_add_u32_e32 v4, 0xc00, v107
	global_load_lds_dwordx4 v[2:3], off
	v_add_u32_e32 v2, s24, v112
	v_ashrrev_i32_e32 v3, 31, v2
	v_lshlrev_b64 v[2:3], 13, v[2:3]
	v_readfirstlane_b32 s17, v4
	v_lshl_add_u64 v[2:3], v[76:77], 0, v[2:3]
	s_mov_b32 m0, s17
	v_lshl_add_u64 v[92:93], v[80:81], 0, v[0:1]
	global_load_lds_dwordx4 v[2:3], off
	v_subrev_u32_e32 v0, s16, v123
	v_ashrrev_i32_e32 v1, 31, v0
	v_lshlrev_b64 v[0:1], 13, v[0:1]
	v_lshl_add_u64 v[94:95], v[82:83], 0, v[0:1]
	v_add_u32_e32 v0, s24, v124
	v_ashrrev_i32_e32 v1, 31, v0
	v_lshlrev_b64 v[0:1], 13, v[0:1]
	v_lshl_add_u64 v[96:97], v[84:85], 0, v[0:1]
	v_subrev_u32_e32 v0, s16, v125
	v_ashrrev_i32_e32 v1, 31, v0
	v_lshlrev_b64 v[0:1], 13, v[0:1]
	v_lshl_add_u64 v[98:99], v[78:79], 0, v[0:1]
	v_add_u32_e32 v0, s24, v126
	v_ashrrev_i32_e32 v1, 31, v0
	v_lshlrev_b64 v[0:1], 13, v[0:1]
	v_lshl_add_u64 v[100:101], v[80:81], 0, v[0:1]
	v_subrev_u32_e32 v0, s16, v64
	v_ashrrev_i32_e32 v1, 31, v0
	v_lshlrev_b64 v[0:1], 13, v[0:1]
	v_subrev_u32_e32 v2, s16, v122
	v_lshl_add_u64 v[102:103], v[86:87], 0, v[0:1]
	v_add_u32_e32 v0, s24, v127
	v_ashrrev_i32_e32 v3, 31, v2
	v_ashrrev_i32_e32 v1, 31, v0
	v_lshlrev_b64 v[2:3], 13, v[2:3]
	v_lshlrev_b64 v[0:1], 13, v[0:1]
	v_lshl_add_u64 v[90:91], v[78:79], 0, v[2:3]
	v_lshl_add_u64 v[104:105], v[88:89], 0, v[0:1]
	s_mov_b32 s26, 0
	s_mov_b64 s[16:17], 0
	v_mov_b32_e32 v0, 0
	v_mov_b32_e32 v1, v65
	v_mov_b32_e32 v2, v65
	v_mov_b32_e32 v3, v65
	v_mov_b32_e32 v4, 0
	v_mov_b32_e32 v5, v65
	v_mov_b32_e32 v6, v65
	v_mov_b32_e32 v7, v65
	v_mov_b32_e32 v8, 0
	v_mov_b32_e32 v9, v65
	v_mov_b32_e32 v10, v65
	v_mov_b32_e32 v11, v65
	v_mov_b32_e32 v12, 0
	v_mov_b32_e32 v13, v65
	v_mov_b32_e32 v14, v65
	v_mov_b32_e32 v15, v65
	v_mov_b32_e32 v16, 0
	v_mov_b32_e32 v17, v65
	v_mov_b32_e32 v18, v65
	v_mov_b32_e32 v19, v65
	v_mov_b32_e32 v20, 0
	v_mov_b32_e32 v21, v65
	v_mov_b32_e32 v22, v65
	v_mov_b32_e32 v23, v65
	v_mov_b32_e32 v24, 0
	v_mov_b32_e32 v25, v65
	v_mov_b32_e32 v26, v65
	v_mov_b32_e32 v27, v65
	v_mov_b32_e32 v28, 0
	v_mov_b32_e32 v29, v65
	v_mov_b32_e32 v30, v65
	v_mov_b32_e32 v31, v65
	s_waitcnt vmcnt(0)
	v_mov_b32_e32 v32, 0
	v_mov_b32_e32 v33, v65
	v_mov_b32_e32 v34, v65
	v_mov_b32_e32 v35, v65
	v_mov_b32_e32 v36, 0
	v_mov_b32_e32 v37, v65
	v_mov_b32_e32 v38, v65
	v_mov_b32_e32 v39, v65
	v_mov_b32_e32 v40, 0
	v_mov_b32_e32 v41, v65
	v_mov_b32_e32 v42, v65
	v_mov_b32_e32 v43, v65
	v_mov_b32_e32 v44, 0
	v_mov_b32_e32 v45, v65
	v_mov_b32_e32 v46, v65
	v_mov_b32_e32 v47, v65
	v_mov_b32_e32 v48, 0
	v_mov_b32_e32 v49, v65
	v_mov_b32_e32 v50, v65
	v_mov_b32_e32 v51, v65
	v_mov_b32_e32 v52, 0
	v_mov_b32_e32 v53, v65
	v_mov_b32_e32 v54, v65
	v_mov_b32_e32 v55, v65
	v_mov_b32_e32 v56, 0
	v_mov_b32_e32 v57, v65
	v_mov_b32_e32 v58, v65
	v_mov_b32_e32 v59, v65
	v_mov_b32_e32 v60, 0
	v_mov_b32_e32 v61, v65
	v_mov_b32_e32 v62, v65
	v_mov_b32_e32 v63, v65
	s_waitcnt lgkmcnt(0)
	s_barrier
	v_add3_u32 v190, 0, v133, v134
	v_add_u32_e32 v191, 0x4000, v190
	s_nop 0
	v_readfirstlane_b32 s82, v191
	v_lshl_add_u32 v191, v109, 1, 0
	s_nop 0
	v_readfirstlane_b32 s83, v190
	v_add3_u32 v191, v191, v134, s19
	s_nop 0
	v_readfirstlane_b32 s84, v191
	v_add_u32_e32 v191, 0x400, v190
	s_nop 0
	v_readfirstlane_b32 s85, v191
	v_lshl_add_u32 v191, v111, 1, 0
	v_add3_u32 v191, v191, v134, s19
	s_nop 0
	v_readfirstlane_b32 s86, v191
	v_add_u32_e32 v191, 0x800, v190
	s_nop 0
	v_readfirstlane_b32 s87, v191
	v_lshl_add_u32 v191, v113, 1, 0
	v_add3_u32 v191, v191, v134, s19
	s_nop 0
	v_readfirstlane_b32 s88, v191
	v_add_u32_e32 v190, 0xc00, v190
	s_nop 0
	v_readfirstlane_b32 s89, v190
	v_subrev_u32_e32 v192, s52, v90
	v_subrev_u32_e32 v193, s52, v92
	v_subrev_u32_e32 v194, s52, v94
	v_subrev_u32_e32 v195, s52, v96
	v_subrev_u32_e32 v196, s52, v98
	v_subrev_u32_e32 v197, s52, v100
	v_subrev_u32_e32 v198, s52, v102
	v_subrev_u32_e32 v199, s52, v104
	s_bitcmp1_b32 s32, 0
	s_cbranch_scc1 .Lxk_2076
.LBB0_2076:
	s_and_b32 s27, s26, 0x4000
	s_xor_b32 s28, s27, 0x4000
	s_lshl_b32 s28, s28, 1
	s_add_i32 s28, s28, 32
	s_add_u32 s90, s52, s16
	s_addc_u32 s91, s53, s17
	s_add_i32 m0, s28, s82
	s_lshl_b32 s27, s27, 1
	global_load_lds_dwordx4 v192, s[90:91]
	s_add_i32 m0, s28, s83
	s_add_i32 s27, s27, 32
	global_load_lds_dwordx4 v193, s[90:91]
	s_add_i32 m0, s28, s84
	v_add3_u32 v170, s27, v114, v135
	global_load_lds_dwordx4 v194, s[90:91]
	s_add_i32 m0, s28, s85
	v_add3_u32 v171, s27, v115, v135
	global_load_lds_dwordx4 v195, s[90:91]
	s_add_i32 m0, s28, s86
	v_add_u32_e32 v158, v170, v136
	global_load_lds_dwordx4 v196, s[90:91]
	s_add_i32 m0, s28, s87
	v_add_u32_e32 v166, v171, v136
	global_load_lds_dwordx4 v197, s[90:91]
	s_add_i32 m0, s28, s88
	s_addk_i32 s26, 0x4000
	global_load_lds_dwordx4 v198, s[90:91]
	s_add_i32 m0, s28, s89
	s_add_u32 s16, s16, 0x80
	s_addc_u32 s17, s17, 0
	global_load_lds_dwordx4 v199, s[90:91]
	ds_read_b128 v[138:141], v158
	ds_read_b128 v[146:149], v166 offset:16384
	ds_read_b128 v[150:153], v166 offset:18432
	ds_read_b128 v[162:165], v166 offset:20480
	ds_read_b128 v[166:169], v166 offset:22528
	ds_read_b128 v[142:145], v158 offset:2048
	ds_read_b128 v[154:157], v158 offset:4096
	ds_read_b128 v[158:161], v158 offset:6144
	v_add_u32_e32 v236, v170, v137
	v_add_u32_e32 v237, v171, v137
	ds_read_b128 v[204:207], v236
	ds_read_b128 v[208:211], v237 offset:16384
	ds_read_b128 v[212:215], v237 offset:18432
	ds_read_b128 v[216:219], v237 offset:20480
	ds_read_b128 v[220:223], v237 offset:22528
	ds_read_b128 v[224:227], v236 offset:2048
	ds_read_b128 v[228:231], v236 offset:4096
	ds_read_b128 v[232:235], v236 offset:6144
	s_setprio 1
	s_waitcnt lgkmcnt(11)
	v_mfma_f32_16x16x32_bf16 v[60:63], v[138:141], v[146:149], v[60:63]
	v_mfma_f32_16x16x32_bf16 v[56:59], v[138:141], v[150:153], v[56:59]
	v_mfma_f32_16x16x32_bf16 v[52:55], v[138:141], v[162:165], v[52:55]
	v_mfma_f32_16x16x32_bf16 v[48:51], v[138:141], v[166:169], v[48:51]
	s_waitcnt lgkmcnt(10)
	v_mfma_f32_16x16x32_bf16 v[44:47], v[142:145], v[146:149], v[44:47]
	v_mfma_f32_16x16x32_bf16 v[40:43], v[142:145], v[150:153], v[40:43]
	v_mfma_f32_16x16x32_bf16 v[36:39], v[142:145], v[162:165], v[36:39]
	v_mfma_f32_16x16x32_bf16 v[32:35], v[142:145], v[166:169], v[32:35]
	s_waitcnt lgkmcnt(9)
	v_mfma_f32_16x16x32_bf16 v[28:31], v[154:157], v[146:149], v[28:31]
	v_mfma_f32_16x16x32_bf16 v[24:27], v[154:157], v[150:153], v[24:27]
	v_mfma_f32_16x16x32_bf16 v[20:23], v[154:157], v[162:165], v[20:23]
	v_mfma_f32_16x16x32_bf16 v[16:19], v[154:157], v[166:169], v[16:19]
	s_waitcnt lgkmcnt(8)
	v_mfma_f32_16x16x32_bf16 v[12:15], v[158:161], v[146:149], v[12:15]
	v_mfma_f32_16x16x32_bf16 v[8:11], v[158:161], v[150:153], v[8:11]
	v_mfma_f32_16x16x32_bf16 v[4:7], v[158:161], v[162:165], v[4:7]
	v_mfma_f32_16x16x32_bf16 v[0:3], v[158:161], v[166:169], v[0:3]
	s_waitcnt lgkmcnt(3)
	v_mfma_f32_16x16x32_bf16 v[60:63], v[204:207], v[208:211], v[60:63]
	v_mfma_f32_16x16x32_bf16 v[56:59], v[204:207], v[212:215], v[56:59]
	v_mfma_f32_16x16x32_bf16 v[52:55], v[204:207], v[216:219], v[52:55]
	v_mfma_f32_16x16x32_bf16 v[48:51], v[204:207], v[220:223], v[48:51]
	s_waitcnt lgkmcnt(2)
	v_mfma_f32_16x16x32_bf16 v[44:47], v[224:227], v[208:211], v[44:47]
	v_mfma_f32_16x16x32_bf16 v[40:43], v[224:227], v[212:215], v[40:43]
	v_mfma_f32_16x16x32_bf16 v[36:39], v[224:227], v[216:219], v[36:39]
	v_mfma_f32_16x16x32_bf16 v[32:35], v[224:227], v[220:223], v[32:35]
	s_waitcnt lgkmcnt(1)
	v_mfma_f32_16x16x32_bf16 v[28:31], v[228:231], v[208:211], v[28:31]
	v_mfma_f32_16x16x32_bf16 v[24:27], v[228:231], v[212:215], v[24:27]
	v_mfma_f32_16x16x32_bf16 v[20:23], v[228:231], v[216:219], v[20:23]
	v_mfma_f32_16x16x32_bf16 v[16:19], v[228:231], v[220:223], v[16:19]
	s_waitcnt lgkmcnt(0)
	v_mfma_f32_16x16x32_bf16 v[12:15], v[232:235], v[208:211], v[12:15]
	v_mfma_f32_16x16x32_bf16 v[8:11], v[232:235], v[212:215], v[8:11]
	v_mfma_f32_16x16x32_bf16 v[4:7], v[232:235], v[216:219], v[4:7]
	v_mfma_f32_16x16x32_bf16 v[0:3], v[232:235], v[220:223], v[0:3]
	s_setprio 0
	s_cmpk_eq_i32 s16, 0x1f80
	s_waitcnt vmcnt(0)
	s_barrier
	s_cbranch_scc0 .LBB0_2076
	s_branch .Lxk_exit_2076
.Lxk_2076:
	s_and_b32 s27, s26, 0x4000
	s_xor_b32 s28, s27, 0x4000
	s_lshl_b32 s28, s28, 1
	s_add_i32 s28, s28, 32
	s_add_u32 s90, s52, s16
	s_addc_u32 s91, s53, s17
	s_add_i32 m0, s28, s82
	s_lshl_b32 s27, s27, 1
	global_load_lds_dwordx4 v192, s[90:91]
	s_add_i32 m0, s28, s83
	s_add_i32 s27, s27, 32
	global_load_lds_dwordx4 v193, s[90:91]
	s_add_i32 m0, s28, s84
	v_add3_u32 v170, s27, v114, v135
	global_load_lds_dwordx4 v194, s[90:91]
	s_add_i32 m0, s28, s85
	v_add3_u32 v171, s27, v115, v135
	global_load_lds_dwordx4 v195, s[90:91]
	s_add_i32 m0, s28, s86
	v_add_u32_e32 v158, v170, v136
	global_load_lds_dwordx4 v196, s[90:91]
	s_add_i32 m0, s28, s87
	v_add_u32_e32 v166, v171, v136
	global_load_lds_dwordx4 v197, s[90:91]
	s_add_i32 m0, s28, s88
	s_addk_i32 s26, 0x4000
	global_load_lds_dwordx4 v198, s[90:91]
	s_add_i32 m0, s28, s89
	s_add_u32 s16, s16, 0x80
	s_addc_u32 s17, s17, 0
	global_load_lds_dwordx4 v199, s[90:91]
	ds_read_b128 v[138:141], v158
	ds_read_b128 v[146:149], v166 offset:16384
	ds_read_b128 v[150:153], v166 offset:18432
	ds_read_b128 v[162:165], v166 offset:20480
	ds_read_b128 v[166:169], v166 offset:22528
	ds_read_b128 v[142:145], v158 offset:2048
	ds_read_b128 v[154:157], v158 offset:4096
	ds_read_b128 v[158:161], v158 offset:6144
	v_add_u32_e32 v236, v170, v137
	v_add_u32_e32 v237, v171, v137
	ds_read_b128 v[204:207], v236
	ds_read_b128 v[208:211], v237 offset:16384
	ds_read_b128 v[212:215], v237 offset:18432
	ds_read_b128 v[216:219], v237 offset:20480
	ds_read_b128 v[220:223], v237 offset:22528
	ds_read_b128 v[224:227], v236 offset:2048
	ds_read_b128 v[228:231], v236 offset:4096
	ds_read_b128 v[232:235], v236 offset:6144
	s_setprio 3
	s_waitcnt lgkmcnt(11)
	v_mfma_f32_16x16x32_bf16 v[60:63], v[138:141], v[146:149], v[60:63]
	v_mfma_f32_16x16x32_bf16 v[56:59], v[138:141], v[150:153], v[56:59]
	v_mfma_f32_16x16x32_bf16 v[52:55], v[138:141], v[162:165], v[52:55]
	v_mfma_f32_16x16x32_bf16 v[48:51], v[138:141], v[166:169], v[48:51]
	s_waitcnt lgkmcnt(10)
	v_mfma_f32_16x16x32_bf16 v[44:47], v[142:145], v[146:149], v[44:47]
	v_mfma_f32_16x16x32_bf16 v[40:43], v[142:145], v[150:153], v[40:43]
	v_mfma_f32_16x16x32_bf16 v[36:39], v[142:145], v[162:165], v[36:39]
	v_mfma_f32_16x16x32_bf16 v[32:35], v[142:145], v[166:169], v[32:35]
	s_waitcnt lgkmcnt(9)
	v_mfma_f32_16x16x32_bf16 v[28:31], v[154:157], v[146:149], v[28:31]
	v_mfma_f32_16x16x32_bf16 v[24:27], v[154:157], v[150:153], v[24:27]
	v_mfma_f32_16x16x32_bf16 v[20:23], v[154:157], v[162:165], v[20:23]
	v_mfma_f32_16x16x32_bf16 v[16:19], v[154:157], v[166:169], v[16:19]
	s_waitcnt lgkmcnt(8)
	v_mfma_f32_16x16x32_bf16 v[12:15], v[158:161], v[146:149], v[12:15]
	v_mfma_f32_16x16x32_bf16 v[8:11], v[158:161], v[150:153], v[8:11]
	v_mfma_f32_16x16x32_bf16 v[4:7], v[158:161], v[162:165], v[4:7]
	v_mfma_f32_16x16x32_bf16 v[0:3], v[158:161], v[166:169], v[0:3]
	s_waitcnt lgkmcnt(3)
	v_mfma_f32_16x16x32_bf16 v[60:63], v[204:207], v[208:211], v[60:63]
	v_mfma_f32_16x16x32_bf16 v[56:59], v[204:207], v[212:215], v[56:59]
	v_mfma_f32_16x16x32_bf16 v[52:55], v[204:207], v[216:219], v[52:55]
	v_mfma_f32_16x16x32_bf16 v[48:51], v[204:207], v[220:223], v[48:51]
	s_waitcnt lgkmcnt(2)
	v_mfma_f32_16x16x32_bf16 v[44:47], v[224:227], v[208:211], v[44:47]
	v_mfma_f32_16x16x32_bf16 v[40:43], v[224:227], v[212:215], v[40:43]
	v_mfma_f32_16x16x32_bf16 v[36:39], v[224:227], v[216:219], v[36:39]
	v_mfma_f32_16x16x32_bf16 v[32:35], v[224:227], v[220:223], v[32:35]
	s_waitcnt lgkmcnt(1)
	v_mfma_f32_16x16x32_bf16 v[28:31], v[228:231], v[208:211], v[28:31]
	v_mfma_f32_16x16x32_bf16 v[24:27], v[228:231], v[212:215], v[24:27]
	v_mfma_f32_16x16x32_bf16 v[20:23], v[228:231], v[216:219], v[20:23]
	v_mfma_f32_16x16x32_bf16 v[16:19], v[228:231], v[220:223], v[16:19]
	s_waitcnt lgkmcnt(0)
	v_mfma_f32_16x16x32_bf16 v[12:15], v[232:235], v[208:211], v[12:15]
	v_mfma_f32_16x16x32_bf16 v[8:11], v[232:235], v[212:215], v[8:11]
	v_mfma_f32_16x16x32_bf16 v[4:7], v[232:235], v[216:219], v[4:7]
	v_mfma_f32_16x16x32_bf16 v[0:3], v[232:235], v[220:223], v[0:3]
	s_setprio 2
	s_cmpk_eq_i32 s16, 0x1f80
	s_waitcnt vmcnt(0)
	s_barrier
	s_cbranch_scc0 .Lxk_2076
.Lxk_exit_2076:
	ds_read_b128 v[90:93], v118 offset:55296
	ds_read_b128 v[94:97], v118 offset:53248
	ds_read_b128 v[98:101], v119 offset:38912
	ds_read_b128 v[102:105], v119 offset:36864
	ds_read_b128 v[138:141], v118 offset:51200
	ds_read_b128 v[142:145], v118 offset:49152
	ds_read_b128 v[146:149], v119 offset:34816
	ds_read_b128 v[150:153], v119 offset:32768
	s_setprio 1
	s_waitcnt lgkmcnt(5)
	v_mfma_f32_16x16x32_bf16 v[4:7], v[98:101], v[94:97], v[4:7]
	v_mfma_f32_16x16x32_bf16 v[0:3], v[98:101], v[90:93], v[0:3]
	s_waitcnt lgkmcnt(0)
	v_mfma_f32_16x16x32_bf16 v[60:63], v[150:153], v[142:145], v[60:63]
	v_mfma_f32_16x16x32_bf16 v[56:59], v[150:153], v[138:141], v[56:59]
	v_mfma_f32_16x16x32_bf16 v[52:55], v[150:153], v[94:97], v[52:55]
	v_mfma_f32_16x16x32_bf16 v[48:51], v[150:153], v[90:93], v[48:51]
	v_mfma_f32_16x16x32_bf16 v[44:47], v[146:149], v[142:145], v[44:47]
	v_mfma_f32_16x16x32_bf16 v[40:43], v[146:149], v[138:141], v[40:43]
	v_mfma_f32_16x16x32_bf16 v[36:39], v[146:149], v[94:97], v[36:39]
	v_mfma_f32_16x16x32_bf16 v[32:35], v[146:149], v[90:93], v[32:35]
	v_mfma_f32_16x16x32_bf16 v[28:31], v[102:105], v[142:145], v[28:31]
	v_mfma_f32_16x16x32_bf16 v[24:27], v[102:105], v[138:141], v[24:27]
	v_mfma_f32_16x16x32_bf16 v[20:23], v[102:105], v[94:97], v[20:23]
	v_mfma_f32_16x16x32_bf16 v[16:19], v[102:105], v[90:93], v[16:19]
	v_mfma_f32_16x16x32_bf16 v[12:15], v[98:101], v[142:145], v[12:15]
	v_mfma_f32_16x16x32_bf16 v[8:11], v[98:101], v[138:141], v[8:11]
	s_setprio 0
	ds_read_b128 v[90:93], v120 offset:32768
	ds_read_b128 v[94:97], v120 offset:34816
	ds_read_b128 v[98:101], v121 offset:49152
	ds_read_b128 v[102:105], v121 offset:51200
	ds_read_b128 v[138:141], v120 offset:36864
	ds_read_b128 v[142:145], v120 offset:38912
	ds_read_b128 v[146:149], v121 offset:53248
	ds_read_b128 v[150:153], v121 offset:55296
	s_setprio 1
	s_waitcnt lgkmcnt(1)
	v_mfma_f32_16x16x32_bf16 v[4:7], v[142:145], v[146:149], v[4:7]
	s_waitcnt lgkmcnt(0)
	v_mfma_f32_16x16x32_bf16 v[0:3], v[142:145], v[150:153], v[0:3]
	v_mfma_f32_16x16x32_bf16 v[60:63], v[90:93], v[98:101], v[60:63]
	v_mfma_f32_16x16x32_bf16 v[56:59], v[90:93], v[102:105], v[56:59]
	v_mfma_f32_16x16x32_bf16 v[52:55], v[90:93], v[146:149], v[52:55]
	v_mfma_f32_16x16x32_bf16 v[48:51], v[90:93], v[150:153], v[48:51]
	v_mfma_f32_16x16x32_bf16 v[44:47], v[94:97], v[98:101], v[44:47]
	v_mfma_f32_16x16x32_bf16 v[40:43], v[94:97], v[102:105], v[40:43]
	v_mfma_f32_16x16x32_bf16 v[36:39], v[94:97], v[146:149], v[36:39]
	v_mfma_f32_16x16x32_bf16 v[32:35], v[94:97], v[150:153], v[32:35]
	v_mfma_f32_16x16x32_bf16 v[28:31], v[138:141], v[98:101], v[28:31]
	v_mfma_f32_16x16x32_bf16 v[24:27], v[138:141], v[102:105], v[24:27]
	v_mfma_f32_16x16x32_bf16 v[20:23], v[138:141], v[146:149], v[20:23]
	v_mfma_f32_16x16x32_bf16 v[16:19], v[138:141], v[150:153], v[16:19]
	v_mfma_f32_16x16x32_bf16 v[12:15], v[142:145], v[98:101], v[12:15]
	v_mfma_f32_16x16x32_bf16 v[8:11], v[142:145], v[102:105], v[8:11]
	s_setprio 0
	s_barrier
	ds_write2_b32 v116, v60, v56 offset1:16
	ds_write2_b32 v116, v61, v57 offset0:132 offset1:148
	v_add_u32_e32 v56, 0x400, v116
	ds_write2_b32 v56, v62, v58 offset0:8 offset1:24
	ds_write2_b32 v56, v63, v59 offset0:140 offset1:156
	ds_write2_b32 v116, v52, v48 offset0:32 offset1:48
	ds_write2_b32 v116, v53, v49 offset0:164 offset1:180
	ds_write2_b32 v56, v54, v50 offset0:40 offset1:56
	ds_write2_b32 v56, v55, v51 offset0:172 offset1:188
	v_add_u32_e32 v48, 0x2000, v116
	ds_write2_b32 v48, v44, v40 offset0:64 offset1:80
	ds_write2_b32 v48, v45, v41 offset0:196 offset1:212
	v_add_u32_e32 v40, 0x2400, v116
	ds_write2_b32 v40, v46, v42 offset0:72 offset1:88
	ds_write2_b32 v40, v47, v43 offset0:204 offset1:220
	ds_write2_b32 v48, v36, v32 offset0:96 offset1:112
	ds_write2_b32 v48, v37, v33 offset0:228 offset1:244
	ds_write2_b32 v40, v38, v34 offset0:104 offset1:120
	ds_write2_b32 v40, v39, v35 offset0:236 offset1:252
	v_add_u32_e32 v32, 0x4000, v116
	ds_write2_b32 v32, v28, v24 offset0:128 offset1:144
	v_add_u32_e32 v24, 0x4400, v116
	ds_write2_b32 v24, v29, v25 offset0:4 offset1:20
	ds_write2_b32 v24, v30, v26 offset0:136 offset1:152
	v_add_u32_e32 v25, 0x4800, v116
	ds_write2_b32 v25, v31, v27 offset0:12 offset1:28
	ds_write2_b32 v32, v20, v16 offset0:160 offset1:176
	ds_write2_b32 v24, v21, v17 offset0:36 offset1:52
	ds_write2_b32 v24, v22, v18 offset0:168 offset1:184
	ds_write2_b32 v25, v23, v19 offset0:44 offset1:60
	v_add_u32_e32 v16, 0x6000, v116
	ds_write2_b32 v16, v12, v8 offset0:192 offset1:208
	v_add_u32_e32 v8, 0x6400, v116
	ds_write2_b32 v8, v13, v9 offset0:68 offset1:84
	ds_write2_b32 v8, v14, v10 offset0:200 offset1:216
	v_add_u32_e32 v9, 0x6800, v116
	ds_write2_b32 v9, v15, v11 offset0:76 offset1:92
	ds_write2_b32 v16, v4, v0 offset0:224 offset1:240
	ds_write2_b32 v8, v5, v1 offset0:100 offset1:116
	ds_write2_b32 v8, v6, v2 offset0:232 offset1:248
	ds_write2_b32 v9, v7, v3 offset0:108 offset1:124
	v_or_b32_e32 v0, s25, v117
	v_ashrrev_i32_e32 v1, 31, v0
	v_lshlrev_b64 v[2:3], 2, v[0:1]
	v_lshl_add_u64 v[0:1], s[14:15], 0, v[2:3]
	v_lshl_add_u64 v[2:3], s[12:13], 0, v[2:3]
	v_add_u32_e32 v4, s24, v128
	s_mov_b32 s16, 0
	s_waitcnt lgkmcnt(0)
	s_barrier

.LBB0_2084:
	s_ashr_i32 s16, s18, 31
	s_lshr_b32 s16, s16, 29
	s_add_i32 s16, s18, s16
	s_ashr_i32 s16, s16, 3
	s_lshl_b32 s17, s16, 10
	s_lshl_b32 s25, s18, 7
	v_add_u32_e32 v0, s16, v104
	s_sub_i32 s25, s25, s17
	v_lshlrev_b32_e32 v2, 7, v0
	v_add_u32_e32 v0, s25, v105
	v_ashrrev_i32_e32 v1, 31, v0
	v_add_u32_e32 v3, 0x4000, v106
	v_lshlrev_b64 v[0:1], 13, v[0:1]
	v_readfirstlane_b32 s26, v3
	v_lshl_add_u64 v[0:1], v[64:65], 0, v[0:1]
	s_mov_b32 m0, s26
	v_readfirstlane_b32 s26, v106
	global_load_lds_dwordx4 v[0:1], off
	v_add_u32_e32 v0, v2, v105
	v_ashrrev_i32_e32 v1, 31, v0
	v_lshlrev_b64 v[0:1], 13, v[0:1]
	v_lshl_add_u64 v[0:1], v[70:71], 0, v[0:1]
	s_mov_b32 m0, s26
	v_readfirstlane_b32 s26, v131
	global_load_lds_dwordx4 v[0:1], off
	v_add_u32_e32 v0, s25, v107
	v_ashrrev_i32_e32 v1, 31, v0
	v_lshlrev_b64 v[0:1], 13, v[0:1]
	v_lshl_add_u64 v[0:1], v[66:67], 0, v[0:1]
	s_mov_b32 m0, s26
	v_add_u32_e32 v3, 0x400, v106
	global_load_lds_dwordx4 v[0:1], off
	v_add_u32_e32 v0, v2, v107
	v_ashrrev_i32_e32 v1, 31, v0
	v_lshlrev_b64 v[0:1], 13, v[0:1]
	v_readfirstlane_b32 s26, v3
	v_lshl_add_u64 v[0:1], v[72:73], 0, v[0:1]
	s_mov_b32 m0, s26
	v_readfirstlane_b32 s26, v132
	global_load_lds_dwordx4 v[0:1], off
	v_add_u32_e32 v0, s25, v109
	v_ashrrev_i32_e32 v1, 31, v0
	v_lshlrev_b64 v[0:1], 13, v[0:1]
	v_lshl_add_u64 v[0:1], v[64:65], 0, v[0:1]
	s_mov_b32 m0, s26
	v_add_u32_e32 v3, 0x800, v106
	global_load_lds_dwordx4 v[0:1], off
	v_add_u32_e32 v0, v2, v109
	v_ashrrev_i32_e32 v1, 31, v0
	v_lshlrev_b64 v[0:1], 13, v[0:1]
	v_readfirstlane_b32 s26, v3
	v_lshl_add_u64 v[0:1], v[70:71], 0, v[0:1]
	s_mov_b32 m0, s26
	v_readfirstlane_b32 s26, v133
	global_load_lds_dwordx4 v[0:1], off
	v_add_u32_e32 v0, s25, v111
	v_ashrrev_i32_e32 v1, 31, v0
	v_lshlrev_b64 v[0:1], 13, v[0:1]
	v_lshl_add_u64 v[0:1], v[68:69], 0, v[0:1]
	s_mov_b32 m0, s26
	s_mov_b32 s27, 0
	global_load_lds_dwordx4 v[0:1], off
	v_add_u32_e32 v0, v2, v111
	v_ashrrev_i32_e32 v1, 31, v0
	v_add_u32_e32 v2, 0xc00, v106
	v_lshlrev_b64 v[0:1], 13, v[0:1]
	v_readfirstlane_b32 s26, v2
	v_lshl_add_u64 v[0:1], v[74:75], 0, v[0:1]
	s_mov_b32 m0, s26
	s_lshl_b32 s26, s16, 7
	global_load_lds_dwordx4 v[0:1], off
	v_subrev_u32_e32 v0, s17, v121
	v_ashrrev_i32_e32 v1, 31, v0
	v_lshlrev_b64 v[0:1], 13, v[0:1]
	v_lshl_add_u64 v[88:89], v[76:77], 0, v[0:1]
	v_add_u32_e32 v0, s26, v122
	v_ashrrev_i32_e32 v1, 31, v0
	v_lshlrev_b64 v[0:1], 13, v[0:1]
	v_lshl_add_u64 v[90:91], v[78:79], 0, v[0:1]
	v_subrev_u32_e32 v0, s17, v123
	v_ashrrev_i32_e32 v1, 31, v0
	v_lshlrev_b64 v[0:1], 13, v[0:1]
	v_lshl_add_u64 v[92:93], v[80:81], 0, v[0:1]
	v_add_u32_e32 v0, s26, v124
	v_ashrrev_i32_e32 v1, 31, v0
	v_lshlrev_b64 v[0:1], 13, v[0:1]
	v_lshl_add_u64 v[94:95], v[82:83], 0, v[0:1]
	v_subrev_u32_e32 v0, s17, v125
	v_ashrrev_i32_e32 v1, 31, v0
	v_lshlrev_b64 v[0:1], 13, v[0:1]
	v_lshl_add_u64 v[96:97], v[76:77], 0, v[0:1]
	v_add_u32_e32 v0, s26, v126
	v_ashrrev_i32_e32 v1, 31, v0
	v_lshlrev_b64 v[0:1], 13, v[0:1]
	v_lshl_add_u64 v[98:99], v[78:79], 0, v[0:1]
	v_subrev_u32_e32 v0, s17, v127
	v_ashrrev_i32_e32 v1, 31, v0
	v_lshlrev_b64 v[0:1], 13, v[0:1]
	v_lshl_add_u64 v[100:101], v[84:85], 0, v[0:1]
	v_add_u32_e32 v0, s26, v128
	v_ashrrev_i32_e32 v1, 31, v0
	v_lshlrev_b64 v[0:1], 13, v[0:1]
	v_lshl_add_u64 v[102:103], v[86:87], 0, v[0:1]
	v_mov_b32_e32 v0, 0
	s_mov_b64 s[16:17], 0
	v_mov_b32_e32 v1, v0
	v_mov_b32_e32 v2, v0
	v_mov_b32_e32 v3, v0
	v_mov_b32_e32 v4, v0
	v_mov_b32_e32 v5, v0
	v_mov_b32_e32 v6, v0
	v_mov_b32_e32 v7, v0
	v_mov_b32_e32 v8, v0
	v_mov_b32_e32 v9, v0
	v_mov_b32_e32 v10, v0
	v_mov_b32_e32 v11, v0
	v_mov_b32_e32 v12, v0
	v_mov_b32_e32 v13, v0
	v_mov_b32_e32 v14, v0
	v_mov_b32_e32 v15, v0
	v_mov_b32_e32 v16, v0
	v_mov_b32_e32 v17, v0
	v_mov_b32_e32 v18, v0
	v_mov_b32_e32 v19, v0
	v_mov_b32_e32 v20, v0
	v_mov_b32_e32 v21, v0
	v_mov_b32_e32 v22, v0
	v_mov_b32_e32 v23, v0
	v_mov_b32_e32 v24, v0
	v_mov_b32_e32 v25, v0
	v_mov_b32_e32 v26, v0
	v_mov_b32_e32 v27, v0
	v_mov_b32_e32 v28, v0
	v_mov_b32_e32 v29, v0
	v_mov_b32_e32 v30, v0
	v_mov_b32_e32 v31, v0
	s_waitcnt vmcnt(0)
	v_mov_b32_e32 v32, v0
	v_mov_b32_e32 v33, v0
	v_mov_b32_e32 v34, v0
	v_mov_b32_e32 v35, v0
	v_mov_b32_e32 v36, v0
	v_mov_b32_e32 v37, v0
	v_mov_b32_e32 v38, v0
	v_mov_b32_e32 v39, v0
	v_mov_b32_e32 v40, v0
	v_mov_b32_e32 v41, v0
	v_mov_b32_e32 v42, v0
	v_mov_b32_e32 v43, v0
	v_mov_b32_e32 v44, v0
	v_mov_b32_e32 v45, v0
	v_mov_b32_e32 v46, v0
	v_mov_b32_e32 v47, v0
	v_mov_b32_e32 v48, v0
	v_mov_b32_e32 v49, v0
	v_mov_b32_e32 v50, v0
	v_mov_b32_e32 v51, v0
	v_mov_b32_e32 v52, v0
	v_mov_b32_e32 v53, v0
	v_mov_b32_e32 v54, v0
	v_mov_b32_e32 v55, v0
	v_mov_b32_e32 v56, v0
	v_mov_b32_e32 v57, v0
	v_mov_b32_e32 v58, v0
	v_mov_b32_e32 v59, v0
	v_mov_b32_e32 v60, v0
	v_mov_b32_e32 v61, v0
	v_mov_b32_e32 v62, v0
	v_mov_b32_e32 v63, v0
	s_waitcnt lgkmcnt(0)
	s_barrier
	v_add3_u32 v190, 0, v134, v135
	v_add_u32_e32 v191, 0x4000, v190
	s_nop 0
	v_readfirstlane_b32 s82, v191
	v_lshl_add_u32 v191, v108, 1, 0
	s_nop 0
	v_readfirstlane_b32 s83, v190
	v_add3_u32 v191, v191, v135, s21
	s_nop 0
	v_readfirstlane_b32 s84, v191
	v_add_u32_e32 v191, 0x400, v190
	s_nop 0
	v_readfirstlane_b32 s85, v191
	v_lshl_add_u32 v191, v110, 1, 0
	v_add3_u32 v191, v191, v135, s21
	s_nop 0
	v_readfirstlane_b32 s86, v191
	v_add_u32_e32 v191, 0x800, v190
	s_nop 0
	v_readfirstlane_b32 s87, v191
	v_lshl_add_u32 v191, v112, 1, 0
	v_add3_u32 v191, v191, v135, s21
	s_nop 0
	v_readfirstlane_b32 s88, v191
	v_add_u32_e32 v190, 0xc00, v190
	s_nop 0
	v_readfirstlane_b32 s89, v190
	v_subrev_u32_e32 v192, s52, v88
	v_subrev_u32_e32 v193, s52, v90
	v_subrev_u32_e32 v194, s52, v92
	v_subrev_u32_e32 v195, s52, v94
	v_subrev_u32_e32 v196, s52, v96
	v_subrev_u32_e32 v197, s52, v98
	v_subrev_u32_e32 v198, s52, v100
	v_subrev_u32_e32 v199, s52, v102
	s_bitcmp1_b32 s32, 0
	s_cbranch_scc1 .Lxk_2085
.LBB0_2085:
	s_and_b32 s28, s27, 0x4000
	s_xor_b32 s29, s28, 0x4000
	s_lshl_b32 s29, s29, 1
	s_add_i32 s29, s29, 32
	s_add_u32 s90, s52, s16
	s_addc_u32 s91, s53, s17
	s_add_i32 m0, s29, s82
	s_lshl_b32 s28, s28, 1
	global_load_lds_dwordx4 v192, s[90:91]
	s_add_i32 m0, s29, s83
	s_add_i32 s28, s28, 32
	global_load_lds_dwordx4 v193, s[90:91]
	s_add_i32 m0, s29, s84
	v_add3_u32 v139, s28, v113, v136
	global_load_lds_dwordx4 v194, s[90:91]
	s_add_i32 m0, s29, s85
	v_add3_u32 v172, s28, v114, v136
	global_load_lds_dwordx4 v195, s[90:91]
	s_add_i32 m0, s29, s86
	v_add_u32_e32 v160, v139, v137
	global_load_lds_dwordx4 v196, s[90:91]
	s_add_i32 m0, s29, s87
	v_add_u32_e32 v168, v172, v137
	global_load_lds_dwordx4 v197, s[90:91]
	s_add_i32 m0, s29, s88
	s_addk_i32 s27, 0x4000
	global_load_lds_dwordx4 v198, s[90:91]
	s_add_i32 m0, s29, s89
	s_add_u32 s16, s16, 0x80
	s_addc_u32 s17, s17, 0
	global_load_lds_dwordx4 v199, s[90:91]
	ds_read_b128 v[140:143], v160
	ds_read_b128 v[148:151], v168 offset:16384
	ds_read_b128 v[152:155], v168 offset:18432
	ds_read_b128 v[164:167], v168 offset:20480
	ds_read_b128 v[168:171], v168 offset:22528
	ds_read_b128 v[144:147], v160 offset:2048
	ds_read_b128 v[156:159], v160 offset:4096
	ds_read_b128 v[160:163], v160 offset:6144
	v_add_u32_e32 v139, v139, v138
	v_add_u32_e32 v236, v172, v138
	ds_read_b128 v[204:207], v139
	ds_read_b128 v[208:211], v236 offset:16384
	ds_read_b128 v[212:215], v236 offset:18432
	ds_read_b128 v[216:219], v236 offset:20480
	ds_read_b128 v[220:223], v236 offset:22528
	ds_read_b128 v[224:227], v139 offset:2048
	ds_read_b128 v[228:231], v139 offset:4096
	ds_read_b128 v[232:235], v139 offset:6144
	s_setprio 1
	s_waitcnt lgkmcnt(11)
	v_mfma_f32_16x16x32_bf16 v[60:63], v[140:143], v[148:151], v[60:63]
	v_mfma_f32_16x16x32_bf16 v[56:59], v[140:143], v[152:155], v[56:59]
	v_mfma_f32_16x16x32_bf16 v[52:55], v[140:143], v[164:167], v[52:55]
	v_mfma_f32_16x16x32_bf16 v[48:51], v[140:143], v[168:171], v[48:51]
	s_waitcnt lgkmcnt(10)
	v_mfma_f32_16x16x32_bf16 v[44:47], v[144:147], v[148:151], v[44:47]
	v_mfma_f32_16x16x32_bf16 v[40:43], v[144:147], v[152:155], v[40:43]
	v_mfma_f32_16x16x32_bf16 v[36:39], v[144:147], v[164:167], v[36:39]
	v_mfma_f32_16x16x32_bf16 v[32:35], v[144:147], v[168:171], v[32:35]
	s_waitcnt lgkmcnt(9)
	v_mfma_f32_16x16x32_bf16 v[28:31], v[156:159], v[148:151], v[28:31]
	v_mfma_f32_16x16x32_bf16 v[24:27], v[156:159], v[152:155], v[24:27]
	v_mfma_f32_16x16x32_bf16 v[20:23], v[156:159], v[164:167], v[20:23]
	v_mfma_f32_16x16x32_bf16 v[16:19], v[156:159], v[168:171], v[16:19]
	s_waitcnt lgkmcnt(8)
	v_mfma_f32_16x16x32_bf16 v[12:15], v[160:163], v[148:151], v[12:15]
	v_mfma_f32_16x16x32_bf16 v[8:11], v[160:163], v[152:155], v[8:11]
	v_mfma_f32_16x16x32_bf16 v[4:7], v[160:163], v[164:167], v[4:7]
	v_mfma_f32_16x16x32_bf16 v[0:3], v[160:163], v[168:171], v[0:3]
	s_waitcnt lgkmcnt(3)
	v_mfma_f32_16x16x32_bf16 v[60:63], v[204:207], v[208:211], v[60:63]
	v_mfma_f32_16x16x32_bf16 v[56:59], v[204:207], v[212:215], v[56:59]
	v_mfma_f32_16x16x32_bf16 v[52:55], v[204:207], v[216:219], v[52:55]
	v_mfma_f32_16x16x32_bf16 v[48:51], v[204:207], v[220:223], v[48:51]
	s_waitcnt lgkmcnt(2)
	v_mfma_f32_16x16x32_bf16 v[44:47], v[224:227], v[208:211], v[44:47]
	v_mfma_f32_16x16x32_bf16 v[40:43], v[224:227], v[212:215], v[40:43]
	v_mfma_f32_16x16x32_bf16 v[36:39], v[224:227], v[216:219], v[36:39]
	v_mfma_f32_16x16x32_bf16 v[32:35], v[224:227], v[220:223], v[32:35]
	s_waitcnt lgkmcnt(1)
	v_mfma_f32_16x16x32_bf16 v[28:31], v[228:231], v[208:211], v[28:31]
	v_mfma_f32_16x16x32_bf16 v[24:27], v[228:231], v[212:215], v[24:27]
	v_mfma_f32_16x16x32_bf16 v[20:23], v[228:231], v[216:219], v[20:23]
	v_mfma_f32_16x16x32_bf16 v[16:19], v[228:231], v[220:223], v[16:19]
	s_waitcnt lgkmcnt(0)
	v_mfma_f32_16x16x32_bf16 v[12:15], v[232:235], v[208:211], v[12:15]
	v_mfma_f32_16x16x32_bf16 v[8:11], v[232:235], v[212:215], v[8:11]
	v_mfma_f32_16x16x32_bf16 v[4:7], v[232:235], v[216:219], v[4:7]
	v_mfma_f32_16x16x32_bf16 v[0:3], v[232:235], v[220:223], v[0:3]
	s_setprio 0
	s_cmpk_eq_i32 s16, 0x1f80
	s_waitcnt vmcnt(0)
	s_barrier
	s_cbranch_scc0 .LBB0_2085
	s_branch .Lxk_exit_2085
.Lxk_2085:
	s_and_b32 s28, s27, 0x4000
	s_xor_b32 s29, s28, 0x4000
	s_lshl_b32 s29, s29, 1
	s_add_i32 s29, s29, 32
	s_add_u32 s90, s52, s16
	s_addc_u32 s91, s53, s17
	s_add_i32 m0, s29, s82
	s_lshl_b32 s28, s28, 1
	global_load_lds_dwordx4 v192, s[90:91]
	s_add_i32 m0, s29, s83
	s_add_i32 s28, s28, 32
	global_load_lds_dwordx4 v193, s[90:91]
	s_add_i32 m0, s29, s84
	v_add3_u32 v139, s28, v113, v136
	global_load_lds_dwordx4 v194, s[90:91]
	s_add_i32 m0, s29, s85
	v_add3_u32 v172, s28, v114, v136
	global_load_lds_dwordx4 v195, s[90:91]
	s_add_i32 m0, s29, s86
	v_add_u32_e32 v160, v139, v137
	global_load_lds_dwordx4 v196, s[90:91]
	s_add_i32 m0, s29, s87
	v_add_u32_e32 v168, v172, v137
	global_load_lds_dwordx4 v197, s[90:91]
	s_add_i32 m0, s29, s88
	s_addk_i32 s27, 0x4000
	global_load_lds_dwordx4 v198, s[90:91]
	s_add_i32 m0, s29, s89
	s_add_u32 s16, s16, 0x80
	s_addc_u32 s17, s17, 0
	global_load_lds_dwordx4 v199, s[90:91]
	ds_read_b128 v[140:143], v160
	ds_read_b128 v[148:151], v168 offset:16384
	ds_read_b128 v[152:155], v168 offset:18432
	ds_read_b128 v[164:167], v168 offset:20480
	ds_read_b128 v[168:171], v168 offset:22528
	ds_read_b128 v[144:147], v160 offset:2048
	ds_read_b128 v[156:159], v160 offset:4096
	ds_read_b128 v[160:163], v160 offset:6144
	v_add_u32_e32 v139, v139, v138
	v_add_u32_e32 v236, v172, v138
	ds_read_b128 v[204:207], v139
	ds_read_b128 v[208:211], v236 offset:16384
	ds_read_b128 v[212:215], v236 offset:18432
	ds_read_b128 v[216:219], v236 offset:20480
	ds_read_b128 v[220:223], v236 offset:22528
	ds_read_b128 v[224:227], v139 offset:2048
	ds_read_b128 v[228:231], v139 offset:4096
	ds_read_b128 v[232:235], v139 offset:6144
	s_setprio 3
	s_waitcnt lgkmcnt(11)
	v_mfma_f32_16x16x32_bf16 v[60:63], v[140:143], v[148:151], v[60:63]
	v_mfma_f32_16x16x32_bf16 v[56:59], v[140:143], v[152:155], v[56:59]
	v_mfma_f32_16x16x32_bf16 v[52:55], v[140:143], v[164:167], v[52:55]
	v_mfma_f32_16x16x32_bf16 v[48:51], v[140:143], v[168:171], v[48:51]
	s_waitcnt lgkmcnt(10)
	v_mfma_f32_16x16x32_bf16 v[44:47], v[144:147], v[148:151], v[44:47]
	v_mfma_f32_16x16x32_bf16 v[40:43], v[144:147], v[152:155], v[40:43]
	v_mfma_f32_16x16x32_bf16 v[36:39], v[144:147], v[164:167], v[36:39]
	v_mfma_f32_16x16x32_bf16 v[32:35], v[144:147], v[168:171], v[32:35]
	s_waitcnt lgkmcnt(9)
	v_mfma_f32_16x16x32_bf16 v[28:31], v[156:159], v[148:151], v[28:31]
	v_mfma_f32_16x16x32_bf16 v[24:27], v[156:159], v[152:155], v[24:27]
	v_mfma_f32_16x16x32_bf16 v[20:23], v[156:159], v[164:167], v[20:23]
	v_mfma_f32_16x16x32_bf16 v[16:19], v[156:159], v[168:171], v[16:19]
	s_waitcnt lgkmcnt(8)
	v_mfma_f32_16x16x32_bf16 v[12:15], v[160:163], v[148:151], v[12:15]
	v_mfma_f32_16x16x32_bf16 v[8:11], v[160:163], v[152:155], v[8:11]
	v_mfma_f32_16x16x32_bf16 v[4:7], v[160:163], v[164:167], v[4:7]
	v_mfma_f32_16x16x32_bf16 v[0:3], v[160:163], v[168:171], v[0:3]
	s_waitcnt lgkmcnt(3)
	v_mfma_f32_16x16x32_bf16 v[60:63], v[204:207], v[208:211], v[60:63]
	v_mfma_f32_16x16x32_bf16 v[56:59], v[204:207], v[212:215], v[56:59]
	v_mfma_f32_16x16x32_bf16 v[52:55], v[204:207], v[216:219], v[52:55]
	v_mfma_f32_16x16x32_bf16 v[48:51], v[204:207], v[220:223], v[48:51]
	s_waitcnt lgkmcnt(2)
	v_mfma_f32_16x16x32_bf16 v[44:47], v[224:227], v[208:211], v[44:47]
	v_mfma_f32_16x16x32_bf16 v[40:43], v[224:227], v[212:215], v[40:43]
	v_mfma_f32_16x16x32_bf16 v[36:39], v[224:227], v[216:219], v[36:39]
	v_mfma_f32_16x16x32_bf16 v[32:35], v[224:227], v[220:223], v[32:35]
	s_waitcnt lgkmcnt(1)
	v_mfma_f32_16x16x32_bf16 v[28:31], v[228:231], v[208:211], v[28:31]
	v_mfma_f32_16x16x32_bf16 v[24:27], v[228:231], v[212:215], v[24:27]
	v_mfma_f32_16x16x32_bf16 v[20:23], v[228:231], v[216:219], v[20:23]
	v_mfma_f32_16x16x32_bf16 v[16:19], v[228:231], v[220:223], v[16:19]
	s_waitcnt lgkmcnt(0)
	v_mfma_f32_16x16x32_bf16 v[12:15], v[232:235], v[208:211], v[12:15]
	v_mfma_f32_16x16x32_bf16 v[8:11], v[232:235], v[212:215], v[8:11]
	v_mfma_f32_16x16x32_bf16 v[4:7], v[232:235], v[216:219], v[4:7]
	v_mfma_f32_16x16x32_bf16 v[0:3], v[232:235], v[220:223], v[0:3]
	s_setprio 2
	s_cmpk_eq_i32 s16, 0x1f80
	s_waitcnt vmcnt(0)
	s_barrier
	s_cbranch_scc0 .Lxk_2085
.Lxk_exit_2085:
	ds_read_b128 v[88:91], v117 offset:55296
	ds_read_b128 v[92:95], v117 offset:53248
	ds_read_b128 v[96:99], v118 offset:38912
	ds_read_b128 v[100:103], v118 offset:36864
	ds_read_b128 v[140:143], v117 offset:51200
	ds_read_b128 v[144:147], v117 offset:49152
	ds_read_b128 v[148:151], v118 offset:34816
	ds_read_b128 v[152:155], v118 offset:32768
	s_setprio 1
	s_waitcnt lgkmcnt(5)
	v_mfma_f32_16x16x32_bf16 v[4:7], v[96:99], v[92:95], v[4:7]
	v_mfma_f32_16x16x32_bf16 v[0:3], v[96:99], v[88:91], v[0:3]
	s_waitcnt lgkmcnt(0)
	v_mfma_f32_16x16x32_bf16 v[60:63], v[152:155], v[144:147], v[60:63]
	v_mfma_f32_16x16x32_bf16 v[56:59], v[152:155], v[140:143], v[56:59]
	v_mfma_f32_16x16x32_bf16 v[52:55], v[152:155], v[92:95], v[52:55]
	v_mfma_f32_16x16x32_bf16 v[48:51], v[152:155], v[88:91], v[48:51]
	v_mfma_f32_16x16x32_bf16 v[44:47], v[148:151], v[144:147], v[44:47]
	v_mfma_f32_16x16x32_bf16 v[40:43], v[148:151], v[140:143], v[40:43]
	v_mfma_f32_16x16x32_bf16 v[36:39], v[148:151], v[92:95], v[36:39]
	v_mfma_f32_16x16x32_bf16 v[32:35], v[148:151], v[88:91], v[32:35]
	v_mfma_f32_16x16x32_bf16 v[28:31], v[100:103], v[144:147], v[28:31]
	v_mfma_f32_16x16x32_bf16 v[24:27], v[100:103], v[140:143], v[24:27]
	v_mfma_f32_16x16x32_bf16 v[20:23], v[100:103], v[92:95], v[20:23]
	v_mfma_f32_16x16x32_bf16 v[16:19], v[100:103], v[88:91], v[16:19]
	v_mfma_f32_16x16x32_bf16 v[12:15], v[96:99], v[144:147], v[12:15]
	v_mfma_f32_16x16x32_bf16 v[8:11], v[96:99], v[140:143], v[8:11]
	s_setprio 0
	ds_read_b128 v[88:91], v119 offset:32768
	ds_read_b128 v[92:95], v119 offset:34816
	ds_read_b128 v[96:99], v120 offset:49152
	ds_read_b128 v[100:103], v120 offset:51200
	ds_read_b128 v[140:143], v119 offset:36864
	ds_read_b128 v[144:147], v119 offset:38912
	ds_read_b128 v[148:151], v120 offset:53248
	ds_read_b128 v[152:155], v120 offset:55296
	s_setprio 1
	s_waitcnt lgkmcnt(1)
	v_mfma_f32_16x16x32_bf16 v[4:7], v[144:147], v[148:151], v[4:7]
	s_waitcnt lgkmcnt(0)
	v_mfma_f32_16x16x32_bf16 v[0:3], v[144:147], v[152:155], v[0:3]
	v_mfma_f32_16x16x32_bf16 v[60:63], v[88:91], v[96:99], v[60:63]
	v_mfma_f32_16x16x32_bf16 v[56:59], v[88:91], v[100:103], v[56:59]
	v_mfma_f32_16x16x32_bf16 v[52:55], v[88:91], v[148:151], v[52:55]
	v_mfma_f32_16x16x32_bf16 v[48:51], v[88:91], v[152:155], v[48:51]
	v_mfma_f32_16x16x32_bf16 v[44:47], v[92:95], v[96:99], v[44:47]
	v_mfma_f32_16x16x32_bf16 v[40:43], v[92:95], v[100:103], v[40:43]
	v_mfma_f32_16x16x32_bf16 v[36:39], v[92:95], v[148:151], v[36:39]
	v_mfma_f32_16x16x32_bf16 v[32:35], v[92:95], v[152:155], v[32:35]
	v_mfma_f32_16x16x32_bf16 v[28:31], v[140:143], v[96:99], v[28:31]
	v_mfma_f32_16x16x32_bf16 v[24:27], v[140:143], v[100:103], v[24:27]
	v_mfma_f32_16x16x32_bf16 v[20:23], v[140:143], v[148:151], v[20:23]
	v_mfma_f32_16x16x32_bf16 v[16:19], v[140:143], v[152:155], v[16:19]
	v_mfma_f32_16x16x32_bf16 v[12:15], v[144:147], v[96:99], v[12:15]
	v_mfma_f32_16x16x32_bf16 v[8:11], v[144:147], v[100:103], v[8:11]
	s_setprio 0
	s_barrier
	ds_write2_b32 v115, v60, v56 offset1:16
	ds_write2_b32 v115, v61, v57 offset0:132 offset1:148
	v_add_u32_e32 v56, 0x400, v115
	ds_write2_b32 v56, v62, v58 offset0:8 offset1:24
	ds_write2_b32 v56, v63, v59 offset0:140 offset1:156
	ds_write2_b32 v115, v52, v48 offset0:32 offset1:48
	ds_write2_b32 v115, v53, v49 offset0:164 offset1:180
	ds_write2_b32 v56, v54, v50 offset0:40 offset1:56
	ds_write2_b32 v56, v55, v51 offset0:172 offset1:188
	v_add_u32_e32 v48, 0x2000, v115
	ds_write2_b32 v48, v44, v40 offset0:64 offset1:80
	ds_write2_b32 v48, v45, v41 offset0:196 offset1:212
	v_add_u32_e32 v40, 0x2400, v115
	ds_write2_b32 v40, v46, v42 offset0:72 offset1:88
	ds_write2_b32 v40, v47, v43 offset0:204 offset1:220
	ds_write2_b32 v48, v36, v32 offset0:96 offset1:112
	ds_write2_b32 v48, v37, v33 offset0:228 offset1:244
	ds_write2_b32 v40, v38, v34 offset0:104 offset1:120
	ds_write2_b32 v40, v39, v35 offset0:236 offset1:252
	v_add_u32_e32 v32, 0x4000, v115
	ds_write2_b32 v32, v28, v24 offset0:128 offset1:144
	v_add_u32_e32 v24, 0x4400, v115
	ds_write2_b32 v24, v29, v25 offset0:4 offset1:20
	ds_write2_b32 v24, v30, v26 offset0:136 offset1:152
	v_add_u32_e32 v25, 0x4800, v115
	ds_write2_b32 v25, v31, v27 offset0:12 offset1:28
	ds_write2_b32 v32, v20, v16 offset0:160 offset1:176
	ds_write2_b32 v24, v21, v17 offset0:36 offset1:52
	ds_write2_b32 v24, v22, v18 offset0:168 offset1:184
	ds_write2_b32 v25, v23, v19 offset0:44 offset1:60
	v_add_u32_e32 v16, 0x6000, v115
	ds_write2_b32 v16, v12, v8 offset0:192 offset1:208
	v_add_u32_e32 v8, 0x6400, v115
	ds_write2_b32 v8, v13, v9 offset0:68 offset1:84
	ds_write2_b32 v8, v14, v10 offset0:200 offset1:216
	v_add_u32_e32 v9, 0x6800, v115
	ds_write2_b32 v9, v15, v11 offset0:76 offset1:92
	ds_write2_b32 v16, v4, v0 offset0:224 offset1:240
	ds_write2_b32 v8, v5, v1 offset0:100 offset1:116
	ds_write2_b32 v8, v6, v2 offset0:232 offset1:248
	ds_write2_b32 v9, v7, v3 offset0:108 offset1:124
	v_or_b32_e32 v0, s25, v116
	v_ashrrev_i32_e32 v1, 31, v0
	v_lshlrev_b64 v[2:3], 2, v[0:1]
	v_lshl_add_u64 v[0:1], s[14:15], 0, v[2:3]
	v_lshl_add_u64 v[2:3], s[12:13], 0, v[2:3]
	v_add_u32_e32 v4, s26, v129
	s_mov_b32 s16, 0
	s_waitcnt lgkmcnt(0)
	s_barrier

.LBB0_2095:
	s_and_b32 s16, s20, 0x380
	v_add_lshl_u32 v72, v141, s16, 13
	v_lshl_add_u64 v[98:99], v[86:87], 0, v[72:73]
	v_add_lshl_u32 v72, v143, s16, 13
	v_lshl_add_u64 v[100:101], v[90:91], 0, v[72:73]
	v_add_lshl_u32 v72, v145, s16, 13
	s_lshl_b32 s26, s25, 7
	v_lshl_add_u64 v[102:103], v[86:87], 0, v[72:73]
	v_add_lshl_u32 v72, v147, s16, 13
	s_ashr_i32 s16, s25, 3
	s_and_b32 s26, s26, 0x380
	v_add_u32_e32 v2, 0x4000, v135
	v_lshl_add_u64 v[104:105], v[94:95], 0, v[72:73]
	s_add_i32 s17, s16, s19
	v_add_lshl_u32 v72, s26, v134, 13
	v_readfirstlane_b32 s27, v2
	s_lshl_b32 s17, s17, 7
	v_lshl_add_u64 v[0:1], v[74:75], 0, v[72:73]
	s_mov_b32 m0, s27
	v_readfirstlane_b32 s27, v135
	global_load_lds_dwordx4 v[0:1], off
	v_add_u32_e32 v0, s17, v134
	v_ashrrev_i32_e32 v1, 31, v0
	v_lshlrev_b64 v[0:1], 13, v[0:1]
	v_lshl_add_u64 v[0:1], v[80:81], 0, v[0:1]
	s_mov_b32 m0, s27
	v_add_lshl_u32 v72, s26, v126, 13
	v_readfirstlane_b32 s27, v151
	global_load_lds_dwordx4 v[0:1], off
	v_lshl_add_u64 v[0:1], v[76:77], 0, v[72:73]
	s_mov_b32 m0, s27
	v_add_u32_e32 v2, 0x400, v135
	global_load_lds_dwordx4 v[0:1], off
	v_add_u32_e32 v0, s17, v126
	v_ashrrev_i32_e32 v1, 31, v0
	v_lshlrev_b64 v[0:1], 13, v[0:1]
	v_readfirstlane_b32 s27, v2
	v_lshl_add_u64 v[0:1], v[82:83], 0, v[0:1]
	s_mov_b32 m0, s27
	v_add_lshl_u32 v72, s26, v127, 13
	v_readfirstlane_b32 s27, v152
	global_load_lds_dwordx4 v[0:1], off
	v_lshl_add_u64 v[0:1], v[74:75], 0, v[72:73]
	s_mov_b32 m0, s27
	v_add_u32_e32 v2, 0x800, v135
	global_load_lds_dwordx4 v[0:1], off
	v_add_u32_e32 v0, s17, v127
	v_ashrrev_i32_e32 v1, 31, v0
	v_lshlrev_b64 v[0:1], 13, v[0:1]
	v_readfirstlane_b32 s27, v2
	v_lshl_add_u64 v[0:1], v[80:81], 0, v[0:1]
	s_mov_b32 m0, s27
	v_add_lshl_u32 v72, s26, v125, 13
	v_readfirstlane_b32 s27, v153
	global_load_lds_dwordx4 v[0:1], off
	v_lshl_add_u64 v[0:1], v[78:79], 0, v[72:73]
	s_mov_b32 m0, s27
	v_add_u32_e32 v2, 0xc00, v135
	global_load_lds_dwordx4 v[0:1], off
	v_add_u32_e32 v0, s17, v125
	v_ashrrev_i32_e32 v1, 31, v0
	v_lshlrev_b64 v[0:1], 13, v[0:1]
	v_readfirstlane_b32 s17, v2
	v_lshl_add_u64 v[0:1], v[84:85], 0, v[0:1]
	s_mov_b32 m0, s17
	s_lshl_b32 s27, s16, 7
	global_load_lds_dwordx4 v[0:1], off
	v_add_u32_e32 v0, s27, v142
	v_ashrrev_i32_e32 v1, 31, v0
	v_lshlrev_b64 v[0:1], 13, v[0:1]
	v_lshl_add_u64 v[106:107], v[88:89], 0, v[0:1]
	v_add_u32_e32 v0, s27, v144
	v_ashrrev_i32_e32 v1, 31, v0
	v_lshlrev_b64 v[0:1], 13, v[0:1]
	v_lshl_add_u64 v[108:109], v[92:93], 0, v[0:1]
	v_add_u32_e32 v0, s27, v146
	v_ashrrev_i32_e32 v1, 31, v0
	v_lshlrev_b64 v[0:1], 13, v[0:1]
	v_lshl_add_u64 v[110:111], v[88:89], 0, v[0:1]
	v_add_u32_e32 v0, s27, v148
	v_ashrrev_i32_e32 v1, 31, v0
	v_lshlrev_b64 v[0:1], 13, v[0:1]
	v_lshl_add_u64 v[112:113], v[96:97], 0, v[0:1]
	s_mov_b64 s[16:17], 0
	s_mov_b32 s28, 0
	v_mov_b32_e32 v0, 0
	v_mov_b32_e32 v1, v73
	v_mov_b32_e32 v2, v73
	v_mov_b32_e32 v3, v73
	v_mov_b32_e32 v4, 0
	v_mov_b32_e32 v5, v73
	v_mov_b32_e32 v6, v73
	v_mov_b32_e32 v7, v73
	v_mov_b32_e32 v8, 0
	v_mov_b32_e32 v9, v73
	v_mov_b32_e32 v10, v73
	v_mov_b32_e32 v11, v73
	v_mov_b32_e32 v12, 0
	v_mov_b32_e32 v13, v73
	v_mov_b32_e32 v14, v73
	v_mov_b32_e32 v15, v73
	v_mov_b32_e32 v16, 0
	v_mov_b32_e32 v17, v73
	v_mov_b32_e32 v18, v73
	v_mov_b32_e32 v19, v73
	v_mov_b32_e32 v20, 0
	v_mov_b32_e32 v21, v73
	v_mov_b32_e32 v22, v73
	v_mov_b32_e32 v23, v73
	v_mov_b32_e32 v24, 0
	v_mov_b32_e32 v25, v73
	v_mov_b32_e32 v26, v73
	v_mov_b32_e32 v27, v73
	v_mov_b32_e32 v28, 0
	v_mov_b32_e32 v29, v73
	v_mov_b32_e32 v30, v73
	v_mov_b32_e32 v31, v73
	s_waitcnt vmcnt(0)
	v_mov_b32_e32 v32, 0
	v_mov_b32_e32 v33, v73
	v_mov_b32_e32 v34, v73
	v_mov_b32_e32 v35, v73
	v_mov_b32_e32 v36, 0
	v_mov_b32_e32 v37, v73
	v_mov_b32_e32 v38, v73
	v_mov_b32_e32 v39, v73
	v_mov_b32_e32 v40, 0
	v_mov_b32_e32 v41, v73
	v_mov_b32_e32 v42, v73
	v_mov_b32_e32 v43, v73
	v_mov_b32_e32 v44, 0
	v_mov_b32_e32 v45, v73
	v_mov_b32_e32 v46, v73
	v_mov_b32_e32 v47, v73
	v_mov_b32_e32 v48, 0
	v_mov_b32_e32 v49, v73
	v_mov_b32_e32 v50, v73
	v_mov_b32_e32 v51, v73
	v_mov_b32_e32 v52, 0
	v_mov_b32_e32 v53, v73
	v_mov_b32_e32 v54, v73
	v_mov_b32_e32 v55, v73
	v_mov_b32_e32 v56, 0
	v_mov_b32_e32 v57, v73
	v_mov_b32_e32 v58, v73
	v_mov_b32_e32 v59, v73
	v_mov_b32_e32 v60, 0
	v_mov_b32_e32 v61, v73
	v_mov_b32_e32 v62, v73
	v_mov_b32_e32 v63, v73
	s_waitcnt lgkmcnt(0)
	s_barrier
	v_lshlrev_b32_e32 v190, 1, v132
	v_lshlrev_b32_e32 v191, 1, v133
	v_add3_u32 v190, 0, v190, v191
	v_add_u32_e32 v192, 0x4000, v190
	s_nop 0
	v_readfirstlane_b32 s82, v192
	v_lshl_add_u32 v192, v118, 1, 0
	s_nop 0
	v_readfirstlane_b32 s83, v190
	v_add3_u32 v192, v192, v191, s21
	s_nop 0
	v_readfirstlane_b32 s84, v192
	v_add_u32_e32 v192, 0x400, v190
	s_nop 0
	v_readfirstlane_b32 s85, v192
	v_lshl_add_u32 v192, v119, 1, 0
	v_add3_u32 v192, v192, v191, s21
	s_nop 0
	v_readfirstlane_b32 s86, v192
	v_add_u32_e32 v192, 0x800, v190
	s_nop 0
	v_readfirstlane_b32 s87, v192
	v_lshl_add_u32 v192, v120, 1, 0
	v_add3_u32 v191, v192, v191, s21
	s_nop 0
	v_readfirstlane_b32 s88, v191
	v_add_u32_e32 v190, 0xc00, v190
	s_nop 0
	v_readfirstlane_b32 s89, v190
	v_subrev_u32_e32 v193, s52, v98
	v_subrev_u32_e32 v194, s52, v106
	v_subrev_u32_e32 v195, s52, v100
	v_subrev_u32_e32 v196, s52, v108
	v_subrev_u32_e32 v197, s52, v102
	v_subrev_u32_e32 v198, s52, v110
	v_subrev_u32_e32 v199, s52, v104
	v_subrev_u32_e32 v200, s52, v112
	s_bitcmp1_b32 s32, 0
	s_cbranch_scc1 .Lxk_2096
.LBB0_2096:
	s_and_b32 s29, s28, 0x4000
	s_xor_b32 s30, s29, 0x4000
	s_lshl_b32 s30, s30, 1
	s_add_i32 s30, s30, 32
	s_add_u32 s90, s52, s16
	s_addc_u32 s91, s53, s17
	s_add_i32 m0, s30, s82
	s_lshl_b32 s29, s29, 1
	global_load_lds_dwordx4 v193, s[90:91]
	s_add_i32 m0, s30, s83
	s_add_i32 s29, s29, 32
	global_load_lds_dwordx4 v194, s[90:91]
	s_add_i32 m0, s30, s84
	v_lshlrev_b32_e32 v72, 1, v131
	global_load_lds_dwordx4 v195, s[90:91]
	s_add_i32 m0, s30, s85
	v_add3_u32 v178, s29, v129, v72
	global_load_lds_dwordx4 v196, s[90:91]
	s_add_i32 m0, s30, s86
	v_lshlrev_b32_e32 v154, 1, v121
	global_load_lds_dwordx4 v197, s[90:91]
	s_add_i32 m0, s30, s87
	v_add3_u32 v72, s29, v130, v72
	global_load_lds_dwordx4 v198, s[90:91]
	s_add_i32 m0, s30, s88
	v_add_u32_e32 v174, v178, v154
	global_load_lds_dwordx4 v199, s[90:91]
	s_add_i32 m0, s30, s89
	v_add_u32_e32 v179, v72, v154
	global_load_lds_dwordx4 v200, s[90:91]
	ds_read_b128 v[154:157], v174
	ds_read_b128 v[162:165], v179 offset:16384
	ds_read_b128 v[166:169], v179 offset:18432
	ds_read_b128 v[182:185], v179 offset:20480
	ds_read_b128 v[186:189], v179 offset:22528
	ds_read_b128 v[158:161], v174 offset:2048
	ds_read_b128 v[170:173], v174 offset:4096
	ds_read_b128 v[174:177], v174 offset:6144
	v_lshlrev_b32_e32 v236, 1, v122
	v_add_u32_e32 v237, v178, v236
	v_add_u32_e32 v72, v72, v236
	ds_read_b128 v[204:207], v237
	ds_read_b128 v[208:211], v72 offset:16384
	ds_read_b128 v[212:215], v72 offset:18432
	ds_read_b128 v[216:219], v72 offset:20480
	ds_read_b128 v[220:223], v72 offset:22528
	ds_read_b128 v[224:227], v237 offset:2048
	ds_read_b128 v[228:231], v237 offset:4096
	ds_read_b128 v[232:235], v237 offset:6144
	s_setprio 1
	s_waitcnt lgkmcnt(11)
	v_mfma_f32_16x16x32_bf16 v[60:63], v[154:157], v[162:165], v[60:63]
	v_mfma_f32_16x16x32_bf16 v[56:59], v[154:157], v[166:169], v[56:59]
	v_mfma_f32_16x16x32_bf16 v[52:55], v[154:157], v[182:185], v[52:55]
	v_mfma_f32_16x16x32_bf16 v[48:51], v[154:157], v[186:189], v[48:51]
	s_waitcnt lgkmcnt(10)
	v_mfma_f32_16x16x32_bf16 v[44:47], v[158:161], v[162:165], v[44:47]
	v_mfma_f32_16x16x32_bf16 v[40:43], v[158:161], v[166:169], v[40:43]
	v_mfma_f32_16x16x32_bf16 v[36:39], v[158:161], v[182:185], v[36:39]
	v_mfma_f32_16x16x32_bf16 v[32:35], v[158:161], v[186:189], v[32:35]
	s_waitcnt lgkmcnt(9)
	v_mfma_f32_16x16x32_bf16 v[28:31], v[170:173], v[162:165], v[28:31]
	v_mfma_f32_16x16x32_bf16 v[24:27], v[170:173], v[166:169], v[24:27]
	v_mfma_f32_16x16x32_bf16 v[20:23], v[170:173], v[182:185], v[20:23]
	v_mfma_f32_16x16x32_bf16 v[16:19], v[170:173], v[186:189], v[16:19]
	s_waitcnt lgkmcnt(8)
	v_mfma_f32_16x16x32_bf16 v[12:15], v[174:177], v[162:165], v[12:15]
	v_mfma_f32_16x16x32_bf16 v[8:11], v[174:177], v[166:169], v[8:11]
	v_mfma_f32_16x16x32_bf16 v[4:7], v[174:177], v[182:185], v[4:7]
	v_mfma_f32_16x16x32_bf16 v[0:3], v[174:177], v[186:189], v[0:3]
	s_waitcnt lgkmcnt(3)
	v_mfma_f32_16x16x32_bf16 v[60:63], v[204:207], v[208:211], v[60:63]
	v_mfma_f32_16x16x32_bf16 v[56:59], v[204:207], v[212:215], v[56:59]
	v_mfma_f32_16x16x32_bf16 v[52:55], v[204:207], v[216:219], v[52:55]
	v_mfma_f32_16x16x32_bf16 v[48:51], v[204:207], v[220:223], v[48:51]
	s_waitcnt lgkmcnt(2)
	v_mfma_f32_16x16x32_bf16 v[44:47], v[224:227], v[208:211], v[44:47]
	v_mfma_f32_16x16x32_bf16 v[40:43], v[224:227], v[212:215], v[40:43]
	v_mfma_f32_16x16x32_bf16 v[36:39], v[224:227], v[216:219], v[36:39]
	v_mfma_f32_16x16x32_bf16 v[32:35], v[224:227], v[220:223], v[32:35]
	s_waitcnt lgkmcnt(1)
	v_mfma_f32_16x16x32_bf16 v[28:31], v[228:231], v[208:211], v[28:31]
	v_mfma_f32_16x16x32_bf16 v[24:27], v[228:231], v[212:215], v[24:27]
	v_mfma_f32_16x16x32_bf16 v[20:23], v[228:231], v[216:219], v[20:23]
	v_mfma_f32_16x16x32_bf16 v[16:19], v[228:231], v[220:223], v[16:19]
	s_waitcnt lgkmcnt(0)
	v_mfma_f32_16x16x32_bf16 v[12:15], v[232:235], v[208:211], v[12:15]
	v_mfma_f32_16x16x32_bf16 v[8:11], v[232:235], v[212:215], v[8:11]
	v_mfma_f32_16x16x32_bf16 v[4:7], v[232:235], v[216:219], v[4:7]
	v_mfma_f32_16x16x32_bf16 v[0:3], v[232:235], v[220:223], v[0:3]
	s_setprio 0
	s_add_u32 s16, s16, 0x80
	s_addc_u32 s17, s17, 0
	s_addk_i32 s28, 0x4000
	s_cmpk_eq_i32 s16, 0x1f80
	s_waitcnt vmcnt(0)
	s_barrier
	s_cbranch_scc0 .LBB0_2096
	s_branch .Lxk_exit_2096
.Lxk_2096:
	s_and_b32 s29, s28, 0x4000
	s_xor_b32 s30, s29, 0x4000
	s_lshl_b32 s30, s30, 1
	s_add_i32 s30, s30, 32
	s_add_u32 s90, s52, s16
	s_addc_u32 s91, s53, s17
	s_add_i32 m0, s30, s82
	s_lshl_b32 s29, s29, 1
	global_load_lds_dwordx4 v193, s[90:91]
	s_add_i32 m0, s30, s83
	s_add_i32 s29, s29, 32
	global_load_lds_dwordx4 v194, s[90:91]
	s_add_i32 m0, s30, s84
	v_lshlrev_b32_e32 v72, 1, v131
	global_load_lds_dwordx4 v195, s[90:91]
	s_add_i32 m0, s30, s85
	v_add3_u32 v178, s29, v129, v72
	global_load_lds_dwordx4 v196, s[90:91]
	s_add_i32 m0, s30, s86
	v_lshlrev_b32_e32 v154, 1, v121
	global_load_lds_dwordx4 v197, s[90:91]
	s_add_i32 m0, s30, s87
	v_add3_u32 v72, s29, v130, v72
	global_load_lds_dwordx4 v198, s[90:91]
	s_add_i32 m0, s30, s88
	v_add_u32_e32 v174, v178, v154
	global_load_lds_dwordx4 v199, s[90:91]
	s_add_i32 m0, s30, s89
	v_add_u32_e32 v179, v72, v154
	global_load_lds_dwordx4 v200, s[90:91]
	ds_read_b128 v[154:157], v174
	ds_read_b128 v[162:165], v179 offset:16384
	ds_read_b128 v[166:169], v179 offset:18432
	ds_read_b128 v[182:185], v179 offset:20480
	ds_read_b128 v[186:189], v179 offset:22528
	ds_read_b128 v[158:161], v174 offset:2048
	ds_read_b128 v[170:173], v174 offset:4096
	ds_read_b128 v[174:177], v174 offset:6144
	v_lshlrev_b32_e32 v236, 1, v122
	v_add_u32_e32 v237, v178, v236
	v_add_u32_e32 v72, v72, v236
	ds_read_b128 v[204:207], v237
	ds_read_b128 v[208:211], v72 offset:16384
	ds_read_b128 v[212:215], v72 offset:18432
	ds_read_b128 v[216:219], v72 offset:20480
	ds_read_b128 v[220:223], v72 offset:22528
	ds_read_b128 v[224:227], v237 offset:2048
	ds_read_b128 v[228:231], v237 offset:4096
	ds_read_b128 v[232:235], v237 offset:6144
	s_setprio 3
	s_waitcnt lgkmcnt(11)
	v_mfma_f32_16x16x32_bf16 v[60:63], v[154:157], v[162:165], v[60:63]
	v_mfma_f32_16x16x32_bf16 v[56:59], v[154:157], v[166:169], v[56:59]
	v_mfma_f32_16x16x32_bf16 v[52:55], v[154:157], v[182:185], v[52:55]
	v_mfma_f32_16x16x32_bf16 v[48:51], v[154:157], v[186:189], v[48:51]
	s_waitcnt lgkmcnt(10)
	v_mfma_f32_16x16x32_bf16 v[44:47], v[158:161], v[162:165], v[44:47]
	v_mfma_f32_16x16x32_bf16 v[40:43], v[158:161], v[166:169], v[40:43]
	v_mfma_f32_16x16x32_bf16 v[36:39], v[158:161], v[182:185], v[36:39]
	v_mfma_f32_16x16x32_bf16 v[32:35], v[158:161], v[186:189], v[32:35]
	s_waitcnt lgkmcnt(9)
	v_mfma_f32_16x16x32_bf16 v[28:31], v[170:173], v[162:165], v[28:31]
	v_mfma_f32_16x16x32_bf16 v[24:27], v[170:173], v[166:169], v[24:27]
	v_mfma_f32_16x16x32_bf16 v[20:23], v[170:173], v[182:185], v[20:23]
	v_mfma_f32_16x16x32_bf16 v[16:19], v[170:173], v[186:189], v[16:19]
	s_waitcnt lgkmcnt(8)
	v_mfma_f32_16x16x32_bf16 v[12:15], v[174:177], v[162:165], v[12:15]
	v_mfma_f32_16x16x32_bf16 v[8:11], v[174:177], v[166:169], v[8:11]
	v_mfma_f32_16x16x32_bf16 v[4:7], v[174:177], v[182:185], v[4:7]
	v_mfma_f32_16x16x32_bf16 v[0:3], v[174:177], v[186:189], v[0:3]
	s_waitcnt lgkmcnt(3)
	v_mfma_f32_16x16x32_bf16 v[60:63], v[204:207], v[208:211], v[60:63]
	v_mfma_f32_16x16x32_bf16 v[56:59], v[204:207], v[212:215], v[56:59]
	v_mfma_f32_16x16x32_bf16 v[52:55], v[204:207], v[216:219], v[52:55]
	v_mfma_f32_16x16x32_bf16 v[48:51], v[204:207], v[220:223], v[48:51]
	s_waitcnt lgkmcnt(2)
	v_mfma_f32_16x16x32_bf16 v[44:47], v[224:227], v[208:211], v[44:47]
	v_mfma_f32_16x16x32_bf16 v[40:43], v[224:227], v[212:215], v[40:43]
	v_mfma_f32_16x16x32_bf16 v[36:39], v[224:227], v[216:219], v[36:39]
	v_mfma_f32_16x16x32_bf16 v[32:35], v[224:227], v[220:223], v[32:35]
	s_waitcnt lgkmcnt(1)
	v_mfma_f32_16x16x32_bf16 v[28:31], v[228:231], v[208:211], v[28:31]
	v_mfma_f32_16x16x32_bf16 v[24:27], v[228:231], v[212:215], v[24:27]
	v_mfma_f32_16x16x32_bf16 v[20:23], v[228:231], v[216:219], v[20:23]
	v_mfma_f32_16x16x32_bf16 v[16:19], v[228:231], v[220:223], v[16:19]
	s_waitcnt lgkmcnt(0)
	v_mfma_f32_16x16x32_bf16 v[12:15], v[232:235], v[208:211], v[12:15]
	v_mfma_f32_16x16x32_bf16 v[8:11], v[232:235], v[212:215], v[8:11]
	v_mfma_f32_16x16x32_bf16 v[4:7], v[232:235], v[216:219], v[4:7]
	v_mfma_f32_16x16x32_bf16 v[0:3], v[232:235], v[220:223], v[0:3]
	s_setprio 2
	s_add_u32 s16, s16, 0x80
	s_addc_u32 s17, s17, 0
	s_addk_i32 s28, 0x4000
	s_cmpk_eq_i32 s16, 0x1f80
	s_waitcnt vmcnt(0)
	s_barrier
	s_cbranch_scc0 .Lxk_2096
.Lxk_exit_2096:
	ds_read_b128 v[98:101], v71 offset:32768
	ds_read_b128 v[102:105], v71 offset:34816
	ds_read_b128 v[106:109], v138 offset:49152
	ds_read_b128 v[110:113], v138 offset:51200
	ds_read_b128 v[154:157], v71 offset:36864
	ds_read_b128 v[158:161], v71 offset:38912
	ds_read_b128 v[162:165], v138 offset:53248
	ds_read_b128 v[166:169], v138 offset:55296
	s_setprio 1
	s_waitcnt lgkmcnt(1)
	v_mfma_f32_16x16x32_bf16 v[4:7], v[158:161], v[162:165], v[4:7]
	s_waitcnt lgkmcnt(0)
	v_mfma_f32_16x16x32_bf16 v[0:3], v[158:161], v[166:169], v[0:3]
	v_mfma_f32_16x16x32_bf16 v[60:63], v[98:101], v[106:109], v[60:63]
	v_mfma_f32_16x16x32_bf16 v[56:59], v[98:101], v[110:113], v[56:59]
	v_mfma_f32_16x16x32_bf16 v[52:55], v[98:101], v[162:165], v[52:55]
	v_mfma_f32_16x16x32_bf16 v[48:51], v[98:101], v[166:169], v[48:51]
	v_mfma_f32_16x16x32_bf16 v[44:47], v[102:105], v[106:109], v[44:47]
	v_mfma_f32_16x16x32_bf16 v[40:43], v[102:105], v[110:113], v[40:43]
	v_mfma_f32_16x16x32_bf16 v[36:39], v[102:105], v[162:165], v[36:39]
	v_mfma_f32_16x16x32_bf16 v[32:35], v[102:105], v[166:169], v[32:35]
	v_mfma_f32_16x16x32_bf16 v[28:31], v[154:157], v[106:109], v[28:31]
	v_mfma_f32_16x16x32_bf16 v[24:27], v[154:157], v[110:113], v[24:27]
	v_mfma_f32_16x16x32_bf16 v[20:23], v[154:157], v[162:165], v[20:23]
	v_mfma_f32_16x16x32_bf16 v[16:19], v[154:157], v[166:169], v[16:19]
	v_mfma_f32_16x16x32_bf16 v[12:15], v[158:161], v[106:109], v[12:15]
	v_mfma_f32_16x16x32_bf16 v[8:11], v[158:161], v[110:113], v[8:11]
	s_setprio 0
	ds_read_b128 v[98:101], v139 offset:32768
	ds_read_b128 v[102:105], v139 offset:34816
	ds_read_b128 v[106:109], v140 offset:49152
	ds_read_b128 v[110:113], v140 offset:51200
	ds_read_b128 v[154:157], v139 offset:36864
	ds_read_b128 v[158:161], v139 offset:38912
	ds_read_b128 v[162:165], v140 offset:53248
	ds_read_b128 v[166:169], v140 offset:55296
	s_setprio 1
	s_waitcnt lgkmcnt(1)
	v_mfma_f32_16x16x32_bf16 v[4:7], v[158:161], v[162:165], v[4:7]
	s_waitcnt lgkmcnt(0)
	v_mfma_f32_16x16x32_bf16 v[0:3], v[158:161], v[166:169], v[0:3]
	v_mfma_f32_16x16x32_bf16 v[60:63], v[98:101], v[106:109], v[60:63]
	v_mfma_f32_16x16x32_bf16 v[56:59], v[98:101], v[110:113], v[56:59]
	v_mfma_f32_16x16x32_bf16 v[52:55], v[98:101], v[162:165], v[52:55]
	v_mfma_f32_16x16x32_bf16 v[48:51], v[98:101], v[166:169], v[48:51]
	v_mfma_f32_16x16x32_bf16 v[44:47], v[102:105], v[106:109], v[44:47]
	v_mfma_f32_16x16x32_bf16 v[40:43], v[102:105], v[110:113], v[40:43]
	v_mfma_f32_16x16x32_bf16 v[36:39], v[102:105], v[162:165], v[36:39]
	v_mfma_f32_16x16x32_bf16 v[32:35], v[102:105], v[166:169], v[32:35]
	v_mfma_f32_16x16x32_bf16 v[28:31], v[154:157], v[106:109], v[28:31]
	v_mfma_f32_16x16x32_bf16 v[24:27], v[154:157], v[110:113], v[24:27]
	v_mfma_f32_16x16x32_bf16 v[20:23], v[154:157], v[162:165], v[20:23]
	v_mfma_f32_16x16x32_bf16 v[16:19], v[154:157], v[166:169], v[16:19]
	v_mfma_f32_16x16x32_bf16 v[12:15], v[158:161], v[106:109], v[12:15]
	v_mfma_f32_16x16x32_bf16 v[8:11], v[158:161], v[110:113], v[8:11]
	s_setprio 0
	s_barrier
	ds_write2_b32 v136, v60, v56 offset1:16
	ds_write2_b32 v136, v61, v57 offset0:132 offset1:148
	v_add_u32_e32 v56, 0x400, v136
	ds_write2_b32 v56, v62, v58 offset0:8 offset1:24
	ds_write2_b32 v56, v63, v59 offset0:140 offset1:156
	ds_write2_b32 v136, v52, v48 offset0:32 offset1:48
	ds_write2_b32 v136, v53, v49 offset0:164 offset1:180
	ds_write2_b32 v56, v54, v50 offset0:40 offset1:56
	ds_write2_b32 v56, v55, v51 offset0:172 offset1:188
	v_add_u32_e32 v48, 0x2000, v136
	ds_write2_b32 v48, v44, v40 offset0:64 offset1:80
	ds_write2_b32 v48, v45, v41 offset0:196 offset1:212
	v_add_u32_e32 v40, 0x2400, v136
	ds_write2_b32 v40, v46, v42 offset0:72 offset1:88
	ds_write2_b32 v40, v47, v43 offset0:204 offset1:220
	ds_write2_b32 v48, v36, v32 offset0:96 offset1:112
	ds_write2_b32 v48, v37, v33 offset0:228 offset1:244
	ds_write2_b32 v40, v38, v34 offset0:104 offset1:120
	ds_write2_b32 v40, v39, v35 offset0:236 offset1:252
	v_add_u32_e32 v32, 0x4000, v136
	ds_write2_b32 v32, v28, v24 offset0:128 offset1:144
	v_add_u32_e32 v24, 0x4400, v136
	ds_write2_b32 v24, v29, v25 offset0:4 offset1:20
	ds_write2_b32 v24, v30, v26 offset0:136 offset1:152
	v_add_u32_e32 v25, 0x4800, v136
	ds_write2_b32 v25, v31, v27 offset0:12 offset1:28
	ds_write2_b32 v32, v20, v16 offset0:160 offset1:176
	ds_write2_b32 v24, v21, v17 offset0:36 offset1:52
	ds_write2_b32 v24, v22, v18 offset0:168 offset1:184
	ds_write2_b32 v25, v23, v19 offset0:44 offset1:60
	v_add_u32_e32 v16, 0x6000, v136
	ds_write2_b32 v16, v12, v8 offset0:192 offset1:208
	v_add_u32_e32 v8, 0x6400, v136
	ds_write2_b32 v8, v13, v9 offset0:68 offset1:84
	ds_write2_b32 v8, v14, v10 offset0:200 offset1:216
	v_add_u32_e32 v9, 0x6800, v136
	ds_write2_b32 v9, v15, v11 offset0:76 offset1:92
	ds_write2_b32 v16, v4, v0 offset0:224 offset1:240
	ds_write2_b32 v8, v5, v1 offset0:100 offset1:116
	ds_write2_b32 v8, v6, v2 offset0:232 offset1:248
	ds_write2_b32 v9, v7, v3 offset0:108 offset1:124
	v_or_b32_e32 v0, s26, v137
	v_lshlrev_b32_e32 v72, 2, v0
	v_lshl_add_u64 v[0:1], s[14:15], 0, v[72:73]
	v_lshl_add_u64 v[2:3], s[12:13], 0, v[72:73]
	v_add_u32_e32 v4, s27, v149
	s_mov_b32 s16, 0
	s_waitcnt lgkmcnt(0)
	s_barrier

.LBB0_2101:
	s_ashr_i32 s17, s18, 2
	s_add_i32 s12, s17, 0x80
	s_and_b32 s16, s18, 3
	s_ashr_i32 s20, s12, 3
	s_add_i32 s21, s20, s19
	s_lshl_b32 s12, s16, 11
	s_add_u32 s8, s8, s12
	s_addc_u32 s9, s9, 0
	s_add_u32 s18, s10, s12
	s_addc_u32 s19, s11, 0
	s_lshl_b32 s11, s17, 7
	s_lshl_b32 s10, s21, 7
	s_and_b32 s11, s11, 0x380
	v_lshlrev_b32_e32 v83, 1, v2
	v_lshlrev_b32_e32 v84, 1, v3
	v_add_lshl_u32 v0, s11, v134, 13
	v_mov_b32_e32 v1, 0
	v_add3_u32 v20, 32, v83, v84
	v_add_u32_e32 v2, s10, v134
	v_lshl_add_u64 v[4:5], s[18:19], 0, v[0:1]
	v_add_u32_e32 v0, 0x4000, v20
	v_ashrrev_i32_e32 v3, 31, v2
	v_mov_b32_e32 v71, v1
	v_readfirstlane_b32 s21, v0
	v_lshlrev_b64 v[2:3], 13, v[2:3]
	v_lshl_add_u64 v[4:5], v[4:5], 0, v[70:71]
	s_mov_b32 m0, s21
	v_lshl_add_u64 v[2:3], s[8:9], 0, v[2:3]
	v_readfirstlane_b32 s21, v20
	global_load_lds_dwordx4 v[4:5], off
	v_lshl_add_u64 v[2:3], v[2:3], 0, v[70:71]
	s_mov_b32 m0, s21
	v_add_lshl_u32 v0, v126, s11, 12
	s_movk_i32 s17, 0x4000
	global_load_lds_dwordx4 v[2:3], off
	v_lshlrev_b64 v[2:3], 1, v[0:1]
	v_lshl_add_u32 v0, v118, 1, 32
	v_add3_u32 v0, v0, v84, s17
	v_lshl_add_u64 v[4:5], s[18:19], 0, v[2:3]
	v_lshlrev_b64 v[6:7], 1, v[66:67]
	v_readfirstlane_b32 s21, v0
	v_lshl_add_u64 v[4:5], v[4:5], 0, v[6:7]
	s_mov_b32 m0, s21
	v_add_u32_e32 v0, 0x400, v20
	global_load_lds_dwordx4 v[4:5], off
	v_add_u32_e32 v4, s10, v126
	v_ashrrev_i32_e32 v5, 31, v4
	v_lshlrev_b64 v[4:5], 13, v[4:5]
	v_lshl_add_u64 v[8:9], s[8:9], 0, v[4:5]
	v_readfirstlane_b32 s21, v0
	v_lshl_add_u64 v[8:9], v[8:9], 0, v[6:7]
	s_mov_b32 m0, s21
	v_add_lshl_u32 v0, v127, s11, 12
	global_load_lds_dwordx4 v[8:9], off
	v_lshlrev_b64 v[8:9], 1, v[0:1]
	v_lshl_add_u32 v0, v119, 1, 32
	v_add3_u32 v0, v0, v84, s17
	v_lshl_add_u64 v[10:11], s[18:19], 0, v[8:9]
	v_readfirstlane_b32 s21, v0
	v_lshl_add_u64 v[10:11], v[10:11], 0, v[70:71]
	s_mov_b32 m0, s21
	v_add_u32_e32 v0, 0x800, v20
	global_load_lds_dwordx4 v[10:11], off
	v_add_u32_e32 v10, s10, v127
	v_ashrrev_i32_e32 v11, 31, v10
	v_lshlrev_b64 v[10:11], 13, v[10:11]
	v_lshl_add_u64 v[12:13], s[8:9], 0, v[10:11]
	v_readfirstlane_b32 s21, v0
	v_lshl_add_u64 v[12:13], v[12:13], 0, v[70:71]
	s_mov_b32 m0, s21
	v_add_lshl_u32 v0, v125, s11, 12
	global_load_lds_dwordx4 v[12:13], off
	v_lshlrev_b64 v[12:13], 1, v[0:1]
	v_lshl_add_u32 v0, v120, 1, 32
	v_add3_u32 v0, v0, v84, s17
	v_lshl_add_u64 v[14:15], s[18:19], 0, v[12:13]
	v_lshlrev_b64 v[16:17], 1, v[68:69]
	v_readfirstlane_b32 s18, v0
	v_lshl_add_u64 v[14:15], v[14:15], 0, v[16:17]
	s_mov_b32 m0, s18
	v_add_u32_e32 v0, 0xc00, v20
	global_load_lds_dwordx4 v[14:15], off
	v_add_u32_e32 v14, s10, v125
	v_ashrrev_i32_e32 v15, 31, v14
	v_lshlrev_b64 v[14:15], 13, v[14:15]
	v_lshl_add_u64 v[18:19], s[8:9], 0, v[14:15]
	v_readfirstlane_b32 s8, v0
	v_lshl_add_u64 v[18:19], v[18:19], 0, v[16:17]
	s_mov_b32 m0, s8
	s_mov_b32 s13, 0
	global_load_lds_dwordx4 v[18:19], off
	v_or_b32_e32 v0, s11, v124
	v_lshl_add_u64 v[6:7], s[12:13], 0, v[6:7]
	v_add_lshl_u32 v0, v0, v123, 13
	v_lshl_add_u64 v[18:19], s[12:13], 0, v[64:65]
	v_lshl_add_u64 v[2:3], v[6:7], 0, v[2:3]
	v_lshl_add_u64 v[20:21], v[18:19], 0, v[0:1]
	s_mov_b64 s[8:9], 0x800080
	v_lshl_add_u64 v[2:3], s[6:7], 0, v[2:3]
	v_lshl_add_u64 v[20:21], s[6:7], 0, v[20:21]
	s_lshl_b32 s18, s20, 7
	v_lshl_add_u64 v[68:69], v[2:3], 0, s[8:9]
	v_lshl_add_u64 v[2:3], v[6:7], 0, v[4:5]
	v_lshl_add_u64 v[64:65], v[20:21], 0, s[8:9]
	v_add3_u32 v20, v128, s18, v123
	s_mov_b64 s[18:19], 0x8600080
	v_lshl_add_u64 v[2:3], s[6:7], 0, v[2:3]
	v_lshl_add_u64 v[70:71], v[2:3], 0, s[18:19]
	v_lshl_add_u64 v[2:3], v[18:19], 0, v[8:9]
	v_lshl_add_u64 v[2:3], s[6:7], 0, v[2:3]
	v_lshl_add_u64 v[72:73], v[2:3], 0, s[8:9]
	v_lshl_add_u64 v[2:3], v[18:19], 0, v[10:11]
	v_ashrrev_i32_e32 v21, 31, v20
	v_lshl_add_u64 v[2:3], s[6:7], 0, v[2:3]
	v_lshlrev_b64 v[20:21], 13, v[20:21]
	v_lshl_add_u64 v[74:75], v[2:3], 0, s[18:19]
	v_lshl_add_u64 v[2:3], s[12:13], 0, v[16:17]
	v_lshl_add_u64 v[20:21], v[18:19], 0, v[20:21]
	v_lshl_add_u64 v[4:5], v[2:3], 0, v[12:13]
	v_lshl_add_u64 v[2:3], v[2:3], 0, v[14:15]
	v_lshl_add_u64 v[20:21], s[6:7], 0, v[20:21]
	v_lshl_add_u64 v[4:5], s[6:7], 0, v[4:5]
	v_lshl_add_u64 v[2:3], s[6:7], 0, v[2:3]
	v_lshl_add_u64 v[66:67], v[20:21], 0, s[18:19]
	v_lshl_add_u64 v[76:77], v[4:5], 0, s[8:9]
	v_lshl_add_u64 v[78:79], v[2:3], 0, s[18:19]
	s_mov_b64 s[6:7], 0
	v_mov_b32_e32 v0, v1
	v_mov_b32_e32 v2, v1
	v_mov_b32_e32 v3, v1
	v_mov_b32_e32 v4, v1
	v_mov_b32_e32 v5, v1
	v_mov_b32_e32 v6, v1
	v_mov_b32_e32 v7, v1
	v_mov_b32_e32 v8, v1
	v_mov_b32_e32 v9, v1
	v_mov_b32_e32 v10, v1
	v_mov_b32_e32 v11, v1
	v_mov_b32_e32 v12, v1
	v_mov_b32_e32 v13, v1
	v_mov_b32_e32 v14, v1
	v_mov_b32_e32 v15, v1
	v_mov_b32_e32 v16, v1
	v_mov_b32_e32 v17, v1
	v_mov_b32_e32 v18, v1
	v_mov_b32_e32 v19, v1
	v_mov_b32_e32 v20, v1
	v_mov_b32_e32 v21, v1
	v_mov_b32_e32 v22, v1
	v_mov_b32_e32 v23, v1
	v_mov_b32_e32 v24, v1
	v_mov_b32_e32 v25, v1
	v_mov_b32_e32 v26, v1
	v_mov_b32_e32 v27, v1
	v_mov_b32_e32 v28, v1
	v_mov_b32_e32 v29, v1
	v_mov_b32_e32 v30, v1
	v_mov_b32_e32 v31, v1
	s_waitcnt vmcnt(0)
	v_mov_b32_e32 v32, v1
	v_mov_b32_e32 v33, v1
	v_mov_b32_e32 v34, v1
	v_mov_b32_e32 v35, v1
	v_mov_b32_e32 v36, v1
	v_mov_b32_e32 v37, v1
	v_mov_b32_e32 v38, v1
	v_mov_b32_e32 v39, v1
	v_mov_b32_e32 v40, v1
	v_mov_b32_e32 v41, v1
	v_mov_b32_e32 v42, v1
	v_mov_b32_e32 v43, v1
	v_mov_b32_e32 v44, v1
	v_mov_b32_e32 v45, v1
	v_mov_b32_e32 v46, v1
	v_mov_b32_e32 v47, v1
	v_mov_b32_e32 v48, v1
	v_mov_b32_e32 v49, v1
	v_mov_b32_e32 v50, v1
	v_mov_b32_e32 v51, v1
	v_mov_b32_e32 v52, v1
	v_mov_b32_e32 v53, v1
	v_mov_b32_e32 v54, v1
	v_mov_b32_e32 v55, v1
	v_mov_b32_e32 v56, v1
	v_mov_b32_e32 v57, v1
	v_mov_b32_e32 v58, v1
	v_mov_b32_e32 v59, v1
	v_mov_b32_e32 v60, v1
	v_mov_b32_e32 v61, v1
	v_mov_b32_e32 v62, v1
	v_mov_b32_e32 v63, v1
	s_waitcnt lgkmcnt(0)
	s_barrier
	v_add3_u32 v190, 0, v83, v84
	v_add_u32_e32 v191, 0x4000, v190
	s_nop 0
	v_readfirstlane_b32 s82, v191
	v_lshl_add_u32 v191, v118, 1, 0
	s_nop 0
	v_readfirstlane_b32 s83, v190
	v_add3_u32 v191, v191, v84, s17
	s_nop 0
	v_readfirstlane_b32 s84, v191
	v_add_u32_e32 v191, 0x400, v190
	s_nop 0
	v_readfirstlane_b32 s85, v191
	v_lshl_add_u32 v191, v119, 1, 0
	v_add3_u32 v191, v191, v84, s17
	s_nop 0
	v_readfirstlane_b32 s86, v191
	v_add_u32_e32 v191, 0x800, v190
	s_nop 0
	v_readfirstlane_b32 s87, v191
	v_lshl_add_u32 v191, v120, 1, 0
	v_add3_u32 v191, v191, v84, s17
	s_nop 0
	v_readfirstlane_b32 s88, v191
	v_add_u32_e32 v190, 0xc00, v190
	s_nop 0
	v_readfirstlane_b32 s89, v190
	v_subrev_u32_e32 v192, s52, v64
	v_subrev_u32_e32 v193, s52, v66
	v_subrev_u32_e32 v194, s52, v68
	v_subrev_u32_e32 v195, s52, v70
	v_subrev_u32_e32 v196, s52, v72
	v_subrev_u32_e32 v197, s52, v74
	v_subrev_u32_e32 v198, s52, v76
	v_subrev_u32_e32 v199, s52, v78
	s_bitcmp1_b32 s32, 0
	s_cbranch_scc1 .Lxk_2102
.LBB0_2102:
	s_and_b32 s8, s13, 0x4000
	s_xor_b32 s9, s8, 0x4000
	s_lshl_b32 s9, s9, 1
	s_add_i32 s9, s9, 32
	s_add_u32 s90, s52, s6
	s_addc_u32 s91, s53, s7
	s_add_i32 m0, s9, s82
	s_lshl_b32 s8, s8, 1
	global_load_lds_dwordx4 v192, s[90:91]
	s_add_i32 m0, s9, s83
	s_add_i32 s8, s8, 32
	global_load_lds_dwordx4 v193, s[90:91]
	s_add_i32 m0, s9, s84
	v_lshlrev_b32_e32 v85, 1, v80
	global_load_lds_dwordx4 v194, s[90:91]
	s_add_i32 m0, s9, s85
	v_add3_u32 v112, s8, v81, v85
	global_load_lds_dwordx4 v195, s[90:91]
	s_add_i32 m0, s9, s86
	v_lshlrev_b32_e32 v86, 1, v121
	global_load_lds_dwordx4 v196, s[90:91]
	s_add_i32 m0, s9, s87
	v_add3_u32 v113, s8, v82, v85
	global_load_lds_dwordx4 v197, s[90:91]
	s_add_i32 m0, s9, s88
	v_add_u32_e32 v87, v112, v86
	global_load_lds_dwordx4 v198, s[90:91]
	s_add_i32 m0, s9, s89
	v_add_u32_e32 v123, v113, v86
	global_load_lds_dwordx4 v199, s[90:91]
	ds_read_b128 v[88:91], v87
	ds_read_b128 v[96:99], v123 offset:16384
	ds_read_b128 v[100:103], v123 offset:18432
	ds_read_b128 v[124:127], v123 offset:20480
	ds_read_b128 v[128:131], v123 offset:22528
	ds_read_b128 v[92:95], v87 offset:2048
	ds_read_b128 v[104:107], v87 offset:4096
	ds_read_b128 v[108:111], v87 offset:6144
	v_lshlrev_b32_e32 v87, 1, v122
	v_add_u32_e32 v236, v112, v87
	v_add_u32_e32 v112, v113, v87
	ds_read_b128 v[204:207], v236
	ds_read_b128 v[208:211], v112 offset:16384
	ds_read_b128 v[212:215], v112 offset:18432
	ds_read_b128 v[216:219], v112 offset:20480
	ds_read_b128 v[220:223], v112 offset:22528
	ds_read_b128 v[224:227], v236 offset:2048
	ds_read_b128 v[228:231], v236 offset:4096
	ds_read_b128 v[232:235], v236 offset:6144
	s_setprio 1
	s_waitcnt lgkmcnt(11)
	v_mfma_f32_16x16x32_bf16 v[60:63], v[88:91], v[96:99], v[60:63]
	v_mfma_f32_16x16x32_bf16 v[56:59], v[88:91], v[100:103], v[56:59]
	v_mfma_f32_16x16x32_bf16 v[52:55], v[88:91], v[124:127], v[52:55]
	v_mfma_f32_16x16x32_bf16 v[48:51], v[88:91], v[128:131], v[48:51]
	s_waitcnt lgkmcnt(10)
	v_mfma_f32_16x16x32_bf16 v[44:47], v[92:95], v[96:99], v[44:47]
	v_mfma_f32_16x16x32_bf16 v[40:43], v[92:95], v[100:103], v[40:43]
	v_mfma_f32_16x16x32_bf16 v[36:39], v[92:95], v[124:127], v[36:39]
	v_mfma_f32_16x16x32_bf16 v[32:35], v[92:95], v[128:131], v[32:35]
	s_waitcnt lgkmcnt(9)
	v_mfma_f32_16x16x32_bf16 v[28:31], v[104:107], v[96:99], v[28:31]
	v_mfma_f32_16x16x32_bf16 v[24:27], v[104:107], v[100:103], v[24:27]
	v_mfma_f32_16x16x32_bf16 v[20:23], v[104:107], v[124:127], v[20:23]
	v_mfma_f32_16x16x32_bf16 v[16:19], v[104:107], v[128:131], v[16:19]
	s_waitcnt lgkmcnt(8)
	v_mfma_f32_16x16x32_bf16 v[12:15], v[108:111], v[96:99], v[12:15]
	v_mfma_f32_16x16x32_bf16 v[8:11], v[108:111], v[100:103], v[8:11]
	v_mfma_f32_16x16x32_bf16 v[4:7], v[108:111], v[124:127], v[4:7]
	v_mfma_f32_16x16x32_bf16 v[0:3], v[108:111], v[128:131], v[0:3]
	s_waitcnt lgkmcnt(3)
	v_mfma_f32_16x16x32_bf16 v[60:63], v[204:207], v[208:211], v[60:63]
	v_mfma_f32_16x16x32_bf16 v[56:59], v[204:207], v[212:215], v[56:59]
	v_mfma_f32_16x16x32_bf16 v[52:55], v[204:207], v[216:219], v[52:55]
	v_mfma_f32_16x16x32_bf16 v[48:51], v[204:207], v[220:223], v[48:51]
	s_waitcnt lgkmcnt(2)
	v_mfma_f32_16x16x32_bf16 v[44:47], v[224:227], v[208:211], v[44:47]
	v_mfma_f32_16x16x32_bf16 v[40:43], v[224:227], v[212:215], v[40:43]
	v_mfma_f32_16x16x32_bf16 v[36:39], v[224:227], v[216:219], v[36:39]
	v_mfma_f32_16x16x32_bf16 v[32:35], v[224:227], v[220:223], v[32:35]
	s_waitcnt lgkmcnt(1)
	v_mfma_f32_16x16x32_bf16 v[28:31], v[228:231], v[208:211], v[28:31]
	v_mfma_f32_16x16x32_bf16 v[24:27], v[228:231], v[212:215], v[24:27]
	v_mfma_f32_16x16x32_bf16 v[20:23], v[228:231], v[216:219], v[20:23]
	v_mfma_f32_16x16x32_bf16 v[16:19], v[228:231], v[220:223], v[16:19]
	s_waitcnt lgkmcnt(0)
	v_mfma_f32_16x16x32_bf16 v[12:15], v[232:235], v[208:211], v[12:15]
	v_mfma_f32_16x16x32_bf16 v[8:11], v[232:235], v[212:215], v[8:11]
	v_mfma_f32_16x16x32_bf16 v[4:7], v[232:235], v[216:219], v[4:7]
	v_mfma_f32_16x16x32_bf16 v[0:3], v[232:235], v[220:223], v[0:3]
	s_setprio 0
	s_add_u32 s6, s6, 0x80
	s_addc_u32 s7, s7, 0
	s_addk_i32 s13, 0x4000
	s_cmpk_eq_i32 s6, 0x780
	s_waitcnt vmcnt(0)
	s_barrier
	s_cbranch_scc0 .LBB0_2102
	s_branch .Lxk_exit_2102
.Lxk_2102:
	s_and_b32 s8, s13, 0x4000
	s_xor_b32 s9, s8, 0x4000
	s_lshl_b32 s9, s9, 1
	s_add_i32 s9, s9, 32
	s_add_u32 s90, s52, s6
	s_addc_u32 s91, s53, s7
	s_add_i32 m0, s9, s82
	s_lshl_b32 s8, s8, 1
	global_load_lds_dwordx4 v192, s[90:91]
	s_add_i32 m0, s9, s83
	s_add_i32 s8, s8, 32
	global_load_lds_dwordx4 v193, s[90:91]
	s_add_i32 m0, s9, s84
	v_lshlrev_b32_e32 v85, 1, v80
	global_load_lds_dwordx4 v194, s[90:91]
	s_add_i32 m0, s9, s85
	v_add3_u32 v112, s8, v81, v85
	global_load_lds_dwordx4 v195, s[90:91]
	s_add_i32 m0, s9, s86
	v_lshlrev_b32_e32 v86, 1, v121
	global_load_lds_dwordx4 v196, s[90:91]
	s_add_i32 m0, s9, s87
	v_add3_u32 v113, s8, v82, v85
	global_load_lds_dwordx4 v197, s[90:91]
	s_add_i32 m0, s9, s88
	v_add_u32_e32 v87, v112, v86
	global_load_lds_dwordx4 v198, s[90:91]
	s_add_i32 m0, s9, s89
	v_add_u32_e32 v123, v113, v86
	global_load_lds_dwordx4 v199, s[90:91]
	ds_read_b128 v[88:91], v87
	ds_read_b128 v[96:99], v123 offset:16384
	ds_read_b128 v[100:103], v123 offset:18432
	ds_read_b128 v[124:127], v123 offset:20480
	ds_read_b128 v[128:131], v123 offset:22528
	ds_read_b128 v[92:95], v87 offset:2048
	ds_read_b128 v[104:107], v87 offset:4096
	ds_read_b128 v[108:111], v87 offset:6144
	v_lshlrev_b32_e32 v87, 1, v122
	v_add_u32_e32 v236, v112, v87
	v_add_u32_e32 v112, v113, v87
	ds_read_b128 v[204:207], v236
	ds_read_b128 v[208:211], v112 offset:16384
	ds_read_b128 v[212:215], v112 offset:18432
	ds_read_b128 v[216:219], v112 offset:20480
	ds_read_b128 v[220:223], v112 offset:22528
	ds_read_b128 v[224:227], v236 offset:2048
	ds_read_b128 v[228:231], v236 offset:4096
	ds_read_b128 v[232:235], v236 offset:6144
	s_setprio 3
	s_waitcnt lgkmcnt(11)
	v_mfma_f32_16x16x32_bf16 v[60:63], v[88:91], v[96:99], v[60:63]
	v_mfma_f32_16x16x32_bf16 v[56:59], v[88:91], v[100:103], v[56:59]
	v_mfma_f32_16x16x32_bf16 v[52:55], v[88:91], v[124:127], v[52:55]
	v_mfma_f32_16x16x32_bf16 v[48:51], v[88:91], v[128:131], v[48:51]
	s_waitcnt lgkmcnt(10)
	v_mfma_f32_16x16x32_bf16 v[44:47], v[92:95], v[96:99], v[44:47]
	v_mfma_f32_16x16x32_bf16 v[40:43], v[92:95], v[100:103], v[40:43]
	v_mfma_f32_16x16x32_bf16 v[36:39], v[92:95], v[124:127], v[36:39]
	v_mfma_f32_16x16x32_bf16 v[32:35], v[92:95], v[128:131], v[32:35]
	s_waitcnt lgkmcnt(9)
	v_mfma_f32_16x16x32_bf16 v[28:31], v[104:107], v[96:99], v[28:31]
	v_mfma_f32_16x16x32_bf16 v[24:27], v[104:107], v[100:103], v[24:27]
	v_mfma_f32_16x16x32_bf16 v[20:23], v[104:107], v[124:127], v[20:23]
	v_mfma_f32_16x16x32_bf16 v[16:19], v[104:107], v[128:131], v[16:19]
	s_waitcnt lgkmcnt(8)
	v_mfma_f32_16x16x32_bf16 v[12:15], v[108:111], v[96:99], v[12:15]
	v_mfma_f32_16x16x32_bf16 v[8:11], v[108:111], v[100:103], v[8:11]
	v_mfma_f32_16x16x32_bf16 v[4:7], v[108:111], v[124:127], v[4:7]
	v_mfma_f32_16x16x32_bf16 v[0:3], v[108:111], v[128:131], v[0:3]
	s_waitcnt lgkmcnt(3)
	v_mfma_f32_16x16x32_bf16 v[60:63], v[204:207], v[208:211], v[60:63]
	v_mfma_f32_16x16x32_bf16 v[56:59], v[204:207], v[212:215], v[56:59]
	v_mfma_f32_16x16x32_bf16 v[52:55], v[204:207], v[216:219], v[52:55]
	v_mfma_f32_16x16x32_bf16 v[48:51], v[204:207], v[220:223], v[48:51]
	s_waitcnt lgkmcnt(2)
	v_mfma_f32_16x16x32_bf16 v[44:47], v[224:227], v[208:211], v[44:47]
	v_mfma_f32_16x16x32_bf16 v[40:43], v[224:227], v[212:215], v[40:43]
	v_mfma_f32_16x16x32_bf16 v[36:39], v[224:227], v[216:219], v[36:39]
	v_mfma_f32_16x16x32_bf16 v[32:35], v[224:227], v[220:223], v[32:35]
	s_waitcnt lgkmcnt(1)
	v_mfma_f32_16x16x32_bf16 v[28:31], v[228:231], v[208:211], v[28:31]
	v_mfma_f32_16x16x32_bf16 v[24:27], v[228:231], v[212:215], v[24:27]
	v_mfma_f32_16x16x32_bf16 v[20:23], v[228:231], v[216:219], v[20:23]
	v_mfma_f32_16x16x32_bf16 v[16:19], v[228:231], v[220:223], v[16:19]
	s_waitcnt lgkmcnt(0)
	v_mfma_f32_16x16x32_bf16 v[12:15], v[232:235], v[208:211], v[12:15]
	v_mfma_f32_16x16x32_bf16 v[8:11], v[232:235], v[212:215], v[8:11]
	v_mfma_f32_16x16x32_bf16 v[4:7], v[232:235], v[216:219], v[4:7]
	v_mfma_f32_16x16x32_bf16 v[0:3], v[232:235], v[220:223], v[0:3]
	s_setprio 2
	s_add_u32 s6, s6, 0x80
	s_addc_u32 s7, s7, 0
	s_addk_i32 s13, 0x4000
	s_cmpk_eq_i32 s6, 0x780
	s_waitcnt vmcnt(0)
	s_barrier
	s_cbranch_scc0 .Lxk_2102
.Lxk_exit_2102:
	v_add3_u32 v84, 32, v81, v85
	v_add3_u32 v85, 32, v82, v85
	v_add_u32_e32 v88, v84, v86
	v_add_u32_e32 v86, v85, v86
	ds_read_b128 v[64:67], v88 offset:32768
	ds_read_b128 v[68:71], v88 offset:34816
	ds_read_b128 v[72:75], v86 offset:49152
	ds_read_b128 v[76:79], v86 offset:51200
	ds_read_b128 v[80:83], v88 offset:36864
	ds_read_b128 v[88:91], v88 offset:38912
	ds_read_b128 v[92:95], v86 offset:53248
	ds_read_b128 v[96:99], v86 offset:55296
	s_setprio 1
	s_waitcnt lgkmcnt(0)
	v_mfma_f32_16x16x32_bf16 v[0:3], v[88:91], v[96:99], v[0:3]
	v_mfma_f32_16x16x32_bf16 v[60:63], v[64:67], v[72:75], v[60:63]
	v_mfma_f32_16x16x32_bf16 v[56:59], v[64:67], v[76:79], v[56:59]
	v_mfma_f32_16x16x32_bf16 v[52:55], v[64:67], v[92:95], v[52:55]
	v_mfma_f32_16x16x32_bf16 v[48:51], v[64:67], v[96:99], v[48:51]
	v_mfma_f32_16x16x32_bf16 v[44:47], v[68:71], v[72:75], v[44:47]
	v_mfma_f32_16x16x32_bf16 v[40:43], v[68:71], v[76:79], v[40:43]
	v_mfma_f32_16x16x32_bf16 v[36:39], v[68:71], v[92:95], v[36:39]
	v_mfma_f32_16x16x32_bf16 v[32:35], v[68:71], v[96:99], v[32:35]
	v_mfma_f32_16x16x32_bf16 v[28:31], v[80:83], v[72:75], v[28:31]
	v_mfma_f32_16x16x32_bf16 v[24:27], v[80:83], v[76:79], v[24:27]
	v_mfma_f32_16x16x32_bf16 v[20:23], v[80:83], v[92:95], v[20:23]
	v_mfma_f32_16x16x32_bf16 v[16:19], v[80:83], v[96:99], v[16:19]
	v_mfma_f32_16x16x32_bf16 v[12:15], v[88:91], v[72:75], v[12:15]
	v_mfma_f32_16x16x32_bf16 v[8:11], v[88:91], v[76:79], v[8:11]
	v_mfma_f32_16x16x32_bf16 v[4:7], v[88:91], v[92:95], v[4:7]
	s_setprio 0
	v_add_u32_e32 v84, v84, v87
	v_add_u32_e32 v92, v85, v87
	ds_read_b128 v[64:67], v84 offset:32768
	ds_read_b128 v[68:71], v84 offset:34816
	ds_read_b128 v[72:75], v92 offset:49152
	ds_read_b128 v[76:79], v92 offset:51200
	ds_read_b128 v[80:83], v84 offset:36864
	ds_read_b128 v[84:87], v84 offset:38912
	ds_read_b128 v[88:91], v92 offset:53248
	ds_read_b128 v[92:95], v92 offset:55296
	s_setprio 1
	s_waitcnt lgkmcnt(0)
	v_mfma_f32_16x16x32_bf16 v[0:3], v[84:87], v[92:95], v[0:3]
	v_mfma_f32_16x16x32_bf16 v[60:63], v[64:67], v[72:75], v[60:63]
	v_mfma_f32_16x16x32_bf16 v[56:59], v[64:67], v[76:79], v[56:59]
	v_mfma_f32_16x16x32_bf16 v[52:55], v[64:67], v[88:91], v[52:55]
	v_mfma_f32_16x16x32_bf16 v[48:51], v[64:67], v[92:95], v[48:51]
	v_mfma_f32_16x16x32_bf16 v[44:47], v[68:71], v[72:75], v[44:47]
	v_mfma_f32_16x16x32_bf16 v[40:43], v[68:71], v[76:79], v[40:43]
	v_mfma_f32_16x16x32_bf16 v[36:39], v[68:71], v[88:91], v[36:39]
	v_mfma_f32_16x16x32_bf16 v[32:35], v[68:71], v[92:95], v[32:35]
	v_mfma_f32_16x16x32_bf16 v[28:31], v[80:83], v[72:75], v[28:31]
	v_mfma_f32_16x16x32_bf16 v[24:27], v[80:83], v[76:79], v[24:27]
	v_mfma_f32_16x16x32_bf16 v[20:23], v[80:83], v[88:91], v[20:23]
	v_mfma_f32_16x16x32_bf16 v[16:19], v[80:83], v[92:95], v[16:19]
	v_mfma_f32_16x16x32_bf16 v[12:15], v[84:87], v[72:75], v[12:15]
	v_mfma_f32_16x16x32_bf16 v[8:11], v[84:87], v[76:79], v[8:11]
	v_mfma_f32_16x16x32_bf16 v[4:7], v[84:87], v[88:91], v[4:7]
	s_setprio 0
	v_lshl_or_b32 v64, v114, 2, v116
	v_mul_u32_u24_e32 v64, 0x210, v64
	v_add3_u32 v64, v115, v117, v64
	s_barrier
	ds_write2_b32 v64, v60, v56 offset1:16
	ds_write2_b32 v64, v61, v57 offset0:132 offset1:148
	v_add_u32_e32 v56, 0x400, v64
	ds_write2_b32 v56, v62, v58 offset0:8 offset1:24
	ds_write2_b32 v56, v63, v59 offset0:140 offset1:156
	ds_write2_b32 v64, v52, v48 offset0:32 offset1:48
	ds_write2_b32 v64, v53, v49 offset0:164 offset1:180
	ds_write2_b32 v56, v54, v50 offset0:40 offset1:56
	ds_write2_b32 v56, v55, v51 offset0:172 offset1:188
	v_add_u32_e32 v48, 0x2000, v64
	ds_write2_b32 v48, v44, v40 offset0:64 offset1:80
	ds_write2_b32 v48, v45, v41 offset0:196 offset1:212
	v_add_u32_e32 v40, 0x2400, v64
	ds_write2_b32 v40, v46, v42 offset0:72 offset1:88
	ds_write2_b32 v40, v47, v43 offset0:204 offset1:220
	ds_write2_b32 v48, v36, v32 offset0:96 offset1:112
	ds_write2_b32 v48, v37, v33 offset0:228 offset1:244
	ds_write2_b32 v40, v38, v34 offset0:104 offset1:120
	ds_write2_b32 v40, v39, v35 offset0:236 offset1:252
	v_add_u32_e32 v32, 0x4000, v64
	ds_write2_b32 v32, v28, v24 offset0:128 offset1:144
	v_add_u32_e32 v24, 0x4400, v64
	ds_write2_b32 v24, v29, v25 offset0:4 offset1:20
	ds_write2_b32 v24, v30, v26 offset0:136 offset1:152
	v_add_u32_e32 v25, 0x4800, v64
	ds_write2_b32 v25, v31, v27 offset0:12 offset1:28
	ds_write2_b32 v32, v20, v16 offset0:160 offset1:176
	ds_write2_b32 v24, v21, v17 offset0:36 offset1:52
	ds_write2_b32 v24, v22, v18 offset0:168 offset1:184
	ds_write2_b32 v25, v23, v19 offset0:44 offset1:60
	v_add_u32_e32 v16, 0x6000, v64
	ds_write2_b32 v16, v12, v8 offset0:192 offset1:208
	v_add_u32_e32 v8, 0x6400, v64
	ds_write2_b32 v8, v13, v9 offset0:68 offset1:84
	ds_write2_b32 v8, v14, v10 offset0:200 offset1:216
	v_add_u32_e32 v9, 0x6800, v64
	ds_write2_b32 v9, v15, v11 offset0:76 offset1:92
	ds_write2_b32 v16, v4, v0 offset0:224 offset1:240
	ds_write2_b32 v8, v5, v1 offset0:100 offset1:116
	ds_write2_b32 v8, v6, v2 offset0:232 offset1:248
	ds_write2_b32 v9, v7, v3 offset0:108 offset1:124
	v_lshlrev_b32_e32 v0, 4, v180
	v_and_b32_e32 v0, 0x70, v0
	s_lshl_b32 s7, s16, 23
	v_or_b32_e32 v0, s11, v0
	s_add_u32 s8, s14, s7
	s_addc_u32 s9, s15, 0
	v_lshlrev_b32_e32 v0, 2, v0
	v_mov_b32_e32 v1, 0
	v_lshrrev_b32_e32 v2, 3, v180
	v_and_b32_e32 v4, 7, v180
	v_lshl_add_u64 v[0:1], s[8:9], 0, v[0:1]
	s_mov_b64 s[8:9], 0x11600000
	v_mul_u32_u24_e32 v3, 0x210, v2
	v_lshlrev_b32_e32 v4, 6, v4
	s_mov_b32 s6, 0
	v_lshl_add_u64 v[0:1], v[0:1], 0, s[8:9]
	v_add3_u32 v3, v3, v4, 32
	s_mov_b32 s7, 0x38e38e39
	s_mov_b32 s8, 0x1ffffee
	s_movk_i32 s9, 0xf800
	s_waitcnt lgkmcnt(0)
	s_barrier

.LBB0_2269:
	s_mul_hi_i32 s8, s49, 0x92492493
	s_add_i32 s8, s8, s49
	s_lshr_b32 s9, s8, 31
	s_ashr_i32 s8, s8, 2
	s_add_i32 s8, s8, s9
	s_mul_i32 s9, s8, -7
	s_add_i32 s28, s9, s49
	s_lshl_b32 s29, s28, 7
	v_add_u32_e32 v0, s29, v106
	v_ashrrev_i32_e32 v1, 31, v0
	v_add_u32_e32 v2, 0x4000, v107
	v_lshlrev_b64 v[0:1], 11, v[0:1]
	v_readfirstlane_b32 s9, v2
	s_lshl_b32 s36, s8, 7
	v_lshl_add_u64 v[0:1], v[66:67], 0, v[0:1]
	s_mov_b32 m0, s9
	v_readfirstlane_b32 s9, v107
	global_load_lds_dwordx4 v[0:1], off
	v_add_u32_e32 v0, s36, v106
	v_ashrrev_i32_e32 v1, 31, v0
	v_lshlrev_b64 v[0:1], 11, v[0:1]
	v_lshl_add_u64 v[2:3], v[72:73], 0, v[0:1]
	s_mov_b32 m0, s9
	v_readfirstlane_b32 s9, v131
	global_load_lds_dwordx4 v[2:3], off
	v_add_u32_e32 v2, s29, v108
	v_ashrrev_i32_e32 v3, 31, v2
	v_lshlrev_b64 v[2:3], 11, v[2:3]
	v_lshl_add_u64 v[2:3], v[68:69], 0, v[2:3]
	s_mov_b32 m0, s9
	v_add_u32_e32 v4, 0x400, v107
	global_load_lds_dwordx4 v[2:3], off
	v_add_u32_e32 v2, s36, v108
	v_ashrrev_i32_e32 v3, 31, v2
	v_lshlrev_b64 v[2:3], 11, v[2:3]
	v_readfirstlane_b32 s9, v4
	v_lshl_add_u64 v[2:3], v[74:75], 0, v[2:3]
	s_mov_b32 m0, s9
	v_readfirstlane_b32 s9, v132
	global_load_lds_dwordx4 v[2:3], off
	v_add_u32_e32 v2, s29, v110
	v_ashrrev_i32_e32 v3, 31, v2
	v_lshlrev_b64 v[2:3], 11, v[2:3]
	v_lshl_add_u64 v[2:3], v[66:67], 0, v[2:3]
	s_mov_b32 m0, s9
	v_add_u32_e32 v4, 0x800, v107
	global_load_lds_dwordx4 v[2:3], off
	v_add_u32_e32 v2, s36, v110
	v_ashrrev_i32_e32 v3, 31, v2
	v_lshlrev_b64 v[2:3], 11, v[2:3]
	v_readfirstlane_b32 s9, v4
	v_lshl_add_u64 v[2:3], v[72:73], 0, v[2:3]
	s_mov_b32 m0, s9
	v_readfirstlane_b32 s9, v133
	global_load_lds_dwordx4 v[2:3], off
	v_add_u32_e32 v2, s29, v112
	v_ashrrev_i32_e32 v3, 31, v2
	v_lshlrev_b64 v[2:3], 11, v[2:3]
	v_lshl_add_u64 v[2:3], v[70:71], 0, v[2:3]
	s_mov_b32 m0, s9
	v_add_u32_e32 v4, 0xc00, v107
	global_load_lds_dwordx4 v[2:3], off
	v_add_u32_e32 v2, s36, v112
	v_ashrrev_i32_e32 v3, 31, v2
	v_lshlrev_b64 v[2:3], 11, v[2:3]
	v_readfirstlane_b32 s9, v4
	v_lshl_add_u64 v[2:3], v[76:77], 0, v[2:3]
	s_mov_b32 m0, s9
	s_mulk_i32 s8, 0x380
	global_load_lds_dwordx4 v[2:3], off
	v_lshl_add_u64 v[92:93], v[80:81], 0, v[0:1]
	v_subrev_u32_e32 v0, s8, v123
	v_ashrrev_i32_e32 v1, 31, v0
	v_lshlrev_b64 v[0:1], 11, v[0:1]
	v_lshl_add_u64 v[94:95], v[82:83], 0, v[0:1]
	v_add_u32_e32 v0, s36, v124
	v_ashrrev_i32_e32 v1, 31, v0
	v_lshlrev_b64 v[0:1], 11, v[0:1]
	v_lshl_add_u64 v[96:97], v[84:85], 0, v[0:1]
	v_subrev_u32_e32 v0, s8, v125
	v_ashrrev_i32_e32 v1, 31, v0
	v_lshlrev_b64 v[0:1], 11, v[0:1]
	v_lshl_add_u64 v[98:99], v[78:79], 0, v[0:1]
	v_add_u32_e32 v0, s36, v126
	v_ashrrev_i32_e32 v1, 31, v0
	v_lshlrev_b64 v[0:1], 11, v[0:1]
	v_lshl_add_u64 v[100:101], v[80:81], 0, v[0:1]
	v_subrev_u32_e32 v0, s8, v127
	v_ashrrev_i32_e32 v1, 31, v0
	v_lshlrev_b64 v[0:1], 11, v[0:1]
	v_subrev_u32_e32 v2, s8, v122
	v_lshl_add_u64 v[102:103], v[86:87], 0, v[0:1]
	v_add_u32_e32 v0, s36, v128
	v_ashrrev_i32_e32 v3, 31, v2
	v_ashrrev_i32_e32 v1, 31, v0
	v_lshlrev_b64 v[2:3], 11, v[2:3]
	v_lshlrev_b64 v[0:1], 11, v[0:1]
	v_lshl_add_u64 v[90:91], v[78:79], 0, v[2:3]
	v_lshl_add_u64 v[104:105], v[88:89], 0, v[0:1]
	s_mov_b64 s[8:9], 0
	s_mov_b32 s30, 0
	v_mov_b32_e32 v0, v65
	v_mov_b32_e32 v1, v65
	v_mov_b32_e32 v2, v65
	v_mov_b32_e32 v3, v65
	v_mov_b32_e32 v4, v65
	v_mov_b32_e32 v5, v65
	v_mov_b32_e32 v6, v65
	v_mov_b32_e32 v7, v65
	v_mov_b32_e32 v8, v65
	v_mov_b32_e32 v9, v65
	v_mov_b32_e32 v10, v65
	v_mov_b32_e32 v11, v65
	v_mov_b32_e32 v12, v65
	v_mov_b32_e32 v13, v65
	v_mov_b32_e32 v14, v65
	v_mov_b32_e32 v15, v65
	v_mov_b32_e32 v16, v65
	v_mov_b32_e32 v17, v65
	v_mov_b32_e32 v18, v65
	v_mov_b32_e32 v19, v65
	v_mov_b32_e32 v20, v65
	v_mov_b32_e32 v21, v65
	v_mov_b32_e32 v22, v65
	v_mov_b32_e32 v23, v65
	v_mov_b32_e32 v24, v65
	v_mov_b32_e32 v25, v65
	v_mov_b32_e32 v26, v65
	v_mov_b32_e32 v27, v65
	v_mov_b32_e32 v28, v65
	v_mov_b32_e32 v29, v65
	v_mov_b32_e32 v30, v65
	v_mov_b32_e32 v31, v65
	s_waitcnt vmcnt(0)
	v_mov_b32_e32 v32, v65
	v_mov_b32_e32 v33, v65
	v_mov_b32_e32 v34, v65
	v_mov_b32_e32 v35, v65
	v_mov_b32_e32 v36, v65
	v_mov_b32_e32 v37, v65
	v_mov_b32_e32 v38, v65
	v_mov_b32_e32 v39, v65
	v_mov_b32_e32 v40, v65
	v_mov_b32_e32 v41, v65
	v_mov_b32_e32 v42, v65
	v_mov_b32_e32 v43, v65
	v_mov_b32_e32 v44, v65
	v_mov_b32_e32 v45, v65
	v_mov_b32_e32 v46, v65
	v_mov_b32_e32 v47, v65
	v_mov_b32_e32 v48, v65
	v_mov_b32_e32 v49, v65
	v_mov_b32_e32 v50, v65
	v_mov_b32_e32 v51, v65
	v_mov_b32_e32 v52, v65
	v_mov_b32_e32 v53, v65
	v_mov_b32_e32 v54, v65
	v_mov_b32_e32 v55, v65
	v_mov_b32_e32 v56, v65
	v_mov_b32_e32 v57, v65
	v_mov_b32_e32 v58, v65
	v_mov_b32_e32 v59, v65
	v_mov_b32_e32 v60, v65
	v_mov_b32_e32 v61, v65
	v_mov_b32_e32 v62, v65
	v_mov_b32_e32 v63, v65
	s_waitcnt lgkmcnt(0)
	s_barrier
	v_add3_u32 v182, 0, v134, v135
	v_add_u32_e32 v183, 0x4000, v182
	s_nop 0
	v_readfirstlane_b32 s82, v183
	v_lshl_add_u32 v183, v109, 1, 0
	s_nop 0
	v_readfirstlane_b32 s83, v182
	v_add3_u32 v183, v183, v135, s43
	s_nop 0
	v_readfirstlane_b32 s84, v183
	v_add_u32_e32 v183, 0x400, v182
	s_nop 0
	v_readfirstlane_b32 s85, v183
	v_lshl_add_u32 v183, v111, 1, 0
	v_add3_u32 v183, v183, v135, s43
	s_nop 0
	v_readfirstlane_b32 s86, v183
	v_add_u32_e32 v183, 0x800, v182
	s_nop 0
	v_readfirstlane_b32 s87, v183
	v_lshl_add_u32 v183, v113, 1, 0
	v_add3_u32 v183, v183, v135, s43
	s_nop 0
	v_readfirstlane_b32 s88, v183
	v_add_u32_e32 v182, 0xc00, v182
	s_nop 0
	v_readfirstlane_b32 s89, v182
	v_subrev_u32_e32 v184, s52, v90
	v_subrev_u32_e32 v185, s52, v92
	v_subrev_u32_e32 v186, s52, v94
	v_subrev_u32_e32 v187, s52, v96
	v_subrev_u32_e32 v188, s52, v98
	v_subrev_u32_e32 v189, s52, v100
	v_subrev_u32_e32 v190, s52, v102
	v_subrev_u32_e32 v191, s52, v104
	s_bitcmp1_b32 s32, 0
	s_cbranch_scc1 .Lxk_2270
.LBB0_2270:
	s_and_b32 s31, s30, 0x4000
	s_xor_b32 s34, s31, 0x4000
	s_lshl_b32 s34, s34, 1
	s_add_i32 s34, s34, 32
	s_add_u32 s90, s52, s8
	s_addc_u32 s91, s53, s9
	s_add_i32 m0, s34, s82
	s_lshl_b32 s31, s31, 1
	global_load_lds_dwordx4 v184, s[90:91]
	s_add_i32 m0, s34, s83
	s_add_i32 s31, s31, 32
	global_load_lds_dwordx4 v185, s[90:91]
	s_add_i32 m0, s34, s84
	v_lshl_add_u32 v64, v114, 1, s31
	global_load_lds_dwordx4 v186, s[90:91]
	s_add_i32 m0, s34, s85
	v_lshl_add_u32 v139, v115, 1, s31
	global_load_lds_dwordx4 v187, s[90:91]
	s_add_i32 m0, s34, s86
	v_add_u32_e32 v160, v64, v136
	global_load_lds_dwordx4 v188, s[90:91]
	s_add_i32 m0, s34, s87
	v_add_u32_e32 v168, v139, v136
	global_load_lds_dwordx4 v189, s[90:91]
	s_add_i32 m0, s34, s88
	s_addk_i32 s30, 0x4000
	global_load_lds_dwordx4 v190, s[90:91]
	s_add_i32 m0, s34, s89
	s_add_u32 s8, s8, 0x80
	s_addc_u32 s9, s9, 0
	global_load_lds_dwordx4 v191, s[90:91]
	ds_read_b128 v[140:143], v160
	ds_read_b128 v[148:151], v168 offset:16384
	ds_read_b128 v[152:155], v168 offset:18432
	ds_read_b128 v[164:167], v168 offset:20480
	ds_read_b128 v[168:171], v168 offset:22528
	ds_read_b128 v[144:147], v160 offset:2048
	ds_read_b128 v[156:159], v160 offset:4096
	ds_read_b128 v[160:163], v160 offset:6144
	v_add_u32_e32 v64, v64, v137
	v_add_u32_e32 v139, v139, v137
	ds_read_b128 v[204:207], v64
	ds_read_b128 v[208:211], v139 offset:16384
	ds_read_b128 v[212:215], v139 offset:18432
	ds_read_b128 v[216:219], v139 offset:20480
	ds_read_b128 v[220:223], v139 offset:22528
	ds_read_b128 v[224:227], v64 offset:2048
	ds_read_b128 v[228:231], v64 offset:4096
	ds_read_b128 v[232:235], v64 offset:6144
	s_setprio 1
	s_waitcnt lgkmcnt(11)
	v_mfma_f32_16x16x32_bf16 v[60:63], v[140:143], v[148:151], v[60:63]
	v_mfma_f32_16x16x32_bf16 v[56:59], v[140:143], v[152:155], v[56:59]
	v_mfma_f32_16x16x32_bf16 v[52:55], v[140:143], v[164:167], v[52:55]
	v_mfma_f32_16x16x32_bf16 v[48:51], v[140:143], v[168:171], v[48:51]
	s_waitcnt lgkmcnt(10)
	v_mfma_f32_16x16x32_bf16 v[44:47], v[144:147], v[148:151], v[44:47]
	v_mfma_f32_16x16x32_bf16 v[40:43], v[144:147], v[152:155], v[40:43]
	v_mfma_f32_16x16x32_bf16 v[36:39], v[144:147], v[164:167], v[36:39]
	v_mfma_f32_16x16x32_bf16 v[32:35], v[144:147], v[168:171], v[32:35]
	s_waitcnt lgkmcnt(9)
	v_mfma_f32_16x16x32_bf16 v[28:31], v[156:159], v[148:151], v[28:31]
	v_mfma_f32_16x16x32_bf16 v[24:27], v[156:159], v[152:155], v[24:27]
	v_mfma_f32_16x16x32_bf16 v[20:23], v[156:159], v[164:167], v[20:23]
	v_mfma_f32_16x16x32_bf16 v[16:19], v[156:159], v[168:171], v[16:19]
	s_waitcnt lgkmcnt(8)
	v_mfma_f32_16x16x32_bf16 v[12:15], v[160:163], v[148:151], v[12:15]
	v_mfma_f32_16x16x32_bf16 v[8:11], v[160:163], v[152:155], v[8:11]
	v_mfma_f32_16x16x32_bf16 v[4:7], v[160:163], v[164:167], v[4:7]
	v_mfma_f32_16x16x32_bf16 v[0:3], v[160:163], v[168:171], v[0:3]
	s_waitcnt lgkmcnt(3)
	v_mfma_f32_16x16x32_bf16 v[60:63], v[204:207], v[208:211], v[60:63]
	v_mfma_f32_16x16x32_bf16 v[56:59], v[204:207], v[212:215], v[56:59]
	v_mfma_f32_16x16x32_bf16 v[52:55], v[204:207], v[216:219], v[52:55]
	v_mfma_f32_16x16x32_bf16 v[48:51], v[204:207], v[220:223], v[48:51]
	s_waitcnt lgkmcnt(2)
	v_mfma_f32_16x16x32_bf16 v[44:47], v[224:227], v[208:211], v[44:47]
	v_mfma_f32_16x16x32_bf16 v[40:43], v[224:227], v[212:215], v[40:43]
	v_mfma_f32_16x16x32_bf16 v[36:39], v[224:227], v[216:219], v[36:39]
	v_mfma_f32_16x16x32_bf16 v[32:35], v[224:227], v[220:223], v[32:35]
	s_waitcnt lgkmcnt(1)
	v_mfma_f32_16x16x32_bf16 v[28:31], v[228:231], v[208:211], v[28:31]
	v_mfma_f32_16x16x32_bf16 v[24:27], v[228:231], v[212:215], v[24:27]
	v_mfma_f32_16x16x32_bf16 v[20:23], v[228:231], v[216:219], v[20:23]
	v_mfma_f32_16x16x32_bf16 v[16:19], v[228:231], v[220:223], v[16:19]
	s_waitcnt lgkmcnt(0)
	v_mfma_f32_16x16x32_bf16 v[12:15], v[232:235], v[208:211], v[12:15]
	v_mfma_f32_16x16x32_bf16 v[8:11], v[232:235], v[212:215], v[8:11]
	v_mfma_f32_16x16x32_bf16 v[4:7], v[232:235], v[216:219], v[4:7]
	v_mfma_f32_16x16x32_bf16 v[0:3], v[232:235], v[220:223], v[0:3]
	s_setprio 0
	s_cmpk_eq_i32 s8, 0x780
	s_waitcnt vmcnt(0)
	s_barrier
	s_cbranch_scc0 .LBB0_2270
	s_branch .Lxk_exit_2270
.Lxk_2270:
	s_and_b32 s31, s30, 0x4000
	s_xor_b32 s34, s31, 0x4000
	s_lshl_b32 s34, s34, 1
	s_add_i32 s34, s34, 32
	s_add_u32 s90, s52, s8
	s_addc_u32 s91, s53, s9
	s_add_i32 m0, s34, s82
	s_lshl_b32 s31, s31, 1
	global_load_lds_dwordx4 v184, s[90:91]
	s_add_i32 m0, s34, s83
	s_add_i32 s31, s31, 32
	global_load_lds_dwordx4 v185, s[90:91]
	s_add_i32 m0, s34, s84
	v_lshl_add_u32 v64, v114, 1, s31
	global_load_lds_dwordx4 v186, s[90:91]
	s_add_i32 m0, s34, s85
	v_lshl_add_u32 v139, v115, 1, s31
	global_load_lds_dwordx4 v187, s[90:91]
	s_add_i32 m0, s34, s86
	v_add_u32_e32 v160, v64, v136
	global_load_lds_dwordx4 v188, s[90:91]
	s_add_i32 m0, s34, s87
	v_add_u32_e32 v168, v139, v136
	global_load_lds_dwordx4 v189, s[90:91]
	s_add_i32 m0, s34, s88
	s_addk_i32 s30, 0x4000
	global_load_lds_dwordx4 v190, s[90:91]
	s_add_i32 m0, s34, s89
	s_add_u32 s8, s8, 0x80
	s_addc_u32 s9, s9, 0
	global_load_lds_dwordx4 v191, s[90:91]
	ds_read_b128 v[140:143], v160
	ds_read_b128 v[148:151], v168 offset:16384
	ds_read_b128 v[152:155], v168 offset:18432
	ds_read_b128 v[164:167], v168 offset:20480
	ds_read_b128 v[168:171], v168 offset:22528
	ds_read_b128 v[144:147], v160 offset:2048
	ds_read_b128 v[156:159], v160 offset:4096
	ds_read_b128 v[160:163], v160 offset:6144
	v_add_u32_e32 v64, v64, v137
	v_add_u32_e32 v139, v139, v137
	ds_read_b128 v[204:207], v64
	ds_read_b128 v[208:211], v139 offset:16384
	ds_read_b128 v[212:215], v139 offset:18432
	ds_read_b128 v[216:219], v139 offset:20480
	ds_read_b128 v[220:223], v139 offset:22528
	ds_read_b128 v[224:227], v64 offset:2048
	ds_read_b128 v[228:231], v64 offset:4096
	ds_read_b128 v[232:235], v64 offset:6144
	s_setprio 3
	s_waitcnt lgkmcnt(11)
	v_mfma_f32_16x16x32_bf16 v[60:63], v[140:143], v[148:151], v[60:63]
	v_mfma_f32_16x16x32_bf16 v[56:59], v[140:143], v[152:155], v[56:59]
	v_mfma_f32_16x16x32_bf16 v[52:55], v[140:143], v[164:167], v[52:55]
	v_mfma_f32_16x16x32_bf16 v[48:51], v[140:143], v[168:171], v[48:51]
	s_waitcnt lgkmcnt(10)
	v_mfma_f32_16x16x32_bf16 v[44:47], v[144:147], v[148:151], v[44:47]
	v_mfma_f32_16x16x32_bf16 v[40:43], v[144:147], v[152:155], v[40:43]
	v_mfma_f32_16x16x32_bf16 v[36:39], v[144:147], v[164:167], v[36:39]
	v_mfma_f32_16x16x32_bf16 v[32:35], v[144:147], v[168:171], v[32:35]
	s_waitcnt lgkmcnt(9)
	v_mfma_f32_16x16x32_bf16 v[28:31], v[156:159], v[148:151], v[28:31]
	v_mfma_f32_16x16x32_bf16 v[24:27], v[156:159], v[152:155], v[24:27]
	v_mfma_f32_16x16x32_bf16 v[20:23], v[156:159], v[164:167], v[20:23]
	v_mfma_f32_16x16x32_bf16 v[16:19], v[156:159], v[168:171], v[16:19]
	s_waitcnt lgkmcnt(8)
	v_mfma_f32_16x16x32_bf16 v[12:15], v[160:163], v[148:151], v[12:15]
	v_mfma_f32_16x16x32_bf16 v[8:11], v[160:163], v[152:155], v[8:11]
	v_mfma_f32_16x16x32_bf16 v[4:7], v[160:163], v[164:167], v[4:7]
	v_mfma_f32_16x16x32_bf16 v[0:3], v[160:163], v[168:171], v[0:3]
	s_waitcnt lgkmcnt(3)
	v_mfma_f32_16x16x32_bf16 v[60:63], v[204:207], v[208:211], v[60:63]
	v_mfma_f32_16x16x32_bf16 v[56:59], v[204:207], v[212:215], v[56:59]
	v_mfma_f32_16x16x32_bf16 v[52:55], v[204:207], v[216:219], v[52:55]
	v_mfma_f32_16x16x32_bf16 v[48:51], v[204:207], v[220:223], v[48:51]
	s_waitcnt lgkmcnt(2)
	v_mfma_f32_16x16x32_bf16 v[44:47], v[224:227], v[208:211], v[44:47]
	v_mfma_f32_16x16x32_bf16 v[40:43], v[224:227], v[212:215], v[40:43]
	v_mfma_f32_16x16x32_bf16 v[36:39], v[224:227], v[216:219], v[36:39]
	v_mfma_f32_16x16x32_bf16 v[32:35], v[224:227], v[220:223], v[32:35]
	s_waitcnt lgkmcnt(1)
	v_mfma_f32_16x16x32_bf16 v[28:31], v[228:231], v[208:211], v[28:31]
	v_mfma_f32_16x16x32_bf16 v[24:27], v[228:231], v[212:215], v[24:27]
	v_mfma_f32_16x16x32_bf16 v[20:23], v[228:231], v[216:219], v[20:23]
	v_mfma_f32_16x16x32_bf16 v[16:19], v[228:231], v[220:223], v[16:19]
	s_waitcnt lgkmcnt(0)
	v_mfma_f32_16x16x32_bf16 v[12:15], v[232:235], v[208:211], v[12:15]
	v_mfma_f32_16x16x32_bf16 v[8:11], v[232:235], v[212:215], v[8:11]
	v_mfma_f32_16x16x32_bf16 v[4:7], v[232:235], v[216:219], v[4:7]
	v_mfma_f32_16x16x32_bf16 v[0:3], v[232:235], v[220:223], v[0:3]
	s_setprio 2
	s_cmpk_eq_i32 s8, 0x780
	s_waitcnt vmcnt(0)
	s_barrier
	s_cbranch_scc0 .Lxk_2270
.Lxk_exit_2270:
	ds_read_b128 v[90:93], v116 offset:55296
	ds_read_b128 v[94:97], v116 offset:53248
	ds_read_b128 v[98:101], v117 offset:38912
	ds_read_b128 v[102:105], v117 offset:36864
	ds_read_b128 v[140:143], v116 offset:51200
	ds_read_b128 v[144:147], v116 offset:49152
	ds_read_b128 v[148:151], v117 offset:34816
	ds_read_b128 v[152:155], v117 offset:32768
	s_setprio 1
	s_waitcnt lgkmcnt(4)
	v_mfma_f32_16x16x32_bf16 v[20:23], v[102:105], v[94:97], v[20:23]
	v_mfma_f32_16x16x32_bf16 v[16:19], v[102:105], v[90:93], v[16:19]
	s_waitcnt lgkmcnt(0)
	v_mfma_f32_16x16x32_bf16 v[60:63], v[152:155], v[144:147], v[60:63]
	v_mfma_f32_16x16x32_bf16 v[56:59], v[152:155], v[140:143], v[56:59]
	v_mfma_f32_16x16x32_bf16 v[52:55], v[152:155], v[94:97], v[52:55]
	v_mfma_f32_16x16x32_bf16 v[48:51], v[152:155], v[90:93], v[48:51]
	v_mfma_f32_16x16x32_bf16 v[44:47], v[148:151], v[144:147], v[44:47]
	v_mfma_f32_16x16x32_bf16 v[40:43], v[148:151], v[140:143], v[40:43]
	v_mfma_f32_16x16x32_bf16 v[36:39], v[148:151], v[94:97], v[36:39]
	v_mfma_f32_16x16x32_bf16 v[32:35], v[148:151], v[90:93], v[32:35]
	v_mfma_f32_16x16x32_bf16 v[28:31], v[102:105], v[144:147], v[28:31]
	v_mfma_f32_16x16x32_bf16 v[24:27], v[102:105], v[140:143], v[24:27]
	v_mfma_f32_16x16x32_bf16 v[12:15], v[98:101], v[144:147], v[12:15]
	v_mfma_f32_16x16x32_bf16 v[8:11], v[98:101], v[140:143], v[8:11]
	v_mfma_f32_16x16x32_bf16 v[4:7], v[98:101], v[94:97], v[4:7]
	v_mfma_f32_16x16x32_bf16 v[0:3], v[98:101], v[90:93], v[0:3]
	s_setprio 0
	ds_read_b128 v[90:93], v118 offset:32768
	ds_read_b128 v[94:97], v118 offset:34816
	ds_read_b128 v[98:101], v119 offset:49152
	ds_read_b128 v[102:105], v119 offset:51200
	ds_read_b128 v[140:143], v118 offset:36864
	ds_read_b128 v[144:147], v118 offset:38912
	ds_read_b128 v[148:151], v119 offset:53248
	ds_read_b128 v[152:155], v119 offset:55296
	s_setprio 1
	s_waitcnt lgkmcnt(1)
	v_mfma_f32_16x16x32_bf16 v[20:23], v[140:143], v[148:151], v[20:23]
	s_waitcnt lgkmcnt(0)
	v_mfma_f32_16x16x32_bf16 v[16:19], v[140:143], v[152:155], v[16:19]
	v_mfma_f32_16x16x32_bf16 v[60:63], v[90:93], v[98:101], v[60:63]
	v_mfma_f32_16x16x32_bf16 v[56:59], v[90:93], v[102:105], v[56:59]
	v_mfma_f32_16x16x32_bf16 v[52:55], v[90:93], v[148:151], v[52:55]
	v_mfma_f32_16x16x32_bf16 v[48:51], v[90:93], v[152:155], v[48:51]
	v_mfma_f32_16x16x32_bf16 v[44:47], v[94:97], v[98:101], v[44:47]
	v_mfma_f32_16x16x32_bf16 v[40:43], v[94:97], v[102:105], v[40:43]
	v_mfma_f32_16x16x32_bf16 v[36:39], v[94:97], v[148:151], v[36:39]
	v_mfma_f32_16x16x32_bf16 v[32:35], v[94:97], v[152:155], v[32:35]
	v_mfma_f32_16x16x32_bf16 v[28:31], v[140:143], v[98:101], v[28:31]
	v_mfma_f32_16x16x32_bf16 v[24:27], v[140:143], v[102:105], v[24:27]
	v_mfma_f32_16x16x32_bf16 v[12:15], v[144:147], v[98:101], v[12:15]
	v_mfma_f32_16x16x32_bf16 v[8:11], v[144:147], v[102:105], v[8:11]
	v_mfma_f32_16x16x32_bf16 v[4:7], v[144:147], v[148:151], v[4:7]
	v_mfma_f32_16x16x32_bf16 v[0:3], v[144:147], v[152:155], v[0:3]
	s_setprio 0
	s_barrier
	ds_write2_b32 v120, v60, v56 offset1:16
	ds_write2_b32 v120, v61, v57 offset0:132 offset1:148
	v_add_u32_e32 v56, 0x400, v120
	ds_write2_b32 v56, v62, v58 offset0:8 offset1:24
	ds_write2_b32 v56, v63, v59 offset0:140 offset1:156
	ds_write2_b32 v120, v52, v48 offset0:32 offset1:48
	ds_write2_b32 v120, v53, v49 offset0:164 offset1:180
	ds_write2_b32 v56, v54, v50 offset0:40 offset1:56
	ds_write2_b32 v56, v55, v51 offset0:172 offset1:188
	v_add_u32_e32 v48, 0x2000, v120
	ds_write2_b32 v48, v44, v40 offset0:64 offset1:80
	ds_write2_b32 v48, v45, v41 offset0:196 offset1:212
	v_add_u32_e32 v40, 0x2400, v120
	ds_write2_b32 v40, v46, v42 offset0:72 offset1:88
	ds_write2_b32 v40, v47, v43 offset0:204 offset1:220
	ds_write2_b32 v48, v36, v32 offset0:96 offset1:112
	ds_write2_b32 v48, v37, v33 offset0:228 offset1:244
	ds_write2_b32 v40, v38, v34 offset0:104 offset1:120
	ds_write2_b32 v40, v39, v35 offset0:236 offset1:252
	v_add_u32_e32 v32, 0x4000, v120
	ds_write2_b32 v32, v28, v24 offset0:128 offset1:144
	v_add_u32_e32 v24, 0x4400, v120
	ds_write2_b32 v24, v29, v25 offset0:4 offset1:20
	ds_write2_b32 v24, v30, v26 offset0:136 offset1:152
	v_add_u32_e32 v25, 0x4800, v120
	s_cmp_gt_i32 s28, 5
	ds_write2_b32 v25, v31, v27 offset0:12 offset1:28
	ds_write2_b32 v32, v20, v16 offset0:160 offset1:176
	ds_write2_b32 v24, v21, v17 offset0:36 offset1:52
	ds_write2_b32 v24, v22, v18 offset0:168 offset1:184
	ds_write2_b32 v25, v23, v19 offset0:44 offset1:60
	v_add_u32_e32 v16, 0x6000, v120
	v_or_b32_e32 v64, s29, v121
	s_cselect_b64 s[30:31], -1, 0
	s_ashr_i32 s29, s28, 31
	ds_write2_b32 v16, v12, v8 offset0:192 offset1:208
	v_add_u32_e32 v8, 0x6400, v120
	s_cmp_gt_i32 s28, 3
	ds_write2_b32 v8, v13, v9 offset0:68 offset1:84
	ds_write2_b32 v8, v14, v10 offset0:200 offset1:216
	v_add_u32_e32 v9, 0x6800, v120
	s_cselect_b64 s[34:35], -1, 0
	s_lshl_b64 s[28:29], s[28:29], 2
	ds_write2_b32 v9, v15, v11 offset0:76 offset1:92
	ds_write2_b32 v16, v4, v0 offset0:224 offset1:240
	ds_write2_b32 v8, v5, v1 offset0:100 offset1:116
	ds_write2_b32 v8, v6, v2 offset0:232 offset1:248
	ds_write2_b32 v9, v7, v3 offset0:108 offset1:124
	v_ashrrev_i32_e32 v1, 31, v64
	v_mov_b32_e32 v0, v64
	v_lshlrev_b64 v[2:3], 1, v[64:65]
	s_add_u32 s28, s40, s28
	v_cmp_gt_u32_e64 s[8:9], s44, v64
	v_lshl_add_u64 v[16:17], s[16:17], 0, v[2:3]
	s_addc_u32 s29, s41, s29
	v_lshl_add_u64 v[18:19], s[14:15], 0, v[2:3]
	v_lshl_add_u64 v[20:21], v[0:1], 1, s[12:13]
	v_add_u32_e32 v22, s36, v129
	s_mov_b32 s50, 0
	s_waitcnt lgkmcnt(0)
	s_barrier
	s_branch .LBB0_2273

.LBB0_2291:
	s_mul_hi_i32 s8, s34, 0x92492493
	s_add_i32 s8, s8, s34
	s_lshr_b32 s9, s8, 31
	s_ashr_i32 s8, s8, 2
	s_add_i32 s8, s8, s9
	s_mul_i32 s9, s8, 0x1fffff9
	s_add_i32 s9, s9, s34
	v_add_u32_e32 v0, s8, v106
	s_lshl_b32 s22, s9, 7
	v_lshlrev_b32_e32 v2, 7, v0
	v_add_u32_e32 v0, s22, v107
	v_ashrrev_i32_e32 v1, 31, v0
	v_add_u32_e32 v3, 0x4000, v108
	v_lshlrev_b64 v[0:1], 11, v[0:1]
	v_readfirstlane_b32 s9, v3
	v_lshl_add_u64 v[0:1], v[66:67], 0, v[0:1]
	s_mov_b32 m0, s9
	v_readfirstlane_b32 s9, v108
	global_load_lds_dwordx4 v[0:1], off
	v_add_u32_e32 v0, v2, v107
	v_ashrrev_i32_e32 v1, 31, v0
	v_lshlrev_b64 v[0:1], 11, v[0:1]
	v_lshl_add_u64 v[0:1], v[72:73], 0, v[0:1]
	s_mov_b32 m0, s9
	v_readfirstlane_b32 s9, v133
	global_load_lds_dwordx4 v[0:1], off
	v_add_u32_e32 v0, s22, v109
	v_ashrrev_i32_e32 v1, 31, v0
	v_lshlrev_b64 v[0:1], 11, v[0:1]
	v_lshl_add_u64 v[0:1], v[68:69], 0, v[0:1]
	s_mov_b32 m0, s9
	v_add_u32_e32 v3, 0x400, v108
	global_load_lds_dwordx4 v[0:1], off
	v_add_u32_e32 v0, v2, v109
	v_ashrrev_i32_e32 v1, 31, v0
	v_lshlrev_b64 v[0:1], 11, v[0:1]
	v_readfirstlane_b32 s9, v3
	v_lshl_add_u64 v[0:1], v[74:75], 0, v[0:1]
	s_mov_b32 m0, s9
	v_readfirstlane_b32 s9, v134
	global_load_lds_dwordx4 v[0:1], off
	v_add_u32_e32 v0, s22, v111
	v_ashrrev_i32_e32 v1, 31, v0
	v_lshlrev_b64 v[0:1], 11, v[0:1]
	v_lshl_add_u64 v[0:1], v[66:67], 0, v[0:1]
	s_mov_b32 m0, s9
	v_add_u32_e32 v3, 0x800, v108
	global_load_lds_dwordx4 v[0:1], off
	v_add_u32_e32 v0, v2, v111
	v_ashrrev_i32_e32 v1, 31, v0
	v_lshlrev_b64 v[0:1], 11, v[0:1]
	v_readfirstlane_b32 s9, v3
	v_lshl_add_u64 v[0:1], v[72:73], 0, v[0:1]
	s_mov_b32 m0, s9
	v_readfirstlane_b32 s9, v135
	global_load_lds_dwordx4 v[0:1], off
	v_add_u32_e32 v0, s22, v113
	v_ashrrev_i32_e32 v1, 31, v0
	v_lshlrev_b64 v[0:1], 11, v[0:1]
	v_lshl_add_u64 v[0:1], v[70:71], 0, v[0:1]
	s_mov_b32 m0, s9
	s_lshl_b32 s28, s8, 7
	global_load_lds_dwordx4 v[0:1], off
	v_add_u32_e32 v0, v2, v113
	v_ashrrev_i32_e32 v1, 31, v0
	v_add_u32_e32 v2, 0xc00, v108
	v_lshlrev_b64 v[0:1], 11, v[0:1]
	v_readfirstlane_b32 s9, v2
	v_lshl_add_u64 v[0:1], v[76:77], 0, v[0:1]
	s_mov_b32 m0, s9
	s_mul_i32 s9, s8, 0x380
	global_load_lds_dwordx4 v[0:1], off
	v_subrev_u32_e32 v0, s9, v123
	v_ashrrev_i32_e32 v1, 31, v0
	v_lshlrev_b64 v[0:1], 11, v[0:1]
	v_lshl_add_u64 v[90:91], v[78:79], 0, v[0:1]
	v_add_u32_e32 v0, s28, v124
	v_ashrrev_i32_e32 v1, 31, v0
	v_lshlrev_b64 v[0:1], 11, v[0:1]
	v_lshl_add_u64 v[92:93], v[80:81], 0, v[0:1]
	v_subrev_u32_e32 v0, s9, v125
	v_ashrrev_i32_e32 v1, 31, v0
	v_lshlrev_b64 v[0:1], 11, v[0:1]
	v_lshl_add_u64 v[94:95], v[82:83], 0, v[0:1]
	v_add_u32_e32 v0, s28, v126
	v_ashrrev_i32_e32 v1, 31, v0
	v_lshlrev_b64 v[0:1], 11, v[0:1]
	v_lshl_add_u64 v[96:97], v[84:85], 0, v[0:1]
	v_subrev_u32_e32 v0, s9, v127
	v_ashrrev_i32_e32 v1, 31, v0
	v_lshlrev_b64 v[0:1], 11, v[0:1]
	v_lshl_add_u64 v[98:99], v[78:79], 0, v[0:1]
	v_add_u32_e32 v0, s28, v128
	v_ashrrev_i32_e32 v1, 31, v0
	v_lshlrev_b64 v[0:1], 11, v[0:1]
	v_lshl_add_u64 v[100:101], v[80:81], 0, v[0:1]
	v_subrev_u32_e32 v0, s9, v129
	v_ashrrev_i32_e32 v1, 31, v0
	v_lshlrev_b64 v[0:1], 11, v[0:1]
	v_lshl_add_u64 v[102:103], v[86:87], 0, v[0:1]
	v_add_u32_e32 v0, s28, v130
	v_ashrrev_i32_e32 v1, 31, v0
	v_lshlrev_b64 v[0:1], 11, v[0:1]
	v_lshl_add_u64 v[104:105], v[88:89], 0, v[0:1]
	v_mov_b32_e32 v0, 0
	s_mov_b64 s[8:9], 0
	s_mov_b32 s23, 0
	v_mov_b32_e32 v1, v0
	v_mov_b32_e32 v2, v0
	v_mov_b32_e32 v3, v0
	v_mov_b32_e32 v4, v0
	v_mov_b32_e32 v5, v0
	v_mov_b32_e32 v6, v0
	v_mov_b32_e32 v7, v0
	v_mov_b32_e32 v8, v0
	v_mov_b32_e32 v9, v0
	v_mov_b32_e32 v10, v0
	v_mov_b32_e32 v11, v0
	v_mov_b32_e32 v12, v0
	v_mov_b32_e32 v13, v0
	v_mov_b32_e32 v14, v0
	v_mov_b32_e32 v15, v0
	v_mov_b32_e32 v16, v0
	v_mov_b32_e32 v17, v0
	v_mov_b32_e32 v18, v0
	v_mov_b32_e32 v19, v0
	v_mov_b32_e32 v20, v0
	v_mov_b32_e32 v21, v0
	v_mov_b32_e32 v22, v0
	v_mov_b32_e32 v23, v0
	v_mov_b32_e32 v24, v0
	v_mov_b32_e32 v25, v0
	v_mov_b32_e32 v26, v0
	v_mov_b32_e32 v27, v0
	v_mov_b32_e32 v28, v0
	v_mov_b32_e32 v29, v0
	v_mov_b32_e32 v30, v0
	v_mov_b32_e32 v31, v0
	s_waitcnt vmcnt(0)
	v_mov_b32_e32 v32, v0
	v_mov_b32_e32 v33, v0
	v_mov_b32_e32 v34, v0
	v_mov_b32_e32 v35, v0
	v_mov_b32_e32 v36, v0
	v_mov_b32_e32 v37, v0
	v_mov_b32_e32 v38, v0
	v_mov_b32_e32 v39, v0
	v_mov_b32_e32 v40, v0
	v_mov_b32_e32 v41, v0
	v_mov_b32_e32 v42, v0
	v_mov_b32_e32 v43, v0
	v_mov_b32_e32 v44, v0
	v_mov_b32_e32 v45, v0
	v_mov_b32_e32 v46, v0
	v_mov_b32_e32 v47, v0
	v_mov_b32_e32 v48, v0
	v_mov_b32_e32 v49, v0
	v_mov_b32_e32 v50, v0
	v_mov_b32_e32 v51, v0
	v_mov_b32_e32 v52, v0
	v_mov_b32_e32 v53, v0
	v_mov_b32_e32 v54, v0
	v_mov_b32_e32 v55, v0
	v_mov_b32_e32 v56, v0
	v_mov_b32_e32 v57, v0
	v_mov_b32_e32 v58, v0
	v_mov_b32_e32 v59, v0
	v_mov_b32_e32 v60, v0
	v_mov_b32_e32 v61, v0
	v_mov_b32_e32 v62, v0
	v_mov_b32_e32 v63, v0
	s_waitcnt lgkmcnt(0)
	s_barrier
	v_add3_u32 v182, 0, v136, v137
	v_add_u32_e32 v183, 0x4000, v182
	s_nop 0
	v_readfirstlane_b32 s82, v183
	v_lshl_add_u32 v183, v110, 1, 0
	s_nop 0
	v_readfirstlane_b32 s83, v182
	v_add3_u32 v183, v183, v137, s37
	s_nop 0
	v_readfirstlane_b32 s84, v183
	v_add_u32_e32 v183, 0x400, v182
	s_nop 0
	v_readfirstlane_b32 s85, v183
	v_lshl_add_u32 v183, v112, 1, 0
	v_add3_u32 v183, v183, v137, s37
	s_nop 0
	v_readfirstlane_b32 s86, v183
	v_add_u32_e32 v183, 0x800, v182
	s_nop 0
	v_readfirstlane_b32 s87, v183
	v_lshl_add_u32 v183, v114, 1, 0
	v_add3_u32 v183, v183, v137, s37
	s_nop 0
	v_readfirstlane_b32 s88, v183
	v_add_u32_e32 v182, 0xc00, v182
	s_nop 0
	v_readfirstlane_b32 s89, v182
	v_subrev_u32_e32 v184, s52, v90
	v_subrev_u32_e32 v185, s52, v92
	v_subrev_u32_e32 v186, s52, v94
	v_subrev_u32_e32 v187, s52, v96
	v_subrev_u32_e32 v188, s52, v98
	v_subrev_u32_e32 v189, s52, v100
	v_subrev_u32_e32 v190, s52, v102
	v_subrev_u32_e32 v191, s52, v104
	s_bitcmp1_b32 s32, 0
	s_cbranch_scc1 .Lxk_2292
.LBB0_2292:
	s_and_b32 s24, s23, 0x4000
	s_xor_b32 s25, s24, 0x4000
	s_lshl_b32 s25, s25, 1
	s_add_i32 s25, s25, 32
	s_add_u32 s90, s52, s8
	s_addc_u32 s91, s53, s9
	s_add_i32 m0, s25, s82
	s_lshl_b32 s24, s24, 1
	global_load_lds_dwordx4 v184, s[90:91]
	s_add_i32 m0, s25, s83
	s_add_i32 s24, s24, 32
	global_load_lds_dwordx4 v185, s[90:91]
	s_add_i32 m0, s25, s84
	v_lshl_add_u32 v64, v115, 1, s24
	global_load_lds_dwordx4 v186, s[90:91]
	s_add_i32 m0, s25, s85
	v_lshl_add_u32 v141, v116, 1, s24
	global_load_lds_dwordx4 v187, s[90:91]
	s_add_i32 m0, s25, s86
	v_add_u32_e32 v162, v64, v138
	global_load_lds_dwordx4 v188, s[90:91]
	s_add_i32 m0, s25, s87
	v_add_u32_e32 v170, v141, v138
	global_load_lds_dwordx4 v189, s[90:91]
	s_add_i32 m0, s25, s88
	s_addk_i32 s23, 0x4000
	global_load_lds_dwordx4 v190, s[90:91]
	s_add_i32 m0, s25, s89
	s_add_u32 s8, s8, 0x80
	s_addc_u32 s9, s9, 0
	global_load_lds_dwordx4 v191, s[90:91]
	ds_read_b128 v[142:145], v162
	ds_read_b128 v[150:153], v170 offset:16384
	ds_read_b128 v[154:157], v170 offset:18432
	ds_read_b128 v[166:169], v170 offset:20480
	ds_read_b128 v[170:173], v170 offset:22528
	ds_read_b128 v[146:149], v162 offset:2048
	ds_read_b128 v[158:161], v162 offset:4096
	ds_read_b128 v[162:165], v162 offset:6144
	v_add_u32_e32 v64, v64, v139
	v_add_u32_e32 v141, v141, v139
	ds_read_b128 v[204:207], v64
	ds_read_b128 v[208:211], v141 offset:16384
	ds_read_b128 v[212:215], v141 offset:18432
	ds_read_b128 v[216:219], v141 offset:20480
	ds_read_b128 v[220:223], v141 offset:22528
	ds_read_b128 v[224:227], v64 offset:2048
	ds_read_b128 v[228:231], v64 offset:4096
	ds_read_b128 v[232:235], v64 offset:6144
	s_setprio 1
	s_waitcnt lgkmcnt(11)
	v_mfma_f32_16x16x32_bf16 v[60:63], v[142:145], v[150:153], v[60:63]
	v_mfma_f32_16x16x32_bf16 v[56:59], v[142:145], v[154:157], v[56:59]
	v_mfma_f32_16x16x32_bf16 v[52:55], v[142:145], v[166:169], v[52:55]
	v_mfma_f32_16x16x32_bf16 v[48:51], v[142:145], v[170:173], v[48:51]
	s_waitcnt lgkmcnt(10)
	v_mfma_f32_16x16x32_bf16 v[44:47], v[146:149], v[150:153], v[44:47]
	v_mfma_f32_16x16x32_bf16 v[40:43], v[146:149], v[154:157], v[40:43]
	v_mfma_f32_16x16x32_bf16 v[36:39], v[146:149], v[166:169], v[36:39]
	v_mfma_f32_16x16x32_bf16 v[32:35], v[146:149], v[170:173], v[32:35]
	s_waitcnt lgkmcnt(9)
	v_mfma_f32_16x16x32_bf16 v[28:31], v[158:161], v[150:153], v[28:31]
	v_mfma_f32_16x16x32_bf16 v[24:27], v[158:161], v[154:157], v[24:27]
	v_mfma_f32_16x16x32_bf16 v[20:23], v[158:161], v[166:169], v[20:23]
	v_mfma_f32_16x16x32_bf16 v[16:19], v[158:161], v[170:173], v[16:19]
	s_waitcnt lgkmcnt(8)
	v_mfma_f32_16x16x32_bf16 v[12:15], v[162:165], v[150:153], v[12:15]
	v_mfma_f32_16x16x32_bf16 v[8:11], v[162:165], v[154:157], v[8:11]
	v_mfma_f32_16x16x32_bf16 v[4:7], v[162:165], v[166:169], v[4:7]
	v_mfma_f32_16x16x32_bf16 v[0:3], v[162:165], v[170:173], v[0:3]
	s_waitcnt lgkmcnt(3)
	v_mfma_f32_16x16x32_bf16 v[60:63], v[204:207], v[208:211], v[60:63]
	v_mfma_f32_16x16x32_bf16 v[56:59], v[204:207], v[212:215], v[56:59]
	v_mfma_f32_16x16x32_bf16 v[52:55], v[204:207], v[216:219], v[52:55]
	v_mfma_f32_16x16x32_bf16 v[48:51], v[204:207], v[220:223], v[48:51]
	s_waitcnt lgkmcnt(2)
	v_mfma_f32_16x16x32_bf16 v[44:47], v[224:227], v[208:211], v[44:47]
	v_mfma_f32_16x16x32_bf16 v[40:43], v[224:227], v[212:215], v[40:43]
	v_mfma_f32_16x16x32_bf16 v[36:39], v[224:227], v[216:219], v[36:39]
	v_mfma_f32_16x16x32_bf16 v[32:35], v[224:227], v[220:223], v[32:35]
	s_waitcnt lgkmcnt(1)
	v_mfma_f32_16x16x32_bf16 v[28:31], v[228:231], v[208:211], v[28:31]
	v_mfma_f32_16x16x32_bf16 v[24:27], v[228:231], v[212:215], v[24:27]
	v_mfma_f32_16x16x32_bf16 v[20:23], v[228:231], v[216:219], v[20:23]
	v_mfma_f32_16x16x32_bf16 v[16:19], v[228:231], v[220:223], v[16:19]
	s_waitcnt lgkmcnt(0)
	v_mfma_f32_16x16x32_bf16 v[12:15], v[232:235], v[208:211], v[12:15]
	v_mfma_f32_16x16x32_bf16 v[8:11], v[232:235], v[212:215], v[8:11]
	v_mfma_f32_16x16x32_bf16 v[4:7], v[232:235], v[216:219], v[4:7]
	v_mfma_f32_16x16x32_bf16 v[0:3], v[232:235], v[220:223], v[0:3]
	s_setprio 0
	s_cmpk_eq_i32 s8, 0x780
	s_waitcnt vmcnt(0)
	s_barrier
	s_cbranch_scc0 .LBB0_2292
	s_branch .Lxk_exit_2292
.Lxk_2292:
	s_and_b32 s24, s23, 0x4000
	s_xor_b32 s25, s24, 0x4000
	s_lshl_b32 s25, s25, 1
	s_add_i32 s25, s25, 32
	s_add_u32 s90, s52, s8
	s_addc_u32 s91, s53, s9
	s_add_i32 m0, s25, s82
	s_lshl_b32 s24, s24, 1
	global_load_lds_dwordx4 v184, s[90:91]
	s_add_i32 m0, s25, s83
	s_add_i32 s24, s24, 32
	global_load_lds_dwordx4 v185, s[90:91]
	s_add_i32 m0, s25, s84
	v_lshl_add_u32 v64, v115, 1, s24
	global_load_lds_dwordx4 v186, s[90:91]
	s_add_i32 m0, s25, s85
	v_lshl_add_u32 v141, v116, 1, s24
	global_load_lds_dwordx4 v187, s[90:91]
	s_add_i32 m0, s25, s86
	v_add_u32_e32 v162, v64, v138
	global_load_lds_dwordx4 v188, s[90:91]
	s_add_i32 m0, s25, s87
	v_add_u32_e32 v170, v141, v138
	global_load_lds_dwordx4 v189, s[90:91]
	s_add_i32 m0, s25, s88
	s_addk_i32 s23, 0x4000
	global_load_lds_dwordx4 v190, s[90:91]
	s_add_i32 m0, s25, s89
	s_add_u32 s8, s8, 0x80
	s_addc_u32 s9, s9, 0
	global_load_lds_dwordx4 v191, s[90:91]
	ds_read_b128 v[142:145], v162
	ds_read_b128 v[150:153], v170 offset:16384
	ds_read_b128 v[154:157], v170 offset:18432
	ds_read_b128 v[166:169], v170 offset:20480
	ds_read_b128 v[170:173], v170 offset:22528
	ds_read_b128 v[146:149], v162 offset:2048
	ds_read_b128 v[158:161], v162 offset:4096
	ds_read_b128 v[162:165], v162 offset:6144
	v_add_u32_e32 v64, v64, v139
	v_add_u32_e32 v141, v141, v139
	ds_read_b128 v[204:207], v64
	ds_read_b128 v[208:211], v141 offset:16384
	ds_read_b128 v[212:215], v141 offset:18432
	ds_read_b128 v[216:219], v141 offset:20480
	ds_read_b128 v[220:223], v141 offset:22528
	ds_read_b128 v[224:227], v64 offset:2048
	ds_read_b128 v[228:231], v64 offset:4096
	ds_read_b128 v[232:235], v64 offset:6144
	s_setprio 3
	s_waitcnt lgkmcnt(11)
	v_mfma_f32_16x16x32_bf16 v[60:63], v[142:145], v[150:153], v[60:63]
	v_mfma_f32_16x16x32_bf16 v[56:59], v[142:145], v[154:157], v[56:59]
	v_mfma_f32_16x16x32_bf16 v[52:55], v[142:145], v[166:169], v[52:55]
	v_mfma_f32_16x16x32_bf16 v[48:51], v[142:145], v[170:173], v[48:51]
	s_waitcnt lgkmcnt(10)
	v_mfma_f32_16x16x32_bf16 v[44:47], v[146:149], v[150:153], v[44:47]
	v_mfma_f32_16x16x32_bf16 v[40:43], v[146:149], v[154:157], v[40:43]
	v_mfma_f32_16x16x32_bf16 v[36:39], v[146:149], v[166:169], v[36:39]
	v_mfma_f32_16x16x32_bf16 v[32:35], v[146:149], v[170:173], v[32:35]
	s_waitcnt lgkmcnt(9)
	v_mfma_f32_16x16x32_bf16 v[28:31], v[158:161], v[150:153], v[28:31]
	v_mfma_f32_16x16x32_bf16 v[24:27], v[158:161], v[154:157], v[24:27]
	v_mfma_f32_16x16x32_bf16 v[20:23], v[158:161], v[166:169], v[20:23]
	v_mfma_f32_16x16x32_bf16 v[16:19], v[158:161], v[170:173], v[16:19]
	s_waitcnt lgkmcnt(8)
	v_mfma_f32_16x16x32_bf16 v[12:15], v[162:165], v[150:153], v[12:15]
	v_mfma_f32_16x16x32_bf16 v[8:11], v[162:165], v[154:157], v[8:11]
	v_mfma_f32_16x16x32_bf16 v[4:7], v[162:165], v[166:169], v[4:7]
	v_mfma_f32_16x16x32_bf16 v[0:3], v[162:165], v[170:173], v[0:3]
	s_waitcnt lgkmcnt(3)
	v_mfma_f32_16x16x32_bf16 v[60:63], v[204:207], v[208:211], v[60:63]
	v_mfma_f32_16x16x32_bf16 v[56:59], v[204:207], v[212:215], v[56:59]
	v_mfma_f32_16x16x32_bf16 v[52:55], v[204:207], v[216:219], v[52:55]
	v_mfma_f32_16x16x32_bf16 v[48:51], v[204:207], v[220:223], v[48:51]
	s_waitcnt lgkmcnt(2)
	v_mfma_f32_16x16x32_bf16 v[44:47], v[224:227], v[208:211], v[44:47]
	v_mfma_f32_16x16x32_bf16 v[40:43], v[224:227], v[212:215], v[40:43]
	v_mfma_f32_16x16x32_bf16 v[36:39], v[224:227], v[216:219], v[36:39]
	v_mfma_f32_16x16x32_bf16 v[32:35], v[224:227], v[220:223], v[32:35]
	s_waitcnt lgkmcnt(1)
	v_mfma_f32_16x16x32_bf16 v[28:31], v[228:231], v[208:211], v[28:31]
	v_mfma_f32_16x16x32_bf16 v[24:27], v[228:231], v[212:215], v[24:27]
	v_mfma_f32_16x16x32_bf16 v[20:23], v[228:231], v[216:219], v[20:23]
	v_mfma_f32_16x16x32_bf16 v[16:19], v[228:231], v[220:223], v[16:19]
	s_waitcnt lgkmcnt(0)
	v_mfma_f32_16x16x32_bf16 v[12:15], v[232:235], v[208:211], v[12:15]
	v_mfma_f32_16x16x32_bf16 v[8:11], v[232:235], v[212:215], v[8:11]
	v_mfma_f32_16x16x32_bf16 v[4:7], v[232:235], v[216:219], v[4:7]
	v_mfma_f32_16x16x32_bf16 v[0:3], v[232:235], v[220:223], v[0:3]
	s_setprio 2
	s_cmpk_eq_i32 s8, 0x780
	s_waitcnt vmcnt(0)
	s_barrier
	s_cbranch_scc0 .Lxk_2292
.Lxk_exit_2292:
	ds_read_b128 v[90:93], v117 offset:55296
	ds_read_b128 v[94:97], v117 offset:53248
	ds_read_b128 v[98:101], v118 offset:38912
	ds_read_b128 v[102:105], v118 offset:36864
	ds_read_b128 v[142:145], v117 offset:51200
	ds_read_b128 v[146:149], v117 offset:49152
	ds_read_b128 v[150:153], v118 offset:34816
	ds_read_b128 v[154:157], v118 offset:32768
	s_setprio 1
	s_waitcnt lgkmcnt(4)
	v_mfma_f32_16x16x32_bf16 v[20:23], v[102:105], v[94:97], v[20:23]
	v_mfma_f32_16x16x32_bf16 v[16:19], v[102:105], v[90:93], v[16:19]
	s_waitcnt lgkmcnt(0)
	v_mfma_f32_16x16x32_bf16 v[60:63], v[154:157], v[146:149], v[60:63]
	v_mfma_f32_16x16x32_bf16 v[56:59], v[154:157], v[142:145], v[56:59]
	v_mfma_f32_16x16x32_bf16 v[52:55], v[154:157], v[94:97], v[52:55]
	v_mfma_f32_16x16x32_bf16 v[48:51], v[154:157], v[90:93], v[48:51]
	v_mfma_f32_16x16x32_bf16 v[44:47], v[150:153], v[146:149], v[44:47]
	v_mfma_f32_16x16x32_bf16 v[40:43], v[150:153], v[142:145], v[40:43]
	v_mfma_f32_16x16x32_bf16 v[36:39], v[150:153], v[94:97], v[36:39]
	v_mfma_f32_16x16x32_bf16 v[32:35], v[150:153], v[90:93], v[32:35]
	v_mfma_f32_16x16x32_bf16 v[28:31], v[102:105], v[146:149], v[28:31]
	v_mfma_f32_16x16x32_bf16 v[24:27], v[102:105], v[142:145], v[24:27]
	v_mfma_f32_16x16x32_bf16 v[12:15], v[98:101], v[146:149], v[12:15]
	v_mfma_f32_16x16x32_bf16 v[8:11], v[98:101], v[142:145], v[8:11]
	v_mfma_f32_16x16x32_bf16 v[4:7], v[98:101], v[94:97], v[4:7]
	v_mfma_f32_16x16x32_bf16 v[0:3], v[98:101], v[90:93], v[0:3]
	s_setprio 0
	ds_read_b128 v[90:93], v119 offset:32768
	ds_read_b128 v[94:97], v119 offset:34816
	ds_read_b128 v[98:101], v120 offset:49152
	ds_read_b128 v[102:105], v120 offset:51200
	ds_read_b128 v[142:145], v119 offset:36864
	ds_read_b128 v[146:149], v119 offset:38912
	ds_read_b128 v[150:153], v120 offset:53248
	ds_read_b128 v[154:157], v120 offset:55296
	s_setprio 1
	s_waitcnt lgkmcnt(1)
	v_mfma_f32_16x16x32_bf16 v[20:23], v[142:145], v[150:153], v[20:23]
	s_waitcnt lgkmcnt(0)
	v_mfma_f32_16x16x32_bf16 v[16:19], v[142:145], v[154:157], v[16:19]
	v_mfma_f32_16x16x32_bf16 v[60:63], v[90:93], v[98:101], v[60:63]
	v_mfma_f32_16x16x32_bf16 v[56:59], v[90:93], v[102:105], v[56:59]
	v_mfma_f32_16x16x32_bf16 v[52:55], v[90:93], v[150:153], v[52:55]
	v_mfma_f32_16x16x32_bf16 v[48:51], v[90:93], v[154:157], v[48:51]
	v_mfma_f32_16x16x32_bf16 v[44:47], v[94:97], v[98:101], v[44:47]
	v_mfma_f32_16x16x32_bf16 v[40:43], v[94:97], v[102:105], v[40:43]
	v_mfma_f32_16x16x32_bf16 v[36:39], v[94:97], v[150:153], v[36:39]
	v_mfma_f32_16x16x32_bf16 v[32:35], v[94:97], v[154:157], v[32:35]
	v_mfma_f32_16x16x32_bf16 v[28:31], v[142:145], v[98:101], v[28:31]
	v_mfma_f32_16x16x32_bf16 v[24:27], v[142:145], v[102:105], v[24:27]
	v_mfma_f32_16x16x32_bf16 v[12:15], v[146:149], v[98:101], v[12:15]
	v_mfma_f32_16x16x32_bf16 v[8:11], v[146:149], v[102:105], v[8:11]
	v_mfma_f32_16x16x32_bf16 v[4:7], v[146:149], v[150:153], v[4:7]
	v_mfma_f32_16x16x32_bf16 v[0:3], v[146:149], v[154:157], v[0:3]
	s_setprio 0
	s_barrier
	ds_write2_b32 v121, v60, v56 offset1:16
	ds_write2_b32 v121, v61, v57 offset0:132 offset1:148
	v_add_u32_e32 v56, 0x400, v121
	ds_write2_b32 v56, v62, v58 offset0:8 offset1:24
	ds_write2_b32 v56, v63, v59 offset0:140 offset1:156
	ds_write2_b32 v121, v52, v48 offset0:32 offset1:48
	ds_write2_b32 v121, v53, v49 offset0:164 offset1:180
	ds_write2_b32 v56, v54, v50 offset0:40 offset1:56
	ds_write2_b32 v56, v55, v51 offset0:172 offset1:188
	v_add_u32_e32 v48, 0x2000, v121
	ds_write2_b32 v48, v44, v40 offset0:64 offset1:80
	ds_write2_b32 v48, v45, v41 offset0:196 offset1:212
	v_add_u32_e32 v40, 0x2400, v121
	ds_write2_b32 v40, v46, v42 offset0:72 offset1:88
	ds_write2_b32 v40, v47, v43 offset0:204 offset1:220
	ds_write2_b32 v48, v36, v32 offset0:96 offset1:112
	ds_write2_b32 v48, v37, v33 offset0:228 offset1:244
	ds_write2_b32 v40, v38, v34 offset0:104 offset1:120
	ds_write2_b32 v40, v39, v35 offset0:236 offset1:252
	v_add_u32_e32 v32, 0x4000, v121
	ds_write2_b32 v32, v28, v24 offset0:128 offset1:144
	v_add_u32_e32 v24, 0x4400, v121
	s_ashr_i32 s26, s22, 7
	ds_write2_b32 v24, v29, v25 offset0:4 offset1:20
	ds_write2_b32 v24, v30, v26 offset0:136 offset1:152
	v_add_u32_e32 v25, 0x4800, v121
	s_cmp_gt_i32 s26, 5
	ds_write2_b32 v25, v31, v27 offset0:12 offset1:28
	ds_write2_b32 v32, v20, v16 offset0:160 offset1:176
	ds_write2_b32 v24, v21, v17 offset0:36 offset1:52
	ds_write2_b32 v24, v22, v18 offset0:168 offset1:184
	ds_write2_b32 v25, v23, v19 offset0:44 offset1:60
	v_add_u32_e32 v16, 0x6000, v121
	v_or_b32_e32 v64, s22, v122
	s_cselect_b64 s[22:23], -1, 0
	s_ashr_i32 s27, s26, 31
	ds_write2_b32 v16, v12, v8 offset0:192 offset1:208
	v_add_u32_e32 v8, 0x6400, v121
	s_cmp_gt_i32 s26, 3
	ds_write2_b32 v8, v13, v9 offset0:68 offset1:84
	ds_write2_b32 v8, v14, v10 offset0:200 offset1:216
	v_add_u32_e32 v9, 0x6800, v121
	s_cselect_b64 s[24:25], -1, 0
	s_lshl_b64 s[26:27], s[26:27], 2
	ds_write2_b32 v9, v15, v11 offset0:76 offset1:92
	ds_write2_b32 v16, v4, v0 offset0:224 offset1:240
	ds_write2_b32 v8, v5, v1 offset0:100 offset1:116
	ds_write2_b32 v8, v6, v2 offset0:232 offset1:248
	ds_write2_b32 v9, v7, v3 offset0:108 offset1:124
	v_ashrrev_i32_e32 v1, 31, v64
	v_mov_b32_e32 v0, v64
	v_lshlrev_b64 v[2:3], 1, v[64:65]
	s_add_u32 s26, s40, s26
	v_cmp_gt_u32_e64 s[8:9], s38, v64
	v_lshl_add_u64 v[16:17], s[16:17], 0, v[2:3]
	s_addc_u32 s27, s41, s27
	v_lshl_add_u64 v[18:19], s[14:15], 0, v[2:3]
	v_lshl_add_u64 v[20:21], v[0:1], 1, s[12:13]
	v_add_u32_e32 v22, s28, v131
	s_mov_b32 s43, 0
	s_waitcnt lgkmcnt(0)
	s_barrier
	s_branch .LBB0_2295

.LBB0_2975:
	s_mul_hi_i32 s4, s43, 0x51eb851f
	s_lshr_b32 s5, s4, 31
	s_ashr_i32 s4, s4, 3
	s_add_i32 s4, s4, s5
	s_mul_i32 s5, s4, 0xffffffe7
	s_add_i32 s5, s5, s43
	s_lshl_b32 s6, s5, 7
	v_add_u32_e32 v0, s6, v106
	v_ashrrev_i32_e32 v1, 31, v0
	v_add_u32_e32 v2, 0x4000, v107
	v_lshlrev_b64 v[0:1], 11, v[0:1]
	v_readfirstlane_b32 s5, v2
	s_lshl_b32 s36, s4, 7
	v_lshl_add_u64 v[0:1], v[66:67], 0, v[0:1]
	s_mov_b32 m0, s5
	v_readfirstlane_b32 s5, v107
	global_load_lds_dwordx4 v[0:1], off
	v_add_u32_e32 v0, s36, v106
	v_ashrrev_i32_e32 v1, 31, v0
	v_lshlrev_b64 v[0:1], 11, v[0:1]
	v_lshl_add_u64 v[2:3], v[72:73], 0, v[0:1]
	s_mov_b32 m0, s5
	v_readfirstlane_b32 s5, v131
	global_load_lds_dwordx4 v[2:3], off
	v_add_u32_e32 v2, s6, v108
	v_ashrrev_i32_e32 v3, 31, v2
	v_lshlrev_b64 v[2:3], 11, v[2:3]
	v_lshl_add_u64 v[2:3], v[68:69], 0, v[2:3]
	s_mov_b32 m0, s5
	v_add_u32_e32 v4, 0x400, v107
	global_load_lds_dwordx4 v[2:3], off
	v_add_u32_e32 v2, s36, v108
	v_ashrrev_i32_e32 v3, 31, v2
	v_lshlrev_b64 v[2:3], 11, v[2:3]
	v_readfirstlane_b32 s5, v4
	v_lshl_add_u64 v[2:3], v[74:75], 0, v[2:3]
	s_mov_b32 m0, s5
	v_readfirstlane_b32 s5, v132
	global_load_lds_dwordx4 v[2:3], off
	v_add_u32_e32 v2, s6, v110
	v_ashrrev_i32_e32 v3, 31, v2
	v_lshlrev_b64 v[2:3], 11, v[2:3]
	v_lshl_add_u64 v[2:3], v[66:67], 0, v[2:3]
	s_mov_b32 m0, s5
	v_add_u32_e32 v4, 0x800, v107
	global_load_lds_dwordx4 v[2:3], off
	v_add_u32_e32 v2, s36, v110
	v_ashrrev_i32_e32 v3, 31, v2
	v_lshlrev_b64 v[2:3], 11, v[2:3]
	v_readfirstlane_b32 s5, v4
	v_lshl_add_u64 v[2:3], v[72:73], 0, v[2:3]
	s_mov_b32 m0, s5
	v_readfirstlane_b32 s5, v133
	global_load_lds_dwordx4 v[2:3], off
	v_add_u32_e32 v2, s6, v112
	v_ashrrev_i32_e32 v3, 31, v2
	v_lshlrev_b64 v[2:3], 11, v[2:3]
	v_lshl_add_u64 v[2:3], v[70:71], 0, v[2:3]
	s_mov_b32 m0, s5
	v_add_u32_e32 v4, 0xc00, v107
	global_load_lds_dwordx4 v[2:3], off
	v_add_u32_e32 v2, s36, v112
	v_ashrrev_i32_e32 v3, 31, v2
	v_lshlrev_b64 v[2:3], 11, v[2:3]
	v_readfirstlane_b32 s5, v4
	v_lshl_add_u64 v[2:3], v[76:77], 0, v[2:3]
	s_mov_b32 m0, s5
	s_mulk_i32 s4, 0xc80
	global_load_lds_dwordx4 v[2:3], off
	v_lshl_add_u64 v[92:93], v[80:81], 0, v[0:1]
	v_subrev_u32_e32 v0, s4, v123
	v_ashrrev_i32_e32 v1, 31, v0
	v_lshlrev_b64 v[0:1], 11, v[0:1]
	v_lshl_add_u64 v[94:95], v[82:83], 0, v[0:1]
	v_add_u32_e32 v0, s36, v124
	v_ashrrev_i32_e32 v1, 31, v0
	v_lshlrev_b64 v[0:1], 11, v[0:1]
	v_lshl_add_u64 v[96:97], v[84:85], 0, v[0:1]
	v_subrev_u32_e32 v0, s4, v125
	v_ashrrev_i32_e32 v1, 31, v0
	v_lshlrev_b64 v[0:1], 11, v[0:1]
	v_lshl_add_u64 v[98:99], v[78:79], 0, v[0:1]
	v_add_u32_e32 v0, s36, v126
	v_ashrrev_i32_e32 v1, 31, v0
	v_lshlrev_b64 v[0:1], 11, v[0:1]
	v_lshl_add_u64 v[100:101], v[80:81], 0, v[0:1]
	v_subrev_u32_e32 v0, s4, v127
	v_ashrrev_i32_e32 v1, 31, v0
	v_lshlrev_b64 v[0:1], 11, v[0:1]
	v_subrev_u32_e32 v2, s4, v122
	v_lshl_add_u64 v[102:103], v[86:87], 0, v[0:1]
	v_add_u32_e32 v0, s36, v128
	v_ashrrev_i32_e32 v3, 31, v2
	v_ashrrev_i32_e32 v1, 31, v0
	v_lshlrev_b64 v[2:3], 11, v[2:3]
	v_lshlrev_b64 v[0:1], 11, v[0:1]
	v_lshl_add_u64 v[90:91], v[78:79], 0, v[2:3]
	v_lshl_add_u64 v[104:105], v[88:89], 0, v[0:1]
	s_mov_b32 s7, 0
	s_mov_b64 s[4:5], 0
	v_mov_b32_e32 v0, 0
	v_mov_b32_e32 v1, v65
	v_mov_b32_e32 v2, v65
	v_mov_b32_e32 v3, v65
	v_mov_b32_e32 v4, 0
	v_mov_b32_e32 v5, v65
	v_mov_b32_e32 v6, v65
	v_mov_b32_e32 v7, v65
	v_mov_b32_e32 v8, 0
	v_mov_b32_e32 v9, v65
	v_mov_b32_e32 v10, v65
	v_mov_b32_e32 v11, v65
	v_mov_b32_e32 v12, 0
	v_mov_b32_e32 v13, v65
	v_mov_b32_e32 v14, v65
	v_mov_b32_e32 v15, v65
	v_mov_b32_e32 v16, 0
	v_mov_b32_e32 v17, v65
	v_mov_b32_e32 v18, v65
	v_mov_b32_e32 v19, v65
	v_mov_b32_e32 v20, 0
	v_mov_b32_e32 v21, v65
	v_mov_b32_e32 v22, v65
	v_mov_b32_e32 v23, v65
	v_mov_b32_e32 v24, 0
	v_mov_b32_e32 v25, v65
	v_mov_b32_e32 v26, v65
	v_mov_b32_e32 v27, v65
	v_mov_b32_e32 v28, 0
	v_mov_b32_e32 v29, v65
	v_mov_b32_e32 v30, v65
	v_mov_b32_e32 v31, v65
	v_mov_b32_e32 v32, 0
	v_mov_b32_e32 v33, v65
	v_mov_b32_e32 v34, v65
	v_mov_b32_e32 v35, v65
	v_mov_b32_e32 v36, 0
	v_mov_b32_e32 v37, v65
	v_mov_b32_e32 v38, v65
	v_mov_b32_e32 v39, v65
	v_mov_b32_e32 v40, 0
	v_mov_b32_e32 v41, v65
	v_mov_b32_e32 v42, v65
	v_mov_b32_e32 v43, v65
	v_mov_b32_e32 v44, 0
	v_mov_b32_e32 v45, v65
	v_mov_b32_e32 v46, v65
	v_mov_b32_e32 v47, v65
	v_mov_b32_e32 v48, 0
	v_mov_b32_e32 v49, v65
	v_mov_b32_e32 v50, v65
	v_mov_b32_e32 v51, v65
	v_mov_b32_e32 v52, 0
	v_mov_b32_e32 v53, v65
	v_mov_b32_e32 v54, v65
	v_mov_b32_e32 v55, v65
	v_mov_b32_e32 v56, 0
	v_mov_b32_e32 v57, v65
	v_mov_b32_e32 v58, v65
	v_mov_b32_e32 v59, v65
	v_mov_b32_e32 v60, 0
	v_mov_b32_e32 v61, v65
	v_mov_b32_e32 v62, v65
	v_mov_b32_e32 v63, v65
	s_waitcnt vmcnt(0) lgkmcnt(0)
	s_barrier
	v_add3_u32 v182, 0, v134, v135
	v_add_u32_e32 v183, 0x4000, v182
	s_nop 0
	v_readfirstlane_b32 s82, v183
	v_lshl_add_u32 v183, v109, 1, 0
	s_nop 0
	v_readfirstlane_b32 s83, v182
	v_add3_u32 v183, v183, v135, s40
	s_nop 0
	v_readfirstlane_b32 s84, v183
	v_add_u32_e32 v183, 0x400, v182
	s_nop 0
	v_readfirstlane_b32 s85, v183
	v_lshl_add_u32 v183, v111, 1, 0
	v_add3_u32 v183, v183, v135, s40
	s_nop 0
	v_readfirstlane_b32 s86, v183
	v_add_u32_e32 v183, 0x800, v182
	s_nop 0
	v_readfirstlane_b32 s87, v183
	v_lshl_add_u32 v183, v113, 1, 0
	v_add3_u32 v183, v183, v135, s40
	s_nop 0
	v_readfirstlane_b32 s88, v183
	v_add_u32_e32 v182, 0xc00, v182
	s_nop 0
	v_readfirstlane_b32 s89, v182
	v_subrev_u32_e32 v184, s52, v90
	v_subrev_u32_e32 v185, s52, v92
	v_subrev_u32_e32 v186, s52, v94
	v_subrev_u32_e32 v187, s52, v96
	v_subrev_u32_e32 v188, s52, v98
	v_subrev_u32_e32 v189, s52, v100
	v_subrev_u32_e32 v190, s52, v102
	v_subrev_u32_e32 v191, s52, v104
	s_bitcmp1_b32 s32, 0
	s_cbranch_scc1 .Lxk_2976
.LBB0_2976:
	s_and_b32 s28, s7, 0x4000
	s_xor_b32 s29, s28, 0x4000
	s_lshl_b32 s29, s29, 1
	s_add_i32 s29, s29, 32
	s_add_u32 s90, s52, s4
	s_addc_u32 s91, s53, s5
	s_add_i32 m0, s29, s82
	s_lshl_b32 s28, s28, 1
	global_load_lds_dwordx4 v184, s[90:91]
	s_add_i32 m0, s29, s83
	s_add_i32 s28, s28, 32
	global_load_lds_dwordx4 v185, s[90:91]
	s_add_i32 m0, s29, s84
	v_lshl_add_u32 v64, v114, 1, s28
	global_load_lds_dwordx4 v186, s[90:91]
	s_add_i32 m0, s29, s85
	v_lshl_add_u32 v170, v115, 1, s28
	global_load_lds_dwordx4 v187, s[90:91]
	s_add_i32 m0, s29, s86
	v_add_u32_e32 v158, v64, v136
	global_load_lds_dwordx4 v188, s[90:91]
	s_add_i32 m0, s29, s87
	v_add_u32_e32 v166, v170, v136
	global_load_lds_dwordx4 v189, s[90:91]
	s_add_i32 m0, s29, s88
	s_addk_i32 s7, 0x4000
	global_load_lds_dwordx4 v190, s[90:91]
	s_add_i32 m0, s29, s89
	s_add_u32 s4, s4, 0x80
	s_addc_u32 s5, s5, 0
	global_load_lds_dwordx4 v191, s[90:91]
	ds_read_b128 v[138:141], v158
	ds_read_b128 v[146:149], v166 offset:16384
	ds_read_b128 v[150:153], v166 offset:18432
	ds_read_b128 v[162:165], v166 offset:20480
	ds_read_b128 v[166:169], v166 offset:22528
	ds_read_b128 v[142:145], v158 offset:2048
	ds_read_b128 v[154:157], v158 offset:4096
	ds_read_b128 v[158:161], v158 offset:6144
	v_add_u32_e32 v64, v64, v137
	v_add_u32_e32 v236, v170, v137
	ds_read_b128 v[204:207], v64
	ds_read_b128 v[208:211], v236 offset:16384
	ds_read_b128 v[212:215], v236 offset:18432
	ds_read_b128 v[216:219], v236 offset:20480
	ds_read_b128 v[220:223], v236 offset:22528
	ds_read_b128 v[224:227], v64 offset:2048
	ds_read_b128 v[228:231], v64 offset:4096
	ds_read_b128 v[232:235], v64 offset:6144
	s_setprio 1
	s_waitcnt lgkmcnt(11)
	v_mfma_f32_16x16x32_bf16 v[60:63], v[138:141], v[146:149], v[60:63]
	v_mfma_f32_16x16x32_bf16 v[56:59], v[138:141], v[150:153], v[56:59]
	v_mfma_f32_16x16x32_bf16 v[52:55], v[138:141], v[162:165], v[52:55]
	v_mfma_f32_16x16x32_bf16 v[48:51], v[138:141], v[166:169], v[48:51]
	s_waitcnt lgkmcnt(10)
	v_mfma_f32_16x16x32_bf16 v[44:47], v[142:145], v[146:149], v[44:47]
	v_mfma_f32_16x16x32_bf16 v[40:43], v[142:145], v[150:153], v[40:43]
	v_mfma_f32_16x16x32_bf16 v[36:39], v[142:145], v[162:165], v[36:39]
	v_mfma_f32_16x16x32_bf16 v[32:35], v[142:145], v[166:169], v[32:35]
	s_waitcnt lgkmcnt(9)
	v_mfma_f32_16x16x32_bf16 v[28:31], v[154:157], v[146:149], v[28:31]
	v_mfma_f32_16x16x32_bf16 v[24:27], v[154:157], v[150:153], v[24:27]
	v_mfma_f32_16x16x32_bf16 v[20:23], v[154:157], v[162:165], v[20:23]
	v_mfma_f32_16x16x32_bf16 v[16:19], v[154:157], v[166:169], v[16:19]
	s_waitcnt lgkmcnt(8)
	v_mfma_f32_16x16x32_bf16 v[12:15], v[158:161], v[146:149], v[12:15]
	v_mfma_f32_16x16x32_bf16 v[8:11], v[158:161], v[150:153], v[8:11]
	v_mfma_f32_16x16x32_bf16 v[4:7], v[158:161], v[162:165], v[4:7]
	v_mfma_f32_16x16x32_bf16 v[0:3], v[158:161], v[166:169], v[0:3]
	s_waitcnt lgkmcnt(3)
	v_mfma_f32_16x16x32_bf16 v[60:63], v[204:207], v[208:211], v[60:63]
	v_mfma_f32_16x16x32_bf16 v[56:59], v[204:207], v[212:215], v[56:59]
	v_mfma_f32_16x16x32_bf16 v[52:55], v[204:207], v[216:219], v[52:55]
	v_mfma_f32_16x16x32_bf16 v[48:51], v[204:207], v[220:223], v[48:51]
	s_waitcnt lgkmcnt(2)
	v_mfma_f32_16x16x32_bf16 v[44:47], v[224:227], v[208:211], v[44:47]
	v_mfma_f32_16x16x32_bf16 v[40:43], v[224:227], v[212:215], v[40:43]
	v_mfma_f32_16x16x32_bf16 v[36:39], v[224:227], v[216:219], v[36:39]
	v_mfma_f32_16x16x32_bf16 v[32:35], v[224:227], v[220:223], v[32:35]
	s_waitcnt lgkmcnt(1)
	v_mfma_f32_16x16x32_bf16 v[28:31], v[228:231], v[208:211], v[28:31]
	v_mfma_f32_16x16x32_bf16 v[24:27], v[228:231], v[212:215], v[24:27]
	v_mfma_f32_16x16x32_bf16 v[20:23], v[228:231], v[216:219], v[20:23]
	v_mfma_f32_16x16x32_bf16 v[16:19], v[228:231], v[220:223], v[16:19]
	s_waitcnt lgkmcnt(0)
	v_mfma_f32_16x16x32_bf16 v[12:15], v[232:235], v[208:211], v[12:15]
	v_mfma_f32_16x16x32_bf16 v[8:11], v[232:235], v[212:215], v[8:11]
	v_mfma_f32_16x16x32_bf16 v[4:7], v[232:235], v[216:219], v[4:7]
	v_mfma_f32_16x16x32_bf16 v[0:3], v[232:235], v[220:223], v[0:3]
	s_setprio 0
	s_cmpk_eq_i32 s4, 0x780
	s_waitcnt vmcnt(0)
	s_barrier
	s_cbranch_scc0 .LBB0_2976
	s_branch .Lxk_exit_2976
.Lxk_2976:
	s_and_b32 s28, s7, 0x4000
	s_xor_b32 s29, s28, 0x4000
	s_lshl_b32 s29, s29, 1
	s_add_i32 s29, s29, 32
	s_add_u32 s90, s52, s4
	s_addc_u32 s91, s53, s5
	s_add_i32 m0, s29, s82
	s_lshl_b32 s28, s28, 1
	global_load_lds_dwordx4 v184, s[90:91]
	s_add_i32 m0, s29, s83
	s_add_i32 s28, s28, 32
	global_load_lds_dwordx4 v185, s[90:91]
	s_add_i32 m0, s29, s84
	v_lshl_add_u32 v64, v114, 1, s28
	global_load_lds_dwordx4 v186, s[90:91]
	s_add_i32 m0, s29, s85
	v_lshl_add_u32 v170, v115, 1, s28
	global_load_lds_dwordx4 v187, s[90:91]
	s_add_i32 m0, s29, s86
	v_add_u32_e32 v158, v64, v136
	global_load_lds_dwordx4 v188, s[90:91]
	s_add_i32 m0, s29, s87
	v_add_u32_e32 v166, v170, v136
	global_load_lds_dwordx4 v189, s[90:91]
	s_add_i32 m0, s29, s88
	s_addk_i32 s7, 0x4000
	global_load_lds_dwordx4 v190, s[90:91]
	s_add_i32 m0, s29, s89
	s_add_u32 s4, s4, 0x80
	s_addc_u32 s5, s5, 0
	global_load_lds_dwordx4 v191, s[90:91]
	ds_read_b128 v[138:141], v158
	ds_read_b128 v[146:149], v166 offset:16384
	ds_read_b128 v[150:153], v166 offset:18432
	ds_read_b128 v[162:165], v166 offset:20480
	ds_read_b128 v[166:169], v166 offset:22528
	ds_read_b128 v[142:145], v158 offset:2048
	ds_read_b128 v[154:157], v158 offset:4096
	ds_read_b128 v[158:161], v158 offset:6144
	v_add_u32_e32 v64, v64, v137
	v_add_u32_e32 v236, v170, v137
	ds_read_b128 v[204:207], v64
	ds_read_b128 v[208:211], v236 offset:16384
	ds_read_b128 v[212:215], v236 offset:18432
	ds_read_b128 v[216:219], v236 offset:20480
	ds_read_b128 v[220:223], v236 offset:22528
	ds_read_b128 v[224:227], v64 offset:2048
	ds_read_b128 v[228:231], v64 offset:4096
	ds_read_b128 v[232:235], v64 offset:6144
	s_setprio 3
	s_waitcnt lgkmcnt(11)
	v_mfma_f32_16x16x32_bf16 v[60:63], v[138:141], v[146:149], v[60:63]
	v_mfma_f32_16x16x32_bf16 v[56:59], v[138:141], v[150:153], v[56:59]
	v_mfma_f32_16x16x32_bf16 v[52:55], v[138:141], v[162:165], v[52:55]
	v_mfma_f32_16x16x32_bf16 v[48:51], v[138:141], v[166:169], v[48:51]
	s_waitcnt lgkmcnt(10)
	v_mfma_f32_16x16x32_bf16 v[44:47], v[142:145], v[146:149], v[44:47]
	v_mfma_f32_16x16x32_bf16 v[40:43], v[142:145], v[150:153], v[40:43]
	v_mfma_f32_16x16x32_bf16 v[36:39], v[142:145], v[162:165], v[36:39]
	v_mfma_f32_16x16x32_bf16 v[32:35], v[142:145], v[166:169], v[32:35]
	s_waitcnt lgkmcnt(9)
	v_mfma_f32_16x16x32_bf16 v[28:31], v[154:157], v[146:149], v[28:31]
	v_mfma_f32_16x16x32_bf16 v[24:27], v[154:157], v[150:153], v[24:27]
	v_mfma_f32_16x16x32_bf16 v[20:23], v[154:157], v[162:165], v[20:23]
	v_mfma_f32_16x16x32_bf16 v[16:19], v[154:157], v[166:169], v[16:19]
	s_waitcnt lgkmcnt(8)
	v_mfma_f32_16x16x32_bf16 v[12:15], v[158:161], v[146:149], v[12:15]
	v_mfma_f32_16x16x32_bf16 v[8:11], v[158:161], v[150:153], v[8:11]
	v_mfma_f32_16x16x32_bf16 v[4:7], v[158:161], v[162:165], v[4:7]
	v_mfma_f32_16x16x32_bf16 v[0:3], v[158:161], v[166:169], v[0:3]
	s_waitcnt lgkmcnt(3)
	v_mfma_f32_16x16x32_bf16 v[60:63], v[204:207], v[208:211], v[60:63]
	v_mfma_f32_16x16x32_bf16 v[56:59], v[204:207], v[212:215], v[56:59]
	v_mfma_f32_16x16x32_bf16 v[52:55], v[204:207], v[216:219], v[52:55]
	v_mfma_f32_16x16x32_bf16 v[48:51], v[204:207], v[220:223], v[48:51]
	s_waitcnt lgkmcnt(2)
	v_mfma_f32_16x16x32_bf16 v[44:47], v[224:227], v[208:211], v[44:47]
	v_mfma_f32_16x16x32_bf16 v[40:43], v[224:227], v[212:215], v[40:43]
	v_mfma_f32_16x16x32_bf16 v[36:39], v[224:227], v[216:219], v[36:39]
	v_mfma_f32_16x16x32_bf16 v[32:35], v[224:227], v[220:223], v[32:35]
	s_waitcnt lgkmcnt(1)
	v_mfma_f32_16x16x32_bf16 v[28:31], v[228:231], v[208:211], v[28:31]
	v_mfma_f32_16x16x32_bf16 v[24:27], v[228:231], v[212:215], v[24:27]
	v_mfma_f32_16x16x32_bf16 v[20:23], v[228:231], v[216:219], v[20:23]
	v_mfma_f32_16x16x32_bf16 v[16:19], v[228:231], v[220:223], v[16:19]
	s_waitcnt lgkmcnt(0)
	v_mfma_f32_16x16x32_bf16 v[12:15], v[232:235], v[208:211], v[12:15]
	v_mfma_f32_16x16x32_bf16 v[8:11], v[232:235], v[212:215], v[8:11]
	v_mfma_f32_16x16x32_bf16 v[4:7], v[232:235], v[216:219], v[4:7]
	v_mfma_f32_16x16x32_bf16 v[0:3], v[232:235], v[220:223], v[0:3]
	s_setprio 2
	s_cmpk_eq_i32 s4, 0x780
	s_waitcnt vmcnt(0)
	s_barrier
	s_cbranch_scc0 .Lxk_2976
.Lxk_exit_2976:
	ds_read_b128 v[90:93], v116 offset:55296
	ds_read_b128 v[94:97], v116 offset:53248
	ds_read_b128 v[98:101], v117 offset:38912
	ds_read_b128 v[102:105], v117 offset:36864
	ds_read_b128 v[138:141], v116 offset:51200
	ds_read_b128 v[142:145], v116 offset:49152
	ds_read_b128 v[146:149], v117 offset:34816
	ds_read_b128 v[150:153], v117 offset:32768
	s_setprio 1
	s_waitcnt lgkmcnt(3)
	v_mfma_f32_16x16x32_bf16 v[24:27], v[102:105], v[138:141], v[24:27]
	v_mfma_f32_16x16x32_bf16 v[20:23], v[102:105], v[94:97], v[20:23]
	v_mfma_f32_16x16x32_bf16 v[16:19], v[102:105], v[90:93], v[16:19]
	s_waitcnt lgkmcnt(0)
	v_mfma_f32_16x16x32_bf16 v[60:63], v[150:153], v[142:145], v[60:63]
	v_mfma_f32_16x16x32_bf16 v[56:59], v[150:153], v[138:141], v[56:59]
	v_mfma_f32_16x16x32_bf16 v[52:55], v[150:153], v[94:97], v[52:55]
	v_mfma_f32_16x16x32_bf16 v[48:51], v[150:153], v[90:93], v[48:51]
	v_mfma_f32_16x16x32_bf16 v[44:47], v[146:149], v[142:145], v[44:47]
	v_mfma_f32_16x16x32_bf16 v[40:43], v[146:149], v[138:141], v[40:43]
	v_mfma_f32_16x16x32_bf16 v[36:39], v[146:149], v[94:97], v[36:39]
	v_mfma_f32_16x16x32_bf16 v[32:35], v[146:149], v[90:93], v[32:35]
	v_mfma_f32_16x16x32_bf16 v[28:31], v[102:105], v[142:145], v[28:31]
	v_mfma_f32_16x16x32_bf16 v[12:15], v[98:101], v[142:145], v[12:15]
	v_mfma_f32_16x16x32_bf16 v[8:11], v[98:101], v[138:141], v[8:11]
	v_mfma_f32_16x16x32_bf16 v[4:7], v[98:101], v[94:97], v[4:7]
	v_mfma_f32_16x16x32_bf16 v[0:3], v[98:101], v[90:93], v[0:3]
	s_setprio 0
	ds_read_b128 v[90:93], v118 offset:32768
	ds_read_b128 v[94:97], v118 offset:34816
	ds_read_b128 v[98:101], v119 offset:49152
	ds_read_b128 v[102:105], v119 offset:51200
	ds_read_b128 v[138:141], v118 offset:36864
	ds_read_b128 v[142:145], v118 offset:38912
	ds_read_b128 v[146:149], v119 offset:53248
	ds_read_b128 v[150:153], v119 offset:55296
	s_setprio 1
	s_waitcnt lgkmcnt(3)
	v_mfma_f32_16x16x32_bf16 v[24:27], v[138:141], v[102:105], v[24:27]
	s_waitcnt lgkmcnt(1)
	v_mfma_f32_16x16x32_bf16 v[20:23], v[138:141], v[146:149], v[20:23]
	s_waitcnt lgkmcnt(0)
	v_mfma_f32_16x16x32_bf16 v[16:19], v[138:141], v[150:153], v[16:19]
	v_mfma_f32_16x16x32_bf16 v[60:63], v[90:93], v[98:101], v[60:63]
	v_mfma_f32_16x16x32_bf16 v[56:59], v[90:93], v[102:105], v[56:59]
	v_mfma_f32_16x16x32_bf16 v[52:55], v[90:93], v[146:149], v[52:55]
	v_mfma_f32_16x16x32_bf16 v[48:51], v[90:93], v[150:153], v[48:51]
	v_mfma_f32_16x16x32_bf16 v[44:47], v[94:97], v[98:101], v[44:47]
	v_mfma_f32_16x16x32_bf16 v[40:43], v[94:97], v[102:105], v[40:43]
	v_mfma_f32_16x16x32_bf16 v[36:39], v[94:97], v[146:149], v[36:39]
	v_mfma_f32_16x16x32_bf16 v[32:35], v[94:97], v[150:153], v[32:35]
	v_mfma_f32_16x16x32_bf16 v[28:31], v[138:141], v[98:101], v[28:31]
	v_mfma_f32_16x16x32_bf16 v[12:15], v[142:145], v[98:101], v[12:15]
	v_mfma_f32_16x16x32_bf16 v[8:11], v[142:145], v[102:105], v[8:11]
	v_mfma_f32_16x16x32_bf16 v[4:7], v[142:145], v[146:149], v[4:7]
	v_mfma_f32_16x16x32_bf16 v[0:3], v[142:145], v[150:153], v[0:3]
	s_setprio 0
	s_barrier
	ds_write2_b32 v120, v60, v56 offset1:16
	ds_write2_b32 v120, v61, v57 offset0:132 offset1:148
	v_add_u32_e32 v56, 0x400, v120
	ds_write2_b32 v56, v62, v58 offset0:8 offset1:24
	ds_write2_b32 v56, v63, v59 offset0:140 offset1:156
	ds_write2_b32 v120, v52, v48 offset0:32 offset1:48
	ds_write2_b32 v120, v53, v49 offset0:164 offset1:180
	ds_write2_b32 v56, v54, v50 offset0:40 offset1:56
	ds_write2_b32 v56, v55, v51 offset0:172 offset1:188
	v_add_u32_e32 v48, 0x2000, v120
	ds_write2_b32 v48, v44, v40 offset0:64 offset1:80
	ds_write2_b32 v48, v45, v41 offset0:196 offset1:212
	v_add_u32_e32 v40, 0x2400, v120
	ds_write2_b32 v40, v46, v42 offset0:72 offset1:88
	ds_write2_b32 v40, v47, v43 offset0:204 offset1:220
	ds_write2_b32 v48, v36, v32 offset0:96 offset1:112
	ds_write2_b32 v48, v37, v33 offset0:228 offset1:244
	ds_write2_b32 v40, v38, v34 offset0:104 offset1:120
	ds_write2_b32 v40, v39, v35 offset0:236 offset1:252
	v_add_u32_e32 v32, 0x4000, v120
	ds_write2_b32 v32, v28, v24 offset0:128 offset1:144
	v_add_u32_e32 v24, 0x4400, v120
	ds_write2_b32 v24, v29, v25 offset0:4 offset1:20
	ds_write2_b32 v24, v30, v26 offset0:136 offset1:152
	v_add_u32_e32 v25, 0x4800, v120
	ds_write2_b32 v25, v31, v27 offset0:12 offset1:28
	ds_write2_b32 v32, v20, v16 offset0:160 offset1:176
	ds_write2_b32 v24, v21, v17 offset0:36 offset1:52
	ds_write2_b32 v24, v22, v18 offset0:168 offset1:184
	ds_write2_b32 v25, v23, v19 offset0:44 offset1:60
	v_add_u32_e32 v16, 0x6000, v120
	ds_write2_b32 v16, v12, v8 offset0:192 offset1:208
	v_add_u32_e32 v8, 0x6400, v120
	s_cmpk_gt_u32 s6, 0x3ff
	ds_write2_b32 v8, v13, v9 offset0:68 offset1:84
	ds_write2_b32 v8, v14, v10 offset0:200 offset1:216
	v_add_u32_e32 v9, 0x6800, v120
	v_or_b32_e32 v64, s6, v121
	s_cselect_b64 s[28:29], -1, 0
	s_cmpk_gt_u32 s6, 0x7ff
	ds_write2_b32 v9, v15, v11 offset0:76 offset1:92
	ds_write2_b32 v16, v4, v0 offset0:224 offset1:240
	ds_write2_b32 v8, v5, v1 offset0:100 offset1:116
	ds_write2_b32 v8, v6, v2 offset0:232 offset1:248
	ds_write2_b32 v9, v7, v3 offset0:108 offset1:124
	s_cselect_b64 s[30:31], -1, 0
	s_cmpk_gt_u32 s6, 0xbff
	v_ashrrev_i32_e32 v1, 31, v64
	v_mov_b32_e32 v0, v64
	v_lshlrev_b64 v[2:3], 1, v[64:65]
	v_cmp_lt_i32_e64 s[4:5], s41, v64
	s_cselect_b64 s[34:35], -1, 0
	v_cmp_gt_u32_e64 s[6:7], s42, v64
	v_lshl_add_u64 v[16:17], v[64:65], 2, s[18:19]
	v_lshl_add_u64 v[18:19], s[16:17], 0, v[2:3]
	v_lshl_add_u64 v[20:21], s[14:15], 0, v[2:3]
	v_lshl_add_u64 v[22:23], s[12:13], 0, v[2:3]
	v_lshl_add_u64 v[24:25], v[0:1], 1, s[10:11]
	v_add_u32_e32 v26, s36, v129
	s_mov_b32 s44, 0
	s_waitcnt lgkmcnt(0)
	s_barrier
	s_branch .LBB0_2979

.LBB0_3007:
	v_cvt_f32_ubyte0_e32 v0, s6
	v_rcp_iflag_f32_e32 v0, v0
	s_sub_i32 s24, 0, s6
	s_abs_i32 s23, s4
	s_ashr_i32 s22, s4, 31
	v_mul_f32_e32 v0, 0x4f7ffffe, v0
	v_cvt_u32_f32_e32 v0, v0
	v_add_u32_e32 v2, 0x4000, v108
	v_add_u32_e32 v4, 0x400, v108
	v_readfirstlane_b32 s25, v0
	s_mul_i32 s24, s24, s25
	s_mul_hi_u32 s24, s25, s24
	s_add_i32 s25, s25, s24
	s_mul_hi_u32 s24, s23, s25
	s_mul_i32 s25, s24, s6
	s_sub_i32 s23, s23, s25
	s_add_i32 s26, s24, 1
	s_sub_i32 s25, s23, s6
	s_cmp_ge_u32 s23, s6
	s_cselect_b32 s24, s26, s24
	s_cselect_b32 s23, s25, s23
	s_add_i32 s25, s24, 1
	s_cmp_ge_u32 s23, s6
	s_cselect_b32 s23, s25, s24
	s_xor_b32 s23, s23, s22
	s_sub_i32 s22, s23, s22
	s_mul_i32 s23, s22, s6
	s_sub_i32 s6, s4, s23
	s_lshl_b32 s6, s6, 7
	v_add_u32_e32 v0, s22, v106
	s_add_i32 s6, s6, s5
	v_lshlrev_b32_e32 v135, 7, v0
	v_add_u32_e32 v0, s6, v107
	v_ashrrev_i32_e32 v1, 31, v0
	v_lshlrev_b64 v[0:1], 11, v[0:1]
	v_readfirstlane_b32 s22, v2
	v_lshl_add_u64 v[0:1], v[66:67], 0, v[0:1]
	s_mov_b32 m0, s22
	v_readfirstlane_b32 s22, v108
	global_load_lds_dwordx4 v[0:1], off
	v_add_u32_e32 v0, v135, v107
	v_ashrrev_i32_e32 v1, 31, v0
	v_lshlrev_b64 v[0:1], 11, v[0:1]
	v_lshl_add_u64 v[2:3], v[72:73], 0, v[0:1]
	s_mov_b32 m0, s22
	v_readfirstlane_b32 s22, v128
	global_load_lds_dwordx4 v[2:3], off
	v_add_u32_e32 v2, s6, v109
	v_ashrrev_i32_e32 v3, 31, v2
	v_lshlrev_b64 v[2:3], 11, v[2:3]
	v_lshl_add_u64 v[2:3], v[68:69], 0, v[2:3]
	s_mov_b32 m0, s22
	v_readfirstlane_b32 s22, v4
	global_load_lds_dwordx4 v[2:3], off
	v_add_u32_e32 v2, v135, v109
	v_ashrrev_i32_e32 v3, 31, v2
	v_lshlrev_b64 v[2:3], 11, v[2:3]
	v_lshl_add_u64 v[2:3], v[74:75], 0, v[2:3]
	s_mov_b32 m0, s22
	v_readfirstlane_b32 s22, v129
	global_load_lds_dwordx4 v[2:3], off
	v_add_u32_e32 v2, s6, v111
	v_ashrrev_i32_e32 v3, 31, v2
	v_lshlrev_b64 v[2:3], 11, v[2:3]
	v_lshl_add_u64 v[2:3], v[66:67], 0, v[2:3]
	s_mov_b32 m0, s22
	v_add_u32_e32 v4, 0x800, v108
	global_load_lds_dwordx4 v[2:3], off
	v_add_u32_e32 v2, v135, v111
	v_ashrrev_i32_e32 v3, 31, v2
	v_lshlrev_b64 v[2:3], 11, v[2:3]
	v_readfirstlane_b32 s22, v4
	v_lshl_add_u64 v[2:3], v[72:73], 0, v[2:3]
	s_mov_b32 m0, s22
	v_readfirstlane_b32 s22, v130
	global_load_lds_dwordx4 v[2:3], off
	v_add_u32_e32 v2, s6, v113
	v_ashrrev_i32_e32 v3, 31, v2
	v_lshlrev_b64 v[2:3], 11, v[2:3]
	v_lshl_add_u64 v[2:3], v[70:71], 0, v[2:3]
	s_mov_b32 m0, s22
	v_add_u32_e32 v4, 0xc00, v108
	global_load_lds_dwordx4 v[2:3], off
	v_add_u32_e32 v2, v135, v113
	v_ashrrev_i32_e32 v3, 31, v2
	v_lshlrev_b64 v[2:3], 11, v[2:3]
	v_readfirstlane_b32 s22, v4
	v_lshl_add_u64 v[2:3], v[76:77], 0, v[2:3]
	s_mov_b32 m0, s22
	s_lshl_b32 s4, s4, 7
	global_load_lds_dwordx4 v[2:3], off
	s_add_i32 s4, s4, s5
	s_lshl_b32 s5, s23, 7
	v_lshl_add_u64 v[92:93], v[80:81], 0, v[0:1]
	v_add_u32_e32 v0, s4, v123
	v_subrev_u32_e32 v0, s5, v0
	v_ashrrev_i32_e32 v1, 31, v0
	v_lshlrev_b64 v[0:1], 11, v[0:1]
	v_lshl_add_u64 v[94:95], v[82:83], 0, v[0:1]
	v_add_u32_e32 v0, v123, v135
	v_ashrrev_i32_e32 v1, 31, v0
	v_lshlrev_b64 v[0:1], 11, v[0:1]
	v_lshl_add_u64 v[96:97], v[84:85], 0, v[0:1]
	v_add_u32_e32 v0, s4, v124
	v_subrev_u32_e32 v0, s5, v0
	v_ashrrev_i32_e32 v1, 31, v0
	v_lshlrev_b64 v[0:1], 11, v[0:1]
	v_lshl_add_u64 v[98:99], v[78:79], 0, v[0:1]
	v_add_u32_e32 v0, v124, v135
	v_ashrrev_i32_e32 v1, 31, v0
	v_lshlrev_b64 v[0:1], 11, v[0:1]
	v_lshl_add_u64 v[100:101], v[80:81], 0, v[0:1]
	v_add_u32_e32 v0, s4, v125
	v_subrev_u32_e32 v0, s5, v0
	v_ashrrev_i32_e32 v1, 31, v0
	v_lshlrev_b64 v[0:1], 11, v[0:1]
	v_add_u32_e32 v2, s4, v107
	v_lshl_add_u64 v[102:103], v[86:87], 0, v[0:1]
	v_add_u32_e32 v0, v125, v135
	v_subrev_u32_e32 v2, s5, v2
	v_ashrrev_i32_e32 v1, 31, v0
	v_ashrrev_i32_e32 v3, 31, v2
	v_lshlrev_b64 v[0:1], 11, v[0:1]
	v_lshlrev_b64 v[2:3], 11, v[2:3]
	v_lshl_add_u64 v[104:105], v[88:89], 0, v[0:1]
	v_mov_b32_e32 v0, 0
	v_lshl_add_u64 v[90:91], v[78:79], 0, v[2:3]
	s_mov_b64 s[4:5], 0
	v_mov_b32_e32 v1, v0
	v_mov_b32_e32 v2, v0
	v_mov_b32_e32 v3, v0
	v_mov_b32_e32 v4, v0
	v_mov_b32_e32 v5, v0
	v_mov_b32_e32 v6, v0
	v_mov_b32_e32 v7, v0
	v_mov_b32_e32 v8, v0
	v_mov_b32_e32 v9, v0
	v_mov_b32_e32 v10, v0
	v_mov_b32_e32 v11, v0
	v_mov_b32_e32 v12, v0
	v_mov_b32_e32 v13, v0
	v_mov_b32_e32 v14, v0
	v_mov_b32_e32 v15, v0
	v_mov_b32_e32 v16, v0
	v_mov_b32_e32 v17, v0
	v_mov_b32_e32 v18, v0
	v_mov_b32_e32 v19, v0
	v_mov_b32_e32 v20, v0
	v_mov_b32_e32 v21, v0
	v_mov_b32_e32 v22, v0
	v_mov_b32_e32 v23, v0
	v_mov_b32_e32 v24, v0
	v_mov_b32_e32 v25, v0
	v_mov_b32_e32 v26, v0
	v_mov_b32_e32 v27, v0
	v_mov_b32_e32 v28, v0
	v_mov_b32_e32 v29, v0
	v_mov_b32_e32 v30, v0
	v_mov_b32_e32 v31, v0
	v_mov_b32_e32 v32, v0
	v_mov_b32_e32 v33, v0
	v_mov_b32_e32 v34, v0
	v_mov_b32_e32 v35, v0
	v_mov_b32_e32 v36, v0
	v_mov_b32_e32 v37, v0
	v_mov_b32_e32 v38, v0
	v_mov_b32_e32 v39, v0
	v_mov_b32_e32 v40, v0
	v_mov_b32_e32 v41, v0
	v_mov_b32_e32 v42, v0
	v_mov_b32_e32 v43, v0
	v_mov_b32_e32 v44, v0
	v_mov_b32_e32 v45, v0
	v_mov_b32_e32 v46, v0
	v_mov_b32_e32 v47, v0
	v_mov_b32_e32 v48, v0
	v_mov_b32_e32 v49, v0
	v_mov_b32_e32 v50, v0
	v_mov_b32_e32 v51, v0
	v_mov_b32_e32 v52, v0
	v_mov_b32_e32 v53, v0
	v_mov_b32_e32 v54, v0
	v_mov_b32_e32 v55, v0
	v_mov_b32_e32 v56, v0
	v_mov_b32_e32 v57, v0
	v_mov_b32_e32 v58, v0
	v_mov_b32_e32 v59, v0
	v_mov_b32_e32 v60, v0
	v_mov_b32_e32 v61, v0
	v_mov_b32_e32 v62, v0
	v_mov_b32_e32 v63, v0
	s_waitcnt vmcnt(0) lgkmcnt(0)
	s_barrier
	v_add3_u32 v182, 0, v131, v132
	v_add_u32_e32 v183, 0x4000, v182
	s_nop 0
	v_readfirstlane_b32 s82, v183
	v_lshl_add_u32 v183, v110, 1, 0
	s_nop 0
	v_readfirstlane_b32 s83, v182
	v_add3_u32 v183, v183, v132, s21
	s_nop 0
	v_readfirstlane_b32 s84, v183
	v_add_u32_e32 v183, 0x400, v182
	s_nop 0
	v_readfirstlane_b32 s85, v183
	v_lshl_add_u32 v183, v112, 1, 0
	v_add3_u32 v183, v183, v132, s21
	s_nop 0
	v_readfirstlane_b32 s86, v183
	v_add_u32_e32 v183, 0x800, v182
	s_nop 0
	v_readfirstlane_b32 s87, v183
	v_lshl_add_u32 v183, v114, 1, 0
	v_add3_u32 v183, v183, v132, s21
	s_nop 0
	v_readfirstlane_b32 s88, v183
	v_add_u32_e32 v182, 0xc00, v182
	s_nop 0
	v_readfirstlane_b32 s89, v182
	v_subrev_u32_e32 v184, s52, v90
	v_subrev_u32_e32 v185, s52, v92
	v_subrev_u32_e32 v186, s52, v94
	v_subrev_u32_e32 v187, s52, v96
	v_subrev_u32_e32 v188, s52, v98
	v_subrev_u32_e32 v189, s52, v100
	v_subrev_u32_e32 v190, s52, v102
	v_subrev_u32_e32 v191, s52, v104
	s_bitcmp1_b32 s32, 0
	s_cbranch_scc1 .Lxk_3008
.LBB0_3008:
	s_and_b32 s22, s7, 0x4000
	s_xor_b32 s23, s22, 0x4000
	s_lshl_b32 s23, s23, 1
	s_add_i32 s23, s23, 32
	s_add_u32 s90, s52, s4
	s_addc_u32 s91, s53, s5
	s_add_i32 m0, s23, s82
	s_lshl_b32 s22, s22, 1
	global_load_lds_dwordx4 v184, s[90:91]
	s_add_i32 m0, s23, s83
	s_add_i32 s22, s22, 32
	global_load_lds_dwordx4 v185, s[90:91]
	s_add_i32 m0, s23, s84
	v_lshl_add_u32 v64, v115, 1, s22
	global_load_lds_dwordx4 v186, s[90:91]
	s_add_i32 m0, s23, s85
	v_lshl_add_u32 v168, v116, 1, s22
	global_load_lds_dwordx4 v187, s[90:91]
	s_add_i32 m0, s23, s86
	v_add_u32_e32 v156, v64, v133
	global_load_lds_dwordx4 v188, s[90:91]
	s_add_i32 m0, s23, s87
	v_add_u32_e32 v164, v168, v133
	global_load_lds_dwordx4 v189, s[90:91]
	s_add_i32 m0, s23, s88
	s_addk_i32 s7, 0x4000
	global_load_lds_dwordx4 v190, s[90:91]
	s_add_i32 m0, s23, s89
	s_add_u32 s4, s4, 0x80
	s_addc_u32 s5, s5, 0
	global_load_lds_dwordx4 v191, s[90:91]
	ds_read_b128 v[136:139], v156
	ds_read_b128 v[144:147], v164 offset:16384
	ds_read_b128 v[148:151], v164 offset:18432
	ds_read_b128 v[160:163], v164 offset:20480
	ds_read_b128 v[164:167], v164 offset:22528
	ds_read_b128 v[140:143], v156 offset:2048
	ds_read_b128 v[152:155], v156 offset:4096
	ds_read_b128 v[156:159], v156 offset:6144
	v_add_u32_e32 v64, v64, v134
	v_add_u32_e32 v236, v168, v134
	ds_read_b128 v[204:207], v64
	ds_read_b128 v[208:211], v236 offset:16384
	ds_read_b128 v[212:215], v236 offset:18432
	ds_read_b128 v[216:219], v236 offset:20480
	ds_read_b128 v[220:223], v236 offset:22528
	ds_read_b128 v[224:227], v64 offset:2048
	ds_read_b128 v[228:231], v64 offset:4096
	ds_read_b128 v[232:235], v64 offset:6144
	s_setprio 1
	s_waitcnt lgkmcnt(11)
	v_mfma_f32_16x16x32_bf16 v[60:63], v[136:139], v[144:147], v[60:63]
	v_mfma_f32_16x16x32_bf16 v[56:59], v[136:139], v[148:151], v[56:59]
	v_mfma_f32_16x16x32_bf16 v[52:55], v[136:139], v[160:163], v[52:55]
	v_mfma_f32_16x16x32_bf16 v[48:51], v[136:139], v[164:167], v[48:51]
	s_waitcnt lgkmcnt(10)
	v_mfma_f32_16x16x32_bf16 v[44:47], v[140:143], v[144:147], v[44:47]
	v_mfma_f32_16x16x32_bf16 v[40:43], v[140:143], v[148:151], v[40:43]
	v_mfma_f32_16x16x32_bf16 v[36:39], v[140:143], v[160:163], v[36:39]
	v_mfma_f32_16x16x32_bf16 v[32:35], v[140:143], v[164:167], v[32:35]
	s_waitcnt lgkmcnt(9)
	v_mfma_f32_16x16x32_bf16 v[28:31], v[152:155], v[144:147], v[28:31]
	v_mfma_f32_16x16x32_bf16 v[24:27], v[152:155], v[148:151], v[24:27]
	v_mfma_f32_16x16x32_bf16 v[20:23], v[152:155], v[160:163], v[20:23]
	v_mfma_f32_16x16x32_bf16 v[16:19], v[152:155], v[164:167], v[16:19]
	s_waitcnt lgkmcnt(8)
	v_mfma_f32_16x16x32_bf16 v[12:15], v[156:159], v[144:147], v[12:15]
	v_mfma_f32_16x16x32_bf16 v[8:11], v[156:159], v[148:151], v[8:11]
	v_mfma_f32_16x16x32_bf16 v[4:7], v[156:159], v[160:163], v[4:7]
	v_mfma_f32_16x16x32_bf16 v[0:3], v[156:159], v[164:167], v[0:3]
	s_waitcnt lgkmcnt(3)
	v_mfma_f32_16x16x32_bf16 v[60:63], v[204:207], v[208:211], v[60:63]
	v_mfma_f32_16x16x32_bf16 v[56:59], v[204:207], v[212:215], v[56:59]
	v_mfma_f32_16x16x32_bf16 v[52:55], v[204:207], v[216:219], v[52:55]
	v_mfma_f32_16x16x32_bf16 v[48:51], v[204:207], v[220:223], v[48:51]
	s_waitcnt lgkmcnt(2)
	v_mfma_f32_16x16x32_bf16 v[44:47], v[224:227], v[208:211], v[44:47]
	v_mfma_f32_16x16x32_bf16 v[40:43], v[224:227], v[212:215], v[40:43]
	v_mfma_f32_16x16x32_bf16 v[36:39], v[224:227], v[216:219], v[36:39]
	v_mfma_f32_16x16x32_bf16 v[32:35], v[224:227], v[220:223], v[32:35]
	s_waitcnt lgkmcnt(1)
	v_mfma_f32_16x16x32_bf16 v[28:31], v[228:231], v[208:211], v[28:31]
	v_mfma_f32_16x16x32_bf16 v[24:27], v[228:231], v[212:215], v[24:27]
	v_mfma_f32_16x16x32_bf16 v[20:23], v[228:231], v[216:219], v[20:23]
	v_mfma_f32_16x16x32_bf16 v[16:19], v[228:231], v[220:223], v[16:19]
	s_waitcnt lgkmcnt(0)
	v_mfma_f32_16x16x32_bf16 v[12:15], v[232:235], v[208:211], v[12:15]
	v_mfma_f32_16x16x32_bf16 v[8:11], v[232:235], v[212:215], v[8:11]
	v_mfma_f32_16x16x32_bf16 v[4:7], v[232:235], v[216:219], v[4:7]
	v_mfma_f32_16x16x32_bf16 v[0:3], v[232:235], v[220:223], v[0:3]
	s_setprio 0
	s_cmpk_eq_i32 s4, 0x780
	s_waitcnt vmcnt(0)
	s_barrier
	s_cbranch_scc0 .LBB0_3008
	s_branch .Lxk_exit_3008
.Lxk_3008:
	s_and_b32 s22, s7, 0x4000
	s_xor_b32 s23, s22, 0x4000
	s_lshl_b32 s23, s23, 1
	s_add_i32 s23, s23, 32
	s_add_u32 s90, s52, s4
	s_addc_u32 s91, s53, s5
	s_add_i32 m0, s23, s82
	s_lshl_b32 s22, s22, 1
	global_load_lds_dwordx4 v184, s[90:91]
	s_add_i32 m0, s23, s83
	s_add_i32 s22, s22, 32
	global_load_lds_dwordx4 v185, s[90:91]
	s_add_i32 m0, s23, s84
	v_lshl_add_u32 v64, v115, 1, s22
	global_load_lds_dwordx4 v186, s[90:91]
	s_add_i32 m0, s23, s85
	v_lshl_add_u32 v168, v116, 1, s22
	global_load_lds_dwordx4 v187, s[90:91]
	s_add_i32 m0, s23, s86
	v_add_u32_e32 v156, v64, v133
	global_load_lds_dwordx4 v188, s[90:91]
	s_add_i32 m0, s23, s87
	v_add_u32_e32 v164, v168, v133
	global_load_lds_dwordx4 v189, s[90:91]
	s_add_i32 m0, s23, s88
	s_addk_i32 s7, 0x4000
	global_load_lds_dwordx4 v190, s[90:91]
	s_add_i32 m0, s23, s89
	s_add_u32 s4, s4, 0x80
	s_addc_u32 s5, s5, 0
	global_load_lds_dwordx4 v191, s[90:91]
	ds_read_b128 v[136:139], v156
	ds_read_b128 v[144:147], v164 offset:16384
	ds_read_b128 v[148:151], v164 offset:18432
	ds_read_b128 v[160:163], v164 offset:20480
	ds_read_b128 v[164:167], v164 offset:22528
	ds_read_b128 v[140:143], v156 offset:2048
	ds_read_b128 v[152:155], v156 offset:4096
	ds_read_b128 v[156:159], v156 offset:6144
	v_add_u32_e32 v64, v64, v134
	v_add_u32_e32 v236, v168, v134
	ds_read_b128 v[204:207], v64
	ds_read_b128 v[208:211], v236 offset:16384
	ds_read_b128 v[212:215], v236 offset:18432
	ds_read_b128 v[216:219], v236 offset:20480
	ds_read_b128 v[220:223], v236 offset:22528
	ds_read_b128 v[224:227], v64 offset:2048
	ds_read_b128 v[228:231], v64 offset:4096
	ds_read_b128 v[232:235], v64 offset:6144
	s_setprio 3
	s_waitcnt lgkmcnt(11)
	v_mfma_f32_16x16x32_bf16 v[60:63], v[136:139], v[144:147], v[60:63]
	v_mfma_f32_16x16x32_bf16 v[56:59], v[136:139], v[148:151], v[56:59]
	v_mfma_f32_16x16x32_bf16 v[52:55], v[136:139], v[160:163], v[52:55]
	v_mfma_f32_16x16x32_bf16 v[48:51], v[136:139], v[164:167], v[48:51]
	s_waitcnt lgkmcnt(10)
	v_mfma_f32_16x16x32_bf16 v[44:47], v[140:143], v[144:147], v[44:47]
	v_mfma_f32_16x16x32_bf16 v[40:43], v[140:143], v[148:151], v[40:43]
	v_mfma_f32_16x16x32_bf16 v[36:39], v[140:143], v[160:163], v[36:39]
	v_mfma_f32_16x16x32_bf16 v[32:35], v[140:143], v[164:167], v[32:35]
	s_waitcnt lgkmcnt(9)
	v_mfma_f32_16x16x32_bf16 v[28:31], v[152:155], v[144:147], v[28:31]
	v_mfma_f32_16x16x32_bf16 v[24:27], v[152:155], v[148:151], v[24:27]
	v_mfma_f32_16x16x32_bf16 v[20:23], v[152:155], v[160:163], v[20:23]
	v_mfma_f32_16x16x32_bf16 v[16:19], v[152:155], v[164:167], v[16:19]
	s_waitcnt lgkmcnt(8)
	v_mfma_f32_16x16x32_bf16 v[12:15], v[156:159], v[144:147], v[12:15]
	v_mfma_f32_16x16x32_bf16 v[8:11], v[156:159], v[148:151], v[8:11]
	v_mfma_f32_16x16x32_bf16 v[4:7], v[156:159], v[160:163], v[4:7]
	v_mfma_f32_16x16x32_bf16 v[0:3], v[156:159], v[164:167], v[0:3]
	s_waitcnt lgkmcnt(3)
	v_mfma_f32_16x16x32_bf16 v[60:63], v[204:207], v[208:211], v[60:63]
	v_mfma_f32_16x16x32_bf16 v[56:59], v[204:207], v[212:215], v[56:59]
	v_mfma_f32_16x16x32_bf16 v[52:55], v[204:207], v[216:219], v[52:55]
	v_mfma_f32_16x16x32_bf16 v[48:51], v[204:207], v[220:223], v[48:51]
	s_waitcnt lgkmcnt(2)
	v_mfma_f32_16x16x32_bf16 v[44:47], v[224:227], v[208:211], v[44:47]
	v_mfma_f32_16x16x32_bf16 v[40:43], v[224:227], v[212:215], v[40:43]
	v_mfma_f32_16x16x32_bf16 v[36:39], v[224:227], v[216:219], v[36:39]
	v_mfma_f32_16x16x32_bf16 v[32:35], v[224:227], v[220:223], v[32:35]
	s_waitcnt lgkmcnt(1)
	v_mfma_f32_16x16x32_bf16 v[28:31], v[228:231], v[208:211], v[28:31]
	v_mfma_f32_16x16x32_bf16 v[24:27], v[228:231], v[212:215], v[24:27]
	v_mfma_f32_16x16x32_bf16 v[20:23], v[228:231], v[216:219], v[20:23]
	v_mfma_f32_16x16x32_bf16 v[16:19], v[228:231], v[220:223], v[16:19]
	s_waitcnt lgkmcnt(0)
	v_mfma_f32_16x16x32_bf16 v[12:15], v[232:235], v[208:211], v[12:15]
	v_mfma_f32_16x16x32_bf16 v[8:11], v[232:235], v[212:215], v[8:11]
	v_mfma_f32_16x16x32_bf16 v[4:7], v[232:235], v[216:219], v[4:7]
	v_mfma_f32_16x16x32_bf16 v[0:3], v[232:235], v[220:223], v[0:3]
	s_setprio 2
	s_cmpk_eq_i32 s4, 0x780
	s_waitcnt vmcnt(0)
	s_barrier
	s_cbranch_scc0 .Lxk_3008
.Lxk_exit_3008:
	ds_read_b128 v[90:93], v117 offset:55296
	ds_read_b128 v[94:97], v117 offset:53248
	ds_read_b128 v[98:101], v118 offset:38912
	ds_read_b128 v[102:105], v118 offset:36864
	ds_read_b128 v[136:139], v117 offset:51200
	ds_read_b128 v[140:143], v117 offset:49152
	ds_read_b128 v[144:147], v118 offset:34816
	ds_read_b128 v[148:151], v118 offset:32768
	s_setprio 1
	s_waitcnt lgkmcnt(3)
	v_mfma_f32_16x16x32_bf16 v[24:27], v[102:105], v[136:139], v[24:27]
	v_mfma_f32_16x16x32_bf16 v[20:23], v[102:105], v[94:97], v[20:23]
	v_mfma_f32_16x16x32_bf16 v[16:19], v[102:105], v[90:93], v[16:19]
	s_waitcnt lgkmcnt(0)
	v_mfma_f32_16x16x32_bf16 v[60:63], v[148:151], v[140:143], v[60:63]
	v_mfma_f32_16x16x32_bf16 v[56:59], v[148:151], v[136:139], v[56:59]
	v_mfma_f32_16x16x32_bf16 v[52:55], v[148:151], v[94:97], v[52:55]
	v_mfma_f32_16x16x32_bf16 v[48:51], v[148:151], v[90:93], v[48:51]
	v_mfma_f32_16x16x32_bf16 v[44:47], v[144:147], v[140:143], v[44:47]
	v_mfma_f32_16x16x32_bf16 v[40:43], v[144:147], v[136:139], v[40:43]
	v_mfma_f32_16x16x32_bf16 v[36:39], v[144:147], v[94:97], v[36:39]
	v_mfma_f32_16x16x32_bf16 v[32:35], v[144:147], v[90:93], v[32:35]
	v_mfma_f32_16x16x32_bf16 v[28:31], v[102:105], v[140:143], v[28:31]
	v_mfma_f32_16x16x32_bf16 v[12:15], v[98:101], v[140:143], v[12:15]
	v_mfma_f32_16x16x32_bf16 v[8:11], v[98:101], v[136:139], v[8:11]
	v_mfma_f32_16x16x32_bf16 v[4:7], v[98:101], v[94:97], v[4:7]
	v_mfma_f32_16x16x32_bf16 v[0:3], v[98:101], v[90:93], v[0:3]
	s_setprio 0
	ds_read_b128 v[90:93], v119 offset:32768
	ds_read_b128 v[94:97], v119 offset:34816
	ds_read_b128 v[98:101], v120 offset:49152
	ds_read_b128 v[102:105], v120 offset:51200
	ds_read_b128 v[136:139], v119 offset:36864
	ds_read_b128 v[140:143], v119 offset:38912
	ds_read_b128 v[144:147], v120 offset:53248
	ds_read_b128 v[148:151], v120 offset:55296
	s_setprio 1
	s_waitcnt lgkmcnt(3)
	v_mfma_f32_16x16x32_bf16 v[24:27], v[136:139], v[102:105], v[24:27]
	s_waitcnt lgkmcnt(1)
	v_mfma_f32_16x16x32_bf16 v[20:23], v[136:139], v[144:147], v[20:23]
	s_waitcnt lgkmcnt(0)
	v_mfma_f32_16x16x32_bf16 v[16:19], v[136:139], v[148:151], v[16:19]
	v_mfma_f32_16x16x32_bf16 v[60:63], v[90:93], v[98:101], v[60:63]
	v_mfma_f32_16x16x32_bf16 v[56:59], v[90:93], v[102:105], v[56:59]
	v_mfma_f32_16x16x32_bf16 v[52:55], v[90:93], v[144:147], v[52:55]
	v_mfma_f32_16x16x32_bf16 v[48:51], v[90:93], v[148:151], v[48:51]
	v_mfma_f32_16x16x32_bf16 v[44:47], v[94:97], v[98:101], v[44:47]
	v_mfma_f32_16x16x32_bf16 v[40:43], v[94:97], v[102:105], v[40:43]
	v_mfma_f32_16x16x32_bf16 v[36:39], v[94:97], v[144:147], v[36:39]
	v_mfma_f32_16x16x32_bf16 v[32:35], v[94:97], v[148:151], v[32:35]
	v_mfma_f32_16x16x32_bf16 v[28:31], v[136:139], v[98:101], v[28:31]
	v_mfma_f32_16x16x32_bf16 v[12:15], v[140:143], v[98:101], v[12:15]
	v_mfma_f32_16x16x32_bf16 v[8:11], v[140:143], v[102:105], v[8:11]
	v_mfma_f32_16x16x32_bf16 v[4:7], v[140:143], v[144:147], v[4:7]
	v_mfma_f32_16x16x32_bf16 v[0:3], v[140:143], v[148:151], v[0:3]
	s_setprio 0
	s_barrier
	ds_write2_b32 v121, v60, v56 offset1:16
	ds_write2_b32 v121, v61, v57 offset0:132 offset1:148
	v_add_u32_e32 v56, 0x400, v121
	ds_write2_b32 v56, v62, v58 offset0:8 offset1:24
	ds_write2_b32 v56, v63, v59 offset0:140 offset1:156
	ds_write2_b32 v121, v52, v48 offset0:32 offset1:48
	ds_write2_b32 v121, v53, v49 offset0:164 offset1:180
	ds_write2_b32 v56, v54, v50 offset0:40 offset1:56
	ds_write2_b32 v56, v55, v51 offset0:172 offset1:188
	v_add_u32_e32 v48, 0x2000, v121
	ds_write2_b32 v48, v44, v40 offset0:64 offset1:80
	ds_write2_b32 v48, v45, v41 offset0:196 offset1:212
	v_add_u32_e32 v40, 0x2400, v121
	ds_write2_b32 v40, v46, v42 offset0:72 offset1:88
	ds_write2_b32 v40, v47, v43 offset0:204 offset1:220
	ds_write2_b32 v48, v36, v32 offset0:96 offset1:112
	ds_write2_b32 v48, v37, v33 offset0:228 offset1:244
	ds_write2_b32 v40, v38, v34 offset0:104 offset1:120
	ds_write2_b32 v40, v39, v35 offset0:236 offset1:252
	v_add_u32_e32 v32, 0x4000, v121
	ds_write2_b32 v32, v28, v24 offset0:128 offset1:144
	v_add_u32_e32 v24, 0x4400, v121
	ds_write2_b32 v24, v29, v25 offset0:4 offset1:20
	ds_write2_b32 v24, v30, v26 offset0:136 offset1:152
	v_add_u32_e32 v25, 0x4800, v121
	ds_write2_b32 v25, v31, v27 offset0:12 offset1:28
	ds_write2_b32 v32, v20, v16 offset0:160 offset1:176
	ds_write2_b32 v24, v21, v17 offset0:36 offset1:52
	ds_write2_b32 v24, v22, v18 offset0:168 offset1:184
	ds_write2_b32 v25, v23, v19 offset0:44 offset1:60
	v_add_u32_e32 v16, 0x6000, v121
	ds_write2_b32 v16, v12, v8 offset0:192 offset1:208
	v_add_u32_e32 v8, 0x6400, v121
	s_cmpk_gt_u32 s6, 0x3ff
	ds_write2_b32 v8, v13, v9 offset0:68 offset1:84
	ds_write2_b32 v8, v14, v10 offset0:200 offset1:216
	v_add_u32_e32 v9, 0x6800, v121
	v_or_b32_e32 v64, s6, v122
	s_cselect_b64 s[22:23], -1, 0
	s_cmpk_gt_u32 s6, 0x7ff
	ds_write2_b32 v9, v15, v11 offset0:76 offset1:92
	ds_write2_b32 v16, v4, v0 offset0:224 offset1:240
	ds_write2_b32 v8, v5, v1 offset0:100 offset1:116
	ds_write2_b32 v8, v6, v2 offset0:232 offset1:248
	ds_write2_b32 v9, v7, v3 offset0:108 offset1:124
	s_cselect_b64 s[24:25], -1, 0
	s_cmpk_gt_u32 s6, 0xbff
	v_ashrrev_i32_e32 v1, 31, v64
	v_mov_b32_e32 v0, v64
	v_lshlrev_b64 v[2:3], 1, v[64:65]
	v_cmp_lt_i32_e64 s[4:5], s36, v64
	s_cselect_b64 s[26:27], -1, 0
	v_cmp_gt_u32_e64 s[6:7], s37, v64
	v_lshl_add_u64 v[16:17], v[64:65], 2, s[18:19]
	v_lshl_add_u64 v[18:19], s[16:17], 0, v[2:3]
	v_lshl_add_u64 v[20:21], s[14:15], 0, v[2:3]
	v_lshl_add_u64 v[22:23], s[12:13], 0, v[2:3]
	v_lshl_add_u64 v[24:25], v[0:1], 1, s[10:11]
	v_add_u32_e32 v26, v126, v135
	s_mov_b32 s38, 0
	s_waitcnt lgkmcnt(0)
	s_barrier
	s_branch .LBB0_3011

.LBB0_3221:
	s_ashr_i32 s16, s23, 31
	s_lshr_b32 s16, s16, 29
	s_add_i32 s16, s23, s16
	s_ashr_i32 s16, s16, 3
	s_lshr_b32 s17, s16, 4
	s_lshl_b32 s24, s16, 7
	s_lshl_b32 s16, s16, 10
	s_lshl_b32 s25, s23, 7
	s_sub_i32 s25, s25, s16
	v_add_u32_e32 v0, s25, v106
	s_mulk_i32 s17, 0x900
	s_and_b32 s24, s24, 0x780
	v_ashrrev_i32_e32 v1, 31, v0
	v_add_u32_e32 v2, 0x4000, v107
	s_add_i32 s24, s24, s17
	v_lshlrev_b64 v[0:1], 11, v[0:1]
	v_readfirstlane_b32 s26, v2
	s_add_i32 s17, s24, 0x100
	v_lshl_add_u64 v[0:1], v[66:67], 0, v[0:1]
	s_mov_b32 m0, s26
	v_readfirstlane_b32 s26, v107
	global_load_lds_dwordx4 v[0:1], off
	v_add_u32_e32 v0, s17, v106
	v_ashrrev_i32_e32 v1, 31, v0
	v_lshlrev_b64 v[0:1], 11, v[0:1]
	v_lshl_add_u64 v[0:1], v[72:73], 0, v[0:1]
	s_mov_b32 m0, s26
	v_readfirstlane_b32 s26, v131
	global_load_lds_dwordx4 v[0:1], off
	v_add_u32_e32 v0, s25, v108
	v_ashrrev_i32_e32 v1, 31, v0
	v_lshlrev_b64 v[0:1], 11, v[0:1]
	v_lshl_add_u64 v[0:1], v[68:69], 0, v[0:1]
	s_mov_b32 m0, s26
	v_add_u32_e32 v2, 0x400, v107
	global_load_lds_dwordx4 v[0:1], off
	v_add_u32_e32 v0, s17, v108
	v_ashrrev_i32_e32 v1, 31, v0
	v_lshlrev_b64 v[0:1], 11, v[0:1]
	v_readfirstlane_b32 s26, v2
	v_lshl_add_u64 v[0:1], v[74:75], 0, v[0:1]
	s_mov_b32 m0, s26
	v_readfirstlane_b32 s26, v132
	global_load_lds_dwordx4 v[0:1], off
	v_add_u32_e32 v0, s25, v110
	v_ashrrev_i32_e32 v1, 31, v0
	v_lshlrev_b64 v[0:1], 11, v[0:1]
	v_lshl_add_u64 v[0:1], v[66:67], 0, v[0:1]
	s_mov_b32 m0, s26
	v_add_u32_e32 v2, 0x800, v107
	global_load_lds_dwordx4 v[0:1], off
	v_add_u32_e32 v0, s17, v110
	v_ashrrev_i32_e32 v1, 31, v0
	v_lshlrev_b64 v[0:1], 11, v[0:1]
	v_readfirstlane_b32 s26, v2
	v_lshl_add_u64 v[0:1], v[72:73], 0, v[0:1]
	s_mov_b32 m0, s26
	v_readfirstlane_b32 s26, v133
	global_load_lds_dwordx4 v[0:1], off
	v_add_u32_e32 v0, s25, v112
	v_ashrrev_i32_e32 v1, 31, v0
	v_lshlrev_b64 v[0:1], 11, v[0:1]
	v_lshl_add_u64 v[0:1], v[70:71], 0, v[0:1]
	s_mov_b32 m0, s26
	v_add_u32_e32 v2, 0xc00, v107
	global_load_lds_dwordx4 v[0:1], off
	v_add_u32_e32 v0, s17, v112
	v_ashrrev_i32_e32 v1, 31, v0
	v_lshlrev_b64 v[0:1], 11, v[0:1]
	v_readfirstlane_b32 s17, v2
	v_lshl_add_u64 v[0:1], v[76:77], 0, v[0:1]
	s_mov_b32 m0, s17
	s_mov_b32 s26, 0
	global_load_lds_dwordx4 v[0:1], off
	v_subrev_u32_e32 v0, s16, v122
	v_ashrrev_i32_e32 v1, 31, v0
	v_lshlrev_b64 v[0:1], 11, v[0:1]
	v_lshl_add_u64 v[90:91], v[78:79], 0, v[0:1]
	v_add_u32_e32 v0, s24, v123
	v_ashrrev_i32_e32 v1, 31, v0
	v_lshlrev_b64 v[0:1], 11, v[0:1]
	v_lshl_add_u64 v[92:93], v[80:81], 0, v[0:1]
	v_subrev_u32_e32 v0, s16, v124
	v_ashrrev_i32_e32 v1, 31, v0
	v_lshlrev_b64 v[0:1], 11, v[0:1]
	v_lshl_add_u64 v[94:95], v[82:83], 0, v[0:1]
	v_add_u32_e32 v0, s24, v125
	v_ashrrev_i32_e32 v1, 31, v0
	v_lshlrev_b64 v[0:1], 11, v[0:1]
	v_lshl_add_u64 v[96:97], v[84:85], 0, v[0:1]
	v_subrev_u32_e32 v0, s16, v126
	v_ashrrev_i32_e32 v1, 31, v0
	v_lshlrev_b64 v[0:1], 11, v[0:1]
	v_lshl_add_u64 v[98:99], v[78:79], 0, v[0:1]
	v_add_u32_e32 v0, s24, v127
	v_ashrrev_i32_e32 v1, 31, v0
	v_lshlrev_b64 v[0:1], 11, v[0:1]
	v_lshl_add_u64 v[100:101], v[80:81], 0, v[0:1]
	v_subrev_u32_e32 v0, s16, v64
	v_ashrrev_i32_e32 v1, 31, v0
	v_lshlrev_b64 v[0:1], 11, v[0:1]
	v_lshl_add_u64 v[102:103], v[86:87], 0, v[0:1]
	v_add_u32_e32 v0, s24, v128
	v_ashrrev_i32_e32 v1, 31, v0
	v_lshlrev_b64 v[0:1], 11, v[0:1]
	v_lshl_add_u64 v[104:105], v[88:89], 0, v[0:1]
	s_mov_b64 s[16:17], 0
	v_mov_b32_e32 v0, 0
	v_mov_b32_e32 v1, v65
	v_mov_b32_e32 v2, v65
	v_mov_b32_e32 v3, v65
	v_mov_b32_e32 v4, 0
	v_mov_b32_e32 v5, v65
	v_mov_b32_e32 v6, v65
	v_mov_b32_e32 v7, v65
	v_mov_b32_e32 v8, 0
	v_mov_b32_e32 v9, v65
	v_mov_b32_e32 v10, v65
	v_mov_b32_e32 v11, v65
	v_mov_b32_e32 v12, 0
	v_mov_b32_e32 v13, v65
	v_mov_b32_e32 v14, v65
	v_mov_b32_e32 v15, v65
	v_mov_b32_e32 v16, 0
	v_mov_b32_e32 v17, v65
	v_mov_b32_e32 v18, v65
	v_mov_b32_e32 v19, v65
	v_mov_b32_e32 v20, 0
	v_mov_b32_e32 v21, v65
	v_mov_b32_e32 v22, v65
	v_mov_b32_e32 v23, v65
	s_waitcnt vmcnt(0)
	v_mov_b32_e32 v24, 0
	v_mov_b32_e32 v25, v65
	v_mov_b32_e32 v26, v65
	v_mov_b32_e32 v27, v65
	v_mov_b32_e32 v28, 0
	v_mov_b32_e32 v29, v65
	v_mov_b32_e32 v30, v65
	v_mov_b32_e32 v31, v65
	v_mov_b32_e32 v32, 0
	v_mov_b32_e32 v33, v65
	v_mov_b32_e32 v34, v65
	v_mov_b32_e32 v35, v65
	v_mov_b32_e32 v36, 0
	v_mov_b32_e32 v37, v65
	v_mov_b32_e32 v38, v65
	v_mov_b32_e32 v39, v65
	v_mov_b32_e32 v40, 0
	v_mov_b32_e32 v41, v65
	v_mov_b32_e32 v42, v65
	v_mov_b32_e32 v43, v65
	v_mov_b32_e32 v44, 0
	v_mov_b32_e32 v45, v65
	v_mov_b32_e32 v46, v65
	v_mov_b32_e32 v47, v65
	v_mov_b32_e32 v48, 0
	v_mov_b32_e32 v49, v65
	v_mov_b32_e32 v50, v65
	v_mov_b32_e32 v51, v65
	v_mov_b32_e32 v52, 0
	v_mov_b32_e32 v53, v65
	v_mov_b32_e32 v54, v65
	v_mov_b32_e32 v55, v65
	v_mov_b32_e32 v56, 0
	v_mov_b32_e32 v57, v65
	v_mov_b32_e32 v58, v65
	v_mov_b32_e32 v59, v65
	v_mov_b32_e32 v60, 0
	v_mov_b32_e32 v61, v65
	v_mov_b32_e32 v62, v65
	v_mov_b32_e32 v63, v65
	s_waitcnt lgkmcnt(0)
	s_barrier
	v_add3_u32 v182, 0, v134, v135
	v_add_u32_e32 v183, 0x4000, v182
	s_nop 0
	v_readfirstlane_b32 s82, v183
	v_lshl_add_u32 v183, v109, 1, 0
	s_nop 0
	v_readfirstlane_b32 s83, v182
	v_add3_u32 v183, v183, v135, s19
	s_nop 0
	v_readfirstlane_b32 s84, v183
	v_add_u32_e32 v183, 0x400, v182
	s_nop 0
	v_readfirstlane_b32 s85, v183
	v_lshl_add_u32 v183, v111, 1, 0
	v_add3_u32 v183, v183, v135, s19
	s_nop 0
	v_readfirstlane_b32 s86, v183
	v_add_u32_e32 v183, 0x800, v182
	s_nop 0
	v_readfirstlane_b32 s87, v183
	v_lshl_add_u32 v183, v113, 1, 0
	v_add3_u32 v183, v183, v135, s19
	s_nop 0
	v_readfirstlane_b32 s88, v183
	v_add_u32_e32 v182, 0xc00, v182
	s_nop 0
	v_readfirstlane_b32 s89, v182
	v_subrev_u32_e32 v184, s52, v90
	v_subrev_u32_e32 v185, s52, v92
	v_subrev_u32_e32 v186, s52, v94
	v_subrev_u32_e32 v187, s52, v96
	v_subrev_u32_e32 v188, s52, v98
	v_subrev_u32_e32 v189, s52, v100
	v_subrev_u32_e32 v190, s52, v102
	v_subrev_u32_e32 v191, s52, v104
	s_bitcmp1_b32 s32, 0
	s_cbranch_scc1 .Lxk_3222
.LBB0_3222:
	s_and_b32 s27, s26, 0x4000
	s_xor_b32 s28, s27, 0x4000
	s_lshl_b32 s28, s28, 1
	s_add_i32 s28, s28, 32
	s_add_u32 s90, s52, s16
	s_addc_u32 s91, s53, s17
	s_add_i32 m0, s28, s82
	s_lshl_b32 s27, s27, 1
	global_load_lds_dwordx4 v184, s[90:91]
	s_add_i32 m0, s28, s83
	s_add_i32 s27, s27, 32
	global_load_lds_dwordx4 v185, s[90:91]
	s_add_i32 m0, s28, s84
	v_add3_u32 v139, s27, v114, v136
	global_load_lds_dwordx4 v186, s[90:91]
	s_add_i32 m0, s28, s85
	v_add3_u32 v172, s27, v115, v136
	global_load_lds_dwordx4 v187, s[90:91]
	s_add_i32 m0, s28, s86
	v_add_u32_e32 v160, v139, v137
	global_load_lds_dwordx4 v188, s[90:91]
	s_add_i32 m0, s28, s87
	v_add_u32_e32 v168, v172, v137
	global_load_lds_dwordx4 v189, s[90:91]
	s_add_i32 m0, s28, s88
	s_addk_i32 s26, 0x4000
	global_load_lds_dwordx4 v190, s[90:91]
	s_add_i32 m0, s28, s89
	s_add_u32 s16, s16, 0x80
	s_addc_u32 s17, s17, 0
	global_load_lds_dwordx4 v191, s[90:91]
	ds_read_b128 v[140:143], v160
	ds_read_b128 v[148:151], v168 offset:16384
	ds_read_b128 v[152:155], v168 offset:18432
	ds_read_b128 v[164:167], v168 offset:20480
	ds_read_b128 v[168:171], v168 offset:22528
	ds_read_b128 v[144:147], v160 offset:2048
	ds_read_b128 v[156:159], v160 offset:4096
	ds_read_b128 v[160:163], v160 offset:6144
	v_add_u32_e32 v139, v139, v138
	v_add_u32_e32 v236, v172, v138
	ds_read_b128 v[204:207], v139
	ds_read_b128 v[208:211], v236 offset:16384
	ds_read_b128 v[212:215], v236 offset:18432
	ds_read_b128 v[216:219], v236 offset:20480
	ds_read_b128 v[220:223], v236 offset:22528
	ds_read_b128 v[224:227], v139 offset:2048
	ds_read_b128 v[228:231], v139 offset:4096
	ds_read_b128 v[232:235], v139 offset:6144
	s_setprio 1
	s_waitcnt lgkmcnt(11)
	v_mfma_f32_16x16x32_bf16 v[60:63], v[140:143], v[148:151], v[60:63]
	v_mfma_f32_16x16x32_bf16 v[56:59], v[140:143], v[152:155], v[56:59]
	v_mfma_f32_16x16x32_bf16 v[52:55], v[140:143], v[164:167], v[52:55]
	v_mfma_f32_16x16x32_bf16 v[48:51], v[140:143], v[168:171], v[48:51]
	s_waitcnt lgkmcnt(10)
	v_mfma_f32_16x16x32_bf16 v[44:47], v[144:147], v[148:151], v[44:47]
	v_mfma_f32_16x16x32_bf16 v[40:43], v[144:147], v[152:155], v[40:43]
	v_mfma_f32_16x16x32_bf16 v[36:39], v[144:147], v[164:167], v[36:39]
	v_mfma_f32_16x16x32_bf16 v[32:35], v[144:147], v[168:171], v[32:35]
	s_waitcnt lgkmcnt(9)
	v_mfma_f32_16x16x32_bf16 v[28:31], v[156:159], v[148:151], v[28:31]
	v_mfma_f32_16x16x32_bf16 v[24:27], v[156:159], v[152:155], v[24:27]
	v_mfma_f32_16x16x32_bf16 v[20:23], v[156:159], v[164:167], v[20:23]
	v_mfma_f32_16x16x32_bf16 v[16:19], v[156:159], v[168:171], v[16:19]
	s_waitcnt lgkmcnt(8)
	v_mfma_f32_16x16x32_bf16 v[12:15], v[160:163], v[148:151], v[12:15]
	v_mfma_f32_16x16x32_bf16 v[8:11], v[160:163], v[152:155], v[8:11]
	v_mfma_f32_16x16x32_bf16 v[4:7], v[160:163], v[164:167], v[4:7]
	v_mfma_f32_16x16x32_bf16 v[0:3], v[160:163], v[168:171], v[0:3]
	s_waitcnt lgkmcnt(3)
	v_mfma_f32_16x16x32_bf16 v[60:63], v[204:207], v[208:211], v[60:63]
	v_mfma_f32_16x16x32_bf16 v[56:59], v[204:207], v[212:215], v[56:59]
	v_mfma_f32_16x16x32_bf16 v[52:55], v[204:207], v[216:219], v[52:55]
	v_mfma_f32_16x16x32_bf16 v[48:51], v[204:207], v[220:223], v[48:51]
	s_waitcnt lgkmcnt(2)
	v_mfma_f32_16x16x32_bf16 v[44:47], v[224:227], v[208:211], v[44:47]
	v_mfma_f32_16x16x32_bf16 v[40:43], v[224:227], v[212:215], v[40:43]
	v_mfma_f32_16x16x32_bf16 v[36:39], v[224:227], v[216:219], v[36:39]
	v_mfma_f32_16x16x32_bf16 v[32:35], v[224:227], v[220:223], v[32:35]
	s_waitcnt lgkmcnt(1)
	v_mfma_f32_16x16x32_bf16 v[28:31], v[228:231], v[208:211], v[28:31]
	v_mfma_f32_16x16x32_bf16 v[24:27], v[228:231], v[212:215], v[24:27]
	v_mfma_f32_16x16x32_bf16 v[20:23], v[228:231], v[216:219], v[20:23]
	v_mfma_f32_16x16x32_bf16 v[16:19], v[228:231], v[220:223], v[16:19]
	s_waitcnt lgkmcnt(0)
	v_mfma_f32_16x16x32_bf16 v[12:15], v[232:235], v[208:211], v[12:15]
	v_mfma_f32_16x16x32_bf16 v[8:11], v[232:235], v[212:215], v[8:11]
	v_mfma_f32_16x16x32_bf16 v[4:7], v[232:235], v[216:219], v[4:7]
	v_mfma_f32_16x16x32_bf16 v[0:3], v[232:235], v[220:223], v[0:3]
	s_setprio 0
	s_cmpk_eq_i32 s16, 0x780
	s_waitcnt vmcnt(0)
	s_barrier
	s_cbranch_scc0 .LBB0_3222
	s_branch .Lxk_exit_3222
.Lxk_3222:
	s_and_b32 s27, s26, 0x4000
	s_xor_b32 s28, s27, 0x4000
	s_lshl_b32 s28, s28, 1
	s_add_i32 s28, s28, 32
	s_add_u32 s90, s52, s16
	s_addc_u32 s91, s53, s17
	s_add_i32 m0, s28, s82
	s_lshl_b32 s27, s27, 1
	global_load_lds_dwordx4 v184, s[90:91]
	s_add_i32 m0, s28, s83
	s_add_i32 s27, s27, 32
	global_load_lds_dwordx4 v185, s[90:91]
	s_add_i32 m0, s28, s84
	v_add3_u32 v139, s27, v114, v136
	global_load_lds_dwordx4 v186, s[90:91]
	s_add_i32 m0, s28, s85
	v_add3_u32 v172, s27, v115, v136
	global_load_lds_dwordx4 v187, s[90:91]
	s_add_i32 m0, s28, s86
	v_add_u32_e32 v160, v139, v137
	global_load_lds_dwordx4 v188, s[90:91]
	s_add_i32 m0, s28, s87
	v_add_u32_e32 v168, v172, v137
	global_load_lds_dwordx4 v189, s[90:91]
	s_add_i32 m0, s28, s88
	s_addk_i32 s26, 0x4000
	global_load_lds_dwordx4 v190, s[90:91]
	s_add_i32 m0, s28, s89
	s_add_u32 s16, s16, 0x80
	s_addc_u32 s17, s17, 0
	global_load_lds_dwordx4 v191, s[90:91]
	ds_read_b128 v[140:143], v160
	ds_read_b128 v[148:151], v168 offset:16384
	ds_read_b128 v[152:155], v168 offset:18432
	ds_read_b128 v[164:167], v168 offset:20480
	ds_read_b128 v[168:171], v168 offset:22528
	ds_read_b128 v[144:147], v160 offset:2048
	ds_read_b128 v[156:159], v160 offset:4096
	ds_read_b128 v[160:163], v160 offset:6144
	v_add_u32_e32 v139, v139, v138
	v_add_u32_e32 v236, v172, v138
	ds_read_b128 v[204:207], v139
	ds_read_b128 v[208:211], v236 offset:16384
	ds_read_b128 v[212:215], v236 offset:18432
	ds_read_b128 v[216:219], v236 offset:20480
	ds_read_b128 v[220:223], v236 offset:22528
	ds_read_b128 v[224:227], v139 offset:2048
	ds_read_b128 v[228:231], v139 offset:4096
	ds_read_b128 v[232:235], v139 offset:6144
	s_setprio 3
	s_waitcnt lgkmcnt(11)
	v_mfma_f32_16x16x32_bf16 v[60:63], v[140:143], v[148:151], v[60:63]
	v_mfma_f32_16x16x32_bf16 v[56:59], v[140:143], v[152:155], v[56:59]
	v_mfma_f32_16x16x32_bf16 v[52:55], v[140:143], v[164:167], v[52:55]
	v_mfma_f32_16x16x32_bf16 v[48:51], v[140:143], v[168:171], v[48:51]
	s_waitcnt lgkmcnt(10)
	v_mfma_f32_16x16x32_bf16 v[44:47], v[144:147], v[148:151], v[44:47]
	v_mfma_f32_16x16x32_bf16 v[40:43], v[144:147], v[152:155], v[40:43]
	v_mfma_f32_16x16x32_bf16 v[36:39], v[144:147], v[164:167], v[36:39]
	v_mfma_f32_16x16x32_bf16 v[32:35], v[144:147], v[168:171], v[32:35]
	s_waitcnt lgkmcnt(9)
	v_mfma_f32_16x16x32_bf16 v[28:31], v[156:159], v[148:151], v[28:31]
	v_mfma_f32_16x16x32_bf16 v[24:27], v[156:159], v[152:155], v[24:27]
	v_mfma_f32_16x16x32_bf16 v[20:23], v[156:159], v[164:167], v[20:23]
	v_mfma_f32_16x16x32_bf16 v[16:19], v[156:159], v[168:171], v[16:19]
	s_waitcnt lgkmcnt(8)
	v_mfma_f32_16x16x32_bf16 v[12:15], v[160:163], v[148:151], v[12:15]
	v_mfma_f32_16x16x32_bf16 v[8:11], v[160:163], v[152:155], v[8:11]
	v_mfma_f32_16x16x32_bf16 v[4:7], v[160:163], v[164:167], v[4:7]
	v_mfma_f32_16x16x32_bf16 v[0:3], v[160:163], v[168:171], v[0:3]
	s_waitcnt lgkmcnt(3)
	v_mfma_f32_16x16x32_bf16 v[60:63], v[204:207], v[208:211], v[60:63]
	v_mfma_f32_16x16x32_bf16 v[56:59], v[204:207], v[212:215], v[56:59]
	v_mfma_f32_16x16x32_bf16 v[52:55], v[204:207], v[216:219], v[52:55]
	v_mfma_f32_16x16x32_bf16 v[48:51], v[204:207], v[220:223], v[48:51]
	s_waitcnt lgkmcnt(2)
	v_mfma_f32_16x16x32_bf16 v[44:47], v[224:227], v[208:211], v[44:47]
	v_mfma_f32_16x16x32_bf16 v[40:43], v[224:227], v[212:215], v[40:43]
	v_mfma_f32_16x16x32_bf16 v[36:39], v[224:227], v[216:219], v[36:39]
	v_mfma_f32_16x16x32_bf16 v[32:35], v[224:227], v[220:223], v[32:35]
	s_waitcnt lgkmcnt(1)
	v_mfma_f32_16x16x32_bf16 v[28:31], v[228:231], v[208:211], v[28:31]
	v_mfma_f32_16x16x32_bf16 v[24:27], v[228:231], v[212:215], v[24:27]
	v_mfma_f32_16x16x32_bf16 v[20:23], v[228:231], v[216:219], v[20:23]
	v_mfma_f32_16x16x32_bf16 v[16:19], v[228:231], v[220:223], v[16:19]
	s_waitcnt lgkmcnt(0)
	v_mfma_f32_16x16x32_bf16 v[12:15], v[232:235], v[208:211], v[12:15]
	v_mfma_f32_16x16x32_bf16 v[8:11], v[232:235], v[212:215], v[8:11]
	v_mfma_f32_16x16x32_bf16 v[4:7], v[232:235], v[216:219], v[4:7]
	v_mfma_f32_16x16x32_bf16 v[0:3], v[232:235], v[220:223], v[0:3]
	s_setprio 2
	s_cmpk_eq_i32 s16, 0x780
	s_waitcnt vmcnt(0)
	s_barrier
	s_cbranch_scc0 .Lxk_3222
.Lxk_exit_3222:
	ds_read_b128 v[90:93], v118 offset:55296
	ds_read_b128 v[94:97], v118 offset:53248
	ds_read_b128 v[98:101], v119 offset:38912
	ds_read_b128 v[102:105], v119 offset:36864
	ds_read_b128 v[140:143], v118 offset:51200
	ds_read_b128 v[144:147], v118 offset:49152
	ds_read_b128 v[148:151], v119 offset:34816
	ds_read_b128 v[152:155], v119 offset:32768
	s_setprio 1
	s_waitcnt lgkmcnt(5)
	v_mfma_f32_16x16x32_bf16 v[4:7], v[98:101], v[94:97], v[4:7]
	v_mfma_f32_16x16x32_bf16 v[0:3], v[98:101], v[90:93], v[0:3]
	s_waitcnt lgkmcnt(0)
	v_mfma_f32_16x16x32_bf16 v[60:63], v[152:155], v[144:147], v[60:63]
	v_mfma_f32_16x16x32_bf16 v[56:59], v[152:155], v[140:143], v[56:59]
	v_mfma_f32_16x16x32_bf16 v[52:55], v[152:155], v[94:97], v[52:55]
	v_mfma_f32_16x16x32_bf16 v[48:51], v[152:155], v[90:93], v[48:51]
	v_mfma_f32_16x16x32_bf16 v[44:47], v[148:151], v[144:147], v[44:47]
	v_mfma_f32_16x16x32_bf16 v[40:43], v[148:151], v[140:143], v[40:43]
	v_mfma_f32_16x16x32_bf16 v[36:39], v[148:151], v[94:97], v[36:39]
	v_mfma_f32_16x16x32_bf16 v[32:35], v[148:151], v[90:93], v[32:35]
	v_mfma_f32_16x16x32_bf16 v[28:31], v[102:105], v[144:147], v[28:31]
	v_mfma_f32_16x16x32_bf16 v[24:27], v[102:105], v[140:143], v[24:27]
	v_mfma_f32_16x16x32_bf16 v[20:23], v[102:105], v[94:97], v[20:23]
	v_mfma_f32_16x16x32_bf16 v[16:19], v[102:105], v[90:93], v[16:19]
	v_mfma_f32_16x16x32_bf16 v[12:15], v[98:101], v[144:147], v[12:15]
	v_mfma_f32_16x16x32_bf16 v[8:11], v[98:101], v[140:143], v[8:11]
	s_setprio 0
	ds_read_b128 v[90:93], v120 offset:32768
	ds_read_b128 v[94:97], v120 offset:34816
	ds_read_b128 v[98:101], v121 offset:49152
	ds_read_b128 v[102:105], v121 offset:51200
	ds_read_b128 v[140:143], v120 offset:36864
	ds_read_b128 v[144:147], v120 offset:38912
	ds_read_b128 v[148:151], v121 offset:53248
	ds_read_b128 v[152:155], v121 offset:55296
	s_setprio 1
	s_waitcnt lgkmcnt(1)
	v_mfma_f32_16x16x32_bf16 v[4:7], v[144:147], v[148:151], v[4:7]
	s_waitcnt lgkmcnt(0)
	v_mfma_f32_16x16x32_bf16 v[0:3], v[144:147], v[152:155], v[0:3]
	v_mfma_f32_16x16x32_bf16 v[60:63], v[90:93], v[98:101], v[60:63]
	v_mfma_f32_16x16x32_bf16 v[56:59], v[90:93], v[102:105], v[56:59]
	v_mfma_f32_16x16x32_bf16 v[52:55], v[90:93], v[148:151], v[52:55]
	v_mfma_f32_16x16x32_bf16 v[48:51], v[90:93], v[152:155], v[48:51]
	v_mfma_f32_16x16x32_bf16 v[44:47], v[94:97], v[98:101], v[44:47]
	v_mfma_f32_16x16x32_bf16 v[40:43], v[94:97], v[102:105], v[40:43]
	v_mfma_f32_16x16x32_bf16 v[36:39], v[94:97], v[148:151], v[36:39]
	v_mfma_f32_16x16x32_bf16 v[32:35], v[94:97], v[152:155], v[32:35]
	v_mfma_f32_16x16x32_bf16 v[28:31], v[140:143], v[98:101], v[28:31]
	v_mfma_f32_16x16x32_bf16 v[24:27], v[140:143], v[102:105], v[24:27]
	v_mfma_f32_16x16x32_bf16 v[20:23], v[140:143], v[148:151], v[20:23]
	v_mfma_f32_16x16x32_bf16 v[16:19], v[140:143], v[152:155], v[16:19]
	v_mfma_f32_16x16x32_bf16 v[12:15], v[144:147], v[98:101], v[12:15]
	v_mfma_f32_16x16x32_bf16 v[8:11], v[144:147], v[102:105], v[8:11]
	s_setprio 0
	s_barrier
	ds_write2_b32 v116, v60, v56 offset1:16
	ds_write2_b32 v116, v61, v57 offset0:132 offset1:148
	v_add_u32_e32 v56, 0x400, v116
	ds_write2_b32 v56, v62, v58 offset0:8 offset1:24
	ds_write2_b32 v56, v63, v59 offset0:140 offset1:156
	ds_write2_b32 v116, v52, v48 offset0:32 offset1:48
	ds_write2_b32 v116, v53, v49 offset0:164 offset1:180
	ds_write2_b32 v56, v54, v50 offset0:40 offset1:56
	ds_write2_b32 v56, v55, v51 offset0:172 offset1:188
	v_add_u32_e32 v48, 0x2000, v116
	ds_write2_b32 v48, v44, v40 offset0:64 offset1:80
	ds_write2_b32 v48, v45, v41 offset0:196 offset1:212
	v_add_u32_e32 v40, 0x2400, v116
	ds_write2_b32 v40, v46, v42 offset0:72 offset1:88
	ds_write2_b32 v40, v47, v43 offset0:204 offset1:220
	ds_write2_b32 v48, v36, v32 offset0:96 offset1:112
	ds_write2_b32 v48, v37, v33 offset0:228 offset1:244
	ds_write2_b32 v40, v38, v34 offset0:104 offset1:120
	ds_write2_b32 v40, v39, v35 offset0:236 offset1:252
	v_add_u32_e32 v32, 0x4000, v116
	ds_write2_b32 v32, v28, v24 offset0:128 offset1:144
	v_add_u32_e32 v24, 0x4400, v116
	ds_write2_b32 v24, v29, v25 offset0:4 offset1:20
	ds_write2_b32 v24, v30, v26 offset0:136 offset1:152
	v_add_u32_e32 v25, 0x4800, v116
	ds_write2_b32 v25, v31, v27 offset0:12 offset1:28
	ds_write2_b32 v32, v20, v16 offset0:160 offset1:176
	ds_write2_b32 v24, v21, v17 offset0:36 offset1:52
	ds_write2_b32 v24, v22, v18 offset0:168 offset1:184
	ds_write2_b32 v25, v23, v19 offset0:44 offset1:60
	v_add_u32_e32 v16, 0x6000, v116
	ds_write2_b32 v16, v12, v8 offset0:192 offset1:208
	v_add_u32_e32 v8, 0x6400, v116
	ds_write2_b32 v8, v13, v9 offset0:68 offset1:84
	ds_write2_b32 v8, v14, v10 offset0:200 offset1:216
	v_add_u32_e32 v9, 0x6800, v116
	ds_write2_b32 v9, v15, v11 offset0:76 offset1:92
	ds_write2_b32 v16, v4, v0 offset0:224 offset1:240
	ds_write2_b32 v8, v5, v1 offset0:100 offset1:116
	ds_write2_b32 v8, v6, v2 offset0:232 offset1:248
	ds_write2_b32 v9, v7, v3 offset0:108 offset1:124
	v_or_b32_e32 v0, s25, v117
	v_ashrrev_i32_e32 v1, 31, v0
	v_lshlrev_b64 v[2:3], 2, v[0:1]
	v_lshl_add_u64 v[0:1], s[14:15], 0, v[2:3]
	v_lshl_add_u64 v[2:3], s[6:7], 0, v[2:3]
	v_add_u32_e32 v4, s24, v129
	s_mov_b32 s16, 0
	s_waitcnt lgkmcnt(0)
	s_barrier

.LBB0_3230:
	s_ashr_i32 s8, s14, 31
	s_lshr_b32 s8, s8, 29
	s_add_i32 s8, s14, s8
	s_ashr_i32 s8, s8, 3
	s_add_i32 s9, s8, s16
	s_lshl_b32 s20, s8, 7
	s_lshl_b32 s8, s8, 10
	s_lshl_b32 s21, s14, 7
	s_sub_i32 s21, s21, s8
	s_lshr_b32 s9, s9, 4
	v_add_u32_e32 v0, s21, v104
	s_mulk_i32 s9, 0x900
	s_and_b32 s20, s20, 0x780
	v_ashrrev_i32_e32 v1, 31, v0
	v_add_u32_e32 v2, 0x4000, v105
	s_add_i32 s20, s20, s9
	v_lshlrev_b64 v[0:1], 11, v[0:1]
	v_readfirstlane_b32 s22, v2
	s_add_i32 s9, s20, 0x100
	v_lshl_add_u64 v[0:1], v[64:65], 0, v[0:1]
	s_mov_b32 m0, s22
	v_readfirstlane_b32 s22, v105
	global_load_lds_dwordx4 v[0:1], off
	v_add_u32_e32 v0, s9, v104
	v_ashrrev_i32_e32 v1, 31, v0
	v_lshlrev_b64 v[0:1], 11, v[0:1]
	v_lshl_add_u64 v[0:1], v[70:71], 0, v[0:1]
	s_mov_b32 m0, s22
	v_readfirstlane_b32 s22, v130
	global_load_lds_dwordx4 v[0:1], off
	v_add_u32_e32 v0, s21, v106
	v_ashrrev_i32_e32 v1, 31, v0
	v_lshlrev_b64 v[0:1], 11, v[0:1]
	v_lshl_add_u64 v[0:1], v[66:67], 0, v[0:1]
	s_mov_b32 m0, s22
	v_add_u32_e32 v2, 0x400, v105
	global_load_lds_dwordx4 v[0:1], off
	v_add_u32_e32 v0, s9, v106
	v_ashrrev_i32_e32 v1, 31, v0
	v_lshlrev_b64 v[0:1], 11, v[0:1]
	v_readfirstlane_b32 s22, v2
	v_lshl_add_u64 v[0:1], v[72:73], 0, v[0:1]
	s_mov_b32 m0, s22
	v_readfirstlane_b32 s22, v131
	global_load_lds_dwordx4 v[0:1], off
	v_add_u32_e32 v0, s21, v108
	v_ashrrev_i32_e32 v1, 31, v0
	v_lshlrev_b64 v[0:1], 11, v[0:1]
	v_lshl_add_u64 v[0:1], v[64:65], 0, v[0:1]
	s_mov_b32 m0, s22
	v_add_u32_e32 v2, 0x800, v105
	global_load_lds_dwordx4 v[0:1], off
	v_add_u32_e32 v0, s9, v108
	v_ashrrev_i32_e32 v1, 31, v0
	v_lshlrev_b64 v[0:1], 11, v[0:1]
	v_readfirstlane_b32 s22, v2
	v_lshl_add_u64 v[0:1], v[70:71], 0, v[0:1]
	s_mov_b32 m0, s22
	v_readfirstlane_b32 s22, v132
	global_load_lds_dwordx4 v[0:1], off
	v_add_u32_e32 v0, s21, v110
	v_ashrrev_i32_e32 v1, 31, v0
	v_lshlrev_b64 v[0:1], 11, v[0:1]
	v_lshl_add_u64 v[0:1], v[68:69], 0, v[0:1]
	s_mov_b32 m0, s22
	v_add_u32_e32 v2, 0xc00, v105
	global_load_lds_dwordx4 v[0:1], off
	v_add_u32_e32 v0, s9, v110
	v_ashrrev_i32_e32 v1, 31, v0
	v_lshlrev_b64 v[0:1], 11, v[0:1]
	v_readfirstlane_b32 s9, v2
	v_lshl_add_u64 v[0:1], v[74:75], 0, v[0:1]
	s_mov_b32 m0, s9
	s_mov_b32 s22, 0
	global_load_lds_dwordx4 v[0:1], off
	v_subrev_u32_e32 v0, s8, v120
	v_ashrrev_i32_e32 v1, 31, v0
	v_lshlrev_b64 v[0:1], 11, v[0:1]
	v_lshl_add_u64 v[88:89], v[76:77], 0, v[0:1]
	v_add_u32_e32 v0, s20, v121
	v_ashrrev_i32_e32 v1, 31, v0
	v_lshlrev_b64 v[0:1], 11, v[0:1]
	v_lshl_add_u64 v[90:91], v[78:79], 0, v[0:1]
	v_subrev_u32_e32 v0, s8, v122
	v_ashrrev_i32_e32 v1, 31, v0
	v_lshlrev_b64 v[0:1], 11, v[0:1]
	v_lshl_add_u64 v[92:93], v[80:81], 0, v[0:1]
	v_add_u32_e32 v0, s20, v123
	v_ashrrev_i32_e32 v1, 31, v0
	v_lshlrev_b64 v[0:1], 11, v[0:1]
	v_lshl_add_u64 v[94:95], v[82:83], 0, v[0:1]
	v_subrev_u32_e32 v0, s8, v124
	v_ashrrev_i32_e32 v1, 31, v0
	v_lshlrev_b64 v[0:1], 11, v[0:1]
	v_lshl_add_u64 v[96:97], v[76:77], 0, v[0:1]
	v_add_u32_e32 v0, s20, v125
	v_ashrrev_i32_e32 v1, 31, v0
	v_lshlrev_b64 v[0:1], 11, v[0:1]
	v_lshl_add_u64 v[98:99], v[78:79], 0, v[0:1]
	v_subrev_u32_e32 v0, s8, v126
	v_ashrrev_i32_e32 v1, 31, v0
	v_lshlrev_b64 v[0:1], 11, v[0:1]
	v_lshl_add_u64 v[100:101], v[84:85], 0, v[0:1]
	v_add_u32_e32 v0, s20, v127
	v_ashrrev_i32_e32 v1, 31, v0
	v_lshlrev_b64 v[0:1], 11, v[0:1]
	v_lshl_add_u64 v[102:103], v[86:87], 0, v[0:1]
	v_mov_b32_e32 v0, 0
	s_mov_b64 s[8:9], 0
	v_mov_b32_e32 v1, v0
	v_mov_b32_e32 v2, v0
	v_mov_b32_e32 v3, v0
	v_mov_b32_e32 v4, v0
	v_mov_b32_e32 v5, v0
	v_mov_b32_e32 v6, v0
	v_mov_b32_e32 v7, v0
	v_mov_b32_e32 v8, v0
	v_mov_b32_e32 v9, v0
	v_mov_b32_e32 v10, v0
	v_mov_b32_e32 v11, v0
	v_mov_b32_e32 v12, v0
	v_mov_b32_e32 v13, v0
	v_mov_b32_e32 v14, v0
	v_mov_b32_e32 v15, v0
	v_mov_b32_e32 v16, v0
	v_mov_b32_e32 v17, v0
	v_mov_b32_e32 v18, v0
	v_mov_b32_e32 v19, v0
	v_mov_b32_e32 v20, v0
	v_mov_b32_e32 v21, v0
	v_mov_b32_e32 v22, v0
	v_mov_b32_e32 v23, v0
	v_mov_b32_e32 v24, v0
	v_mov_b32_e32 v25, v0
	v_mov_b32_e32 v26, v0
	v_mov_b32_e32 v27, v0
	s_waitcnt vmcnt(0)
	v_mov_b32_e32 v28, v0
	v_mov_b32_e32 v29, v0
	v_mov_b32_e32 v30, v0
	v_mov_b32_e32 v31, v0
	v_mov_b32_e32 v32, v0
	v_mov_b32_e32 v33, v0
	v_mov_b32_e32 v34, v0
	v_mov_b32_e32 v35, v0
	v_mov_b32_e32 v36, v0
	v_mov_b32_e32 v37, v0
	v_mov_b32_e32 v38, v0
	v_mov_b32_e32 v39, v0
	v_mov_b32_e32 v40, v0
	v_mov_b32_e32 v41, v0
	v_mov_b32_e32 v42, v0
	v_mov_b32_e32 v43, v0
	v_mov_b32_e32 v44, v0
	v_mov_b32_e32 v45, v0
	v_mov_b32_e32 v46, v0
	v_mov_b32_e32 v47, v0
	v_mov_b32_e32 v48, v0
	v_mov_b32_e32 v49, v0
	v_mov_b32_e32 v50, v0
	v_mov_b32_e32 v51, v0
	v_mov_b32_e32 v52, v0
	v_mov_b32_e32 v53, v0
	v_mov_b32_e32 v54, v0
	v_mov_b32_e32 v55, v0
	v_mov_b32_e32 v56, v0
	v_mov_b32_e32 v57, v0
	v_mov_b32_e32 v58, v0
	v_mov_b32_e32 v59, v0
	v_mov_b32_e32 v60, v0
	v_mov_b32_e32 v61, v0
	v_mov_b32_e32 v62, v0
	v_mov_b32_e32 v63, v0
	s_waitcnt lgkmcnt(0)
	s_barrier
	v_add3_u32 v182, 0, v133, v134
	v_add_u32_e32 v183, 0x4000, v182
	s_nop 0
	v_readfirstlane_b32 s82, v183
	v_lshl_add_u32 v183, v107, 1, 0
	s_nop 0
	v_readfirstlane_b32 s83, v182
	v_add3_u32 v183, v183, v134, s13
	s_nop 0
	v_readfirstlane_b32 s84, v183
	v_add_u32_e32 v183, 0x400, v182
	s_nop 0
	v_readfirstlane_b32 s85, v183
	v_lshl_add_u32 v183, v109, 1, 0
	v_add3_u32 v183, v183, v134, s13
	s_nop 0
	v_readfirstlane_b32 s86, v183
	v_add_u32_e32 v183, 0x800, v182
	s_nop 0
	v_readfirstlane_b32 s87, v183
	v_lshl_add_u32 v183, v111, 1, 0
	v_add3_u32 v183, v183, v134, s13
	s_nop 0
	v_readfirstlane_b32 s88, v183
	v_add_u32_e32 v182, 0xc00, v182
	s_nop 0
	v_readfirstlane_b32 s89, v182
	v_subrev_u32_e32 v184, s52, v88
	v_subrev_u32_e32 v185, s52, v90
	v_subrev_u32_e32 v186, s52, v92
	v_subrev_u32_e32 v187, s52, v94
	v_subrev_u32_e32 v188, s52, v96
	v_subrev_u32_e32 v189, s52, v98
	v_subrev_u32_e32 v190, s52, v100
	v_subrev_u32_e32 v191, s52, v102
	s_bitcmp1_b32 s32, 0
	s_cbranch_scc1 .Lxk_3231
.LBB0_3231:
	s_and_b32 s23, s22, 0x4000
	s_xor_b32 s24, s23, 0x4000
	s_lshl_b32 s24, s24, 1
	s_add_i32 s24, s24, 32
	s_add_u32 s90, s52, s8
	s_addc_u32 s91, s53, s9
	s_add_i32 m0, s24, s82
	s_lshl_b32 s23, s23, 1
	global_load_lds_dwordx4 v184, s[90:91]
	s_add_i32 m0, s24, s83
	s_add_i32 s23, s23, 32
	global_load_lds_dwordx4 v185, s[90:91]
	s_add_i32 m0, s24, s84
	v_add3_u32 v170, s23, v112, v135
	global_load_lds_dwordx4 v186, s[90:91]
	s_add_i32 m0, s24, s85
	v_add3_u32 v171, s23, v113, v135
	global_load_lds_dwordx4 v187, s[90:91]
	s_add_i32 m0, s24, s86
	v_add_u32_e32 v158, v170, v136
	global_load_lds_dwordx4 v188, s[90:91]
	s_add_i32 m0, s24, s87
	v_add_u32_e32 v166, v171, v136
	global_load_lds_dwordx4 v189, s[90:91]
	s_add_i32 m0, s24, s88
	s_addk_i32 s22, 0x4000
	global_load_lds_dwordx4 v190, s[90:91]
	s_add_i32 m0, s24, s89
	s_add_u32 s8, s8, 0x80
	s_addc_u32 s9, s9, 0
	global_load_lds_dwordx4 v191, s[90:91]
	ds_read_b128 v[138:141], v158
	ds_read_b128 v[146:149], v166 offset:16384
	ds_read_b128 v[150:153], v166 offset:18432
	ds_read_b128 v[162:165], v166 offset:20480
	ds_read_b128 v[166:169], v166 offset:22528
	ds_read_b128 v[142:145], v158 offset:2048
	ds_read_b128 v[154:157], v158 offset:4096
	ds_read_b128 v[158:161], v158 offset:6144
	v_add_u32_e32 v236, v170, v137
	v_add_u32_e32 v237, v171, v137
	ds_read_b128 v[204:207], v236
	ds_read_b128 v[208:211], v237 offset:16384
	ds_read_b128 v[212:215], v237 offset:18432
	ds_read_b128 v[216:219], v237 offset:20480
	ds_read_b128 v[220:223], v237 offset:22528
	ds_read_b128 v[224:227], v236 offset:2048
	ds_read_b128 v[228:231], v236 offset:4096
	ds_read_b128 v[232:235], v236 offset:6144
	s_setprio 1
	s_waitcnt lgkmcnt(11)
	v_mfma_f32_16x16x32_bf16 v[60:63], v[138:141], v[146:149], v[60:63]
	v_mfma_f32_16x16x32_bf16 v[56:59], v[138:141], v[150:153], v[56:59]
	v_mfma_f32_16x16x32_bf16 v[52:55], v[138:141], v[162:165], v[52:55]
	v_mfma_f32_16x16x32_bf16 v[48:51], v[138:141], v[166:169], v[48:51]
	s_waitcnt lgkmcnt(10)
	v_mfma_f32_16x16x32_bf16 v[44:47], v[142:145], v[146:149], v[44:47]
	v_mfma_f32_16x16x32_bf16 v[40:43], v[142:145], v[150:153], v[40:43]
	v_mfma_f32_16x16x32_bf16 v[36:39], v[142:145], v[162:165], v[36:39]
	v_mfma_f32_16x16x32_bf16 v[32:35], v[142:145], v[166:169], v[32:35]
	s_waitcnt lgkmcnt(9)
	v_mfma_f32_16x16x32_bf16 v[28:31], v[154:157], v[146:149], v[28:31]
	v_mfma_f32_16x16x32_bf16 v[24:27], v[154:157], v[150:153], v[24:27]
	v_mfma_f32_16x16x32_bf16 v[20:23], v[154:157], v[162:165], v[20:23]
	v_mfma_f32_16x16x32_bf16 v[16:19], v[154:157], v[166:169], v[16:19]
	s_waitcnt lgkmcnt(8)
	v_mfma_f32_16x16x32_bf16 v[12:15], v[158:161], v[146:149], v[12:15]
	v_mfma_f32_16x16x32_bf16 v[8:11], v[158:161], v[150:153], v[8:11]
	v_mfma_f32_16x16x32_bf16 v[4:7], v[158:161], v[162:165], v[4:7]
	v_mfma_f32_16x16x32_bf16 v[0:3], v[158:161], v[166:169], v[0:3]
	s_waitcnt lgkmcnt(3)
	v_mfma_f32_16x16x32_bf16 v[60:63], v[204:207], v[208:211], v[60:63]
	v_mfma_f32_16x16x32_bf16 v[56:59], v[204:207], v[212:215], v[56:59]
	v_mfma_f32_16x16x32_bf16 v[52:55], v[204:207], v[216:219], v[52:55]
	v_mfma_f32_16x16x32_bf16 v[48:51], v[204:207], v[220:223], v[48:51]
	s_waitcnt lgkmcnt(2)
	v_mfma_f32_16x16x32_bf16 v[44:47], v[224:227], v[208:211], v[44:47]
	v_mfma_f32_16x16x32_bf16 v[40:43], v[224:227], v[212:215], v[40:43]
	v_mfma_f32_16x16x32_bf16 v[36:39], v[224:227], v[216:219], v[36:39]
	v_mfma_f32_16x16x32_bf16 v[32:35], v[224:227], v[220:223], v[32:35]
	s_waitcnt lgkmcnt(1)
	v_mfma_f32_16x16x32_bf16 v[28:31], v[228:231], v[208:211], v[28:31]
	v_mfma_f32_16x16x32_bf16 v[24:27], v[228:231], v[212:215], v[24:27]
	v_mfma_f32_16x16x32_bf16 v[20:23], v[228:231], v[216:219], v[20:23]
	v_mfma_f32_16x16x32_bf16 v[16:19], v[228:231], v[220:223], v[16:19]
	s_waitcnt lgkmcnt(0)
	v_mfma_f32_16x16x32_bf16 v[12:15], v[232:235], v[208:211], v[12:15]
	v_mfma_f32_16x16x32_bf16 v[8:11], v[232:235], v[212:215], v[8:11]
	v_mfma_f32_16x16x32_bf16 v[4:7], v[232:235], v[216:219], v[4:7]
	v_mfma_f32_16x16x32_bf16 v[0:3], v[232:235], v[220:223], v[0:3]
	s_setprio 0
	s_cmpk_eq_i32 s8, 0x780
	s_waitcnt vmcnt(0)
	s_barrier
	s_cbranch_scc0 .LBB0_3231
	s_branch .Lxk_exit_3231
.Lxk_3231:
	s_and_b32 s23, s22, 0x4000
	s_xor_b32 s24, s23, 0x4000
	s_lshl_b32 s24, s24, 1
	s_add_i32 s24, s24, 32
	s_add_u32 s90, s52, s8
	s_addc_u32 s91, s53, s9
	s_add_i32 m0, s24, s82
	s_lshl_b32 s23, s23, 1
	global_load_lds_dwordx4 v184, s[90:91]
	s_add_i32 m0, s24, s83
	s_add_i32 s23, s23, 32
	global_load_lds_dwordx4 v185, s[90:91]
	s_add_i32 m0, s24, s84
	v_add3_u32 v170, s23, v112, v135
	global_load_lds_dwordx4 v186, s[90:91]
	s_add_i32 m0, s24, s85
	v_add3_u32 v171, s23, v113, v135
	global_load_lds_dwordx4 v187, s[90:91]
	s_add_i32 m0, s24, s86
	v_add_u32_e32 v158, v170, v136
	global_load_lds_dwordx4 v188, s[90:91]
	s_add_i32 m0, s24, s87
	v_add_u32_e32 v166, v171, v136
	global_load_lds_dwordx4 v189, s[90:91]
	s_add_i32 m0, s24, s88
	s_addk_i32 s22, 0x4000
	global_load_lds_dwordx4 v190, s[90:91]
	s_add_i32 m0, s24, s89
	s_add_u32 s8, s8, 0x80
	s_addc_u32 s9, s9, 0
	global_load_lds_dwordx4 v191, s[90:91]
	ds_read_b128 v[138:141], v158
	ds_read_b128 v[146:149], v166 offset:16384
	ds_read_b128 v[150:153], v166 offset:18432
	ds_read_b128 v[162:165], v166 offset:20480
	ds_read_b128 v[166:169], v166 offset:22528
	ds_read_b128 v[142:145], v158 offset:2048
	ds_read_b128 v[154:157], v158 offset:4096
	ds_read_b128 v[158:161], v158 offset:6144
	v_add_u32_e32 v236, v170, v137
	v_add_u32_e32 v237, v171, v137
	ds_read_b128 v[204:207], v236
	ds_read_b128 v[208:211], v237 offset:16384
	ds_read_b128 v[212:215], v237 offset:18432
	ds_read_b128 v[216:219], v237 offset:20480
	ds_read_b128 v[220:223], v237 offset:22528
	ds_read_b128 v[224:227], v236 offset:2048
	ds_read_b128 v[228:231], v236 offset:4096
	ds_read_b128 v[232:235], v236 offset:6144
	s_setprio 3
	s_waitcnt lgkmcnt(11)
	v_mfma_f32_16x16x32_bf16 v[60:63], v[138:141], v[146:149], v[60:63]
	v_mfma_f32_16x16x32_bf16 v[56:59], v[138:141], v[150:153], v[56:59]
	v_mfma_f32_16x16x32_bf16 v[52:55], v[138:141], v[162:165], v[52:55]
	v_mfma_f32_16x16x32_bf16 v[48:51], v[138:141], v[166:169], v[48:51]
	s_waitcnt lgkmcnt(10)
	v_mfma_f32_16x16x32_bf16 v[44:47], v[142:145], v[146:149], v[44:47]
	v_mfma_f32_16x16x32_bf16 v[40:43], v[142:145], v[150:153], v[40:43]
	v_mfma_f32_16x16x32_bf16 v[36:39], v[142:145], v[162:165], v[36:39]
	v_mfma_f32_16x16x32_bf16 v[32:35], v[142:145], v[166:169], v[32:35]
	s_waitcnt lgkmcnt(9)
	v_mfma_f32_16x16x32_bf16 v[28:31], v[154:157], v[146:149], v[28:31]
	v_mfma_f32_16x16x32_bf16 v[24:27], v[154:157], v[150:153], v[24:27]
	v_mfma_f32_16x16x32_bf16 v[20:23], v[154:157], v[162:165], v[20:23]
	v_mfma_f32_16x16x32_bf16 v[16:19], v[154:157], v[166:169], v[16:19]
	s_waitcnt lgkmcnt(8)
	v_mfma_f32_16x16x32_bf16 v[12:15], v[158:161], v[146:149], v[12:15]
	v_mfma_f32_16x16x32_bf16 v[8:11], v[158:161], v[150:153], v[8:11]
	v_mfma_f32_16x16x32_bf16 v[4:7], v[158:161], v[162:165], v[4:7]
	v_mfma_f32_16x16x32_bf16 v[0:3], v[158:161], v[166:169], v[0:3]
	s_waitcnt lgkmcnt(3)
	v_mfma_f32_16x16x32_bf16 v[60:63], v[204:207], v[208:211], v[60:63]
	v_mfma_f32_16x16x32_bf16 v[56:59], v[204:207], v[212:215], v[56:59]
	v_mfma_f32_16x16x32_bf16 v[52:55], v[204:207], v[216:219], v[52:55]
	v_mfma_f32_16x16x32_bf16 v[48:51], v[204:207], v[220:223], v[48:51]
	s_waitcnt lgkmcnt(2)
	v_mfma_f32_16x16x32_bf16 v[44:47], v[224:227], v[208:211], v[44:47]
	v_mfma_f32_16x16x32_bf16 v[40:43], v[224:227], v[212:215], v[40:43]
	v_mfma_f32_16x16x32_bf16 v[36:39], v[224:227], v[216:219], v[36:39]
	v_mfma_f32_16x16x32_bf16 v[32:35], v[224:227], v[220:223], v[32:35]
	s_waitcnt lgkmcnt(1)
	v_mfma_f32_16x16x32_bf16 v[28:31], v[228:231], v[208:211], v[28:31]
	v_mfma_f32_16x16x32_bf16 v[24:27], v[228:231], v[212:215], v[24:27]
	v_mfma_f32_16x16x32_bf16 v[20:23], v[228:231], v[216:219], v[20:23]
	v_mfma_f32_16x16x32_bf16 v[16:19], v[228:231], v[220:223], v[16:19]
	s_waitcnt lgkmcnt(0)
	v_mfma_f32_16x16x32_bf16 v[12:15], v[232:235], v[208:211], v[12:15]
	v_mfma_f32_16x16x32_bf16 v[8:11], v[232:235], v[212:215], v[8:11]
	v_mfma_f32_16x16x32_bf16 v[4:7], v[232:235], v[216:219], v[4:7]
	v_mfma_f32_16x16x32_bf16 v[0:3], v[232:235], v[220:223], v[0:3]
	s_setprio 2
	s_cmpk_eq_i32 s8, 0x780
	s_waitcnt vmcnt(0)
	s_barrier
	s_cbranch_scc0 .Lxk_3231
.Lxk_exit_3231:
	ds_read_b128 v[88:91], v116 offset:55296
	ds_read_b128 v[92:95], v116 offset:53248
	ds_read_b128 v[96:99], v117 offset:38912
	ds_read_b128 v[100:103], v117 offset:36864
	ds_read_b128 v[138:141], v116 offset:51200
	ds_read_b128 v[142:145], v116 offset:49152
	ds_read_b128 v[146:149], v117 offset:34816
	ds_read_b128 v[150:153], v117 offset:32768
	s_setprio 1
	s_waitcnt lgkmcnt(5)
	v_mfma_f32_16x16x32_bf16 v[4:7], v[96:99], v[92:95], v[4:7]
	v_mfma_f32_16x16x32_bf16 v[0:3], v[96:99], v[88:91], v[0:3]
	s_waitcnt lgkmcnt(0)
	v_mfma_f32_16x16x32_bf16 v[60:63], v[150:153], v[142:145], v[60:63]
	v_mfma_f32_16x16x32_bf16 v[56:59], v[150:153], v[138:141], v[56:59]
	v_mfma_f32_16x16x32_bf16 v[52:55], v[150:153], v[92:95], v[52:55]
	v_mfma_f32_16x16x32_bf16 v[48:51], v[150:153], v[88:91], v[48:51]
	v_mfma_f32_16x16x32_bf16 v[44:47], v[146:149], v[142:145], v[44:47]
	v_mfma_f32_16x16x32_bf16 v[40:43], v[146:149], v[138:141], v[40:43]
	v_mfma_f32_16x16x32_bf16 v[36:39], v[146:149], v[92:95], v[36:39]
	v_mfma_f32_16x16x32_bf16 v[32:35], v[146:149], v[88:91], v[32:35]
	v_mfma_f32_16x16x32_bf16 v[28:31], v[100:103], v[142:145], v[28:31]
	v_mfma_f32_16x16x32_bf16 v[24:27], v[100:103], v[138:141], v[24:27]
	v_mfma_f32_16x16x32_bf16 v[20:23], v[100:103], v[92:95], v[20:23]
	v_mfma_f32_16x16x32_bf16 v[16:19], v[100:103], v[88:91], v[16:19]
	v_mfma_f32_16x16x32_bf16 v[12:15], v[96:99], v[142:145], v[12:15]
	v_mfma_f32_16x16x32_bf16 v[8:11], v[96:99], v[138:141], v[8:11]
	s_setprio 0
	ds_read_b128 v[88:91], v118 offset:32768
	ds_read_b128 v[92:95], v118 offset:34816
	ds_read_b128 v[96:99], v119 offset:49152
	ds_read_b128 v[100:103], v119 offset:51200
	ds_read_b128 v[138:141], v118 offset:36864
	ds_read_b128 v[142:145], v118 offset:38912
	ds_read_b128 v[146:149], v119 offset:53248
	ds_read_b128 v[150:153], v119 offset:55296
	s_setprio 1
	s_waitcnt lgkmcnt(1)
	v_mfma_f32_16x16x32_bf16 v[4:7], v[142:145], v[146:149], v[4:7]
	s_waitcnt lgkmcnt(0)
	v_mfma_f32_16x16x32_bf16 v[0:3], v[142:145], v[150:153], v[0:3]
	v_mfma_f32_16x16x32_bf16 v[60:63], v[88:91], v[96:99], v[60:63]
	v_mfma_f32_16x16x32_bf16 v[56:59], v[88:91], v[100:103], v[56:59]
	v_mfma_f32_16x16x32_bf16 v[52:55], v[88:91], v[146:149], v[52:55]
	v_mfma_f32_16x16x32_bf16 v[48:51], v[88:91], v[150:153], v[48:51]
	v_mfma_f32_16x16x32_bf16 v[44:47], v[92:95], v[96:99], v[44:47]
	v_mfma_f32_16x16x32_bf16 v[40:43], v[92:95], v[100:103], v[40:43]
	v_mfma_f32_16x16x32_bf16 v[36:39], v[92:95], v[146:149], v[36:39]
	v_mfma_f32_16x16x32_bf16 v[32:35], v[92:95], v[150:153], v[32:35]
	v_mfma_f32_16x16x32_bf16 v[28:31], v[138:141], v[96:99], v[28:31]
	v_mfma_f32_16x16x32_bf16 v[24:27], v[138:141], v[100:103], v[24:27]
	v_mfma_f32_16x16x32_bf16 v[20:23], v[138:141], v[146:149], v[20:23]
	v_mfma_f32_16x16x32_bf16 v[16:19], v[138:141], v[150:153], v[16:19]
	v_mfma_f32_16x16x32_bf16 v[12:15], v[142:145], v[96:99], v[12:15]
	v_mfma_f32_16x16x32_bf16 v[8:11], v[142:145], v[100:103], v[8:11]
	s_setprio 0
	s_barrier
	ds_write2_b32 v114, v60, v56 offset1:16
	ds_write2_b32 v114, v61, v57 offset0:132 offset1:148
	v_add_u32_e32 v56, 0x400, v114
	ds_write2_b32 v56, v62, v58 offset0:8 offset1:24
	ds_write2_b32 v56, v63, v59 offset0:140 offset1:156
	ds_write2_b32 v114, v52, v48 offset0:32 offset1:48
	ds_write2_b32 v114, v53, v49 offset0:164 offset1:180
	ds_write2_b32 v56, v54, v50 offset0:40 offset1:56
	ds_write2_b32 v56, v55, v51 offset0:172 offset1:188
	v_add_u32_e32 v48, 0x2000, v114
	ds_write2_b32 v48, v44, v40 offset0:64 offset1:80
	ds_write2_b32 v48, v45, v41 offset0:196 offset1:212
	v_add_u32_e32 v40, 0x2400, v114
	ds_write2_b32 v40, v46, v42 offset0:72 offset1:88
	ds_write2_b32 v40, v47, v43 offset0:204 offset1:220
	ds_write2_b32 v48, v36, v32 offset0:96 offset1:112
	ds_write2_b32 v48, v37, v33 offset0:228 offset1:244
	ds_write2_b32 v40, v38, v34 offset0:104 offset1:120
	ds_write2_b32 v40, v39, v35 offset0:236 offset1:252
	v_add_u32_e32 v32, 0x4000, v114
	ds_write2_b32 v32, v28, v24 offset0:128 offset1:144
	v_add_u32_e32 v24, 0x4400, v114
	ds_write2_b32 v24, v29, v25 offset0:4 offset1:20
	ds_write2_b32 v24, v30, v26 offset0:136 offset1:152
	v_add_u32_e32 v25, 0x4800, v114
	ds_write2_b32 v25, v31, v27 offset0:12 offset1:28
	ds_write2_b32 v32, v20, v16 offset0:160 offset1:176
	ds_write2_b32 v24, v21, v17 offset0:36 offset1:52
	ds_write2_b32 v24, v22, v18 offset0:168 offset1:184
	ds_write2_b32 v25, v23, v19 offset0:44 offset1:60
	v_add_u32_e32 v16, 0x6000, v114
	ds_write2_b32 v16, v12, v8 offset0:192 offset1:208
	v_add_u32_e32 v8, 0x6400, v114
	ds_write2_b32 v8, v13, v9 offset0:68 offset1:84
	ds_write2_b32 v8, v14, v10 offset0:200 offset1:216
	v_add_u32_e32 v9, 0x6800, v114
	ds_write2_b32 v9, v15, v11 offset0:76 offset1:92
	ds_write2_b32 v16, v4, v0 offset0:224 offset1:240
	ds_write2_b32 v8, v5, v1 offset0:100 offset1:116
	ds_write2_b32 v8, v6, v2 offset0:232 offset1:248
	ds_write2_b32 v9, v7, v3 offset0:108 offset1:124
	v_or_b32_e32 v0, s21, v115
	v_ashrrev_i32_e32 v1, 31, v0
	v_lshlrev_b64 v[2:3], 2, v[0:1]
	v_lshl_add_u64 v[0:1], s[10:11], 0, v[2:3]
	v_lshl_add_u64 v[2:3], s[6:7], 0, v[2:3]
	v_add_u32_e32 v4, s20, v128
	s_mov_b32 s8, 0
	s_waitcnt lgkmcnt(0)
	s_barrier

.LBB0_3387:
	s_ashr_i32 s12, s16, 31
	s_lshr_b32 s12, s12, 27
	s_add_i32 s12, s16, s12
	s_ashr_i32 s12, s12, 5
	s_lshr_b32 s13, s12, 4
	s_lshl_b32 s17, s12, 7
	s_lshl_b32 s12, s12, 12
	s_lshl_b32 s18, s16, 7
	s_sub_i32 s18, s18, s12
	v_add_u32_e32 v0, s18, v106
	s_mulk_i32 s13, 0x900
	s_and_b32 s17, s17, 0x780
	v_ashrrev_i32_e32 v1, 31, v0
	v_add_u32_e32 v2, 0x4000, v107
	s_add_i32 s17, s17, s13
	v_lshlrev_b64 v[0:1], 11, v[0:1]
	v_readfirstlane_b32 s19, v2
	s_add_i32 s13, s17, 0x100
	v_lshl_add_u64 v[0:1], v[66:67], 0, v[0:1]
	s_mov_b32 m0, s19
	v_readfirstlane_b32 s19, v107
	global_load_lds_dwordx4 v[0:1], off
	v_add_u32_e32 v0, s13, v106
	v_ashrrev_i32_e32 v1, 31, v0
	v_lshlrev_b64 v[0:1], 11, v[0:1]
	v_lshl_add_u64 v[0:1], v[72:73], 0, v[0:1]
	s_mov_b32 m0, s19
	v_readfirstlane_b32 s19, v131
	global_load_lds_dwordx4 v[0:1], off
	v_add_u32_e32 v0, s18, v108
	v_ashrrev_i32_e32 v1, 31, v0
	v_lshlrev_b64 v[0:1], 11, v[0:1]
	v_lshl_add_u64 v[0:1], v[68:69], 0, v[0:1]
	s_mov_b32 m0, s19
	v_add_u32_e32 v2, 0x400, v107
	global_load_lds_dwordx4 v[0:1], off
	v_add_u32_e32 v0, s13, v108
	v_ashrrev_i32_e32 v1, 31, v0
	v_lshlrev_b64 v[0:1], 11, v[0:1]
	v_readfirstlane_b32 s19, v2
	v_lshl_add_u64 v[0:1], v[74:75], 0, v[0:1]
	s_mov_b32 m0, s19
	v_readfirstlane_b32 s19, v132
	global_load_lds_dwordx4 v[0:1], off
	v_add_u32_e32 v0, s18, v110
	v_ashrrev_i32_e32 v1, 31, v0
	v_lshlrev_b64 v[0:1], 11, v[0:1]
	v_lshl_add_u64 v[0:1], v[66:67], 0, v[0:1]
	s_mov_b32 m0, s19
	v_add_u32_e32 v2, 0x800, v107
	global_load_lds_dwordx4 v[0:1], off
	v_add_u32_e32 v0, s13, v110
	v_ashrrev_i32_e32 v1, 31, v0
	v_lshlrev_b64 v[0:1], 11, v[0:1]
	v_readfirstlane_b32 s19, v2
	v_lshl_add_u64 v[0:1], v[72:73], 0, v[0:1]
	s_mov_b32 m0, s19
	v_readfirstlane_b32 s19, v133
	global_load_lds_dwordx4 v[0:1], off
	v_add_u32_e32 v0, s18, v112
	v_ashrrev_i32_e32 v1, 31, v0
	v_lshlrev_b64 v[0:1], 11, v[0:1]
	v_lshl_add_u64 v[0:1], v[70:71], 0, v[0:1]
	s_mov_b32 m0, s19
	v_add_u32_e32 v2, 0xc00, v107
	global_load_lds_dwordx4 v[0:1], off
	v_add_u32_e32 v0, s13, v112
	v_ashrrev_i32_e32 v1, 31, v0
	v_lshlrev_b64 v[0:1], 11, v[0:1]
	v_readfirstlane_b32 s13, v2
	v_lshl_add_u64 v[0:1], v[76:77], 0, v[0:1]
	s_mov_b32 m0, s13
	s_mov_b32 s19, 0
	global_load_lds_dwordx4 v[0:1], off
	v_subrev_u32_e32 v0, s12, v122
	v_ashrrev_i32_e32 v1, 31, v0
	v_lshlrev_b64 v[0:1], 11, v[0:1]
	v_lshl_add_u64 v[90:91], v[78:79], 0, v[0:1]
	v_add_u32_e32 v0, s17, v123
	v_ashrrev_i32_e32 v1, 31, v0
	v_lshlrev_b64 v[0:1], 11, v[0:1]
	v_lshl_add_u64 v[92:93], v[80:81], 0, v[0:1]
	v_subrev_u32_e32 v0, s12, v124
	v_ashrrev_i32_e32 v1, 31, v0
	v_lshlrev_b64 v[0:1], 11, v[0:1]
	v_lshl_add_u64 v[94:95], v[82:83], 0, v[0:1]
	v_add_u32_e32 v0, s17, v125
	v_ashrrev_i32_e32 v1, 31, v0
	v_lshlrev_b64 v[0:1], 11, v[0:1]
	v_lshl_add_u64 v[96:97], v[84:85], 0, v[0:1]
	v_subrev_u32_e32 v0, s12, v126
	v_ashrrev_i32_e32 v1, 31, v0
	v_lshlrev_b64 v[0:1], 11, v[0:1]
	v_lshl_add_u64 v[98:99], v[78:79], 0, v[0:1]
	v_add_u32_e32 v0, s17, v127
	v_ashrrev_i32_e32 v1, 31, v0
	v_lshlrev_b64 v[0:1], 11, v[0:1]
	v_lshl_add_u64 v[100:101], v[80:81], 0, v[0:1]
	v_subrev_u32_e32 v0, s12, v64
	v_ashrrev_i32_e32 v1, 31, v0
	v_lshlrev_b64 v[0:1], 11, v[0:1]
	v_lshl_add_u64 v[102:103], v[86:87], 0, v[0:1]
	v_add_u32_e32 v0, s17, v128
	v_ashrrev_i32_e32 v1, 31, v0
	v_lshlrev_b64 v[0:1], 11, v[0:1]
	v_lshl_add_u64 v[104:105], v[88:89], 0, v[0:1]
	s_mov_b64 s[12:13], 0
	v_mov_b32_e32 v0, 0
	v_mov_b32_e32 v1, v65
	v_mov_b32_e32 v2, v65
	v_mov_b32_e32 v3, v65
	v_mov_b32_e32 v4, 0
	v_mov_b32_e32 v5, v65
	v_mov_b32_e32 v6, v65
	v_mov_b32_e32 v7, v65
	v_mov_b32_e32 v8, 0
	v_mov_b32_e32 v9, v65
	v_mov_b32_e32 v10, v65
	v_mov_b32_e32 v11, v65
	v_mov_b32_e32 v12, 0
	v_mov_b32_e32 v13, v65
	v_mov_b32_e32 v14, v65
	v_mov_b32_e32 v15, v65
	v_mov_b32_e32 v16, 0
	v_mov_b32_e32 v17, v65
	v_mov_b32_e32 v18, v65
	v_mov_b32_e32 v19, v65
	v_mov_b32_e32 v20, 0
	v_mov_b32_e32 v21, v65
	v_mov_b32_e32 v22, v65
	v_mov_b32_e32 v23, v65
	v_mov_b32_e32 v24, 0
	v_mov_b32_e32 v25, v65
	v_mov_b32_e32 v26, v65
	v_mov_b32_e32 v27, v65
	v_mov_b32_e32 v28, 0
	v_mov_b32_e32 v29, v65
	v_mov_b32_e32 v30, v65
	v_mov_b32_e32 v31, v65
	v_mov_b32_e32 v32, 0
	v_mov_b32_e32 v33, v65
	v_mov_b32_e32 v34, v65
	v_mov_b32_e32 v35, v65
	v_mov_b32_e32 v36, 0
	v_mov_b32_e32 v37, v65
	v_mov_b32_e32 v38, v65
	v_mov_b32_e32 v39, v65
	v_mov_b32_e32 v40, 0
	v_mov_b32_e32 v41, v65
	v_mov_b32_e32 v42, v65
	v_mov_b32_e32 v43, v65
	v_mov_b32_e32 v44, 0
	v_mov_b32_e32 v45, v65
	v_mov_b32_e32 v46, v65
	v_mov_b32_e32 v47, v65
	v_mov_b32_e32 v48, 0
	v_mov_b32_e32 v49, v65
	v_mov_b32_e32 v50, v65
	v_mov_b32_e32 v51, v65
	v_mov_b32_e32 v52, 0
	v_mov_b32_e32 v53, v65
	v_mov_b32_e32 v54, v65
	v_mov_b32_e32 v55, v65
	v_mov_b32_e32 v56, 0
	v_mov_b32_e32 v57, v65
	v_mov_b32_e32 v58, v65
	v_mov_b32_e32 v59, v65
	v_mov_b32_e32 v60, 0
	v_mov_b32_e32 v61, v65
	v_mov_b32_e32 v62, v65
	v_mov_b32_e32 v63, v65
	s_waitcnt vmcnt(0) lgkmcnt(0)
	s_barrier
	v_add3_u32 v182, 0, v134, v135
	v_add_u32_e32 v183, 0x4000, v182
	s_nop 0
	v_readfirstlane_b32 s82, v183
	v_lshl_add_u32 v183, v109, 1, 0
	s_nop 0
	v_readfirstlane_b32 s83, v182
	v_add3_u32 v183, v183, v135, s15
	s_nop 0
	v_readfirstlane_b32 s84, v183
	v_add_u32_e32 v183, 0x400, v182
	s_nop 0
	v_readfirstlane_b32 s85, v183
	v_lshl_add_u32 v183, v111, 1, 0
	v_add3_u32 v183, v183, v135, s15
	s_nop 0
	v_readfirstlane_b32 s86, v183
	v_add_u32_e32 v183, 0x800, v182
	s_nop 0
	v_readfirstlane_b32 s87, v183
	v_lshl_add_u32 v183, v113, 1, 0
	v_add3_u32 v183, v183, v135, s15
	s_nop 0
	v_readfirstlane_b32 s88, v183
	v_add_u32_e32 v182, 0xc00, v182
	s_nop 0
	v_readfirstlane_b32 s89, v182
	v_subrev_u32_e32 v184, s52, v90
	v_subrev_u32_e32 v185, s52, v92
	v_subrev_u32_e32 v186, s52, v94
	v_subrev_u32_e32 v187, s52, v96
	v_subrev_u32_e32 v188, s52, v98
	v_subrev_u32_e32 v189, s52, v100
	v_subrev_u32_e32 v190, s52, v102
	v_subrev_u32_e32 v191, s52, v104
	s_bitcmp1_b32 s32, 0
	s_cbranch_scc1 .Lxk_3388
.LBB0_3388:
	s_and_b32 s20, s19, 0x4000
	s_xor_b32 s21, s20, 0x4000
	s_lshl_b32 s21, s21, 1
	s_add_i32 s21, s21, 32
	s_add_u32 s90, s52, s12
	s_addc_u32 s91, s53, s13
	s_add_i32 m0, s21, s82
	s_lshl_b32 s20, s20, 1
	global_load_lds_dwordx4 v184, s[90:91]
	s_add_i32 m0, s21, s83
	s_add_i32 s20, s20, 32
	global_load_lds_dwordx4 v185, s[90:91]
	s_add_i32 m0, s21, s84
	v_lshl_add_u32 v170, v114, 1, s20
	global_load_lds_dwordx4 v186, s[90:91]
	s_add_i32 m0, s21, s85
	v_lshl_add_u32 v171, v115, 1, s20
	global_load_lds_dwordx4 v187, s[90:91]
	s_add_i32 m0, s21, s86
	v_add_u32_e32 v158, v170, v136
	global_load_lds_dwordx4 v188, s[90:91]
	s_add_i32 m0, s21, s87
	v_add_u32_e32 v166, v171, v136
	global_load_lds_dwordx4 v189, s[90:91]
	s_add_i32 m0, s21, s88
	s_addk_i32 s19, 0x4000
	global_load_lds_dwordx4 v190, s[90:91]
	s_add_i32 m0, s21, s89
	s_add_u32 s12, s12, 0x80
	s_addc_u32 s13, s13, 0
	global_load_lds_dwordx4 v191, s[90:91]
	ds_read_b128 v[138:141], v158
	ds_read_b128 v[146:149], v166 offset:16384
	ds_read_b128 v[150:153], v166 offset:18432
	ds_read_b128 v[162:165], v166 offset:20480
	ds_read_b128 v[166:169], v166 offset:22528
	ds_read_b128 v[142:145], v158 offset:2048
	ds_read_b128 v[154:157], v158 offset:4096
	ds_read_b128 v[158:161], v158 offset:6144
	v_add_u32_e32 v236, v170, v137
	v_add_u32_e32 v237, v171, v137
	ds_read_b128 v[204:207], v236
	ds_read_b128 v[208:211], v237 offset:16384
	ds_read_b128 v[212:215], v237 offset:18432
	ds_read_b128 v[216:219], v237 offset:20480
	ds_read_b128 v[220:223], v237 offset:22528
	ds_read_b128 v[224:227], v236 offset:2048
	ds_read_b128 v[228:231], v236 offset:4096
	ds_read_b128 v[232:235], v236 offset:6144
	s_setprio 1
	s_waitcnt lgkmcnt(11)
	v_mfma_f32_16x16x32_bf16 v[60:63], v[138:141], v[146:149], v[60:63]
	v_mfma_f32_16x16x32_bf16 v[56:59], v[138:141], v[150:153], v[56:59]
	v_mfma_f32_16x16x32_bf16 v[52:55], v[138:141], v[162:165], v[52:55]
	v_mfma_f32_16x16x32_bf16 v[48:51], v[138:141], v[166:169], v[48:51]
	s_waitcnt lgkmcnt(10)
	v_mfma_f32_16x16x32_bf16 v[44:47], v[142:145], v[146:149], v[44:47]
	v_mfma_f32_16x16x32_bf16 v[40:43], v[142:145], v[150:153], v[40:43]
	v_mfma_f32_16x16x32_bf16 v[36:39], v[142:145], v[162:165], v[36:39]
	v_mfma_f32_16x16x32_bf16 v[32:35], v[142:145], v[166:169], v[32:35]
	s_waitcnt lgkmcnt(9)
	v_mfma_f32_16x16x32_bf16 v[28:31], v[154:157], v[146:149], v[28:31]
	v_mfma_f32_16x16x32_bf16 v[24:27], v[154:157], v[150:153], v[24:27]
	v_mfma_f32_16x16x32_bf16 v[20:23], v[154:157], v[162:165], v[20:23]
	v_mfma_f32_16x16x32_bf16 v[16:19], v[154:157], v[166:169], v[16:19]
	s_waitcnt lgkmcnt(8)
	v_mfma_f32_16x16x32_bf16 v[12:15], v[158:161], v[146:149], v[12:15]
	v_mfma_f32_16x16x32_bf16 v[8:11], v[158:161], v[150:153], v[8:11]
	v_mfma_f32_16x16x32_bf16 v[4:7], v[158:161], v[162:165], v[4:7]
	v_mfma_f32_16x16x32_bf16 v[0:3], v[158:161], v[166:169], v[0:3]
	s_waitcnt lgkmcnt(3)
	v_mfma_f32_16x16x32_bf16 v[60:63], v[204:207], v[208:211], v[60:63]
	v_mfma_f32_16x16x32_bf16 v[56:59], v[204:207], v[212:215], v[56:59]
	v_mfma_f32_16x16x32_bf16 v[52:55], v[204:207], v[216:219], v[52:55]
	v_mfma_f32_16x16x32_bf16 v[48:51], v[204:207], v[220:223], v[48:51]
	s_waitcnt lgkmcnt(2)
	v_mfma_f32_16x16x32_bf16 v[44:47], v[224:227], v[208:211], v[44:47]
	v_mfma_f32_16x16x32_bf16 v[40:43], v[224:227], v[212:215], v[40:43]
	v_mfma_f32_16x16x32_bf16 v[36:39], v[224:227], v[216:219], v[36:39]
	v_mfma_f32_16x16x32_bf16 v[32:35], v[224:227], v[220:223], v[32:35]
	s_waitcnt lgkmcnt(1)
	v_mfma_f32_16x16x32_bf16 v[28:31], v[228:231], v[208:211], v[28:31]
	v_mfma_f32_16x16x32_bf16 v[24:27], v[228:231], v[212:215], v[24:27]
	v_mfma_f32_16x16x32_bf16 v[20:23], v[228:231], v[216:219], v[20:23]
	v_mfma_f32_16x16x32_bf16 v[16:19], v[228:231], v[220:223], v[16:19]
	s_waitcnt lgkmcnt(0)
	v_mfma_f32_16x16x32_bf16 v[12:15], v[232:235], v[208:211], v[12:15]
	v_mfma_f32_16x16x32_bf16 v[8:11], v[232:235], v[212:215], v[8:11]
	v_mfma_f32_16x16x32_bf16 v[4:7], v[232:235], v[216:219], v[4:7]
	v_mfma_f32_16x16x32_bf16 v[0:3], v[232:235], v[220:223], v[0:3]
	s_setprio 0
	s_cmpk_eq_i32 s12, 0x780
	s_waitcnt vmcnt(0)
	s_barrier
	s_cbranch_scc0 .LBB0_3388
	s_branch .Lxk_exit_3388
.Lxk_3388:
	s_and_b32 s20, s19, 0x4000
	s_xor_b32 s21, s20, 0x4000
	s_lshl_b32 s21, s21, 1
	s_add_i32 s21, s21, 32
	s_add_u32 s90, s52, s12
	s_addc_u32 s91, s53, s13
	s_add_i32 m0, s21, s82
	s_lshl_b32 s20, s20, 1
	global_load_lds_dwordx4 v184, s[90:91]
	s_add_i32 m0, s21, s83
	s_add_i32 s20, s20, 32
	global_load_lds_dwordx4 v185, s[90:91]
	s_add_i32 m0, s21, s84
	v_lshl_add_u32 v170, v114, 1, s20
	global_load_lds_dwordx4 v186, s[90:91]
	s_add_i32 m0, s21, s85
	v_lshl_add_u32 v171, v115, 1, s20
	global_load_lds_dwordx4 v187, s[90:91]
	s_add_i32 m0, s21, s86
	v_add_u32_e32 v158, v170, v136
	global_load_lds_dwordx4 v188, s[90:91]
	s_add_i32 m0, s21, s87
	v_add_u32_e32 v166, v171, v136
	global_load_lds_dwordx4 v189, s[90:91]
	s_add_i32 m0, s21, s88
	s_addk_i32 s19, 0x4000
	global_load_lds_dwordx4 v190, s[90:91]
	s_add_i32 m0, s21, s89
	s_add_u32 s12, s12, 0x80
	s_addc_u32 s13, s13, 0
	global_load_lds_dwordx4 v191, s[90:91]
	ds_read_b128 v[138:141], v158
	ds_read_b128 v[146:149], v166 offset:16384
	ds_read_b128 v[150:153], v166 offset:18432
	ds_read_b128 v[162:165], v166 offset:20480
	ds_read_b128 v[166:169], v166 offset:22528
	ds_read_b128 v[142:145], v158 offset:2048
	ds_read_b128 v[154:157], v158 offset:4096
	ds_read_b128 v[158:161], v158 offset:6144
	v_add_u32_e32 v236, v170, v137
	v_add_u32_e32 v237, v171, v137
	ds_read_b128 v[204:207], v236
	ds_read_b128 v[208:211], v237 offset:16384
	ds_read_b128 v[212:215], v237 offset:18432
	ds_read_b128 v[216:219], v237 offset:20480
	ds_read_b128 v[220:223], v237 offset:22528
	ds_read_b128 v[224:227], v236 offset:2048
	ds_read_b128 v[228:231], v236 offset:4096
	ds_read_b128 v[232:235], v236 offset:6144
	s_setprio 3
	s_waitcnt lgkmcnt(11)
	v_mfma_f32_16x16x32_bf16 v[60:63], v[138:141], v[146:149], v[60:63]
	v_mfma_f32_16x16x32_bf16 v[56:59], v[138:141], v[150:153], v[56:59]
	v_mfma_f32_16x16x32_bf16 v[52:55], v[138:141], v[162:165], v[52:55]
	v_mfma_f32_16x16x32_bf16 v[48:51], v[138:141], v[166:169], v[48:51]
	s_waitcnt lgkmcnt(10)
	v_mfma_f32_16x16x32_bf16 v[44:47], v[142:145], v[146:149], v[44:47]
	v_mfma_f32_16x16x32_bf16 v[40:43], v[142:145], v[150:153], v[40:43]
	v_mfma_f32_16x16x32_bf16 v[36:39], v[142:145], v[162:165], v[36:39]
	v_mfma_f32_16x16x32_bf16 v[32:35], v[142:145], v[166:169], v[32:35]
	s_waitcnt lgkmcnt(9)
	v_mfma_f32_16x16x32_bf16 v[28:31], v[154:157], v[146:149], v[28:31]
	v_mfma_f32_16x16x32_bf16 v[24:27], v[154:157], v[150:153], v[24:27]
	v_mfma_f32_16x16x32_bf16 v[20:23], v[154:157], v[162:165], v[20:23]
	v_mfma_f32_16x16x32_bf16 v[16:19], v[154:157], v[166:169], v[16:19]
	s_waitcnt lgkmcnt(8)
	v_mfma_f32_16x16x32_bf16 v[12:15], v[158:161], v[146:149], v[12:15]
	v_mfma_f32_16x16x32_bf16 v[8:11], v[158:161], v[150:153], v[8:11]
	v_mfma_f32_16x16x32_bf16 v[4:7], v[158:161], v[162:165], v[4:7]
	v_mfma_f32_16x16x32_bf16 v[0:3], v[158:161], v[166:169], v[0:3]
	s_waitcnt lgkmcnt(3)
	v_mfma_f32_16x16x32_bf16 v[60:63], v[204:207], v[208:211], v[60:63]
	v_mfma_f32_16x16x32_bf16 v[56:59], v[204:207], v[212:215], v[56:59]
	v_mfma_f32_16x16x32_bf16 v[52:55], v[204:207], v[216:219], v[52:55]
	v_mfma_f32_16x16x32_bf16 v[48:51], v[204:207], v[220:223], v[48:51]
	s_waitcnt lgkmcnt(2)
	v_mfma_f32_16x16x32_bf16 v[44:47], v[224:227], v[208:211], v[44:47]
	v_mfma_f32_16x16x32_bf16 v[40:43], v[224:227], v[212:215], v[40:43]
	v_mfma_f32_16x16x32_bf16 v[36:39], v[224:227], v[216:219], v[36:39]
	v_mfma_f32_16x16x32_bf16 v[32:35], v[224:227], v[220:223], v[32:35]
	s_waitcnt lgkmcnt(1)
	v_mfma_f32_16x16x32_bf16 v[28:31], v[228:231], v[208:211], v[28:31]
	v_mfma_f32_16x16x32_bf16 v[24:27], v[228:231], v[212:215], v[24:27]
	v_mfma_f32_16x16x32_bf16 v[20:23], v[228:231], v[216:219], v[20:23]
	v_mfma_f32_16x16x32_bf16 v[16:19], v[228:231], v[220:223], v[16:19]
	s_waitcnt lgkmcnt(0)
	v_mfma_f32_16x16x32_bf16 v[12:15], v[232:235], v[208:211], v[12:15]
	v_mfma_f32_16x16x32_bf16 v[8:11], v[232:235], v[212:215], v[8:11]
	v_mfma_f32_16x16x32_bf16 v[4:7], v[232:235], v[216:219], v[4:7]
	v_mfma_f32_16x16x32_bf16 v[0:3], v[232:235], v[220:223], v[0:3]
	s_setprio 2
	s_cmpk_eq_i32 s12, 0x780
	s_waitcnt vmcnt(0)
	s_barrier
	s_cbranch_scc0 .Lxk_3388
.Lxk_exit_3388:
	ds_read_b128 v[90:93], v116 offset:55296
	ds_read_b128 v[94:97], v116 offset:53248
	ds_read_b128 v[98:101], v117 offset:38912
	ds_read_b128 v[102:105], v117 offset:36864
	ds_read_b128 v[138:141], v116 offset:51200
	ds_read_b128 v[142:145], v116 offset:49152
	ds_read_b128 v[146:149], v117 offset:34816
	ds_read_b128 v[150:153], v117 offset:32768
	s_setprio 1
	s_waitcnt lgkmcnt(5)
	v_mfma_f32_16x16x32_bf16 v[0:3], v[98:101], v[90:93], v[0:3]
	s_waitcnt lgkmcnt(0)
	v_mfma_f32_16x16x32_bf16 v[60:63], v[150:153], v[142:145], v[60:63]
	v_mfma_f32_16x16x32_bf16 v[56:59], v[150:153], v[138:141], v[56:59]
	v_mfma_f32_16x16x32_bf16 v[52:55], v[150:153], v[94:97], v[52:55]
	v_mfma_f32_16x16x32_bf16 v[48:51], v[150:153], v[90:93], v[48:51]
	v_mfma_f32_16x16x32_bf16 v[44:47], v[146:149], v[142:145], v[44:47]
	v_mfma_f32_16x16x32_bf16 v[40:43], v[146:149], v[138:141], v[40:43]
	v_mfma_f32_16x16x32_bf16 v[36:39], v[146:149], v[94:97], v[36:39]
	v_mfma_f32_16x16x32_bf16 v[32:35], v[146:149], v[90:93], v[32:35]
	v_mfma_f32_16x16x32_bf16 v[28:31], v[102:105], v[142:145], v[28:31]
	v_mfma_f32_16x16x32_bf16 v[24:27], v[102:105], v[138:141], v[24:27]
	v_mfma_f32_16x16x32_bf16 v[20:23], v[102:105], v[94:97], v[20:23]
	v_mfma_f32_16x16x32_bf16 v[16:19], v[102:105], v[90:93], v[16:19]
	v_mfma_f32_16x16x32_bf16 v[12:15], v[98:101], v[142:145], v[12:15]
	v_mfma_f32_16x16x32_bf16 v[8:11], v[98:101], v[138:141], v[8:11]
	v_mfma_f32_16x16x32_bf16 v[4:7], v[98:101], v[94:97], v[4:7]
	s_setprio 0
	ds_read_b128 v[90:93], v118 offset:32768
	ds_read_b128 v[94:97], v118 offset:34816
	ds_read_b128 v[98:101], v119 offset:49152
	ds_read_b128 v[102:105], v119 offset:51200
	ds_read_b128 v[138:141], v118 offset:36864
	ds_read_b128 v[142:145], v118 offset:38912
	ds_read_b128 v[146:149], v119 offset:53248
	ds_read_b128 v[150:153], v119 offset:55296
	s_setprio 1
	s_waitcnt lgkmcnt(0)
	v_mfma_f32_16x16x32_bf16 v[0:3], v[142:145], v[150:153], v[0:3]
	v_mfma_f32_16x16x32_bf16 v[60:63], v[90:93], v[98:101], v[60:63]
	v_mfma_f32_16x16x32_bf16 v[56:59], v[90:93], v[102:105], v[56:59]
	v_mfma_f32_16x16x32_bf16 v[52:55], v[90:93], v[146:149], v[52:55]
	v_mfma_f32_16x16x32_bf16 v[48:51], v[90:93], v[150:153], v[48:51]
	v_mfma_f32_16x16x32_bf16 v[44:47], v[94:97], v[98:101], v[44:47]
	v_mfma_f32_16x16x32_bf16 v[40:43], v[94:97], v[102:105], v[40:43]
	v_mfma_f32_16x16x32_bf16 v[36:39], v[94:97], v[146:149], v[36:39]
	v_mfma_f32_16x16x32_bf16 v[32:35], v[94:97], v[150:153], v[32:35]
	v_mfma_f32_16x16x32_bf16 v[28:31], v[138:141], v[98:101], v[28:31]
	v_mfma_f32_16x16x32_bf16 v[24:27], v[138:141], v[102:105], v[24:27]
	v_mfma_f32_16x16x32_bf16 v[20:23], v[138:141], v[146:149], v[20:23]
	v_mfma_f32_16x16x32_bf16 v[16:19], v[138:141], v[150:153], v[16:19]
	v_mfma_f32_16x16x32_bf16 v[12:15], v[142:145], v[98:101], v[12:15]
	v_mfma_f32_16x16x32_bf16 v[8:11], v[142:145], v[102:105], v[8:11]
	v_mfma_f32_16x16x32_bf16 v[4:7], v[142:145], v[146:149], v[4:7]
	s_setprio 0
	s_barrier
	ds_write2_b32 v120, v60, v56 offset1:16
	ds_write2_b32 v120, v61, v57 offset0:132 offset1:148
	v_add_u32_e32 v56, 0x400, v120
	ds_write2_b32 v56, v62, v58 offset0:8 offset1:24
	ds_write2_b32 v56, v63, v59 offset0:140 offset1:156
	ds_write2_b32 v120, v52, v48 offset0:32 offset1:48
	ds_write2_b32 v120, v53, v49 offset0:164 offset1:180
	ds_write2_b32 v56, v54, v50 offset0:40 offset1:56
	ds_write2_b32 v56, v55, v51 offset0:172 offset1:188
	v_add_u32_e32 v48, 0x2000, v120
	ds_write2_b32 v48, v44, v40 offset0:64 offset1:80
	ds_write2_b32 v48, v45, v41 offset0:196 offset1:212
	v_add_u32_e32 v40, 0x2400, v120
	ds_write2_b32 v40, v46, v42 offset0:72 offset1:88
	ds_write2_b32 v40, v47, v43 offset0:204 offset1:220
	ds_write2_b32 v48, v36, v32 offset0:96 offset1:112
	ds_write2_b32 v48, v37, v33 offset0:228 offset1:244
	ds_write2_b32 v40, v38, v34 offset0:104 offset1:120
	ds_write2_b32 v40, v39, v35 offset0:236 offset1:252
	v_add_u32_e32 v32, 0x4000, v120
	ds_write2_b32 v32, v28, v24 offset0:128 offset1:144
	v_add_u32_e32 v24, 0x4400, v120
	ds_write2_b32 v24, v29, v25 offset0:4 offset1:20
	ds_write2_b32 v24, v30, v26 offset0:136 offset1:152
	v_add_u32_e32 v25, 0x4800, v120
	ds_write2_b32 v25, v31, v27 offset0:12 offset1:28
	ds_write2_b32 v32, v20, v16 offset0:160 offset1:176
	ds_write2_b32 v24, v21, v17 offset0:36 offset1:52
	ds_write2_b32 v24, v22, v18 offset0:168 offset1:184
	ds_write2_b32 v25, v23, v19 offset0:44 offset1:60
	v_add_u32_e32 v16, 0x6000, v120
	ds_write2_b32 v16, v12, v8 offset0:192 offset1:208
	v_add_u32_e32 v8, 0x6400, v120
	ds_write2_b32 v8, v13, v9 offset0:68 offset1:84
	ds_write2_b32 v8, v14, v10 offset0:200 offset1:216
	v_add_u32_e32 v9, 0x6800, v120
	ds_write2_b32 v9, v15, v11 offset0:76 offset1:92
	ds_write2_b32 v16, v4, v0 offset0:224 offset1:240
	ds_write2_b32 v8, v5, v1 offset0:100 offset1:116
	ds_write2_b32 v8, v6, v2 offset0:232 offset1:248
	ds_write2_b32 v9, v7, v3 offset0:108 offset1:124
	v_or_b32_e32 v0, s18, v121
	v_ashrrev_i32_e32 v1, 31, v0
	v_lshl_add_u64 v[0:1], v[0:1], 1, s[6:7]
	v_add_u32_e32 v2, s17, v129
	s_mov_b32 s12, 0
	s_waitcnt lgkmcnt(0)
	s_barrier

.LBB0_3398:
	s_ashr_i32 s15, s9, 31
	s_lshr_b32 s15, s15, 29
	s_add_i32 s15, s9, s15
	s_ashr_i32 s16, s15, 3
	s_lshl_b32 s18, s16, 10
	s_lshl_b32 s9, s9, 7
	s_add_i32 s15, s16, s14
	s_lshl_b32 s17, s16, 7
	s_sub_i32 s16, s9, s18
	s_add_i32 s16, s16, s8
	s_lshr_b32 s15, s15, 4
	v_add_u32_e32 v0, s16, v104
	s_mulk_i32 s15, 0x900
	s_and_b32 s17, s17, 0x780
	v_ashrrev_i32_e32 v1, 31, v0
	v_add_u32_e32 v2, 0x4000, v105
	s_add_i32 s15, s17, s15
	v_lshlrev_b64 v[0:1], 11, v[0:1]
	v_readfirstlane_b32 s19, v2
	s_add_i32 s17, s15, 0x100
	v_lshl_add_u64 v[0:1], v[64:65], 0, v[0:1]
	s_mov_b32 m0, s19
	v_readfirstlane_b32 s19, v105
	global_load_lds_dwordx4 v[0:1], off
	v_add_u32_e32 v0, s17, v104
	v_ashrrev_i32_e32 v1, 31, v0
	v_lshlrev_b64 v[0:1], 11, v[0:1]
	v_lshl_add_u64 v[0:1], v[70:71], 0, v[0:1]
	s_mov_b32 m0, s19
	v_readfirstlane_b32 s19, v129
	global_load_lds_dwordx4 v[0:1], off
	v_add_u32_e32 v0, s16, v106
	v_ashrrev_i32_e32 v1, 31, v0
	v_lshlrev_b64 v[0:1], 11, v[0:1]
	v_lshl_add_u64 v[0:1], v[66:67], 0, v[0:1]
	s_mov_b32 m0, s19
	v_add_u32_e32 v2, 0x400, v105
	global_load_lds_dwordx4 v[0:1], off
	v_add_u32_e32 v0, s17, v106
	v_ashrrev_i32_e32 v1, 31, v0
	v_lshlrev_b64 v[0:1], 11, v[0:1]
	v_readfirstlane_b32 s19, v2
	v_lshl_add_u64 v[0:1], v[72:73], 0, v[0:1]
	s_mov_b32 m0, s19
	v_readfirstlane_b32 s19, v130
	global_load_lds_dwordx4 v[0:1], off
	v_add_u32_e32 v0, s16, v108
	v_ashrrev_i32_e32 v1, 31, v0
	v_lshlrev_b64 v[0:1], 11, v[0:1]
	v_lshl_add_u64 v[0:1], v[64:65], 0, v[0:1]
	s_mov_b32 m0, s19
	v_add_u32_e32 v2, 0x800, v105
	global_load_lds_dwordx4 v[0:1], off
	v_add_u32_e32 v0, s17, v108
	v_ashrrev_i32_e32 v1, 31, v0
	v_lshlrev_b64 v[0:1], 11, v[0:1]
	v_readfirstlane_b32 s19, v2
	v_lshl_add_u64 v[0:1], v[70:71], 0, v[0:1]
	s_mov_b32 m0, s19
	v_readfirstlane_b32 s19, v131
	global_load_lds_dwordx4 v[0:1], off
	v_add_u32_e32 v0, s16, v110
	v_ashrrev_i32_e32 v1, 31, v0
	v_lshlrev_b64 v[0:1], 11, v[0:1]
	v_lshl_add_u64 v[0:1], v[68:69], 0, v[0:1]
	s_mov_b32 m0, s19
	v_add_u32_e32 v2, 0xc00, v105
	global_load_lds_dwordx4 v[0:1], off
	v_add_u32_e32 v0, s17, v110
	v_ashrrev_i32_e32 v1, 31, v0
	v_lshlrev_b64 v[0:1], 11, v[0:1]
	v_readfirstlane_b32 s17, v2
	v_lshl_add_u64 v[0:1], v[74:75], 0, v[0:1]
	s_mov_b32 m0, s17
	s_add_i32 s9, s9, s8
	global_load_lds_dwordx4 v[0:1], off
	v_add_u32_e32 v0, s9, v104
	v_subrev_u32_e32 v0, s18, v0
	v_ashrrev_i32_e32 v1, 31, v0
	v_lshlrev_b64 v[0:1], 11, v[0:1]
	v_lshl_add_u64 v[88:89], v[76:77], 0, v[0:1]
	v_add_u32_e32 v0, s15, v120
	v_ashrrev_i32_e32 v1, 31, v0
	v_lshlrev_b64 v[0:1], 11, v[0:1]
	v_lshl_add_u64 v[90:91], v[78:79], 0, v[0:1]
	v_add_u32_e32 v0, s9, v121
	v_subrev_u32_e32 v0, s18, v0
	v_ashrrev_i32_e32 v1, 31, v0
	v_lshlrev_b64 v[0:1], 11, v[0:1]
	v_lshl_add_u64 v[92:93], v[80:81], 0, v[0:1]
	v_add_u32_e32 v0, s15, v122
	v_ashrrev_i32_e32 v1, 31, v0
	v_lshlrev_b64 v[0:1], 11, v[0:1]
	v_lshl_add_u64 v[94:95], v[82:83], 0, v[0:1]
	v_add_u32_e32 v0, s9, v123
	v_subrev_u32_e32 v0, s18, v0
	v_ashrrev_i32_e32 v1, 31, v0
	v_lshlrev_b64 v[0:1], 11, v[0:1]
	v_lshl_add_u64 v[96:97], v[76:77], 0, v[0:1]
	v_add_u32_e32 v0, s15, v124
	v_ashrrev_i32_e32 v1, 31, v0
	v_lshlrev_b64 v[0:1], 11, v[0:1]
	v_lshl_add_u64 v[98:99], v[78:79], 0, v[0:1]
	v_add_u32_e32 v0, s9, v125
	v_subrev_u32_e32 v0, s18, v0
	v_ashrrev_i32_e32 v1, 31, v0
	v_lshlrev_b64 v[0:1], 11, v[0:1]
	v_lshl_add_u64 v[100:101], v[84:85], 0, v[0:1]
	v_add_u32_e32 v0, s15, v126
	v_ashrrev_i32_e32 v1, 31, v0
	v_lshlrev_b64 v[0:1], 11, v[0:1]
	v_lshl_add_u64 v[102:103], v[86:87], 0, v[0:1]
	v_mov_b32_e32 v0, 0
	s_mov_b32 s17, 0
	s_mov_b64 s[8:9], 0
	v_mov_b32_e32 v1, v0
	v_mov_b32_e32 v2, v0
	v_mov_b32_e32 v3, v0
	v_mov_b32_e32 v4, v0
	v_mov_b32_e32 v5, v0
	v_mov_b32_e32 v6, v0
	v_mov_b32_e32 v7, v0
	v_mov_b32_e32 v8, v0
	v_mov_b32_e32 v9, v0
	v_mov_b32_e32 v10, v0
	v_mov_b32_e32 v11, v0
	v_mov_b32_e32 v12, v0
	v_mov_b32_e32 v13, v0
	v_mov_b32_e32 v14, v0
	v_mov_b32_e32 v15, v0
	v_mov_b32_e32 v16, v0
	v_mov_b32_e32 v17, v0
	v_mov_b32_e32 v18, v0
	v_mov_b32_e32 v19, v0
	v_mov_b32_e32 v20, v0
	v_mov_b32_e32 v21, v0
	v_mov_b32_e32 v22, v0
	v_mov_b32_e32 v23, v0
	v_mov_b32_e32 v24, v0
	v_mov_b32_e32 v25, v0
	v_mov_b32_e32 v26, v0
	v_mov_b32_e32 v27, v0
	v_mov_b32_e32 v28, v0
	v_mov_b32_e32 v29, v0
	v_mov_b32_e32 v30, v0
	v_mov_b32_e32 v31, v0
	v_mov_b32_e32 v32, v0
	v_mov_b32_e32 v33, v0
	v_mov_b32_e32 v34, v0
	v_mov_b32_e32 v35, v0
	v_mov_b32_e32 v36, v0
	v_mov_b32_e32 v37, v0
	v_mov_b32_e32 v38, v0
	v_mov_b32_e32 v39, v0
	v_mov_b32_e32 v40, v0
	v_mov_b32_e32 v41, v0
	v_mov_b32_e32 v42, v0
	v_mov_b32_e32 v43, v0
	v_mov_b32_e32 v44, v0
	v_mov_b32_e32 v45, v0
	v_mov_b32_e32 v46, v0
	v_mov_b32_e32 v47, v0
	v_mov_b32_e32 v48, v0
	v_mov_b32_e32 v49, v0
	v_mov_b32_e32 v50, v0
	v_mov_b32_e32 v51, v0
	v_mov_b32_e32 v52, v0
	v_mov_b32_e32 v53, v0
	v_mov_b32_e32 v54, v0
	v_mov_b32_e32 v55, v0
	v_mov_b32_e32 v56, v0
	v_mov_b32_e32 v57, v0
	v_mov_b32_e32 v58, v0
	v_mov_b32_e32 v59, v0
	v_mov_b32_e32 v60, v0
	v_mov_b32_e32 v61, v0
	v_mov_b32_e32 v62, v0
	v_mov_b32_e32 v63, v0
	s_waitcnt vmcnt(0) lgkmcnt(0)
	s_barrier
	v_add3_u32 v182, 0, v132, v133
	v_add_u32_e32 v183, 0x4000, v182
	s_nop 0
	v_readfirstlane_b32 s82, v183
	v_lshl_add_u32 v183, v107, 1, 0
	s_nop 0
	v_readfirstlane_b32 s83, v182
	v_add3_u32 v183, v183, v133, s11
	s_nop 0
	v_readfirstlane_b32 s84, v183
	v_add_u32_e32 v183, 0x400, v182
	s_nop 0
	v_readfirstlane_b32 s85, v183
	v_lshl_add_u32 v183, v109, 1, 0
	v_add3_u32 v183, v183, v133, s11
	s_nop 0
	v_readfirstlane_b32 s86, v183
	v_add_u32_e32 v183, 0x800, v182
	s_nop 0
	v_readfirstlane_b32 s87, v183
	v_lshl_add_u32 v183, v111, 1, 0
	v_add3_u32 v183, v183, v133, s11
	s_nop 0
	v_readfirstlane_b32 s88, v183
	v_add_u32_e32 v182, 0xc00, v182
	s_nop 0
	v_readfirstlane_b32 s89, v182
	v_subrev_u32_e32 v184, s52, v88
	v_subrev_u32_e32 v185, s52, v90
	v_subrev_u32_e32 v186, s52, v92
	v_subrev_u32_e32 v187, s52, v94
	v_subrev_u32_e32 v188, s52, v96
	v_subrev_u32_e32 v189, s52, v98
	v_subrev_u32_e32 v190, s52, v100
	v_subrev_u32_e32 v191, s52, v102
	s_bitcmp1_b32 s32, 0
	s_cbranch_scc1 .Lxk_3399
.LBB0_3399:
	s_and_b32 s18, s17, 0x4000
	s_xor_b32 s19, s18, 0x4000
	s_lshl_b32 s19, s19, 1
	s_add_i32 s19, s19, 32
	s_add_u32 s90, s52, s8
	s_addc_u32 s91, s53, s9
	s_add_i32 m0, s19, s82
	s_lshl_b32 s18, s18, 1
	global_load_lds_dwordx4 v184, s[90:91]
	s_add_i32 m0, s19, s83
	s_add_i32 s18, s18, 32
	global_load_lds_dwordx4 v185, s[90:91]
	s_add_i32 m0, s19, s84
	v_lshl_add_u32 v168, v112, 1, s18
	global_load_lds_dwordx4 v186, s[90:91]
	s_add_i32 m0, s19, s85
	v_lshl_add_u32 v169, v113, 1, s18
	global_load_lds_dwordx4 v187, s[90:91]
	s_add_i32 m0, s19, s86
	v_add_u32_e32 v156, v168, v134
	global_load_lds_dwordx4 v188, s[90:91]
	s_add_i32 m0, s19, s87
	v_add_u32_e32 v164, v169, v134
	global_load_lds_dwordx4 v189, s[90:91]
	s_add_i32 m0, s19, s88
	s_addk_i32 s17, 0x4000
	global_load_lds_dwordx4 v190, s[90:91]
	s_add_i32 m0, s19, s89
	s_add_u32 s8, s8, 0x80
	s_addc_u32 s9, s9, 0
	global_load_lds_dwordx4 v191, s[90:91]
	ds_read_b128 v[136:139], v156
	ds_read_b128 v[144:147], v164 offset:16384
	ds_read_b128 v[148:151], v164 offset:18432
	ds_read_b128 v[160:163], v164 offset:20480
	ds_read_b128 v[164:167], v164 offset:22528
	ds_read_b128 v[140:143], v156 offset:2048
	ds_read_b128 v[152:155], v156 offset:4096
	ds_read_b128 v[156:159], v156 offset:6144
	v_add_u32_e32 v236, v168, v135
	v_add_u32_e32 v237, v169, v135
	ds_read_b128 v[204:207], v236
	ds_read_b128 v[208:211], v237 offset:16384
	ds_read_b128 v[212:215], v237 offset:18432
	ds_read_b128 v[216:219], v237 offset:20480
	ds_read_b128 v[220:223], v237 offset:22528
	ds_read_b128 v[224:227], v236 offset:2048
	ds_read_b128 v[228:231], v236 offset:4096
	ds_read_b128 v[232:235], v236 offset:6144
	s_setprio 1
	s_waitcnt lgkmcnt(11)
	v_mfma_f32_16x16x32_bf16 v[60:63], v[136:139], v[144:147], v[60:63]
	v_mfma_f32_16x16x32_bf16 v[56:59], v[136:139], v[148:151], v[56:59]
	v_mfma_f32_16x16x32_bf16 v[52:55], v[136:139], v[160:163], v[52:55]
	v_mfma_f32_16x16x32_bf16 v[48:51], v[136:139], v[164:167], v[48:51]
	s_waitcnt lgkmcnt(10)
	v_mfma_f32_16x16x32_bf16 v[44:47], v[140:143], v[144:147], v[44:47]
	v_mfma_f32_16x16x32_bf16 v[40:43], v[140:143], v[148:151], v[40:43]
	v_mfma_f32_16x16x32_bf16 v[36:39], v[140:143], v[160:163], v[36:39]
	v_mfma_f32_16x16x32_bf16 v[32:35], v[140:143], v[164:167], v[32:35]
	s_waitcnt lgkmcnt(9)
	v_mfma_f32_16x16x32_bf16 v[28:31], v[152:155], v[144:147], v[28:31]
	v_mfma_f32_16x16x32_bf16 v[24:27], v[152:155], v[148:151], v[24:27]
	v_mfma_f32_16x16x32_bf16 v[20:23], v[152:155], v[160:163], v[20:23]
	v_mfma_f32_16x16x32_bf16 v[16:19], v[152:155], v[164:167], v[16:19]
	s_waitcnt lgkmcnt(8)
	v_mfma_f32_16x16x32_bf16 v[12:15], v[156:159], v[144:147], v[12:15]
	v_mfma_f32_16x16x32_bf16 v[8:11], v[156:159], v[148:151], v[8:11]
	v_mfma_f32_16x16x32_bf16 v[4:7], v[156:159], v[160:163], v[4:7]
	v_mfma_f32_16x16x32_bf16 v[0:3], v[156:159], v[164:167], v[0:3]
	s_waitcnt lgkmcnt(3)
	v_mfma_f32_16x16x32_bf16 v[60:63], v[204:207], v[208:211], v[60:63]
	v_mfma_f32_16x16x32_bf16 v[56:59], v[204:207], v[212:215], v[56:59]
	v_mfma_f32_16x16x32_bf16 v[52:55], v[204:207], v[216:219], v[52:55]
	v_mfma_f32_16x16x32_bf16 v[48:51], v[204:207], v[220:223], v[48:51]
	s_waitcnt lgkmcnt(2)
	v_mfma_f32_16x16x32_bf16 v[44:47], v[224:227], v[208:211], v[44:47]
	v_mfma_f32_16x16x32_bf16 v[40:43], v[224:227], v[212:215], v[40:43]
	v_mfma_f32_16x16x32_bf16 v[36:39], v[224:227], v[216:219], v[36:39]
	v_mfma_f32_16x16x32_bf16 v[32:35], v[224:227], v[220:223], v[32:35]
	s_waitcnt lgkmcnt(1)
	v_mfma_f32_16x16x32_bf16 v[28:31], v[228:231], v[208:211], v[28:31]
	v_mfma_f32_16x16x32_bf16 v[24:27], v[228:231], v[212:215], v[24:27]
	v_mfma_f32_16x16x32_bf16 v[20:23], v[228:231], v[216:219], v[20:23]
	v_mfma_f32_16x16x32_bf16 v[16:19], v[228:231], v[220:223], v[16:19]
	s_waitcnt lgkmcnt(0)
	v_mfma_f32_16x16x32_bf16 v[12:15], v[232:235], v[208:211], v[12:15]
	v_mfma_f32_16x16x32_bf16 v[8:11], v[232:235], v[212:215], v[8:11]
	v_mfma_f32_16x16x32_bf16 v[4:7], v[232:235], v[216:219], v[4:7]
	v_mfma_f32_16x16x32_bf16 v[0:3], v[232:235], v[220:223], v[0:3]
	s_setprio 0
	s_cmpk_eq_i32 s8, 0x780
	s_waitcnt vmcnt(0)
	s_barrier
	s_cbranch_scc0 .LBB0_3399
	s_branch .Lxk_exit_3399
.Lxk_3399:
	s_and_b32 s18, s17, 0x4000
	s_xor_b32 s19, s18, 0x4000
	s_lshl_b32 s19, s19, 1
	s_add_i32 s19, s19, 32
	s_add_u32 s90, s52, s8
	s_addc_u32 s91, s53, s9
	s_add_i32 m0, s19, s82
	s_lshl_b32 s18, s18, 1
	global_load_lds_dwordx4 v184, s[90:91]
	s_add_i32 m0, s19, s83
	s_add_i32 s18, s18, 32
	global_load_lds_dwordx4 v185, s[90:91]
	s_add_i32 m0, s19, s84
	v_lshl_add_u32 v168, v112, 1, s18
	global_load_lds_dwordx4 v186, s[90:91]
	s_add_i32 m0, s19, s85
	v_lshl_add_u32 v169, v113, 1, s18
	global_load_lds_dwordx4 v187, s[90:91]
	s_add_i32 m0, s19, s86
	v_add_u32_e32 v156, v168, v134
	global_load_lds_dwordx4 v188, s[90:91]
	s_add_i32 m0, s19, s87
	v_add_u32_e32 v164, v169, v134
	global_load_lds_dwordx4 v189, s[90:91]
	s_add_i32 m0, s19, s88
	s_addk_i32 s17, 0x4000
	global_load_lds_dwordx4 v190, s[90:91]
	s_add_i32 m0, s19, s89
	s_add_u32 s8, s8, 0x80
	s_addc_u32 s9, s9, 0
	global_load_lds_dwordx4 v191, s[90:91]
	ds_read_b128 v[136:139], v156
	ds_read_b128 v[144:147], v164 offset:16384
	ds_read_b128 v[148:151], v164 offset:18432
	ds_read_b128 v[160:163], v164 offset:20480
	ds_read_b128 v[164:167], v164 offset:22528
	ds_read_b128 v[140:143], v156 offset:2048
	ds_read_b128 v[152:155], v156 offset:4096
	ds_read_b128 v[156:159], v156 offset:6144
	v_add_u32_e32 v236, v168, v135
	v_add_u32_e32 v237, v169, v135
	ds_read_b128 v[204:207], v236
	ds_read_b128 v[208:211], v237 offset:16384
	ds_read_b128 v[212:215], v237 offset:18432
	ds_read_b128 v[216:219], v237 offset:20480
	ds_read_b128 v[220:223], v237 offset:22528
	ds_read_b128 v[224:227], v236 offset:2048
	ds_read_b128 v[228:231], v236 offset:4096
	ds_read_b128 v[232:235], v236 offset:6144
	s_setprio 3
	s_waitcnt lgkmcnt(11)
	v_mfma_f32_16x16x32_bf16 v[60:63], v[136:139], v[144:147], v[60:63]
	v_mfma_f32_16x16x32_bf16 v[56:59], v[136:139], v[148:151], v[56:59]
	v_mfma_f32_16x16x32_bf16 v[52:55], v[136:139], v[160:163], v[52:55]
	v_mfma_f32_16x16x32_bf16 v[48:51], v[136:139], v[164:167], v[48:51]
	s_waitcnt lgkmcnt(10)
	v_mfma_f32_16x16x32_bf16 v[44:47], v[140:143], v[144:147], v[44:47]
	v_mfma_f32_16x16x32_bf16 v[40:43], v[140:143], v[148:151], v[40:43]
	v_mfma_f32_16x16x32_bf16 v[36:39], v[140:143], v[160:163], v[36:39]
	v_mfma_f32_16x16x32_bf16 v[32:35], v[140:143], v[164:167], v[32:35]
	s_waitcnt lgkmcnt(9)
	v_mfma_f32_16x16x32_bf16 v[28:31], v[152:155], v[144:147], v[28:31]
	v_mfma_f32_16x16x32_bf16 v[24:27], v[152:155], v[148:151], v[24:27]
	v_mfma_f32_16x16x32_bf16 v[20:23], v[152:155], v[160:163], v[20:23]
	v_mfma_f32_16x16x32_bf16 v[16:19], v[152:155], v[164:167], v[16:19]
	s_waitcnt lgkmcnt(8)
	v_mfma_f32_16x16x32_bf16 v[12:15], v[156:159], v[144:147], v[12:15]
	v_mfma_f32_16x16x32_bf16 v[8:11], v[156:159], v[148:151], v[8:11]
	v_mfma_f32_16x16x32_bf16 v[4:7], v[156:159], v[160:163], v[4:7]
	v_mfma_f32_16x16x32_bf16 v[0:3], v[156:159], v[164:167], v[0:3]
	s_waitcnt lgkmcnt(3)
	v_mfma_f32_16x16x32_bf16 v[60:63], v[204:207], v[208:211], v[60:63]
	v_mfma_f32_16x16x32_bf16 v[56:59], v[204:207], v[212:215], v[56:59]
	v_mfma_f32_16x16x32_bf16 v[52:55], v[204:207], v[216:219], v[52:55]
	v_mfma_f32_16x16x32_bf16 v[48:51], v[204:207], v[220:223], v[48:51]
	s_waitcnt lgkmcnt(2)
	v_mfma_f32_16x16x32_bf16 v[44:47], v[224:227], v[208:211], v[44:47]
	v_mfma_f32_16x16x32_bf16 v[40:43], v[224:227], v[212:215], v[40:43]
	v_mfma_f32_16x16x32_bf16 v[36:39], v[224:227], v[216:219], v[36:39]
	v_mfma_f32_16x16x32_bf16 v[32:35], v[224:227], v[220:223], v[32:35]
	s_waitcnt lgkmcnt(1)
	v_mfma_f32_16x16x32_bf16 v[28:31], v[228:231], v[208:211], v[28:31]
	v_mfma_f32_16x16x32_bf16 v[24:27], v[228:231], v[212:215], v[24:27]
	v_mfma_f32_16x16x32_bf16 v[20:23], v[228:231], v[216:219], v[20:23]
	v_mfma_f32_16x16x32_bf16 v[16:19], v[228:231], v[220:223], v[16:19]
	s_waitcnt lgkmcnt(0)
	v_mfma_f32_16x16x32_bf16 v[12:15], v[232:235], v[208:211], v[12:15]
	v_mfma_f32_16x16x32_bf16 v[8:11], v[232:235], v[212:215], v[8:11]
	v_mfma_f32_16x16x32_bf16 v[4:7], v[232:235], v[216:219], v[4:7]
	v_mfma_f32_16x16x32_bf16 v[0:3], v[232:235], v[220:223], v[0:3]
	s_setprio 2
	s_cmpk_eq_i32 s8, 0x780
	s_waitcnt vmcnt(0)
	s_barrier
	s_cbranch_scc0 .Lxk_3399
.Lxk_exit_3399:
	ds_read_b128 v[88:91], v114 offset:55296
	ds_read_b128 v[92:95], v114 offset:53248
	ds_read_b128 v[96:99], v115 offset:38912
	ds_read_b128 v[100:103], v115 offset:36864
	ds_read_b128 v[136:139], v114 offset:51200
	ds_read_b128 v[140:143], v114 offset:49152
	ds_read_b128 v[144:147], v115 offset:34816
	ds_read_b128 v[148:151], v115 offset:32768
	s_setprio 1
	s_waitcnt lgkmcnt(5)
	v_mfma_f32_16x16x32_bf16 v[0:3], v[96:99], v[88:91], v[0:3]
	s_waitcnt lgkmcnt(0)
	v_mfma_f32_16x16x32_bf16 v[60:63], v[148:151], v[140:143], v[60:63]
	v_mfma_f32_16x16x32_bf16 v[56:59], v[148:151], v[136:139], v[56:59]
	v_mfma_f32_16x16x32_bf16 v[52:55], v[148:151], v[92:95], v[52:55]
	v_mfma_f32_16x16x32_bf16 v[48:51], v[148:151], v[88:91], v[48:51]
	v_mfma_f32_16x16x32_bf16 v[44:47], v[144:147], v[140:143], v[44:47]
	v_mfma_f32_16x16x32_bf16 v[40:43], v[144:147], v[136:139], v[40:43]
	v_mfma_f32_16x16x32_bf16 v[36:39], v[144:147], v[92:95], v[36:39]
	v_mfma_f32_16x16x32_bf16 v[32:35], v[144:147], v[88:91], v[32:35]
	v_mfma_f32_16x16x32_bf16 v[28:31], v[100:103], v[140:143], v[28:31]
	v_mfma_f32_16x16x32_bf16 v[24:27], v[100:103], v[136:139], v[24:27]
	v_mfma_f32_16x16x32_bf16 v[20:23], v[100:103], v[92:95], v[20:23]
	v_mfma_f32_16x16x32_bf16 v[16:19], v[100:103], v[88:91], v[16:19]
	v_mfma_f32_16x16x32_bf16 v[12:15], v[96:99], v[140:143], v[12:15]
	v_mfma_f32_16x16x32_bf16 v[8:11], v[96:99], v[136:139], v[8:11]
	v_mfma_f32_16x16x32_bf16 v[4:7], v[96:99], v[92:95], v[4:7]
	s_setprio 0
	ds_read_b128 v[88:91], v116 offset:32768
	ds_read_b128 v[92:95], v116 offset:34816
	ds_read_b128 v[96:99], v117 offset:49152
	ds_read_b128 v[100:103], v117 offset:51200
	ds_read_b128 v[136:139], v116 offset:36864
	ds_read_b128 v[140:143], v116 offset:38912
	ds_read_b128 v[144:147], v117 offset:53248
	ds_read_b128 v[148:151], v117 offset:55296
	s_setprio 1
	s_waitcnt lgkmcnt(0)
	v_mfma_f32_16x16x32_bf16 v[0:3], v[140:143], v[148:151], v[0:3]
	v_mfma_f32_16x16x32_bf16 v[60:63], v[88:91], v[96:99], v[60:63]
	v_mfma_f32_16x16x32_bf16 v[56:59], v[88:91], v[100:103], v[56:59]
	v_mfma_f32_16x16x32_bf16 v[52:55], v[88:91], v[144:147], v[52:55]
	v_mfma_f32_16x16x32_bf16 v[48:51], v[88:91], v[148:151], v[48:51]
	v_mfma_f32_16x16x32_bf16 v[44:47], v[92:95], v[96:99], v[44:47]
	v_mfma_f32_16x16x32_bf16 v[40:43], v[92:95], v[100:103], v[40:43]
	v_mfma_f32_16x16x32_bf16 v[36:39], v[92:95], v[144:147], v[36:39]
	v_mfma_f32_16x16x32_bf16 v[32:35], v[92:95], v[148:151], v[32:35]
	v_mfma_f32_16x16x32_bf16 v[28:31], v[136:139], v[96:99], v[28:31]
	v_mfma_f32_16x16x32_bf16 v[24:27], v[136:139], v[100:103], v[24:27]
	v_mfma_f32_16x16x32_bf16 v[20:23], v[136:139], v[144:147], v[20:23]
	v_mfma_f32_16x16x32_bf16 v[16:19], v[136:139], v[148:151], v[16:19]
	v_mfma_f32_16x16x32_bf16 v[12:15], v[140:143], v[96:99], v[12:15]
	v_mfma_f32_16x16x32_bf16 v[8:11], v[140:143], v[100:103], v[8:11]
	v_mfma_f32_16x16x32_bf16 v[4:7], v[140:143], v[144:147], v[4:7]
	s_setprio 0
	s_barrier
	ds_write2_b32 v118, v60, v56 offset1:16
	ds_write2_b32 v118, v61, v57 offset0:132 offset1:148
	v_add_u32_e32 v56, 0x400, v118
	ds_write2_b32 v56, v62, v58 offset0:8 offset1:24
	ds_write2_b32 v56, v63, v59 offset0:140 offset1:156
	ds_write2_b32 v118, v52, v48 offset0:32 offset1:48
	ds_write2_b32 v118, v53, v49 offset0:164 offset1:180
	ds_write2_b32 v56, v54, v50 offset0:40 offset1:56
	ds_write2_b32 v56, v55, v51 offset0:172 offset1:188
	v_add_u32_e32 v48, 0x2000, v118
	ds_write2_b32 v48, v44, v40 offset0:64 offset1:80
	ds_write2_b32 v48, v45, v41 offset0:196 offset1:212
	v_add_u32_e32 v40, 0x2400, v118
	ds_write2_b32 v40, v46, v42 offset0:72 offset1:88
	ds_write2_b32 v40, v47, v43 offset0:204 offset1:220
	ds_write2_b32 v48, v36, v32 offset0:96 offset1:112
	ds_write2_b32 v48, v37, v33 offset0:228 offset1:244
	ds_write2_b32 v40, v38, v34 offset0:104 offset1:120
	ds_write2_b32 v40, v39, v35 offset0:236 offset1:252
	v_add_u32_e32 v32, 0x4000, v118
	ds_write2_b32 v32, v28, v24 offset0:128 offset1:144
	v_add_u32_e32 v24, 0x4400, v118
	ds_write2_b32 v24, v29, v25 offset0:4 offset1:20
	ds_write2_b32 v24, v30, v26 offset0:136 offset1:152
	v_add_u32_e32 v25, 0x4800, v118
	ds_write2_b32 v25, v31, v27 offset0:12 offset1:28
	ds_write2_b32 v32, v20, v16 offset0:160 offset1:176
	ds_write2_b32 v24, v21, v17 offset0:36 offset1:52
	ds_write2_b32 v24, v22, v18 offset0:168 offset1:184
	ds_write2_b32 v25, v23, v19 offset0:44 offset1:60
	v_add_u32_e32 v16, 0x6000, v118
	ds_write2_b32 v16, v12, v8 offset0:192 offset1:208
	v_add_u32_e32 v8, 0x6400, v118
	ds_write2_b32 v8, v13, v9 offset0:68 offset1:84
	ds_write2_b32 v8, v14, v10 offset0:200 offset1:216
	v_add_u32_e32 v9, 0x6800, v118
	ds_write2_b32 v9, v15, v11 offset0:76 offset1:92
	ds_write2_b32 v16, v4, v0 offset0:224 offset1:240
	ds_write2_b32 v8, v5, v1 offset0:100 offset1:116
	ds_write2_b32 v8, v6, v2 offset0:232 offset1:248
	ds_write2_b32 v9, v7, v3 offset0:108 offset1:124
	v_or_b32_e32 v0, s16, v119
	v_ashrrev_i32_e32 v1, 31, v0
	v_lshl_add_u64 v[0:1], v[0:1], 1, s[6:7]
	v_add_u32_e32 v2, s15, v127
	s_mov_b32 s8, 0
	s_waitcnt lgkmcnt(0)
	s_barrier

.LBB0_3462:
	s_ashr_i32 s16, s23, 31
	s_lshr_b32 s16, s16, 29
	s_add_i32 s16, s23, s16
	s_ashr_i32 s16, s16, 3
	s_lshr_b32 s17, s16, 4
	s_lshl_b32 s24, s16, 7
	s_lshl_b32 s16, s16, 10
	s_lshl_b32 s25, s23, 7
	s_sub_i32 s25, s25, s16
	v_add_u32_e32 v0, s25, v106
	s_mulk_i32 s17, 0x900
	s_and_b32 s24, s24, 0x780
	v_ashrrev_i32_e32 v1, 31, v0
	v_add_u32_e32 v2, 0x4000, v107
	s_add_i32 s24, s24, s17
	v_lshlrev_b64 v[0:1], 13, v[0:1]
	v_readfirstlane_b32 s26, v2
	s_add_i32 s17, s24, 0x100
	v_lshl_add_u64 v[0:1], v[66:67], 0, v[0:1]
	s_mov_b32 m0, s26
	v_readfirstlane_b32 s26, v107
	global_load_lds_dwordx4 v[0:1], off
	v_add_u32_e32 v0, s17, v106
	v_ashrrev_i32_e32 v1, 31, v0
	v_lshlrev_b64 v[0:1], 13, v[0:1]
	v_lshl_add_u64 v[0:1], v[72:73], 0, v[0:1]
	s_mov_b32 m0, s26
	v_readfirstlane_b32 s26, v131
	global_load_lds_dwordx4 v[0:1], off
	v_add_u32_e32 v0, s25, v108
	v_ashrrev_i32_e32 v1, 31, v0
	v_lshlrev_b64 v[0:1], 13, v[0:1]
	v_lshl_add_u64 v[0:1], v[68:69], 0, v[0:1]
	s_mov_b32 m0, s26
	v_add_u32_e32 v2, 0x400, v107
	global_load_lds_dwordx4 v[0:1], off
	v_add_u32_e32 v0, s17, v108
	v_ashrrev_i32_e32 v1, 31, v0
	v_lshlrev_b64 v[0:1], 13, v[0:1]
	v_readfirstlane_b32 s26, v2
	v_lshl_add_u64 v[0:1], v[74:75], 0, v[0:1]
	s_mov_b32 m0, s26
	v_readfirstlane_b32 s26, v132
	global_load_lds_dwordx4 v[0:1], off
	v_add_u32_e32 v0, s25, v110
	v_ashrrev_i32_e32 v1, 31, v0
	v_lshlrev_b64 v[0:1], 13, v[0:1]
	v_lshl_add_u64 v[0:1], v[66:67], 0, v[0:1]
	s_mov_b32 m0, s26
	v_add_u32_e32 v2, 0x800, v107
	global_load_lds_dwordx4 v[0:1], off
	v_add_u32_e32 v0, s17, v110
	v_ashrrev_i32_e32 v1, 31, v0
	v_lshlrev_b64 v[0:1], 13, v[0:1]
	v_readfirstlane_b32 s26, v2
	v_lshl_add_u64 v[0:1], v[72:73], 0, v[0:1]
	s_mov_b32 m0, s26
	v_readfirstlane_b32 s26, v133
	global_load_lds_dwordx4 v[0:1], off
	v_add_u32_e32 v0, s25, v112
	v_ashrrev_i32_e32 v1, 31, v0
	v_lshlrev_b64 v[0:1], 13, v[0:1]
	v_lshl_add_u64 v[0:1], v[70:71], 0, v[0:1]
	s_mov_b32 m0, s26
	v_add_u32_e32 v2, 0xc00, v107
	global_load_lds_dwordx4 v[0:1], off
	v_add_u32_e32 v0, s17, v112
	v_ashrrev_i32_e32 v1, 31, v0
	v_lshlrev_b64 v[0:1], 13, v[0:1]
	v_readfirstlane_b32 s17, v2
	v_lshl_add_u64 v[0:1], v[76:77], 0, v[0:1]
	s_mov_b32 m0, s17
	s_mov_b32 s26, 0
	global_load_lds_dwordx4 v[0:1], off
	v_subrev_u32_e32 v0, s16, v122
	v_ashrrev_i32_e32 v1, 31, v0
	v_lshlrev_b64 v[0:1], 13, v[0:1]
	v_lshl_add_u64 v[90:91], v[78:79], 0, v[0:1]
	v_add_u32_e32 v0, s24, v123
	v_ashrrev_i32_e32 v1, 31, v0
	v_lshlrev_b64 v[0:1], 13, v[0:1]
	v_lshl_add_u64 v[92:93], v[80:81], 0, v[0:1]
	v_subrev_u32_e32 v0, s16, v124
	v_ashrrev_i32_e32 v1, 31, v0
	v_lshlrev_b64 v[0:1], 13, v[0:1]
	v_lshl_add_u64 v[94:95], v[82:83], 0, v[0:1]
	v_add_u32_e32 v0, s24, v125
	v_ashrrev_i32_e32 v1, 31, v0
	v_lshlrev_b64 v[0:1], 13, v[0:1]
	v_lshl_add_u64 v[96:97], v[84:85], 0, v[0:1]
	v_subrev_u32_e32 v0, s16, v126
	v_ashrrev_i32_e32 v1, 31, v0
	v_lshlrev_b64 v[0:1], 13, v[0:1]
	v_lshl_add_u64 v[98:99], v[78:79], 0, v[0:1]
	v_add_u32_e32 v0, s24, v127
	v_ashrrev_i32_e32 v1, 31, v0
	v_lshlrev_b64 v[0:1], 13, v[0:1]
	v_lshl_add_u64 v[100:101], v[80:81], 0, v[0:1]
	v_subrev_u32_e32 v0, s16, v64
	v_ashrrev_i32_e32 v1, 31, v0
	v_lshlrev_b64 v[0:1], 13, v[0:1]
	v_lshl_add_u64 v[102:103], v[86:87], 0, v[0:1]
	v_add_u32_e32 v0, s24, v128
	v_ashrrev_i32_e32 v1, 31, v0
	v_lshlrev_b64 v[0:1], 13, v[0:1]
	v_lshl_add_u64 v[104:105], v[88:89], 0, v[0:1]
	s_mov_b64 s[16:17], 0
	v_mov_b32_e32 v0, 0
	v_mov_b32_e32 v1, v65
	v_mov_b32_e32 v2, v65
	v_mov_b32_e32 v3, v65
	v_mov_b32_e32 v4, 0
	v_mov_b32_e32 v5, v65
	v_mov_b32_e32 v6, v65
	v_mov_b32_e32 v7, v65
	v_mov_b32_e32 v8, 0
	v_mov_b32_e32 v9, v65
	v_mov_b32_e32 v10, v65
	v_mov_b32_e32 v11, v65
	v_mov_b32_e32 v12, 0
	v_mov_b32_e32 v13, v65
	v_mov_b32_e32 v14, v65
	v_mov_b32_e32 v15, v65
	v_mov_b32_e32 v16, 0
	v_mov_b32_e32 v17, v65
	v_mov_b32_e32 v18, v65
	v_mov_b32_e32 v19, v65
	v_mov_b32_e32 v20, 0
	v_mov_b32_e32 v21, v65
	v_mov_b32_e32 v22, v65
	v_mov_b32_e32 v23, v65
	s_waitcnt vmcnt(0)
	v_mov_b32_e32 v24, 0
	v_mov_b32_e32 v25, v65
	v_mov_b32_e32 v26, v65
	v_mov_b32_e32 v27, v65
	v_mov_b32_e32 v28, 0
	v_mov_b32_e32 v29, v65
	v_mov_b32_e32 v30, v65
	v_mov_b32_e32 v31, v65
	v_mov_b32_e32 v32, 0
	v_mov_b32_e32 v33, v65
	v_mov_b32_e32 v34, v65
	v_mov_b32_e32 v35, v65
	v_mov_b32_e32 v36, 0
	v_mov_b32_e32 v37, v65
	v_mov_b32_e32 v38, v65
	v_mov_b32_e32 v39, v65
	v_mov_b32_e32 v40, 0
	v_mov_b32_e32 v41, v65
	v_mov_b32_e32 v42, v65
	v_mov_b32_e32 v43, v65
	v_mov_b32_e32 v44, 0
	v_mov_b32_e32 v45, v65
	v_mov_b32_e32 v46, v65
	v_mov_b32_e32 v47, v65
	v_mov_b32_e32 v48, 0
	v_mov_b32_e32 v49, v65
	v_mov_b32_e32 v50, v65
	v_mov_b32_e32 v51, v65
	v_mov_b32_e32 v52, 0
	v_mov_b32_e32 v53, v65
	v_mov_b32_e32 v54, v65
	v_mov_b32_e32 v55, v65
	v_mov_b32_e32 v56, 0
	v_mov_b32_e32 v57, v65
	v_mov_b32_e32 v58, v65
	v_mov_b32_e32 v59, v65
	v_mov_b32_e32 v60, 0
	v_mov_b32_e32 v61, v65
	v_mov_b32_e32 v62, v65
	v_mov_b32_e32 v63, v65
	s_waitcnt lgkmcnt(0)
	s_barrier
	v_add3_u32 v182, 0, v134, v135
	v_add_u32_e32 v183, 0x4000, v182
	s_nop 0
	v_readfirstlane_b32 s82, v183
	v_lshl_add_u32 v183, v109, 1, 0
	s_nop 0
	v_readfirstlane_b32 s83, v182
	v_add3_u32 v183, v183, v135, s19
	s_nop 0
	v_readfirstlane_b32 s84, v183
	v_add_u32_e32 v183, 0x400, v182
	s_nop 0
	v_readfirstlane_b32 s85, v183
	v_lshl_add_u32 v183, v111, 1, 0
	v_add3_u32 v183, v183, v135, s19
	s_nop 0
	v_readfirstlane_b32 s86, v183
	v_add_u32_e32 v183, 0x800, v182
	s_nop 0
	v_readfirstlane_b32 s87, v183
	v_lshl_add_u32 v183, v113, 1, 0
	v_add3_u32 v183, v183, v135, s19
	s_nop 0
	v_readfirstlane_b32 s88, v183
	v_add_u32_e32 v182, 0xc00, v182
	s_nop 0
	v_readfirstlane_b32 s89, v182
	v_subrev_u32_e32 v184, s52, v90
	v_subrev_u32_e32 v185, s52, v92
	v_subrev_u32_e32 v186, s52, v94
	v_subrev_u32_e32 v187, s52, v96
	v_subrev_u32_e32 v188, s52, v98
	v_subrev_u32_e32 v189, s52, v100
	v_subrev_u32_e32 v190, s52, v102
	v_subrev_u32_e32 v191, s52, v104
	s_bitcmp1_b32 s32, 0
	s_cbranch_scc1 .Lxk_3463
.LBB0_3463:
	s_and_b32 s27, s26, 0x4000
	s_xor_b32 s28, s27, 0x4000
	s_lshl_b32 s28, s28, 1
	s_add_i32 s28, s28, 32
	s_add_u32 s90, s52, s16
	s_addc_u32 s91, s53, s17
	s_add_i32 m0, s28, s82
	s_lshl_b32 s27, s27, 1
	global_load_lds_dwordx4 v184, s[90:91]
	s_add_i32 m0, s28, s83
	s_add_i32 s27, s27, 32
	global_load_lds_dwordx4 v185, s[90:91]
	s_add_i32 m0, s28, s84
	v_add3_u32 v139, s27, v114, v136
	global_load_lds_dwordx4 v186, s[90:91]
	s_add_i32 m0, s28, s85
	v_add3_u32 v172, s27, v115, v136
	global_load_lds_dwordx4 v187, s[90:91]
	s_add_i32 m0, s28, s86
	v_add_u32_e32 v160, v139, v137
	global_load_lds_dwordx4 v188, s[90:91]
	s_add_i32 m0, s28, s87
	v_add_u32_e32 v168, v172, v137
	global_load_lds_dwordx4 v189, s[90:91]
	s_add_i32 m0, s28, s88
	s_addk_i32 s26, 0x4000
	global_load_lds_dwordx4 v190, s[90:91]
	s_add_i32 m0, s28, s89
	s_add_u32 s16, s16, 0x80
	s_addc_u32 s17, s17, 0
	global_load_lds_dwordx4 v191, s[90:91]
	ds_read_b128 v[140:143], v160
	ds_read_b128 v[148:151], v168 offset:16384
	ds_read_b128 v[152:155], v168 offset:18432
	ds_read_b128 v[164:167], v168 offset:20480
	ds_read_b128 v[168:171], v168 offset:22528
	ds_read_b128 v[144:147], v160 offset:2048
	ds_read_b128 v[156:159], v160 offset:4096
	ds_read_b128 v[160:163], v160 offset:6144
	v_add_u32_e32 v139, v139, v138
	v_add_u32_e32 v236, v172, v138
	ds_read_b128 v[204:207], v139
	ds_read_b128 v[208:211], v236 offset:16384
	ds_read_b128 v[212:215], v236 offset:18432
	ds_read_b128 v[216:219], v236 offset:20480
	ds_read_b128 v[220:223], v236 offset:22528
	ds_read_b128 v[224:227], v139 offset:2048
	ds_read_b128 v[228:231], v139 offset:4096
	ds_read_b128 v[232:235], v139 offset:6144
	s_setprio 1
	s_waitcnt lgkmcnt(11)
	v_mfma_f32_16x16x32_bf16 v[60:63], v[140:143], v[148:151], v[60:63]
	v_mfma_f32_16x16x32_bf16 v[56:59], v[140:143], v[152:155], v[56:59]
	v_mfma_f32_16x16x32_bf16 v[52:55], v[140:143], v[164:167], v[52:55]
	v_mfma_f32_16x16x32_bf16 v[48:51], v[140:143], v[168:171], v[48:51]
	s_waitcnt lgkmcnt(10)
	v_mfma_f32_16x16x32_bf16 v[44:47], v[144:147], v[148:151], v[44:47]
	v_mfma_f32_16x16x32_bf16 v[40:43], v[144:147], v[152:155], v[40:43]
	v_mfma_f32_16x16x32_bf16 v[36:39], v[144:147], v[164:167], v[36:39]
	v_mfma_f32_16x16x32_bf16 v[32:35], v[144:147], v[168:171], v[32:35]
	s_waitcnt lgkmcnt(9)
	v_mfma_f32_16x16x32_bf16 v[28:31], v[156:159], v[148:151], v[28:31]
	v_mfma_f32_16x16x32_bf16 v[24:27], v[156:159], v[152:155], v[24:27]
	v_mfma_f32_16x16x32_bf16 v[20:23], v[156:159], v[164:167], v[20:23]
	v_mfma_f32_16x16x32_bf16 v[16:19], v[156:159], v[168:171], v[16:19]
	s_waitcnt lgkmcnt(8)
	v_mfma_f32_16x16x32_bf16 v[12:15], v[160:163], v[148:151], v[12:15]
	v_mfma_f32_16x16x32_bf16 v[8:11], v[160:163], v[152:155], v[8:11]
	v_mfma_f32_16x16x32_bf16 v[4:7], v[160:163], v[164:167], v[4:7]
	v_mfma_f32_16x16x32_bf16 v[0:3], v[160:163], v[168:171], v[0:3]
	s_waitcnt lgkmcnt(3)
	v_mfma_f32_16x16x32_bf16 v[60:63], v[204:207], v[208:211], v[60:63]
	v_mfma_f32_16x16x32_bf16 v[56:59], v[204:207], v[212:215], v[56:59]
	v_mfma_f32_16x16x32_bf16 v[52:55], v[204:207], v[216:219], v[52:55]
	v_mfma_f32_16x16x32_bf16 v[48:51], v[204:207], v[220:223], v[48:51]
	s_waitcnt lgkmcnt(2)
	v_mfma_f32_16x16x32_bf16 v[44:47], v[224:227], v[208:211], v[44:47]
	v_mfma_f32_16x16x32_bf16 v[40:43], v[224:227], v[212:215], v[40:43]
	v_mfma_f32_16x16x32_bf16 v[36:39], v[224:227], v[216:219], v[36:39]
	v_mfma_f32_16x16x32_bf16 v[32:35], v[224:227], v[220:223], v[32:35]
	s_waitcnt lgkmcnt(1)
	v_mfma_f32_16x16x32_bf16 v[28:31], v[228:231], v[208:211], v[28:31]
	v_mfma_f32_16x16x32_bf16 v[24:27], v[228:231], v[212:215], v[24:27]
	v_mfma_f32_16x16x32_bf16 v[20:23], v[228:231], v[216:219], v[20:23]
	v_mfma_f32_16x16x32_bf16 v[16:19], v[228:231], v[220:223], v[16:19]
	s_waitcnt lgkmcnt(0)
	v_mfma_f32_16x16x32_bf16 v[12:15], v[232:235], v[208:211], v[12:15]
	v_mfma_f32_16x16x32_bf16 v[8:11], v[232:235], v[212:215], v[8:11]
	v_mfma_f32_16x16x32_bf16 v[4:7], v[232:235], v[216:219], v[4:7]
	v_mfma_f32_16x16x32_bf16 v[0:3], v[232:235], v[220:223], v[0:3]
	s_setprio 0
	s_cmpk_eq_i32 s16, 0x1f80
	s_waitcnt vmcnt(0)
	s_barrier
	s_cbranch_scc0 .LBB0_3463
	s_branch .Lxk_exit_3463
.Lxk_3463:
	s_and_b32 s27, s26, 0x4000
	s_xor_b32 s28, s27, 0x4000
	s_lshl_b32 s28, s28, 1
	s_add_i32 s28, s28, 32
	s_add_u32 s90, s52, s16
	s_addc_u32 s91, s53, s17
	s_add_i32 m0, s28, s82
	s_lshl_b32 s27, s27, 1
	global_load_lds_dwordx4 v184, s[90:91]
	s_add_i32 m0, s28, s83
	s_add_i32 s27, s27, 32
	global_load_lds_dwordx4 v185, s[90:91]
	s_add_i32 m0, s28, s84
	v_add3_u32 v139, s27, v114, v136
	global_load_lds_dwordx4 v186, s[90:91]
	s_add_i32 m0, s28, s85
	v_add3_u32 v172, s27, v115, v136
	global_load_lds_dwordx4 v187, s[90:91]
	s_add_i32 m0, s28, s86
	v_add_u32_e32 v160, v139, v137
	global_load_lds_dwordx4 v188, s[90:91]
	s_add_i32 m0, s28, s87
	v_add_u32_e32 v168, v172, v137
	global_load_lds_dwordx4 v189, s[90:91]
	s_add_i32 m0, s28, s88
	s_addk_i32 s26, 0x4000
	global_load_lds_dwordx4 v190, s[90:91]
	s_add_i32 m0, s28, s89
	s_add_u32 s16, s16, 0x80
	s_addc_u32 s17, s17, 0
	global_load_lds_dwordx4 v191, s[90:91]
	ds_read_b128 v[140:143], v160
	ds_read_b128 v[148:151], v168 offset:16384
	ds_read_b128 v[152:155], v168 offset:18432
	ds_read_b128 v[164:167], v168 offset:20480
	ds_read_b128 v[168:171], v168 offset:22528
	ds_read_b128 v[144:147], v160 offset:2048
	ds_read_b128 v[156:159], v160 offset:4096
	ds_read_b128 v[160:163], v160 offset:6144
	v_add_u32_e32 v139, v139, v138
	v_add_u32_e32 v236, v172, v138
	ds_read_b128 v[204:207], v139
	ds_read_b128 v[208:211], v236 offset:16384
	ds_read_b128 v[212:215], v236 offset:18432
	ds_read_b128 v[216:219], v236 offset:20480
	ds_read_b128 v[220:223], v236 offset:22528
	ds_read_b128 v[224:227], v139 offset:2048
	ds_read_b128 v[228:231], v139 offset:4096
	ds_read_b128 v[232:235], v139 offset:6144
	s_setprio 3
	s_waitcnt lgkmcnt(11)
	v_mfma_f32_16x16x32_bf16 v[60:63], v[140:143], v[148:151], v[60:63]
	v_mfma_f32_16x16x32_bf16 v[56:59], v[140:143], v[152:155], v[56:59]
	v_mfma_f32_16x16x32_bf16 v[52:55], v[140:143], v[164:167], v[52:55]
	v_mfma_f32_16x16x32_bf16 v[48:51], v[140:143], v[168:171], v[48:51]
	s_waitcnt lgkmcnt(10)
	v_mfma_f32_16x16x32_bf16 v[44:47], v[144:147], v[148:151], v[44:47]
	v_mfma_f32_16x16x32_bf16 v[40:43], v[144:147], v[152:155], v[40:43]
	v_mfma_f32_16x16x32_bf16 v[36:39], v[144:147], v[164:167], v[36:39]
	v_mfma_f32_16x16x32_bf16 v[32:35], v[144:147], v[168:171], v[32:35]
	s_waitcnt lgkmcnt(9)
	v_mfma_f32_16x16x32_bf16 v[28:31], v[156:159], v[148:151], v[28:31]
	v_mfma_f32_16x16x32_bf16 v[24:27], v[156:159], v[152:155], v[24:27]
	v_mfma_f32_16x16x32_bf16 v[20:23], v[156:159], v[164:167], v[20:23]
	v_mfma_f32_16x16x32_bf16 v[16:19], v[156:159], v[168:171], v[16:19]
	s_waitcnt lgkmcnt(8)
	v_mfma_f32_16x16x32_bf16 v[12:15], v[160:163], v[148:151], v[12:15]
	v_mfma_f32_16x16x32_bf16 v[8:11], v[160:163], v[152:155], v[8:11]
	v_mfma_f32_16x16x32_bf16 v[4:7], v[160:163], v[164:167], v[4:7]
	v_mfma_f32_16x16x32_bf16 v[0:3], v[160:163], v[168:171], v[0:3]
	s_waitcnt lgkmcnt(3)
	v_mfma_f32_16x16x32_bf16 v[60:63], v[204:207], v[208:211], v[60:63]
	v_mfma_f32_16x16x32_bf16 v[56:59], v[204:207], v[212:215], v[56:59]
	v_mfma_f32_16x16x32_bf16 v[52:55], v[204:207], v[216:219], v[52:55]
	v_mfma_f32_16x16x32_bf16 v[48:51], v[204:207], v[220:223], v[48:51]
	s_waitcnt lgkmcnt(2)
	v_mfma_f32_16x16x32_bf16 v[44:47], v[224:227], v[208:211], v[44:47]
	v_mfma_f32_16x16x32_bf16 v[40:43], v[224:227], v[212:215], v[40:43]
	v_mfma_f32_16x16x32_bf16 v[36:39], v[224:227], v[216:219], v[36:39]
	v_mfma_f32_16x16x32_bf16 v[32:35], v[224:227], v[220:223], v[32:35]
	s_waitcnt lgkmcnt(1)
	v_mfma_f32_16x16x32_bf16 v[28:31], v[228:231], v[208:211], v[28:31]
	v_mfma_f32_16x16x32_bf16 v[24:27], v[228:231], v[212:215], v[24:27]
	v_mfma_f32_16x16x32_bf16 v[20:23], v[228:231], v[216:219], v[20:23]
	v_mfma_f32_16x16x32_bf16 v[16:19], v[228:231], v[220:223], v[16:19]
	s_waitcnt lgkmcnt(0)
	v_mfma_f32_16x16x32_bf16 v[12:15], v[232:235], v[208:211], v[12:15]
	v_mfma_f32_16x16x32_bf16 v[8:11], v[232:235], v[212:215], v[8:11]
	v_mfma_f32_16x16x32_bf16 v[4:7], v[232:235], v[216:219], v[4:7]
	v_mfma_f32_16x16x32_bf16 v[0:3], v[232:235], v[220:223], v[0:3]
	s_setprio 2
	s_cmpk_eq_i32 s16, 0x1f80
	s_waitcnt vmcnt(0)
	s_barrier
	s_cbranch_scc0 .Lxk_3463

.LBB0_3471:
	s_ashr_i32 s8, s14, 31
	s_lshr_b32 s8, s8, 29
	s_add_i32 s8, s14, s8
	s_ashr_i32 s8, s8, 3
	s_add_i32 s9, s8, s16
	s_lshl_b32 s20, s8, 7
	s_lshl_b32 s8, s8, 10
	s_lshl_b32 s21, s14, 7
	s_sub_i32 s21, s21, s8
	s_lshr_b32 s9, s9, 4
	v_add_u32_e32 v0, s21, v104
	s_mulk_i32 s9, 0x900
	s_and_b32 s20, s20, 0x780
	v_ashrrev_i32_e32 v1, 31, v0
	v_add_u32_e32 v2, 0x4000, v105
	s_add_i32 s20, s20, s9
	v_lshlrev_b64 v[0:1], 13, v[0:1]
	v_readfirstlane_b32 s22, v2
	s_add_i32 s9, s20, 0x100
	v_lshl_add_u64 v[0:1], v[64:65], 0, v[0:1]
	s_mov_b32 m0, s22
	v_readfirstlane_b32 s22, v105
	global_load_lds_dwordx4 v[0:1], off
	v_add_u32_e32 v0, s9, v104
	v_ashrrev_i32_e32 v1, 31, v0
	v_lshlrev_b64 v[0:1], 13, v[0:1]
	v_lshl_add_u64 v[0:1], v[70:71], 0, v[0:1]
	s_mov_b32 m0, s22
	v_readfirstlane_b32 s22, v130
	global_load_lds_dwordx4 v[0:1], off
	v_add_u32_e32 v0, s21, v106
	v_ashrrev_i32_e32 v1, 31, v0
	v_lshlrev_b64 v[0:1], 13, v[0:1]
	v_lshl_add_u64 v[0:1], v[66:67], 0, v[0:1]
	s_mov_b32 m0, s22
	v_add_u32_e32 v2, 0x400, v105
	global_load_lds_dwordx4 v[0:1], off
	v_add_u32_e32 v0, s9, v106
	v_ashrrev_i32_e32 v1, 31, v0
	v_lshlrev_b64 v[0:1], 13, v[0:1]
	v_readfirstlane_b32 s22, v2
	v_lshl_add_u64 v[0:1], v[72:73], 0, v[0:1]
	s_mov_b32 m0, s22
	v_readfirstlane_b32 s22, v131
	global_load_lds_dwordx4 v[0:1], off
	v_add_u32_e32 v0, s21, v108
	v_ashrrev_i32_e32 v1, 31, v0
	v_lshlrev_b64 v[0:1], 13, v[0:1]
	v_lshl_add_u64 v[0:1], v[64:65], 0, v[0:1]
	s_mov_b32 m0, s22
	v_add_u32_e32 v2, 0x800, v105
	global_load_lds_dwordx4 v[0:1], off
	v_add_u32_e32 v0, s9, v108
	v_ashrrev_i32_e32 v1, 31, v0
	v_lshlrev_b64 v[0:1], 13, v[0:1]
	v_readfirstlane_b32 s22, v2
	v_lshl_add_u64 v[0:1], v[70:71], 0, v[0:1]
	s_mov_b32 m0, s22
	v_readfirstlane_b32 s22, v132
	global_load_lds_dwordx4 v[0:1], off
	v_add_u32_e32 v0, s21, v110
	v_ashrrev_i32_e32 v1, 31, v0
	v_lshlrev_b64 v[0:1], 13, v[0:1]
	v_lshl_add_u64 v[0:1], v[68:69], 0, v[0:1]
	s_mov_b32 m0, s22
	v_add_u32_e32 v2, 0xc00, v105
	global_load_lds_dwordx4 v[0:1], off
	v_add_u32_e32 v0, s9, v110
	v_ashrrev_i32_e32 v1, 31, v0
	v_lshlrev_b64 v[0:1], 13, v[0:1]
	v_readfirstlane_b32 s9, v2
	v_lshl_add_u64 v[0:1], v[74:75], 0, v[0:1]
	s_mov_b32 m0, s9
	s_mov_b32 s22, 0
	global_load_lds_dwordx4 v[0:1], off
	v_subrev_u32_e32 v0, s8, v120
	v_ashrrev_i32_e32 v1, 31, v0
	v_lshlrev_b64 v[0:1], 13, v[0:1]
	v_lshl_add_u64 v[88:89], v[76:77], 0, v[0:1]
	v_add_u32_e32 v0, s20, v121
	v_ashrrev_i32_e32 v1, 31, v0
	v_lshlrev_b64 v[0:1], 13, v[0:1]
	v_lshl_add_u64 v[90:91], v[78:79], 0, v[0:1]
	v_subrev_u32_e32 v0, s8, v122
	v_ashrrev_i32_e32 v1, 31, v0
	v_lshlrev_b64 v[0:1], 13, v[0:1]
	v_lshl_add_u64 v[92:93], v[80:81], 0, v[0:1]
	v_add_u32_e32 v0, s20, v123
	v_ashrrev_i32_e32 v1, 31, v0
	v_lshlrev_b64 v[0:1], 13, v[0:1]
	v_lshl_add_u64 v[94:95], v[82:83], 0, v[0:1]
	v_subrev_u32_e32 v0, s8, v124
	v_ashrrev_i32_e32 v1, 31, v0
	v_lshlrev_b64 v[0:1], 13, v[0:1]
	v_lshl_add_u64 v[96:97], v[76:77], 0, v[0:1]
	v_add_u32_e32 v0, s20, v125
	v_ashrrev_i32_e32 v1, 31, v0
	v_lshlrev_b64 v[0:1], 13, v[0:1]
	v_lshl_add_u64 v[98:99], v[78:79], 0, v[0:1]
	v_subrev_u32_e32 v0, s8, v126
	v_ashrrev_i32_e32 v1, 31, v0
	v_lshlrev_b64 v[0:1], 13, v[0:1]
	v_lshl_add_u64 v[100:101], v[84:85], 0, v[0:1]
	v_add_u32_e32 v0, s20, v127
	v_ashrrev_i32_e32 v1, 31, v0
	v_lshlrev_b64 v[0:1], 13, v[0:1]
	v_lshl_add_u64 v[102:103], v[86:87], 0, v[0:1]
	v_mov_b32_e32 v0, 0
	s_mov_b64 s[8:9], 0
	v_mov_b32_e32 v1, v0
	v_mov_b32_e32 v2, v0
	v_mov_b32_e32 v3, v0
	v_mov_b32_e32 v4, v0
	v_mov_b32_e32 v5, v0
	v_mov_b32_e32 v6, v0
	v_mov_b32_e32 v7, v0
	v_mov_b32_e32 v8, v0
	v_mov_b32_e32 v9, v0
	v_mov_b32_e32 v10, v0
	v_mov_b32_e32 v11, v0
	v_mov_b32_e32 v12, v0
	v_mov_b32_e32 v13, v0
	v_mov_b32_e32 v14, v0
	v_mov_b32_e32 v15, v0
	v_mov_b32_e32 v16, v0
	v_mov_b32_e32 v17, v0
	v_mov_b32_e32 v18, v0
	v_mov_b32_e32 v19, v0
	v_mov_b32_e32 v20, v0
	v_mov_b32_e32 v21, v0
	v_mov_b32_e32 v22, v0
	v_mov_b32_e32 v23, v0
	v_mov_b32_e32 v24, v0
	v_mov_b32_e32 v25, v0
	v_mov_b32_e32 v26, v0
	v_mov_b32_e32 v27, v0
	s_waitcnt vmcnt(0)
	v_mov_b32_e32 v28, v0
	v_mov_b32_e32 v29, v0
	v_mov_b32_e32 v30, v0
	v_mov_b32_e32 v31, v0
	v_mov_b32_e32 v32, v0
	v_mov_b32_e32 v33, v0
	v_mov_b32_e32 v34, v0
	v_mov_b32_e32 v35, v0
	v_mov_b32_e32 v36, v0
	v_mov_b32_e32 v37, v0
	v_mov_b32_e32 v38, v0
	v_mov_b32_e32 v39, v0
	v_mov_b32_e32 v40, v0
	v_mov_b32_e32 v41, v0
	v_mov_b32_e32 v42, v0
	v_mov_b32_e32 v43, v0
	v_mov_b32_e32 v44, v0
	v_mov_b32_e32 v45, v0
	v_mov_b32_e32 v46, v0
	v_mov_b32_e32 v47, v0
	v_mov_b32_e32 v48, v0
	v_mov_b32_e32 v49, v0
	v_mov_b32_e32 v50, v0
	v_mov_b32_e32 v51, v0
	v_mov_b32_e32 v52, v0
	v_mov_b32_e32 v53, v0
	v_mov_b32_e32 v54, v0
	v_mov_b32_e32 v55, v0
	v_mov_b32_e32 v56, v0
	v_mov_b32_e32 v57, v0
	v_mov_b32_e32 v58, v0
	v_mov_b32_e32 v59, v0
	v_mov_b32_e32 v60, v0
	v_mov_b32_e32 v61, v0
	v_mov_b32_e32 v62, v0
	v_mov_b32_e32 v63, v0
	s_waitcnt lgkmcnt(0)
	s_barrier
	v_add3_u32 v182, 0, v133, v134
	v_add_u32_e32 v183, 0x4000, v182
	s_nop 0
	v_readfirstlane_b32 s82, v183
	v_lshl_add_u32 v183, v107, 1, 0
	s_nop 0
	v_readfirstlane_b32 s83, v182
	v_add3_u32 v183, v183, v134, s13
	s_nop 0
	v_readfirstlane_b32 s84, v183
	v_add_u32_e32 v183, 0x400, v182
	s_nop 0
	v_readfirstlane_b32 s85, v183
	v_lshl_add_u32 v183, v109, 1, 0
	v_add3_u32 v183, v183, v134, s13
	s_nop 0
	v_readfirstlane_b32 s86, v183
	v_add_u32_e32 v183, 0x800, v182
	s_nop 0
	v_readfirstlane_b32 s87, v183
	v_lshl_add_u32 v183, v111, 1, 0
	v_add3_u32 v183, v183, v134, s13
	s_nop 0
	v_readfirstlane_b32 s88, v183
	v_add_u32_e32 v182, 0xc00, v182
	s_nop 0
	v_readfirstlane_b32 s89, v182
	v_subrev_u32_e32 v184, s52, v88
	v_subrev_u32_e32 v185, s52, v90
	v_subrev_u32_e32 v186, s52, v92
	v_subrev_u32_e32 v187, s52, v94
	v_subrev_u32_e32 v188, s52, v96
	v_subrev_u32_e32 v189, s52, v98
	v_subrev_u32_e32 v190, s52, v100
	v_subrev_u32_e32 v191, s52, v102
	s_bitcmp1_b32 s32, 0
	s_cbranch_scc1 .Lxk_3472
.LBB0_3472:
	s_and_b32 s23, s22, 0x4000
	s_xor_b32 s24, s23, 0x4000
	s_lshl_b32 s24, s24, 1
	s_add_i32 s24, s24, 32
	s_add_u32 s90, s52, s8
	s_addc_u32 s91, s53, s9
	s_add_i32 m0, s24, s82
	s_lshl_b32 s23, s23, 1
	global_load_lds_dwordx4 v184, s[90:91]
	s_add_i32 m0, s24, s83
	s_add_i32 s23, s23, 32
	global_load_lds_dwordx4 v185, s[90:91]
	s_add_i32 m0, s24, s84
	v_add3_u32 v170, s23, v112, v135
	global_load_lds_dwordx4 v186, s[90:91]
	s_add_i32 m0, s24, s85
	v_add3_u32 v171, s23, v113, v135
	global_load_lds_dwordx4 v187, s[90:91]
	s_add_i32 m0, s24, s86
	v_add_u32_e32 v158, v170, v136
	global_load_lds_dwordx4 v188, s[90:91]
	s_add_i32 m0, s24, s87
	v_add_u32_e32 v166, v171, v136
	global_load_lds_dwordx4 v189, s[90:91]
	s_add_i32 m0, s24, s88
	s_addk_i32 s22, 0x4000
	global_load_lds_dwordx4 v190, s[90:91]
	s_add_i32 m0, s24, s89
	s_add_u32 s8, s8, 0x80
	s_addc_u32 s9, s9, 0
	global_load_lds_dwordx4 v191, s[90:91]
	ds_read_b128 v[138:141], v158
	ds_read_b128 v[146:149], v166 offset:16384
	ds_read_b128 v[150:153], v166 offset:18432
	ds_read_b128 v[162:165], v166 offset:20480
	ds_read_b128 v[166:169], v166 offset:22528
	ds_read_b128 v[142:145], v158 offset:2048
	ds_read_b128 v[154:157], v158 offset:4096
	ds_read_b128 v[158:161], v158 offset:6144
	v_add_u32_e32 v236, v170, v137
	v_add_u32_e32 v237, v171, v137
	ds_read_b128 v[204:207], v236
	ds_read_b128 v[208:211], v237 offset:16384
	ds_read_b128 v[212:215], v237 offset:18432
	ds_read_b128 v[216:219], v237 offset:20480
	ds_read_b128 v[220:223], v237 offset:22528
	ds_read_b128 v[224:227], v236 offset:2048
	ds_read_b128 v[228:231], v236 offset:4096
	ds_read_b128 v[232:235], v236 offset:6144
	s_setprio 1
	s_waitcnt lgkmcnt(11)
	v_mfma_f32_16x16x32_bf16 v[60:63], v[138:141], v[146:149], v[60:63]
	v_mfma_f32_16x16x32_bf16 v[56:59], v[138:141], v[150:153], v[56:59]
	v_mfma_f32_16x16x32_bf16 v[52:55], v[138:141], v[162:165], v[52:55]
	v_mfma_f32_16x16x32_bf16 v[48:51], v[138:141], v[166:169], v[48:51]
	s_waitcnt lgkmcnt(10)
	v_mfma_f32_16x16x32_bf16 v[44:47], v[142:145], v[146:149], v[44:47]
	v_mfma_f32_16x16x32_bf16 v[40:43], v[142:145], v[150:153], v[40:43]
	v_mfma_f32_16x16x32_bf16 v[36:39], v[142:145], v[162:165], v[36:39]
	v_mfma_f32_16x16x32_bf16 v[32:35], v[142:145], v[166:169], v[32:35]
	s_waitcnt lgkmcnt(9)
	v_mfma_f32_16x16x32_bf16 v[28:31], v[154:157], v[146:149], v[28:31]
	v_mfma_f32_16x16x32_bf16 v[24:27], v[154:157], v[150:153], v[24:27]
	v_mfma_f32_16x16x32_bf16 v[20:23], v[154:157], v[162:165], v[20:23]
	v_mfma_f32_16x16x32_bf16 v[16:19], v[154:157], v[166:169], v[16:19]
	s_waitcnt lgkmcnt(8)
	v_mfma_f32_16x16x32_bf16 v[12:15], v[158:161], v[146:149], v[12:15]
	v_mfma_f32_16x16x32_bf16 v[8:11], v[158:161], v[150:153], v[8:11]
	v_mfma_f32_16x16x32_bf16 v[4:7], v[158:161], v[162:165], v[4:7]
	v_mfma_f32_16x16x32_bf16 v[0:3], v[158:161], v[166:169], v[0:3]
	s_waitcnt lgkmcnt(3)
	v_mfma_f32_16x16x32_bf16 v[60:63], v[204:207], v[208:211], v[60:63]
	v_mfma_f32_16x16x32_bf16 v[56:59], v[204:207], v[212:215], v[56:59]
	v_mfma_f32_16x16x32_bf16 v[52:55], v[204:207], v[216:219], v[52:55]
	v_mfma_f32_16x16x32_bf16 v[48:51], v[204:207], v[220:223], v[48:51]
	s_waitcnt lgkmcnt(2)
	v_mfma_f32_16x16x32_bf16 v[44:47], v[224:227], v[208:211], v[44:47]
	v_mfma_f32_16x16x32_bf16 v[40:43], v[224:227], v[212:215], v[40:43]
	v_mfma_f32_16x16x32_bf16 v[36:39], v[224:227], v[216:219], v[36:39]
	v_mfma_f32_16x16x32_bf16 v[32:35], v[224:227], v[220:223], v[32:35]
	s_waitcnt lgkmcnt(1)
	v_mfma_f32_16x16x32_bf16 v[28:31], v[228:231], v[208:211], v[28:31]
	v_mfma_f32_16x16x32_bf16 v[24:27], v[228:231], v[212:215], v[24:27]
	v_mfma_f32_16x16x32_bf16 v[20:23], v[228:231], v[216:219], v[20:23]
	v_mfma_f32_16x16x32_bf16 v[16:19], v[228:231], v[220:223], v[16:19]
	s_waitcnt lgkmcnt(0)
	v_mfma_f32_16x16x32_bf16 v[12:15], v[232:235], v[208:211], v[12:15]
	v_mfma_f32_16x16x32_bf16 v[8:11], v[232:235], v[212:215], v[8:11]
	v_mfma_f32_16x16x32_bf16 v[4:7], v[232:235], v[216:219], v[4:7]
	v_mfma_f32_16x16x32_bf16 v[0:3], v[232:235], v[220:223], v[0:3]
	s_setprio 0
	s_cmpk_eq_i32 s8, 0x1f80
	s_waitcnt vmcnt(0)
	s_barrier
	s_cbranch_scc0 .LBB0_3472
	s_branch .Lxk_exit_3472
.Lxk_3472:
	s_and_b32 s23, s22, 0x4000
	s_xor_b32 s24, s23, 0x4000
	s_lshl_b32 s24, s24, 1
	s_add_i32 s24, s24, 32
	s_add_u32 s90, s52, s8
	s_addc_u32 s91, s53, s9
	s_add_i32 m0, s24, s82
	s_lshl_b32 s23, s23, 1
	global_load_lds_dwordx4 v184, s[90:91]
	s_add_i32 m0, s24, s83
	s_add_i32 s23, s23, 32
	global_load_lds_dwordx4 v185, s[90:91]
	s_add_i32 m0, s24, s84
	v_add3_u32 v170, s23, v112, v135
	global_load_lds_dwordx4 v186, s[90:91]
	s_add_i32 m0, s24, s85
	v_add3_u32 v171, s23, v113, v135
	global_load_lds_dwordx4 v187, s[90:91]
	s_add_i32 m0, s24, s86
	v_add_u32_e32 v158, v170, v136
	global_load_lds_dwordx4 v188, s[90:91]
	s_add_i32 m0, s24, s87
	v_add_u32_e32 v166, v171, v136
	global_load_lds_dwordx4 v189, s[90:91]
	s_add_i32 m0, s24, s88
	s_addk_i32 s22, 0x4000
	global_load_lds_dwordx4 v190, s[90:91]
	s_add_i32 m0, s24, s89
	s_add_u32 s8, s8, 0x80
	s_addc_u32 s9, s9, 0
	global_load_lds_dwordx4 v191, s[90:91]
	ds_read_b128 v[138:141], v158
	ds_read_b128 v[146:149], v166 offset:16384
	ds_read_b128 v[150:153], v166 offset:18432
	ds_read_b128 v[162:165], v166 offset:20480
	ds_read_b128 v[166:169], v166 offset:22528
	ds_read_b128 v[142:145], v158 offset:2048
	ds_read_b128 v[154:157], v158 offset:4096
	ds_read_b128 v[158:161], v158 offset:6144
	v_add_u32_e32 v236, v170, v137
	v_add_u32_e32 v237, v171, v137
	ds_read_b128 v[204:207], v236
	ds_read_b128 v[208:211], v237 offset:16384
	ds_read_b128 v[212:215], v237 offset:18432
	ds_read_b128 v[216:219], v237 offset:20480
	ds_read_b128 v[220:223], v237 offset:22528
	ds_read_b128 v[224:227], v236 offset:2048
	ds_read_b128 v[228:231], v236 offset:4096
	ds_read_b128 v[232:235], v236 offset:6144
	s_setprio 3
	s_waitcnt lgkmcnt(11)
	v_mfma_f32_16x16x32_bf16 v[60:63], v[138:141], v[146:149], v[60:63]
	v_mfma_f32_16x16x32_bf16 v[56:59], v[138:141], v[150:153], v[56:59]
	v_mfma_f32_16x16x32_bf16 v[52:55], v[138:141], v[162:165], v[52:55]
	v_mfma_f32_16x16x32_bf16 v[48:51], v[138:141], v[166:169], v[48:51]
	s_waitcnt lgkmcnt(10)
	v_mfma_f32_16x16x32_bf16 v[44:47], v[142:145], v[146:149], v[44:47]
	v_mfma_f32_16x16x32_bf16 v[40:43], v[142:145], v[150:153], v[40:43]
	v_mfma_f32_16x16x32_bf16 v[36:39], v[142:145], v[162:165], v[36:39]
	v_mfma_f32_16x16x32_bf16 v[32:35], v[142:145], v[166:169], v[32:35]
	s_waitcnt lgkmcnt(9)
	v_mfma_f32_16x16x32_bf16 v[28:31], v[154:157], v[146:149], v[28:31]
	v_mfma_f32_16x16x32_bf16 v[24:27], v[154:157], v[150:153], v[24:27]
	v_mfma_f32_16x16x32_bf16 v[20:23], v[154:157], v[162:165], v[20:23]
	v_mfma_f32_16x16x32_bf16 v[16:19], v[154:157], v[166:169], v[16:19]
	s_waitcnt lgkmcnt(8)
	v_mfma_f32_16x16x32_bf16 v[12:15], v[158:161], v[146:149], v[12:15]
	v_mfma_f32_16x16x32_bf16 v[8:11], v[158:161], v[150:153], v[8:11]
	v_mfma_f32_16x16x32_bf16 v[4:7], v[158:161], v[162:165], v[4:7]
	v_mfma_f32_16x16x32_bf16 v[0:3], v[158:161], v[166:169], v[0:3]
	s_waitcnt lgkmcnt(3)
	v_mfma_f32_16x16x32_bf16 v[60:63], v[204:207], v[208:211], v[60:63]
	v_mfma_f32_16x16x32_bf16 v[56:59], v[204:207], v[212:215], v[56:59]
	v_mfma_f32_16x16x32_bf16 v[52:55], v[204:207], v[216:219], v[52:55]
	v_mfma_f32_16x16x32_bf16 v[48:51], v[204:207], v[220:223], v[48:51]
	s_waitcnt lgkmcnt(2)
	v_mfma_f32_16x16x32_bf16 v[44:47], v[224:227], v[208:211], v[44:47]
	v_mfma_f32_16x16x32_bf16 v[40:43], v[224:227], v[212:215], v[40:43]
	v_mfma_f32_16x16x32_bf16 v[36:39], v[224:227], v[216:219], v[36:39]
	v_mfma_f32_16x16x32_bf16 v[32:35], v[224:227], v[220:223], v[32:35]
	s_waitcnt lgkmcnt(1)
	v_mfma_f32_16x16x32_bf16 v[28:31], v[228:231], v[208:211], v[28:31]
	v_mfma_f32_16x16x32_bf16 v[24:27], v[228:231], v[212:215], v[24:27]
	v_mfma_f32_16x16x32_bf16 v[20:23], v[228:231], v[216:219], v[20:23]
	v_mfma_f32_16x16x32_bf16 v[16:19], v[228:231], v[220:223], v[16:19]
	s_waitcnt lgkmcnt(0)
	v_mfma_f32_16x16x32_bf16 v[12:15], v[232:235], v[208:211], v[12:15]
	v_mfma_f32_16x16x32_bf16 v[8:11], v[232:235], v[212:215], v[8:11]
	v_mfma_f32_16x16x32_bf16 v[4:7], v[232:235], v[216:219], v[4:7]
	v_mfma_f32_16x16x32_bf16 v[0:3], v[232:235], v[220:223], v[0:3]
	s_setprio 2
	s_cmpk_eq_i32 s8, 0x1f80
	s_waitcnt vmcnt(0)
	s_barrier
	s_cbranch_scc0 .Lxk_3472
